# speedup vs baseline: 1.0063x; 1.0063x over previous
; __device__ __forceinline__ void convert_phase(const Params& p, char* smem, const int wave) {
;     ...
;   const float* x = p.in[0];
;   u16* xb = reinterpret_cast<u16*>(p.ws + OFF_XB);
;   const long n8 = (long)MT * DM / 8;
;   for (long i = (long)blockIdx.x * NTHREADS + opaque_tid(wave); i < n8; i += (long)gridDim.x * NTHREADS) {
;     float4 a = *reinterpret_cast<const float4*>(x + i * 8);
;     float4 b = *reinterpret_cast<const float4*>(x + i * 8 + 4);
;     uint4 o; o.x = pack2(a.x, a.y); o.y = pack2(a.z, a.w); o.z = pack2(b.x, b.y); o.w = pack2(b.z, b.w);
;     *reinterpret_cast<uint4*>(xb + i * 8) = o;
;   }
.LBB0_69:
	s_or_b64 exec, exec, s[8:9]
	v_mbcnt_lo_u32_b32 v2, -1, 0
	v_mbcnt_hi_u32_b32 v2, -1, v2
	s_nop 0
	v_add_u32_e32 v2, s0, v2
	v_ashrrev_i32_e32 v3, 31, v2
	v_lshl_add_u64 v[2:3], s[6:7], 0, v[2:3]
	s_mov_b64 s[0:1], 0x800000
	v_cmp_gt_i64_e32 vcc, s[0:1], v[2:3]
	s_and_saveexec_b64 s[6:7], vcc
	s_cbranch_execz .LBB0_72
	s_add_u32 s10, s88, 0xea00000
	s_addc_u32 s11, s89, 0
	s_mov_b32 s8, s72
	s_mov_b32 s9, s73
	v_lshlrev_b32_e32 v3, 5, v2
	v_lshlrev_b32_e32 v4, 4, v2
	v_add_u32_e32 v5, 0x400000, v3
	v_add_u32_e32 v9, 0x200000, v4
	v_add_u32_e32 v6, 0x800000, v3
	v_add_u32_e32 v10, 0x400000, v4
	v_add_u32_e32 v7, 0xc00000, v3
	v_add_u32_e32 v11, 0x600000, v4
	s_mov_b32 s3, 16
.Lmy_xcv:
	global_load_dwordx4 v[16:19], v3, s[8:9]
	global_load_dwordx4 v[20:23], v3, s[8:9] offset:16
	global_load_dwordx4 v[24:27], v5, s[8:9]
	global_load_dwordx4 v[28:31], v5, s[8:9] offset:16
	global_load_dwordx4 v[32:35], v6, s[8:9]
	global_load_dwordx4 v[36:39], v6, s[8:9] offset:16
	global_load_dwordx4 v[40:43], v7, s[8:9]
	global_load_dwordx4 v[44:47], v7, s[8:9] offset:16
	s_waitcnt vmcnt(6)
	v_cvt_pk_bf16_f32 v48, v16, v17
	v_cvt_pk_bf16_f32 v49, v18, v19
	v_cvt_pk_bf16_f32 v50, v20, v21
	v_cvt_pk_bf16_f32 v51, v22, v23
	s_nop 0
	global_store_dwordx4 v4, v[48:51], s[10:11]
	s_waitcnt vmcnt(5)
	v_cvt_pk_bf16_f32 v52, v24, v25
	v_cvt_pk_bf16_f32 v53, v26, v27
	v_cvt_pk_bf16_f32 v54, v28, v29
	v_cvt_pk_bf16_f32 v55, v30, v31
	s_nop 0
	global_store_dwordx4 v9, v[52:55], s[10:11]
	s_waitcnt vmcnt(4)
	v_cvt_pk_bf16_f32 v56, v32, v33
	v_cvt_pk_bf16_f32 v57, v34, v35
	v_cvt_pk_bf16_f32 v58, v36, v37
	v_cvt_pk_bf16_f32 v59, v38, v39
	s_nop 0
	global_store_dwordx4 v10, v[56:59], s[10:11]
	s_waitcnt vmcnt(3)
	v_cvt_pk_bf16_f32 v60, v40, v41
	v_cvt_pk_bf16_f32 v61, v42, v43
	v_cvt_pk_bf16_f32 v62, v44, v45
	v_cvt_pk_bf16_f32 v63, v46, v47
	s_nop 0
	global_store_dwordx4 v11, v[60:63], s[10:11]
	s_add_u32 s8, s8, 0x1000000
	s_addc_u32 s9, s9, 0
	s_add_u32 s10, s10, 0x800000
	s_addc_u32 s11, s11, 0
	s_sub_u32 s3, s3, 1
	s_cmp_lg_u32 s3, 0
	s_cbranch_scc1 .Lmy_xcv

;     ...
;       const int tid3 = opaque_tid(wave);
;       const int wr3 = tid3 >> 8, wc3 = (tid3 >> 6) & 3, fr3 = tid3 & 15, fq3 = (tid3 & 63) >> 4;
;       const int ebase3 = (brow + wr3 * 64 + fr3) * DM + pn * BM + wc3 * 32 + fq3 * 4;
;       const int vo4b = ebase3 * 4, vo2 = ebase3 * 2, vo1 = ebase3;
;       (void)vo4b; (void)vo2; (void)vo1;
;       if constexpr (OUTF) {
;         _Pragma("unroll") for (int bj = 0; bj < 2; ++bj) _Pragma("unroll") for (int n = 0; n < 2; ++n) {
;           const int col = pn * BM + bj * HALF + wc3 * 32 + n * 16 + fq3 * 4;
;           const float4 gm = *reinterpret_cast<const float4*>(g.gam + col), bt = *reinterpret_cast<const float4*>(g.bet + col);
;           _Pragma("unroll") for (int ai = 0; ai < 2; ++ai) _Pragma("unroll") for (int m = 0; m < 4; ++m) {
;             const int rl = ai * HALF + wr3 * 64 + m * 16 + fr3;
;             const float2 ms = *reinterpret_cast<const float2*>(mr + rl * 2);
;             f32x4 y = acc[ai][bj][m][n];
;             u32x4 o;
;             o[0] = __float_as_uint((y[0] - ms.x) * ms.y * gm.x + bt.x); o[1] = __float_as_uint((y[1] - ms.x) * ms.y * gm.y + bt.y);
;             o[2] = __float_as_uint((y[2] - ms.x) * ms.y * gm.z + bt.z); o[3] = __float_as_uint((y[3] - ms.x) * ms.y * gm.w + bt.w);
;             __builtin_amdgcn_raw_buffer_store_b128(o, rsO, vo4b + ((ai * HALF + m * 16) * DM + bj * HALF + n * 16) * 4, 0, 0);
;           }
;         }
;       } else {
;         constexpr int PIECE = 1024 + 16, LOBASE = 64 * PIECE;
;         const int lane3 = tid3 & 63;
;         const int hvo = (lane3 >> 5) * (DM * 2) + (lane3 & 31) * 16;
;         const int lvo = (lane3 >> 4) * DM + (lane3 & 15) * 16;
;         _Pragma("unroll") for (int ai = 0; ai < 2; ++ai) {
;           _Pragma("unroll") for (int bj = 0; bj < 2; ++bj) _Pragma("unroll") for (int n = 0; n < 2; ++n) {
;             const int cc = bj * HALF + wc3 * 32 + n * 16 + fq3 * 4;
;             const float4 gm = *reinterpret_cast<const float4*>(g.gam + pn * BM + cc), bt = *reinterpret_cast<const float4*>(g.bet + pn * BM + cc);
;             _Pragma("unroll") for (int m = 0; m < 4; ++m) {
;               const int rr = wr3 * 64 + m * 16 + fr3;
;               const float2 ms = *reinterpret_cast<const float2*>(mr + (ai * HALF + rr) * 2);
;               f32x4 y = acc[ai][bj][m][n];
.LBB0_177:
	s_or_b64 exec, exec, s[6:7]
	s_waitcnt lgkmcnt(0)
	s_barrier
	v_mbcnt_lo_u32_b32 v0, -1, 0
	v_mbcnt_hi_u32_b32 v0, -1, v0
	s_movk_i32 s4, 0x1000
	v_add_u32_e32 v1, s29, v0
	v_ashrrev_i32_e32 v5, 2, v1
	v_lshrrev_b32_e32 v6, 1, v1
	v_lshlrev_b32_e32 v1, 4, v1
	v_lshlrev_b32_e32 v12, 7, v0
	v_and_b32_e32 v13, 0x1f0, v1
	v_and_b32_e32 v2, 15, v0
	v_and_or_b32 v70, v12, s4, v13
	s_lshl_b32 s4, s0, 8
	s_movk_i32 s0, 0xffc0
	v_and_or_b32 v97, v5, s0, v2
	s_lshl_b32 s0, s18, 19
	v_bfe_u32 v4, v0, 4, 2
	s_ashr_i32 s5, s4, 31
	s_add_i32 s0, s0, s42
	v_lshlrev_b32_e32 v7, 2, v4
	s_add_i32 s0, s0, s4
	s_lshl_b64 s[4:5], s[4:5], 2
	v_and_or_b32 v12, v6, s61, v7
	s_add_u32 s6, s78, s4
	v_and_b32_e32 v3, 63, v0
	v_and_b32_e32 v1, 0xf0, v1
	v_lshlrev_b32_e32 v13, 9, v0
	v_lshlrev_b32_e32 v0, 8, v0
	s_addc_u32 s7, s79, s5
	v_lshlrev_b32_e32 v72, 2, v12
	v_lshl_or_b32 v68, v4, 11, v1
	v_and_b32_e32 v14, 0x300, v0
	v_lshlrev_b32_e32 v74, 4, v3
	global_load_dwordx4 v[196:199], v72, s[6:7]
	global_load_dwordx4 v[200:203], v72, s[6:7] offset:64
	global_load_dwordx4 v[204:207], v72, s[6:7] offset:512
	global_load_dwordx4 v[208:211], v72, s[6:7] offset:576
	s_add_u32 s4, s80, s4
	s_addc_u32 s5, s81, s5
	global_load_dwordx4 v[212:215], v72, s[4:5]
	global_load_dwordx4 v[220:223], v72, s[4:5] offset:64
	global_load_dwordx4 v[240:243], v72, s[4:5] offset:512
	global_load_dwordx4 v[248:251], v72, s[4:5] offset:576
	v_lshl_add_u32 v71, v97, 3, v246
	s_mov_b32 s18, 0x10400
	v_lshrrev_b32_e32 v67, 1, v97
	v_mul_lo_u32 v105, v67, s68
	v_add_u32_e32 v69, s59, v74
	s_lshl_b32 s22, s0, 1
	s_mov_b32 s23, s75
	s_andn2_b64 vcc, exec, s[14:15]
	s_waitcnt vmcnt(0)
	v_mov_b32_e32 v0, v196
	v_mov_b32_e32 v1, v197
	v_mov_b32_e32 v2, v198
	v_mov_b32_e32 v3, v199
	v_mov_b32_e32 v4, v212
	v_mov_b32_e32 v5, v213
	v_mov_b32_e32 v6, v214
	v_mov_b32_e32 v7, v215
	v_mov_b32_e32 v22, v1
	v_lshlrev_b32_e32 v1, 1, v12
	v_mov_b32_e32 v23, v2
	v_and_or_b32 v109, v13, s66, v1
	v_or3_b32 v2, v14, v12, s18
	ds_read_b64 v[12:13], v71
	v_mov_b32_e32 v64, v5
	v_mov_b32_e32 v65, v6
	v_mov_b32_e32 v1, v3
	v_mov_b32_e32 v5, v7
	s_waitcnt lgkmcnt(0)
	v_pk_add_f32 v[14:15], v[238:239], v[12:13] op_sel_hi:[1,0] neg_lo:[0,1] neg_hi:[0,1]
	v_pk_add_f32 v[20:21], v[236:237], v[12:13] op_sel_hi:[1,0] neg_lo:[0,1] neg_hi:[0,1]
	v_pk_mul_f32 v[14:15], v[12:13], v[14:15] op_sel:[1,0]
	v_pk_mul_f32 v[12:13], v[12:13], v[20:21] op_sel:[1,0]
	v_pk_fma_f32 v[14:15], v[22:23], v[14:15], v[64:65]
	v_pk_fma_f32 v[6:7], v[0:1], v[12:13], v[4:5]
	v_and_b32_sdwa v12, v14, v244 dst_sel:DWORD dst_unused:UNUSED_PAD src0_sel:WORD_1 src1_sel:DWORD
	v_add3_u32 v12, v14, v12, s67
	v_and_b32_e32 v20, 0xffff0000, v12
	v_and_b32_sdwa v12, v7, v244 dst_sel:DWORD dst_unused:UNUSED_PAD src0_sel:WORD_1 src1_sel:DWORD
	v_and_b32_sdwa v3, v15, v244 dst_sel:DWORD dst_unused:UNUSED_PAD src0_sel:WORD_1 src1_sel:DWORD
	v_and_b32_sdwa v13, v6, v244 dst_sel:DWORD dst_unused:UNUSED_PAD src0_sel:WORD_1 src1_sel:DWORD
	v_add3_u32 v12, v7, v12, s67
	v_add3_u32 v3, v15, v3, s67
	v_add3_u32 v21, v6, v13, s67
	v_and_b32_e32 v66, 0xffff0000, v12
	v_or_b32_sdwa v13, v66, v3 dst_sel:DWORD dst_unused:UNUSED_PAD src0_sel:DWORD src1_sel:WORD_1
	v_or_b32_sdwa v12, v21, v20 dst_sel:DWORD dst_unused:UNUSED_PAD src0_sel:WORD_1 src1_sel:DWORD
	v_add_u32_e32 v73, v109, v105
	ds_write_b64 v73, v[12:13]
	v_and_b32_e32 v12, 0xffff0000, v21
	v_sub_u32_e32 v6, v6, v12
	v_sub_u32_e32 v12, v14, v20
	v_and_b32_e32 v3, 0xffff0000, v3
	v_add_u32_e32 v12, 0x80, v12
	v_sub_u32_e32 v3, v15, v3
	v_sub_u32_e32 v7, v7, v66
	v_add_u32_e32 v6, 0x80, v6
	v_ashrrev_i32_e32 v12, 8, v12
	v_add_u32_e32 v3, 0x80, v3
	v_add_u32_e32 v7, 0x80, v7
	v_ashrrev_i32_e32 v6, 8, v6
	v_min_i32_e32 v12, 0x7f, v12
	v_ashrrev_i32_e32 v3, 8, v3
	v_ashrrev_i32_e32 v7, 8, v7
	v_min_i32_e32 v6, 0x7f, v6
	v_min_i32_sdwa v3, v3, s69 dst_sel:WORD_1 dst_unused:UNUSED_PAD src0_sel:DWORD src1_sel:DWORD
	v_min_i32_e32 v7, 0x7f, v7
	v_lshlrev_b32_e32 v12, 8, v12
	v_and_b32_e32 v12, 0xff00, v12
	v_and_b32_e32 v3, 0xff0000, v3
	v_perm_b32 v6, v7, v6, s76
	v_or3_b32 v3, v6, v12, v3
	v_lshrrev_b32_e32 v6, 2, v97
	v_mad_u64_u32 v[12:13], s[18:19], v6, s68, v[2:3]
	ds_write_b32 v12, v3
	v_or_b32_e32 v3, 16, v97
	v_lshl_add_u32 v13, v3, 3, v246
	ds_read_b64 v[6:7], v13
	v_lshrrev_b32_e32 v75, 1, v3
	v_mul_lo_u32 v106, v75, s68
	v_add_u32_e32 v75, v109, v106
	v_lshrrev_b32_e32 v3, 2, v3
	s_waitcnt lgkmcnt(0)
	v_pk_add_f32 v[14:15], v[218:219], v[6:7] op_sel_hi:[1,0] neg_lo:[0,1] neg_hi:[0,1]
	v_pk_add_f32 v[20:21], v[216:217], v[6:7] op_sel_hi:[1,0] neg_lo:[0,1] neg_hi:[0,1]
	v_pk_mul_f32 v[14:15], v[6:7], v[14:15] op_sel:[1,0]
	v_pk_mul_f32 v[6:7], v[6:7], v[20:21] op_sel:[1,0]
	v_pk_fma_f32 v[14:15], v[22:23], v[14:15], v[64:65]
	v_pk_fma_f32 v[6:7], v[0:1], v[6:7], v[4:5]
	v_and_b32_sdwa v20, v15, v244 dst_sel:DWORD dst_unused:UNUSED_PAD src0_sel:WORD_1 src1_sel:DWORD
	v_and_b32_sdwa v21, v14, v244 dst_sel:DWORD dst_unused:UNUSED_PAD src0_sel:WORD_1 src1_sel:DWORD
	v_add3_u32 v66, v15, v20, s67
	v_add3_u32 v20, v14, v21, s67
	v_and_b32_e32 v67, 0xffff0000, v20
	v_and_b32_sdwa v20, v7, v244 dst_sel:DWORD dst_unused:UNUSED_PAD src0_sel:WORD_1 src1_sel:DWORD
	v_and_b32_sdwa v21, v6, v244 dst_sel:DWORD dst_unused:UNUSED_PAD src0_sel:WORD_1 src1_sel:DWORD
	v_add3_u32 v20, v7, v20, s67
	v_add3_u32 v96, v6, v21, s67
	v_and_b32_e32 v98, 0xffff0000, v20
	v_or_b32_sdwa v21, v98, v66 dst_sel:DWORD dst_unused:UNUSED_PAD src0_sel:DWORD src1_sel:WORD_1
	v_or_b32_sdwa v20, v96, v67 dst_sel:DWORD dst_unused:UNUSED_PAD src0_sel:WORD_1 src1_sel:DWORD
	ds_write_b64 v75, v[20:21]
	v_and_b32_e32 v20, 0xffff0000, v96
	v_sub_u32_e32 v6, v6, v20
	v_sub_u32_e32 v14, v14, v67
	v_and_b32_e32 v20, 0xffff0000, v66
	v_add_u32_e32 v14, 0x80, v14
	v_sub_u32_e32 v15, v15, v20
	v_sub_u32_e32 v7, v7, v98
	v_add_u32_e32 v6, 0x80, v6
	v_ashrrev_i32_e32 v14, 8, v14
	v_add_u32_e32 v15, 0x80, v15
	v_add_u32_e32 v7, 0x80, v7
	v_ashrrev_i32_e32 v6, 8, v6
	v_min_i32_e32 v14, 0x7f, v14
	v_ashrrev_i32_e32 v15, 8, v15
	v_ashrrev_i32_e32 v7, 8, v7
	v_min_i32_e32 v6, 0x7f, v6
	v_min_i32_sdwa v15, v15, s69 dst_sel:WORD_1 dst_unused:UNUSED_PAD src0_sel:DWORD src1_sel:DWORD
	v_min_i32_e32 v7, 0x7f, v7
	v_lshlrev_b32_e32 v14, 8, v14
	v_and_b32_e32 v14, 0xff00, v14
	v_and_b32_e32 v15, 0xff0000, v15
	v_perm_b32 v6, v7, v6, s76
	v_or3_b32 v6, v6, v14, v15
	v_mad_u64_u32 v[14:15], s[18:19], v3, s68, v[2:3]
	v_or_b32_e32 v3, 32, v97
	ds_write_b32 v14, v6
	v_lshl_add_u32 v15, v3, 3, v246
	ds_read_b64 v[6:7], v15
	v_lshrrev_b32_e32 v96, 1, v3
	v_mul_lo_u32 v107, v96, s68
	v_add_u32_e32 v96, v109, v107
	v_lshrrev_b32_e32 v3, 2, v3
	s_waitcnt lgkmcnt(0)
;     ...
;         _Pragma("unroll") for (int ai = 0; ai < 2; ++ai) {
;           _Pragma("unroll") for (int bj = 0; bj < 2; ++bj) _Pragma("unroll") for (int n = 0; n < 2; ++n) {
;             const int cc = bj * HALF + wc3 * 32 + n * 16 + fq3 * 4;
;             const float4 gm = *reinterpret_cast<const float4*>(g.gam + pn * BM + cc), bt = *reinterpret_cast<const float4*>(g.bet + pn * BM + cc);
;             _Pragma("unroll") for (int m = 0; m < 4; ++m) {
;               const int rr = wr3 * 64 + m * 16 + fr3;
;               const float2 ms = *reinterpret_cast<const float2*>(mr + (ai * HALF + rr) * 2);
;               f32x4 y = acc[ai][bj][m][n];
;               const float o0 = (y[0] - ms.x) * ms.y * gm.x + bt.x, o1 = (y[1] - ms.x) * ms.y * gm.y + bt.y;
;               const float o2 = (y[2] - ms.x) * ms.y * gm.z + bt.z, o3 = (y[3] - ms.x) * ms.y * gm.w + bt.w;
;               const unsigned h0 = f2bf(o0), h1 = f2bf(o1), h2 = f2bf(o2), h3 = f2bf(o3);
;               u32x2 ob; ob[0] = h0 | (h1 << 16); ob[1] = h2 | (h3 << 16);
;               *reinterpret_cast<u32x2*>(smem + (rr >> 1) * PIECE + (rr & 1) * 512 + cc * 2) = ob;
;               const int l0 = min(((int)__float_as_uint(o0) - (int)(h0 << 16) + 128) >> 8, 127);
;               const int l1 = min(((int)__float_as_uint(o1) - (int)(h1 << 16) + 128) >> 8, 127);
;               const int l2 = min(((int)__float_as_uint(o2) - (int)(h2 << 16) + 128) >> 8, 127);
;               const int l3 = min(((int)__float_as_uint(o3) - (int)(h3 << 16) + 128) >> 8, 127);
;               *reinterpret_cast<unsigned*>(smem + LOBASE + (rr >> 2) * PIECE + (rr & 3) * 256 + cc) =
;                   (unsigned)(l0 & 255) | ((unsigned)(l1 & 255) << 8) | ((unsigned)(l2 & 255) << 16) | ((unsigned)l3 << 24);
;             }
	v_pk_add_f32 v[20:21], v[194:195], v[6:7] op_sel_hi:[1,0] neg_lo:[0,1] neg_hi:[0,1]
	v_pk_add_f32 v[66:67], v[192:193], v[6:7] op_sel_hi:[1,0] neg_lo:[0,1] neg_hi:[0,1]
	v_pk_mul_f32 v[20:21], v[6:7], v[20:21] op_sel:[1,0]
	v_pk_mul_f32 v[6:7], v[6:7], v[66:67] op_sel:[1,0]
	v_pk_fma_f32 v[20:21], v[22:23], v[20:21], v[64:65]
	v_pk_fma_f32 v[6:7], v[0:1], v[6:7], v[4:5]
	v_and_b32_sdwa v66, v21, v244 dst_sel:DWORD dst_unused:UNUSED_PAD src0_sel:WORD_1 src1_sel:DWORD
	v_and_b32_sdwa v67, v20, v244 dst_sel:DWORD dst_unused:UNUSED_PAD src0_sel:WORD_1 src1_sel:DWORD
	v_add3_u32 v98, v21, v66, s67
	v_add3_u32 v66, v20, v67, s67
	v_and_b32_e32 v99, 0xffff0000, v66
	v_and_b32_sdwa v66, v7, v244 dst_sel:DWORD dst_unused:UNUSED_PAD src0_sel:WORD_1 src1_sel:DWORD
	v_and_b32_sdwa v67, v6, v244 dst_sel:DWORD dst_unused:UNUSED_PAD src0_sel:WORD_1 src1_sel:DWORD
	v_add3_u32 v66, v7, v66, s67
	v_add3_u32 v100, v6, v67, s67
	v_and_b32_e32 v101, 0xffff0000, v66
	v_or_b32_sdwa v67, v101, v98 dst_sel:DWORD dst_unused:UNUSED_PAD src0_sel:DWORD src1_sel:WORD_1
	v_or_b32_sdwa v66, v100, v99 dst_sel:DWORD dst_unused:UNUSED_PAD src0_sel:WORD_1 src1_sel:DWORD
	ds_write_b64 v96, v[66:67]
	v_and_b32_e32 v66, 0xffff0000, v100
	v_sub_u32_e32 v6, v6, v66
	v_sub_u32_e32 v20, v20, v99
	v_and_b32_e32 v66, 0xffff0000, v98
	v_add_u32_e32 v20, 0x80, v20
	v_sub_u32_e32 v21, v21, v66
	v_sub_u32_e32 v7, v7, v101
	v_add_u32_e32 v6, 0x80, v6
	v_ashrrev_i32_e32 v20, 8, v20
	v_add_u32_e32 v21, 0x80, v21
	v_add_u32_e32 v7, 0x80, v7
	v_ashrrev_i32_e32 v6, 8, v6
	v_min_i32_e32 v20, 0x7f, v20
	v_ashrrev_i32_e32 v21, 8, v21
	v_ashrrev_i32_e32 v7, 8, v7
	v_min_i32_e32 v6, 0x7f, v6
	v_min_i32_sdwa v21, v21, s69 dst_sel:WORD_1 dst_unused:UNUSED_PAD src0_sel:DWORD src1_sel:DWORD
	v_min_i32_e32 v7, 0x7f, v7
	v_lshlrev_b32_e32 v20, 8, v20
	v_and_b32_e32 v20, 0xff00, v20
	v_and_b32_e32 v21, 0xff0000, v21
	v_perm_b32 v6, v7, v6, s76
	v_or3_b32 v6, v6, v20, v21
	v_mad_u64_u32 v[20:21], s[18:19], v3, s68, v[2:3]
	v_or_b32_e32 v3, 48, v97
	ds_write_b32 v20, v6
	v_lshl_add_u32 v21, v3, 3, v246
	ds_read_b64 v[6:7], v21
	s_waitcnt lgkmcnt(0)
	v_pk_add_f32 v[66:67], v[190:191], v[6:7] op_sel_hi:[1,0] neg_lo:[0,1] neg_hi:[0,1]
	s_nop 0
	v_pk_mul_f32 v[66:67], v[6:7], v[66:67] op_sel:[1,0]
	s_nop 0
	v_pk_fma_f32 v[22:23], v[22:23], v[66:67], v[64:65]
	v_pk_add_f32 v[64:65], v[188:189], v[6:7] op_sel_hi:[1,0] neg_lo:[0,1] neg_hi:[0,1]
	v_lshrrev_b32_e32 v66, 1, v3
	v_pk_mul_f32 v[6:7], v[6:7], v[64:65] op_sel:[1,0]
	v_mul_lo_u32 v108, v66, s68
	v_pk_fma_f32 v[0:1], v[0:1], v[6:7], v[4:5]
	v_and_b32_sdwa v4, v23, v244 dst_sel:DWORD dst_unused:UNUSED_PAD src0_sel:WORD_1 src1_sel:DWORD
	v_and_b32_sdwa v5, v22, v244 dst_sel:DWORD dst_unused:UNUSED_PAD src0_sel:WORD_1 src1_sel:DWORD
	v_add3_u32 v6, v23, v4, s67
	v_add3_u32 v4, v22, v5, s67
	v_and_b32_e32 v7, 0xffff0000, v4
	v_and_b32_sdwa v4, v1, v244 dst_sel:DWORD dst_unused:UNUSED_PAD src0_sel:WORD_1 src1_sel:DWORD
	v_and_b32_sdwa v5, v0, v244 dst_sel:DWORD dst_unused:UNUSED_PAD src0_sel:WORD_1 src1_sel:DWORD
	v_add3_u32 v4, v1, v4, s67
	v_add3_u32 v64, v0, v5, s67
	v_and_b32_e32 v65, 0xffff0000, v4
	v_or_b32_sdwa v5, v65, v6 dst_sel:DWORD dst_unused:UNUSED_PAD src0_sel:DWORD src1_sel:WORD_1
	v_or_b32_sdwa v4, v64, v7 dst_sel:DWORD dst_unused:UNUSED_PAD src0_sel:WORD_1 src1_sel:DWORD
	v_add_u32_e32 v97, v109, v108
	ds_write_b64 v97, v[4:5]
	v_and_b32_e32 v4, 0xffff0000, v64
	v_sub_u32_e32 v0, v0, v4
	v_sub_u32_e32 v4, v22, v7
	v_and_b32_e32 v5, 0xffff0000, v6
	v_add_u32_e32 v4, 0x80, v4
	v_sub_u32_e32 v5, v23, v5
	v_sub_u32_e32 v1, v1, v65
	v_add_u32_e32 v0, 0x80, v0
	v_ashrrev_i32_e32 v4, 8, v4
	v_add_u32_e32 v5, 0x80, v5
	v_add_u32_e32 v1, 0x80, v1
	v_ashrrev_i32_e32 v0, 8, v0
	v_min_i32_e32 v4, 0x7f, v4
	v_ashrrev_i32_e32 v5, 8, v5
	v_ashrrev_i32_e32 v1, 8, v1
	v_min_i32_e32 v0, 0x7f, v0
	v_min_i32_sdwa v5, v5, s69 dst_sel:WORD_1 dst_unused:UNUSED_PAD src0_sel:DWORD src1_sel:DWORD
	v_min_i32_e32 v1, 0x7f, v1
	v_lshlrev_b32_e32 v4, 8, v4
	v_and_b32_e32 v4, 0xff00, v4
	v_and_b32_e32 v5, 0xff0000, v5
	v_perm_b32 v0, v1, v0, s76
	v_lshrrev_b32_e32 v1, 2, v3
	v_or3_b32 v0, v0, v4, v5
	v_mad_u64_u32 v[22:23], s[18:19], v1, s68, v[2:3]
	ds_write_b32 v22, v0
	v_mov_b32_e32 v0, v200
	v_mov_b32_e32 v1, v201
	v_mov_b32_e32 v2, v202
	v_mov_b32_e32 v3, v203
	v_mov_b32_e32 v4, v220
	v_mov_b32_e32 v5, v221
	v_mov_b32_e32 v6, v222
	v_mov_b32_e32 v7, v223
	ds_read_b64 v[98:99], v71
	s_mul_i32 s18, s52, 0x2080
	v_add_u32_e32 v74, s18, v74
	s_mov_b32 s18, s74
	s_mov_b32 s19, s75
	s_waitcnt lgkmcnt(0)
;     ...
;         _Pragma("unroll") for (int ai = 0; ai < 2; ++ai) {
;           _Pragma("unroll") for (int bj = 0; bj < 2; ++bj) _Pragma("unroll") for (int n = 0; n < 2; ++n) {
;             const int cc = bj * HALF + wc3 * 32 + n * 16 + fq3 * 4;
;             const float4 gm = *reinterpret_cast<const float4*>(g.gam + pn * BM + cc), bt = *reinterpret_cast<const float4*>(g.bet + pn * BM + cc);
;             _Pragma("unroll") for (int m = 0; m < 4; ++m) {
;               const int rr = wr3 * 64 + m * 16 + fr3;
;               const float2 ms = *reinterpret_cast<const float2*>(mr + (ai * HALF + rr) * 2);
;               f32x4 y = acc[ai][bj][m][n];
;               const float o0 = (y[0] - ms.x) * ms.y * gm.x + bt.x, o1 = (y[1] - ms.x) * ms.y * gm.y + bt.y;
;               const float o2 = (y[2] - ms.x) * ms.y * gm.z + bt.z, o3 = (y[3] - ms.x) * ms.y * gm.w + bt.w;
;               const unsigned h0 = f2bf(o0), h1 = f2bf(o1), h2 = f2bf(o2), h3 = f2bf(o3);
;               u32x2 ob; ob[0] = h0 | (h1 << 16); ob[1] = h2 | (h3 << 16);
;               *reinterpret_cast<u32x2*>(smem + (rr >> 1) * PIECE + (rr & 1) * 512 + cc * 2) = ob;
;               const int l0 = min(((int)__float_as_uint(o0) - (int)(h0 << 16) + 128) >> 8, 127);
;               const int l1 = min(((int)__float_as_uint(o1) - (int)(h1 << 16) + 128) >> 8, 127);
;               const int l2 = min(((int)__float_as_uint(o2) - (int)(h2 << 16) + 128) >> 8, 127);
;               const int l3 = min(((int)__float_as_uint(o3) - (int)(h3 << 16) + 128) >> 8, 127);
;               *reinterpret_cast<unsigned*>(smem + LOBASE + (rr >> 2) * PIECE + (rr & 3) * 256 + cc) =
;                   (unsigned)(l0 & 255) | ((unsigned)(l1 & 255) << 8) | ((unsigned)(l2 & 255) << 16) | ((unsigned)l3 << 24);
;             }
	v_pk_add_f32 v[100:101], v[234:235], v[98:99] op_sel_hi:[1,0] neg_lo:[0,1] neg_hi:[0,1]
	v_pk_add_f32 v[102:103], v[232:233], v[98:99] op_sel_hi:[1,0] neg_lo:[0,1] neg_hi:[0,1]
	v_pk_mul_f32 v[100:101], v[98:99], v[100:101] op_sel:[1,0]
	v_pk_mul_f32 v[98:99], v[98:99], v[102:103] op_sel:[1,0]
	v_mov_b32_e32 v64, v1
	v_mov_b32_e32 v65, v2
	v_mov_b32_e32 v66, v5
	v_mov_b32_e32 v67, v6
	v_pk_fma_f32 v[100:101], v[64:65], v[100:101], v[66:67]
	v_mov_b32_e32 v1, v3
	v_mov_b32_e32 v5, v7
	v_and_b32_sdwa v23, v100, v244 dst_sel:DWORD dst_unused:UNUSED_PAD src0_sel:WORD_1 src1_sel:DWORD
	v_pk_fma_f32 v[6:7], v[0:1], v[98:99], v[4:5]
	v_add3_u32 v23, v100, v23, s67
	v_and_b32_e32 v102, 0xffff0000, v23
	v_and_b32_sdwa v23, v7, v244 dst_sel:DWORD dst_unused:UNUSED_PAD src0_sel:WORD_1 src1_sel:DWORD
	v_and_b32_sdwa v3, v101, v244 dst_sel:DWORD dst_unused:UNUSED_PAD src0_sel:WORD_1 src1_sel:DWORD
	v_and_b32_sdwa v98, v6, v244 dst_sel:DWORD dst_unused:UNUSED_PAD src0_sel:WORD_1 src1_sel:DWORD
	v_add3_u32 v23, v7, v23, s67
	v_or_b32_e32 v2, 32, v109
	v_add3_u32 v3, v101, v3, s67
	v_add3_u32 v103, v6, v98, s67
	v_and_b32_e32 v104, 0xffff0000, v23
	v_or_b32_sdwa v99, v104, v3 dst_sel:DWORD dst_unused:UNUSED_PAD src0_sel:DWORD src1_sel:WORD_1
	v_or_b32_sdwa v98, v103, v102 dst_sel:DWORD dst_unused:UNUSED_PAD src0_sel:WORD_1 src1_sel:DWORD
	v_add_u32_e32 v23, v2, v105
	ds_write_b64 v23, v[98:99]
	v_and_b32_e32 v98, 0xffff0000, v103
	v_sub_u32_e32 v6, v6, v98
	v_sub_u32_e32 v98, v100, v102
	v_and_b32_e32 v3, 0xffff0000, v3
	v_add_u32_e32 v98, 0x80, v98
	v_sub_u32_e32 v3, v101, v3
	v_sub_u32_e32 v7, v7, v104
	v_add_u32_e32 v6, 0x80, v6
	v_ashrrev_i32_e32 v98, 8, v98
	v_add_u32_e32 v3, 0x80, v3
	v_add_u32_e32 v7, 0x80, v7
	v_ashrrev_i32_e32 v6, 8, v6
	v_min_i32_e32 v98, 0x7f, v98
	v_ashrrev_i32_e32 v3, 8, v3
	v_ashrrev_i32_e32 v7, 8, v7
	v_min_i32_e32 v6, 0x7f, v6
	v_min_i32_sdwa v3, v3, s69 dst_sel:WORD_1 dst_unused:UNUSED_PAD src0_sel:DWORD src1_sel:DWORD
	v_min_i32_e32 v7, 0x7f, v7
	v_lshlrev_b32_e32 v98, 8, v98
	v_and_b32_e32 v98, 0xff00, v98
	v_and_b32_e32 v3, 0xff0000, v3
	v_perm_b32 v6, v7, v6, s76
	v_or3_b32 v3, v6, v98, v3
	ds_write_b32 v12, v3 offset:16
	ds_read_b64 v[6:7], v13
	s_waitcnt lgkmcnt(0)
	v_pk_add_f32 v[98:99], v[158:159], v[6:7] op_sel_hi:[1,0] neg_lo:[0,1] neg_hi:[0,1]
	s_nop 0
	v_pk_mul_f32 v[98:99], v[6:7], v[98:99] op_sel:[1,0]
	s_nop 0
	v_pk_fma_f32 v[100:101], v[64:65], v[98:99], v[66:67]
	v_pk_add_f32 v[98:99], v[156:157], v[6:7] op_sel_hi:[1,0] neg_lo:[0,1] neg_hi:[0,1]
	v_and_b32_sdwa v3, v101, v244 dst_sel:DWORD dst_unused:UNUSED_PAD src0_sel:WORD_1 src1_sel:DWORD
	v_pk_mul_f32 v[6:7], v[6:7], v[98:99] op_sel:[1,0]
	v_and_b32_sdwa v98, v100, v244 dst_sel:DWORD dst_unused:UNUSED_PAD src0_sel:WORD_1 src1_sel:DWORD
	v_pk_fma_f32 v[6:7], v[0:1], v[6:7], v[4:5]
	v_add3_u32 v98, v100, v98, s67
	v_and_b32_e32 v99, 0xffff0000, v98
	v_and_b32_sdwa v98, v7, v244 dst_sel:DWORD dst_unused:UNUSED_PAD src0_sel:WORD_1 src1_sel:DWORD
	v_and_b32_sdwa v102, v6, v244 dst_sel:DWORD dst_unused:UNUSED_PAD src0_sel:WORD_1 src1_sel:DWORD
	v_add3_u32 v98, v7, v98, s67
	v_add3_u32 v3, v101, v3, s67
	v_add3_u32 v104, v6, v102, s67
	v_and_b32_e32 v110, 0xffff0000, v98
	v_or_b32_sdwa v103, v110, v3 dst_sel:DWORD dst_unused:UNUSED_PAD src0_sel:DWORD src1_sel:WORD_1
	v_or_b32_sdwa v102, v104, v99 dst_sel:DWORD dst_unused:UNUSED_PAD src0_sel:WORD_1 src1_sel:DWORD
	v_add_u32_e32 v98, v2, v106
	ds_write_b64 v98, v[102:103]
	v_and_b32_e32 v102, 0xffff0000, v104
	v_sub_u32_e32 v99, v100, v99
	v_and_b32_e32 v3, 0xffff0000, v3
	v_sub_u32_e32 v6, v6, v102
	v_add_u32_e32 v99, 0x80, v99
	v_sub_u32_e32 v3, v101, v3
	v_sub_u32_e32 v7, v7, v110
	v_add_u32_e32 v6, 0x80, v6
	v_ashrrev_i32_e32 v99, 8, v99
	v_add_u32_e32 v3, 0x80, v3
	v_add_u32_e32 v7, 0x80, v7
	v_ashrrev_i32_e32 v6, 8, v6
	v_min_i32_e32 v99, 0x7f, v99
	v_ashrrev_i32_e32 v3, 8, v3
	v_ashrrev_i32_e32 v7, 8, v7
	v_min_i32_e32 v6, 0x7f, v6
	v_min_i32_sdwa v3, v3, s69 dst_sel:WORD_1 dst_unused:UNUSED_PAD src0_sel:DWORD src1_sel:DWORD
	v_min_i32_e32 v7, 0x7f, v7
	v_lshlrev_b32_e32 v99, 8, v99
	v_and_b32_e32 v99, 0xff00, v99
	v_and_b32_e32 v3, 0xff0000, v3
	v_perm_b32 v6, v7, v6, s76
	v_or3_b32 v3, v6, v99, v3
	ds_write_b32 v14, v3 offset:16
	ds_read_b64 v[6:7], v15
	s_waitcnt lgkmcnt(0)
	v_pk_add_f32 v[100:101], v[126:127], v[6:7] op_sel_hi:[1,0] neg_lo:[0,1] neg_hi:[0,1]
	s_nop 0
	v_pk_mul_f32 v[100:101], v[6:7], v[100:101] op_sel:[1,0]
	v_pk_add_f32 v[102:103], v[124:125], v[6:7] op_sel_hi:[1,0] neg_lo:[0,1] neg_hi:[0,1]
	v_pk_fma_f32 v[100:101], v[64:65], v[100:101], v[66:67]
	v_pk_mul_f32 v[6:7], v[6:7], v[102:103] op_sel:[1,0]
	v_and_b32_sdwa v99, v100, v244 dst_sel:DWORD dst_unused:UNUSED_PAD src0_sel:WORD_1 src1_sel:DWORD
	v_pk_fma_f32 v[6:7], v[0:1], v[6:7], v[4:5]
	v_add3_u32 v99, v100, v99, s67
	v_and_b32_e32 v104, 0xffff0000, v99
	v_and_b32_sdwa v99, v7, v244 dst_sel:DWORD dst_unused:UNUSED_PAD src0_sel:WORD_1 src1_sel:DWORD
	v_and_b32_sdwa v3, v101, v244 dst_sel:DWORD dst_unused:UNUSED_PAD src0_sel:WORD_1 src1_sel:DWORD
	v_and_b32_sdwa v102, v6, v244 dst_sel:DWORD dst_unused:UNUSED_PAD src0_sel:WORD_1 src1_sel:DWORD
	v_add3_u32 v99, v7, v99, s67
	v_add3_u32 v3, v101, v3, s67
	v_add3_u32 v110, v6, v102, s67
	v_and_b32_e32 v111, 0xffff0000, v99
	v_or_b32_sdwa v103, v111, v3 dst_sel:DWORD dst_unused:UNUSED_PAD src0_sel:DWORD src1_sel:WORD_1
	v_or_b32_sdwa v102, v110, v104 dst_sel:DWORD dst_unused:UNUSED_PAD src0_sel:WORD_1 src1_sel:DWORD
	v_add_u32_e32 v99, v2, v107
	ds_write_b64 v99, v[102:103]
	v_and_b32_e32 v102, 0xffff0000, v110
	v_sub_u32_e32 v100, v100, v104
	v_and_b32_e32 v3, 0xffff0000, v3
	v_sub_u32_e32 v6, v6, v102
	v_add_u32_e32 v100, 0x80, v100
	v_sub_u32_e32 v3, v101, v3
	v_sub_u32_e32 v7, v7, v111
	v_add_u32_e32 v6, 0x80, v6
	v_ashrrev_i32_e32 v100, 8, v100
	v_add_u32_e32 v3, 0x80, v3
	v_add_u32_e32 v7, 0x80, v7
	v_ashrrev_i32_e32 v6, 8, v6
	v_min_i32_e32 v100, 0x7f, v100
	v_ashrrev_i32_e32 v3, 8, v3
	v_ashrrev_i32_e32 v7, 8, v7
	v_min_i32_e32 v6, 0x7f, v6
	v_min_i32_sdwa v3, v3, s69 dst_sel:WORD_1 dst_unused:UNUSED_PAD src0_sel:DWORD src1_sel:DWORD
	v_min_i32_e32 v7, 0x7f, v7
	v_lshlrev_b32_e32 v100, 8, v100
	v_and_b32_e32 v100, 0xff00, v100
	v_and_b32_e32 v3, 0xff0000, v3
	v_perm_b32 v6, v7, v6, s76
	v_or3_b32 v3, v6, v100, v3
	ds_write_b32 v20, v3 offset:16
	ds_read_b64 v[6:7], v21
	v_or_b32_e32 v104, 0x100, v109
	s_waitcnt lgkmcnt(0)
;     ...
;         _Pragma("unroll") for (int ai = 0; ai < 2; ++ai) {
;           _Pragma("unroll") for (int bj = 0; bj < 2; ++bj) _Pragma("unroll") for (int n = 0; n < 2; ++n) {
;             const int cc = bj * HALF + wc3 * 32 + n * 16 + fq3 * 4;
;             const float4 gm = *reinterpret_cast<const float4*>(g.gam + pn * BM + cc), bt = *reinterpret_cast<const float4*>(g.bet + pn * BM + cc);
;             _Pragma("unroll") for (int m = 0; m < 4; ++m) {
;               const int rr = wr3 * 64 + m * 16 + fr3;
;               const float2 ms = *reinterpret_cast<const float2*>(mr + (ai * HALF + rr) * 2);
;               f32x4 y = acc[ai][bj][m][n];
;               const float o0 = (y[0] - ms.x) * ms.y * gm.x + bt.x, o1 = (y[1] - ms.x) * ms.y * gm.y + bt.y;
;               const float o2 = (y[2] - ms.x) * ms.y * gm.z + bt.z, o3 = (y[3] - ms.x) * ms.y * gm.w + bt.w;
;               const unsigned h0 = f2bf(o0), h1 = f2bf(o1), h2 = f2bf(o2), h3 = f2bf(o3);
;               u32x2 ob; ob[0] = h0 | (h1 << 16); ob[1] = h2 | (h3 << 16);
;               *reinterpret_cast<u32x2*>(smem + (rr >> 1) * PIECE + (rr & 1) * 512 + cc * 2) = ob;
;               const int l0 = min(((int)__float_as_uint(o0) - (int)(h0 << 16) + 128) >> 8, 127);
;               const int l1 = min(((int)__float_as_uint(o1) - (int)(h1 << 16) + 128) >> 8, 127);
;               const int l2 = min(((int)__float_as_uint(o2) - (int)(h2 << 16) + 128) >> 8, 127);
;               const int l3 = min(((int)__float_as_uint(o3) - (int)(h3 << 16) + 128) >> 8, 127);
;               *reinterpret_cast<unsigned*>(smem + LOBASE + (rr >> 2) * PIECE + (rr & 3) * 256 + cc) =
;                   (unsigned)(l0 & 255) | ((unsigned)(l1 & 255) << 8) | ((unsigned)(l2 & 255) << 16) | ((unsigned)l3 << 24);
;             }
	v_pk_add_f32 v[100:101], v[154:155], v[6:7] op_sel_hi:[1,0] neg_lo:[0,1] neg_hi:[0,1]
	s_nop 0
	v_pk_mul_f32 v[100:101], v[6:7], v[100:101] op_sel:[1,0]
	s_nop 0
	v_pk_fma_f32 v[64:65], v[64:65], v[100:101], v[66:67]
	v_pk_add_f32 v[66:67], v[152:153], v[6:7] op_sel_hi:[1,0] neg_lo:[0,1] neg_hi:[0,1]
	v_and_b32_sdwa v3, v65, v244 dst_sel:DWORD dst_unused:UNUSED_PAD src0_sel:WORD_1 src1_sel:DWORD
	v_pk_mul_f32 v[6:7], v[6:7], v[66:67] op_sel:[1,0]
	v_add3_u32 v3, v65, v3, s67
	v_pk_fma_f32 v[0:1], v[0:1], v[6:7], v[4:5]
	v_and_b32_sdwa v4, v64, v244 dst_sel:DWORD dst_unused:UNUSED_PAD src0_sel:WORD_1 src1_sel:DWORD
	v_add3_u32 v4, v64, v4, s67
	v_and_b32_e32 v6, 0xffff0000, v4
	v_and_b32_sdwa v4, v1, v244 dst_sel:DWORD dst_unused:UNUSED_PAD src0_sel:WORD_1 src1_sel:DWORD
	v_and_b32_sdwa v5, v0, v244 dst_sel:DWORD dst_unused:UNUSED_PAD src0_sel:WORD_1 src1_sel:DWORD
	v_add3_u32 v4, v1, v4, s67
	v_add3_u32 v7, v0, v5, s67
	v_and_b32_e32 v66, 0xffff0000, v4
	v_add_u32_e32 v100, v2, v108
	v_and_b32_e32 v2, 0xffff0000, v7
	v_or_b32_sdwa v5, v66, v3 dst_sel:DWORD dst_unused:UNUSED_PAD src0_sel:DWORD src1_sel:WORD_1
	v_sub_u32_e32 v0, v0, v2
	v_sub_u32_e32 v2, v64, v6
	v_and_b32_e32 v3, 0xffff0000, v3
	v_add_u32_e32 v2, 0x80, v2
	v_sub_u32_e32 v3, v65, v3
	v_sub_u32_e32 v1, v1, v66
	v_add_u32_e32 v0, 0x80, v0
	v_ashrrev_i32_e32 v2, 8, v2
	v_add_u32_e32 v3, 0x80, v3
	v_add_u32_e32 v1, 0x80, v1
	v_ashrrev_i32_e32 v0, 8, v0
	v_min_i32_e32 v2, 0x7f, v2
	v_ashrrev_i32_e32 v3, 8, v3
	v_ashrrev_i32_e32 v1, 8, v1
	v_min_i32_e32 v0, 0x7f, v0
	v_min_i32_sdwa v3, v3, s69 dst_sel:WORD_1 dst_unused:UNUSED_PAD src0_sel:DWORD src1_sel:DWORD
	v_min_i32_e32 v1, 0x7f, v1
	v_lshlrev_b32_e32 v2, 8, v2
	v_and_b32_e32 v2, 0xff00, v2
	v_and_b32_e32 v3, 0xff0000, v3
	v_perm_b32 v0, v1, v0, s76
	v_or_b32_sdwa v4, v7, v6 dst_sel:DWORD dst_unused:UNUSED_PAD src0_sel:WORD_1 src1_sel:DWORD
	v_or3_b32 v0, v0, v2, v3
	ds_write_b64 v100, v[4:5]
	ds_write_b32 v22, v0 offset:16
	v_mov_b32_e32 v0, v204
	v_mov_b32_e32 v1, v205
	v_mov_b32_e32 v2, v206
	v_mov_b32_e32 v3, v207
	v_mov_b32_e32 v4, v240
	v_mov_b32_e32 v5, v241
	v_mov_b32_e32 v6, v242
	v_mov_b32_e32 v7, v243
	ds_read_b64 v[102:103], v71
	v_add_u32_e32 v101, v104, v105
	s_waitcnt lgkmcnt(0)
	v_pk_add_f32 v[110:111], v[230:231], v[102:103] op_sel_hi:[1,0] neg_lo:[0,1] neg_hi:[0,1]
	s_nop 0
	v_pk_mul_f32 v[110:111], v[102:103], v[110:111] op_sel:[1,0]
	v_pk_add_f32 v[124:125], v[228:229], v[102:103] op_sel_hi:[1,0] neg_lo:[0,1] neg_hi:[0,1]
	v_mov_b32_e32 v64, v1
	v_mov_b32_e32 v65, v2
	v_mov_b32_e32 v66, v5
	v_mov_b32_e32 v67, v6
	v_pk_fma_f32 v[110:111], v[64:65], v[110:111], v[66:67]
	v_pk_mul_f32 v[102:103], v[102:103], v[124:125] op_sel:[1,0]
	v_mov_b32_e32 v1, v3
	v_mov_b32_e32 v5, v7
	v_and_b32_sdwa v6, v111, v244 dst_sel:DWORD dst_unused:UNUSED_PAD src0_sel:WORD_1 src1_sel:DWORD
	v_and_b32_sdwa v7, v110, v244 dst_sel:DWORD dst_unused:UNUSED_PAD src0_sel:WORD_1 src1_sel:DWORD
	v_pk_fma_f32 v[2:3], v[0:1], v[102:103], v[4:5]
	v_add3_u32 v102, v111, v6, s67
	v_add3_u32 v6, v110, v7, s67
	v_and_b32_e32 v103, 0xffff0000, v6
	v_and_b32_sdwa v6, v3, v244 dst_sel:DWORD dst_unused:UNUSED_PAD src0_sel:WORD_1 src1_sel:DWORD
	v_and_b32_sdwa v7, v2, v244 dst_sel:DWORD dst_unused:UNUSED_PAD src0_sel:WORD_1 src1_sel:DWORD
	v_add3_u32 v6, v3, v6, s67
	v_add3_u32 v124, v2, v7, s67
	v_and_b32_e32 v125, 0xffff0000, v6
	v_or_b32_sdwa v7, v125, v102 dst_sel:DWORD dst_unused:UNUSED_PAD src0_sel:DWORD src1_sel:WORD_1
	v_or_b32_sdwa v6, v124, v103 dst_sel:DWORD dst_unused:UNUSED_PAD src0_sel:WORD_1 src1_sel:DWORD
	ds_write_b64 v101, v[6:7]
	v_and_b32_e32 v6, 0xffff0000, v124
	v_sub_u32_e32 v2, v2, v6
	v_sub_u32_e32 v6, v110, v103
	v_and_b32_e32 v7, 0xffff0000, v102
	v_add_u32_e32 v6, 0x80, v6
	v_sub_u32_e32 v7, v111, v7
	v_sub_u32_e32 v3, v3, v125
	v_add_u32_e32 v2, 0x80, v2
	v_ashrrev_i32_e32 v6, 8, v6
	v_add_u32_e32 v7, 0x80, v7
	v_add_u32_e32 v3, 0x80, v3
	v_ashrrev_i32_e32 v2, 8, v2
	v_min_i32_e32 v6, 0x7f, v6
	v_ashrrev_i32_e32 v7, 8, v7
	v_ashrrev_i32_e32 v3, 8, v3
	v_min_i32_e32 v2, 0x7f, v2
	v_min_i32_sdwa v7, v7, s69 dst_sel:WORD_1 dst_unused:UNUSED_PAD src0_sel:DWORD src1_sel:DWORD
	v_min_i32_e32 v3, 0x7f, v3
	v_lshlrev_b32_e32 v6, 8, v6
	v_and_b32_e32 v6, 0xff00, v6
	v_and_b32_e32 v7, 0xff0000, v7
	v_perm_b32 v2, v3, v2, s76
	v_or3_b32 v2, v2, v6, v7
	ds_write_b32 v12, v2 offset:128
	ds_read_b64 v[2:3], v13
	s_waitcnt lgkmcnt(0)
	v_pk_add_f32 v[6:7], v[150:151], v[2:3] op_sel_hi:[1,0] neg_lo:[0,1] neg_hi:[0,1]
	s_nop 0
	v_pk_mul_f32 v[6:7], v[2:3], v[6:7] op_sel:[1,0]
	v_pk_add_f32 v[102:103], v[148:149], v[2:3] op_sel_hi:[1,0] neg_lo:[0,1] neg_hi:[0,1]
	v_pk_fma_f32 v[6:7], v[64:65], v[6:7], v[66:67]
	v_pk_mul_f32 v[2:3], v[2:3], v[102:103] op_sel:[1,0]
	v_and_b32_sdwa v102, v7, v244 dst_sel:DWORD dst_unused:UNUSED_PAD src0_sel:WORD_1 src1_sel:DWORD
	v_and_b32_sdwa v103, v6, v244 dst_sel:DWORD dst_unused:UNUSED_PAD src0_sel:WORD_1 src1_sel:DWORD
	v_pk_fma_f32 v[2:3], v[0:1], v[2:3], v[4:5]
	v_add3_u32 v124, v7, v102, s67
	v_add3_u32 v102, v6, v103, s67
	v_and_b32_e32 v103, 0xffff0000, v102
	v_and_b32_sdwa v102, v3, v244 dst_sel:DWORD dst_unused:UNUSED_PAD src0_sel:WORD_1 src1_sel:DWORD
	v_and_b32_sdwa v110, v2, v244 dst_sel:DWORD dst_unused:UNUSED_PAD src0_sel:WORD_1 src1_sel:DWORD
	v_add3_u32 v102, v3, v102, s67
	v_add3_u32 v125, v2, v110, s67
	v_and_b32_e32 v126, 0xffff0000, v102
	v_or_b32_sdwa v111, v126, v124 dst_sel:DWORD dst_unused:UNUSED_PAD src0_sel:DWORD src1_sel:WORD_1
	v_or_b32_sdwa v110, v125, v103 dst_sel:DWORD dst_unused:UNUSED_PAD src0_sel:WORD_1 src1_sel:DWORD
	v_add_u32_e32 v102, v104, v106
	ds_write_b64 v102, v[110:111]
	v_and_b32_e32 v110, 0xffff0000, v125
	v_sub_u32_e32 v6, v6, v103
	v_and_b32_e32 v103, 0xffff0000, v124
	v_sub_u32_e32 v2, v2, v110
	v_add_u32_e32 v6, 0x80, v6
	v_sub_u32_e32 v7, v7, v103
	v_sub_u32_e32 v3, v3, v126
	v_add_u32_e32 v2, 0x80, v2
	v_ashrrev_i32_e32 v6, 8, v6
	v_add_u32_e32 v7, 0x80, v7
	v_add_u32_e32 v3, 0x80, v3
	v_ashrrev_i32_e32 v2, 8, v2
	v_min_i32_e32 v6, 0x7f, v6
	v_ashrrev_i32_e32 v7, 8, v7
	v_ashrrev_i32_e32 v3, 8, v3
	v_min_i32_e32 v2, 0x7f, v2
	v_min_i32_sdwa v7, v7, s69 dst_sel:WORD_1 dst_unused:UNUSED_PAD src0_sel:DWORD src1_sel:DWORD
	v_min_i32_e32 v3, 0x7f, v3
	v_lshlrev_b32_e32 v6, 8, v6
	v_and_b32_e32 v6, 0xff00, v6
	v_and_b32_e32 v7, 0xff0000, v7
	v_perm_b32 v2, v3, v2, s76
	v_or3_b32 v2, v2, v6, v7
	ds_write_b32 v14, v2 offset:128
	ds_read_b64 v[2:3], v15
	s_waitcnt lgkmcnt(0)
;     ...
;         _Pragma("unroll") for (int ai = 0; ai < 2; ++ai) {
;           _Pragma("unroll") for (int bj = 0; bj < 2; ++bj) _Pragma("unroll") for (int n = 0; n < 2; ++n) {
;             const int cc = bj * HALF + wc3 * 32 + n * 16 + fq3 * 4;
;             const float4 gm = *reinterpret_cast<const float4*>(g.gam + pn * BM + cc), bt = *reinterpret_cast<const float4*>(g.bet + pn * BM + cc);
;             _Pragma("unroll") for (int m = 0; m < 4; ++m) {
;               const int rr = wr3 * 64 + m * 16 + fr3;
;               const float2 ms = *reinterpret_cast<const float2*>(mr + (ai * HALF + rr) * 2);
;               f32x4 y = acc[ai][bj][m][n];
;               const float o0 = (y[0] - ms.x) * ms.y * gm.x + bt.x, o1 = (y[1] - ms.x) * ms.y * gm.y + bt.y;
;               const float o2 = (y[2] - ms.x) * ms.y * gm.z + bt.z, o3 = (y[3] - ms.x) * ms.y * gm.w + bt.w;
;               const unsigned h0 = f2bf(o0), h1 = f2bf(o1), h2 = f2bf(o2), h3 = f2bf(o3);
;               u32x2 ob; ob[0] = h0 | (h1 << 16); ob[1] = h2 | (h3 << 16);
;               *reinterpret_cast<u32x2*>(smem + (rr >> 1) * PIECE + (rr & 1) * 512 + cc * 2) = ob;
;               const int l0 = min(((int)__float_as_uint(o0) - (int)(h0 << 16) + 128) >> 8, 127);
;               const int l1 = min(((int)__float_as_uint(o1) - (int)(h1 << 16) + 128) >> 8, 127);
;               const int l2 = min(((int)__float_as_uint(o2) - (int)(h2 << 16) + 128) >> 8, 127);
;               const int l3 = min(((int)__float_as_uint(o3) - (int)(h3 << 16) + 128) >> 8, 127);
;               *reinterpret_cast<unsigned*>(smem + LOBASE + (rr >> 2) * PIECE + (rr & 3) * 256 + cc) =
;                   (unsigned)(l0 & 255) | ((unsigned)(l1 & 255) << 8) | ((unsigned)(l2 & 255) << 16) | ((unsigned)l3 << 24);
;             }
	v_pk_add_f32 v[6:7], v[118:119], v[2:3] op_sel_hi:[1,0] neg_lo:[0,1] neg_hi:[0,1]
	s_nop 0
	v_pk_mul_f32 v[6:7], v[2:3], v[6:7] op_sel:[1,0]
	v_pk_add_f32 v[110:111], v[116:117], v[2:3] op_sel_hi:[1,0] neg_lo:[0,1] neg_hi:[0,1]
	v_pk_fma_f32 v[6:7], v[64:65], v[6:7], v[66:67]
	v_pk_mul_f32 v[2:3], v[2:3], v[110:111] op_sel:[1,0]
	v_and_b32_sdwa v103, v7, v244 dst_sel:DWORD dst_unused:UNUSED_PAD src0_sel:WORD_1 src1_sel:DWORD
	v_and_b32_sdwa v110, v6, v244 dst_sel:DWORD dst_unused:UNUSED_PAD src0_sel:WORD_1 src1_sel:DWORD
	v_pk_fma_f32 v[2:3], v[0:1], v[2:3], v[4:5]
	v_add3_u32 v116, v7, v103, s67
	v_add3_u32 v103, v6, v110, s67
	v_and_b32_e32 v117, 0xffff0000, v103
	v_and_b32_sdwa v103, v3, v244 dst_sel:DWORD dst_unused:UNUSED_PAD src0_sel:WORD_1 src1_sel:DWORD
	v_and_b32_sdwa v110, v2, v244 dst_sel:DWORD dst_unused:UNUSED_PAD src0_sel:WORD_1 src1_sel:DWORD
	v_add3_u32 v103, v3, v103, s67
	v_add3_u32 v118, v2, v110, s67
	v_and_b32_e32 v119, 0xffff0000, v103
	v_or_b32_sdwa v111, v119, v116 dst_sel:DWORD dst_unused:UNUSED_PAD src0_sel:DWORD src1_sel:WORD_1
	v_or_b32_sdwa v110, v118, v117 dst_sel:DWORD dst_unused:UNUSED_PAD src0_sel:WORD_1 src1_sel:DWORD
	v_add_u32_e32 v103, v104, v107
	ds_write_b64 v103, v[110:111]
	v_and_b32_e32 v110, 0xffff0000, v118
	v_sub_u32_e32 v2, v2, v110
	v_sub_u32_e32 v6, v6, v117
	v_and_b32_e32 v110, 0xffff0000, v116
	v_add_u32_e32 v6, 0x80, v6
	v_sub_u32_e32 v7, v7, v110
	v_sub_u32_e32 v3, v3, v119
	v_add_u32_e32 v2, 0x80, v2
	v_ashrrev_i32_e32 v6, 8, v6
	v_add_u32_e32 v7, 0x80, v7
	v_add_u32_e32 v3, 0x80, v3
	v_ashrrev_i32_e32 v2, 8, v2
	v_min_i32_e32 v6, 0x7f, v6
	v_ashrrev_i32_e32 v7, 8, v7
	v_ashrrev_i32_e32 v3, 8, v3
	v_min_i32_e32 v2, 0x7f, v2
	v_min_i32_sdwa v7, v7, s69 dst_sel:WORD_1 dst_unused:UNUSED_PAD src0_sel:DWORD src1_sel:DWORD
	v_min_i32_e32 v3, 0x7f, v3
	v_lshlrev_b32_e32 v6, 8, v6
	v_and_b32_e32 v6, 0xff00, v6
	v_and_b32_e32 v7, 0xff0000, v7
	v_perm_b32 v2, v3, v2, s76
	v_or3_b32 v2, v2, v6, v7
	ds_write_b32 v20, v2 offset:128
	ds_read_b64 v[2:3], v21
	v_add_u32_e32 v104, v104, v108
	s_waitcnt lgkmcnt(0)
	v_pk_add_f32 v[6:7], v[122:123], v[2:3] op_sel_hi:[1,0] neg_lo:[0,1] neg_hi:[0,1]
	s_nop 0
	v_pk_mul_f32 v[6:7], v[2:3], v[6:7] op_sel:[1,0]
	s_nop 0
	v_pk_fma_f32 v[6:7], v[64:65], v[6:7], v[66:67]
	v_pk_add_f32 v[64:65], v[120:121], v[2:3] op_sel_hi:[1,0] neg_lo:[0,1] neg_hi:[0,1]
	s_nop 0
	v_pk_mul_f32 v[2:3], v[2:3], v[64:65] op_sel:[1,0]
	s_nop 0
	v_pk_fma_f32 v[0:1], v[0:1], v[2:3], v[4:5]
	v_and_b32_sdwa v2, v7, v244 dst_sel:DWORD dst_unused:UNUSED_PAD src0_sel:WORD_1 src1_sel:DWORD
	v_and_b32_sdwa v3, v6, v244 dst_sel:DWORD dst_unused:UNUSED_PAD src0_sel:WORD_1 src1_sel:DWORD
	v_add3_u32 v4, v7, v2, s67
	v_add3_u32 v2, v6, v3, s67
	v_and_b32_e32 v5, 0xffff0000, v2
	v_and_b32_sdwa v2, v1, v244 dst_sel:DWORD dst_unused:UNUSED_PAD src0_sel:WORD_1 src1_sel:DWORD
	v_and_b32_sdwa v3, v0, v244 dst_sel:DWORD dst_unused:UNUSED_PAD src0_sel:WORD_1 src1_sel:DWORD
	v_add3_u32 v2, v1, v2, s67
	v_add3_u32 v64, v0, v3, s67
	v_and_b32_e32 v65, 0xffff0000, v2
	v_or_b32_sdwa v3, v65, v4 dst_sel:DWORD dst_unused:UNUSED_PAD src0_sel:DWORD src1_sel:WORD_1
	v_or_b32_sdwa v2, v64, v5 dst_sel:DWORD dst_unused:UNUSED_PAD src0_sel:WORD_1 src1_sel:DWORD
	ds_write_b64 v104, v[2:3]
	v_and_b32_e32 v2, 0xffff0000, v64
	v_sub_u32_e32 v0, v0, v2
	v_sub_u32_e32 v2, v6, v5
	v_and_b32_e32 v3, 0xffff0000, v4
	v_add_u32_e32 v2, 0x80, v2
	v_sub_u32_e32 v3, v7, v3
	v_sub_u32_e32 v1, v1, v65
	v_add_u32_e32 v0, 0x80, v0
	v_ashrrev_i32_e32 v2, 8, v2
	v_add_u32_e32 v3, 0x80, v3
	v_add_u32_e32 v1, 0x80, v1
	v_ashrrev_i32_e32 v0, 8, v0
	v_min_i32_e32 v2, 0x7f, v2
	v_ashrrev_i32_e32 v3, 8, v3
	v_ashrrev_i32_e32 v1, 8, v1
	v_min_i32_e32 v0, 0x7f, v0
	v_min_i32_sdwa v3, v3, s69 dst_sel:WORD_1 dst_unused:UNUSED_PAD src0_sel:DWORD src1_sel:DWORD
	v_min_i32_e32 v1, 0x7f, v1
	v_lshlrev_b32_e32 v2, 8, v2
	v_and_b32_e32 v2, 0xff00, v2
	v_and_b32_e32 v3, 0xff0000, v3
	v_perm_b32 v0, v1, v0, s76
	v_or3_b32 v0, v0, v2, v3
	ds_write_b32 v22, v0 offset:128
	v_mov_b32_e32 v0, v208
	v_mov_b32_e32 v1, v209
	v_mov_b32_e32 v2, v210
	v_mov_b32_e32 v3, v211
	v_mov_b32_e32 v4, v248
	v_mov_b32_e32 v5, v249
	v_mov_b32_e32 v6, v250
	v_mov_b32_e32 v7, v251
	ds_read_b64 v[110:111], v71
	s_waitcnt lgkmcnt(0)
	v_pk_add_f32 v[116:117], v[226:227], v[110:111] op_sel_hi:[1,0] neg_lo:[0,1] neg_hi:[0,1]
	v_pk_add_f32 v[118:119], v[224:225], v[110:111] op_sel_hi:[1,0] neg_lo:[0,1] neg_hi:[0,1]
	v_pk_mul_f32 v[116:117], v[110:111], v[116:117] op_sel:[1,0]
	v_pk_mul_f32 v[110:111], v[110:111], v[118:119] op_sel:[1,0]
	v_mov_b32_e32 v64, v1
	v_mov_b32_e32 v65, v2
	v_mov_b32_e32 v66, v5
	v_mov_b32_e32 v67, v6
	v_mov_b32_e32 v1, v3
	v_mov_b32_e32 v5, v7
	v_pk_fma_f32 v[116:117], v[64:65], v[116:117], v[66:67]
	v_pk_fma_f32 v[6:7], v[0:1], v[110:111], v[4:5]
	v_or_b32_e32 v2, 0x120, v109
	v_and_b32_sdwa v109, v116, v244 dst_sel:DWORD dst_unused:UNUSED_PAD src0_sel:WORD_1 src1_sel:DWORD
	v_and_b32_sdwa v110, v7, v244 dst_sel:DWORD dst_unused:UNUSED_PAD src0_sel:WORD_1 src1_sel:DWORD
	v_and_b32_sdwa v3, v117, v244 dst_sel:DWORD dst_unused:UNUSED_PAD src0_sel:WORD_1 src1_sel:DWORD
	v_add3_u32 v109, v116, v109, s67
	v_and_b32_sdwa v111, v6, v244 dst_sel:DWORD dst_unused:UNUSED_PAD src0_sel:WORD_1 src1_sel:DWORD
	v_add3_u32 v110, v7, v110, s67
	v_add3_u32 v3, v117, v3, s67
	v_and_b32_e32 v109, 0xffff0000, v109
	v_add3_u32 v118, v6, v111, s67
	v_and_b32_e32 v119, 0xffff0000, v110
	v_or_b32_sdwa v111, v119, v3 dst_sel:DWORD dst_unused:UNUSED_PAD src0_sel:DWORD src1_sel:WORD_1
	v_or_b32_sdwa v110, v118, v109 dst_sel:DWORD dst_unused:UNUSED_PAD src0_sel:WORD_1 src1_sel:DWORD
	v_add_u32_e32 v105, v2, v105
	ds_write_b64 v105, v[110:111]
	v_and_b32_e32 v110, 0xffff0000, v118
	v_sub_u32_e32 v109, v116, v109
	v_and_b32_e32 v3, 0xffff0000, v3
	v_sub_u32_e32 v6, v6, v110
	v_add_u32_e32 v109, 0x80, v109
	v_sub_u32_e32 v3, v117, v3
	v_sub_u32_e32 v7, v7, v119
	v_add_u32_e32 v6, 0x80, v6
	v_ashrrev_i32_e32 v109, 8, v109
	v_add_u32_e32 v3, 0x80, v3
	v_add_u32_e32 v7, 0x80, v7
	v_ashrrev_i32_e32 v6, 8, v6
	v_min_i32_e32 v109, 0x7f, v109
	v_ashrrev_i32_e32 v3, 8, v3
	v_ashrrev_i32_e32 v7, 8, v7
	v_min_i32_e32 v6, 0x7f, v6
	v_min_i32_sdwa v3, v3, s69 dst_sel:WORD_1 dst_unused:UNUSED_PAD src0_sel:DWORD src1_sel:DWORD
	v_min_i32_e32 v7, 0x7f, v7
	v_lshlrev_b32_e32 v109, 8, v109
	v_and_b32_e32 v109, 0xff00, v109
	v_and_b32_e32 v3, 0xff0000, v3
	v_perm_b32 v6, v7, v6, s76
	v_or3_b32 v3, v6, v109, v3
	ds_write_b32 v12, v3 offset:144
	ds_read_b64 v[6:7], v13
	v_add_u32_e32 v106, v2, v106
	v_add_u32_e32 v107, v2, v107
	s_waitcnt lgkmcnt(0)
; #define WAIT_L(n) asm volatile("s_waitcnt lgkmcnt(" #n ")" ::: "memory")
; #define BAR __builtin_amdgcn_s_barrier()
;     ...
;             _Pragma("unroll") for (int m = 0; m < 4; ++m) {
;               const int rr = wr3 * 64 + m * 16 + fr3;
;               const float2 ms = *reinterpret_cast<const float2*>(mr + (ai * HALF + rr) * 2);
;               f32x4 y = acc[ai][bj][m][n];
;               const float o0 = (y[0] - ms.x) * ms.y * gm.x + bt.x, o1 = (y[1] - ms.x) * ms.y * gm.y + bt.y;
;               const float o2 = (y[2] - ms.x) * ms.y * gm.z + bt.z, o3 = (y[3] - ms.x) * ms.y * gm.w + bt.w;
;               const unsigned h0 = f2bf(o0), h1 = f2bf(o1), h2 = f2bf(o2), h3 = f2bf(o3);
;               u32x2 ob; ob[0] = h0 | (h1 << 16); ob[1] = h2 | (h3 << 16);
;               *reinterpret_cast<u32x2*>(smem + (rr >> 1) * PIECE + (rr & 1) * 512 + cc * 2) = ob;
;               const int l0 = min(((int)__float_as_uint(o0) - (int)(h0 << 16) + 128) >> 8, 127);
;               const int l1 = min(((int)__float_as_uint(o1) - (int)(h1 << 16) + 128) >> 8, 127);
;               const int l2 = min(((int)__float_as_uint(o2) - (int)(h2 << 16) + 128) >> 8, 127);
;               const int l3 = min(((int)__float_as_uint(o3) - (int)(h3 << 16) + 128) >> 8, 127);
;               *reinterpret_cast<unsigned*>(smem + LOBASE + (rr >> 2) * PIECE + (rr & 3) * 256 + cc) =
;                   (unsigned)(l0 & 255) | ((unsigned)(l1 & 255) << 8) | ((unsigned)(l2 & 255) << 16) | ((unsigned)l3 << 24);
;             }
;           }
;           WAIT_L(0); BAR;
	v_pk_add_f32 v[110:111], v[146:147], v[6:7] op_sel_hi:[1,0] neg_lo:[0,1] neg_hi:[0,1]
	v_pk_add_f32 v[116:117], v[144:145], v[6:7] op_sel_hi:[1,0] neg_lo:[0,1] neg_hi:[0,1]
	v_pk_mul_f32 v[110:111], v[6:7], v[110:111] op_sel:[1,0]
	v_pk_mul_f32 v[6:7], v[6:7], v[116:117] op_sel:[1,0]
	v_pk_fma_f32 v[110:111], v[64:65], v[110:111], v[66:67]
	v_pk_fma_f32 v[6:7], v[0:1], v[6:7], v[4:5]
	v_and_b32_sdwa v109, v110, v244 dst_sel:DWORD dst_unused:UNUSED_PAD src0_sel:WORD_1 src1_sel:DWORD
	v_and_b32_sdwa v116, v7, v244 dst_sel:DWORD dst_unused:UNUSED_PAD src0_sel:WORD_1 src1_sel:DWORD
	v_and_b32_sdwa v3, v111, v244 dst_sel:DWORD dst_unused:UNUSED_PAD src0_sel:WORD_1 src1_sel:DWORD
	v_add3_u32 v109, v110, v109, s67
	v_and_b32_sdwa v117, v6, v244 dst_sel:DWORD dst_unused:UNUSED_PAD src0_sel:WORD_1 src1_sel:DWORD
	v_add3_u32 v116, v7, v116, s67
	v_add3_u32 v3, v111, v3, s67
	v_and_b32_e32 v109, 0xffff0000, v109
	v_add3_u32 v118, v6, v117, s67
	v_and_b32_e32 v119, 0xffff0000, v116
	v_or_b32_sdwa v117, v119, v3 dst_sel:DWORD dst_unused:UNUSED_PAD src0_sel:DWORD src1_sel:WORD_1
	v_or_b32_sdwa v116, v118, v109 dst_sel:DWORD dst_unused:UNUSED_PAD src0_sel:WORD_1 src1_sel:DWORD
	ds_write_b64 v106, v[116:117]
	v_and_b32_e32 v116, 0xffff0000, v118
	v_sub_u32_e32 v109, v110, v109
	v_and_b32_e32 v3, 0xffff0000, v3
	v_sub_u32_e32 v6, v6, v116
	v_add_u32_e32 v109, 0x80, v109
	v_sub_u32_e32 v3, v111, v3
	v_sub_u32_e32 v7, v7, v119
	v_add_u32_e32 v6, 0x80, v6
	v_ashrrev_i32_e32 v109, 8, v109
	v_add_u32_e32 v3, 0x80, v3
	v_add_u32_e32 v7, 0x80, v7
	v_ashrrev_i32_e32 v6, 8, v6
	v_min_i32_e32 v109, 0x7f, v109
	v_ashrrev_i32_e32 v3, 8, v3
	v_ashrrev_i32_e32 v7, 8, v7
	v_min_i32_e32 v6, 0x7f, v6
	v_min_i32_sdwa v3, v3, s69 dst_sel:WORD_1 dst_unused:UNUSED_PAD src0_sel:DWORD src1_sel:DWORD
	v_min_i32_e32 v7, 0x7f, v7
	v_lshlrev_b32_e32 v109, 8, v109
	v_and_b32_e32 v109, 0xff00, v109
	v_and_b32_e32 v3, 0xff0000, v3
	v_perm_b32 v6, v7, v6, s76
	v_or3_b32 v3, v6, v109, v3
	ds_write_b32 v14, v3 offset:144
	ds_read_b64 v[6:7], v15
	s_waitcnt lgkmcnt(0)
	v_pk_add_f32 v[110:111], v[114:115], v[6:7] op_sel_hi:[1,0] neg_lo:[0,1] neg_hi:[0,1]
	v_pk_add_f32 v[112:113], v[112:113], v[6:7] op_sel_hi:[1,0] neg_lo:[0,1] neg_hi:[0,1]
	v_pk_mul_f32 v[110:111], v[6:7], v[110:111] op_sel:[1,0]
	v_pk_mul_f32 v[6:7], v[6:7], v[112:113] op_sel:[1,0]
	v_pk_fma_f32 v[110:111], v[64:65], v[110:111], v[66:67]
	v_pk_fma_f32 v[6:7], v[0:1], v[6:7], v[4:5]
	v_and_b32_sdwa v109, v110, v244 dst_sel:DWORD dst_unused:UNUSED_PAD src0_sel:WORD_1 src1_sel:DWORD
	v_and_b32_sdwa v112, v7, v244 dst_sel:DWORD dst_unused:UNUSED_PAD src0_sel:WORD_1 src1_sel:DWORD
	v_and_b32_sdwa v3, v111, v244 dst_sel:DWORD dst_unused:UNUSED_PAD src0_sel:WORD_1 src1_sel:DWORD
	v_add3_u32 v109, v110, v109, s67
	v_and_b32_sdwa v113, v6, v244 dst_sel:DWORD dst_unused:UNUSED_PAD src0_sel:WORD_1 src1_sel:DWORD
	v_add3_u32 v112, v7, v112, s67
	v_add3_u32 v3, v111, v3, s67
	v_and_b32_e32 v109, 0xffff0000, v109
	v_add3_u32 v114, v6, v113, s67
	v_and_b32_e32 v115, 0xffff0000, v112
	v_or_b32_sdwa v113, v115, v3 dst_sel:DWORD dst_unused:UNUSED_PAD src0_sel:DWORD src1_sel:WORD_1
	v_or_b32_sdwa v112, v114, v109 dst_sel:DWORD dst_unused:UNUSED_PAD src0_sel:WORD_1 src1_sel:DWORD
	ds_write_b64 v107, v[112:113]
	v_and_b32_e32 v112, 0xffff0000, v114
	v_sub_u32_e32 v109, v110, v109
	v_and_b32_e32 v3, 0xffff0000, v3
	v_sub_u32_e32 v6, v6, v112
	v_add_u32_e32 v109, 0x80, v109
	v_sub_u32_e32 v3, v111, v3
	v_sub_u32_e32 v7, v7, v115
	v_add_u32_e32 v6, 0x80, v6
	v_ashrrev_i32_e32 v109, 8, v109
	v_add_u32_e32 v3, 0x80, v3
	v_add_u32_e32 v7, 0x80, v7
	v_ashrrev_i32_e32 v6, 8, v6
	v_min_i32_e32 v109, 0x7f, v109
	v_ashrrev_i32_e32 v3, 8, v3
	v_ashrrev_i32_e32 v7, 8, v7
	v_min_i32_e32 v6, 0x7f, v6
	v_min_i32_sdwa v3, v3, s69 dst_sel:WORD_1 dst_unused:UNUSED_PAD src0_sel:DWORD src1_sel:DWORD
	v_min_i32_e32 v7, 0x7f, v7
	v_lshlrev_b32_e32 v109, 8, v109
	v_and_b32_e32 v109, 0xff00, v109
	v_and_b32_e32 v3, 0xff0000, v3
	v_perm_b32 v6, v7, v6, s76
	v_or3_b32 v3, v6, v109, v3
	ds_write_b32 v20, v3 offset:144
	ds_read_b64 v[6:7], v21
	v_or_b32_e32 v109, 0xa000, v70
	v_or_b32_e32 v110, 0xc000, v70
	v_or_b32_e32 v111, 0xe000, v70
	v_or_b32_e32 v112, 0x2000, v68
	s_waitcnt lgkmcnt(0)
	v_pk_add_f32 v[90:91], v[90:91], v[6:7] op_sel_hi:[1,0] neg_lo:[0,1] neg_hi:[0,1]
	v_or_b32_e32 v113, 0x4000, v68
	v_pk_mul_f32 v[90:91], v[6:7], v[90:91] op_sel:[1,0]
	v_or_b32_e32 v114, 0x6000, v68
	v_pk_fma_f32 v[64:65], v[64:65], v[90:91], v[66:67]
	v_pk_add_f32 v[66:67], v[88:89], v[6:7] op_sel_hi:[1,0] neg_lo:[0,1] neg_hi:[0,1]
	v_and_b32_sdwa v3, v65, v244 dst_sel:DWORD dst_unused:UNUSED_PAD src0_sel:WORD_1 src1_sel:DWORD
	v_pk_mul_f32 v[6:7], v[6:7], v[66:67] op_sel:[1,0]
	v_add3_u32 v3, v65, v3, s67
	v_pk_fma_f32 v[0:1], v[0:1], v[6:7], v[4:5]
	v_and_b32_sdwa v4, v64, v244 dst_sel:DWORD dst_unused:UNUSED_PAD src0_sel:WORD_1 src1_sel:DWORD
	v_add3_u32 v4, v64, v4, s67
	v_and_b32_e32 v6, 0xffff0000, v4
	v_and_b32_sdwa v4, v1, v244 dst_sel:DWORD dst_unused:UNUSED_PAD src0_sel:WORD_1 src1_sel:DWORD
	v_and_b32_sdwa v5, v0, v244 dst_sel:DWORD dst_unused:UNUSED_PAD src0_sel:WORD_1 src1_sel:DWORD
	v_add3_u32 v4, v1, v4, s67
	v_add3_u32 v7, v0, v5, s67
	v_and_b32_e32 v66, 0xffff0000, v4
	v_add_u32_e32 v88, v2, v108
	v_and_b32_e32 v2, 0xffff0000, v7
	v_or_b32_sdwa v5, v66, v3 dst_sel:DWORD dst_unused:UNUSED_PAD src0_sel:DWORD src1_sel:WORD_1
	v_sub_u32_e32 v0, v0, v2
	v_sub_u32_e32 v2, v64, v6
	v_and_b32_e32 v3, 0xffff0000, v3
	v_add_u32_e32 v2, 0x80, v2
	v_sub_u32_e32 v3, v65, v3
	v_sub_u32_e32 v1, v1, v66
	v_add_u32_e32 v0, 0x80, v0
	v_ashrrev_i32_e32 v2, 8, v2
	v_add_u32_e32 v3, 0x80, v3
	v_add_u32_e32 v1, 0x80, v1
	v_ashrrev_i32_e32 v0, 8, v0
	v_min_i32_e32 v2, 0x7f, v2
	v_ashrrev_i32_e32 v3, 8, v3
	v_ashrrev_i32_e32 v1, 8, v1
	v_min_i32_e32 v0, 0x7f, v0
	v_min_i32_sdwa v3, v3, s69 dst_sel:WORD_1 dst_unused:UNUSED_PAD src0_sel:DWORD src1_sel:DWORD
	v_min_i32_e32 v1, 0x7f, v1
	v_lshlrev_b32_e32 v2, 8, v2
	v_and_b32_e32 v2, 0xff00, v2
	v_and_b32_e32 v3, 0xff0000, v3
	v_perm_b32 v0, v1, v0, s76
	v_or_b32_sdwa v4, v7, v6 dst_sel:DWORD dst_unused:UNUSED_PAD src0_sel:WORD_1 src1_sel:DWORD
	v_or3_b32 v0, v0, v2, v3
	ds_write_b64 v88, v[4:5]
	ds_write_b32 v22, v0 offset:144
	s_waitcnt lgkmcnt(0)
	s_barrier
;     ...
;         _Pragma("unroll") for (int ai = 0; ai < 2; ++ai) {
;           _Pragma("unroll") for (int bj = 0; bj < 2; ++bj) _Pragma("unroll") for (int n = 0; n < 2; ++n) {
;             const int cc = bj * HALF + wc3 * 32 + n * 16 + fq3 * 4;
;             const float4 gm = *reinterpret_cast<const float4*>(g.gam + pn * BM + cc), bt = *reinterpret_cast<const float4*>(g.bet + pn * BM + cc);
;             _Pragma("unroll") for (int m = 0; m < 4; ++m) {
;               const int rr = wr3 * 64 + m * 16 + fr3;
;               const float2 ms = *reinterpret_cast<const float2*>(mr + (ai * HALF + rr) * 2);
;               f32x4 y = acc[ai][bj][m][n];
;               const float o0 = (y[0] - ms.x) * ms.y * gm.x + bt.x, o1 = (y[1] - ms.x) * ms.y * gm.y + bt.y;
;               const float o2 = (y[2] - ms.x) * ms.y * gm.z + bt.z, o3 = (y[3] - ms.x) * ms.y * gm.w + bt.w;
;               const unsigned h0 = f2bf(o0), h1 = f2bf(o1), h2 = f2bf(o2), h3 = f2bf(o3);
;               u32x2 ob; ob[0] = h0 | (h1 << 16); ob[1] = h2 | (h3 << 16);
;               *reinterpret_cast<u32x2*>(smem + (rr >> 1) * PIECE + (rr & 1) * 512 + cc * 2) = ob;
;               const int l0 = min(((int)__float_as_uint(o0) - (int)(h0 << 16) + 128) >> 8, 127);
;               const int l1 = min(((int)__float_as_uint(o1) - (int)(h1 << 16) + 128) >> 8, 127);
;               const int l2 = min(((int)__float_as_uint(o2) - (int)(h2 << 16) + 128) >> 8, 127);
;               const int l3 = min(((int)__float_as_uint(o3) - (int)(h3 << 16) + 128) >> 8, 127);
;               *reinterpret_cast<unsigned*>(smem + LOBASE + (rr >> 2) * PIECE + (rr & 3) * 256 + cc) =
;     ...
;           WAIT_L(0); BAR;
;           const int hso = ((brow + ai * HALF + 16 * wave) * DM + pn * BM) * 2;
;           const int lso = (brow + ai * HALF + 16 * wave) * DM + pn * BM;
;           _Pragma("unroll") for (int i = 0; i < 8; ++i) {
;             const u32x4 v = *reinterpret_cast<const u32x4*>(smem + (wave * 8 + i) * PIECE + lane3 * 16);
;             __builtin_amdgcn_raw_buffer_store_b128(v, rsXB, hvo + i * (2 * DM * 2), hso, 0);
;           }
;           _Pragma("unroll") for (int i = 0; i < 4; ++i) {
;             const u32x4 v = *reinterpret_cast<const u32x4*>(smem + LOBASE + (wave * 4 + i) * PIECE + lane3 * 16);
;             __builtin_amdgcn_raw_buffer_store_b128(v, rsLO, lvo + i * (4 * DM), lso, 0);
;           }
	ds_read_b128 v[0:3], v74
	v_or_b32_e32 v89, 0x2000, v70
	v_or_b32_e32 v90, 0x4000, v70
	v_or_b32_e32 v91, 0x6000, v70
	v_or_b32_e32 v108, 0x8000, v70
	s_waitcnt lgkmcnt(0)
	buffer_store_dwordx4 v[0:3], v70, s[16:19], s22 offen
	ds_read_b128 v[0:3], v74 offset:1040
	s_waitcnt lgkmcnt(0)
	buffer_store_dwordx4 v[0:3], v89, s[16:19], s22 offen
	ds_read_b128 v[0:3], v74 offset:2080
	s_waitcnt lgkmcnt(0)
	buffer_store_dwordx4 v[0:3], v90, s[16:19], s22 offen
	ds_read_b128 v[0:3], v74 offset:3120
	s_waitcnt lgkmcnt(0)
	buffer_store_dwordx4 v[0:3], v91, s[16:19], s22 offen
	ds_read_b128 v[0:3], v74 offset:4160
	s_waitcnt lgkmcnt(0)
	buffer_store_dwordx4 v[0:3], v108, s[16:19], s22 offen
	ds_read_b128 v[0:3], v74 offset:5200
	s_waitcnt lgkmcnt(0)
	buffer_store_dwordx4 v[0:3], v109, s[16:19], s22 offen
	ds_read_b128 v[0:3], v74 offset:6240
	s_waitcnt lgkmcnt(0)
	buffer_store_dwordx4 v[0:3], v110, s[16:19], s22 offen
	ds_read_b128 v[0:3], v74 offset:7280
	s_waitcnt lgkmcnt(0)
	buffer_store_dwordx4 v[0:3], v111, s[16:19], s22 offen
	ds_read_b128 v[0:3], v69
	s_mov_b32 s22, s74
	s_waitcnt lgkmcnt(0)
	buffer_store_dwordx4 v[0:3], v68, s[20:23], s0 offen
	ds_read_b128 v[0:3], v69 offset:1040
	s_waitcnt lgkmcnt(0)
	buffer_store_dwordx4 v[0:3], v112, s[20:23], s0 offen
	ds_read_b128 v[0:3], v69 offset:2080
	s_waitcnt lgkmcnt(0)
	buffer_store_dwordx4 v[0:3], v113, s[20:23], s0 offen
	ds_read_b128 v[0:3], v69 offset:3120
	s_waitcnt lgkmcnt(0)
	buffer_store_dwordx4 v[0:3], v114, s[20:23], s0 offen
	s_waitcnt lgkmcnt(0)
	s_barrier
	s_nop 1
	v_mov_b32_e32 v0, v196
	v_mov_b32_e32 v1, v197
	v_mov_b32_e32 v2, v198
	v_mov_b32_e32 v3, v199
	v_mov_b32_e32 v4, v212
	v_mov_b32_e32 v5, v213
	v_mov_b32_e32 v6, v214
	v_mov_b32_e32 v7, v215
	ds_read_b64 v[116:117], v71 offset:1024
	s_add_i32 s0, s0, 0x40000
	s_waitcnt lgkmcnt(0)
	v_pk_add_f32 v[82:83], v[82:83], v[116:117] op_sel_hi:[1,0] neg_lo:[0,1] neg_hi:[0,1]
	s_nop 0
	v_pk_mul_f32 v[82:83], v[116:117], v[82:83] op_sel:[1,0]
	v_pk_add_f32 v[80:81], v[80:81], v[116:117] op_sel_hi:[1,0] neg_lo:[0,1] neg_hi:[0,1]
	v_mov_b32_e32 v64, v1
	v_mov_b32_e32 v65, v2
	v_mov_b32_e32 v66, v5
	v_mov_b32_e32 v67, v6
	v_pk_fma_f32 v[82:83], v[64:65], v[82:83], v[66:67]
	v_pk_mul_f32 v[80:81], v[116:117], v[80:81] op_sel:[1,0]
	v_mov_b32_e32 v1, v3
	v_mov_b32_e32 v5, v7
	v_and_b32_sdwa v6, v83, v244 dst_sel:DWORD dst_unused:UNUSED_PAD src0_sel:WORD_1 src1_sel:DWORD
	v_and_b32_sdwa v7, v82, v244 dst_sel:DWORD dst_unused:UNUSED_PAD src0_sel:WORD_1 src1_sel:DWORD
	v_pk_fma_f32 v[2:3], v[0:1], v[80:81], v[4:5]
	v_add3_u32 v80, v83, v6, s67
	v_add3_u32 v6, v82, v7, s67
	v_and_b32_e32 v81, 0xffff0000, v6
	v_and_b32_sdwa v6, v3, v244 dst_sel:DWORD dst_unused:UNUSED_PAD src0_sel:WORD_1 src1_sel:DWORD
	v_and_b32_sdwa v7, v2, v244 dst_sel:DWORD dst_unused:UNUSED_PAD src0_sel:WORD_1 src1_sel:DWORD
	v_add3_u32 v6, v3, v6, s67
	v_add3_u32 v115, v2, v7, s67
	v_and_b32_e32 v116, 0xffff0000, v6
	v_or_b32_sdwa v7, v116, v80 dst_sel:DWORD dst_unused:UNUSED_PAD src0_sel:DWORD src1_sel:WORD_1
	v_or_b32_sdwa v6, v115, v81 dst_sel:DWORD dst_unused:UNUSED_PAD src0_sel:WORD_1 src1_sel:DWORD
	ds_write_b64 v73, v[6:7]
	v_and_b32_e32 v6, 0xffff0000, v115
	v_sub_u32_e32 v2, v2, v6
	v_sub_u32_e32 v6, v82, v81
	v_and_b32_e32 v7, 0xffff0000, v80
	v_add_u32_e32 v6, 0x80, v6
	v_sub_u32_e32 v7, v83, v7
	v_sub_u32_e32 v3, v3, v116
	v_add_u32_e32 v2, 0x80, v2
	v_ashrrev_i32_e32 v6, 8, v6
	v_add_u32_e32 v7, 0x80, v7
	v_add_u32_e32 v3, 0x80, v3
	v_ashrrev_i32_e32 v2, 8, v2
	v_min_i32_e32 v6, 0x7f, v6
	v_ashrrev_i32_e32 v7, 8, v7
	v_ashrrev_i32_e32 v3, 8, v3
	v_min_i32_e32 v2, 0x7f, v2
	v_min_i32_sdwa v7, v7, s69 dst_sel:WORD_1 dst_unused:UNUSED_PAD src0_sel:DWORD src1_sel:DWORD
	v_min_i32_e32 v3, 0x7f, v3
	v_lshlrev_b32_e32 v6, 8, v6
	v_and_b32_e32 v6, 0xff00, v6
	v_and_b32_e32 v7, 0xff0000, v7
	v_perm_b32 v2, v3, v2, s76
	v_or3_b32 v2, v2, v6, v7
	ds_write_b32 v12, v2
	ds_read_b64 v[2:3], v13 offset:1024
	s_waitcnt lgkmcnt(0)
	v_pk_add_f32 v[6:7], v[86:87], v[2:3] op_sel_hi:[1,0] neg_lo:[0,1] neg_hi:[0,1]
	s_nop 0
	v_pk_mul_f32 v[6:7], v[2:3], v[6:7] op_sel:[1,0]
	v_pk_add_f32 v[80:81], v[84:85], v[2:3] op_sel_hi:[1,0] neg_lo:[0,1] neg_hi:[0,1]
	v_pk_fma_f32 v[6:7], v[64:65], v[6:7], v[66:67]
	v_pk_mul_f32 v[2:3], v[2:3], v[80:81] op_sel:[1,0]
	v_and_b32_sdwa v80, v6, v244 dst_sel:DWORD dst_unused:UNUSED_PAD src0_sel:WORD_1 src1_sel:DWORD
	v_pk_fma_f32 v[2:3], v[0:1], v[2:3], v[4:5]
	v_add3_u32 v80, v6, v80, s67
	v_and_b32_e32 v82, 0xffff0000, v80
	v_and_b32_sdwa v80, v3, v244 dst_sel:DWORD dst_unused:UNUSED_PAD src0_sel:WORD_1 src1_sel:DWORD
	v_and_b32_sdwa v73, v7, v244 dst_sel:DWORD dst_unused:UNUSED_PAD src0_sel:WORD_1 src1_sel:DWORD
	v_and_b32_sdwa v81, v2, v244 dst_sel:DWORD dst_unused:UNUSED_PAD src0_sel:WORD_1 src1_sel:DWORD
	v_add3_u32 v80, v3, v80, s67
	v_add3_u32 v73, v7, v73, s67
	v_add3_u32 v83, v2, v81, s67
	v_and_b32_e32 v84, 0xffff0000, v80
	v_or_b32_sdwa v81, v84, v73 dst_sel:DWORD dst_unused:UNUSED_PAD src0_sel:DWORD src1_sel:WORD_1
	v_or_b32_sdwa v80, v83, v82 dst_sel:DWORD dst_unused:UNUSED_PAD src0_sel:WORD_1 src1_sel:DWORD
	ds_write_b64 v75, v[80:81]
	v_and_b32_e32 v75, 0xffff0000, v83
	v_sub_u32_e32 v6, v6, v82
	v_and_b32_e32 v73, 0xffff0000, v73
	v_sub_u32_e32 v2, v2, v75
	v_add_u32_e32 v6, 0x80, v6
	v_sub_u32_e32 v7, v7, v73
	v_sub_u32_e32 v3, v3, v84
	v_add_u32_e32 v2, 0x80, v2
	v_ashrrev_i32_e32 v6, 8, v6
	v_add_u32_e32 v7, 0x80, v7
	v_add_u32_e32 v3, 0x80, v3
	v_ashrrev_i32_e32 v2, 8, v2
	v_min_i32_e32 v6, 0x7f, v6
	v_ashrrev_i32_e32 v7, 8, v7
	v_ashrrev_i32_e32 v3, 8, v3
	v_min_i32_e32 v2, 0x7f, v2
	v_min_i32_sdwa v7, v7, s69 dst_sel:WORD_1 dst_unused:UNUSED_PAD src0_sel:DWORD src1_sel:DWORD
	v_min_i32_e32 v3, 0x7f, v3
	v_lshlrev_b32_e32 v6, 8, v6
	v_and_b32_e32 v6, 0xff00, v6
	v_and_b32_e32 v7, 0xff0000, v7
	v_perm_b32 v2, v3, v2, s76
	v_or3_b32 v2, v2, v6, v7
	ds_write_b32 v14, v2
	ds_read_b64 v[2:3], v15 offset:1024
	s_waitcnt lgkmcnt(0)
;     ...
;         _Pragma("unroll") for (int ai = 0; ai < 2; ++ai) {
;           _Pragma("unroll") for (int bj = 0; bj < 2; ++bj) _Pragma("unroll") for (int n = 0; n < 2; ++n) {
;             const int cc = bj * HALF + wc3 * 32 + n * 16 + fq3 * 4;
;             const float4 gm = *reinterpret_cast<const float4*>(g.gam + pn * BM + cc), bt = *reinterpret_cast<const float4*>(g.bet + pn * BM + cc);
;             _Pragma("unroll") for (int m = 0; m < 4; ++m) {
;               const int rr = wr3 * 64 + m * 16 + fr3;
;               const float2 ms = *reinterpret_cast<const float2*>(mr + (ai * HALF + rr) * 2);
;               f32x4 y = acc[ai][bj][m][n];
;               const float o0 = (y[0] - ms.x) * ms.y * gm.x + bt.x, o1 = (y[1] - ms.x) * ms.y * gm.y + bt.y;
;               const float o2 = (y[2] - ms.x) * ms.y * gm.z + bt.z, o3 = (y[3] - ms.x) * ms.y * gm.w + bt.w;
;               const unsigned h0 = f2bf(o0), h1 = f2bf(o1), h2 = f2bf(o2), h3 = f2bf(o3);
;               u32x2 ob; ob[0] = h0 | (h1 << 16); ob[1] = h2 | (h3 << 16);
;               *reinterpret_cast<u32x2*>(smem + (rr >> 1) * PIECE + (rr & 1) * 512 + cc * 2) = ob;
;               const int l0 = min(((int)__float_as_uint(o0) - (int)(h0 << 16) + 128) >> 8, 127);
;               const int l1 = min(((int)__float_as_uint(o1) - (int)(h1 << 16) + 128) >> 8, 127);
;               const int l2 = min(((int)__float_as_uint(o2) - (int)(h2 << 16) + 128) >> 8, 127);
;               const int l3 = min(((int)__float_as_uint(o3) - (int)(h3 << 16) + 128) >> 8, 127);
;               *reinterpret_cast<unsigned*>(smem + LOBASE + (rr >> 2) * PIECE + (rr & 3) * 256 + cc) =
;                   (unsigned)(l0 & 255) | ((unsigned)(l1 & 255) << 8) | ((unsigned)(l2 & 255) << 16) | ((unsigned)l3 << 24);
;             }
	v_pk_add_f32 v[6:7], v[94:95], v[2:3] op_sel_hi:[1,0] neg_lo:[0,1] neg_hi:[0,1]
	v_pk_add_f32 v[80:81], v[92:93], v[2:3] op_sel_hi:[1,0] neg_lo:[0,1] neg_hi:[0,1]
	v_pk_mul_f32 v[6:7], v[2:3], v[6:7] op_sel:[1,0]
	v_pk_mul_f32 v[2:3], v[2:3], v[80:81] op_sel:[1,0]
	v_pk_fma_f32 v[6:7], v[64:65], v[6:7], v[66:67]
	v_pk_fma_f32 v[2:3], v[0:1], v[2:3], v[4:5]
	v_and_b32_sdwa v75, v6, v244 dst_sel:DWORD dst_unused:UNUSED_PAD src0_sel:WORD_1 src1_sel:DWORD
	v_and_b32_sdwa v80, v3, v244 dst_sel:DWORD dst_unused:UNUSED_PAD src0_sel:WORD_1 src1_sel:DWORD
	v_and_b32_sdwa v73, v7, v244 dst_sel:DWORD dst_unused:UNUSED_PAD src0_sel:WORD_1 src1_sel:DWORD
	v_add3_u32 v75, v6, v75, s67
	v_and_b32_sdwa v81, v2, v244 dst_sel:DWORD dst_unused:UNUSED_PAD src0_sel:WORD_1 src1_sel:DWORD
	v_add3_u32 v80, v3, v80, s67
	v_add3_u32 v73, v7, v73, s67
	v_and_b32_e32 v75, 0xffff0000, v75
	v_add3_u32 v82, v2, v81, s67
	v_and_b32_e32 v83, 0xffff0000, v80
	v_or_b32_sdwa v81, v83, v73 dst_sel:DWORD dst_unused:UNUSED_PAD src0_sel:DWORD src1_sel:WORD_1
	v_or_b32_sdwa v80, v82, v75 dst_sel:DWORD dst_unused:UNUSED_PAD src0_sel:WORD_1 src1_sel:DWORD
	ds_write_b64 v96, v[80:81]
	v_and_b32_e32 v80, 0xffff0000, v82
	v_sub_u32_e32 v6, v6, v75
	v_and_b32_e32 v73, 0xffff0000, v73
	v_sub_u32_e32 v2, v2, v80
	v_add_u32_e32 v6, 0x80, v6
	v_sub_u32_e32 v7, v7, v73
	v_sub_u32_e32 v3, v3, v83
	v_add_u32_e32 v2, 0x80, v2
	v_ashrrev_i32_e32 v6, 8, v6
	v_add_u32_e32 v7, 0x80, v7
	v_add_u32_e32 v3, 0x80, v3
	v_ashrrev_i32_e32 v2, 8, v2
	v_min_i32_e32 v6, 0x7f, v6
	v_ashrrev_i32_e32 v7, 8, v7
	v_ashrrev_i32_e32 v3, 8, v3
	v_min_i32_e32 v2, 0x7f, v2
	v_min_i32_sdwa v7, v7, s69 dst_sel:WORD_1 dst_unused:UNUSED_PAD src0_sel:DWORD src1_sel:DWORD
	v_min_i32_e32 v3, 0x7f, v3
	v_lshlrev_b32_e32 v6, 8, v6
	v_and_b32_e32 v6, 0xff00, v6
	v_and_b32_e32 v7, 0xff0000, v7
	v_perm_b32 v2, v3, v2, s76
	v_or3_b32 v2, v2, v6, v7
	ds_write_b32 v20, v2
	ds_read_b64 v[2:3], v21 offset:1024
	s_waitcnt lgkmcnt(0)
	v_pk_add_f32 v[6:7], v[78:79], v[2:3] op_sel_hi:[1,0] neg_lo:[0,1] neg_hi:[0,1]
	s_nop 0
	v_pk_mul_f32 v[6:7], v[2:3], v[6:7] op_sel:[1,0]
	s_nop 0
	v_pk_fma_f32 v[6:7], v[64:65], v[6:7], v[66:67]
	v_pk_add_f32 v[64:65], v[76:77], v[2:3] op_sel_hi:[1,0] neg_lo:[0,1] neg_hi:[0,1]
	s_nop 0
	v_pk_mul_f32 v[2:3], v[2:3], v[64:65] op_sel:[1,0]
	s_nop 0
	v_pk_fma_f32 v[0:1], v[0:1], v[2:3], v[4:5]
	v_and_b32_sdwa v2, v7, v244 dst_sel:DWORD dst_unused:UNUSED_PAD src0_sel:WORD_1 src1_sel:DWORD
	v_and_b32_sdwa v3, v6, v244 dst_sel:DWORD dst_unused:UNUSED_PAD src0_sel:WORD_1 src1_sel:DWORD
	v_add3_u32 v4, v7, v2, s67
	v_add3_u32 v2, v6, v3, s67
	v_and_b32_e32 v5, 0xffff0000, v2
	v_and_b32_sdwa v2, v1, v244 dst_sel:DWORD dst_unused:UNUSED_PAD src0_sel:WORD_1 src1_sel:DWORD
	v_and_b32_sdwa v3, v0, v244 dst_sel:DWORD dst_unused:UNUSED_PAD src0_sel:WORD_1 src1_sel:DWORD
	v_add3_u32 v2, v1, v2, s67
	v_add3_u32 v64, v0, v3, s67
	v_and_b32_e32 v65, 0xffff0000, v2
	v_or_b32_sdwa v3, v65, v4 dst_sel:DWORD dst_unused:UNUSED_PAD src0_sel:DWORD src1_sel:WORD_1
	v_or_b32_sdwa v2, v64, v5 dst_sel:DWORD dst_unused:UNUSED_PAD src0_sel:WORD_1 src1_sel:DWORD
	ds_write_b64 v97, v[2:3]
	v_and_b32_e32 v2, 0xffff0000, v64
	v_sub_u32_e32 v0, v0, v2
	v_sub_u32_e32 v2, v6, v5
	v_and_b32_e32 v3, 0xffff0000, v4
	v_add_u32_e32 v2, 0x80, v2
	v_sub_u32_e32 v3, v7, v3
	v_sub_u32_e32 v1, v1, v65
	v_add_u32_e32 v0, 0x80, v0
	v_ashrrev_i32_e32 v2, 8, v2
	v_add_u32_e32 v3, 0x80, v3
	v_add_u32_e32 v1, 0x80, v1
	v_ashrrev_i32_e32 v0, 8, v0
	v_min_i32_e32 v2, 0x7f, v2
	v_ashrrev_i32_e32 v3, 8, v3
	v_ashrrev_i32_e32 v1, 8, v1
	v_min_i32_e32 v0, 0x7f, v0
	v_min_i32_sdwa v3, v3, s69 dst_sel:WORD_1 dst_unused:UNUSED_PAD src0_sel:DWORD src1_sel:DWORD
	v_min_i32_e32 v1, 0x7f, v1
	v_lshlrev_b32_e32 v2, 8, v2
	v_and_b32_e32 v2, 0xff00, v2
	v_and_b32_e32 v3, 0xff0000, v3
	v_perm_b32 v0, v1, v0, s76
	v_or3_b32 v0, v0, v2, v3
	ds_write_b32 v22, v0
	v_mov_b32_e32 v0, v200
	v_mov_b32_e32 v1, v201
	v_mov_b32_e32 v2, v202
	v_mov_b32_e32 v3, v203
	v_mov_b32_e32 v4, v220
	v_mov_b32_e32 v5, v221
	v_mov_b32_e32 v6, v222
	v_mov_b32_e32 v7, v223
	ds_read_b64 v[76:77], v71 offset:1024
	s_waitcnt lgkmcnt(0)
	v_pk_add_f32 v[62:63], v[62:63], v[76:77] op_sel_hi:[1,0] neg_lo:[0,1] neg_hi:[0,1]
	s_nop 0
	v_pk_mul_f32 v[62:63], v[76:77], v[62:63] op_sel:[1,0]
	v_pk_add_f32 v[60:61], v[60:61], v[76:77] op_sel_hi:[1,0] neg_lo:[0,1] neg_hi:[0,1]
	v_mov_b32_e32 v64, v1
	v_mov_b32_e32 v65, v2
	v_mov_b32_e32 v66, v5
	v_mov_b32_e32 v67, v6
	v_pk_fma_f32 v[62:63], v[64:65], v[62:63], v[66:67]
	v_pk_mul_f32 v[60:61], v[76:77], v[60:61] op_sel:[1,0]
	v_mov_b32_e32 v1, v3
	v_mov_b32_e32 v5, v7
	v_and_b32_sdwa v6, v63, v244 dst_sel:DWORD dst_unused:UNUSED_PAD src0_sel:WORD_1 src1_sel:DWORD
	v_and_b32_sdwa v7, v62, v244 dst_sel:DWORD dst_unused:UNUSED_PAD src0_sel:WORD_1 src1_sel:DWORD
	v_pk_fma_f32 v[2:3], v[0:1], v[60:61], v[4:5]
	v_add3_u32 v60, v63, v6, s67
	v_add3_u32 v6, v62, v7, s67
	v_and_b32_e32 v61, 0xffff0000, v6
	v_and_b32_sdwa v6, v3, v244 dst_sel:DWORD dst_unused:UNUSED_PAD src0_sel:WORD_1 src1_sel:DWORD
	v_and_b32_sdwa v7, v2, v244 dst_sel:DWORD dst_unused:UNUSED_PAD src0_sel:WORD_1 src1_sel:DWORD
	v_add3_u32 v6, v3, v6, s67
	v_add3_u32 v73, v2, v7, s67
	v_and_b32_e32 v75, 0xffff0000, v6
	v_or_b32_sdwa v7, v75, v60 dst_sel:DWORD dst_unused:UNUSED_PAD src0_sel:DWORD src1_sel:WORD_1
	v_or_b32_sdwa v6, v73, v61 dst_sel:DWORD dst_unused:UNUSED_PAD src0_sel:WORD_1 src1_sel:DWORD
	ds_write_b64 v23, v[6:7]
	v_and_b32_e32 v6, 0xffff0000, v73
	v_sub_u32_e32 v2, v2, v6
	v_sub_u32_e32 v6, v62, v61
	v_and_b32_e32 v7, 0xffff0000, v60
	v_add_u32_e32 v6, 0x80, v6
	v_sub_u32_e32 v7, v63, v7
	v_sub_u32_e32 v3, v3, v75
	v_add_u32_e32 v2, 0x80, v2
	v_ashrrev_i32_e32 v6, 8, v6
	v_add_u32_e32 v7, 0x80, v7
	v_add_u32_e32 v3, 0x80, v3
	v_ashrrev_i32_e32 v2, 8, v2
	v_min_i32_e32 v6, 0x7f, v6
	v_ashrrev_i32_e32 v7, 8, v7
	v_ashrrev_i32_e32 v3, 8, v3
	v_min_i32_e32 v2, 0x7f, v2
	v_min_i32_sdwa v7, v7, s69 dst_sel:WORD_1 dst_unused:UNUSED_PAD src0_sel:DWORD src1_sel:DWORD
	v_min_i32_e32 v3, 0x7f, v3
	v_lshlrev_b32_e32 v6, 8, v6
	v_and_b32_e32 v6, 0xff00, v6
	v_and_b32_e32 v7, 0xff0000, v7
	v_perm_b32 v2, v3, v2, s76
	v_or3_b32 v2, v2, v6, v7
	ds_write_b32 v12, v2 offset:16
	ds_read_b64 v[2:3], v13 offset:1024
	s_waitcnt lgkmcnt(0)
;     ...
;         _Pragma("unroll") for (int ai = 0; ai < 2; ++ai) {
;           _Pragma("unroll") for (int bj = 0; bj < 2; ++bj) _Pragma("unroll") for (int n = 0; n < 2; ++n) {
;             const int cc = bj * HALF + wc3 * 32 + n * 16 + fq3 * 4;
;             const float4 gm = *reinterpret_cast<const float4*>(g.gam + pn * BM + cc), bt = *reinterpret_cast<const float4*>(g.bet + pn * BM + cc);
;             _Pragma("unroll") for (int m = 0; m < 4; ++m) {
;               const int rr = wr3 * 64 + m * 16 + fr3;
;               const float2 ms = *reinterpret_cast<const float2*>(mr + (ai * HALF + rr) * 2);
;               f32x4 y = acc[ai][bj][m][n];
;               const float o0 = (y[0] - ms.x) * ms.y * gm.x + bt.x, o1 = (y[1] - ms.x) * ms.y * gm.y + bt.y;
;               const float o2 = (y[2] - ms.x) * ms.y * gm.z + bt.z, o3 = (y[3] - ms.x) * ms.y * gm.w + bt.w;
;               const unsigned h0 = f2bf(o0), h1 = f2bf(o1), h2 = f2bf(o2), h3 = f2bf(o3);
;               u32x2 ob; ob[0] = h0 | (h1 << 16); ob[1] = h2 | (h3 << 16);
;               *reinterpret_cast<u32x2*>(smem + (rr >> 1) * PIECE + (rr & 1) * 512 + cc * 2) = ob;
;               const int l0 = min(((int)__float_as_uint(o0) - (int)(h0 << 16) + 128) >> 8, 127);
;               const int l1 = min(((int)__float_as_uint(o1) - (int)(h1 << 16) + 128) >> 8, 127);
;               const int l2 = min(((int)__float_as_uint(o2) - (int)(h2 << 16) + 128) >> 8, 127);
;               const int l3 = min(((int)__float_as_uint(o3) - (int)(h3 << 16) + 128) >> 8, 127);
;               *reinterpret_cast<unsigned*>(smem + LOBASE + (rr >> 2) * PIECE + (rr & 3) * 256 + cc) =
;                   (unsigned)(l0 & 255) | ((unsigned)(l1 & 255) << 8) | ((unsigned)(l2 & 255) << 16) | ((unsigned)l3 << 24);
;             }
	v_pk_add_f32 v[6:7], v[46:47], v[2:3] op_sel_hi:[1,0] neg_lo:[0,1] neg_hi:[0,1]
	s_nop 0
	v_pk_mul_f32 v[6:7], v[2:3], v[6:7] op_sel:[1,0]
	v_pk_add_f32 v[44:45], v[44:45], v[2:3] op_sel_hi:[1,0] neg_lo:[0,1] neg_hi:[0,1]
	v_pk_fma_f32 v[6:7], v[64:65], v[6:7], v[66:67]
	v_pk_mul_f32 v[2:3], v[2:3], v[44:45] op_sel:[1,0]
	v_and_b32_sdwa v44, v6, v244 dst_sel:DWORD dst_unused:UNUSED_PAD src0_sel:WORD_1 src1_sel:DWORD
	v_pk_fma_f32 v[2:3], v[0:1], v[2:3], v[4:5]
	v_add3_u32 v44, v6, v44, s67
	v_and_b32_e32 v46, 0xffff0000, v44
	v_and_b32_sdwa v44, v3, v244 dst_sel:DWORD dst_unused:UNUSED_PAD src0_sel:WORD_1 src1_sel:DWORD
	v_and_b32_sdwa v23, v7, v244 dst_sel:DWORD dst_unused:UNUSED_PAD src0_sel:WORD_1 src1_sel:DWORD
	v_and_b32_sdwa v45, v2, v244 dst_sel:DWORD dst_unused:UNUSED_PAD src0_sel:WORD_1 src1_sel:DWORD
	v_add3_u32 v44, v3, v44, s67
	v_add3_u32 v23, v7, v23, s67
	v_add3_u32 v47, v2, v45, s67
	v_and_b32_e32 v60, 0xffff0000, v44
	v_or_b32_sdwa v45, v60, v23 dst_sel:DWORD dst_unused:UNUSED_PAD src0_sel:DWORD src1_sel:WORD_1
	v_or_b32_sdwa v44, v47, v46 dst_sel:DWORD dst_unused:UNUSED_PAD src0_sel:WORD_1 src1_sel:DWORD
	ds_write_b64 v98, v[44:45]
	v_and_b32_e32 v44, 0xffff0000, v47
	v_sub_u32_e32 v6, v6, v46
	v_and_b32_e32 v23, 0xffff0000, v23
	v_sub_u32_e32 v2, v2, v44
	v_add_u32_e32 v6, 0x80, v6
	v_sub_u32_e32 v7, v7, v23
	v_sub_u32_e32 v3, v3, v60
	v_add_u32_e32 v2, 0x80, v2
	v_ashrrev_i32_e32 v6, 8, v6
	v_add_u32_e32 v7, 0x80, v7
	v_add_u32_e32 v3, 0x80, v3
	v_ashrrev_i32_e32 v2, 8, v2
	v_min_i32_e32 v6, 0x7f, v6
	v_ashrrev_i32_e32 v7, 8, v7
	v_ashrrev_i32_e32 v3, 8, v3
	v_min_i32_e32 v2, 0x7f, v2
	v_min_i32_sdwa v7, v7, s69 dst_sel:WORD_1 dst_unused:UNUSED_PAD src0_sel:DWORD src1_sel:DWORD
	v_min_i32_e32 v3, 0x7f, v3
	v_lshlrev_b32_e32 v6, 8, v6
	v_and_b32_e32 v6, 0xff00, v6
	v_and_b32_e32 v7, 0xff0000, v7
	v_perm_b32 v2, v3, v2, s76
	v_or3_b32 v2, v2, v6, v7
	ds_write_b32 v14, v2 offset:16
	ds_read_b64 v[2:3], v15 offset:1024
	s_waitcnt lgkmcnt(0)
	v_pk_add_f32 v[6:7], v[42:43], v[2:3] op_sel_hi:[1,0] neg_lo:[0,1] neg_hi:[0,1]
	s_nop 0
	v_pk_mul_f32 v[6:7], v[2:3], v[6:7] op_sel:[1,0]
	v_pk_add_f32 v[40:41], v[40:41], v[2:3] op_sel_hi:[1,0] neg_lo:[0,1] neg_hi:[0,1]
	v_pk_fma_f32 v[6:7], v[64:65], v[6:7], v[66:67]
	v_pk_mul_f32 v[2:3], v[2:3], v[40:41] op_sel:[1,0]
	v_and_b32_sdwa v40, v6, v244 dst_sel:DWORD dst_unused:UNUSED_PAD src0_sel:WORD_1 src1_sel:DWORD
	v_pk_fma_f32 v[2:3], v[0:1], v[2:3], v[4:5]
	v_add3_u32 v40, v6, v40, s67
	v_and_b32_e32 v42, 0xffff0000, v40
	v_and_b32_sdwa v40, v3, v244 dst_sel:DWORD dst_unused:UNUSED_PAD src0_sel:WORD_1 src1_sel:DWORD
	v_and_b32_sdwa v23, v7, v244 dst_sel:DWORD dst_unused:UNUSED_PAD src0_sel:WORD_1 src1_sel:DWORD
	v_and_b32_sdwa v41, v2, v244 dst_sel:DWORD dst_unused:UNUSED_PAD src0_sel:WORD_1 src1_sel:DWORD
	v_add3_u32 v40, v3, v40, s67
	v_add3_u32 v23, v7, v23, s67
	v_add3_u32 v43, v2, v41, s67
	v_and_b32_e32 v44, 0xffff0000, v40
	v_or_b32_sdwa v41, v44, v23 dst_sel:DWORD dst_unused:UNUSED_PAD src0_sel:DWORD src1_sel:WORD_1
	v_or_b32_sdwa v40, v43, v42 dst_sel:DWORD dst_unused:UNUSED_PAD src0_sel:WORD_1 src1_sel:DWORD
	ds_write_b64 v99, v[40:41]
	v_and_b32_e32 v40, 0xffff0000, v43
	v_sub_u32_e32 v6, v6, v42
	v_and_b32_e32 v23, 0xffff0000, v23
	v_sub_u32_e32 v2, v2, v40
	v_add_u32_e32 v6, 0x80, v6
	v_sub_u32_e32 v7, v7, v23
	v_sub_u32_e32 v3, v3, v44
	v_add_u32_e32 v2, 0x80, v2
	v_ashrrev_i32_e32 v6, 8, v6
	v_add_u32_e32 v7, 0x80, v7
	v_add_u32_e32 v3, 0x80, v3
	v_ashrrev_i32_e32 v2, 8, v2
	v_min_i32_e32 v6, 0x7f, v6
	v_ashrrev_i32_e32 v7, 8, v7
	v_ashrrev_i32_e32 v3, 8, v3
	v_min_i32_e32 v2, 0x7f, v2
	v_min_i32_sdwa v7, v7, s69 dst_sel:WORD_1 dst_unused:UNUSED_PAD src0_sel:DWORD src1_sel:DWORD
	v_min_i32_e32 v3, 0x7f, v3
	v_lshlrev_b32_e32 v6, 8, v6
	v_and_b32_e32 v6, 0xff00, v6
	v_and_b32_e32 v7, 0xff0000, v7
	v_perm_b32 v2, v3, v2, s76
	v_or3_b32 v2, v2, v6, v7
	ds_write_b32 v20, v2 offset:16
	ds_read_b64 v[2:3], v21 offset:1024
	s_waitcnt lgkmcnt(0)
	v_pk_add_f32 v[6:7], v[58:59], v[2:3] op_sel_hi:[1,0] neg_lo:[0,1] neg_hi:[0,1]
	s_nop 0
	v_pk_mul_f32 v[6:7], v[2:3], v[6:7] op_sel:[1,0]
	v_pk_add_f32 v[40:41], v[56:57], v[2:3] op_sel_hi:[1,0] neg_lo:[0,1] neg_hi:[0,1]
	v_pk_fma_f32 v[6:7], v[64:65], v[6:7], v[66:67]
	v_pk_mul_f32 v[2:3], v[2:3], v[40:41] op_sel:[1,0]
	s_nop 0
	v_pk_fma_f32 v[0:1], v[0:1], v[2:3], v[4:5]
	v_and_b32_sdwa v2, v7, v244 dst_sel:DWORD dst_unused:UNUSED_PAD src0_sel:WORD_1 src1_sel:DWORD
	v_and_b32_sdwa v3, v6, v244 dst_sel:DWORD dst_unused:UNUSED_PAD src0_sel:WORD_1 src1_sel:DWORD
	v_add3_u32 v4, v7, v2, s67
	v_add3_u32 v2, v6, v3, s67
	v_and_b32_e32 v5, 0xffff0000, v2
	v_and_b32_sdwa v2, v1, v244 dst_sel:DWORD dst_unused:UNUSED_PAD src0_sel:WORD_1 src1_sel:DWORD
	v_and_b32_sdwa v3, v0, v244 dst_sel:DWORD dst_unused:UNUSED_PAD src0_sel:WORD_1 src1_sel:DWORD
	v_add3_u32 v2, v1, v2, s67
	v_add3_u32 v23, v0, v3, s67
	v_and_b32_e32 v40, 0xffff0000, v2
	v_or_b32_sdwa v3, v40, v4 dst_sel:DWORD dst_unused:UNUSED_PAD src0_sel:DWORD src1_sel:WORD_1
	v_or_b32_sdwa v2, v23, v5 dst_sel:DWORD dst_unused:UNUSED_PAD src0_sel:WORD_1 src1_sel:DWORD
	ds_write_b64 v100, v[2:3]
	v_and_b32_e32 v2, 0xffff0000, v23
	v_sub_u32_e32 v0, v0, v2
	v_sub_u32_e32 v2, v6, v5
	v_and_b32_e32 v3, 0xffff0000, v4
	v_add_u32_e32 v2, 0x80, v2
	v_sub_u32_e32 v3, v7, v3
	v_sub_u32_e32 v1, v1, v40
	v_add_u32_e32 v0, 0x80, v0
	v_ashrrev_i32_e32 v2, 8, v2
	v_add_u32_e32 v3, 0x80, v3
	v_add_u32_e32 v1, 0x80, v1
	v_ashrrev_i32_e32 v0, 8, v0
	v_min_i32_e32 v2, 0x7f, v2
	v_ashrrev_i32_e32 v3, 8, v3
	v_ashrrev_i32_e32 v1, 8, v1
	v_min_i32_e32 v0, 0x7f, v0
	v_min_i32_sdwa v3, v3, s69 dst_sel:WORD_1 dst_unused:UNUSED_PAD src0_sel:DWORD src1_sel:DWORD
	v_min_i32_e32 v1, 0x7f, v1
	v_lshlrev_b32_e32 v2, 8, v2
	v_and_b32_e32 v2, 0xff00, v2
	v_and_b32_e32 v3, 0xff0000, v3
	v_perm_b32 v0, v1, v0, s76
	v_or3_b32 v0, v0, v2, v3
	ds_write_b32 v22, v0 offset:16
	v_mov_b32_e32 v0, v204
	v_mov_b32_e32 v1, v205
	v_mov_b32_e32 v2, v206
	v_mov_b32_e32 v3, v207
	v_mov_b32_e32 v4, v240
	v_mov_b32_e32 v5, v241
	v_mov_b32_e32 v6, v242
	v_mov_b32_e32 v7, v243
	ds_read_b64 v[44:45], v71 offset:1024
	s_waitcnt lgkmcnt(0)
;     ...
;         _Pragma("unroll") for (int ai = 0; ai < 2; ++ai) {
;           _Pragma("unroll") for (int bj = 0; bj < 2; ++bj) _Pragma("unroll") for (int n = 0; n < 2; ++n) {
;             const int cc = bj * HALF + wc3 * 32 + n * 16 + fq3 * 4;
;             const float4 gm = *reinterpret_cast<const float4*>(g.gam + pn * BM + cc), bt = *reinterpret_cast<const float4*>(g.bet + pn * BM + cc);
;             _Pragma("unroll") for (int m = 0; m < 4; ++m) {
;               const int rr = wr3 * 64 + m * 16 + fr3;
;               const float2 ms = *reinterpret_cast<const float2*>(mr + (ai * HALF + rr) * 2);
;               f32x4 y = acc[ai][bj][m][n];
;               const float o0 = (y[0] - ms.x) * ms.y * gm.x + bt.x, o1 = (y[1] - ms.x) * ms.y * gm.y + bt.y;
;               const float o2 = (y[2] - ms.x) * ms.y * gm.z + bt.z, o3 = (y[3] - ms.x) * ms.y * gm.w + bt.w;
;               const unsigned h0 = f2bf(o0), h1 = f2bf(o1), h2 = f2bf(o2), h3 = f2bf(o3);
;               u32x2 ob; ob[0] = h0 | (h1 << 16); ob[1] = h2 | (h3 << 16);
;               *reinterpret_cast<u32x2*>(smem + (rr >> 1) * PIECE + (rr & 1) * 512 + cc * 2) = ob;
;               const int l0 = min(((int)__float_as_uint(o0) - (int)(h0 << 16) + 128) >> 8, 127);
;               const int l1 = min(((int)__float_as_uint(o1) - (int)(h1 << 16) + 128) >> 8, 127);
;               const int l2 = min(((int)__float_as_uint(o2) - (int)(h2 << 16) + 128) >> 8, 127);
;               const int l3 = min(((int)__float_as_uint(o3) - (int)(h3 << 16) + 128) >> 8, 127);
;               *reinterpret_cast<unsigned*>(smem + LOBASE + (rr >> 2) * PIECE + (rr & 3) * 256 + cc) =
;                   (unsigned)(l0 & 255) | ((unsigned)(l1 & 255) << 8) | ((unsigned)(l2 & 255) << 16) | ((unsigned)l3 << 24);
;             }
	v_pk_add_f32 v[46:47], v[54:55], v[44:45] op_sel_hi:[1,0] neg_lo:[0,1] neg_hi:[0,1]
	s_nop 0
	v_pk_mul_f32 v[46:47], v[44:45], v[46:47] op_sel:[1,0]
	v_pk_add_f32 v[52:53], v[52:53], v[44:45] op_sel_hi:[1,0] neg_lo:[0,1] neg_hi:[0,1]
	v_mov_b32_e32 v40, v1
	v_mov_b32_e32 v41, v2
	v_mov_b32_e32 v42, v5
	v_mov_b32_e32 v43, v6
	v_pk_fma_f32 v[46:47], v[40:41], v[46:47], v[42:43]
	v_pk_mul_f32 v[44:45], v[44:45], v[52:53] op_sel:[1,0]
	v_mov_b32_e32 v1, v3
	v_mov_b32_e32 v5, v7
	v_and_b32_sdwa v6, v47, v244 dst_sel:DWORD dst_unused:UNUSED_PAD src0_sel:WORD_1 src1_sel:DWORD
	v_and_b32_sdwa v7, v46, v244 dst_sel:DWORD dst_unused:UNUSED_PAD src0_sel:WORD_1 src1_sel:DWORD
	v_pk_fma_f32 v[2:3], v[0:1], v[44:45], v[4:5]
	v_add3_u32 v23, v47, v6, s67
	v_add3_u32 v6, v46, v7, s67
	v_and_b32_e32 v44, 0xffff0000, v6
	v_and_b32_sdwa v6, v3, v244 dst_sel:DWORD dst_unused:UNUSED_PAD src0_sel:WORD_1 src1_sel:DWORD
	v_and_b32_sdwa v7, v2, v244 dst_sel:DWORD dst_unused:UNUSED_PAD src0_sel:WORD_1 src1_sel:DWORD
	v_add3_u32 v6, v3, v6, s67
	v_add3_u32 v45, v2, v7, s67
	v_and_b32_e32 v52, 0xffff0000, v6
	v_or_b32_sdwa v7, v52, v23 dst_sel:DWORD dst_unused:UNUSED_PAD src0_sel:DWORD src1_sel:WORD_1
	v_or_b32_sdwa v6, v45, v44 dst_sel:DWORD dst_unused:UNUSED_PAD src0_sel:WORD_1 src1_sel:DWORD
	ds_write_b64 v101, v[6:7]
	v_and_b32_e32 v6, 0xffff0000, v45
	v_sub_u32_e32 v2, v2, v6
	v_sub_u32_e32 v6, v46, v44
	v_and_b32_e32 v7, 0xffff0000, v23
	v_add_u32_e32 v6, 0x80, v6
	v_sub_u32_e32 v7, v47, v7
	v_sub_u32_e32 v3, v3, v52
	v_add_u32_e32 v2, 0x80, v2
	v_ashrrev_i32_e32 v6, 8, v6
	v_add_u32_e32 v7, 0x80, v7
	v_add_u32_e32 v3, 0x80, v3
	v_ashrrev_i32_e32 v2, 8, v2
	v_min_i32_e32 v6, 0x7f, v6
	v_ashrrev_i32_e32 v7, 8, v7
	v_ashrrev_i32_e32 v3, 8, v3
	v_min_i32_e32 v2, 0x7f, v2
	v_min_i32_sdwa v7, v7, s69 dst_sel:WORD_1 dst_unused:UNUSED_PAD src0_sel:DWORD src1_sel:DWORD
	v_min_i32_e32 v3, 0x7f, v3
	v_lshlrev_b32_e32 v6, 8, v6
	v_and_b32_e32 v6, 0xff00, v6
	v_and_b32_e32 v7, 0xff0000, v7
	v_perm_b32 v2, v3, v2, s76
	v_or3_b32 v2, v2, v6, v7
	ds_write_b32 v12, v2 offset:128
	ds_read_b64 v[2:3], v13 offset:1024
	s_waitcnt lgkmcnt(0)
	v_pk_add_f32 v[6:7], v[38:39], v[2:3] op_sel_hi:[1,0] neg_lo:[0,1] neg_hi:[0,1]
	s_nop 0
	v_pk_mul_f32 v[6:7], v[2:3], v[6:7] op_sel:[1,0]
	v_pk_add_f32 v[36:37], v[36:37], v[2:3] op_sel_hi:[1,0] neg_lo:[0,1] neg_hi:[0,1]
	v_pk_fma_f32 v[6:7], v[40:41], v[6:7], v[42:43]
	v_pk_mul_f32 v[2:3], v[2:3], v[36:37] op_sel:[1,0]
	v_and_b32_sdwa v36, v6, v244 dst_sel:DWORD dst_unused:UNUSED_PAD src0_sel:WORD_1 src1_sel:DWORD
	v_pk_fma_f32 v[2:3], v[0:1], v[2:3], v[4:5]
	v_add3_u32 v36, v6, v36, s67
	v_and_b32_e32 v38, 0xffff0000, v36
	v_and_b32_sdwa v36, v3, v244 dst_sel:DWORD dst_unused:UNUSED_PAD src0_sel:WORD_1 src1_sel:DWORD
	v_and_b32_sdwa v23, v7, v244 dst_sel:DWORD dst_unused:UNUSED_PAD src0_sel:WORD_1 src1_sel:DWORD
	v_and_b32_sdwa v37, v2, v244 dst_sel:DWORD dst_unused:UNUSED_PAD src0_sel:WORD_1 src1_sel:DWORD
	v_add3_u32 v36, v3, v36, s67
	v_add3_u32 v23, v7, v23, s67
	v_add3_u32 v39, v2, v37, s67
	v_and_b32_e32 v44, 0xffff0000, v36
	v_or_b32_sdwa v37, v44, v23 dst_sel:DWORD dst_unused:UNUSED_PAD src0_sel:DWORD src1_sel:WORD_1
	v_or_b32_sdwa v36, v39, v38 dst_sel:DWORD dst_unused:UNUSED_PAD src0_sel:WORD_1 src1_sel:DWORD
	ds_write_b64 v102, v[36:37]
	v_and_b32_e32 v36, 0xffff0000, v39
	v_sub_u32_e32 v6, v6, v38
	v_and_b32_e32 v23, 0xffff0000, v23
	v_sub_u32_e32 v2, v2, v36
	v_add_u32_e32 v6, 0x80, v6
	v_sub_u32_e32 v7, v7, v23
	v_sub_u32_e32 v3, v3, v44
	v_add_u32_e32 v2, 0x80, v2
	v_ashrrev_i32_e32 v6, 8, v6
	v_add_u32_e32 v7, 0x80, v7
	v_add_u32_e32 v3, 0x80, v3
	v_ashrrev_i32_e32 v2, 8, v2
	v_min_i32_e32 v6, 0x7f, v6
	v_ashrrev_i32_e32 v7, 8, v7
	v_ashrrev_i32_e32 v3, 8, v3
	v_min_i32_e32 v2, 0x7f, v2
	v_min_i32_sdwa v7, v7, s69 dst_sel:WORD_1 dst_unused:UNUSED_PAD src0_sel:DWORD src1_sel:DWORD
	v_min_i32_e32 v3, 0x7f, v3
	v_lshlrev_b32_e32 v6, 8, v6
	v_and_b32_e32 v6, 0xff00, v6
	v_and_b32_e32 v7, 0xff0000, v7
	v_perm_b32 v2, v3, v2, s76
	v_or3_b32 v2, v2, v6, v7
	ds_write_b32 v14, v2 offset:128
	ds_read_b64 v[2:3], v15 offset:1024
	s_waitcnt lgkmcnt(0)
	v_pk_add_f32 v[6:7], v[26:27], v[2:3] op_sel_hi:[1,0] neg_lo:[0,1] neg_hi:[0,1]
	s_nop 0
	v_pk_mul_f32 v[6:7], v[2:3], v[6:7] op_sel:[1,0]
	v_pk_add_f32 v[24:25], v[24:25], v[2:3] op_sel_hi:[1,0] neg_lo:[0,1] neg_hi:[0,1]
	v_pk_fma_f32 v[6:7], v[40:41], v[6:7], v[42:43]
	v_pk_mul_f32 v[2:3], v[2:3], v[24:25] op_sel:[1,0]
	v_and_b32_sdwa v24, v6, v244 dst_sel:DWORD dst_unused:UNUSED_PAD src0_sel:WORD_1 src1_sel:DWORD
	v_pk_fma_f32 v[2:3], v[0:1], v[2:3], v[4:5]
	v_add3_u32 v24, v6, v24, s67
	v_and_b32_e32 v26, 0xffff0000, v24
	v_and_b32_sdwa v24, v3, v244 dst_sel:DWORD dst_unused:UNUSED_PAD src0_sel:WORD_1 src1_sel:DWORD
	v_and_b32_sdwa v23, v7, v244 dst_sel:DWORD dst_unused:UNUSED_PAD src0_sel:WORD_1 src1_sel:DWORD
	v_and_b32_sdwa v25, v2, v244 dst_sel:DWORD dst_unused:UNUSED_PAD src0_sel:WORD_1 src1_sel:DWORD
	v_add3_u32 v24, v3, v24, s67
	v_add3_u32 v23, v7, v23, s67
	v_add3_u32 v27, v2, v25, s67
	v_and_b32_e32 v36, 0xffff0000, v24
	v_or_b32_sdwa v25, v36, v23 dst_sel:DWORD dst_unused:UNUSED_PAD src0_sel:DWORD src1_sel:WORD_1
	v_or_b32_sdwa v24, v27, v26 dst_sel:DWORD dst_unused:UNUSED_PAD src0_sel:WORD_1 src1_sel:DWORD
	ds_write_b64 v103, v[24:25]
	v_and_b32_e32 v24, 0xffff0000, v27
	v_sub_u32_e32 v6, v6, v26
	v_and_b32_e32 v23, 0xffff0000, v23
	v_sub_u32_e32 v2, v2, v24
	v_add_u32_e32 v6, 0x80, v6
	v_sub_u32_e32 v7, v7, v23
	v_sub_u32_e32 v3, v3, v36
	v_add_u32_e32 v2, 0x80, v2
	v_ashrrev_i32_e32 v6, 8, v6
	v_add_u32_e32 v7, 0x80, v7
	v_add_u32_e32 v3, 0x80, v3
	v_ashrrev_i32_e32 v2, 8, v2
	v_min_i32_e32 v6, 0x7f, v6
	v_ashrrev_i32_e32 v7, 8, v7
	v_ashrrev_i32_e32 v3, 8, v3
	v_min_i32_e32 v2, 0x7f, v2
	v_min_i32_sdwa v7, v7, s69 dst_sel:WORD_1 dst_unused:UNUSED_PAD src0_sel:DWORD src1_sel:DWORD
	v_min_i32_e32 v3, 0x7f, v3
	v_lshlrev_b32_e32 v6, 8, v6
	v_and_b32_e32 v6, 0xff00, v6
	v_and_b32_e32 v7, 0xff0000, v7
	v_perm_b32 v2, v3, v2, s76
	v_or3_b32 v2, v2, v6, v7
	ds_write_b32 v20, v2 offset:128
	ds_read_b64 v[2:3], v21 offset:1024
	s_waitcnt lgkmcnt(0)
;     ...
;         _Pragma("unroll") for (int ai = 0; ai < 2; ++ai) {
;           _Pragma("unroll") for (int bj = 0; bj < 2; ++bj) _Pragma("unroll") for (int n = 0; n < 2; ++n) {
;             const int cc = bj * HALF + wc3 * 32 + n * 16 + fq3 * 4;
;             const float4 gm = *reinterpret_cast<const float4*>(g.gam + pn * BM + cc), bt = *reinterpret_cast<const float4*>(g.bet + pn * BM + cc);
;             _Pragma("unroll") for (int m = 0; m < 4; ++m) {
;               const int rr = wr3 * 64 + m * 16 + fr3;
;               const float2 ms = *reinterpret_cast<const float2*>(mr + (ai * HALF + rr) * 2);
;               f32x4 y = acc[ai][bj][m][n];
;               const float o0 = (y[0] - ms.x) * ms.y * gm.x + bt.x, o1 = (y[1] - ms.x) * ms.y * gm.y + bt.y;
;               const float o2 = (y[2] - ms.x) * ms.y * gm.z + bt.z, o3 = (y[3] - ms.x) * ms.y * gm.w + bt.w;
;               const unsigned h0 = f2bf(o0), h1 = f2bf(o1), h2 = f2bf(o2), h3 = f2bf(o3);
;               u32x2 ob; ob[0] = h0 | (h1 << 16); ob[1] = h2 | (h3 << 16);
;               *reinterpret_cast<u32x2*>(smem + (rr >> 1) * PIECE + (rr & 1) * 512 + cc * 2) = ob;
;               const int l0 = min(((int)__float_as_uint(o0) - (int)(h0 << 16) + 128) >> 8, 127);
;               const int l1 = min(((int)__float_as_uint(o1) - (int)(h1 << 16) + 128) >> 8, 127);
;               const int l2 = min(((int)__float_as_uint(o2) - (int)(h2 << 16) + 128) >> 8, 127);
;               const int l3 = min(((int)__float_as_uint(o3) - (int)(h3 << 16) + 128) >> 8, 127);
;               *reinterpret_cast<unsigned*>(smem + LOBASE + (rr >> 2) * PIECE + (rr & 3) * 256 + cc) =
;                   (unsigned)(l0 & 255) | ((unsigned)(l1 & 255) << 8) | ((unsigned)(l2 & 255) << 16) | ((unsigned)l3 << 24);
;             }
	v_pk_add_f32 v[6:7], v[30:31], v[2:3] op_sel_hi:[1,0] neg_lo:[0,1] neg_hi:[0,1]
	s_nop 0
	v_pk_mul_f32 v[6:7], v[2:3], v[6:7] op_sel:[1,0]
	v_pk_add_f32 v[24:25], v[28:29], v[2:3] op_sel_hi:[1,0] neg_lo:[0,1] neg_hi:[0,1]
	v_pk_fma_f32 v[6:7], v[40:41], v[6:7], v[42:43]
	v_pk_mul_f32 v[2:3], v[2:3], v[24:25] op_sel:[1,0]
	s_nop 0
	v_pk_fma_f32 v[0:1], v[0:1], v[2:3], v[4:5]
	v_and_b32_sdwa v2, v7, v244 dst_sel:DWORD dst_unused:UNUSED_PAD src0_sel:WORD_1 src1_sel:DWORD
	v_and_b32_sdwa v3, v6, v244 dst_sel:DWORD dst_unused:UNUSED_PAD src0_sel:WORD_1 src1_sel:DWORD
	v_add3_u32 v4, v7, v2, s67
	v_add3_u32 v2, v6, v3, s67
	v_and_b32_e32 v5, 0xffff0000, v2
	v_and_b32_sdwa v2, v1, v244 dst_sel:DWORD dst_unused:UNUSED_PAD src0_sel:WORD_1 src1_sel:DWORD
	v_and_b32_sdwa v3, v0, v244 dst_sel:DWORD dst_unused:UNUSED_PAD src0_sel:WORD_1 src1_sel:DWORD
	v_add3_u32 v2, v1, v2, s67
	v_add3_u32 v23, v0, v3, s67
	v_and_b32_e32 v24, 0xffff0000, v2
	v_or_b32_sdwa v3, v24, v4 dst_sel:DWORD dst_unused:UNUSED_PAD src0_sel:DWORD src1_sel:WORD_1
	v_or_b32_sdwa v2, v23, v5 dst_sel:DWORD dst_unused:UNUSED_PAD src0_sel:WORD_1 src1_sel:DWORD
	ds_write_b64 v104, v[2:3]
	v_and_b32_e32 v2, 0xffff0000, v23
	v_sub_u32_e32 v0, v0, v2
	v_sub_u32_e32 v2, v6, v5
	v_and_b32_e32 v3, 0xffff0000, v4
	v_add_u32_e32 v2, 0x80, v2
	v_sub_u32_e32 v3, v7, v3
	v_sub_u32_e32 v1, v1, v24
	v_add_u32_e32 v0, 0x80, v0
	v_ashrrev_i32_e32 v2, 8, v2
	v_add_u32_e32 v3, 0x80, v3
	v_add_u32_e32 v1, 0x80, v1
	v_ashrrev_i32_e32 v0, 8, v0
	v_min_i32_e32 v2, 0x7f, v2
	v_ashrrev_i32_e32 v3, 8, v3
	v_ashrrev_i32_e32 v1, 8, v1
	v_min_i32_e32 v0, 0x7f, v0
	v_min_i32_sdwa v3, v3, s69 dst_sel:WORD_1 dst_unused:UNUSED_PAD src0_sel:DWORD src1_sel:DWORD
	v_min_i32_e32 v1, 0x7f, v1
	v_lshlrev_b32_e32 v2, 8, v2
	v_and_b32_e32 v2, 0xff00, v2
	v_and_b32_e32 v3, 0xff0000, v3
	v_perm_b32 v0, v1, v0, s76
	v_or3_b32 v0, v0, v2, v3
	ds_write_b32 v22, v0 offset:128
	v_mov_b32_e32 v0, v208
	v_mov_b32_e32 v1, v209
	v_mov_b32_e32 v2, v210
	v_mov_b32_e32 v3, v211
	v_mov_b32_e32 v4, v248
	v_mov_b32_e32 v5, v249
	v_mov_b32_e32 v6, v250
	v_mov_b32_e32 v7, v251
	ds_read_b64 v[28:29], v71 offset:1024
	s_lshl_b32 s4, s0, 1
	s_mov_b64 s[6:7], -1
	s_waitcnt lgkmcnt(0)
	v_pk_add_f32 v[30:31], v[50:51], v[28:29] op_sel_hi:[1,0] neg_lo:[0,1] neg_hi:[0,1]
	s_nop 0
	v_pk_mul_f32 v[30:31], v[28:29], v[30:31] op_sel:[1,0]
	v_pk_add_f32 v[36:37], v[48:49], v[28:29] op_sel_hi:[1,0] neg_lo:[0,1] neg_hi:[0,1]
	v_mov_b32_e32 v24, v1
	v_mov_b32_e32 v25, v2
	v_mov_b32_e32 v26, v5
	v_mov_b32_e32 v27, v6
	v_pk_fma_f32 v[30:31], v[24:25], v[30:31], v[26:27]
	v_pk_mul_f32 v[28:29], v[28:29], v[36:37] op_sel:[1,0]
	v_mov_b32_e32 v1, v3
	v_mov_b32_e32 v5, v7
	v_and_b32_sdwa v6, v31, v244 dst_sel:DWORD dst_unused:UNUSED_PAD src0_sel:WORD_1 src1_sel:DWORD
	v_and_b32_sdwa v7, v30, v244 dst_sel:DWORD dst_unused:UNUSED_PAD src0_sel:WORD_1 src1_sel:DWORD
	v_pk_fma_f32 v[2:3], v[0:1], v[28:29], v[4:5]
	v_add3_u32 v23, v31, v6, s67
	v_add3_u32 v6, v30, v7, s67
	v_and_b32_e32 v28, 0xffff0000, v6
	v_and_b32_sdwa v6, v3, v244 dst_sel:DWORD dst_unused:UNUSED_PAD src0_sel:WORD_1 src1_sel:DWORD
	v_and_b32_sdwa v7, v2, v244 dst_sel:DWORD dst_unused:UNUSED_PAD src0_sel:WORD_1 src1_sel:DWORD
	v_add3_u32 v6, v3, v6, s67
	v_add3_u32 v29, v2, v7, s67
	v_and_b32_e32 v36, 0xffff0000, v6
	v_or_b32_sdwa v7, v36, v23 dst_sel:DWORD dst_unused:UNUSED_PAD src0_sel:DWORD src1_sel:WORD_1
	v_or_b32_sdwa v6, v29, v28 dst_sel:DWORD dst_unused:UNUSED_PAD src0_sel:WORD_1 src1_sel:DWORD
	ds_write_b64 v105, v[6:7]
	v_and_b32_e32 v6, 0xffff0000, v29
	v_sub_u32_e32 v2, v2, v6
	v_sub_u32_e32 v6, v30, v28
	v_and_b32_e32 v7, 0xffff0000, v23
	v_add_u32_e32 v6, 0x80, v6
	v_sub_u32_e32 v7, v31, v7
	v_sub_u32_e32 v3, v3, v36
	v_add_u32_e32 v2, 0x80, v2
	v_ashrrev_i32_e32 v6, 8, v6
	v_add_u32_e32 v7, 0x80, v7
	v_add_u32_e32 v3, 0x80, v3
	v_ashrrev_i32_e32 v2, 8, v2
	v_min_i32_e32 v6, 0x7f, v6
	v_ashrrev_i32_e32 v7, 8, v7
	v_ashrrev_i32_e32 v3, 8, v3
	v_min_i32_e32 v2, 0x7f, v2
	v_min_i32_sdwa v7, v7, s69 dst_sel:WORD_1 dst_unused:UNUSED_PAD src0_sel:DWORD src1_sel:DWORD
	v_min_i32_e32 v3, 0x7f, v3
	v_lshlrev_b32_e32 v6, 8, v6
	v_and_b32_e32 v6, 0xff00, v6
	v_and_b32_e32 v7, 0xff0000, v7
	v_perm_b32 v2, v3, v2, s76
	v_or3_b32 v2, v2, v6, v7
	ds_write_b32 v12, v2 offset:144
	ds_read_b64 v[2:3], v13 offset:1024
	s_waitcnt lgkmcnt(0)
	v_pk_add_f32 v[6:7], v[34:35], v[2:3] op_sel_hi:[1,0] neg_lo:[0,1] neg_hi:[0,1]
	s_nop 0
	v_pk_mul_f32 v[6:7], v[2:3], v[6:7] op_sel:[1,0]
	v_pk_add_f32 v[12:13], v[32:33], v[2:3] op_sel_hi:[1,0] neg_lo:[0,1] neg_hi:[0,1]
	v_pk_fma_f32 v[6:7], v[24:25], v[6:7], v[26:27]
	v_pk_mul_f32 v[2:3], v[2:3], v[12:13] op_sel:[1,0]
	v_and_b32_sdwa v12, v7, v244 dst_sel:DWORD dst_unused:UNUSED_PAD src0_sel:WORD_1 src1_sel:DWORD
	v_and_b32_sdwa v13, v6, v244 dst_sel:DWORD dst_unused:UNUSED_PAD src0_sel:WORD_1 src1_sel:DWORD
	v_pk_fma_f32 v[2:3], v[0:1], v[2:3], v[4:5]
	v_add3_u32 v23, v7, v12, s67
	v_add3_u32 v12, v6, v13, s67
	v_and_b32_e32 v28, 0xffff0000, v12
	v_and_b32_sdwa v12, v3, v244 dst_sel:DWORD dst_unused:UNUSED_PAD src0_sel:WORD_1 src1_sel:DWORD
	v_and_b32_sdwa v13, v2, v244 dst_sel:DWORD dst_unused:UNUSED_PAD src0_sel:WORD_1 src1_sel:DWORD
	v_add3_u32 v12, v3, v12, s67
	v_add3_u32 v29, v2, v13, s67
	v_and_b32_e32 v30, 0xffff0000, v12
	v_or_b32_sdwa v13, v30, v23 dst_sel:DWORD dst_unused:UNUSED_PAD src0_sel:DWORD src1_sel:WORD_1
	v_or_b32_sdwa v12, v29, v28 dst_sel:DWORD dst_unused:UNUSED_PAD src0_sel:WORD_1 src1_sel:DWORD
	ds_write_b64 v106, v[12:13]
	v_and_b32_e32 v12, 0xffff0000, v29
	v_sub_u32_e32 v2, v2, v12
	v_sub_u32_e32 v6, v6, v28
	v_and_b32_e32 v12, 0xffff0000, v23
	v_add_u32_e32 v6, 0x80, v6
	v_sub_u32_e32 v7, v7, v12
	v_sub_u32_e32 v3, v3, v30
	v_add_u32_e32 v2, 0x80, v2
	v_ashrrev_i32_e32 v6, 8, v6
	v_add_u32_e32 v7, 0x80, v7
	v_add_u32_e32 v3, 0x80, v3
	v_ashrrev_i32_e32 v2, 8, v2
	v_min_i32_e32 v6, 0x7f, v6
	v_ashrrev_i32_e32 v7, 8, v7
	v_ashrrev_i32_e32 v3, 8, v3
	v_min_i32_e32 v2, 0x7f, v2
	v_min_i32_sdwa v7, v7, s69 dst_sel:WORD_1 dst_unused:UNUSED_PAD src0_sel:DWORD src1_sel:DWORD
	v_min_i32_e32 v3, 0x7f, v3
	v_lshlrev_b32_e32 v6, 8, v6
	v_and_b32_e32 v6, 0xff00, v6
	v_and_b32_e32 v7, 0xff0000, v7
	v_perm_b32 v2, v3, v2, s76
	v_or3_b32 v2, v2, v6, v7
	ds_write_b32 v14, v2 offset:144
	ds_read_b64 v[2:3], v15 offset:1024
	s_waitcnt lgkmcnt(0)
; #define WAIT_L(n) asm volatile("s_waitcnt lgkmcnt(" #n ")" ::: "memory")
; #define BAR __builtin_amdgcn_s_barrier()
;     ...
;             _Pragma("unroll") for (int m = 0; m < 4; ++m) {
;               const int rr = wr3 * 64 + m * 16 + fr3;
;               const float2 ms = *reinterpret_cast<const float2*>(mr + (ai * HALF + rr) * 2);
;               f32x4 y = acc[ai][bj][m][n];
;               const float o0 = (y[0] - ms.x) * ms.y * gm.x + bt.x, o1 = (y[1] - ms.x) * ms.y * gm.y + bt.y;
;               const float o2 = (y[2] - ms.x) * ms.y * gm.z + bt.z, o3 = (y[3] - ms.x) * ms.y * gm.w + bt.w;
;               const unsigned h0 = f2bf(o0), h1 = f2bf(o1), h2 = f2bf(o2), h3 = f2bf(o3);
;               u32x2 ob; ob[0] = h0 | (h1 << 16); ob[1] = h2 | (h3 << 16);
;               *reinterpret_cast<u32x2*>(smem + (rr >> 1) * PIECE + (rr & 1) * 512 + cc * 2) = ob;
;               const int l0 = min(((int)__float_as_uint(o0) - (int)(h0 << 16) + 128) >> 8, 127);
;               const int l1 = min(((int)__float_as_uint(o1) - (int)(h1 << 16) + 128) >> 8, 127);
;               const int l2 = min(((int)__float_as_uint(o2) - (int)(h2 << 16) + 128) >> 8, 127);
;               const int l3 = min(((int)__float_as_uint(o3) - (int)(h3 << 16) + 128) >> 8, 127);
;               *reinterpret_cast<unsigned*>(smem + LOBASE + (rr >> 2) * PIECE + (rr & 3) * 256 + cc) =
;                   (unsigned)(l0 & 255) | ((unsigned)(l1 & 255) << 8) | ((unsigned)(l2 & 255) << 16) | ((unsigned)l3 << 24);
;             }
;           }
;           WAIT_L(0); BAR;
	v_pk_add_f32 v[6:7], v[18:19], v[2:3] op_sel_hi:[1,0] neg_lo:[0,1] neg_hi:[0,1]
	s_nop 0
	v_pk_mul_f32 v[6:7], v[2:3], v[6:7] op_sel:[1,0]
	v_pk_add_f32 v[12:13], v[16:17], v[2:3] op_sel_hi:[1,0] neg_lo:[0,1] neg_hi:[0,1]
	v_pk_fma_f32 v[6:7], v[24:25], v[6:7], v[26:27]
	v_pk_mul_f32 v[2:3], v[2:3], v[12:13] op_sel:[1,0]
	v_and_b32_sdwa v12, v7, v244 dst_sel:DWORD dst_unused:UNUSED_PAD src0_sel:WORD_1 src1_sel:DWORD
	v_and_b32_sdwa v13, v6, v244 dst_sel:DWORD dst_unused:UNUSED_PAD src0_sel:WORD_1 src1_sel:DWORD
	v_pk_fma_f32 v[2:3], v[0:1], v[2:3], v[4:5]
	v_add3_u32 v14, v7, v12, s67
	v_add3_u32 v12, v6, v13, s67
	v_and_b32_e32 v15, 0xffff0000, v12
	v_and_b32_sdwa v12, v3, v244 dst_sel:DWORD dst_unused:UNUSED_PAD src0_sel:WORD_1 src1_sel:DWORD
	v_and_b32_sdwa v13, v2, v244 dst_sel:DWORD dst_unused:UNUSED_PAD src0_sel:WORD_1 src1_sel:DWORD
	v_add3_u32 v12, v3, v12, s67
	v_add3_u32 v16, v2, v13, s67
	v_and_b32_e32 v17, 0xffff0000, v12
	v_or_b32_sdwa v13, v17, v14 dst_sel:DWORD dst_unused:UNUSED_PAD src0_sel:DWORD src1_sel:WORD_1
	v_or_b32_sdwa v12, v16, v15 dst_sel:DWORD dst_unused:UNUSED_PAD src0_sel:WORD_1 src1_sel:DWORD
	ds_write_b64 v107, v[12:13]
	v_and_b32_e32 v12, 0xffff0000, v16
	v_sub_u32_e32 v2, v2, v12
	v_sub_u32_e32 v6, v6, v15
	v_and_b32_e32 v12, 0xffff0000, v14
	v_add_u32_e32 v6, 0x80, v6
	v_sub_u32_e32 v7, v7, v12
	v_sub_u32_e32 v3, v3, v17
	v_add_u32_e32 v2, 0x80, v2
	v_ashrrev_i32_e32 v6, 8, v6
	v_add_u32_e32 v7, 0x80, v7
	v_add_u32_e32 v3, 0x80, v3
	v_ashrrev_i32_e32 v2, 8, v2
	v_min_i32_e32 v6, 0x7f, v6
	v_ashrrev_i32_e32 v7, 8, v7
	v_ashrrev_i32_e32 v3, 8, v3
	v_min_i32_e32 v2, 0x7f, v2
	v_min_i32_sdwa v7, v7, s69 dst_sel:WORD_1 dst_unused:UNUSED_PAD src0_sel:DWORD src1_sel:DWORD
	v_min_i32_e32 v3, 0x7f, v3
	v_lshlrev_b32_e32 v6, 8, v6
	v_and_b32_e32 v6, 0xff00, v6
	v_and_b32_e32 v7, 0xff0000, v7
	v_perm_b32 v2, v3, v2, s76
	v_or3_b32 v2, v2, v6, v7
	ds_write_b32 v20, v2 offset:144
	ds_read_b64 v[2:3], v21 offset:1024
	s_waitcnt lgkmcnt(0)
	v_pk_add_f32 v[6:7], v[10:11], v[2:3] op_sel_hi:[1,0] neg_lo:[0,1] neg_hi:[0,1]
	s_nop 0
	v_pk_mul_f32 v[6:7], v[2:3], v[6:7] op_sel:[1,0]
	v_pk_add_f32 v[8:9], v[8:9], v[2:3] op_sel_hi:[1,0] neg_lo:[0,1] neg_hi:[0,1]
	v_pk_fma_f32 v[6:7], v[24:25], v[6:7], v[26:27]
	v_pk_mul_f32 v[2:3], v[2:3], v[8:9] op_sel:[1,0]
	s_nop 0
	v_pk_fma_f32 v[0:1], v[0:1], v[2:3], v[4:5]
	v_and_b32_sdwa v2, v7, v244 dst_sel:DWORD dst_unused:UNUSED_PAD src0_sel:WORD_1 src1_sel:DWORD
	v_and_b32_sdwa v3, v6, v244 dst_sel:DWORD dst_unused:UNUSED_PAD src0_sel:WORD_1 src1_sel:DWORD
	v_add3_u32 v4, v7, v2, s67
	v_add3_u32 v2, v6, v3, s67
	v_and_b32_e32 v5, 0xffff0000, v2
	v_and_b32_sdwa v2, v1, v244 dst_sel:DWORD dst_unused:UNUSED_PAD src0_sel:WORD_1 src1_sel:DWORD
	v_and_b32_sdwa v3, v0, v244 dst_sel:DWORD dst_unused:UNUSED_PAD src0_sel:WORD_1 src1_sel:DWORD
	v_add3_u32 v2, v1, v2, s67
	v_add3_u32 v8, v0, v3, s67
	v_and_b32_e32 v9, 0xffff0000, v2
	v_or_b32_sdwa v3, v9, v4 dst_sel:DWORD dst_unused:UNUSED_PAD src0_sel:DWORD src1_sel:WORD_1
	v_or_b32_sdwa v2, v8, v5 dst_sel:DWORD dst_unused:UNUSED_PAD src0_sel:WORD_1 src1_sel:DWORD
	ds_write_b64 v88, v[2:3]
	v_and_b32_e32 v2, 0xffff0000, v8
	v_sub_u32_e32 v0, v0, v2
	v_sub_u32_e32 v2, v6, v5
	v_and_b32_e32 v3, 0xffff0000, v4
	v_add_u32_e32 v2, 0x80, v2
	v_sub_u32_e32 v3, v7, v3
	v_sub_u32_e32 v1, v1, v9
	v_add_u32_e32 v0, 0x80, v0
	v_ashrrev_i32_e32 v2, 8, v2
	v_add_u32_e32 v3, 0x80, v3
	v_add_u32_e32 v1, 0x80, v1
	v_ashrrev_i32_e32 v0, 8, v0
	v_min_i32_e32 v2, 0x7f, v2
	v_ashrrev_i32_e32 v3, 8, v3
	v_ashrrev_i32_e32 v1, 8, v1
	v_min_i32_e32 v0, 0x7f, v0
	v_min_i32_sdwa v3, v3, s69 dst_sel:WORD_1 dst_unused:UNUSED_PAD src0_sel:DWORD src1_sel:DWORD
	v_min_i32_e32 v1, 0x7f, v1
	v_lshlrev_b32_e32 v2, 8, v2
	v_and_b32_e32 v2, 0xff00, v2
	v_and_b32_e32 v3, 0xff0000, v3
	v_perm_b32 v0, v1, v0, s76
	v_or3_b32 v0, v0, v2, v3
	ds_write_b32 v22, v0 offset:144
	s_waitcnt lgkmcnt(0)
	s_barrier
; #define STAGE(P, RS, SOFF, OFF, kt) do { const int _so = (SOFF) + (kt) * (BK * 2); \
;     _Pragma("unroll") for (int _i = 0; _i < 2; ++_i) { \
;       __builtin_amdgcn_raw_ptr_buffer_load_lds(RS, (__attribute__((address_space(3))) void*)((P) + wave * 1024 + _i * 8192), 16, OFF[_i], _so, 0, 0); } } while (0)
; #define WAIT_L(n) asm volatile("s_waitcnt lgkmcnt(" #n ")" ::: "memory")
; #define BAR __builtin_amdgcn_s_barrier()
;     ...
;   auto issue_prologue = [&](int sA0, int sA1, int sB0, int sB1) {
;     const int tid = opaque_tid(wave);
;     int offA[2], offB[2];
;     _Pragma("unroll") for (int i = 0; i < 2; ++i) {
;       int r, c; stage_rc(tid * 16 + i * 8192, r, c);
;       offA[i] = (r * lda + c) * 2; offB[i] = (r * ldb + c) * 2;
;     }
;     STAGE(SB(0, 0), rsB, sB0, offB, 0); STAGE(SA(0, 0), rsA, sA0, offA, 0);
;     STAGE(SB(0, 1), rsB, sB1, offB, 0); STAGE(SA(0, 1), rsA, sA1, offA, 0);
;     STAGE(SB(1, 0), rsB, sB0, offB, 1); STAGE(SA(1, 0), rsA, sA0, offA, 1); STAGE(SB(1, 1), rsB, sB1, offB, 1);
;     ...
;           _Pragma("unroll") for (int i = 0; i < 8; ++i) {
;             const u32x4 v = *reinterpret_cast<const u32x4*>(smem + (wave * 8 + i) * PIECE + lane3 * 16);
;             __builtin_amdgcn_raw_buffer_store_b128(v, rsXB, hvo + i * (2 * DM * 2), hso, 0);
;           }
;           _Pragma("unroll") for (int i = 0; i < 4; ++i) {
;             const u32x4 v = *reinterpret_cast<const u32x4*>(smem + LOBASE + (wave * 4 + i) * PIECE + lane3 * 16);
;             __builtin_amdgcn_raw_buffer_store_b128(v, rsLO, lvo + i * (4 * DM), lso, 0);
;           }
;           WAIT_L(0); BAR;
;         }
;       }
;       if (has_next) issue_prologue(nA0, nA1, nB0, nB1);
	ds_read_b128 v[0:3], v74
	s_waitcnt lgkmcnt(0)
	buffer_store_dwordx4 v[0:3], v70, s[16:19], s4 offen
	ds_read_b128 v[0:3], v74 offset:1040
	s_waitcnt lgkmcnt(0)
	buffer_store_dwordx4 v[0:3], v89, s[16:19], s4 offen
	ds_read_b128 v[0:3], v74 offset:2080
	s_waitcnt lgkmcnt(0)
	buffer_store_dwordx4 v[0:3], v90, s[16:19], s4 offen
	ds_read_b128 v[0:3], v74 offset:3120
	s_waitcnt lgkmcnt(0)
	buffer_store_dwordx4 v[0:3], v91, s[16:19], s4 offen
	ds_read_b128 v[0:3], v74 offset:4160
	s_waitcnt lgkmcnt(0)
	buffer_store_dwordx4 v[0:3], v108, s[16:19], s4 offen
	ds_read_b128 v[0:3], v74 offset:5200
	s_waitcnt lgkmcnt(0)
	buffer_store_dwordx4 v[0:3], v109, s[16:19], s4 offen
	ds_read_b128 v[0:3], v74 offset:6240
	s_waitcnt lgkmcnt(0)
	buffer_store_dwordx4 v[0:3], v110, s[16:19], s4 offen
	ds_read_b128 v[0:3], v74 offset:7280
	s_waitcnt lgkmcnt(0)
	buffer_store_dwordx4 v[0:3], v111, s[16:19], s4 offen
	ds_read_b128 v[0:3], v69
	s_waitcnt lgkmcnt(0)
	buffer_store_dwordx4 v[0:3], v68, s[20:23], s0 offen
	ds_read_b128 v[0:3], v69 offset:1040
	s_waitcnt lgkmcnt(0)
	buffer_store_dwordx4 v[0:3], v112, s[20:23], s0 offen
	ds_read_b128 v[0:3], v69 offset:2080
	s_waitcnt lgkmcnt(0)
	buffer_store_dwordx4 v[0:3], v113, s[20:23], s0 offen
	ds_read_b128 v[0:3], v69 offset:3120
	s_waitcnt lgkmcnt(0)
	buffer_store_dwordx4 v[0:3], v114, s[20:23], s0 offen
	s_waitcnt lgkmcnt(0)
	s_barrier
	s_cbranch_vccnz .LBB0_140
	v_mbcnt_lo_u32_b32 v0, -1, 0
	v_mbcnt_hi_u32_b32 v0, -1, v0
	s_mov_b32 m0, s34
	v_lshl_add_u32 v0, v0, 4, s30
	v_ashrrev_i32_e32 v1, 31, v0
	v_lshrrev_b32_e32 v1, 22, v1
	v_add_u32_e32 v1, v0, v1
	v_ashrrev_i32_e32 v1, 10, v1
	v_mul_i32_i24_e32 v2, 0x400, v1
	v_sub_u32_e32 v2, v0, v2
	v_lshrrev_b32_e32 v3, 4, v2
	v_bitop3_b32 v2, v3, v2, 32 bitop3:0x6c
	v_ashrrev_i32_e32 v4, 31, v2
	v_lshrrev_b32_e32 v4, 26, v4
	v_add_u32_e32 v4, v2, v4
	v_lshrrev_b32_e32 v5, 6, v4
	v_and_b32_e32 v4, 0xc0, v4
	v_lshlrev_b32_e32 v3, 3, v1
	v_lshlrev_b32_e32 v1, 5, v1
	v_sub_u32_e32 v2, v2, v4
	v_and_b32_e32 v3, 0x7fff0, v3
	v_and_b32_e32 v1, 32, v1
	v_ashrrev_i16_sdwa v2, v244, sext(v2) dst_sel:DWORD dst_unused:UNUSED_PAD src0_sel:DWORD src1_sel:BYTE_0
	v_add_u32_sdwa v1, v1, sext(v2) dst_sel:DWORD dst_unused:UNUSED_PAD src0_sel:DWORD src1_sel:WORD_0
	v_add_lshl_u32 v2, v5, v3, 13
	v_add_u32_e32 v0, 0x2000, v0
	v_lshl_add_u32 v1, v1, 1, v2
	v_ashrrev_i32_e32 v2, 31, v0
	v_lshrrev_b32_e32 v2, 22, v2
	v_add_u32_e32 v2, v0, v2
	v_ashrrev_i32_e32 v2, 10, v2
	v_mul_i32_i24_e32 v3, 0x400, v2
	v_sub_u32_e32 v0, v0, v3
	v_lshrrev_b32_e32 v3, 4, v0
	v_bitop3_b32 v0, v3, v0, 32 bitop3:0x6c
	v_ashrrev_i32_e32 v4, 31, v0
	v_lshrrev_b32_e32 v4, 26, v4
	v_add_u32_e32 v4, v0, v4
	v_lshrrev_b32_e32 v5, 6, v4
	v_and_b32_e32 v4, 0xffc0, v4
	v_sub_u32_e32 v0, v0, v4
	v_lshrrev_b16_e32 v4, 7, v0
	v_and_b32_e32 v4, 1, v4
	v_lshlrev_b32_e32 v3, 3, v2
	v_lshlrev_b32_e32 v2, 5, v2
	v_add_u16_e32 v0, v0, v4
	v_and_b32_e32 v3, 0x7fff0, v3
	v_and_b32_e32 v2, 32, v2
	v_ashrrev_i16_sdwa v0, v244, sext(v0) dst_sel:DWORD dst_unused:UNUSED_PAD src0_sel:DWORD src1_sel:BYTE_0
	v_add_u32_sdwa v0, v2, sext(v0) dst_sel:DWORD dst_unused:UNUSED_PAD src0_sel:DWORD src1_sel:WORD_0
	v_add_lshl_u32 v2, v5, v3, 13
	s_mov_b32 s14, s10
	s_mov_b32 s15, s11
	v_lshl_add_u32 v0, v0, 1, v2
	buffer_load_dwordx4 v1, s[12:15], s84 offen lds
	s_mov_b32 m0, s43
	s_or_b32 s0, s84, 0x80
	buffer_load_dwordx4 v0, s[12:15], s84 offen lds
	s_mov_b32 m0, s30
	s_mov_b64 s[6:7], 0
	buffer_load_dwordx4 v1, s[8:11], s83 offen lds
	s_mov_b32 m0, s44
	s_nop 0
	buffer_load_dwordx4 v0, s[8:11], s83 offen lds
	s_mov_b32 m0, s35
	s_nop 0
	buffer_load_dwordx4 v1, s[12:15], s85 offen lds
	s_mov_b32 m0, s45
	s_nop 0
	buffer_load_dwordx4 v0, s[12:15], s85 offen lds
	s_mov_b32 m0, s36
	s_nop 0
	buffer_load_dwordx4 v1, s[8:11], s82 offen lds
	s_mov_b32 m0, s48
	s_nop 0
	buffer_load_dwordx4 v0, s[8:11], s82 offen lds
	s_mov_b32 m0, s37
	s_nop 0
	buffer_load_dwordx4 v1, s[12:15], s0 offen lds
	s_mov_b32 m0, s49
	s_nop 0
	buffer_load_dwordx4 v0, s[12:15], s0 offen lds
	s_or_b32 s0, s83, 0x80
	s_mov_b32 m0, s38
	s_nop 0
	buffer_load_dwordx4 v1, s[8:11], s0 offen lds
	s_mov_b32 m0, s54
	s_nop 0
	buffer_load_dwordx4 v0, s[8:11], s0 offen lds
	s_add_i32 s0, s85, 0x80
	s_mov_b32 m0, s39
	s_nop 0
	buffer_load_dwordx4 v1, s[12:15], s0 offen lds
	s_mov_b32 m0, s55
	s_nop 0
	buffer_load_dwordx4 v0, s[12:15], s0 offen lds
	s_branch .LBB0_140

;     ...
;       const int tid3 = opaque_tid(wave);
;       const int wr3 = tid3 >> 8, wc3 = (tid3 >> 6) & 3, fr3 = tid3 & 15, fq3 = (tid3 & 63) >> 4;
;       const int ebase3 = (brow + wr3 * 64 + fr3) * DM + pn * BM + wc3 * 32 + fq3 * 4;
;       const int vo4b = ebase3 * 4, vo2 = ebase3 * 2, vo1 = ebase3;
;       (void)vo4b; (void)vo2; (void)vo1;
;       if constexpr (OUTF) {
;         _Pragma("unroll") for (int bj = 0; bj < 2; ++bj) _Pragma("unroll") for (int n = 0; n < 2; ++n) {
;           const int col = pn * BM + bj * HALF + wc3 * 32 + n * 16 + fq3 * 4;
;           const float4 gm = *reinterpret_cast<const float4*>(g.gam + col), bt = *reinterpret_cast<const float4*>(g.bet + col);
;           _Pragma("unroll") for (int ai = 0; ai < 2; ++ai) _Pragma("unroll") for (int m = 0; m < 4; ++m) {
;             const int rl = ai * HALF + wr3 * 64 + m * 16 + fr3;
;             const float2 ms = *reinterpret_cast<const float2*>(mr + rl * 2);
;             f32x4 y = acc[ai][bj][m][n];
;             u32x4 o;
;             o[0] = __float_as_uint((y[0] - ms.x) * ms.y * gm.x + bt.x); o[1] = __float_as_uint((y[1] - ms.x) * ms.y * gm.y + bt.y);
;             o[2] = __float_as_uint((y[2] - ms.x) * ms.y * gm.z + bt.z); o[3] = __float_as_uint((y[3] - ms.x) * ms.y * gm.w + bt.w);
;             __builtin_amdgcn_raw_buffer_store_b128(o, rsO, vo4b + ((ai * HALF + m * 16) * DM + bj * HALF + n * 16) * 4, 0, 0);
;           }
;         }
;       } else {
;         constexpr int PIECE = 1024 + 16, LOBASE = 64 * PIECE;
;         const int lane3 = tid3 & 63;
;         const int hvo = (lane3 >> 5) * (DM * 2) + (lane3 & 31) * 16;
;         const int lvo = (lane3 >> 4) * DM + (lane3 & 15) * 16;
;         _Pragma("unroll") for (int ai = 0; ai < 2; ++ai) {
;           _Pragma("unroll") for (int bj = 0; bj < 2; ++bj) _Pragma("unroll") for (int n = 0; n < 2; ++n) {
;             const int cc = bj * HALF + wc3 * 32 + n * 16 + fq3 * 4;
;             const float4 gm = *reinterpret_cast<const float4*>(g.gam + pn * BM + cc), bt = *reinterpret_cast<const float4*>(g.bet + pn * BM + cc);
;             _Pragma("unroll") for (int m = 0; m < 4; ++m) {
;               const int rr = wr3 * 64 + m * 16 + fr3;
;               const float2 ms = *reinterpret_cast<const float2*>(mr + (ai * HALF + rr) * 2);
;               f32x4 y = acc[ai][bj][m][n];
.LBB0_320:
	s_or_b64 exec, exec, s[6:7]
	s_waitcnt lgkmcnt(0)
	s_barrier
	v_mbcnt_lo_u32_b32 v0, -1, 0
	v_mbcnt_hi_u32_b32 v0, -1, v0
	s_movk_i32 s4, 0x60
	v_add_u32_e32 v1, s34, v0
	v_ashrrev_i32_e32 v5, 2, v1
	v_lshrrev_b32_e32 v6, 1, v1
	v_lshlrev_b32_e32 v1, 4, v1
	v_bfe_u32 v4, v0, 4, 2
	v_lshlrev_b32_e32 v12, 7, v0
	v_and_b32_e32 v13, 0x1f0, v1
	v_lshlrev_b32_e32 v7, 2, v4
	v_and_or_b32 v148, v12, s29, v13
	s_ashr_i32 s29, s28, 31
	v_and_or_b32 v12, v6, s4, v7
	s_lshl_b64 s[4:5], s[28:29], 2
	s_add_u32 s6, s86, s4
	v_and_b32_e32 v2, 15, v0
	v_and_b32_e32 v3, 63, v0
	v_and_b32_e32 v1, 0xf0, v1
	v_lshlrev_b32_e32 v13, 9, v0
	v_lshlrev_b32_e32 v0, 8, v0
	s_addc_u32 s7, s87, s5
	v_lshlrev_b32_e32 v150, 2, v12
	v_lshl_or_b32 v146, v4, 11, v1
	v_and_or_b32 v155, v5, s64, v2
	v_and_b32_e32 v14, 0x300, v0
	v_lshlrev_b32_e32 v151, 4, v3
	global_load_dwordx4 v[220:223], v150, s[6:7]
	global_load_dwordx4 v[224:227], v150, s[6:7] offset:64
	global_load_dwordx4 v[228:231], v150, s[6:7] offset:512
	global_load_dwordx4 v[232:235], v150, s[6:7] offset:576
	v_readlane_b32 s64, v255, 0
	v_readlane_b32 s65, v255, 1
	s_add_u32 s4, s64, s4
	s_addc_u32 s5, s65, s5
	global_load_dwordx4 v[236:239], v150, s[4:5]
	global_load_dwordx4 v[240:243], v150, s[4:5] offset:64
	global_load_dwordx4 v[244:247], v150, s[4:5] offset:512
	global_load_dwordx4 v[248:251], v150, s[4:5] offset:576
	s_movk_i32 s22, 0x200
	v_lshl_add_u32 v149, v155, 3, v219
	v_add_u32_e32 v147, s56, v151
	s_andn2_b64 vcc, exec, s[14:15]
	s_movk_i32 s46, 0x100
	v_readlane_b32 s66, v255, 2
	v_readlane_b32 s67, v255, 3
	v_readlane_b32 s68, v255, 4
	v_readlane_b32 s69, v255, 5
	v_readlane_b32 s70, v255, 6
	v_readlane_b32 s71, v255, 7
	v_readlane_b32 s72, v255, 8
	v_readlane_b32 s73, v255, 9
	v_readlane_b32 s74, v255, 10
	v_readlane_b32 s75, v255, 11
	v_readlane_b32 s76, v255, 12
	v_readlane_b32 s77, v255, 13
	v_readlane_b32 s78, v255, 14
	v_readlane_b32 s79, v255, 15
	s_waitcnt vmcnt(0)
	v_mov_b32_e32 v0, v220
	v_mov_b32_e32 v1, v221
	v_mov_b32_e32 v2, v222
	v_mov_b32_e32 v3, v223
	v_mov_b32_e32 v4, v236
	v_mov_b32_e32 v5, v237
	v_mov_b32_e32 v6, v238
	v_mov_b32_e32 v7, v239
	v_mov_b32_e32 v22, v1
	v_lshlrev_b32_e32 v1, 1, v12
	v_and_or_b32 v154, v13, s22, v1
	s_mov_b32 s22, 0x10400
	v_mov_b32_e32 v23, v2
	v_or3_b32 v2, v14, v12, s22
	ds_read_b64 v[12:13], v149
	v_mov_b32_e32 v144, v5
	v_mov_b32_e32 v145, v6
	v_mov_b32_e32 v1, v3
	v_mov_b32_e32 v5, v7
	s_waitcnt lgkmcnt(0)
	v_pk_add_f32 v[14:15], v[132:133], v[12:13] op_sel_hi:[1,0] neg_lo:[0,1] neg_hi:[0,1]
	v_pk_add_f32 v[18:19], v[130:131], v[12:13] op_sel_hi:[1,0] neg_lo:[0,1] neg_hi:[0,1]
	v_pk_mul_f32 v[14:15], v[12:13], v[14:15] op_sel:[1,0]
	v_pk_mul_f32 v[12:13], v[12:13], v[18:19] op_sel:[1,0]
	v_pk_fma_f32 v[14:15], v[22:23], v[14:15], v[144:145]
	v_pk_fma_f32 v[6:7], v[0:1], v[12:13], v[4:5]
	v_and_b32_sdwa v12, v14, v216 dst_sel:DWORD dst_unused:UNUSED_PAD src0_sel:WORD_1 src1_sel:DWORD
	v_add3_u32 v12, v14, v12, s84
	v_and_b32_e32 v18, 0xffff0000, v12
	v_and_b32_sdwa v12, v7, v216 dst_sel:DWORD dst_unused:UNUSED_PAD src0_sel:WORD_1 src1_sel:DWORD
	v_and_b32_sdwa v3, v15, v216 dst_sel:DWORD dst_unused:UNUSED_PAD src0_sel:WORD_1 src1_sel:DWORD
	v_and_b32_sdwa v13, v6, v216 dst_sel:DWORD dst_unused:UNUSED_PAD src0_sel:WORD_1 src1_sel:DWORD
	v_add3_u32 v12, v7, v12, s84
	v_lshrrev_b32_e32 v131, 1, v155
	v_add3_u32 v3, v15, v3, s84
	v_add3_u32 v19, v6, v13, s84
	v_and_b32_e32 v130, 0xffff0000, v12
	v_mul_lo_u32 v152, v131, s63
	v_or_b32_sdwa v13, v130, v3 dst_sel:DWORD dst_unused:UNUSED_PAD src0_sel:DWORD src1_sel:WORD_1
	v_or_b32_sdwa v12, v19, v18 dst_sel:DWORD dst_unused:UNUSED_PAD src0_sel:WORD_1 src1_sel:DWORD
	v_add_u32_e32 v132, v154, v152
	ds_write_b64 v132, v[12:13]
	v_and_b32_e32 v12, 0xffff0000, v19
	v_sub_u32_e32 v6, v6, v12
	v_sub_u32_e32 v12, v14, v18
	v_and_b32_e32 v3, 0xffff0000, v3
	v_add_u32_e32 v12, 0x80, v12
	v_sub_u32_e32 v3, v15, v3
	v_sub_u32_e32 v7, v7, v130
	v_add_u32_e32 v6, 0x80, v6
	v_ashrrev_i32_e32 v12, 8, v12
	v_add_u32_e32 v3, 0x80, v3
	v_add_u32_e32 v7, 0x80, v7
	v_ashrrev_i32_e32 v6, 8, v6
	v_min_i32_e32 v12, 0x7f, v12
	v_ashrrev_i32_e32 v3, 8, v3
	v_ashrrev_i32_e32 v7, 8, v7
	v_min_i32_e32 v6, 0x7f, v6
	v_min_i32_sdwa v3, v3, s85 dst_sel:WORD_1 dst_unused:UNUSED_PAD src0_sel:DWORD src1_sel:DWORD
	v_min_i32_e32 v7, 0x7f, v7
	v_lshlrev_b32_e32 v12, 8, v12
	v_and_b32_e32 v12, 0xff00, v12
	v_and_b32_e32 v3, 0xff0000, v3
	v_perm_b32 v6, v7, v6, s92
	v_or3_b32 v3, v6, v12, v3
	v_lshrrev_b32_e32 v6, 2, v155
	v_mad_u64_u32 v[12:13], s[22:23], v6, s63, v[2:3]
	ds_write_b32 v12, v3
	v_or_b32_e32 v3, 16, v155
	v_lshl_add_u32 v13, v3, 3, v219
	ds_read_b64 v[6:7], v13
	v_lshrrev_b32_e32 v133, 1, v3
	v_mul_lo_u32 v153, v133, s63
	v_add_u32_e32 v133, v154, v153
	v_lshrrev_b32_e32 v3, 2, v3
	s_waitcnt lgkmcnt(0)
;     ...
;         _Pragma("unroll") for (int ai = 0; ai < 2; ++ai) {
;           _Pragma("unroll") for (int bj = 0; bj < 2; ++bj) _Pragma("unroll") for (int n = 0; n < 2; ++n) {
;             const int cc = bj * HALF + wc3 * 32 + n * 16 + fq3 * 4;
;             const float4 gm = *reinterpret_cast<const float4*>(g.gam + pn * BM + cc), bt = *reinterpret_cast<const float4*>(g.bet + pn * BM + cc);
;             _Pragma("unroll") for (int m = 0; m < 4; ++m) {
;               const int rr = wr3 * 64 + m * 16 + fr3;
;               const float2 ms = *reinterpret_cast<const float2*>(mr + (ai * HALF + rr) * 2);
;               f32x4 y = acc[ai][bj][m][n];
;               const float o0 = (y[0] - ms.x) * ms.y * gm.x + bt.x, o1 = (y[1] - ms.x) * ms.y * gm.y + bt.y;
;               const float o2 = (y[2] - ms.x) * ms.y * gm.z + bt.z, o3 = (y[3] - ms.x) * ms.y * gm.w + bt.w;
;               const unsigned h0 = f2bf(o0), h1 = f2bf(o1), h2 = f2bf(o2), h3 = f2bf(o3);
;               u32x2 ob; ob[0] = h0 | (h1 << 16); ob[1] = h2 | (h3 << 16);
;               *reinterpret_cast<u32x2*>(smem + (rr >> 1) * PIECE + (rr & 1) * 512 + cc * 2) = ob;
;               const int l0 = min(((int)__float_as_uint(o0) - (int)(h0 << 16) + 128) >> 8, 127);
;               const int l1 = min(((int)__float_as_uint(o1) - (int)(h1 << 16) + 128) >> 8, 127);
;               const int l2 = min(((int)__float_as_uint(o2) - (int)(h2 << 16) + 128) >> 8, 127);
;               const int l3 = min(((int)__float_as_uint(o3) - (int)(h3 << 16) + 128) >> 8, 127);
;               *reinterpret_cast<unsigned*>(smem + LOBASE + (rr >> 2) * PIECE + (rr & 3) * 256 + cc) =
;                   (unsigned)(l0 & 255) | ((unsigned)(l1 & 255) << 8) | ((unsigned)(l2 & 255) << 16) | ((unsigned)l3 << 24);
;             }
	v_pk_add_f32 v[14:15], v[122:123], v[6:7] op_sel_hi:[1,0] neg_lo:[0,1] neg_hi:[0,1]
	v_pk_add_f32 v[18:19], v[134:135], v[6:7] op_sel_hi:[1,0] neg_lo:[0,1] neg_hi:[0,1]
	v_pk_mul_f32 v[14:15], v[6:7], v[14:15] op_sel:[1,0]
	v_pk_mul_f32 v[6:7], v[6:7], v[18:19] op_sel:[1,0]
	v_pk_fma_f32 v[14:15], v[22:23], v[14:15], v[144:145]
	v_pk_fma_f32 v[6:7], v[0:1], v[6:7], v[4:5]
	v_and_b32_sdwa v18, v15, v216 dst_sel:DWORD dst_unused:UNUSED_PAD src0_sel:WORD_1 src1_sel:DWORD
	v_and_b32_sdwa v19, v14, v216 dst_sel:DWORD dst_unused:UNUSED_PAD src0_sel:WORD_1 src1_sel:DWORD
	v_add3_u32 v122, v15, v18, s84
	v_add3_u32 v18, v14, v19, s84
	v_and_b32_e32 v123, 0xffff0000, v18
	v_and_b32_sdwa v18, v7, v216 dst_sel:DWORD dst_unused:UNUSED_PAD src0_sel:WORD_1 src1_sel:DWORD
	v_and_b32_sdwa v19, v6, v216 dst_sel:DWORD dst_unused:UNUSED_PAD src0_sel:WORD_1 src1_sel:DWORD
	v_add3_u32 v18, v7, v18, s84
	v_add3_u32 v130, v6, v19, s84
	v_and_b32_e32 v131, 0xffff0000, v18
	v_or_b32_sdwa v19, v131, v122 dst_sel:DWORD dst_unused:UNUSED_PAD src0_sel:DWORD src1_sel:WORD_1
	v_or_b32_sdwa v18, v130, v123 dst_sel:DWORD dst_unused:UNUSED_PAD src0_sel:WORD_1 src1_sel:DWORD
	ds_write_b64 v133, v[18:19]
	v_and_b32_e32 v18, 0xffff0000, v130
	v_sub_u32_e32 v6, v6, v18
	v_sub_u32_e32 v14, v14, v123
	v_and_b32_e32 v18, 0xffff0000, v122
	v_add_u32_e32 v14, 0x80, v14
	v_sub_u32_e32 v15, v15, v18
	v_sub_u32_e32 v7, v7, v131
	v_add_u32_e32 v6, 0x80, v6
	v_ashrrev_i32_e32 v14, 8, v14
	v_add_u32_e32 v15, 0x80, v15
	v_add_u32_e32 v7, 0x80, v7
	v_ashrrev_i32_e32 v6, 8, v6
	v_min_i32_e32 v14, 0x7f, v14
	v_ashrrev_i32_e32 v15, 8, v15
	v_ashrrev_i32_e32 v7, 8, v7
	v_min_i32_e32 v6, 0x7f, v6
	v_min_i32_sdwa v15, v15, s85 dst_sel:WORD_1 dst_unused:UNUSED_PAD src0_sel:DWORD src1_sel:DWORD
	v_min_i32_e32 v7, 0x7f, v7
	v_lshlrev_b32_e32 v14, 8, v14
	v_and_b32_e32 v14, 0xff00, v14
	v_and_b32_e32 v15, 0xff0000, v15
	v_perm_b32 v6, v7, v6, s92
	v_or3_b32 v6, v6, v14, v15
	v_mad_u64_u32 v[14:15], s[22:23], v3, s63, v[2:3]
	v_or_b32_e32 v3, 32, v155
	ds_write_b32 v14, v6
	v_lshl_add_u32 v15, v3, 3, v219
	ds_read_b64 v[6:7], v15
	v_lshrrev_b32_e32 v134, 1, v3
	v_lshrrev_b32_e32 v3, 2, v3
	s_waitcnt lgkmcnt(0)
	v_pk_add_f32 v[18:19], v[136:137], v[6:7] op_sel_hi:[1,0] neg_lo:[0,1] neg_hi:[0,1]
	s_nop 0
	v_pk_mul_f32 v[18:19], v[6:7], v[18:19] op_sel:[1,0]
	v_pk_add_f32 v[122:123], v[138:139], v[6:7] op_sel_hi:[1,0] neg_lo:[0,1] neg_hi:[0,1]
	v_pk_fma_f32 v[18:19], v[22:23], v[18:19], v[144:145]
	v_pk_mul_f32 v[6:7], v[6:7], v[122:123] op_sel:[1,0]
	v_and_b32_sdwa v122, v19, v216 dst_sel:DWORD dst_unused:UNUSED_PAD src0_sel:WORD_1 src1_sel:DWORD
	v_and_b32_sdwa v123, v18, v216 dst_sel:DWORD dst_unused:UNUSED_PAD src0_sel:WORD_1 src1_sel:DWORD
	v_pk_fma_f32 v[6:7], v[0:1], v[6:7], v[4:5]
	v_add3_u32 v130, v19, v122, s84
	v_add3_u32 v122, v18, v123, s84
	v_and_b32_e32 v131, 0xffff0000, v122
	v_and_b32_sdwa v122, v7, v216 dst_sel:DWORD dst_unused:UNUSED_PAD src0_sel:WORD_1 src1_sel:DWORD
	v_and_b32_sdwa v123, v6, v216 dst_sel:DWORD dst_unused:UNUSED_PAD src0_sel:WORD_1 src1_sel:DWORD
	v_add3_u32 v122, v7, v122, s84
	v_add3_u32 v135, v6, v123, s84
	v_and_b32_e32 v136, 0xffff0000, v122
	v_mul_lo_u32 v137, v134, s63
	v_or_b32_sdwa v123, v136, v130 dst_sel:DWORD dst_unused:UNUSED_PAD src0_sel:DWORD src1_sel:WORD_1
	v_or_b32_sdwa v122, v135, v131 dst_sel:DWORD dst_unused:UNUSED_PAD src0_sel:WORD_1 src1_sel:DWORD
	v_add_u32_e32 v134, v154, v137
	ds_write_b64 v134, v[122:123]
	v_and_b32_e32 v122, 0xffff0000, v135
	v_sub_u32_e32 v6, v6, v122
	v_sub_u32_e32 v18, v18, v131
	v_and_b32_e32 v122, 0xffff0000, v130
	v_add_u32_e32 v18, 0x80, v18
	v_sub_u32_e32 v19, v19, v122
	v_sub_u32_e32 v7, v7, v136
	v_add_u32_e32 v6, 0x80, v6
	v_ashrrev_i32_e32 v18, 8, v18
	v_add_u32_e32 v19, 0x80, v19
	v_add_u32_e32 v7, 0x80, v7
	v_ashrrev_i32_e32 v6, 8, v6
	v_min_i32_e32 v18, 0x7f, v18
	v_ashrrev_i32_e32 v19, 8, v19
	v_ashrrev_i32_e32 v7, 8, v7
	v_min_i32_e32 v6, 0x7f, v6
	v_min_i32_sdwa v19, v19, s85 dst_sel:WORD_1 dst_unused:UNUSED_PAD src0_sel:DWORD src1_sel:DWORD
	v_min_i32_e32 v7, 0x7f, v7
	v_lshlrev_b32_e32 v18, 8, v18
	v_and_b32_e32 v18, 0xff00, v18
	v_and_b32_e32 v19, 0xff0000, v19
	v_perm_b32 v6, v7, v6, s92
	v_or3_b32 v6, v6, v18, v19
	v_mad_u64_u32 v[18:19], s[22:23], v3, s63, v[2:3]
	v_or_b32_e32 v3, 48, v155
	ds_write_b32 v18, v6
	v_lshl_add_u32 v19, v3, 3, v219
	ds_read_b64 v[6:7], v19
	v_lshrrev_b32_e32 v130, 1, v3
	v_mul_lo_u32 v136, v130, s63
	v_add_u32_e32 v135, v154, v136
	s_waitcnt lgkmcnt(0)
;     ...
;         _Pragma("unroll") for (int ai = 0; ai < 2; ++ai) {
;           _Pragma("unroll") for (int bj = 0; bj < 2; ++bj) _Pragma("unroll") for (int n = 0; n < 2; ++n) {
;             const int cc = bj * HALF + wc3 * 32 + n * 16 + fq3 * 4;
;             const float4 gm = *reinterpret_cast<const float4*>(g.gam + pn * BM + cc), bt = *reinterpret_cast<const float4*>(g.bet + pn * BM + cc);
;             _Pragma("unroll") for (int m = 0; m < 4; ++m) {
;               const int rr = wr3 * 64 + m * 16 + fr3;
;               const float2 ms = *reinterpret_cast<const float2*>(mr + (ai * HALF + rr) * 2);
;               f32x4 y = acc[ai][bj][m][n];
;               const float o0 = (y[0] - ms.x) * ms.y * gm.x + bt.x, o1 = (y[1] - ms.x) * ms.y * gm.y + bt.y;
;               const float o2 = (y[2] - ms.x) * ms.y * gm.z + bt.z, o3 = (y[3] - ms.x) * ms.y * gm.w + bt.w;
;               const unsigned h0 = f2bf(o0), h1 = f2bf(o1), h2 = f2bf(o2), h3 = f2bf(o3);
;               u32x2 ob; ob[0] = h0 | (h1 << 16); ob[1] = h2 | (h3 << 16);
;               *reinterpret_cast<u32x2*>(smem + (rr >> 1) * PIECE + (rr & 1) * 512 + cc * 2) = ob;
;               const int l0 = min(((int)__float_as_uint(o0) - (int)(h0 << 16) + 128) >> 8, 127);
;               const int l1 = min(((int)__float_as_uint(o1) - (int)(h1 << 16) + 128) >> 8, 127);
;               const int l2 = min(((int)__float_as_uint(o2) - (int)(h2 << 16) + 128) >> 8, 127);
;               const int l3 = min(((int)__float_as_uint(o3) - (int)(h3 << 16) + 128) >> 8, 127);
;               *reinterpret_cast<unsigned*>(smem + LOBASE + (rr >> 2) * PIECE + (rr & 3) * 256 + cc) =
;                   (unsigned)(l0 & 255) | ((unsigned)(l1 & 255) << 8) | ((unsigned)(l2 & 255) << 16) | ((unsigned)l3 << 24);
;             }
	v_pk_add_f32 v[122:123], v[140:141], v[6:7] op_sel_hi:[1,0] neg_lo:[0,1] neg_hi:[0,1]
	s_nop 0
	v_pk_mul_f32 v[122:123], v[6:7], v[122:123] op_sel:[1,0]
	s_nop 0
	v_pk_fma_f32 v[22:23], v[22:23], v[122:123], v[144:145]
	v_pk_add_f32 v[122:123], v[142:143], v[6:7] op_sel_hi:[1,0] neg_lo:[0,1] neg_hi:[0,1]
	s_nop 0
	v_pk_mul_f32 v[6:7], v[6:7], v[122:123] op_sel:[1,0]
	s_nop 0
	v_pk_fma_f32 v[0:1], v[0:1], v[6:7], v[4:5]
	v_and_b32_sdwa v4, v23, v216 dst_sel:DWORD dst_unused:UNUSED_PAD src0_sel:WORD_1 src1_sel:DWORD
	v_and_b32_sdwa v5, v22, v216 dst_sel:DWORD dst_unused:UNUSED_PAD src0_sel:WORD_1 src1_sel:DWORD
	v_add3_u32 v6, v23, v4, s84
	v_add3_u32 v4, v22, v5, s84
	v_and_b32_e32 v7, 0xffff0000, v4
	v_and_b32_sdwa v4, v1, v216 dst_sel:DWORD dst_unused:UNUSED_PAD src0_sel:WORD_1 src1_sel:DWORD
	v_and_b32_sdwa v5, v0, v216 dst_sel:DWORD dst_unused:UNUSED_PAD src0_sel:WORD_1 src1_sel:DWORD
	v_add3_u32 v4, v1, v4, s84
	v_add3_u32 v122, v0, v5, s84
	v_and_b32_e32 v123, 0xffff0000, v4
	v_or_b32_sdwa v5, v123, v6 dst_sel:DWORD dst_unused:UNUSED_PAD src0_sel:DWORD src1_sel:WORD_1
	v_or_b32_sdwa v4, v122, v7 dst_sel:DWORD dst_unused:UNUSED_PAD src0_sel:WORD_1 src1_sel:DWORD
	ds_write_b64 v135, v[4:5]
	v_and_b32_e32 v4, 0xffff0000, v122
	v_sub_u32_e32 v0, v0, v4
	v_sub_u32_e32 v4, v22, v7
	v_and_b32_e32 v5, 0xffff0000, v6
	v_add_u32_e32 v4, 0x80, v4
	v_sub_u32_e32 v5, v23, v5
	v_sub_u32_e32 v1, v1, v123
	v_add_u32_e32 v0, 0x80, v0
	v_ashrrev_i32_e32 v4, 8, v4
	v_add_u32_e32 v5, 0x80, v5
	v_add_u32_e32 v1, 0x80, v1
	v_ashrrev_i32_e32 v0, 8, v0
	v_min_i32_e32 v4, 0x7f, v4
	v_ashrrev_i32_e32 v5, 8, v5
	v_ashrrev_i32_e32 v1, 8, v1
	v_min_i32_e32 v0, 0x7f, v0
	v_min_i32_sdwa v5, v5, s85 dst_sel:WORD_1 dst_unused:UNUSED_PAD src0_sel:DWORD src1_sel:DWORD
	v_min_i32_e32 v1, 0x7f, v1
	v_lshlrev_b32_e32 v4, 8, v4
	v_and_b32_e32 v4, 0xff00, v4
	v_and_b32_e32 v5, 0xff0000, v5
	v_perm_b32 v0, v1, v0, s92
	v_lshrrev_b32_e32 v1, 2, v3
	v_or3_b32 v0, v0, v4, v5
	v_mad_u64_u32 v[22:23], s[22:23], v1, s63, v[2:3]
	ds_write_b32 v22, v0
	v_mov_b32_e32 v0, v224
	v_mov_b32_e32 v1, v225
	v_mov_b32_e32 v2, v226
	v_mov_b32_e32 v3, v227
	v_mov_b32_e32 v4, v240
	v_mov_b32_e32 v5, v241
	v_mov_b32_e32 v6, v242
	v_mov_b32_e32 v7, v243
	ds_read_b64 v[138:139], v149
	s_mov_b32 s22, s18
	s_mov_b32 s23, s19
	s_waitcnt lgkmcnt(0)
	v_pk_add_f32 v[128:129], v[128:129], v[138:139] op_sel_hi:[1,0] neg_lo:[0,1] neg_hi:[0,1]
	s_nop 0
	v_pk_mul_f32 v[128:129], v[138:139], v[128:129] op_sel:[1,0]
	v_pk_add_f32 v[126:127], v[126:127], v[138:139] op_sel_hi:[1,0] neg_lo:[0,1] neg_hi:[0,1]
	v_mov_b32_e32 v122, v1
	v_mov_b32_e32 v123, v2
	v_mov_b32_e32 v130, v5
	v_mov_b32_e32 v131, v6
	v_pk_fma_f32 v[128:129], v[122:123], v[128:129], v[130:131]
	v_pk_mul_f32 v[126:127], v[138:139], v[126:127] op_sel:[1,0]
	v_mov_b32_e32 v1, v3
	v_mov_b32_e32 v5, v7
	v_and_b32_sdwa v23, v128, v216 dst_sel:DWORD dst_unused:UNUSED_PAD src0_sel:WORD_1 src1_sel:DWORD
	v_pk_fma_f32 v[6:7], v[0:1], v[126:127], v[4:5]
	v_add3_u32 v23, v128, v23, s84
	v_and_b32_e32 v138, 0xffff0000, v23
	v_and_b32_sdwa v23, v7, v216 dst_sel:DWORD dst_unused:UNUSED_PAD src0_sel:WORD_1 src1_sel:DWORD
	v_and_b32_sdwa v3, v129, v216 dst_sel:DWORD dst_unused:UNUSED_PAD src0_sel:WORD_1 src1_sel:DWORD
	v_and_b32_sdwa v126, v6, v216 dst_sel:DWORD dst_unused:UNUSED_PAD src0_sel:WORD_1 src1_sel:DWORD
	v_add3_u32 v23, v7, v23, s84
	v_or_b32_e32 v2, 32, v154
	v_add3_u32 v3, v129, v3, s84
	v_add3_u32 v139, v6, v126, s84
	v_and_b32_e32 v140, 0xffff0000, v23
	v_or_b32_sdwa v127, v140, v3 dst_sel:DWORD dst_unused:UNUSED_PAD src0_sel:DWORD src1_sel:WORD_1
	v_or_b32_sdwa v126, v139, v138 dst_sel:DWORD dst_unused:UNUSED_PAD src0_sel:WORD_1 src1_sel:DWORD
	v_add_u32_e32 v23, v2, v152
	ds_write_b64 v23, v[126:127]
	v_and_b32_e32 v126, 0xffff0000, v139
	v_sub_u32_e32 v6, v6, v126
	v_sub_u32_e32 v126, v128, v138
	v_and_b32_e32 v3, 0xffff0000, v3
	v_add_u32_e32 v126, 0x80, v126
	v_sub_u32_e32 v3, v129, v3
	v_sub_u32_e32 v7, v7, v140
	v_add_u32_e32 v6, 0x80, v6
	v_ashrrev_i32_e32 v126, 8, v126
	v_add_u32_e32 v3, 0x80, v3
	v_add_u32_e32 v7, 0x80, v7
	v_ashrrev_i32_e32 v6, 8, v6
	v_min_i32_e32 v126, 0x7f, v126
	v_ashrrev_i32_e32 v3, 8, v3
	v_ashrrev_i32_e32 v7, 8, v7
	v_min_i32_e32 v6, 0x7f, v6
	v_min_i32_sdwa v3, v3, s85 dst_sel:WORD_1 dst_unused:UNUSED_PAD src0_sel:DWORD src1_sel:DWORD
	v_min_i32_e32 v7, 0x7f, v7
	v_lshlrev_b32_e32 v126, 8, v126
	v_and_b32_e32 v126, 0xff00, v126
	v_and_b32_e32 v3, 0xff0000, v3
	v_perm_b32 v6, v7, v6, s92
	v_or3_b32 v3, v6, v126, v3
	ds_write_b32 v12, v3 offset:16
	ds_read_b64 v[6:7], v13
	s_waitcnt lgkmcnt(0)
;     ...
;         _Pragma("unroll") for (int ai = 0; ai < 2; ++ai) {
;           _Pragma("unroll") for (int bj = 0; bj < 2; ++bj) _Pragma("unroll") for (int n = 0; n < 2; ++n) {
;             const int cc = bj * HALF + wc3 * 32 + n * 16 + fq3 * 4;
;             const float4 gm = *reinterpret_cast<const float4*>(g.gam + pn * BM + cc), bt = *reinterpret_cast<const float4*>(g.bet + pn * BM + cc);
;             _Pragma("unroll") for (int m = 0; m < 4; ++m) {
;               const int rr = wr3 * 64 + m * 16 + fr3;
;               const float2 ms = *reinterpret_cast<const float2*>(mr + (ai * HALF + rr) * 2);
;               f32x4 y = acc[ai][bj][m][n];
;               const float o0 = (y[0] - ms.x) * ms.y * gm.x + bt.x, o1 = (y[1] - ms.x) * ms.y * gm.y + bt.y;
;               const float o2 = (y[2] - ms.x) * ms.y * gm.z + bt.z, o3 = (y[3] - ms.x) * ms.y * gm.w + bt.w;
;               const unsigned h0 = f2bf(o0), h1 = f2bf(o1), h2 = f2bf(o2), h3 = f2bf(o3);
;               u32x2 ob; ob[0] = h0 | (h1 << 16); ob[1] = h2 | (h3 << 16);
;               *reinterpret_cast<u32x2*>(smem + (rr >> 1) * PIECE + (rr & 1) * 512 + cc * 2) = ob;
;               const int l0 = min(((int)__float_as_uint(o0) - (int)(h0 << 16) + 128) >> 8, 127);
;               const int l1 = min(((int)__float_as_uint(o1) - (int)(h1 << 16) + 128) >> 8, 127);
;               const int l2 = min(((int)__float_as_uint(o2) - (int)(h2 << 16) + 128) >> 8, 127);
;               const int l3 = min(((int)__float_as_uint(o3) - (int)(h3 << 16) + 128) >> 8, 127);
;               *reinterpret_cast<unsigned*>(smem + LOBASE + (rr >> 2) * PIECE + (rr & 3) * 256 + cc) =
;                   (unsigned)(l0 & 255) | ((unsigned)(l1 & 255) << 8) | ((unsigned)(l2 & 255) << 16) | ((unsigned)l3 << 24);
;             }
	v_pk_add_f32 v[108:109], v[108:109], v[6:7] op_sel_hi:[1,0] neg_lo:[0,1] neg_hi:[0,1]
	s_nop 0
	v_pk_mul_f32 v[108:109], v[6:7], v[108:109] op_sel:[1,0]
	s_nop 0
	v_pk_fma_f32 v[126:127], v[122:123], v[108:109], v[130:131]
	v_pk_add_f32 v[108:109], v[110:111], v[6:7] op_sel_hi:[1,0] neg_lo:[0,1] neg_hi:[0,1]
	v_and_b32_sdwa v3, v127, v216 dst_sel:DWORD dst_unused:UNUSED_PAD src0_sel:WORD_1 src1_sel:DWORD
	v_pk_mul_f32 v[6:7], v[6:7], v[108:109] op_sel:[1,0]
	v_and_b32_sdwa v108, v126, v216 dst_sel:DWORD dst_unused:UNUSED_PAD src0_sel:WORD_1 src1_sel:DWORD
	v_pk_fma_f32 v[6:7], v[0:1], v[6:7], v[4:5]
	v_add3_u32 v108, v126, v108, s84
	v_and_b32_e32 v109, 0xffff0000, v108
	v_and_b32_sdwa v108, v7, v216 dst_sel:DWORD dst_unused:UNUSED_PAD src0_sel:WORD_1 src1_sel:DWORD
	v_and_b32_sdwa v110, v6, v216 dst_sel:DWORD dst_unused:UNUSED_PAD src0_sel:WORD_1 src1_sel:DWORD
	v_add3_u32 v108, v7, v108, s84
	v_add3_u32 v3, v127, v3, s84
	v_add3_u32 v128, v6, v110, s84
	v_and_b32_e32 v129, 0xffff0000, v108
	v_or_b32_sdwa v111, v129, v3 dst_sel:DWORD dst_unused:UNUSED_PAD src0_sel:DWORD src1_sel:WORD_1
	v_or_b32_sdwa v110, v128, v109 dst_sel:DWORD dst_unused:UNUSED_PAD src0_sel:WORD_1 src1_sel:DWORD
	v_add_u32_e32 v108, v2, v153
	ds_write_b64 v108, v[110:111]
	v_and_b32_e32 v110, 0xffff0000, v128
	v_sub_u32_e32 v109, v126, v109
	v_and_b32_e32 v3, 0xffff0000, v3
	v_sub_u32_e32 v6, v6, v110
	v_add_u32_e32 v109, 0x80, v109
	v_sub_u32_e32 v3, v127, v3
	v_sub_u32_e32 v7, v7, v129
	v_add_u32_e32 v6, 0x80, v6
	v_ashrrev_i32_e32 v109, 8, v109
	v_add_u32_e32 v3, 0x80, v3
	v_add_u32_e32 v7, 0x80, v7
	v_ashrrev_i32_e32 v6, 8, v6
	v_min_i32_e32 v109, 0x7f, v109
	v_ashrrev_i32_e32 v3, 8, v3
	v_ashrrev_i32_e32 v7, 8, v7
	v_min_i32_e32 v6, 0x7f, v6
	v_min_i32_sdwa v3, v3, s85 dst_sel:WORD_1 dst_unused:UNUSED_PAD src0_sel:DWORD src1_sel:DWORD
	v_min_i32_e32 v7, 0x7f, v7
	v_lshlrev_b32_e32 v109, 8, v109
	v_and_b32_e32 v109, 0xff00, v109
	v_and_b32_e32 v3, 0xff0000, v3
	v_perm_b32 v6, v7, v6, s92
	v_or3_b32 v3, v6, v109, v3
	ds_write_b32 v14, v3 offset:16
	ds_read_b64 v[6:7], v15
	s_waitcnt lgkmcnt(0)
	v_pk_add_f32 v[98:99], v[98:99], v[6:7] op_sel_hi:[1,0] neg_lo:[0,1] neg_hi:[0,1]
	s_nop 0
	v_pk_mul_f32 v[98:99], v[6:7], v[98:99] op_sel:[1,0]
	s_nop 0
	v_pk_fma_f32 v[110:111], v[122:123], v[98:99], v[130:131]
	v_pk_add_f32 v[98:99], v[106:107], v[6:7] op_sel_hi:[1,0] neg_lo:[0,1] neg_hi:[0,1]
	v_and_b32_sdwa v3, v111, v216 dst_sel:DWORD dst_unused:UNUSED_PAD src0_sel:WORD_1 src1_sel:DWORD
	v_pk_mul_f32 v[6:7], v[6:7], v[98:99] op_sel:[1,0]
	v_and_b32_sdwa v98, v110, v216 dst_sel:DWORD dst_unused:UNUSED_PAD src0_sel:WORD_1 src1_sel:DWORD
	v_pk_fma_f32 v[6:7], v[0:1], v[6:7], v[4:5]
	v_add3_u32 v98, v110, v98, s84
	v_and_b32_e32 v99, 0xffff0000, v98
	v_and_b32_sdwa v98, v7, v216 dst_sel:DWORD dst_unused:UNUSED_PAD src0_sel:WORD_1 src1_sel:DWORD
	v_and_b32_sdwa v106, v6, v216 dst_sel:DWORD dst_unused:UNUSED_PAD src0_sel:WORD_1 src1_sel:DWORD
	v_add3_u32 v98, v7, v98, s84
	v_add3_u32 v3, v111, v3, s84
	v_add3_u32 v109, v6, v106, s84
	v_and_b32_e32 v126, 0xffff0000, v98
	v_or_b32_sdwa v107, v126, v3 dst_sel:DWORD dst_unused:UNUSED_PAD src0_sel:DWORD src1_sel:WORD_1
	v_or_b32_sdwa v106, v109, v99 dst_sel:DWORD dst_unused:UNUSED_PAD src0_sel:WORD_1 src1_sel:DWORD
	v_add_u32_e32 v98, v2, v137
	ds_write_b64 v98, v[106:107]
	v_and_b32_e32 v106, 0xffff0000, v109
	v_sub_u32_e32 v99, v110, v99
	v_and_b32_e32 v3, 0xffff0000, v3
	v_sub_u32_e32 v6, v6, v106
	v_add_u32_e32 v99, 0x80, v99
	v_sub_u32_e32 v3, v111, v3
	v_sub_u32_e32 v7, v7, v126
	v_add_u32_e32 v6, 0x80, v6
	v_ashrrev_i32_e32 v99, 8, v99
	v_add_u32_e32 v3, 0x80, v3
	v_add_u32_e32 v7, 0x80, v7
	v_ashrrev_i32_e32 v6, 8, v6
	v_min_i32_e32 v99, 0x7f, v99
	v_ashrrev_i32_e32 v3, 8, v3
	v_ashrrev_i32_e32 v7, 8, v7
	v_min_i32_e32 v6, 0x7f, v6
	v_min_i32_sdwa v3, v3, s85 dst_sel:WORD_1 dst_unused:UNUSED_PAD src0_sel:DWORD src1_sel:DWORD
	v_min_i32_e32 v7, 0x7f, v7
	v_lshlrev_b32_e32 v99, 8, v99
	v_and_b32_e32 v99, 0xff00, v99
	v_and_b32_e32 v3, 0xff0000, v3
	v_perm_b32 v6, v7, v6, s92
	v_or3_b32 v3, v6, v99, v3
	ds_write_b32 v18, v3 offset:16
	ds_read_b64 v[6:7], v19
	v_add_u32_e32 v99, v2, v136
	s_waitcnt lgkmcnt(0)
	v_pk_add_f32 v[106:107], v[114:115], v[6:7] op_sel_hi:[1,0] neg_lo:[0,1] neg_hi:[0,1]
	s_nop 0
	v_pk_mul_f32 v[106:107], v[6:7], v[106:107] op_sel:[1,0]
	v_pk_add_f32 v[110:111], v[120:121], v[6:7] op_sel_hi:[1,0] neg_lo:[0,1] neg_hi:[0,1]
	v_pk_fma_f32 v[106:107], v[122:123], v[106:107], v[130:131]
	v_pk_mul_f32 v[6:7], v[6:7], v[110:111] op_sel:[1,0]
	v_and_b32_sdwa v3, v107, v216 dst_sel:DWORD dst_unused:UNUSED_PAD src0_sel:WORD_1 src1_sel:DWORD
	v_pk_fma_f32 v[0:1], v[0:1], v[6:7], v[4:5]
	v_and_b32_sdwa v4, v106, v216 dst_sel:DWORD dst_unused:UNUSED_PAD src0_sel:WORD_1 src1_sel:DWORD
	v_add3_u32 v4, v106, v4, s84
	v_and_b32_e32 v6, 0xffff0000, v4
	v_and_b32_sdwa v4, v1, v216 dst_sel:DWORD dst_unused:UNUSED_PAD src0_sel:WORD_1 src1_sel:DWORD
	v_and_b32_sdwa v5, v0, v216 dst_sel:DWORD dst_unused:UNUSED_PAD src0_sel:WORD_1 src1_sel:DWORD
	v_add3_u32 v4, v1, v4, s84
	v_add3_u32 v7, v0, v5, s84
	v_add3_u32 v3, v107, v3, s84
	v_and_b32_e32 v109, 0xffff0000, v4
	v_and_b32_e32 v2, 0xffff0000, v7
	v_or_b32_sdwa v5, v109, v3 dst_sel:DWORD dst_unused:UNUSED_PAD src0_sel:DWORD src1_sel:WORD_1
	v_sub_u32_e32 v0, v0, v2
	v_sub_u32_e32 v2, v106, v6
	v_and_b32_e32 v3, 0xffff0000, v3
	v_add_u32_e32 v2, 0x80, v2
	v_sub_u32_e32 v3, v107, v3
	v_sub_u32_e32 v1, v1, v109
	v_add_u32_e32 v0, 0x80, v0
	v_ashrrev_i32_e32 v2, 8, v2
	v_add_u32_e32 v3, 0x80, v3
	v_add_u32_e32 v1, 0x80, v1
	v_ashrrev_i32_e32 v0, 8, v0
	v_min_i32_e32 v2, 0x7f, v2
	v_ashrrev_i32_e32 v3, 8, v3
	v_ashrrev_i32_e32 v1, 8, v1
	v_min_i32_e32 v0, 0x7f, v0
	v_min_i32_sdwa v3, v3, s85 dst_sel:WORD_1 dst_unused:UNUSED_PAD src0_sel:DWORD src1_sel:DWORD
	v_min_i32_e32 v1, 0x7f, v1
	v_lshlrev_b32_e32 v2, 8, v2
	v_and_b32_e32 v2, 0xff00, v2
	v_and_b32_e32 v3, 0xff0000, v3
	v_perm_b32 v0, v1, v0, s92
	v_or_b32_sdwa v4, v7, v6 dst_sel:DWORD dst_unused:UNUSED_PAD src0_sel:WORD_1 src1_sel:DWORD
	v_or3_b32 v0, v0, v2, v3
	ds_write_b64 v99, v[4:5]
	ds_write_b32 v22, v0 offset:16
	v_mov_b32_e32 v0, v228
	v_mov_b32_e32 v1, v229
	v_mov_b32_e32 v2, v230
	v_mov_b32_e32 v3, v231
	v_mov_b32_e32 v4, v244
	v_mov_b32_e32 v5, v245
	v_mov_b32_e32 v6, v246
	v_mov_b32_e32 v7, v247
	ds_read_b64 v[106:107], v149
	v_or_b32_e32 v109, 0x100, v154
	s_waitcnt lgkmcnt(0)
;     ...
;         _Pragma("unroll") for (int ai = 0; ai < 2; ++ai) {
;           _Pragma("unroll") for (int bj = 0; bj < 2; ++bj) _Pragma("unroll") for (int n = 0; n < 2; ++n) {
;             const int cc = bj * HALF + wc3 * 32 + n * 16 + fq3 * 4;
;             const float4 gm = *reinterpret_cast<const float4*>(g.gam + pn * BM + cc), bt = *reinterpret_cast<const float4*>(g.bet + pn * BM + cc);
;             _Pragma("unroll") for (int m = 0; m < 4; ++m) {
;               const int rr = wr3 * 64 + m * 16 + fr3;
;               const float2 ms = *reinterpret_cast<const float2*>(mr + (ai * HALF + rr) * 2);
;               f32x4 y = acc[ai][bj][m][n];
;               const float o0 = (y[0] - ms.x) * ms.y * gm.x + bt.x, o1 = (y[1] - ms.x) * ms.y * gm.y + bt.y;
;               const float o2 = (y[2] - ms.x) * ms.y * gm.z + bt.z, o3 = (y[3] - ms.x) * ms.y * gm.w + bt.w;
;               const unsigned h0 = f2bf(o0), h1 = f2bf(o1), h2 = f2bf(o2), h3 = f2bf(o3);
;               u32x2 ob; ob[0] = h0 | (h1 << 16); ob[1] = h2 | (h3 << 16);
;               *reinterpret_cast<u32x2*>(smem + (rr >> 1) * PIECE + (rr & 1) * 512 + cc * 2) = ob;
;               const int l0 = min(((int)__float_as_uint(o0) - (int)(h0 << 16) + 128) >> 8, 127);
;               const int l1 = min(((int)__float_as_uint(o1) - (int)(h1 << 16) + 128) >> 8, 127);
;               const int l2 = min(((int)__float_as_uint(o2) - (int)(h2 << 16) + 128) >> 8, 127);
;               const int l3 = min(((int)__float_as_uint(o3) - (int)(h3 << 16) + 128) >> 8, 127);
;               *reinterpret_cast<unsigned*>(smem + LOBASE + (rr >> 2) * PIECE + (rr & 3) * 256 + cc) =
;                   (unsigned)(l0 & 255) | ((unsigned)(l1 & 255) << 8) | ((unsigned)(l2 & 255) << 16) | ((unsigned)l3 << 24);
;             }
	v_pk_add_f32 v[120:121], v[124:125], v[106:107] op_sel_hi:[1,0] neg_lo:[0,1] neg_hi:[0,1]
	s_nop 0
	v_pk_mul_f32 v[120:121], v[106:107], v[120:121] op_sel:[1,0]
	v_pk_add_f32 v[118:119], v[118:119], v[106:107] op_sel_hi:[1,0] neg_lo:[0,1] neg_hi:[0,1]
	v_mov_b32_e32 v110, v1
	v_mov_b32_e32 v111, v2
	v_mov_b32_e32 v114, v5
	v_mov_b32_e32 v115, v6
	v_pk_fma_f32 v[120:121], v[110:111], v[120:121], v[114:115]
	v_pk_mul_f32 v[106:107], v[106:107], v[118:119] op_sel:[1,0]
	v_mov_b32_e32 v1, v3
	v_mov_b32_e32 v5, v7
	v_and_b32_sdwa v6, v121, v216 dst_sel:DWORD dst_unused:UNUSED_PAD src0_sel:WORD_1 src1_sel:DWORD
	v_and_b32_sdwa v7, v120, v216 dst_sel:DWORD dst_unused:UNUSED_PAD src0_sel:WORD_1 src1_sel:DWORD
	v_pk_fma_f32 v[2:3], v[0:1], v[106:107], v[4:5]
	v_add3_u32 v107, v121, v6, s84
	v_add3_u32 v6, v120, v7, s84
	v_and_b32_e32 v118, 0xffff0000, v6
	v_and_b32_sdwa v6, v3, v216 dst_sel:DWORD dst_unused:UNUSED_PAD src0_sel:WORD_1 src1_sel:DWORD
	v_and_b32_sdwa v7, v2, v216 dst_sel:DWORD dst_unused:UNUSED_PAD src0_sel:WORD_1 src1_sel:DWORD
	v_add3_u32 v6, v3, v6, s84
	v_add3_u32 v119, v2, v7, s84
	v_and_b32_e32 v122, 0xffff0000, v6
	v_or_b32_sdwa v7, v122, v107 dst_sel:DWORD dst_unused:UNUSED_PAD src0_sel:DWORD src1_sel:WORD_1
	v_or_b32_sdwa v6, v119, v118 dst_sel:DWORD dst_unused:UNUSED_PAD src0_sel:WORD_1 src1_sel:DWORD
	v_add_u32_e32 v106, v109, v152
	ds_write_b64 v106, v[6:7]
	v_and_b32_e32 v6, 0xffff0000, v119
	v_sub_u32_e32 v2, v2, v6
	v_sub_u32_e32 v6, v120, v118
	v_and_b32_e32 v7, 0xffff0000, v107
	v_add_u32_e32 v6, 0x80, v6
	v_sub_u32_e32 v7, v121, v7
	v_sub_u32_e32 v3, v3, v122
	v_add_u32_e32 v2, 0x80, v2
	v_ashrrev_i32_e32 v6, 8, v6
	v_add_u32_e32 v7, 0x80, v7
	v_add_u32_e32 v3, 0x80, v3
	v_ashrrev_i32_e32 v2, 8, v2
	v_min_i32_e32 v6, 0x7f, v6
	v_ashrrev_i32_e32 v7, 8, v7
	v_ashrrev_i32_e32 v3, 8, v3
	v_min_i32_e32 v2, 0x7f, v2
	v_min_i32_sdwa v7, v7, s85 dst_sel:WORD_1 dst_unused:UNUSED_PAD src0_sel:DWORD src1_sel:DWORD
	v_min_i32_e32 v3, 0x7f, v3
	v_lshlrev_b32_e32 v6, 8, v6
	v_and_b32_e32 v6, 0xff00, v6
	v_and_b32_e32 v7, 0xff0000, v7
	v_perm_b32 v2, v3, v2, s92
	v_or3_b32 v2, v2, v6, v7
	ds_write_b32 v12, v2 offset:128
	ds_read_b64 v[2:3], v13
	s_waitcnt lgkmcnt(0)
	v_pk_add_f32 v[6:7], v[102:103], v[2:3] op_sel_hi:[1,0] neg_lo:[0,1] neg_hi:[0,1]
	s_nop 0
	v_pk_mul_f32 v[6:7], v[2:3], v[6:7] op_sel:[1,0]
	v_pk_add_f32 v[102:103], v[104:105], v[2:3] op_sel_hi:[1,0] neg_lo:[0,1] neg_hi:[0,1]
	v_pk_fma_f32 v[6:7], v[110:111], v[6:7], v[114:115]
	v_pk_mul_f32 v[2:3], v[2:3], v[102:103] op_sel:[1,0]
	v_and_b32_sdwa v102, v7, v216 dst_sel:DWORD dst_unused:UNUSED_PAD src0_sel:WORD_1 src1_sel:DWORD
	v_and_b32_sdwa v103, v6, v216 dst_sel:DWORD dst_unused:UNUSED_PAD src0_sel:WORD_1 src1_sel:DWORD
	v_pk_fma_f32 v[2:3], v[0:1], v[2:3], v[4:5]
	v_add3_u32 v107, v7, v102, s84
	v_add3_u32 v102, v6, v103, s84
	v_and_b32_e32 v103, 0xffff0000, v102
	v_and_b32_sdwa v102, v3, v216 dst_sel:DWORD dst_unused:UNUSED_PAD src0_sel:WORD_1 src1_sel:DWORD
	v_and_b32_sdwa v104, v2, v216 dst_sel:DWORD dst_unused:UNUSED_PAD src0_sel:WORD_1 src1_sel:DWORD
	v_add3_u32 v102, v3, v102, s84
	v_add3_u32 v118, v2, v104, s84
	v_and_b32_e32 v119, 0xffff0000, v102
	v_or_b32_sdwa v105, v119, v107 dst_sel:DWORD dst_unused:UNUSED_PAD src0_sel:DWORD src1_sel:WORD_1
	v_or_b32_sdwa v104, v118, v103 dst_sel:DWORD dst_unused:UNUSED_PAD src0_sel:WORD_1 src1_sel:DWORD
	v_add_u32_e32 v102, v109, v153
	ds_write_b64 v102, v[104:105]
	v_and_b32_e32 v104, 0xffff0000, v118
	v_sub_u32_e32 v6, v6, v103
	v_and_b32_e32 v103, 0xffff0000, v107
	v_sub_u32_e32 v2, v2, v104
	v_add_u32_e32 v6, 0x80, v6
	v_sub_u32_e32 v7, v7, v103
	v_sub_u32_e32 v3, v3, v119
	v_add_u32_e32 v2, 0x80, v2
	v_ashrrev_i32_e32 v6, 8, v6
	v_add_u32_e32 v7, 0x80, v7
	v_add_u32_e32 v3, 0x80, v3
	v_ashrrev_i32_e32 v2, 8, v2
	v_min_i32_e32 v6, 0x7f, v6
	v_ashrrev_i32_e32 v7, 8, v7
	v_ashrrev_i32_e32 v3, 8, v3
	v_min_i32_e32 v2, 0x7f, v2
	v_min_i32_sdwa v7, v7, s85 dst_sel:WORD_1 dst_unused:UNUSED_PAD src0_sel:DWORD src1_sel:DWORD
	v_min_i32_e32 v3, 0x7f, v3
	v_lshlrev_b32_e32 v6, 8, v6
	v_and_b32_e32 v6, 0xff00, v6
	v_and_b32_e32 v7, 0xff0000, v7
	v_perm_b32 v2, v3, v2, s92
	v_or3_b32 v2, v2, v6, v7
	ds_write_b32 v14, v2 offset:128
	ds_read_b64 v[2:3], v15
	s_waitcnt lgkmcnt(0)
	v_pk_add_f32 v[6:7], v[92:93], v[2:3] op_sel_hi:[1,0] neg_lo:[0,1] neg_hi:[0,1]
	s_nop 0
	v_pk_mul_f32 v[6:7], v[2:3], v[6:7] op_sel:[1,0]
	v_pk_add_f32 v[88:89], v[88:89], v[2:3] op_sel_hi:[1,0] neg_lo:[0,1] neg_hi:[0,1]
	v_pk_fma_f32 v[6:7], v[110:111], v[6:7], v[114:115]
	v_pk_mul_f32 v[2:3], v[2:3], v[88:89] op_sel:[1,0]
	v_and_b32_sdwa v88, v7, v216 dst_sel:DWORD dst_unused:UNUSED_PAD src0_sel:WORD_1 src1_sel:DWORD
	v_and_b32_sdwa v89, v6, v216 dst_sel:DWORD dst_unused:UNUSED_PAD src0_sel:WORD_1 src1_sel:DWORD
	v_pk_fma_f32 v[2:3], v[0:1], v[2:3], v[4:5]
	v_add3_u32 v93, v7, v88, s84
	v_add3_u32 v88, v6, v89, s84
	v_and_b32_e32 v103, 0xffff0000, v88
	v_and_b32_sdwa v88, v3, v216 dst_sel:DWORD dst_unused:UNUSED_PAD src0_sel:WORD_1 src1_sel:DWORD
	v_and_b32_sdwa v89, v2, v216 dst_sel:DWORD dst_unused:UNUSED_PAD src0_sel:WORD_1 src1_sel:DWORD
	v_add3_u32 v88, v3, v88, s84
	v_add3_u32 v104, v2, v89, s84
	v_and_b32_e32 v105, 0xffff0000, v88
	v_or_b32_sdwa v89, v105, v93 dst_sel:DWORD dst_unused:UNUSED_PAD src0_sel:DWORD src1_sel:WORD_1
	v_or_b32_sdwa v88, v104, v103 dst_sel:DWORD dst_unused:UNUSED_PAD src0_sel:WORD_1 src1_sel:DWORD
	v_add_u32_e32 v92, v109, v137
	ds_write_b64 v92, v[88:89]
	v_and_b32_e32 v88, 0xffff0000, v104
	v_sub_u32_e32 v2, v2, v88
	v_sub_u32_e32 v6, v6, v103
	v_and_b32_e32 v88, 0xffff0000, v93
	v_add_u32_e32 v6, 0x80, v6
	v_sub_u32_e32 v7, v7, v88
	v_sub_u32_e32 v3, v3, v105
	v_add_u32_e32 v2, 0x80, v2
	v_ashrrev_i32_e32 v6, 8, v6
	v_add_u32_e32 v7, 0x80, v7
	v_add_u32_e32 v3, 0x80, v3
	v_ashrrev_i32_e32 v2, 8, v2
	v_min_i32_e32 v6, 0x7f, v6
	v_ashrrev_i32_e32 v7, 8, v7
	v_ashrrev_i32_e32 v3, 8, v3
	v_min_i32_e32 v2, 0x7f, v2
	v_min_i32_sdwa v7, v7, s85 dst_sel:WORD_1 dst_unused:UNUSED_PAD src0_sel:DWORD src1_sel:DWORD
	v_min_i32_e32 v3, 0x7f, v3
	v_lshlrev_b32_e32 v6, 8, v6
	v_and_b32_e32 v6, 0xff00, v6
	v_and_b32_e32 v7, 0xff0000, v7
	v_perm_b32 v2, v3, v2, s92
	v_or3_b32 v2, v2, v6, v7
	ds_write_b32 v18, v2 offset:128
	ds_read_b64 v[2:3], v19
	v_add_u32_e32 v93, v109, v136
	s_waitcnt lgkmcnt(0)
;     ...
;         _Pragma("unroll") for (int ai = 0; ai < 2; ++ai) {
;           _Pragma("unroll") for (int bj = 0; bj < 2; ++bj) _Pragma("unroll") for (int n = 0; n < 2; ++n) {
;             const int cc = bj * HALF + wc3 * 32 + n * 16 + fq3 * 4;
;             const float4 gm = *reinterpret_cast<const float4*>(g.gam + pn * BM + cc), bt = *reinterpret_cast<const float4*>(g.bet + pn * BM + cc);
;             _Pragma("unroll") for (int m = 0; m < 4; ++m) {
;               const int rr = wr3 * 64 + m * 16 + fr3;
;               const float2 ms = *reinterpret_cast<const float2*>(mr + (ai * HALF + rr) * 2);
;               f32x4 y = acc[ai][bj][m][n];
;               const float o0 = (y[0] - ms.x) * ms.y * gm.x + bt.x, o1 = (y[1] - ms.x) * ms.y * gm.y + bt.y;
;               const float o2 = (y[2] - ms.x) * ms.y * gm.z + bt.z, o3 = (y[3] - ms.x) * ms.y * gm.w + bt.w;
;               const unsigned h0 = f2bf(o0), h1 = f2bf(o1), h2 = f2bf(o2), h3 = f2bf(o3);
;               u32x2 ob; ob[0] = h0 | (h1 << 16); ob[1] = h2 | (h3 << 16);
;               *reinterpret_cast<u32x2*>(smem + (rr >> 1) * PIECE + (rr & 1) * 512 + cc * 2) = ob;
;               const int l0 = min(((int)__float_as_uint(o0) - (int)(h0 << 16) + 128) >> 8, 127);
;               const int l1 = min(((int)__float_as_uint(o1) - (int)(h1 << 16) + 128) >> 8, 127);
;               const int l2 = min(((int)__float_as_uint(o2) - (int)(h2 << 16) + 128) >> 8, 127);
;               const int l3 = min(((int)__float_as_uint(o3) - (int)(h3 << 16) + 128) >> 8, 127);
;               *reinterpret_cast<unsigned*>(smem + LOBASE + (rr >> 2) * PIECE + (rr & 3) * 256 + cc) =
;                   (unsigned)(l0 & 255) | ((unsigned)(l1 & 255) << 8) | ((unsigned)(l2 & 255) << 16) | ((unsigned)l3 << 24);
;             }
	v_pk_add_f32 v[6:7], v[90:91], v[2:3] op_sel_hi:[1,0] neg_lo:[0,1] neg_hi:[0,1]
	s_nop 0
	v_pk_mul_f32 v[6:7], v[2:3], v[6:7] op_sel:[1,0]
	v_pk_add_f32 v[88:89], v[94:95], v[2:3] op_sel_hi:[1,0] neg_lo:[0,1] neg_hi:[0,1]
	v_pk_fma_f32 v[6:7], v[110:111], v[6:7], v[114:115]
	v_pk_mul_f32 v[2:3], v[2:3], v[88:89] op_sel:[1,0]
	s_nop 0
	v_pk_fma_f32 v[0:1], v[0:1], v[2:3], v[4:5]
	v_and_b32_sdwa v2, v7, v216 dst_sel:DWORD dst_unused:UNUSED_PAD src0_sel:WORD_1 src1_sel:DWORD
	v_and_b32_sdwa v3, v6, v216 dst_sel:DWORD dst_unused:UNUSED_PAD src0_sel:WORD_1 src1_sel:DWORD
	v_add3_u32 v4, v7, v2, s84
	v_add3_u32 v2, v6, v3, s84
	v_and_b32_e32 v5, 0xffff0000, v2
	v_and_b32_sdwa v2, v1, v216 dst_sel:DWORD dst_unused:UNUSED_PAD src0_sel:WORD_1 src1_sel:DWORD
	v_and_b32_sdwa v3, v0, v216 dst_sel:DWORD dst_unused:UNUSED_PAD src0_sel:WORD_1 src1_sel:DWORD
	v_add3_u32 v2, v1, v2, s84
	v_add3_u32 v88, v0, v3, s84
	v_and_b32_e32 v89, 0xffff0000, v2
	v_or_b32_sdwa v3, v89, v4 dst_sel:DWORD dst_unused:UNUSED_PAD src0_sel:DWORD src1_sel:WORD_1
	v_or_b32_sdwa v2, v88, v5 dst_sel:DWORD dst_unused:UNUSED_PAD src0_sel:WORD_1 src1_sel:DWORD
	ds_write_b64 v93, v[2:3]
	v_and_b32_e32 v2, 0xffff0000, v88
	v_sub_u32_e32 v0, v0, v2
	v_sub_u32_e32 v2, v6, v5
	v_and_b32_e32 v3, 0xffff0000, v4
	v_add_u32_e32 v2, 0x80, v2
	v_sub_u32_e32 v3, v7, v3
	v_sub_u32_e32 v1, v1, v89
	v_add_u32_e32 v0, 0x80, v0
	v_ashrrev_i32_e32 v2, 8, v2
	v_add_u32_e32 v3, 0x80, v3
	v_add_u32_e32 v1, 0x80, v1
	v_ashrrev_i32_e32 v0, 8, v0
	v_min_i32_e32 v2, 0x7f, v2
	v_ashrrev_i32_e32 v3, 8, v3
	v_ashrrev_i32_e32 v1, 8, v1
	v_min_i32_e32 v0, 0x7f, v0
	v_min_i32_sdwa v3, v3, s85 dst_sel:WORD_1 dst_unused:UNUSED_PAD src0_sel:DWORD src1_sel:DWORD
	v_min_i32_e32 v1, 0x7f, v1
	v_lshlrev_b32_e32 v2, 8, v2
	v_and_b32_e32 v2, 0xff00, v2
	v_and_b32_e32 v3, 0xff0000, v3
	v_perm_b32 v0, v1, v0, s92
	v_or3_b32 v0, v0, v2, v3
	ds_write_b32 v22, v0 offset:128
	v_mov_b32_e32 v0, v232
	v_mov_b32_e32 v1, v233
	v_mov_b32_e32 v2, v234
	v_mov_b32_e32 v3, v235
	v_mov_b32_e32 v4, v248
	v_mov_b32_e32 v5, v249
	v_mov_b32_e32 v6, v250
	v_mov_b32_e32 v7, v251
	ds_read_b64 v[94:95], v149
	s_waitcnt lgkmcnt(0)
	v_pk_add_f32 v[104:105], v[116:117], v[94:95] op_sel_hi:[1,0] neg_lo:[0,1] neg_hi:[0,1]
	s_nop 0
	v_pk_mul_f32 v[104:105], v[94:95], v[104:105] op_sel:[1,0]
	v_pk_add_f32 v[110:111], v[112:113], v[94:95] op_sel_hi:[1,0] neg_lo:[0,1] neg_hi:[0,1]
	v_mov_b32_e32 v88, v1
	v_mov_b32_e32 v89, v2
	v_mov_b32_e32 v90, v5
	v_mov_b32_e32 v91, v6
	v_pk_fma_f32 v[104:105], v[88:89], v[104:105], v[90:91]
	v_pk_mul_f32 v[94:95], v[94:95], v[110:111] op_sel:[1,0]
	v_mov_b32_e32 v1, v3
	v_mov_b32_e32 v5, v7
	v_pk_fma_f32 v[6:7], v[0:1], v[94:95], v[4:5]
	v_and_b32_sdwa v94, v104, v216 dst_sel:DWORD dst_unused:UNUSED_PAD src0_sel:WORD_1 src1_sel:DWORD
	v_add3_u32 v94, v104, v94, s84
	v_and_b32_e32 v95, 0xffff0000, v94
	v_and_b32_sdwa v94, v7, v216 dst_sel:DWORD dst_unused:UNUSED_PAD src0_sel:WORD_1 src1_sel:DWORD
	v_and_b32_sdwa v3, v105, v216 dst_sel:DWORD dst_unused:UNUSED_PAD src0_sel:WORD_1 src1_sel:DWORD
	v_and_b32_sdwa v103, v6, v216 dst_sel:DWORD dst_unused:UNUSED_PAD src0_sel:WORD_1 src1_sel:DWORD
	v_add3_u32 v94, v7, v94, s84
	v_add3_u32 v3, v105, v3, s84
	v_add3_u32 v103, v6, v103, s84
	v_and_b32_e32 v107, 0xffff0000, v94
	v_or_b32_sdwa v111, v107, v3 dst_sel:DWORD dst_unused:UNUSED_PAD src0_sel:DWORD src1_sel:WORD_1
	v_or_b32_sdwa v110, v103, v95 dst_sel:DWORD dst_unused:UNUSED_PAD src0_sel:WORD_1 src1_sel:DWORD
	v_and_b32_e32 v103, 0xffff0000, v103
	v_sub_u32_e32 v95, v104, v95
	v_and_b32_e32 v3, 0xffff0000, v3
	v_sub_u32_e32 v6, v6, v103
	v_add_u32_e32 v95, 0x80, v95
	v_sub_u32_e32 v3, v105, v3
	v_sub_u32_e32 v7, v7, v107
	v_add_u32_e32 v6, 0x80, v6
	v_ashrrev_i32_e32 v95, 8, v95
	v_add_u32_e32 v3, 0x80, v3
	v_add_u32_e32 v7, 0x80, v7
	v_ashrrev_i32_e32 v6, 8, v6
	v_min_i32_e32 v95, 0x7f, v95
	v_ashrrev_i32_e32 v3, 8, v3
	v_ashrrev_i32_e32 v7, 8, v7
	v_min_i32_e32 v6, 0x7f, v6
	v_min_i32_sdwa v3, v3, s85 dst_sel:WORD_1 dst_unused:UNUSED_PAD src0_sel:DWORD src1_sel:DWORD
	v_min_i32_e32 v7, 0x7f, v7
	v_lshlrev_b32_e32 v95, 8, v95
	v_or_b32_e32 v2, 0x120, v154
	v_and_b32_e32 v95, 0xff00, v95
	v_and_b32_e32 v3, 0xff0000, v3
	v_perm_b32 v6, v7, v6, s92
	v_add_u32_e32 v94, v2, v152
	v_or3_b32 v3, v6, v95, v3
	ds_write_b64 v94, v[110:111]
	ds_write_b32 v12, v3 offset:144
	ds_read_b64 v[6:7], v13
	s_waitcnt lgkmcnt(0)
	v_pk_add_f32 v[100:101], v[100:101], v[6:7] op_sel_hi:[1,0] neg_lo:[0,1] neg_hi:[0,1]
	s_nop 0
	v_pk_mul_f32 v[100:101], v[6:7], v[100:101] op_sel:[1,0]
	v_pk_add_f32 v[96:97], v[96:97], v[6:7] op_sel_hi:[1,0] neg_lo:[0,1] neg_hi:[0,1]
	v_pk_fma_f32 v[100:101], v[88:89], v[100:101], v[90:91]
	v_pk_mul_f32 v[6:7], v[6:7], v[96:97] op_sel:[1,0]
	v_and_b32_sdwa v95, v100, v216 dst_sel:DWORD dst_unused:UNUSED_PAD src0_sel:WORD_1 src1_sel:DWORD
	v_pk_fma_f32 v[6:7], v[0:1], v[6:7], v[4:5]
	v_add3_u32 v95, v100, v95, s84
	v_and_b32_e32 v103, 0xffff0000, v95
	v_and_b32_sdwa v95, v7, v216 dst_sel:DWORD dst_unused:UNUSED_PAD src0_sel:WORD_1 src1_sel:DWORD
	v_and_b32_sdwa v3, v101, v216 dst_sel:DWORD dst_unused:UNUSED_PAD src0_sel:WORD_1 src1_sel:DWORD
	v_and_b32_sdwa v96, v6, v216 dst_sel:DWORD dst_unused:UNUSED_PAD src0_sel:WORD_1 src1_sel:DWORD
	v_add3_u32 v95, v7, v95, s84
	v_add3_u32 v3, v101, v3, s84
	v_add3_u32 v104, v6, v96, s84
	v_and_b32_e32 v105, 0xffff0000, v95
	v_or_b32_sdwa v97, v105, v3 dst_sel:DWORD dst_unused:UNUSED_PAD src0_sel:DWORD src1_sel:WORD_1
	v_or_b32_sdwa v96, v104, v103 dst_sel:DWORD dst_unused:UNUSED_PAD src0_sel:WORD_1 src1_sel:DWORD
	v_add_u32_e32 v95, v2, v153
	ds_write_b64 v95, v[96:97]
	v_and_b32_e32 v96, 0xffff0000, v104
	v_sub_u32_e32 v6, v6, v96
	v_sub_u32_e32 v96, v100, v103
	v_and_b32_e32 v3, 0xffff0000, v3
	v_add_u32_e32 v96, 0x80, v96
	v_sub_u32_e32 v3, v101, v3
	v_sub_u32_e32 v7, v7, v105
	v_add_u32_e32 v6, 0x80, v6
	v_ashrrev_i32_e32 v96, 8, v96
	v_add_u32_e32 v3, 0x80, v3
	v_add_u32_e32 v7, 0x80, v7
	v_ashrrev_i32_e32 v6, 8, v6
	v_min_i32_e32 v96, 0x7f, v96
	v_ashrrev_i32_e32 v3, 8, v3
	v_ashrrev_i32_e32 v7, 8, v7
	v_min_i32_e32 v6, 0x7f, v6
	v_min_i32_sdwa v3, v3, s85 dst_sel:WORD_1 dst_unused:UNUSED_PAD src0_sel:DWORD src1_sel:DWORD
	v_min_i32_e32 v7, 0x7f, v7
	v_lshlrev_b32_e32 v96, 8, v96
	v_and_b32_e32 v96, 0xff00, v96
	v_and_b32_e32 v3, 0xff0000, v3
	v_perm_b32 v6, v7, v6, s92
	v_or3_b32 v3, v6, v96, v3
	ds_write_b32 v14, v3 offset:144
	ds_read_b64 v[6:7], v15
	s_waitcnt lgkmcnt(0)
; #define WAIT_L(n) asm volatile("s_waitcnt lgkmcnt(" #n ")" ::: "memory")
; #define BAR __builtin_amdgcn_s_barrier()
;     ...
;             _Pragma("unroll") for (int m = 0; m < 4; ++m) {
;               const int rr = wr3 * 64 + m * 16 + fr3;
;               const float2 ms = *reinterpret_cast<const float2*>(mr + (ai * HALF + rr) * 2);
;               f32x4 y = acc[ai][bj][m][n];
;               const float o0 = (y[0] - ms.x) * ms.y * gm.x + bt.x, o1 = (y[1] - ms.x) * ms.y * gm.y + bt.y;
;               const float o2 = (y[2] - ms.x) * ms.y * gm.z + bt.z, o3 = (y[3] - ms.x) * ms.y * gm.w + bt.w;
;               const unsigned h0 = f2bf(o0), h1 = f2bf(o1), h2 = f2bf(o2), h3 = f2bf(o3);
;               u32x2 ob; ob[0] = h0 | (h1 << 16); ob[1] = h2 | (h3 << 16);
;               *reinterpret_cast<u32x2*>(smem + (rr >> 1) * PIECE + (rr & 1) * 512 + cc * 2) = ob;
;               const int l0 = min(((int)__float_as_uint(o0) - (int)(h0 << 16) + 128) >> 8, 127);
;               const int l1 = min(((int)__float_as_uint(o1) - (int)(h1 << 16) + 128) >> 8, 127);
;               const int l2 = min(((int)__float_as_uint(o2) - (int)(h2 << 16) + 128) >> 8, 127);
;               const int l3 = min(((int)__float_as_uint(o3) - (int)(h3 << 16) + 128) >> 8, 127);
;               *reinterpret_cast<unsigned*>(smem + LOBASE + (rr >> 2) * PIECE + (rr & 3) * 256 + cc) =
;                   (unsigned)(l0 & 255) | ((unsigned)(l1 & 255) << 8) | ((unsigned)(l2 & 255) << 16) | ((unsigned)l3 << 24);
;             }
;           }
;           WAIT_L(0); BAR;
;           const int hso = ((brow + ai * HALF + 16 * wave) * DM + pn * BM) * 2;
;           const int lso = (brow + ai * HALF + 16 * wave) * DM + pn * BM;
;           _Pragma("unroll") for (int i = 0; i < 8; ++i) {
;             const u32x4 v = *reinterpret_cast<const u32x4*>(smem + (wave * 8 + i) * PIECE + lane3 * 16);
;             __builtin_amdgcn_raw_buffer_store_b128(v, rsXB, hvo + i * (2 * DM * 2), hso, 0);
;           }
;           _Pragma("unroll") for (int i = 0; i < 4; ++i) {
;             const u32x4 v = *reinterpret_cast<const u32x4*>(smem + LOBASE + (wave * 4 + i) * PIECE + lane3 * 16);
;             __builtin_amdgcn_raw_buffer_store_b128(v, rsLO, lvo + i * (4 * DM), lso, 0);
;           }
;           WAIT_L(0); BAR;
	v_pk_add_f32 v[84:85], v[84:85], v[6:7] op_sel_hi:[1,0] neg_lo:[0,1] neg_hi:[0,1]
	s_nop 0
	v_pk_mul_f32 v[84:85], v[6:7], v[84:85] op_sel:[1,0]
	v_pk_add_f32 v[80:81], v[80:81], v[6:7] op_sel_hi:[1,0] neg_lo:[0,1] neg_hi:[0,1]
	v_pk_fma_f32 v[84:85], v[88:89], v[84:85], v[90:91]
	v_pk_mul_f32 v[6:7], v[6:7], v[80:81] op_sel:[1,0]
	v_and_b32_sdwa v80, v84, v216 dst_sel:DWORD dst_unused:UNUSED_PAD src0_sel:WORD_1 src1_sel:DWORD
	v_pk_fma_f32 v[6:7], v[0:1], v[6:7], v[4:5]
	v_add3_u32 v80, v84, v80, s84
	v_and_b32_e32 v81, 0xffff0000, v80
	v_and_b32_sdwa v80, v7, v216 dst_sel:DWORD dst_unused:UNUSED_PAD src0_sel:WORD_1 src1_sel:DWORD
	v_and_b32_sdwa v3, v85, v216 dst_sel:DWORD dst_unused:UNUSED_PAD src0_sel:WORD_1 src1_sel:DWORD
	v_and_b32_sdwa v96, v6, v216 dst_sel:DWORD dst_unused:UNUSED_PAD src0_sel:WORD_1 src1_sel:DWORD
	v_add3_u32 v80, v7, v80, s84
	v_add3_u32 v3, v85, v3, s84
	v_add3_u32 v100, v6, v96, s84
	v_and_b32_e32 v101, 0xffff0000, v80
	v_or_b32_sdwa v97, v101, v3 dst_sel:DWORD dst_unused:UNUSED_PAD src0_sel:DWORD src1_sel:WORD_1
	v_or_b32_sdwa v96, v100, v81 dst_sel:DWORD dst_unused:UNUSED_PAD src0_sel:WORD_1 src1_sel:DWORD
	v_add_u32_e32 v80, v2, v137
	ds_write_b64 v80, v[96:97]
	v_and_b32_e32 v96, 0xffff0000, v100
	v_sub_u32_e32 v81, v84, v81
	v_and_b32_e32 v3, 0xffff0000, v3
	v_sub_u32_e32 v6, v6, v96
	v_add_u32_e32 v81, 0x80, v81
	v_sub_u32_e32 v3, v85, v3
	v_sub_u32_e32 v7, v7, v101
	v_add_u32_e32 v6, 0x80, v6
	v_ashrrev_i32_e32 v81, 8, v81
	v_add_u32_e32 v3, 0x80, v3
	v_add_u32_e32 v7, 0x80, v7
	v_ashrrev_i32_e32 v6, 8, v6
	v_min_i32_e32 v81, 0x7f, v81
	v_ashrrev_i32_e32 v3, 8, v3
	v_ashrrev_i32_e32 v7, 8, v7
	v_min_i32_e32 v6, 0x7f, v6
	v_min_i32_sdwa v3, v3, s85 dst_sel:WORD_1 dst_unused:UNUSED_PAD src0_sel:DWORD src1_sel:DWORD
	v_min_i32_e32 v7, 0x7f, v7
	v_lshlrev_b32_e32 v81, 8, v81
	v_and_b32_e32 v81, 0xff00, v81
	v_and_b32_e32 v3, 0xff0000, v3
	v_perm_b32 v6, v7, v6, s92
	v_or3_b32 v3, v6, v81, v3
	ds_write_b32 v18, v3 offset:144
	ds_read_b64 v[6:7], v19
	v_or_b32_e32 v81, 0x6000, v148
	v_or_b32_e32 v96, 0x6000, v146
	s_waitcnt lgkmcnt(0)
	v_pk_add_f32 v[72:73], v[72:73], v[6:7] op_sel_hi:[1,0] neg_lo:[0,1] neg_hi:[0,1]
	s_nop 0
	v_pk_mul_f32 v[72:73], v[6:7], v[72:73] op_sel:[1,0]
	s_nop 0
	v_pk_fma_f32 v[84:85], v[88:89], v[72:73], v[90:91]
	v_pk_add_f32 v[72:73], v[74:75], v[6:7] op_sel_hi:[1,0] neg_lo:[0,1] neg_hi:[0,1]
	v_and_b32_sdwa v3, v85, v216 dst_sel:DWORD dst_unused:UNUSED_PAD src0_sel:WORD_1 src1_sel:DWORD
	v_pk_mul_f32 v[6:7], v[6:7], v[72:73] op_sel:[1,0]
	v_add3_u32 v3, v85, v3, s84
	v_pk_fma_f32 v[0:1], v[0:1], v[6:7], v[4:5]
	v_and_b32_sdwa v4, v84, v216 dst_sel:DWORD dst_unused:UNUSED_PAD src0_sel:WORD_1 src1_sel:DWORD
	v_add3_u32 v4, v84, v4, s84
	v_and_b32_e32 v6, 0xffff0000, v4
	v_and_b32_sdwa v4, v1, v216 dst_sel:DWORD dst_unused:UNUSED_PAD src0_sel:WORD_1 src1_sel:DWORD
	v_and_b32_sdwa v5, v0, v216 dst_sel:DWORD dst_unused:UNUSED_PAD src0_sel:WORD_1 src1_sel:DWORD
	v_add3_u32 v4, v1, v4, s84
	v_add3_u32 v7, v0, v5, s84
	v_and_b32_e32 v72, 0xffff0000, v4
	v_add_u32_e32 v73, v2, v136
	v_and_b32_e32 v2, 0xffff0000, v7
	v_or_b32_sdwa v5, v72, v3 dst_sel:DWORD dst_unused:UNUSED_PAD src0_sel:DWORD src1_sel:WORD_1
	v_sub_u32_e32 v0, v0, v2
	v_sub_u32_e32 v2, v84, v6
	v_and_b32_e32 v3, 0xffff0000, v3
	v_add_u32_e32 v2, 0x80, v2
	v_sub_u32_e32 v3, v85, v3
	v_sub_u32_e32 v1, v1, v72
	v_add_u32_e32 v0, 0x80, v0
	v_ashrrev_i32_e32 v2, 8, v2
	v_add_u32_e32 v3, 0x80, v3
	v_add_u32_e32 v1, 0x80, v1
	v_ashrrev_i32_e32 v0, 8, v0
	v_min_i32_e32 v2, 0x7f, v2
	v_ashrrev_i32_e32 v3, 8, v3
	v_ashrrev_i32_e32 v1, 8, v1
	v_min_i32_e32 v0, 0x7f, v0
	v_min_i32_sdwa v3, v3, s85 dst_sel:WORD_1 dst_unused:UNUSED_PAD src0_sel:DWORD src1_sel:DWORD
	v_min_i32_e32 v1, 0x7f, v1
	v_lshlrev_b32_e32 v2, 8, v2
	v_and_b32_e32 v2, 0xff00, v2
	v_and_b32_e32 v3, 0xff0000, v3
	v_perm_b32 v0, v1, v0, s92
	v_or_b32_sdwa v4, v7, v6 dst_sel:DWORD dst_unused:UNUSED_PAD src0_sel:WORD_1 src1_sel:DWORD
	v_or3_b32 v0, v0, v2, v3
	ds_write_b64 v73, v[4:5]
	ds_write_b32 v22, v0 offset:144
	v_add_u32_e32 v72, s2, v151
	s_waitcnt lgkmcnt(0)
	s_barrier
	ds_read_b128 v[128:131], v72
	v_or_b32_e32 v74, 0x2000, v148
	v_or_b32_e32 v75, 0x4000, v148
	v_or_b32_e32 v84, 0x8000, v148
	v_or_b32_e32 v85, 0xa000, v148
	ds_read_b128 v[136:139], v72 offset:1040
	v_or_b32_e32 v88, 0xc000, v148
	v_or_b32_e32 v89, 0xe000, v148
	v_or_b32_e32 v90, 0x2000, v146
	v_or_b32_e32 v91, 0x4000, v146
	ds_read_b128 v[140:143], v72 offset:2080
	ds_read_b128 v[152:155], v72 offset:3120
	ds_read_b128 v[156:159], v72 offset:4160
	ds_read_b128 v[160:163], v72 offset:5200
	ds_read_b128 v[164:167], v72 offset:6240
	ds_read_b128 v[168:171], v72 offset:7280
	ds_read_b128 v[172:175], v147
	ds_read_b128 v[176:179], v147 offset:1040
	ds_read_b128 v[180:183], v147 offset:2080
	ds_read_b128 v[184:187], v147 offset:3120
	s_waitcnt lgkmcnt(0)
	s_barrier
;     ...
;           _Pragma("unroll") for (int bj = 0; bj < 2; ++bj) _Pragma("unroll") for (int n = 0; n < 2; ++n) {
;             const int cc = bj * HALF + wc3 * 32 + n * 16 + fq3 * 4;
;             const float4 gm = *reinterpret_cast<const float4*>(g.gam + pn * BM + cc), bt = *reinterpret_cast<const float4*>(g.bet + pn * BM + cc);
;             _Pragma("unroll") for (int m = 0; m < 4; ++m) {
;               const int rr = wr3 * 64 + m * 16 + fr3;
;               const float2 ms = *reinterpret_cast<const float2*>(mr + (ai * HALF + rr) * 2);
;               f32x4 y = acc[ai][bj][m][n];
;               const float o0 = (y[0] - ms.x) * ms.y * gm.x + bt.x, o1 = (y[1] - ms.x) * ms.y * gm.y + bt.y;
;               const float o2 = (y[2] - ms.x) * ms.y * gm.z + bt.z, o3 = (y[3] - ms.x) * ms.y * gm.w + bt.w;
;               const unsigned h0 = f2bf(o0), h1 = f2bf(o1), h2 = f2bf(o2), h3 = f2bf(o3);
;               u32x2 ob; ob[0] = h0 | (h1 << 16); ob[1] = h2 | (h3 << 16);
;               *reinterpret_cast<u32x2*>(smem + (rr >> 1) * PIECE + (rr & 1) * 512 + cc * 2) = ob;
;               const int l0 = min(((int)__float_as_uint(o0) - (int)(h0 << 16) + 128) >> 8, 127);
;               const int l1 = min(((int)__float_as_uint(o1) - (int)(h1 << 16) + 128) >> 8, 127);
;               const int l2 = min(((int)__float_as_uint(o2) - (int)(h2 << 16) + 128) >> 8, 127);
;               const int l3 = min(((int)__float_as_uint(o3) - (int)(h3 << 16) + 128) >> 8, 127);
;               *reinterpret_cast<unsigned*>(smem + LOBASE + (rr >> 2) * PIECE + (rr & 3) * 256 + cc) =
;                   (unsigned)(l0 & 255) | ((unsigned)(l1 & 255) << 8) | ((unsigned)(l2 & 255) << 16) | ((unsigned)l3 << 24);
;             }
;     ...
;           _Pragma("unroll") for (int i = 0; i < 8; ++i) {
;             const u32x4 v = *reinterpret_cast<const u32x4*>(smem + (wave * 8 + i) * PIECE + lane3 * 16);
;             __builtin_amdgcn_raw_buffer_store_b128(v, rsXB, hvo + i * (2 * DM * 2), hso, 0);
;           }
;           _Pragma("unroll") for (int i = 0; i < 4; ++i) {
;             const u32x4 v = *reinterpret_cast<const u32x4*>(smem + LOBASE + (wave * 4 + i) * PIECE + lane3 * 16);
;             __builtin_amdgcn_raw_buffer_store_b128(v, rsLO, lvo + i * (4 * DM), lso, 0);
;           }
	s_nop 1
	v_mov_b32_e32 v0, v220
	v_mov_b32_e32 v1, v221
	v_mov_b32_e32 v2, v222
	v_mov_b32_e32 v3, v223
	v_mov_b32_e32 v4, v236
	v_mov_b32_e32 v5, v237
	v_mov_b32_e32 v6, v238
	v_mov_b32_e32 v7, v239
	ds_read_b64 v[110:111], v149 offset:1024
	s_waitcnt lgkmcnt(0)
	v_pk_add_f32 v[64:65], v[64:65], v[110:111] op_sel_hi:[1,0] neg_lo:[0,1] neg_hi:[0,1]
	s_nop 0
	v_pk_mul_f32 v[64:65], v[110:111], v[64:65] op_sel:[1,0]
	v_pk_add_f32 v[66:67], v[66:67], v[110:111] op_sel_hi:[1,0] neg_lo:[0,1] neg_hi:[0,1]
	v_mov_b32_e32 v100, v1
	v_mov_b32_e32 v101, v2
	v_mov_b32_e32 v104, v5
	v_mov_b32_e32 v105, v6
	v_pk_fma_f32 v[64:65], v[100:101], v[64:65], v[104:105]
	v_pk_mul_f32 v[66:67], v[110:111], v[66:67] op_sel:[1,0]
	v_mov_b32_e32 v1, v3
	v_mov_b32_e32 v5, v7
	v_and_b32_sdwa v6, v65, v216 dst_sel:DWORD dst_unused:UNUSED_PAD src0_sel:WORD_1 src1_sel:DWORD
	v_and_b32_sdwa v7, v64, v216 dst_sel:DWORD dst_unused:UNUSED_PAD src0_sel:WORD_1 src1_sel:DWORD
	v_pk_fma_f32 v[2:3], v[0:1], v[66:67], v[4:5]
	v_add3_u32 v66, v65, v6, s84
	v_add3_u32 v6, v64, v7, s84
	v_and_b32_e32 v67, 0xffff0000, v6
	v_and_b32_sdwa v6, v3, v216 dst_sel:DWORD dst_unused:UNUSED_PAD src0_sel:WORD_1 src1_sel:DWORD
	v_and_b32_sdwa v7, v2, v216 dst_sel:DWORD dst_unused:UNUSED_PAD src0_sel:WORD_1 src1_sel:DWORD
	v_add3_u32 v6, v3, v6, s84
	v_add3_u32 v97, v2, v7, s84
	v_and_b32_e32 v103, 0xffff0000, v6
	v_or_b32_sdwa v7, v103, v66 dst_sel:DWORD dst_unused:UNUSED_PAD src0_sel:DWORD src1_sel:WORD_1
	v_or_b32_sdwa v6, v97, v67 dst_sel:DWORD dst_unused:UNUSED_PAD src0_sel:WORD_1 src1_sel:DWORD
	ds_write_b64 v132, v[6:7]
	v_and_b32_e32 v6, 0xffff0000, v97
	v_sub_u32_e32 v2, v2, v6
	v_sub_u32_e32 v6, v64, v67
	v_and_b32_e32 v7, 0xffff0000, v66
	v_add_u32_e32 v6, 0x80, v6
	v_sub_u32_e32 v7, v65, v7
	v_sub_u32_e32 v3, v3, v103
	v_add_u32_e32 v2, 0x80, v2
	v_ashrrev_i32_e32 v6, 8, v6
	v_add_u32_e32 v7, 0x80, v7
	v_add_u32_e32 v3, 0x80, v3
	v_ashrrev_i32_e32 v2, 8, v2
	v_min_i32_e32 v6, 0x7f, v6
	v_ashrrev_i32_e32 v7, 8, v7
	v_ashrrev_i32_e32 v3, 8, v3
	v_min_i32_e32 v2, 0x7f, v2
	v_min_i32_sdwa v7, v7, s85 dst_sel:WORD_1 dst_unused:UNUSED_PAD src0_sel:DWORD src1_sel:DWORD
	v_min_i32_e32 v3, 0x7f, v3
	v_lshlrev_b32_e32 v6, 8, v6
	v_and_b32_e32 v6, 0xff00, v6
	v_and_b32_e32 v7, 0xff0000, v7
	v_perm_b32 v2, v3, v2, s92
	v_or3_b32 v2, v2, v6, v7
	ds_write_b32 v12, v2
	buffer_store_dwordx4 v[128:131], v148, s[16:19], s41 offen
	ds_read_b64 v[2:3], v13 offset:1024
	s_waitcnt lgkmcnt(0)
	v_pk_add_f32 v[6:7], v[68:69], v[2:3] op_sel_hi:[1,0] neg_lo:[0,1] neg_hi:[0,1]
	s_nop 0
	v_pk_mul_f32 v[6:7], v[2:3], v[6:7] op_sel:[1,0]
	v_pk_add_f32 v[64:65], v[70:71], v[2:3] op_sel_hi:[1,0] neg_lo:[0,1] neg_hi:[0,1]
	v_pk_fma_f32 v[6:7], v[100:101], v[6:7], v[104:105]
	v_pk_mul_f32 v[2:3], v[2:3], v[64:65] op_sel:[1,0]
	v_and_b32_sdwa v64, v7, v216 dst_sel:DWORD dst_unused:UNUSED_PAD src0_sel:WORD_1 src1_sel:DWORD
	v_and_b32_sdwa v65, v6, v216 dst_sel:DWORD dst_unused:UNUSED_PAD src0_sel:WORD_1 src1_sel:DWORD
	v_pk_fma_f32 v[2:3], v[0:1], v[2:3], v[4:5]
	v_add3_u32 v66, v7, v64, s84
	v_add3_u32 v64, v6, v65, s84
	v_and_b32_e32 v67, 0xffff0000, v64
	v_and_b32_sdwa v64, v3, v216 dst_sel:DWORD dst_unused:UNUSED_PAD src0_sel:WORD_1 src1_sel:DWORD
	v_and_b32_sdwa v65, v2, v216 dst_sel:DWORD dst_unused:UNUSED_PAD src0_sel:WORD_1 src1_sel:DWORD
	v_add3_u32 v64, v3, v64, s84
	v_add3_u32 v68, v2, v65, s84
	v_and_b32_e32 v69, 0xffff0000, v64
	v_or_b32_sdwa v65, v69, v66 dst_sel:DWORD dst_unused:UNUSED_PAD src0_sel:DWORD src1_sel:WORD_1
	v_or_b32_sdwa v64, v68, v67 dst_sel:DWORD dst_unused:UNUSED_PAD src0_sel:WORD_1 src1_sel:DWORD
	ds_write_b64 v133, v[64:65]
	v_and_b32_e32 v64, 0xffff0000, v68
	v_sub_u32_e32 v2, v2, v64
	v_sub_u32_e32 v6, v6, v67
	v_and_b32_e32 v64, 0xffff0000, v66
	v_add_u32_e32 v6, 0x80, v6
	v_sub_u32_e32 v7, v7, v64
	v_sub_u32_e32 v3, v3, v69
	v_add_u32_e32 v2, 0x80, v2
	v_ashrrev_i32_e32 v6, 8, v6
	v_add_u32_e32 v7, 0x80, v7
	v_add_u32_e32 v3, 0x80, v3
	v_ashrrev_i32_e32 v2, 8, v2
	v_min_i32_e32 v6, 0x7f, v6
	v_ashrrev_i32_e32 v7, 8, v7
	v_ashrrev_i32_e32 v3, 8, v3
	v_min_i32_e32 v2, 0x7f, v2
	v_min_i32_sdwa v7, v7, s85 dst_sel:WORD_1 dst_unused:UNUSED_PAD src0_sel:DWORD src1_sel:DWORD
	v_min_i32_e32 v3, 0x7f, v3
	v_lshlrev_b32_e32 v6, 8, v6
	v_and_b32_e32 v6, 0xff00, v6
	v_and_b32_e32 v7, 0xff0000, v7
	v_perm_b32 v2, v3, v2, s92
	v_or3_b32 v2, v2, v6, v7
	ds_write_b32 v14, v2
	buffer_store_dwordx4 v[136:139], v74, s[16:19], s41 offen
	ds_read_b64 v[2:3], v15 offset:1024
	s_waitcnt lgkmcnt(0)
	v_pk_add_f32 v[6:7], v[76:77], v[2:3] op_sel_hi:[1,0] neg_lo:[0,1] neg_hi:[0,1]
	s_nop 0
	v_pk_mul_f32 v[6:7], v[2:3], v[6:7] op_sel:[1,0]
	v_pk_add_f32 v[64:65], v[78:79], v[2:3] op_sel_hi:[1,0] neg_lo:[0,1] neg_hi:[0,1]
	v_pk_fma_f32 v[6:7], v[100:101], v[6:7], v[104:105]
	v_pk_mul_f32 v[2:3], v[2:3], v[64:65] op_sel:[1,0]
	v_and_b32_sdwa v64, v7, v216 dst_sel:DWORD dst_unused:UNUSED_PAD src0_sel:WORD_1 src1_sel:DWORD
	v_and_b32_sdwa v65, v6, v216 dst_sel:DWORD dst_unused:UNUSED_PAD src0_sel:WORD_1 src1_sel:DWORD
	v_pk_fma_f32 v[2:3], v[0:1], v[2:3], v[4:5]
	v_add3_u32 v66, v7, v64, s84
	v_add3_u32 v64, v6, v65, s84
	v_and_b32_e32 v67, 0xffff0000, v64
	v_and_b32_sdwa v64, v3, v216 dst_sel:DWORD dst_unused:UNUSED_PAD src0_sel:WORD_1 src1_sel:DWORD
	v_and_b32_sdwa v65, v2, v216 dst_sel:DWORD dst_unused:UNUSED_PAD src0_sel:WORD_1 src1_sel:DWORD
	v_add3_u32 v64, v3, v64, s84
	v_add3_u32 v68, v2, v65, s84
	v_and_b32_e32 v69, 0xffff0000, v64
	v_or_b32_sdwa v65, v69, v66 dst_sel:DWORD dst_unused:UNUSED_PAD src0_sel:DWORD src1_sel:WORD_1
	v_or_b32_sdwa v64, v68, v67 dst_sel:DWORD dst_unused:UNUSED_PAD src0_sel:WORD_1 src1_sel:DWORD
	ds_write_b64 v134, v[64:65]
	v_and_b32_e32 v64, 0xffff0000, v68
	v_sub_u32_e32 v2, v2, v64
	v_sub_u32_e32 v6, v6, v67
	v_and_b32_e32 v64, 0xffff0000, v66
	v_add_u32_e32 v6, 0x80, v6
	v_sub_u32_e32 v7, v7, v64
	v_sub_u32_e32 v3, v3, v69
	v_add_u32_e32 v2, 0x80, v2
	v_ashrrev_i32_e32 v6, 8, v6
	v_add_u32_e32 v7, 0x80, v7
	v_add_u32_e32 v3, 0x80, v3
	v_ashrrev_i32_e32 v2, 8, v2
	v_min_i32_e32 v6, 0x7f, v6
	v_ashrrev_i32_e32 v7, 8, v7
	v_ashrrev_i32_e32 v3, 8, v3
	v_min_i32_e32 v2, 0x7f, v2
	v_min_i32_sdwa v7, v7, s85 dst_sel:WORD_1 dst_unused:UNUSED_PAD src0_sel:DWORD src1_sel:DWORD
	v_min_i32_e32 v3, 0x7f, v3
	v_lshlrev_b32_e32 v6, 8, v6
	v_and_b32_e32 v6, 0xff00, v6
	v_and_b32_e32 v7, 0xff0000, v7
	v_perm_b32 v2, v3, v2, s92
	v_or3_b32 v2, v2, v6, v7
	ds_write_b32 v18, v2
	buffer_store_dwordx4 v[140:143], v75, s[16:19], s41 offen
	ds_read_b64 v[2:3], v19 offset:1024
	s_waitcnt lgkmcnt(0)
;     ...
;           _Pragma("unroll") for (int bj = 0; bj < 2; ++bj) _Pragma("unroll") for (int n = 0; n < 2; ++n) {
;             const int cc = bj * HALF + wc3 * 32 + n * 16 + fq3 * 4;
;             const float4 gm = *reinterpret_cast<const float4*>(g.gam + pn * BM + cc), bt = *reinterpret_cast<const float4*>(g.bet + pn * BM + cc);
;             _Pragma("unroll") for (int m = 0; m < 4; ++m) {
;               const int rr = wr3 * 64 + m * 16 + fr3;
;               const float2 ms = *reinterpret_cast<const float2*>(mr + (ai * HALF + rr) * 2);
;               f32x4 y = acc[ai][bj][m][n];
;               const float o0 = (y[0] - ms.x) * ms.y * gm.x + bt.x, o1 = (y[1] - ms.x) * ms.y * gm.y + bt.y;
;               const float o2 = (y[2] - ms.x) * ms.y * gm.z + bt.z, o3 = (y[3] - ms.x) * ms.y * gm.w + bt.w;
;               const unsigned h0 = f2bf(o0), h1 = f2bf(o1), h2 = f2bf(o2), h3 = f2bf(o3);
;               u32x2 ob; ob[0] = h0 | (h1 << 16); ob[1] = h2 | (h3 << 16);
;               *reinterpret_cast<u32x2*>(smem + (rr >> 1) * PIECE + (rr & 1) * 512 + cc * 2) = ob;
;               const int l0 = min(((int)__float_as_uint(o0) - (int)(h0 << 16) + 128) >> 8, 127);
;               const int l1 = min(((int)__float_as_uint(o1) - (int)(h1 << 16) + 128) >> 8, 127);
;               const int l2 = min(((int)__float_as_uint(o2) - (int)(h2 << 16) + 128) >> 8, 127);
;               const int l3 = min(((int)__float_as_uint(o3) - (int)(h3 << 16) + 128) >> 8, 127);
;               *reinterpret_cast<unsigned*>(smem + LOBASE + (rr >> 2) * PIECE + (rr & 3) * 256 + cc) =
;                   (unsigned)(l0 & 255) | ((unsigned)(l1 & 255) << 8) | ((unsigned)(l2 & 255) << 16) | ((unsigned)l3 << 24);
;             }
;     ...
;           _Pragma("unroll") for (int i = 0; i < 8; ++i) {
;             const u32x4 v = *reinterpret_cast<const u32x4*>(smem + (wave * 8 + i) * PIECE + lane3 * 16);
;             __builtin_amdgcn_raw_buffer_store_b128(v, rsXB, hvo + i * (2 * DM * 2), hso, 0);
;           }
;           _Pragma("unroll") for (int i = 0; i < 4; ++i) {
;             const u32x4 v = *reinterpret_cast<const u32x4*>(smem + LOBASE + (wave * 4 + i) * PIECE + lane3 * 16);
;             __builtin_amdgcn_raw_buffer_store_b128(v, rsLO, lvo + i * (4 * DM), lso, 0);
;           }
	v_pk_add_f32 v[6:7], v[82:83], v[2:3] op_sel_hi:[1,0] neg_lo:[0,1] neg_hi:[0,1]
	s_nop 0
	v_pk_mul_f32 v[6:7], v[2:3], v[6:7] op_sel:[1,0]
	v_pk_add_f32 v[64:65], v[86:87], v[2:3] op_sel_hi:[1,0] neg_lo:[0,1] neg_hi:[0,1]
	v_pk_fma_f32 v[6:7], v[100:101], v[6:7], v[104:105]
	v_pk_mul_f32 v[2:3], v[2:3], v[64:65] op_sel:[1,0]
	s_nop 0
	v_pk_fma_f32 v[0:1], v[0:1], v[2:3], v[4:5]
	v_and_b32_sdwa v2, v7, v216 dst_sel:DWORD dst_unused:UNUSED_PAD src0_sel:WORD_1 src1_sel:DWORD
	v_and_b32_sdwa v3, v6, v216 dst_sel:DWORD dst_unused:UNUSED_PAD src0_sel:WORD_1 src1_sel:DWORD
	v_add3_u32 v4, v7, v2, s84
	v_add3_u32 v2, v6, v3, s84
	v_and_b32_e32 v5, 0xffff0000, v2
	v_and_b32_sdwa v2, v1, v216 dst_sel:DWORD dst_unused:UNUSED_PAD src0_sel:WORD_1 src1_sel:DWORD
	v_and_b32_sdwa v3, v0, v216 dst_sel:DWORD dst_unused:UNUSED_PAD src0_sel:WORD_1 src1_sel:DWORD
	v_add3_u32 v2, v1, v2, s84
	v_add3_u32 v64, v0, v3, s84
	v_and_b32_e32 v65, 0xffff0000, v2
	v_or_b32_sdwa v3, v65, v4 dst_sel:DWORD dst_unused:UNUSED_PAD src0_sel:DWORD src1_sel:WORD_1
	v_or_b32_sdwa v2, v64, v5 dst_sel:DWORD dst_unused:UNUSED_PAD src0_sel:WORD_1 src1_sel:DWORD
	ds_write_b64 v135, v[2:3]
	v_and_b32_e32 v2, 0xffff0000, v64
	v_sub_u32_e32 v0, v0, v2
	v_sub_u32_e32 v2, v6, v5
	v_and_b32_e32 v3, 0xffff0000, v4
	v_add_u32_e32 v2, 0x80, v2
	v_sub_u32_e32 v3, v7, v3
	v_sub_u32_e32 v1, v1, v65
	v_add_u32_e32 v0, 0x80, v0
	v_ashrrev_i32_e32 v2, 8, v2
	v_add_u32_e32 v3, 0x80, v3
	v_add_u32_e32 v1, 0x80, v1
	v_ashrrev_i32_e32 v0, 8, v0
	v_min_i32_e32 v2, 0x7f, v2
	v_ashrrev_i32_e32 v3, 8, v3
	v_ashrrev_i32_e32 v1, 8, v1
	v_min_i32_e32 v0, 0x7f, v0
	v_min_i32_sdwa v3, v3, s85 dst_sel:WORD_1 dst_unused:UNUSED_PAD src0_sel:DWORD src1_sel:DWORD
	v_min_i32_e32 v1, 0x7f, v1
	v_lshlrev_b32_e32 v2, 8, v2
	v_and_b32_e32 v2, 0xff00, v2
	v_and_b32_e32 v3, 0xff0000, v3
	v_perm_b32 v0, v1, v0, s92
	v_or3_b32 v0, v0, v2, v3
	ds_write_b32 v22, v0
	buffer_store_dwordx4 v[152:155], v81, s[16:19], s41 offen
	v_mov_b32_e32 v0, v224
	v_mov_b32_e32 v1, v225
	v_mov_b32_e32 v2, v226
	v_mov_b32_e32 v3, v227
	v_mov_b32_e32 v4, v240
	v_mov_b32_e32 v5, v241
	v_mov_b32_e32 v6, v242
	v_mov_b32_e32 v7, v243
	ds_read_b64 v[68:69], v149 offset:1024
	s_waitcnt lgkmcnt(0)
	v_pk_add_f32 v[60:61], v[60:61], v[68:69] op_sel_hi:[1,0] neg_lo:[0,1] neg_hi:[0,1]
	s_nop 0
	v_pk_mul_f32 v[60:61], v[68:69], v[60:61] op_sel:[1,0]
	v_pk_add_f32 v[58:59], v[58:59], v[68:69] op_sel_hi:[1,0] neg_lo:[0,1] neg_hi:[0,1]
	v_mov_b32_e32 v64, v1
	v_mov_b32_e32 v65, v2
	v_mov_b32_e32 v66, v5
	v_mov_b32_e32 v67, v6
	v_pk_fma_f32 v[60:61], v[64:65], v[60:61], v[66:67]
	v_pk_mul_f32 v[58:59], v[68:69], v[58:59] op_sel:[1,0]
	v_mov_b32_e32 v1, v3
	v_mov_b32_e32 v5, v7
	v_and_b32_sdwa v6, v61, v216 dst_sel:DWORD dst_unused:UNUSED_PAD src0_sel:WORD_1 src1_sel:DWORD
	v_and_b32_sdwa v7, v60, v216 dst_sel:DWORD dst_unused:UNUSED_PAD src0_sel:WORD_1 src1_sel:DWORD
	v_pk_fma_f32 v[2:3], v[0:1], v[58:59], v[4:5]
	v_add3_u32 v58, v61, v6, s84
	v_add3_u32 v6, v60, v7, s84
	v_and_b32_e32 v59, 0xffff0000, v6
	v_and_b32_sdwa v6, v3, v216 dst_sel:DWORD dst_unused:UNUSED_PAD src0_sel:WORD_1 src1_sel:DWORD
	v_and_b32_sdwa v7, v2, v216 dst_sel:DWORD dst_unused:UNUSED_PAD src0_sel:WORD_1 src1_sel:DWORD
	v_add3_u32 v6, v3, v6, s84
	v_add3_u32 v68, v2, v7, s84
	v_and_b32_e32 v69, 0xffff0000, v6
	v_or_b32_sdwa v7, v69, v58 dst_sel:DWORD dst_unused:UNUSED_PAD src0_sel:DWORD src1_sel:WORD_1
	v_or_b32_sdwa v6, v68, v59 dst_sel:DWORD dst_unused:UNUSED_PAD src0_sel:WORD_1 src1_sel:DWORD
	ds_write_b64 v23, v[6:7]
	v_and_b32_e32 v6, 0xffff0000, v68
	v_sub_u32_e32 v2, v2, v6
	v_sub_u32_e32 v6, v60, v59
	v_and_b32_e32 v7, 0xffff0000, v58
	v_add_u32_e32 v6, 0x80, v6
	v_sub_u32_e32 v7, v61, v7
	v_sub_u32_e32 v3, v3, v69
	v_add_u32_e32 v2, 0x80, v2
	v_ashrrev_i32_e32 v6, 8, v6
	v_add_u32_e32 v7, 0x80, v7
	v_add_u32_e32 v3, 0x80, v3
	v_ashrrev_i32_e32 v2, 8, v2
	v_min_i32_e32 v6, 0x7f, v6
	v_ashrrev_i32_e32 v7, 8, v7
	v_ashrrev_i32_e32 v3, 8, v3
	v_min_i32_e32 v2, 0x7f, v2
	v_min_i32_sdwa v7, v7, s85 dst_sel:WORD_1 dst_unused:UNUSED_PAD src0_sel:DWORD src1_sel:DWORD
	v_min_i32_e32 v3, 0x7f, v3
	v_lshlrev_b32_e32 v6, 8, v6
	v_and_b32_e32 v6, 0xff00, v6
	v_and_b32_e32 v7, 0xff0000, v7
	v_perm_b32 v2, v3, v2, s92
	v_or3_b32 v2, v2, v6, v7
	ds_write_b32 v12, v2 offset:16
	buffer_store_dwordx4 v[156:159], v84, s[16:19], s41 offen
	ds_read_b64 v[2:3], v13 offset:1024
	s_waitcnt lgkmcnt(0)
	v_pk_add_f32 v[6:7], v[44:45], v[2:3] op_sel_hi:[1,0] neg_lo:[0,1] neg_hi:[0,1]
	s_nop 0
	v_pk_mul_f32 v[6:7], v[2:3], v[6:7] op_sel:[1,0]
	v_pk_add_f32 v[42:43], v[42:43], v[2:3] op_sel_hi:[1,0] neg_lo:[0,1] neg_hi:[0,1]
	v_pk_fma_f32 v[6:7], v[64:65], v[6:7], v[66:67]
	v_pk_mul_f32 v[2:3], v[2:3], v[42:43] op_sel:[1,0]
	v_and_b32_sdwa v42, v6, v216 dst_sel:DWORD dst_unused:UNUSED_PAD src0_sel:WORD_1 src1_sel:DWORD
	v_pk_fma_f32 v[2:3], v[0:1], v[2:3], v[4:5]
	v_add3_u32 v42, v6, v42, s84
	v_and_b32_e32 v44, 0xffff0000, v42
	v_and_b32_sdwa v42, v3, v216 dst_sel:DWORD dst_unused:UNUSED_PAD src0_sel:WORD_1 src1_sel:DWORD
	v_and_b32_sdwa v23, v7, v216 dst_sel:DWORD dst_unused:UNUSED_PAD src0_sel:WORD_1 src1_sel:DWORD
	v_and_b32_sdwa v43, v2, v216 dst_sel:DWORD dst_unused:UNUSED_PAD src0_sel:WORD_1 src1_sel:DWORD
	v_add3_u32 v42, v3, v42, s84
	v_add3_u32 v23, v7, v23, s84
	v_add3_u32 v45, v2, v43, s84
	v_and_b32_e32 v58, 0xffff0000, v42
	v_or_b32_sdwa v43, v58, v23 dst_sel:DWORD dst_unused:UNUSED_PAD src0_sel:DWORD src1_sel:WORD_1
	v_or_b32_sdwa v42, v45, v44 dst_sel:DWORD dst_unused:UNUSED_PAD src0_sel:WORD_1 src1_sel:DWORD
	ds_write_b64 v108, v[42:43]
	v_and_b32_e32 v42, 0xffff0000, v45
	v_sub_u32_e32 v6, v6, v44
	v_and_b32_e32 v23, 0xffff0000, v23
	v_sub_u32_e32 v2, v2, v42
	v_add_u32_e32 v6, 0x80, v6
	v_sub_u32_e32 v7, v7, v23
	v_sub_u32_e32 v3, v3, v58
	v_add_u32_e32 v2, 0x80, v2
	v_ashrrev_i32_e32 v6, 8, v6
	v_add_u32_e32 v7, 0x80, v7
	v_add_u32_e32 v3, 0x80, v3
	v_ashrrev_i32_e32 v2, 8, v2
	v_min_i32_e32 v6, 0x7f, v6
	v_ashrrev_i32_e32 v7, 8, v7
	v_ashrrev_i32_e32 v3, 8, v3
	v_min_i32_e32 v2, 0x7f, v2
	v_min_i32_sdwa v7, v7, s85 dst_sel:WORD_1 dst_unused:UNUSED_PAD src0_sel:DWORD src1_sel:DWORD
	v_min_i32_e32 v3, 0x7f, v3
	v_lshlrev_b32_e32 v6, 8, v6
	v_and_b32_e32 v6, 0xff00, v6
	v_and_b32_e32 v7, 0xff0000, v7
	v_perm_b32 v2, v3, v2, s92
	v_or3_b32 v2, v2, v6, v7
	ds_write_b32 v14, v2 offset:16
	buffer_store_dwordx4 v[160:163], v85, s[16:19], s41 offen
	ds_read_b64 v[2:3], v15 offset:1024
	s_waitcnt lgkmcnt(0)
;     ...
;           _Pragma("unroll") for (int bj = 0; bj < 2; ++bj) _Pragma("unroll") for (int n = 0; n < 2; ++n) {
;             const int cc = bj * HALF + wc3 * 32 + n * 16 + fq3 * 4;
;             const float4 gm = *reinterpret_cast<const float4*>(g.gam + pn * BM + cc), bt = *reinterpret_cast<const float4*>(g.bet + pn * BM + cc);
;             _Pragma("unroll") for (int m = 0; m < 4; ++m) {
;               const int rr = wr3 * 64 + m * 16 + fr3;
;               const float2 ms = *reinterpret_cast<const float2*>(mr + (ai * HALF + rr) * 2);
;               f32x4 y = acc[ai][bj][m][n];
;               const float o0 = (y[0] - ms.x) * ms.y * gm.x + bt.x, o1 = (y[1] - ms.x) * ms.y * gm.y + bt.y;
;               const float o2 = (y[2] - ms.x) * ms.y * gm.z + bt.z, o3 = (y[3] - ms.x) * ms.y * gm.w + bt.w;
;               const unsigned h0 = f2bf(o0), h1 = f2bf(o1), h2 = f2bf(o2), h3 = f2bf(o3);
;               u32x2 ob; ob[0] = h0 | (h1 << 16); ob[1] = h2 | (h3 << 16);
;               *reinterpret_cast<u32x2*>(smem + (rr >> 1) * PIECE + (rr & 1) * 512 + cc * 2) = ob;
;               const int l0 = min(((int)__float_as_uint(o0) - (int)(h0 << 16) + 128) >> 8, 127);
;               const int l1 = min(((int)__float_as_uint(o1) - (int)(h1 << 16) + 128) >> 8, 127);
;               const int l2 = min(((int)__float_as_uint(o2) - (int)(h2 << 16) + 128) >> 8, 127);
;               const int l3 = min(((int)__float_as_uint(o3) - (int)(h3 << 16) + 128) >> 8, 127);
;               *reinterpret_cast<unsigned*>(smem + LOBASE + (rr >> 2) * PIECE + (rr & 3) * 256 + cc) =
;                   (unsigned)(l0 & 255) | ((unsigned)(l1 & 255) << 8) | ((unsigned)(l2 & 255) << 16) | ((unsigned)l3 << 24);
;             }
;     ...
;           _Pragma("unroll") for (int i = 0; i < 8; ++i) {
;             const u32x4 v = *reinterpret_cast<const u32x4*>(smem + (wave * 8 + i) * PIECE + lane3 * 16);
;             __builtin_amdgcn_raw_buffer_store_b128(v, rsXB, hvo + i * (2 * DM * 2), hso, 0);
;           }
;           _Pragma("unroll") for (int i = 0; i < 4; ++i) {
;             const u32x4 v = *reinterpret_cast<const u32x4*>(smem + LOBASE + (wave * 4 + i) * PIECE + lane3 * 16);
;             __builtin_amdgcn_raw_buffer_store_b128(v, rsLO, lvo + i * (4 * DM), lso, 0);
;           }
	v_pk_add_f32 v[6:7], v[34:35], v[2:3] op_sel_hi:[1,0] neg_lo:[0,1] neg_hi:[0,1]
	s_nop 0
	v_pk_mul_f32 v[6:7], v[2:3], v[6:7] op_sel:[1,0]
	v_pk_add_f32 v[34:35], v[46:47], v[2:3] op_sel_hi:[1,0] neg_lo:[0,1] neg_hi:[0,1]
	v_pk_fma_f32 v[6:7], v[64:65], v[6:7], v[66:67]
	v_pk_mul_f32 v[2:3], v[2:3], v[34:35] op_sel:[1,0]
	v_and_b32_sdwa v34, v6, v216 dst_sel:DWORD dst_unused:UNUSED_PAD src0_sel:WORD_1 src1_sel:DWORD
	v_pk_fma_f32 v[2:3], v[0:1], v[2:3], v[4:5]
	v_add3_u32 v34, v6, v34, s84
	v_and_b32_e32 v42, 0xffff0000, v34
	v_and_b32_sdwa v34, v3, v216 dst_sel:DWORD dst_unused:UNUSED_PAD src0_sel:WORD_1 src1_sel:DWORD
	v_and_b32_sdwa v23, v7, v216 dst_sel:DWORD dst_unused:UNUSED_PAD src0_sel:WORD_1 src1_sel:DWORD
	v_and_b32_sdwa v35, v2, v216 dst_sel:DWORD dst_unused:UNUSED_PAD src0_sel:WORD_1 src1_sel:DWORD
	v_add3_u32 v34, v3, v34, s84
	v_add3_u32 v23, v7, v23, s84
	v_add3_u32 v43, v2, v35, s84
	v_and_b32_e32 v44, 0xffff0000, v34
	v_or_b32_sdwa v35, v44, v23 dst_sel:DWORD dst_unused:UNUSED_PAD src0_sel:DWORD src1_sel:WORD_1
	v_or_b32_sdwa v34, v43, v42 dst_sel:DWORD dst_unused:UNUSED_PAD src0_sel:WORD_1 src1_sel:DWORD
	ds_write_b64 v98, v[34:35]
	v_and_b32_e32 v34, 0xffff0000, v43
	v_sub_u32_e32 v6, v6, v42
	v_and_b32_e32 v23, 0xffff0000, v23
	v_sub_u32_e32 v2, v2, v34
	v_add_u32_e32 v6, 0x80, v6
	v_sub_u32_e32 v7, v7, v23
	v_sub_u32_e32 v3, v3, v44
	v_add_u32_e32 v2, 0x80, v2
	v_ashrrev_i32_e32 v6, 8, v6
	v_add_u32_e32 v7, 0x80, v7
	v_add_u32_e32 v3, 0x80, v3
	v_ashrrev_i32_e32 v2, 8, v2
	v_min_i32_e32 v6, 0x7f, v6
	v_ashrrev_i32_e32 v7, 8, v7
	v_ashrrev_i32_e32 v3, 8, v3
	v_min_i32_e32 v2, 0x7f, v2
	v_min_i32_sdwa v7, v7, s85 dst_sel:WORD_1 dst_unused:UNUSED_PAD src0_sel:DWORD src1_sel:DWORD
	v_min_i32_e32 v3, 0x7f, v3
	v_lshlrev_b32_e32 v6, 8, v6
	v_and_b32_e32 v6, 0xff00, v6
	v_and_b32_e32 v7, 0xff0000, v7
	v_perm_b32 v2, v3, v2, s92
	v_or3_b32 v2, v2, v6, v7
	ds_write_b32 v18, v2 offset:16
	buffer_store_dwordx4 v[164:167], v88, s[16:19], s41 offen
	ds_read_b64 v[2:3], v19 offset:1024
	s_waitcnt lgkmcnt(0)
	v_pk_add_f32 v[6:7], v[50:51], v[2:3] op_sel_hi:[1,0] neg_lo:[0,1] neg_hi:[0,1]
	s_nop 0
	v_pk_mul_f32 v[6:7], v[2:3], v[6:7] op_sel:[1,0]
	v_pk_add_f32 v[34:35], v[62:63], v[2:3] op_sel_hi:[1,0] neg_lo:[0,1] neg_hi:[0,1]
	v_pk_fma_f32 v[6:7], v[64:65], v[6:7], v[66:67]
	v_pk_mul_f32 v[2:3], v[2:3], v[34:35] op_sel:[1,0]
	s_nop 0
	v_pk_fma_f32 v[0:1], v[0:1], v[2:3], v[4:5]
	v_and_b32_sdwa v2, v7, v216 dst_sel:DWORD dst_unused:UNUSED_PAD src0_sel:WORD_1 src1_sel:DWORD
	v_and_b32_sdwa v3, v6, v216 dst_sel:DWORD dst_unused:UNUSED_PAD src0_sel:WORD_1 src1_sel:DWORD
	v_add3_u32 v4, v7, v2, s84
	v_add3_u32 v2, v6, v3, s84
	v_and_b32_e32 v5, 0xffff0000, v2
	v_and_b32_sdwa v2, v1, v216 dst_sel:DWORD dst_unused:UNUSED_PAD src0_sel:WORD_1 src1_sel:DWORD
	v_and_b32_sdwa v3, v0, v216 dst_sel:DWORD dst_unused:UNUSED_PAD src0_sel:WORD_1 src1_sel:DWORD
	v_add3_u32 v2, v1, v2, s84
	v_add3_u32 v23, v0, v3, s84
	v_and_b32_e32 v34, 0xffff0000, v2
	v_or_b32_sdwa v3, v34, v4 dst_sel:DWORD dst_unused:UNUSED_PAD src0_sel:DWORD src1_sel:WORD_1
	v_or_b32_sdwa v2, v23, v5 dst_sel:DWORD dst_unused:UNUSED_PAD src0_sel:WORD_1 src1_sel:DWORD
	ds_write_b64 v99, v[2:3]
	v_and_b32_e32 v2, 0xffff0000, v23
	v_sub_u32_e32 v0, v0, v2
	v_sub_u32_e32 v2, v6, v5
	v_and_b32_e32 v3, 0xffff0000, v4
	v_add_u32_e32 v2, 0x80, v2
	v_sub_u32_e32 v3, v7, v3
	v_sub_u32_e32 v1, v1, v34
	v_add_u32_e32 v0, 0x80, v0
	v_ashrrev_i32_e32 v2, 8, v2
	v_add_u32_e32 v3, 0x80, v3
	v_add_u32_e32 v1, 0x80, v1
	v_ashrrev_i32_e32 v0, 8, v0
	v_min_i32_e32 v2, 0x7f, v2
	v_ashrrev_i32_e32 v3, 8, v3
	v_ashrrev_i32_e32 v1, 8, v1
	v_min_i32_e32 v0, 0x7f, v0
	v_min_i32_sdwa v3, v3, s85 dst_sel:WORD_1 dst_unused:UNUSED_PAD src0_sel:DWORD src1_sel:DWORD
	v_min_i32_e32 v1, 0x7f, v1
	v_lshlrev_b32_e32 v2, 8, v2
	v_and_b32_e32 v2, 0xff00, v2
	v_and_b32_e32 v3, 0xff0000, v3
	v_perm_b32 v0, v1, v0, s92
	v_or3_b32 v0, v0, v2, v3
	ds_write_b32 v22, v0 offset:16
	buffer_store_dwordx4 v[168:171], v89, s[16:19], s41 offen
	v_mov_b32_e32 v0, v228
	v_mov_b32_e32 v1, v229
	v_mov_b32_e32 v2, v230
	v_mov_b32_e32 v3, v231
	v_mov_b32_e32 v4, v244
	v_mov_b32_e32 v5, v245
	v_mov_b32_e32 v6, v246
	v_mov_b32_e32 v7, v247
	ds_read_b64 v[44:45], v149 offset:1024
	s_waitcnt lgkmcnt(0)
	v_pk_add_f32 v[46:47], v[56:57], v[44:45] op_sel_hi:[1,0] neg_lo:[0,1] neg_hi:[0,1]
	s_nop 0
	v_pk_mul_f32 v[46:47], v[44:45], v[46:47] op_sel:[1,0]
	v_pk_add_f32 v[50:51], v[54:55], v[44:45] op_sel_hi:[1,0] neg_lo:[0,1] neg_hi:[0,1]
	v_mov_b32_e32 v34, v1
	v_mov_b32_e32 v35, v2
	v_mov_b32_e32 v42, v5
	v_mov_b32_e32 v43, v6
	v_pk_fma_f32 v[46:47], v[34:35], v[46:47], v[42:43]
	v_pk_mul_f32 v[44:45], v[44:45], v[50:51] op_sel:[1,0]
	v_mov_b32_e32 v1, v3
	v_mov_b32_e32 v5, v7
	v_and_b32_sdwa v6, v47, v216 dst_sel:DWORD dst_unused:UNUSED_PAD src0_sel:WORD_1 src1_sel:DWORD
	v_and_b32_sdwa v7, v46, v216 dst_sel:DWORD dst_unused:UNUSED_PAD src0_sel:WORD_1 src1_sel:DWORD
	v_pk_fma_f32 v[2:3], v[0:1], v[44:45], v[4:5]
	v_add3_u32 v23, v47, v6, s84
	v_add3_u32 v6, v46, v7, s84
	v_and_b32_e32 v44, 0xffff0000, v6
	v_and_b32_sdwa v6, v3, v216 dst_sel:DWORD dst_unused:UNUSED_PAD src0_sel:WORD_1 src1_sel:DWORD
	v_and_b32_sdwa v7, v2, v216 dst_sel:DWORD dst_unused:UNUSED_PAD src0_sel:WORD_1 src1_sel:DWORD
	v_add3_u32 v6, v3, v6, s84
	v_add3_u32 v45, v2, v7, s84
	v_and_b32_e32 v50, 0xffff0000, v6
	v_or_b32_sdwa v7, v50, v23 dst_sel:DWORD dst_unused:UNUSED_PAD src0_sel:DWORD src1_sel:WORD_1
	v_or_b32_sdwa v6, v45, v44 dst_sel:DWORD dst_unused:UNUSED_PAD src0_sel:WORD_1 src1_sel:DWORD
	ds_write_b64 v106, v[6:7]
	v_and_b32_e32 v6, 0xffff0000, v45
	v_sub_u32_e32 v2, v2, v6
	v_sub_u32_e32 v6, v46, v44
	v_and_b32_e32 v7, 0xffff0000, v23
	v_add_u32_e32 v6, 0x80, v6
	v_sub_u32_e32 v7, v47, v7
	v_sub_u32_e32 v3, v3, v50
	v_add_u32_e32 v2, 0x80, v2
	v_ashrrev_i32_e32 v6, 8, v6
	v_add_u32_e32 v7, 0x80, v7
	v_add_u32_e32 v3, 0x80, v3
	v_ashrrev_i32_e32 v2, 8, v2
	v_min_i32_e32 v6, 0x7f, v6
	v_ashrrev_i32_e32 v7, 8, v7
	v_ashrrev_i32_e32 v3, 8, v3
	v_min_i32_e32 v2, 0x7f, v2
	v_min_i32_sdwa v7, v7, s85 dst_sel:WORD_1 dst_unused:UNUSED_PAD src0_sel:DWORD src1_sel:DWORD
	v_min_i32_e32 v3, 0x7f, v3
	v_lshlrev_b32_e32 v6, 8, v6
	v_and_b32_e32 v6, 0xff00, v6
	v_and_b32_e32 v7, 0xff0000, v7
	v_perm_b32 v2, v3, v2, s92
	v_or3_b32 v2, v2, v6, v7
	ds_write_b32 v12, v2 offset:128
	buffer_store_dwordx4 v[172:175], v146, s[20:23], s1 offen
	ds_read_b64 v[2:3], v13 offset:1024
	s_waitcnt lgkmcnt(0)
;     ...
;           _Pragma("unroll") for (int bj = 0; bj < 2; ++bj) _Pragma("unroll") for (int n = 0; n < 2; ++n) {
;             const int cc = bj * HALF + wc3 * 32 + n * 16 + fq3 * 4;
;             const float4 gm = *reinterpret_cast<const float4*>(g.gam + pn * BM + cc), bt = *reinterpret_cast<const float4*>(g.bet + pn * BM + cc);
;             _Pragma("unroll") for (int m = 0; m < 4; ++m) {
;               const int rr = wr3 * 64 + m * 16 + fr3;
;               const float2 ms = *reinterpret_cast<const float2*>(mr + (ai * HALF + rr) * 2);
;               f32x4 y = acc[ai][bj][m][n];
;               const float o0 = (y[0] - ms.x) * ms.y * gm.x + bt.x, o1 = (y[1] - ms.x) * ms.y * gm.y + bt.y;
;               const float o2 = (y[2] - ms.x) * ms.y * gm.z + bt.z, o3 = (y[3] - ms.x) * ms.y * gm.w + bt.w;
;               const unsigned h0 = f2bf(o0), h1 = f2bf(o1), h2 = f2bf(o2), h3 = f2bf(o3);
;               u32x2 ob; ob[0] = h0 | (h1 << 16); ob[1] = h2 | (h3 << 16);
;               *reinterpret_cast<u32x2*>(smem + (rr >> 1) * PIECE + (rr & 1) * 512 + cc * 2) = ob;
;               const int l0 = min(((int)__float_as_uint(o0) - (int)(h0 << 16) + 128) >> 8, 127);
;               const int l1 = min(((int)__float_as_uint(o1) - (int)(h1 << 16) + 128) >> 8, 127);
;               const int l2 = min(((int)__float_as_uint(o2) - (int)(h2 << 16) + 128) >> 8, 127);
;               const int l3 = min(((int)__float_as_uint(o3) - (int)(h3 << 16) + 128) >> 8, 127);
;               *reinterpret_cast<unsigned*>(smem + LOBASE + (rr >> 2) * PIECE + (rr & 3) * 256 + cc) =
;                   (unsigned)(l0 & 255) | ((unsigned)(l1 & 255) << 8) | ((unsigned)(l2 & 255) << 16) | ((unsigned)l3 << 24);
;             }
;     ...
;           _Pragma("unroll") for (int i = 0; i < 8; ++i) {
;             const u32x4 v = *reinterpret_cast<const u32x4*>(smem + (wave * 8 + i) * PIECE + lane3 * 16);
;             __builtin_amdgcn_raw_buffer_store_b128(v, rsXB, hvo + i * (2 * DM * 2), hso, 0);
;           }
;           _Pragma("unroll") for (int i = 0; i < 4; ++i) {
;             const u32x4 v = *reinterpret_cast<const u32x4*>(smem + LOBASE + (wave * 4 + i) * PIECE + lane3 * 16);
;             __builtin_amdgcn_raw_buffer_store_b128(v, rsLO, lvo + i * (4 * DM), lso, 0);
;           }
	v_pk_add_f32 v[6:7], v[40:41], v[2:3] op_sel_hi:[1,0] neg_lo:[0,1] neg_hi:[0,1]
	s_nop 0
	v_pk_mul_f32 v[6:7], v[2:3], v[6:7] op_sel:[1,0]
	v_pk_add_f32 v[38:39], v[38:39], v[2:3] op_sel_hi:[1,0] neg_lo:[0,1] neg_hi:[0,1]
	v_pk_fma_f32 v[6:7], v[34:35], v[6:7], v[42:43]
	v_pk_mul_f32 v[2:3], v[2:3], v[38:39] op_sel:[1,0]
	v_and_b32_sdwa v38, v6, v216 dst_sel:DWORD dst_unused:UNUSED_PAD src0_sel:WORD_1 src1_sel:DWORD
	v_pk_fma_f32 v[2:3], v[0:1], v[2:3], v[4:5]
	v_add3_u32 v38, v6, v38, s84
	v_and_b32_e32 v40, 0xffff0000, v38
	v_and_b32_sdwa v38, v3, v216 dst_sel:DWORD dst_unused:UNUSED_PAD src0_sel:WORD_1 src1_sel:DWORD
	v_and_b32_sdwa v23, v7, v216 dst_sel:DWORD dst_unused:UNUSED_PAD src0_sel:WORD_1 src1_sel:DWORD
	v_and_b32_sdwa v39, v2, v216 dst_sel:DWORD dst_unused:UNUSED_PAD src0_sel:WORD_1 src1_sel:DWORD
	v_add3_u32 v38, v3, v38, s84
	v_add3_u32 v23, v7, v23, s84
	v_add3_u32 v41, v2, v39, s84
	v_and_b32_e32 v44, 0xffff0000, v38
	v_or_b32_sdwa v39, v44, v23 dst_sel:DWORD dst_unused:UNUSED_PAD src0_sel:DWORD src1_sel:WORD_1
	v_or_b32_sdwa v38, v41, v40 dst_sel:DWORD dst_unused:UNUSED_PAD src0_sel:WORD_1 src1_sel:DWORD
	ds_write_b64 v102, v[38:39]
	v_and_b32_e32 v38, 0xffff0000, v41
	v_sub_u32_e32 v6, v6, v40
	v_and_b32_e32 v23, 0xffff0000, v23
	v_sub_u32_e32 v2, v2, v38
	v_add_u32_e32 v6, 0x80, v6
	v_sub_u32_e32 v7, v7, v23
	v_sub_u32_e32 v3, v3, v44
	v_add_u32_e32 v2, 0x80, v2
	v_ashrrev_i32_e32 v6, 8, v6
	v_add_u32_e32 v7, 0x80, v7
	v_add_u32_e32 v3, 0x80, v3
	v_ashrrev_i32_e32 v2, 8, v2
	v_min_i32_e32 v6, 0x7f, v6
	v_ashrrev_i32_e32 v7, 8, v7
	v_ashrrev_i32_e32 v3, 8, v3
	v_min_i32_e32 v2, 0x7f, v2
	v_min_i32_sdwa v7, v7, s85 dst_sel:WORD_1 dst_unused:UNUSED_PAD src0_sel:DWORD src1_sel:DWORD
	v_min_i32_e32 v3, 0x7f, v3
	v_lshlrev_b32_e32 v6, 8, v6
	v_and_b32_e32 v6, 0xff00, v6
	v_and_b32_e32 v7, 0xff0000, v7
	v_perm_b32 v2, v3, v2, s92
	v_or3_b32 v2, v2, v6, v7
	ds_write_b32 v14, v2 offset:128
	buffer_store_dwordx4 v[176:179], v90, s[20:23], s1 offen
	ds_read_b64 v[2:3], v15 offset:1024
	s_waitcnt lgkmcnt(0)
	v_pk_add_f32 v[6:7], v[24:25], v[2:3] op_sel_hi:[1,0] neg_lo:[0,1] neg_hi:[0,1]
	s_nop 0
	v_pk_mul_f32 v[6:7], v[2:3], v[6:7] op_sel:[1,0]
	v_pk_add_f32 v[24:25], v[26:27], v[2:3] op_sel_hi:[1,0] neg_lo:[0,1] neg_hi:[0,1]
	v_pk_fma_f32 v[6:7], v[34:35], v[6:7], v[42:43]
	v_pk_mul_f32 v[2:3], v[2:3], v[24:25] op_sel:[1,0]
	v_and_b32_sdwa v24, v6, v216 dst_sel:DWORD dst_unused:UNUSED_PAD src0_sel:WORD_1 src1_sel:DWORD
	v_pk_fma_f32 v[2:3], v[0:1], v[2:3], v[4:5]
	v_add3_u32 v24, v6, v24, s84
	v_and_b32_e32 v26, 0xffff0000, v24
	v_and_b32_sdwa v24, v3, v216 dst_sel:DWORD dst_unused:UNUSED_PAD src0_sel:WORD_1 src1_sel:DWORD
	v_and_b32_sdwa v23, v7, v216 dst_sel:DWORD dst_unused:UNUSED_PAD src0_sel:WORD_1 src1_sel:DWORD
	v_and_b32_sdwa v25, v2, v216 dst_sel:DWORD dst_unused:UNUSED_PAD src0_sel:WORD_1 src1_sel:DWORD
	v_add3_u32 v24, v3, v24, s84
	v_add3_u32 v23, v7, v23, s84
	v_add3_u32 v27, v2, v25, s84
	v_and_b32_e32 v38, 0xffff0000, v24
	v_or_b32_sdwa v25, v38, v23 dst_sel:DWORD dst_unused:UNUSED_PAD src0_sel:DWORD src1_sel:WORD_1
	v_or_b32_sdwa v24, v27, v26 dst_sel:DWORD dst_unused:UNUSED_PAD src0_sel:WORD_1 src1_sel:DWORD
	ds_write_b64 v92, v[24:25]
	v_and_b32_e32 v24, 0xffff0000, v27
	v_sub_u32_e32 v6, v6, v26
	v_and_b32_e32 v23, 0xffff0000, v23
	v_sub_u32_e32 v2, v2, v24
	v_add_u32_e32 v6, 0x80, v6
	v_sub_u32_e32 v7, v7, v23
	v_sub_u32_e32 v3, v3, v38
	v_add_u32_e32 v2, 0x80, v2
	v_ashrrev_i32_e32 v6, 8, v6
	v_add_u32_e32 v7, 0x80, v7
	v_add_u32_e32 v3, 0x80, v3
	v_ashrrev_i32_e32 v2, 8, v2
	v_min_i32_e32 v6, 0x7f, v6
	v_ashrrev_i32_e32 v7, 8, v7
	v_ashrrev_i32_e32 v3, 8, v3
	v_min_i32_e32 v2, 0x7f, v2
	v_min_i32_sdwa v7, v7, s85 dst_sel:WORD_1 dst_unused:UNUSED_PAD src0_sel:DWORD src1_sel:DWORD
	v_min_i32_e32 v3, 0x7f, v3
	v_lshlrev_b32_e32 v6, 8, v6
	v_and_b32_e32 v6, 0xff00, v6
	v_and_b32_e32 v7, 0xff0000, v7
	v_perm_b32 v2, v3, v2, s92
	v_or3_b32 v2, v2, v6, v7
	ds_write_b32 v18, v2 offset:128
	buffer_store_dwordx4 v[180:183], v91, s[20:23], s1 offen
	ds_read_b64 v[2:3], v19 offset:1024
	s_waitcnt lgkmcnt(0)
	v_pk_add_f32 v[6:7], v[28:29], v[2:3] op_sel_hi:[1,0] neg_lo:[0,1] neg_hi:[0,1]
	s_nop 0
	v_pk_mul_f32 v[6:7], v[2:3], v[6:7] op_sel:[1,0]
	v_pk_add_f32 v[24:25], v[30:31], v[2:3] op_sel_hi:[1,0] neg_lo:[0,1] neg_hi:[0,1]
	v_pk_fma_f32 v[6:7], v[34:35], v[6:7], v[42:43]
	v_pk_mul_f32 v[2:3], v[2:3], v[24:25] op_sel:[1,0]
	s_nop 0
	v_pk_fma_f32 v[0:1], v[0:1], v[2:3], v[4:5]
	v_and_b32_sdwa v2, v7, v216 dst_sel:DWORD dst_unused:UNUSED_PAD src0_sel:WORD_1 src1_sel:DWORD
	v_and_b32_sdwa v3, v6, v216 dst_sel:DWORD dst_unused:UNUSED_PAD src0_sel:WORD_1 src1_sel:DWORD
	v_add3_u32 v4, v7, v2, s84
	v_add3_u32 v2, v6, v3, s84
	v_and_b32_e32 v5, 0xffff0000, v2
	v_and_b32_sdwa v2, v1, v216 dst_sel:DWORD dst_unused:UNUSED_PAD src0_sel:WORD_1 src1_sel:DWORD
	v_and_b32_sdwa v3, v0, v216 dst_sel:DWORD dst_unused:UNUSED_PAD src0_sel:WORD_1 src1_sel:DWORD
	v_add3_u32 v2, v1, v2, s84
	v_add3_u32 v23, v0, v3, s84
	v_and_b32_e32 v24, 0xffff0000, v2
	v_or_b32_sdwa v3, v24, v4 dst_sel:DWORD dst_unused:UNUSED_PAD src0_sel:DWORD src1_sel:WORD_1
	v_or_b32_sdwa v2, v23, v5 dst_sel:DWORD dst_unused:UNUSED_PAD src0_sel:WORD_1 src1_sel:DWORD
	ds_write_b64 v93, v[2:3]
	v_and_b32_e32 v2, 0xffff0000, v23
	v_sub_u32_e32 v0, v0, v2
	v_sub_u32_e32 v2, v6, v5
	v_and_b32_e32 v3, 0xffff0000, v4
	v_add_u32_e32 v2, 0x80, v2
	v_sub_u32_e32 v3, v7, v3
	v_sub_u32_e32 v1, v1, v24
	v_add_u32_e32 v0, 0x80, v0
	v_ashrrev_i32_e32 v2, 8, v2
	v_add_u32_e32 v3, 0x80, v3
	v_add_u32_e32 v1, 0x80, v1
	v_ashrrev_i32_e32 v0, 8, v0
	v_min_i32_e32 v2, 0x7f, v2
	v_ashrrev_i32_e32 v3, 8, v3
	v_ashrrev_i32_e32 v1, 8, v1
	v_min_i32_e32 v0, 0x7f, v0
	v_min_i32_sdwa v3, v3, s85 dst_sel:WORD_1 dst_unused:UNUSED_PAD src0_sel:DWORD src1_sel:DWORD
	v_min_i32_e32 v1, 0x7f, v1
	v_lshlrev_b32_e32 v2, 8, v2
	v_and_b32_e32 v2, 0xff00, v2
	v_and_b32_e32 v3, 0xff0000, v3
	v_perm_b32 v0, v1, v0, s92
	v_or3_b32 v0, v0, v2, v3
	ds_write_b32 v22, v0 offset:128
	buffer_store_dwordx4 v[184:187], v96, s[20:23], s1 offen
	v_mov_b32_e32 v0, v232
	v_mov_b32_e32 v1, v233
	v_mov_b32_e32 v2, v234
	v_mov_b32_e32 v3, v235
	v_mov_b32_e32 v4, v248
	v_mov_b32_e32 v5, v249
	v_mov_b32_e32 v6, v250
	v_mov_b32_e32 v7, v251
	ds_read_b64 v[28:29], v149 offset:1024
	s_mov_b64 s[4:5], -1
	s_waitcnt lgkmcnt(0)
;     ...
;           _Pragma("unroll") for (int bj = 0; bj < 2; ++bj) _Pragma("unroll") for (int n = 0; n < 2; ++n) {
;             const int cc = bj * HALF + wc3 * 32 + n * 16 + fq3 * 4;
;             const float4 gm = *reinterpret_cast<const float4*>(g.gam + pn * BM + cc), bt = *reinterpret_cast<const float4*>(g.bet + pn * BM + cc);
;             _Pragma("unroll") for (int m = 0; m < 4; ++m) {
;               const int rr = wr3 * 64 + m * 16 + fr3;
;               const float2 ms = *reinterpret_cast<const float2*>(mr + (ai * HALF + rr) * 2);
;               f32x4 y = acc[ai][bj][m][n];
;               const float o0 = (y[0] - ms.x) * ms.y * gm.x + bt.x, o1 = (y[1] - ms.x) * ms.y * gm.y + bt.y;
;               const float o2 = (y[2] - ms.x) * ms.y * gm.z + bt.z, o3 = (y[3] - ms.x) * ms.y * gm.w + bt.w;
;               const unsigned h0 = f2bf(o0), h1 = f2bf(o1), h2 = f2bf(o2), h3 = f2bf(o3);
;               u32x2 ob; ob[0] = h0 | (h1 << 16); ob[1] = h2 | (h3 << 16);
;               *reinterpret_cast<u32x2*>(smem + (rr >> 1) * PIECE + (rr & 1) * 512 + cc * 2) = ob;
;               const int l0 = min(((int)__float_as_uint(o0) - (int)(h0 << 16) + 128) >> 8, 127);
;               const int l1 = min(((int)__float_as_uint(o1) - (int)(h1 << 16) + 128) >> 8, 127);
;               const int l2 = min(((int)__float_as_uint(o2) - (int)(h2 << 16) + 128) >> 8, 127);
;               const int l3 = min(((int)__float_as_uint(o3) - (int)(h3 << 16) + 128) >> 8, 127);
;               *reinterpret_cast<unsigned*>(smem + LOBASE + (rr >> 2) * PIECE + (rr & 3) * 256 + cc) =
;                   (unsigned)(l0 & 255) | ((unsigned)(l1 & 255) << 8) | ((unsigned)(l2 & 255) << 16) | ((unsigned)l3 << 24);
;             }
	v_pk_add_f32 v[30:31], v[52:53], v[28:29] op_sel_hi:[1,0] neg_lo:[0,1] neg_hi:[0,1]
	s_nop 0
	v_pk_mul_f32 v[30:31], v[28:29], v[30:31] op_sel:[1,0]
	v_pk_add_f32 v[34:35], v[48:49], v[28:29] op_sel_hi:[1,0] neg_lo:[0,1] neg_hi:[0,1]
	v_mov_b32_e32 v24, v1
	v_mov_b32_e32 v25, v2
	v_mov_b32_e32 v26, v5
	v_mov_b32_e32 v27, v6
	v_pk_fma_f32 v[30:31], v[24:25], v[30:31], v[26:27]
	v_pk_mul_f32 v[28:29], v[28:29], v[34:35] op_sel:[1,0]
	v_mov_b32_e32 v1, v3
	v_mov_b32_e32 v5, v7
	v_and_b32_sdwa v6, v31, v216 dst_sel:DWORD dst_unused:UNUSED_PAD src0_sel:WORD_1 src1_sel:DWORD
	v_and_b32_sdwa v7, v30, v216 dst_sel:DWORD dst_unused:UNUSED_PAD src0_sel:WORD_1 src1_sel:DWORD
	v_pk_fma_f32 v[2:3], v[0:1], v[28:29], v[4:5]
	v_add3_u32 v23, v31, v6, s84
	v_add3_u32 v6, v30, v7, s84
	v_and_b32_e32 v28, 0xffff0000, v6
	v_and_b32_sdwa v6, v3, v216 dst_sel:DWORD dst_unused:UNUSED_PAD src0_sel:WORD_1 src1_sel:DWORD
	v_and_b32_sdwa v7, v2, v216 dst_sel:DWORD dst_unused:UNUSED_PAD src0_sel:WORD_1 src1_sel:DWORD
	v_add3_u32 v6, v3, v6, s84
	v_add3_u32 v29, v2, v7, s84
	v_and_b32_e32 v34, 0xffff0000, v6
	v_or_b32_sdwa v7, v34, v23 dst_sel:DWORD dst_unused:UNUSED_PAD src0_sel:DWORD src1_sel:WORD_1
	v_or_b32_sdwa v6, v29, v28 dst_sel:DWORD dst_unused:UNUSED_PAD src0_sel:WORD_1 src1_sel:DWORD
	ds_write_b64 v94, v[6:7]
	v_and_b32_e32 v6, 0xffff0000, v29
	v_sub_u32_e32 v2, v2, v6
	v_sub_u32_e32 v6, v30, v28
	v_and_b32_e32 v7, 0xffff0000, v23
	v_add_u32_e32 v6, 0x80, v6
	v_sub_u32_e32 v7, v31, v7
	v_sub_u32_e32 v3, v3, v34
	v_add_u32_e32 v2, 0x80, v2
	v_ashrrev_i32_e32 v6, 8, v6
	v_add_u32_e32 v7, 0x80, v7
	v_add_u32_e32 v3, 0x80, v3
	v_ashrrev_i32_e32 v2, 8, v2
	v_min_i32_e32 v6, 0x7f, v6
	v_ashrrev_i32_e32 v7, 8, v7
	v_ashrrev_i32_e32 v3, 8, v3
	v_min_i32_e32 v2, 0x7f, v2
	v_min_i32_sdwa v7, v7, s85 dst_sel:WORD_1 dst_unused:UNUSED_PAD src0_sel:DWORD src1_sel:DWORD
	v_min_i32_e32 v3, 0x7f, v3
	v_lshlrev_b32_e32 v6, 8, v6
	v_and_b32_e32 v6, 0xff00, v6
	v_and_b32_e32 v7, 0xff0000, v7
	v_perm_b32 v2, v3, v2, s92
	v_or3_b32 v2, v2, v6, v7
	ds_write_b32 v12, v2 offset:144
	ds_read_b64 v[2:3], v13 offset:1024
	s_waitcnt lgkmcnt(0)
	v_pk_add_f32 v[6:7], v[36:37], v[2:3] op_sel_hi:[1,0] neg_lo:[0,1] neg_hi:[0,1]
	s_nop 0
	v_pk_mul_f32 v[6:7], v[2:3], v[6:7] op_sel:[1,0]
	v_pk_add_f32 v[12:13], v[32:33], v[2:3] op_sel_hi:[1,0] neg_lo:[0,1] neg_hi:[0,1]
	v_pk_fma_f32 v[6:7], v[24:25], v[6:7], v[26:27]
	v_pk_mul_f32 v[2:3], v[2:3], v[12:13] op_sel:[1,0]
	v_and_b32_sdwa v12, v7, v216 dst_sel:DWORD dst_unused:UNUSED_PAD src0_sel:WORD_1 src1_sel:DWORD
	v_and_b32_sdwa v13, v6, v216 dst_sel:DWORD dst_unused:UNUSED_PAD src0_sel:WORD_1 src1_sel:DWORD
	v_pk_fma_f32 v[2:3], v[0:1], v[2:3], v[4:5]
	v_add3_u32 v23, v7, v12, s84
	v_add3_u32 v12, v6, v13, s84
	v_and_b32_e32 v28, 0xffff0000, v12
	v_and_b32_sdwa v12, v3, v216 dst_sel:DWORD dst_unused:UNUSED_PAD src0_sel:WORD_1 src1_sel:DWORD
	v_and_b32_sdwa v13, v2, v216 dst_sel:DWORD dst_unused:UNUSED_PAD src0_sel:WORD_1 src1_sel:DWORD
	v_add3_u32 v12, v3, v12, s84
	v_add3_u32 v29, v2, v13, s84
	v_and_b32_e32 v30, 0xffff0000, v12
	v_or_b32_sdwa v13, v30, v23 dst_sel:DWORD dst_unused:UNUSED_PAD src0_sel:DWORD src1_sel:WORD_1
	v_or_b32_sdwa v12, v29, v28 dst_sel:DWORD dst_unused:UNUSED_PAD src0_sel:WORD_1 src1_sel:DWORD
	ds_write_b64 v95, v[12:13]
	v_and_b32_e32 v12, 0xffff0000, v29
	v_sub_u32_e32 v2, v2, v12
	v_sub_u32_e32 v6, v6, v28
	v_and_b32_e32 v12, 0xffff0000, v23
	v_add_u32_e32 v6, 0x80, v6
	v_sub_u32_e32 v7, v7, v12
	v_sub_u32_e32 v3, v3, v30
	v_add_u32_e32 v2, 0x80, v2
	v_ashrrev_i32_e32 v6, 8, v6
	v_add_u32_e32 v7, 0x80, v7
	v_add_u32_e32 v3, 0x80, v3
	v_ashrrev_i32_e32 v2, 8, v2
	v_min_i32_e32 v6, 0x7f, v6
	v_ashrrev_i32_e32 v7, 8, v7
	v_ashrrev_i32_e32 v3, 8, v3
	v_min_i32_e32 v2, 0x7f, v2
	v_min_i32_sdwa v7, v7, s85 dst_sel:WORD_1 dst_unused:UNUSED_PAD src0_sel:DWORD src1_sel:DWORD
	v_min_i32_e32 v3, 0x7f, v3
	v_lshlrev_b32_e32 v6, 8, v6
	v_and_b32_e32 v6, 0xff00, v6
	v_and_b32_e32 v7, 0xff0000, v7
	v_perm_b32 v2, v3, v2, s92
	v_or3_b32 v2, v2, v6, v7
	ds_write_b32 v14, v2 offset:144
	ds_read_b64 v[2:3], v15 offset:1024
	s_waitcnt lgkmcnt(0)
	v_pk_add_f32 v[6:7], v[20:21], v[2:3] op_sel_hi:[1,0] neg_lo:[0,1] neg_hi:[0,1]
	s_nop 0
	v_pk_mul_f32 v[6:7], v[2:3], v[6:7] op_sel:[1,0]
	v_pk_add_f32 v[12:13], v[16:17], v[2:3] op_sel_hi:[1,0] neg_lo:[0,1] neg_hi:[0,1]
	v_pk_fma_f32 v[6:7], v[24:25], v[6:7], v[26:27]
	v_pk_mul_f32 v[2:3], v[2:3], v[12:13] op_sel:[1,0]
	v_and_b32_sdwa v12, v7, v216 dst_sel:DWORD dst_unused:UNUSED_PAD src0_sel:WORD_1 src1_sel:DWORD
	v_and_b32_sdwa v13, v6, v216 dst_sel:DWORD dst_unused:UNUSED_PAD src0_sel:WORD_1 src1_sel:DWORD
	v_pk_fma_f32 v[2:3], v[0:1], v[2:3], v[4:5]
	v_add3_u32 v14, v7, v12, s84
	v_add3_u32 v12, v6, v13, s84
	v_and_b32_e32 v15, 0xffff0000, v12
	v_and_b32_sdwa v12, v3, v216 dst_sel:DWORD dst_unused:UNUSED_PAD src0_sel:WORD_1 src1_sel:DWORD
	v_and_b32_sdwa v13, v2, v216 dst_sel:DWORD dst_unused:UNUSED_PAD src0_sel:WORD_1 src1_sel:DWORD
	v_add3_u32 v12, v3, v12, s84
	v_add3_u32 v16, v2, v13, s84
	v_and_b32_e32 v17, 0xffff0000, v12
	v_or_b32_sdwa v13, v17, v14 dst_sel:DWORD dst_unused:UNUSED_PAD src0_sel:DWORD src1_sel:WORD_1
	v_or_b32_sdwa v12, v16, v15 dst_sel:DWORD dst_unused:UNUSED_PAD src0_sel:WORD_1 src1_sel:DWORD
	ds_write_b64 v80, v[12:13]
	v_and_b32_e32 v12, 0xffff0000, v16
	v_sub_u32_e32 v2, v2, v12
	v_sub_u32_e32 v6, v6, v15
	v_and_b32_e32 v12, 0xffff0000, v14
	v_add_u32_e32 v6, 0x80, v6
	v_sub_u32_e32 v7, v7, v12
	v_sub_u32_e32 v3, v3, v17
	v_add_u32_e32 v2, 0x80, v2
	v_ashrrev_i32_e32 v6, 8, v6
	v_add_u32_e32 v7, 0x80, v7
	v_add_u32_e32 v3, 0x80, v3
	v_ashrrev_i32_e32 v2, 8, v2
	v_min_i32_e32 v6, 0x7f, v6
	v_ashrrev_i32_e32 v7, 8, v7
	v_ashrrev_i32_e32 v3, 8, v3
	v_min_i32_e32 v2, 0x7f, v2
	v_min_i32_sdwa v7, v7, s85 dst_sel:WORD_1 dst_unused:UNUSED_PAD src0_sel:DWORD src1_sel:DWORD
	v_min_i32_e32 v3, 0x7f, v3
	v_lshlrev_b32_e32 v6, 8, v6
	v_and_b32_e32 v6, 0xff00, v6
	v_and_b32_e32 v7, 0xff0000, v7
	v_perm_b32 v2, v3, v2, s92
	v_or3_b32 v2, v2, v6, v7
	ds_write_b32 v18, v2 offset:144
	ds_read_b64 v[2:3], v19 offset:1024
	s_waitcnt lgkmcnt(0)
;     ...
;   auto issue_prologue = [&](int sA0, int sA1, int sB0, int sB1) {
;     const int tid = opaque_tid(wave);
;     int offA[2], offB[2];
;     _Pragma("unroll") for (int i = 0; i < 2; ++i) {
;       int r, c; stage_rc(tid * 16 + i * 8192, r, c);
;       offA[i] = (r * lda + c) * 2; offB[i] = (r * ldb + c) * 2;
;     }
;     STAGE(SB(0, 0), rsB, sB0, offB, 0); STAGE(SA(0, 0), rsA, sA0, offA, 0);
;     STAGE(SB(0, 1), rsB, sB1, offB, 0); STAGE(SA(0, 1), rsA, sA1, offA, 0);
;     ...
;               const float o0 = (y[0] - ms.x) * ms.y * gm.x + bt.x, o1 = (y[1] - ms.x) * ms.y * gm.y + bt.y;
;               const float o2 = (y[2] - ms.x) * ms.y * gm.z + bt.z, o3 = (y[3] - ms.x) * ms.y * gm.w + bt.w;
;               const unsigned h0 = f2bf(o0), h1 = f2bf(o1), h2 = f2bf(o2), h3 = f2bf(o3);
;               u32x2 ob; ob[0] = h0 | (h1 << 16); ob[1] = h2 | (h3 << 16);
;               *reinterpret_cast<u32x2*>(smem + (rr >> 1) * PIECE + (rr & 1) * 512 + cc * 2) = ob;
;               const int l0 = min(((int)__float_as_uint(o0) - (int)(h0 << 16) + 128) >> 8, 127);
;               const int l1 = min(((int)__float_as_uint(o1) - (int)(h1 << 16) + 128) >> 8, 127);
;               const int l2 = min(((int)__float_as_uint(o2) - (int)(h2 << 16) + 128) >> 8, 127);
;               const int l3 = min(((int)__float_as_uint(o3) - (int)(h3 << 16) + 128) >> 8, 127);
;               *reinterpret_cast<unsigned*>(smem + LOBASE + (rr >> 2) * PIECE + (rr & 3) * 256 + cc) =
;                   (unsigned)(l0 & 255) | ((unsigned)(l1 & 255) << 8) | ((unsigned)(l2 & 255) << 16) | ((unsigned)l3 << 24);
;             }
;           }
;           WAIT_L(0); BAR;
;           const int hso = ((brow + ai * HALF + 16 * wave) * DM + pn * BM) * 2;
;           const int lso = (brow + ai * HALF + 16 * wave) * DM + pn * BM;
;           _Pragma("unroll") for (int i = 0; i < 8; ++i) {
;             const u32x4 v = *reinterpret_cast<const u32x4*>(smem + (wave * 8 + i) * PIECE + lane3 * 16);
;             __builtin_amdgcn_raw_buffer_store_b128(v, rsXB, hvo + i * (2 * DM * 2), hso, 0);
;           }
;           _Pragma("unroll") for (int i = 0; i < 4; ++i) {
;             const u32x4 v = *reinterpret_cast<const u32x4*>(smem + LOBASE + (wave * 4 + i) * PIECE + lane3 * 16);
;             __builtin_amdgcn_raw_buffer_store_b128(v, rsLO, lvo + i * (4 * DM), lso, 0);
;           }
;           WAIT_L(0); BAR;
	v_pk_add_f32 v[6:7], v[8:9], v[2:3] op_sel_hi:[1,0] neg_lo:[0,1] neg_hi:[0,1]
	s_nop 0
	v_pk_mul_f32 v[6:7], v[2:3], v[6:7] op_sel:[1,0]
	v_pk_add_f32 v[8:9], v[10:11], v[2:3] op_sel_hi:[1,0] neg_lo:[0,1] neg_hi:[0,1]
	v_pk_fma_f32 v[6:7], v[24:25], v[6:7], v[26:27]
	v_pk_mul_f32 v[2:3], v[2:3], v[8:9] op_sel:[1,0]
	s_nop 0
	v_pk_fma_f32 v[0:1], v[0:1], v[2:3], v[4:5]
	v_and_b32_sdwa v2, v7, v216 dst_sel:DWORD dst_unused:UNUSED_PAD src0_sel:WORD_1 src1_sel:DWORD
	v_and_b32_sdwa v3, v6, v216 dst_sel:DWORD dst_unused:UNUSED_PAD src0_sel:WORD_1 src1_sel:DWORD
	v_add3_u32 v4, v7, v2, s84
	v_add3_u32 v2, v6, v3, s84
	v_and_b32_e32 v5, 0xffff0000, v2
	v_and_b32_sdwa v2, v1, v216 dst_sel:DWORD dst_unused:UNUSED_PAD src0_sel:WORD_1 src1_sel:DWORD
	v_and_b32_sdwa v3, v0, v216 dst_sel:DWORD dst_unused:UNUSED_PAD src0_sel:WORD_1 src1_sel:DWORD
	v_add3_u32 v2, v1, v2, s84
	v_add3_u32 v8, v0, v3, s84
	v_and_b32_e32 v9, 0xffff0000, v2
	v_or_b32_sdwa v3, v9, v4 dst_sel:DWORD dst_unused:UNUSED_PAD src0_sel:DWORD src1_sel:WORD_1
	v_or_b32_sdwa v2, v8, v5 dst_sel:DWORD dst_unused:UNUSED_PAD src0_sel:WORD_1 src1_sel:DWORD
	ds_write_b64 v73, v[2:3]
	v_and_b32_e32 v2, 0xffff0000, v8
	v_sub_u32_e32 v0, v0, v2
	v_sub_u32_e32 v2, v6, v5
	v_and_b32_e32 v3, 0xffff0000, v4
	v_add_u32_e32 v2, 0x80, v2
	v_sub_u32_e32 v3, v7, v3
	v_sub_u32_e32 v1, v1, v9
	v_add_u32_e32 v0, 0x80, v0
	v_ashrrev_i32_e32 v2, 8, v2
	v_add_u32_e32 v3, 0x80, v3
	v_add_u32_e32 v1, 0x80, v1
	v_ashrrev_i32_e32 v0, 8, v0
	v_min_i32_e32 v2, 0x7f, v2
	v_ashrrev_i32_e32 v3, 8, v3
	v_ashrrev_i32_e32 v1, 8, v1
	v_min_i32_e32 v0, 0x7f, v0
	v_min_i32_sdwa v3, v3, s85 dst_sel:WORD_1 dst_unused:UNUSED_PAD src0_sel:DWORD src1_sel:DWORD
	v_min_i32_e32 v1, 0x7f, v1
	v_lshlrev_b32_e32 v2, 8, v2
	v_and_b32_e32 v2, 0xff00, v2
	v_and_b32_e32 v3, 0xff0000, v3
	v_perm_b32 v0, v1, v0, s92
	v_or3_b32 v0, v0, v2, v3
	ds_write_b32 v22, v0 offset:144
	s_waitcnt lgkmcnt(0)
	s_barrier
	ds_read_b128 v[0:3], v72
	s_waitcnt lgkmcnt(0)
	buffer_store_dwordx4 v[0:3], v148, s[16:19], s0 offen
	ds_read_b128 v[0:3], v72 offset:1040
	s_waitcnt lgkmcnt(0)
	buffer_store_dwordx4 v[0:3], v74, s[16:19], s0 offen
	ds_read_b128 v[0:3], v72 offset:2080
	s_waitcnt lgkmcnt(0)
	buffer_store_dwordx4 v[0:3], v75, s[16:19], s0 offen
	ds_read_b128 v[0:3], v72 offset:3120
	s_waitcnt lgkmcnt(0)
	buffer_store_dwordx4 v[0:3], v81, s[16:19], s0 offen
	ds_read_b128 v[0:3], v72 offset:4160
	s_waitcnt lgkmcnt(0)
	buffer_store_dwordx4 v[0:3], v84, s[16:19], s0 offen
	ds_read_b128 v[0:3], v72 offset:5200
	s_waitcnt lgkmcnt(0)
	buffer_store_dwordx4 v[0:3], v85, s[16:19], s0 offen
	ds_read_b128 v[0:3], v72 offset:6240
	s_waitcnt lgkmcnt(0)
	buffer_store_dwordx4 v[0:3], v88, s[16:19], s0 offen
	ds_read_b128 v[0:3], v72 offset:7280
	s_waitcnt lgkmcnt(0)
	buffer_store_dwordx4 v[0:3], v89, s[16:19], s0 offen
	ds_read_b128 v[0:3], v147
	s_waitcnt lgkmcnt(0)
	buffer_store_dwordx4 v[0:3], v146, s[20:23], s40 offen
	ds_read_b128 v[0:3], v147 offset:1040
	s_waitcnt lgkmcnt(0)
	buffer_store_dwordx4 v[0:3], v90, s[20:23], s40 offen
	ds_read_b128 v[0:3], v147 offset:2080
	s_waitcnt lgkmcnt(0)
	buffer_store_dwordx4 v[0:3], v91, s[20:23], s40 offen
	ds_read_b128 v[0:3], v147 offset:3120
	s_waitcnt lgkmcnt(0)
	buffer_store_dwordx4 v[0:3], v96, s[20:23], s40 offen
	s_waitcnt lgkmcnt(0)
	s_barrier
	s_cbranch_vccnz .LBB0_283
	v_mbcnt_lo_u32_b32 v0, -1, 0
	v_mbcnt_hi_u32_b32 v0, -1, v0
	s_mov_b32 m0, s37
	v_lshl_add_u32 v0, v0, 4, s35
	v_ashrrev_i32_e32 v1, 31, v0
	v_lshrrev_b32_e32 v1, 22, v1
	v_add_u32_e32 v1, v0, v1
	v_ashrrev_i32_e32 v1, 10, v1
	v_mul_i32_i24_e32 v2, 0x400, v1
	v_sub_u32_e32 v2, v0, v2
	v_lshrrev_b32_e32 v3, 4, v2
	v_bitop3_b32 v2, v3, v2, 32 bitop3:0x6c
	v_ashrrev_i32_e32 v4, 31, v2
	v_lshrrev_b32_e32 v4, 26, v4
	v_add_u32_e32 v4, v2, v4
	v_lshrrev_b32_e32 v5, 6, v4
	v_and_b32_e32 v4, 0xc0, v4
	v_lshlrev_b32_e32 v3, 3, v1
	v_lshlrev_b32_e32 v1, 5, v1
	v_sub_u32_e32 v2, v2, v4
	v_and_b32_e32 v3, 0x1ffff0, v3
	v_and_b32_e32 v1, 32, v1
	v_ashrrev_i16_sdwa v2, v216, sext(v2) dst_sel:DWORD dst_unused:UNUSED_PAD src0_sel:DWORD src1_sel:BYTE_0
	v_add_u32_sdwa v1, v1, sext(v2) dst_sel:DWORD dst_unused:UNUSED_PAD src0_sel:DWORD src1_sel:WORD_0
	v_add_lshl_u32 v2, v5, v3, 11
	v_add_u32_e32 v0, 0x2000, v0
	v_lshl_add_u32 v1, v1, 1, v2
	v_ashrrev_i32_e32 v2, 31, v0
	v_lshrrev_b32_e32 v2, 22, v2
	v_add_u32_e32 v2, v0, v2
	v_ashrrev_i32_e32 v2, 10, v2
	v_mul_i32_i24_e32 v3, 0x400, v2
	v_sub_u32_e32 v0, v0, v3
	v_lshrrev_b32_e32 v3, 4, v0
	v_bitop3_b32 v0, v3, v0, 32 bitop3:0x6c
	v_ashrrev_i32_e32 v4, 31, v0
	v_lshrrev_b32_e32 v4, 26, v4
	v_add_u32_e32 v4, v0, v4
	v_lshrrev_b32_e32 v5, 6, v4
	v_and_b32_e32 v4, 0xffc0, v4
	v_sub_u32_e32 v0, v0, v4
	v_lshrrev_b16_e32 v4, 7, v0
	v_and_b32_e32 v4, 1, v4
	v_lshlrev_b32_e32 v3, 3, v2
	v_lshlrev_b32_e32 v2, 5, v2
	v_add_u16_e32 v0, v0, v4
	v_and_b32_e32 v3, 0x1ffff0, v3
	v_and_b32_e32 v2, 32, v2
	v_ashrrev_i16_sdwa v0, v216, sext(v0) dst_sel:DWORD dst_unused:UNUSED_PAD src0_sel:DWORD src1_sel:BYTE_0
	v_add_u32_sdwa v0, v2, sext(v0) dst_sel:DWORD dst_unused:UNUSED_PAD src0_sel:DWORD src1_sel:WORD_0
	v_add_lshl_u32 v2, v5, v3, 11
	s_mov_b32 s14, s10
	s_mov_b32 s15, s11
	v_lshl_add_u32 v0, v0, 1, v2
	buffer_load_dwordx4 v1, s[12:15], s96 offen lds
	s_mov_b32 m0, s48
	s_or_b32 s0, s96, 0x80
	buffer_load_dwordx4 v0, s[12:15], s96 offen lds
	s_mov_b32 m0, s35
	s_mov_b64 s[4:5], 0
	buffer_load_dwordx4 v1, s[8:11], s95 offen lds
	s_mov_b32 m0, s49
	s_nop 0
	buffer_load_dwordx4 v0, s[8:11], s95 offen lds
	s_mov_b32 m0, s38
	s_nop 0
	buffer_load_dwordx4 v1, s[12:15], s97 offen lds
	s_mov_b32 m0, s54
	s_nop 0
	buffer_load_dwordx4 v0, s[12:15], s97 offen lds
	s_mov_b32 m0, s39
	s_nop 0
	buffer_load_dwordx4 v1, s[8:11], s94 offen lds
	s_mov_b32 m0, s55
	s_nop 0
	buffer_load_dwordx4 v0, s[8:11], s94 offen lds
	s_mov_b32 m0, s42
	s_nop 0
	buffer_load_dwordx4 v1, s[12:15], s0 offen lds
	s_mov_b32 m0, s58
	s_nop 0
	buffer_load_dwordx4 v0, s[12:15], s0 offen lds
	s_or_b32 s0, s95, 0x80
	s_mov_b32 m0, s43
	s_nop 0
	buffer_load_dwordx4 v1, s[8:11], s0 offen lds
	s_mov_b32 m0, s59
	s_nop 0
	buffer_load_dwordx4 v0, s[8:11], s0 offen lds
	s_add_i32 s0, s97, 0x80
	s_mov_b32 m0, s44
	s_nop 0
	buffer_load_dwordx4 v1, s[12:15], s0 offen lds
	s_mov_b32 m0, s60
	s_nop 0
	buffer_load_dwordx4 v0, s[12:15], s0 offen lds
	s_branch .LBB0_283

;     ...
;       const int tid3 = opaque_tid(wave);
;       const int wr3 = tid3 >> 8, wc3 = (tid3 >> 6) & 3, fr3 = tid3 & 15, fq3 = (tid3 & 63) >> 4;
;       const int ebase3 = (brow + wr3 * 64 + fr3) * DM + pn * BM + wc3 * 32 + fq3 * 4;
;       const int vo4b = ebase3 * 4, vo2 = ebase3 * 2, vo1 = ebase3;
;     ...
;         constexpr int PIECE = 1024 + 16, LOBASE = 64 * PIECE;
;         const int lane3 = tid3 & 63;
;         const int hvo = (lane3 >> 5) * (DM * 2) + (lane3 & 31) * 16;
;         const int lvo = (lane3 >> 4) * DM + (lane3 & 15) * 16;
;         _Pragma("unroll") for (int ai = 0; ai < 2; ++ai) {
;           _Pragma("unroll") for (int bj = 0; bj < 2; ++bj) _Pragma("unroll") for (int n = 0; n < 2; ++n) {
;             const int cc = bj * HALF + wc3 * 32 + n * 16 + fq3 * 4;
;             const float4 gm = *reinterpret_cast<const float4*>(g.gam + pn * BM + cc), bt = *reinterpret_cast<const float4*>(g.bet + pn * BM + cc);
;             _Pragma("unroll") for (int m = 0; m < 4; ++m) {
;               const int rr = wr3 * 64 + m * 16 + fr3;
;               const float2 ms = *reinterpret_cast<const float2*>(mr + (ai * HALF + rr) * 2);
;               f32x4 y = acc[ai][bj][m][n];
;               const float o0 = (y[0] - ms.x) * ms.y * gm.x + bt.x, o1 = (y[1] - ms.x) * ms.y * gm.y + bt.y;
;               const float o2 = (y[2] - ms.x) * ms.y * gm.z + bt.z, o3 = (y[3] - ms.x) * ms.y * gm.w + bt.w;
;               const unsigned h0 = f2bf(o0), h1 = f2bf(o1), h2 = f2bf(o2), h3 = f2bf(o3);
;               u32x2 ob; ob[0] = h0 | (h1 << 16); ob[1] = h2 | (h3 << 16);
;               *reinterpret_cast<u32x2*>(smem + (rr >> 1) * PIECE + (rr & 1) * 512 + cc * 2) = ob;
;               const int l0 = min(((int)__float_as_uint(o0) - (int)(h0 << 16) + 128) >> 8, 127);
;               const int l1 = min(((int)__float_as_uint(o1) - (int)(h1 << 16) + 128) >> 8, 127);
;               const int l2 = min(((int)__float_as_uint(o2) - (int)(h2 << 16) + 128) >> 8, 127);
;               const int l3 = min(((int)__float_as_uint(o3) - (int)(h3 << 16) + 128) >> 8, 127);
;               *reinterpret_cast<unsigned*>(smem + LOBASE + (rr >> 2) * PIECE + (rr & 3) * 256 + cc) =
;                   (unsigned)(l0 & 255) | ((unsigned)(l1 & 255) << 8) | ((unsigned)(l2 & 255) << 16) | ((unsigned)l3 << 24);
;             }
.LBB0_421:
	s_or_b64 exec, exec, s[6:7]
	s_waitcnt lgkmcnt(0)
	s_barrier
	v_mbcnt_lo_u32_b32 v0, -1, 0
	v_mbcnt_hi_u32_b32 v0, -1, v0
	s_movk_i32 s4, 0x60
	v_add_u32_e32 v1, s34, v0
	v_ashrrev_i32_e32 v5, 2, v1
	v_lshrrev_b32_e32 v6, 1, v1
	v_lshlrev_b32_e32 v1, 4, v1
	v_bfe_u32 v4, v0, 4, 2
	v_lshlrev_b32_e32 v12, 7, v0
	v_and_b32_e32 v13, 0x1f0, v1
	v_lshlrev_b32_e32 v7, 2, v4
	v_and_or_b32 v148, v12, s29, v13
	s_ashr_i32 s29, s28, 31
	v_readlane_b32 s60, v255, 0
	v_and_or_b32 v12, v6, s4, v7
	s_lshl_b64 s[4:5], s[28:29], 2
	v_readlane_b32 s66, v255, 6
	v_readlane_b32 s67, v255, 7
	s_add_u32 s6, s66, s4
	v_and_b32_e32 v2, 15, v0
	v_and_b32_e32 v3, 63, v0
	v_and_b32_e32 v1, 0xf0, v1
	v_lshlrev_b32_e32 v13, 9, v0
	v_lshlrev_b32_e32 v0, 8, v0
	s_addc_u32 s7, s67, s5
	v_lshlrev_b32_e32 v150, 2, v12
	v_lshl_or_b32 v146, v4, 11, v1
	v_and_or_b32 v156, v5, s2, v2
	v_and_b32_e32 v14, 0x300, v0
	v_lshlrev_b32_e32 v152, 4, v3
	global_load_dwordx4 v[220:223], v150, s[6:7]
	global_load_dwordx4 v[224:227], v150, s[6:7] offset:64
	global_load_dwordx4 v[228:231], v150, s[6:7] offset:512
	global_load_dwordx4 v[232:235], v150, s[6:7] offset:576
	v_readlane_b32 s68, v255, 8
	v_readlane_b32 s69, v255, 9
	s_add_u32 s4, s68, s4
	s_addc_u32 s5, s69, s5
	global_load_dwordx4 v[236:239], v150, s[4:5]
	global_load_dwordx4 v[240:243], v150, s[4:5] offset:64
	global_load_dwordx4 v[244:247], v150, s[4:5] offset:512
	global_load_dwordx4 v[248:251], v150, s[4:5] offset:576
	s_movk_i32 s22, 0x200
	v_lshl_add_u32 v149, v156, 3, v219
	v_add_u32_e32 v147, s46, v152
	s_andn2_b64 vcc, exec, s[14:15]
	s_movk_i32 s40, 0x100
	v_readlane_b32 s61, v255, 1
	v_readlane_b32 s62, v255, 2
	v_readlane_b32 s63, v255, 3
	v_readlane_b32 s64, v255, 4
	v_readlane_b32 s65, v255, 5
	v_readlane_b32 s70, v255, 10
	v_readlane_b32 s71, v255, 11
	v_readlane_b32 s72, v255, 12
	v_readlane_b32 s73, v255, 13
	v_readlane_b32 s74, v255, 14
	v_readlane_b32 s75, v255, 15
	s_waitcnt vmcnt(0)
	v_mov_b32_e32 v0, v220
	v_mov_b32_e32 v1, v221
	v_mov_b32_e32 v2, v222
	v_mov_b32_e32 v3, v223
	v_mov_b32_e32 v4, v236
	v_mov_b32_e32 v5, v237
	v_mov_b32_e32 v6, v238
	v_mov_b32_e32 v7, v239
	v_mov_b32_e32 v22, v1
	v_lshlrev_b32_e32 v1, 1, v12
	v_and_or_b32 v155, v13, s22, v1
	s_mov_b32 s22, 0x10400
	v_mov_b32_e32 v23, v2
	v_or3_b32 v2, v14, v12, s22
	ds_read_b64 v[12:13], v149
	v_mov_b32_e32 v144, v5
	v_mov_b32_e32 v145, v6
	v_mov_b32_e32 v1, v3
	v_mov_b32_e32 v5, v7
	s_waitcnt lgkmcnt(0)
	v_pk_add_f32 v[14:15], v[128:129], v[12:13] op_sel_hi:[1,0] neg_lo:[0,1] neg_hi:[0,1]
	v_pk_add_f32 v[20:21], v[130:131], v[12:13] op_sel_hi:[1,0] neg_lo:[0,1] neg_hi:[0,1]
	v_pk_mul_f32 v[14:15], v[12:13], v[14:15] op_sel:[1,0]
	v_pk_mul_f32 v[12:13], v[12:13], v[20:21] op_sel:[1,0]
	v_pk_fma_f32 v[14:15], v[22:23], v[14:15], v[144:145]
	v_pk_fma_f32 v[6:7], v[0:1], v[12:13], v[4:5]
	v_and_b32_sdwa v12, v14, v216 dst_sel:DWORD dst_unused:UNUSED_PAD src0_sel:WORD_1 src1_sel:DWORD
	v_add3_u32 v12, v14, v12, s82
	v_and_b32_e32 v20, 0xffff0000, v12
	v_and_b32_sdwa v12, v7, v216 dst_sel:DWORD dst_unused:UNUSED_PAD src0_sel:WORD_1 src1_sel:DWORD
	v_and_b32_sdwa v3, v15, v216 dst_sel:DWORD dst_unused:UNUSED_PAD src0_sel:WORD_1 src1_sel:DWORD
	v_and_b32_sdwa v13, v6, v216 dst_sel:DWORD dst_unused:UNUSED_PAD src0_sel:WORD_1 src1_sel:DWORD
	v_add3_u32 v12, v7, v12, s82
	v_lshrrev_b32_e32 v129, 1, v156
	v_add3_u32 v3, v15, v3, s82
	v_add3_u32 v21, v6, v13, s82
	v_and_b32_e32 v128, 0xffff0000, v12
	v_mul_lo_u32 v153, v129, s50
	v_or_b32_sdwa v13, v128, v3 dst_sel:DWORD dst_unused:UNUSED_PAD src0_sel:DWORD src1_sel:WORD_1
	v_or_b32_sdwa v12, v21, v20 dst_sel:DWORD dst_unused:UNUSED_PAD src0_sel:WORD_1 src1_sel:DWORD
	v_add_u32_e32 v151, v155, v153
	ds_write_b64 v151, v[12:13]
	v_and_b32_e32 v12, 0xffff0000, v21
	v_sub_u32_e32 v6, v6, v12
	v_sub_u32_e32 v12, v14, v20
	v_and_b32_e32 v3, 0xffff0000, v3
	v_add_u32_e32 v12, 0x80, v12
	v_sub_u32_e32 v3, v15, v3
	v_sub_u32_e32 v7, v7, v128
	v_add_u32_e32 v6, 0x80, v6
	v_ashrrev_i32_e32 v12, 8, v12
	v_add_u32_e32 v3, 0x80, v3
	v_add_u32_e32 v7, 0x80, v7
	v_ashrrev_i32_e32 v6, 8, v6
	v_min_i32_e32 v12, 0x7f, v12
	v_ashrrev_i32_e32 v3, 8, v3
	v_ashrrev_i32_e32 v7, 8, v7
	v_min_i32_e32 v6, 0x7f, v6
	v_min_i32_sdwa v3, v3, s83 dst_sel:WORD_1 dst_unused:UNUSED_PAD src0_sel:DWORD src1_sel:DWORD
	v_min_i32_e32 v7, 0x7f, v7
	v_lshlrev_b32_e32 v12, 8, v12
	v_and_b32_e32 v12, 0xff00, v12
	v_and_b32_e32 v3, 0xff0000, v3
	v_perm_b32 v6, v7, v6, s84
	v_or3_b32 v3, v6, v12, v3
	v_lshrrev_b32_e32 v6, 2, v156
	v_mad_u64_u32 v[12:13], s[22:23], v6, s50, v[2:3]
	ds_write_b32 v12, v3
	v_or_b32_e32 v3, 16, v156
	v_lshl_add_u32 v13, v3, 3, v219
	ds_read_b64 v[6:7], v13
	s_waitcnt lgkmcnt(0)
;     ...
;             _Pragma("unroll") for (int m = 0; m < 4; ++m) {
;               const int rr = wr3 * 64 + m * 16 + fr3;
;               const float2 ms = *reinterpret_cast<const float2*>(mr + (ai * HALF + rr) * 2);
;               f32x4 y = acc[ai][bj][m][n];
;               const float o0 = (y[0] - ms.x) * ms.y * gm.x + bt.x, o1 = (y[1] - ms.x) * ms.y * gm.y + bt.y;
;               const float o2 = (y[2] - ms.x) * ms.y * gm.z + bt.z, o3 = (y[3] - ms.x) * ms.y * gm.w + bt.w;
;               const unsigned h0 = f2bf(o0), h1 = f2bf(o1), h2 = f2bf(o2), h3 = f2bf(o3);
;               u32x2 ob; ob[0] = h0 | (h1 << 16); ob[1] = h2 | (h3 << 16);
;               *reinterpret_cast<u32x2*>(smem + (rr >> 1) * PIECE + (rr & 1) * 512 + cc * 2) = ob;
;               const int l0 = min(((int)__float_as_uint(o0) - (int)(h0 << 16) + 128) >> 8, 127);
;               const int l1 = min(((int)__float_as_uint(o1) - (int)(h1 << 16) + 128) >> 8, 127);
;               const int l2 = min(((int)__float_as_uint(o2) - (int)(h2 << 16) + 128) >> 8, 127);
;               const int l3 = min(((int)__float_as_uint(o3) - (int)(h3 << 16) + 128) >> 8, 127);
;               *reinterpret_cast<unsigned*>(smem + LOBASE + (rr >> 2) * PIECE + (rr & 3) * 256 + cc) =
;                   (unsigned)(l0 & 255) | ((unsigned)(l1 & 255) << 8) | ((unsigned)(l2 & 255) << 16) | ((unsigned)l3 << 24);
;             }
	v_pk_add_f32 v[14:15], v[134:135], v[6:7] op_sel_hi:[1,0] neg_lo:[0,1] neg_hi:[0,1]
	s_nop 0
	v_pk_mul_f32 v[14:15], v[6:7], v[14:15] op_sel:[1,0]
	v_pk_add_f32 v[20:21], v[132:133], v[6:7] op_sel_hi:[1,0] neg_lo:[0,1] neg_hi:[0,1]
	v_pk_fma_f32 v[14:15], v[22:23], v[14:15], v[144:145]
	v_pk_mul_f32 v[6:7], v[6:7], v[20:21] op_sel:[1,0]
	v_and_b32_sdwa v20, v15, v216 dst_sel:DWORD dst_unused:UNUSED_PAD src0_sel:WORD_1 src1_sel:DWORD
	v_and_b32_sdwa v21, v14, v216 dst_sel:DWORD dst_unused:UNUSED_PAD src0_sel:WORD_1 src1_sel:DWORD
	v_pk_fma_f32 v[6:7], v[0:1], v[6:7], v[4:5]
	v_add3_u32 v128, v15, v20, s82
	v_add3_u32 v20, v14, v21, s82
	v_and_b32_e32 v129, 0xffff0000, v20
	v_and_b32_sdwa v20, v7, v216 dst_sel:DWORD dst_unused:UNUSED_PAD src0_sel:WORD_1 src1_sel:DWORD
	v_and_b32_sdwa v21, v6, v216 dst_sel:DWORD dst_unused:UNUSED_PAD src0_sel:WORD_1 src1_sel:DWORD
	v_add3_u32 v20, v7, v20, s82
	v_lshrrev_b32_e32 v132, 1, v3
	v_add3_u32 v130, v6, v21, s82
	v_and_b32_e32 v131, 0xffff0000, v20
	v_mul_lo_u32 v154, v132, s50
	v_or_b32_sdwa v21, v131, v128 dst_sel:DWORD dst_unused:UNUSED_PAD src0_sel:DWORD src1_sel:WORD_1
	v_or_b32_sdwa v20, v130, v129 dst_sel:DWORD dst_unused:UNUSED_PAD src0_sel:WORD_1 src1_sel:DWORD
	v_add_u32_e32 v132, v155, v154
	ds_write_b64 v132, v[20:21]
	v_and_b32_e32 v20, 0xffff0000, v130
	v_sub_u32_e32 v6, v6, v20
	v_sub_u32_e32 v14, v14, v129
	v_and_b32_e32 v20, 0xffff0000, v128
	v_add_u32_e32 v14, 0x80, v14
	v_sub_u32_e32 v15, v15, v20
	v_sub_u32_e32 v7, v7, v131
	v_add_u32_e32 v6, 0x80, v6
	v_ashrrev_i32_e32 v14, 8, v14
	v_add_u32_e32 v15, 0x80, v15
	v_add_u32_e32 v7, 0x80, v7
	v_ashrrev_i32_e32 v6, 8, v6
	v_min_i32_e32 v14, 0x7f, v14
	v_ashrrev_i32_e32 v15, 8, v15
	v_ashrrev_i32_e32 v7, 8, v7
	v_min_i32_e32 v6, 0x7f, v6
	v_min_i32_sdwa v15, v15, s83 dst_sel:WORD_1 dst_unused:UNUSED_PAD src0_sel:DWORD src1_sel:DWORD
	v_min_i32_e32 v7, 0x7f, v7
	v_lshlrev_b32_e32 v14, 8, v14
	v_and_b32_e32 v14, 0xff00, v14
	v_and_b32_e32 v15, 0xff0000, v15
	v_perm_b32 v6, v7, v6, s84
	v_lshrrev_b32_e32 v3, 2, v3
	v_or3_b32 v6, v6, v14, v15
	v_mad_u64_u32 v[14:15], s[22:23], v3, s50, v[2:3]
	v_or_b32_e32 v3, 32, v156
	ds_write_b32 v14, v6
	v_lshl_add_u32 v15, v3, 3, v219
	ds_read_b64 v[6:7], v15
	v_lshrrev_b32_e32 v133, 1, v3
	v_lshrrev_b32_e32 v3, 2, v3
	s_waitcnt lgkmcnt(0)
	v_pk_add_f32 v[20:21], v[138:139], v[6:7] op_sel_hi:[1,0] neg_lo:[0,1] neg_hi:[0,1]
	s_nop 0
	v_pk_mul_f32 v[20:21], v[6:7], v[20:21] op_sel:[1,0]
	v_pk_add_f32 v[128:129], v[136:137], v[6:7] op_sel_hi:[1,0] neg_lo:[0,1] neg_hi:[0,1]
	v_pk_fma_f32 v[20:21], v[22:23], v[20:21], v[144:145]
	v_pk_mul_f32 v[6:7], v[6:7], v[128:129] op_sel:[1,0]
	v_and_b32_sdwa v128, v21, v216 dst_sel:DWORD dst_unused:UNUSED_PAD src0_sel:WORD_1 src1_sel:DWORD
	v_and_b32_sdwa v129, v20, v216 dst_sel:DWORD dst_unused:UNUSED_PAD src0_sel:WORD_1 src1_sel:DWORD
	v_pk_fma_f32 v[6:7], v[0:1], v[6:7], v[4:5]
	v_add3_u32 v130, v21, v128, s82
	v_add3_u32 v128, v20, v129, s82
	v_and_b32_e32 v131, 0xffff0000, v128
	v_and_b32_sdwa v128, v7, v216 dst_sel:DWORD dst_unused:UNUSED_PAD src0_sel:WORD_1 src1_sel:DWORD
	v_and_b32_sdwa v129, v6, v216 dst_sel:DWORD dst_unused:UNUSED_PAD src0_sel:WORD_1 src1_sel:DWORD
	v_add3_u32 v128, v7, v128, s82
	v_add3_u32 v134, v6, v129, s82
	v_and_b32_e32 v135, 0xffff0000, v128
	v_mul_lo_u32 v136, v133, s50
	v_or_b32_sdwa v129, v135, v130 dst_sel:DWORD dst_unused:UNUSED_PAD src0_sel:DWORD src1_sel:WORD_1
	v_or_b32_sdwa v128, v134, v131 dst_sel:DWORD dst_unused:UNUSED_PAD src0_sel:WORD_1 src1_sel:DWORD
	v_add_u32_e32 v133, v155, v136
	ds_write_b64 v133, v[128:129]
	v_and_b32_e32 v128, 0xffff0000, v134
	v_sub_u32_e32 v6, v6, v128
	v_sub_u32_e32 v20, v20, v131
	v_and_b32_e32 v128, 0xffff0000, v130
	v_add_u32_e32 v20, 0x80, v20
	v_sub_u32_e32 v21, v21, v128
	v_sub_u32_e32 v7, v7, v135
	v_add_u32_e32 v6, 0x80, v6
	v_ashrrev_i32_e32 v20, 8, v20
	v_add_u32_e32 v21, 0x80, v21
	v_add_u32_e32 v7, 0x80, v7
	v_ashrrev_i32_e32 v6, 8, v6
	v_min_i32_e32 v20, 0x7f, v20
	v_ashrrev_i32_e32 v21, 8, v21
	v_ashrrev_i32_e32 v7, 8, v7
	v_min_i32_e32 v6, 0x7f, v6
	v_min_i32_sdwa v21, v21, s83 dst_sel:WORD_1 dst_unused:UNUSED_PAD src0_sel:DWORD src1_sel:DWORD
	v_min_i32_e32 v7, 0x7f, v7
	v_lshlrev_b32_e32 v20, 8, v20
	v_and_b32_e32 v20, 0xff00, v20
	v_and_b32_e32 v21, 0xff0000, v21
	v_perm_b32 v6, v7, v6, s84
	v_or3_b32 v6, v6, v20, v21
	v_mad_u64_u32 v[20:21], s[22:23], v3, s50, v[2:3]
	v_or_b32_e32 v3, 48, v156
	ds_write_b32 v20, v6
	v_lshl_add_u32 v21, v3, 3, v219
	ds_read_b64 v[6:7], v21
	v_lshrrev_b32_e32 v130, 1, v3
	v_mul_lo_u32 v135, v130, s50
	v_add_u32_e32 v134, v155, v135
	s_waitcnt lgkmcnt(0)
;     ...
;           _Pragma("unroll") for (int bj = 0; bj < 2; ++bj) _Pragma("unroll") for (int n = 0; n < 2; ++n) {
;             const int cc = bj * HALF + wc3 * 32 + n * 16 + fq3 * 4;
;             const float4 gm = *reinterpret_cast<const float4*>(g.gam + pn * BM + cc), bt = *reinterpret_cast<const float4*>(g.bet + pn * BM + cc);
;             _Pragma("unroll") for (int m = 0; m < 4; ++m) {
;               const int rr = wr3 * 64 + m * 16 + fr3;
;               const float2 ms = *reinterpret_cast<const float2*>(mr + (ai * HALF + rr) * 2);
;               f32x4 y = acc[ai][bj][m][n];
;               const float o0 = (y[0] - ms.x) * ms.y * gm.x + bt.x, o1 = (y[1] - ms.x) * ms.y * gm.y + bt.y;
;               const float o2 = (y[2] - ms.x) * ms.y * gm.z + bt.z, o3 = (y[3] - ms.x) * ms.y * gm.w + bt.w;
;               const unsigned h0 = f2bf(o0), h1 = f2bf(o1), h2 = f2bf(o2), h3 = f2bf(o3);
;               u32x2 ob; ob[0] = h0 | (h1 << 16); ob[1] = h2 | (h3 << 16);
;               *reinterpret_cast<u32x2*>(smem + (rr >> 1) * PIECE + (rr & 1) * 512 + cc * 2) = ob;
;               const int l0 = min(((int)__float_as_uint(o0) - (int)(h0 << 16) + 128) >> 8, 127);
;               const int l1 = min(((int)__float_as_uint(o1) - (int)(h1 << 16) + 128) >> 8, 127);
;               const int l2 = min(((int)__float_as_uint(o2) - (int)(h2 << 16) + 128) >> 8, 127);
;               const int l3 = min(((int)__float_as_uint(o3) - (int)(h3 << 16) + 128) >> 8, 127);
;               *reinterpret_cast<unsigned*>(smem + LOBASE + (rr >> 2) * PIECE + (rr & 3) * 256 + cc) =
;                   (unsigned)(l0 & 255) | ((unsigned)(l1 & 255) << 8) | ((unsigned)(l2 & 255) << 16) | ((unsigned)l3 << 24);
;             }
	v_pk_add_f32 v[128:129], v[142:143], v[6:7] op_sel_hi:[1,0] neg_lo:[0,1] neg_hi:[0,1]
	s_nop 0
	v_pk_mul_f32 v[128:129], v[6:7], v[128:129] op_sel:[1,0]
	s_nop 0
	v_pk_fma_f32 v[22:23], v[22:23], v[128:129], v[144:145]
	v_pk_add_f32 v[128:129], v[140:141], v[6:7] op_sel_hi:[1,0] neg_lo:[0,1] neg_hi:[0,1]
	s_nop 0
	v_pk_mul_f32 v[6:7], v[6:7], v[128:129] op_sel:[1,0]
	s_nop 0
	v_pk_fma_f32 v[0:1], v[0:1], v[6:7], v[4:5]
	v_and_b32_sdwa v4, v23, v216 dst_sel:DWORD dst_unused:UNUSED_PAD src0_sel:WORD_1 src1_sel:DWORD
	v_and_b32_sdwa v5, v22, v216 dst_sel:DWORD dst_unused:UNUSED_PAD src0_sel:WORD_1 src1_sel:DWORD
	v_add3_u32 v6, v23, v4, s82
	v_add3_u32 v4, v22, v5, s82
	v_and_b32_e32 v7, 0xffff0000, v4
	v_and_b32_sdwa v4, v1, v216 dst_sel:DWORD dst_unused:UNUSED_PAD src0_sel:WORD_1 src1_sel:DWORD
	v_and_b32_sdwa v5, v0, v216 dst_sel:DWORD dst_unused:UNUSED_PAD src0_sel:WORD_1 src1_sel:DWORD
	v_add3_u32 v4, v1, v4, s82
	v_add3_u32 v128, v0, v5, s82
	v_and_b32_e32 v129, 0xffff0000, v4
	v_or_b32_sdwa v5, v129, v6 dst_sel:DWORD dst_unused:UNUSED_PAD src0_sel:DWORD src1_sel:WORD_1
	v_or_b32_sdwa v4, v128, v7 dst_sel:DWORD dst_unused:UNUSED_PAD src0_sel:WORD_1 src1_sel:DWORD
	ds_write_b64 v134, v[4:5]
	v_and_b32_e32 v4, 0xffff0000, v128
	v_sub_u32_e32 v0, v0, v4
	v_sub_u32_e32 v4, v22, v7
	v_and_b32_e32 v5, 0xffff0000, v6
	v_add_u32_e32 v4, 0x80, v4
	v_sub_u32_e32 v5, v23, v5
	v_sub_u32_e32 v1, v1, v129
	v_add_u32_e32 v0, 0x80, v0
	v_ashrrev_i32_e32 v4, 8, v4
	v_add_u32_e32 v5, 0x80, v5
	v_add_u32_e32 v1, 0x80, v1
	v_ashrrev_i32_e32 v0, 8, v0
	v_min_i32_e32 v4, 0x7f, v4
	v_ashrrev_i32_e32 v5, 8, v5
	v_ashrrev_i32_e32 v1, 8, v1
	v_min_i32_e32 v0, 0x7f, v0
	v_min_i32_sdwa v5, v5, s83 dst_sel:WORD_1 dst_unused:UNUSED_PAD src0_sel:DWORD src1_sel:DWORD
	v_min_i32_e32 v1, 0x7f, v1
	v_lshlrev_b32_e32 v4, 8, v4
	v_and_b32_e32 v4, 0xff00, v4
	v_and_b32_e32 v5, 0xff0000, v5
	v_perm_b32 v0, v1, v0, s84
	v_lshrrev_b32_e32 v1, 2, v3
	v_or3_b32 v0, v0, v4, v5
	v_mad_u64_u32 v[22:23], s[22:23], v1, s50, v[2:3]
	ds_write_b32 v22, v0
	v_mov_b32_e32 v0, v224
	v_mov_b32_e32 v1, v225
	v_mov_b32_e32 v2, v226
	v_mov_b32_e32 v3, v227
	v_mov_b32_e32 v4, v240
	v_mov_b32_e32 v5, v241
	v_mov_b32_e32 v6, v242
	v_mov_b32_e32 v7, v243
	ds_read_b64 v[138:139], v149
	s_mov_b32 s22, s18
	s_mov_b32 s23, s19
	s_waitcnt lgkmcnt(0)
	v_pk_add_f32 v[124:125], v[124:125], v[138:139] op_sel_hi:[1,0] neg_lo:[0,1] neg_hi:[0,1]
	s_nop 0
	v_pk_mul_f32 v[124:125], v[138:139], v[124:125] op_sel:[1,0]
	v_pk_add_f32 v[126:127], v[126:127], v[138:139] op_sel_hi:[1,0] neg_lo:[0,1] neg_hi:[0,1]
	v_mov_b32_e32 v128, v1
	v_mov_b32_e32 v129, v2
	v_mov_b32_e32 v130, v5
	v_mov_b32_e32 v131, v6
	v_pk_fma_f32 v[124:125], v[128:129], v[124:125], v[130:131]
	v_pk_mul_f32 v[126:127], v[138:139], v[126:127] op_sel:[1,0]
	v_mov_b32_e32 v1, v3
	v_mov_b32_e32 v5, v7
	v_and_b32_sdwa v23, v124, v216 dst_sel:DWORD dst_unused:UNUSED_PAD src0_sel:WORD_1 src1_sel:DWORD
	v_pk_fma_f32 v[6:7], v[0:1], v[126:127], v[4:5]
	v_add3_u32 v23, v124, v23, s82
	v_and_b32_e32 v137, 0xffff0000, v23
	v_and_b32_sdwa v23, v7, v216 dst_sel:DWORD dst_unused:UNUSED_PAD src0_sel:WORD_1 src1_sel:DWORD
	v_and_b32_sdwa v3, v125, v216 dst_sel:DWORD dst_unused:UNUSED_PAD src0_sel:WORD_1 src1_sel:DWORD
	v_and_b32_sdwa v126, v6, v216 dst_sel:DWORD dst_unused:UNUSED_PAD src0_sel:WORD_1 src1_sel:DWORD
	v_add3_u32 v23, v7, v23, s82
	v_or_b32_e32 v2, 32, v155
	v_add3_u32 v3, v125, v3, s82
	v_add3_u32 v138, v6, v126, s82
	v_and_b32_e32 v139, 0xffff0000, v23
	v_or_b32_sdwa v127, v139, v3 dst_sel:DWORD dst_unused:UNUSED_PAD src0_sel:DWORD src1_sel:WORD_1
	v_or_b32_sdwa v126, v138, v137 dst_sel:DWORD dst_unused:UNUSED_PAD src0_sel:WORD_1 src1_sel:DWORD
	v_add_u32_e32 v23, v2, v153
	ds_write_b64 v23, v[126:127]
	v_and_b32_e32 v126, 0xffff0000, v138
	v_sub_u32_e32 v124, v124, v137
	v_and_b32_e32 v3, 0xffff0000, v3
	v_sub_u32_e32 v6, v6, v126
	v_add_u32_e32 v124, 0x80, v124
	v_sub_u32_e32 v3, v125, v3
	v_sub_u32_e32 v7, v7, v139
	v_add_u32_e32 v6, 0x80, v6
	v_ashrrev_i32_e32 v124, 8, v124
	v_add_u32_e32 v3, 0x80, v3
	v_add_u32_e32 v7, 0x80, v7
	v_ashrrev_i32_e32 v6, 8, v6
	v_min_i32_e32 v124, 0x7f, v124
	v_ashrrev_i32_e32 v3, 8, v3
	v_ashrrev_i32_e32 v7, 8, v7
	v_min_i32_e32 v6, 0x7f, v6
	v_min_i32_sdwa v3, v3, s83 dst_sel:WORD_1 dst_unused:UNUSED_PAD src0_sel:DWORD src1_sel:DWORD
	v_min_i32_e32 v7, 0x7f, v7
	v_lshlrev_b32_e32 v124, 8, v124
	v_and_b32_e32 v124, 0xff00, v124
	v_and_b32_e32 v3, 0xff0000, v3
	v_perm_b32 v6, v7, v6, s84
	v_or3_b32 v3, v6, v124, v3
	ds_write_b32 v12, v3 offset:16
	ds_read_b64 v[6:7], v13
	s_waitcnt lgkmcnt(0)
;     ...
;           _Pragma("unroll") for (int bj = 0; bj < 2; ++bj) _Pragma("unroll") for (int n = 0; n < 2; ++n) {
;             const int cc = bj * HALF + wc3 * 32 + n * 16 + fq3 * 4;
;             const float4 gm = *reinterpret_cast<const float4*>(g.gam + pn * BM + cc), bt = *reinterpret_cast<const float4*>(g.bet + pn * BM + cc);
;             _Pragma("unroll") for (int m = 0; m < 4; ++m) {
;               const int rr = wr3 * 64 + m * 16 + fr3;
;               const float2 ms = *reinterpret_cast<const float2*>(mr + (ai * HALF + rr) * 2);
;               f32x4 y = acc[ai][bj][m][n];
;               const float o0 = (y[0] - ms.x) * ms.y * gm.x + bt.x, o1 = (y[1] - ms.x) * ms.y * gm.y + bt.y;
;               const float o2 = (y[2] - ms.x) * ms.y * gm.z + bt.z, o3 = (y[3] - ms.x) * ms.y * gm.w + bt.w;
;               const unsigned h0 = f2bf(o0), h1 = f2bf(o1), h2 = f2bf(o2), h3 = f2bf(o3);
;               u32x2 ob; ob[0] = h0 | (h1 << 16); ob[1] = h2 | (h3 << 16);
;               *reinterpret_cast<u32x2*>(smem + (rr >> 1) * PIECE + (rr & 1) * 512 + cc * 2) = ob;
;               const int l0 = min(((int)__float_as_uint(o0) - (int)(h0 << 16) + 128) >> 8, 127);
;               const int l1 = min(((int)__float_as_uint(o1) - (int)(h1 << 16) + 128) >> 8, 127);
;               const int l2 = min(((int)__float_as_uint(o2) - (int)(h2 << 16) + 128) >> 8, 127);
;               const int l3 = min(((int)__float_as_uint(o3) - (int)(h3 << 16) + 128) >> 8, 127);
;               *reinterpret_cast<unsigned*>(smem + LOBASE + (rr >> 2) * PIECE + (rr & 3) * 256 + cc) =
;                   (unsigned)(l0 & 255) | ((unsigned)(l1 & 255) << 8) | ((unsigned)(l2 & 255) << 16) | ((unsigned)l3 << 24);
;             }
	v_pk_add_f32 v[106:107], v[106:107], v[6:7] op_sel_hi:[1,0] neg_lo:[0,1] neg_hi:[0,1]
	s_nop 0
	v_pk_mul_f32 v[106:107], v[6:7], v[106:107] op_sel:[1,0]
	v_pk_add_f32 v[104:105], v[104:105], v[6:7] op_sel_hi:[1,0] neg_lo:[0,1] neg_hi:[0,1]
	v_pk_fma_f32 v[106:107], v[128:129], v[106:107], v[130:131]
	v_pk_mul_f32 v[6:7], v[6:7], v[104:105] op_sel:[1,0]
	v_and_b32_sdwa v104, v106, v216 dst_sel:DWORD dst_unused:UNUSED_PAD src0_sel:WORD_1 src1_sel:DWORD
	v_pk_fma_f32 v[6:7], v[0:1], v[6:7], v[4:5]
	v_add3_u32 v104, v106, v104, s82
	v_and_b32_e32 v105, 0xffff0000, v104
	v_and_b32_sdwa v104, v7, v216 dst_sel:DWORD dst_unused:UNUSED_PAD src0_sel:WORD_1 src1_sel:DWORD
	v_and_b32_sdwa v3, v107, v216 dst_sel:DWORD dst_unused:UNUSED_PAD src0_sel:WORD_1 src1_sel:DWORD
	v_and_b32_sdwa v124, v6, v216 dst_sel:DWORD dst_unused:UNUSED_PAD src0_sel:WORD_1 src1_sel:DWORD
	v_add3_u32 v104, v7, v104, s82
	v_add3_u32 v3, v107, v3, s82
	v_add3_u32 v126, v6, v124, s82
	v_and_b32_e32 v127, 0xffff0000, v104
	v_or_b32_sdwa v125, v127, v3 dst_sel:DWORD dst_unused:UNUSED_PAD src0_sel:DWORD src1_sel:WORD_1
	v_or_b32_sdwa v124, v126, v105 dst_sel:DWORD dst_unused:UNUSED_PAD src0_sel:WORD_1 src1_sel:DWORD
	v_add_u32_e32 v104, v2, v154
	ds_write_b64 v104, v[124:125]
	v_and_b32_e32 v124, 0xffff0000, v126
	v_sub_u32_e32 v105, v106, v105
	v_and_b32_e32 v3, 0xffff0000, v3
	v_sub_u32_e32 v6, v6, v124
	v_add_u32_e32 v105, 0x80, v105
	v_sub_u32_e32 v3, v107, v3
	v_sub_u32_e32 v7, v7, v127
	v_add_u32_e32 v6, 0x80, v6
	v_ashrrev_i32_e32 v105, 8, v105
	v_add_u32_e32 v3, 0x80, v3
	v_add_u32_e32 v7, 0x80, v7
	v_ashrrev_i32_e32 v6, 8, v6
	v_min_i32_e32 v105, 0x7f, v105
	v_ashrrev_i32_e32 v3, 8, v3
	v_ashrrev_i32_e32 v7, 8, v7
	v_min_i32_e32 v6, 0x7f, v6
	v_min_i32_sdwa v3, v3, s83 dst_sel:WORD_1 dst_unused:UNUSED_PAD src0_sel:DWORD src1_sel:DWORD
	v_min_i32_e32 v7, 0x7f, v7
	v_lshlrev_b32_e32 v105, 8, v105
	v_and_b32_e32 v105, 0xff00, v105
	v_and_b32_e32 v3, 0xff0000, v3
	v_perm_b32 v6, v7, v6, s84
	v_or3_b32 v3, v6, v105, v3
	ds_write_b32 v14, v3 offset:16
	ds_read_b64 v[6:7], v15
	s_waitcnt lgkmcnt(0)
	v_pk_add_f32 v[106:107], v[110:111], v[6:7] op_sel_hi:[1,0] neg_lo:[0,1] neg_hi:[0,1]
	s_nop 0
	v_pk_mul_f32 v[106:107], v[6:7], v[106:107] op_sel:[1,0]
	v_pk_add_f32 v[108:109], v[108:109], v[6:7] op_sel_hi:[1,0] neg_lo:[0,1] neg_hi:[0,1]
	v_pk_fma_f32 v[106:107], v[128:129], v[106:107], v[130:131]
	v_pk_mul_f32 v[6:7], v[6:7], v[108:109] op_sel:[1,0]
	v_and_b32_sdwa v105, v106, v216 dst_sel:DWORD dst_unused:UNUSED_PAD src0_sel:WORD_1 src1_sel:DWORD
	v_pk_fma_f32 v[6:7], v[0:1], v[6:7], v[4:5]
	v_add3_u32 v105, v106, v105, s82
	v_and_b32_e32 v110, 0xffff0000, v105
	v_and_b32_sdwa v105, v7, v216 dst_sel:DWORD dst_unused:UNUSED_PAD src0_sel:WORD_1 src1_sel:DWORD
	v_and_b32_sdwa v3, v107, v216 dst_sel:DWORD dst_unused:UNUSED_PAD src0_sel:WORD_1 src1_sel:DWORD
	v_and_b32_sdwa v108, v6, v216 dst_sel:DWORD dst_unused:UNUSED_PAD src0_sel:WORD_1 src1_sel:DWORD
	v_add3_u32 v105, v7, v105, s82
	v_add3_u32 v3, v107, v3, s82
	v_add3_u32 v111, v6, v108, s82
	v_and_b32_e32 v124, 0xffff0000, v105
	v_or_b32_sdwa v109, v124, v3 dst_sel:DWORD dst_unused:UNUSED_PAD src0_sel:DWORD src1_sel:WORD_1
	v_or_b32_sdwa v108, v111, v110 dst_sel:DWORD dst_unused:UNUSED_PAD src0_sel:WORD_1 src1_sel:DWORD
	v_add_u32_e32 v105, v2, v136
	ds_write_b64 v105, v[108:109]
	v_and_b32_e32 v108, 0xffff0000, v111
	v_sub_u32_e32 v106, v106, v110
	v_and_b32_e32 v3, 0xffff0000, v3
	v_sub_u32_e32 v6, v6, v108
	v_add_u32_e32 v106, 0x80, v106
	v_sub_u32_e32 v3, v107, v3
	v_sub_u32_e32 v7, v7, v124
	v_add_u32_e32 v6, 0x80, v6
	v_ashrrev_i32_e32 v106, 8, v106
	v_add_u32_e32 v3, 0x80, v3
	v_add_u32_e32 v7, 0x80, v7
	v_ashrrev_i32_e32 v6, 8, v6
	v_min_i32_e32 v106, 0x7f, v106
	v_ashrrev_i32_e32 v3, 8, v3
	v_ashrrev_i32_e32 v7, 8, v7
	v_min_i32_e32 v6, 0x7f, v6
	v_min_i32_sdwa v3, v3, s83 dst_sel:WORD_1 dst_unused:UNUSED_PAD src0_sel:DWORD src1_sel:DWORD
	v_min_i32_e32 v7, 0x7f, v7
	v_lshlrev_b32_e32 v106, 8, v106
	v_and_b32_e32 v106, 0xff00, v106
	v_and_b32_e32 v3, 0xff0000, v3
	v_perm_b32 v6, v7, v6, s84
	v_or3_b32 v3, v6, v106, v3
	ds_write_b32 v20, v3 offset:16
	ds_read_b64 v[6:7], v21
	s_waitcnt lgkmcnt(0)
	v_pk_add_f32 v[106:107], v[122:123], v[6:7] op_sel_hi:[1,0] neg_lo:[0,1] neg_hi:[0,1]
	s_nop 0
	v_pk_mul_f32 v[106:107], v[6:7], v[106:107] op_sel:[1,0]
	v_or_b32_e32 v122, 0x100, v155
	v_pk_fma_f32 v[108:109], v[128:129], v[106:107], v[130:131]
	v_pk_add_f32 v[106:107], v[114:115], v[6:7] op_sel_hi:[1,0] neg_lo:[0,1] neg_hi:[0,1]
	v_and_b32_sdwa v3, v109, v216 dst_sel:DWORD dst_unused:UNUSED_PAD src0_sel:WORD_1 src1_sel:DWORD
	v_pk_mul_f32 v[6:7], v[6:7], v[106:107] op_sel:[1,0]
	v_add3_u32 v3, v109, v3, s82
	v_pk_fma_f32 v[0:1], v[0:1], v[6:7], v[4:5]
	v_and_b32_sdwa v4, v108, v216 dst_sel:DWORD dst_unused:UNUSED_PAD src0_sel:WORD_1 src1_sel:DWORD
	v_add3_u32 v4, v108, v4, s82
	v_and_b32_e32 v6, 0xffff0000, v4
	v_and_b32_sdwa v4, v1, v216 dst_sel:DWORD dst_unused:UNUSED_PAD src0_sel:WORD_1 src1_sel:DWORD
	v_and_b32_sdwa v5, v0, v216 dst_sel:DWORD dst_unused:UNUSED_PAD src0_sel:WORD_1 src1_sel:DWORD
	v_add3_u32 v4, v1, v4, s82
	v_add3_u32 v7, v0, v5, s82
	v_and_b32_e32 v107, 0xffff0000, v4
	v_add_u32_e32 v106, v2, v135
	v_and_b32_e32 v2, 0xffff0000, v7
	v_or_b32_sdwa v5, v107, v3 dst_sel:DWORD dst_unused:UNUSED_PAD src0_sel:DWORD src1_sel:WORD_1
	v_sub_u32_e32 v0, v0, v2
	v_sub_u32_e32 v2, v108, v6
	v_and_b32_e32 v3, 0xffff0000, v3
	v_add_u32_e32 v2, 0x80, v2
	v_sub_u32_e32 v3, v109, v3
	v_sub_u32_e32 v1, v1, v107
	v_add_u32_e32 v0, 0x80, v0
	v_ashrrev_i32_e32 v2, 8, v2
	v_add_u32_e32 v3, 0x80, v3
	v_add_u32_e32 v1, 0x80, v1
	v_ashrrev_i32_e32 v0, 8, v0
	v_min_i32_e32 v2, 0x7f, v2
	v_ashrrev_i32_e32 v3, 8, v3
	v_ashrrev_i32_e32 v1, 8, v1
	v_min_i32_e32 v0, 0x7f, v0
	v_min_i32_sdwa v3, v3, s83 dst_sel:WORD_1 dst_unused:UNUSED_PAD src0_sel:DWORD src1_sel:DWORD
	v_min_i32_e32 v1, 0x7f, v1
	v_lshlrev_b32_e32 v2, 8, v2
	v_and_b32_e32 v2, 0xff00, v2
	v_and_b32_e32 v3, 0xff0000, v3
	v_perm_b32 v0, v1, v0, s84
	v_or_b32_sdwa v4, v7, v6 dst_sel:DWORD dst_unused:UNUSED_PAD src0_sel:WORD_1 src1_sel:DWORD
	v_or3_b32 v0, v0, v2, v3
	ds_write_b64 v106, v[4:5]
	ds_write_b32 v22, v0 offset:16
	v_mov_b32_e32 v0, v228
	v_mov_b32_e32 v1, v229
	v_mov_b32_e32 v2, v230
	v_mov_b32_e32 v3, v231
	v_mov_b32_e32 v4, v244
	v_mov_b32_e32 v5, v245
	v_mov_b32_e32 v6, v246
	v_mov_b32_e32 v7, v247
	ds_read_b64 v[114:115], v149
	v_add_u32_e32 v107, v122, v153
	s_waitcnt lgkmcnt(0)
;     ...
;             _Pragma("unroll") for (int m = 0; m < 4; ++m) {
;               const int rr = wr3 * 64 + m * 16 + fr3;
;               const float2 ms = *reinterpret_cast<const float2*>(mr + (ai * HALF + rr) * 2);
;               f32x4 y = acc[ai][bj][m][n];
;               const float o0 = (y[0] - ms.x) * ms.y * gm.x + bt.x, o1 = (y[1] - ms.x) * ms.y * gm.y + bt.y;
;               const float o2 = (y[2] - ms.x) * ms.y * gm.z + bt.z, o3 = (y[3] - ms.x) * ms.y * gm.w + bt.w;
;               const unsigned h0 = f2bf(o0), h1 = f2bf(o1), h2 = f2bf(o2), h3 = f2bf(o3);
;               u32x2 ob; ob[0] = h0 | (h1 << 16); ob[1] = h2 | (h3 << 16);
;               *reinterpret_cast<u32x2*>(smem + (rr >> 1) * PIECE + (rr & 1) * 512 + cc * 2) = ob;
;               const int l0 = min(((int)__float_as_uint(o0) - (int)(h0 << 16) + 128) >> 8, 127);
;               const int l1 = min(((int)__float_as_uint(o1) - (int)(h1 << 16) + 128) >> 8, 127);
;               const int l2 = min(((int)__float_as_uint(o2) - (int)(h2 << 16) + 128) >> 8, 127);
;               const int l3 = min(((int)__float_as_uint(o3) - (int)(h3 << 16) + 128) >> 8, 127);
;               *reinterpret_cast<unsigned*>(smem + LOBASE + (rr >> 2) * PIECE + (rr & 3) * 256 + cc) =
;                   (unsigned)(l0 & 255) | ((unsigned)(l1 & 255) << 8) | ((unsigned)(l2 & 255) << 16) | ((unsigned)l3 << 24);
;             }
	v_pk_add_f32 v[118:119], v[118:119], v[114:115] op_sel_hi:[1,0] neg_lo:[0,1] neg_hi:[0,1]
	s_nop 0
	v_pk_mul_f32 v[118:119], v[114:115], v[118:119] op_sel:[1,0]
	v_pk_add_f32 v[120:121], v[120:121], v[114:115] op_sel_hi:[1,0] neg_lo:[0,1] neg_hi:[0,1]
	v_mov_b32_e32 v108, v1
	v_mov_b32_e32 v109, v2
	v_mov_b32_e32 v110, v5
	v_mov_b32_e32 v111, v6
	v_pk_fma_f32 v[118:119], v[108:109], v[118:119], v[110:111]
	v_pk_mul_f32 v[114:115], v[114:115], v[120:121] op_sel:[1,0]
	v_mov_b32_e32 v1, v3
	v_mov_b32_e32 v5, v7
	v_and_b32_sdwa v6, v119, v216 dst_sel:DWORD dst_unused:UNUSED_PAD src0_sel:WORD_1 src1_sel:DWORD
	v_and_b32_sdwa v7, v118, v216 dst_sel:DWORD dst_unused:UNUSED_PAD src0_sel:WORD_1 src1_sel:DWORD
	v_pk_fma_f32 v[2:3], v[0:1], v[114:115], v[4:5]
	v_add3_u32 v114, v119, v6, s82
	v_add3_u32 v6, v118, v7, s82
	v_and_b32_e32 v115, 0xffff0000, v6
	v_and_b32_sdwa v6, v3, v216 dst_sel:DWORD dst_unused:UNUSED_PAD src0_sel:WORD_1 src1_sel:DWORD
	v_and_b32_sdwa v7, v2, v216 dst_sel:DWORD dst_unused:UNUSED_PAD src0_sel:WORD_1 src1_sel:DWORD
	v_add3_u32 v6, v3, v6, s82
	v_add3_u32 v120, v2, v7, s82
	v_and_b32_e32 v121, 0xffff0000, v6
	v_or_b32_sdwa v7, v121, v114 dst_sel:DWORD dst_unused:UNUSED_PAD src0_sel:DWORD src1_sel:WORD_1
	v_or_b32_sdwa v6, v120, v115 dst_sel:DWORD dst_unused:UNUSED_PAD src0_sel:WORD_1 src1_sel:DWORD
	ds_write_b64 v107, v[6:7]
	v_and_b32_e32 v6, 0xffff0000, v120
	v_sub_u32_e32 v2, v2, v6
	v_sub_u32_e32 v6, v118, v115
	v_and_b32_e32 v7, 0xffff0000, v114
	v_add_u32_e32 v6, 0x80, v6
	v_sub_u32_e32 v7, v119, v7
	v_sub_u32_e32 v3, v3, v121
	v_add_u32_e32 v2, 0x80, v2
	v_ashrrev_i32_e32 v6, 8, v6
	v_add_u32_e32 v7, 0x80, v7
	v_add_u32_e32 v3, 0x80, v3
	v_ashrrev_i32_e32 v2, 8, v2
	v_min_i32_e32 v6, 0x7f, v6
	v_ashrrev_i32_e32 v7, 8, v7
	v_ashrrev_i32_e32 v3, 8, v3
	v_min_i32_e32 v2, 0x7f, v2
	v_min_i32_sdwa v7, v7, s83 dst_sel:WORD_1 dst_unused:UNUSED_PAD src0_sel:DWORD src1_sel:DWORD
	v_min_i32_e32 v3, 0x7f, v3
	v_lshlrev_b32_e32 v6, 8, v6
	v_and_b32_e32 v6, 0xff00, v6
	v_and_b32_e32 v7, 0xff0000, v7
	v_perm_b32 v2, v3, v2, s84
	v_or3_b32 v2, v2, v6, v7
	ds_write_b32 v12, v2 offset:128
	ds_read_b64 v[2:3], v13
	s_waitcnt lgkmcnt(0)
	v_pk_add_f32 v[6:7], v[102:103], v[2:3] op_sel_hi:[1,0] neg_lo:[0,1] neg_hi:[0,1]
	s_nop 0
	v_pk_mul_f32 v[6:7], v[2:3], v[6:7] op_sel:[1,0]
	v_pk_add_f32 v[100:101], v[100:101], v[2:3] op_sel_hi:[1,0] neg_lo:[0,1] neg_hi:[0,1]
	v_pk_fma_f32 v[6:7], v[108:109], v[6:7], v[110:111]
	v_pk_mul_f32 v[2:3], v[2:3], v[100:101] op_sel:[1,0]
	v_and_b32_sdwa v100, v7, v216 dst_sel:DWORD dst_unused:UNUSED_PAD src0_sel:WORD_1 src1_sel:DWORD
	v_and_b32_sdwa v101, v6, v216 dst_sel:DWORD dst_unused:UNUSED_PAD src0_sel:WORD_1 src1_sel:DWORD
	v_pk_fma_f32 v[2:3], v[0:1], v[2:3], v[4:5]
	v_add3_u32 v114, v7, v100, s82
	v_add3_u32 v100, v6, v101, s82
	v_and_b32_e32 v101, 0xffff0000, v100
	v_and_b32_sdwa v100, v3, v216 dst_sel:DWORD dst_unused:UNUSED_PAD src0_sel:WORD_1 src1_sel:DWORD
	v_and_b32_sdwa v102, v2, v216 dst_sel:DWORD dst_unused:UNUSED_PAD src0_sel:WORD_1 src1_sel:DWORD
	v_add3_u32 v100, v3, v100, s82
	v_add3_u32 v115, v2, v102, s82
	v_and_b32_e32 v118, 0xffff0000, v100
	v_or_b32_sdwa v103, v118, v114 dst_sel:DWORD dst_unused:UNUSED_PAD src0_sel:DWORD src1_sel:WORD_1
	v_or_b32_sdwa v102, v115, v101 dst_sel:DWORD dst_unused:UNUSED_PAD src0_sel:WORD_1 src1_sel:DWORD
	v_add_u32_e32 v100, v122, v154
	ds_write_b64 v100, v[102:103]
	v_and_b32_e32 v102, 0xffff0000, v115
	v_sub_u32_e32 v6, v6, v101
	v_and_b32_e32 v101, 0xffff0000, v114
	v_sub_u32_e32 v2, v2, v102
	v_add_u32_e32 v6, 0x80, v6
	v_sub_u32_e32 v7, v7, v101
	v_sub_u32_e32 v3, v3, v118
	v_add_u32_e32 v2, 0x80, v2
	v_ashrrev_i32_e32 v6, 8, v6
	v_add_u32_e32 v7, 0x80, v7
	v_add_u32_e32 v3, 0x80, v3
	v_ashrrev_i32_e32 v2, 8, v2
	v_min_i32_e32 v6, 0x7f, v6
	v_ashrrev_i32_e32 v7, 8, v7
	v_ashrrev_i32_e32 v3, 8, v3
	v_min_i32_e32 v2, 0x7f, v2
	v_min_i32_sdwa v7, v7, s83 dst_sel:WORD_1 dst_unused:UNUSED_PAD src0_sel:DWORD src1_sel:DWORD
	v_min_i32_e32 v3, 0x7f, v3
	v_lshlrev_b32_e32 v6, 8, v6
	v_and_b32_e32 v6, 0xff00, v6
	v_and_b32_e32 v7, 0xff0000, v7
	v_perm_b32 v2, v3, v2, s84
	v_or3_b32 v2, v2, v6, v7
	ds_write_b32 v14, v2 offset:128
	ds_read_b64 v[2:3], v15
	v_add_u32_e32 v101, v122, v136
	s_waitcnt lgkmcnt(0)
	v_pk_add_f32 v[6:7], v[90:91], v[2:3] op_sel_hi:[1,0] neg_lo:[0,1] neg_hi:[0,1]
	s_nop 0
	v_pk_mul_f32 v[6:7], v[2:3], v[6:7] op_sel:[1,0]
	v_pk_add_f32 v[88:89], v[88:89], v[2:3] op_sel_hi:[1,0] neg_lo:[0,1] neg_hi:[0,1]
	v_pk_fma_f32 v[6:7], v[108:109], v[6:7], v[110:111]
	v_pk_mul_f32 v[2:3], v[2:3], v[88:89] op_sel:[1,0]
	v_and_b32_sdwa v88, v7, v216 dst_sel:DWORD dst_unused:UNUSED_PAD src0_sel:WORD_1 src1_sel:DWORD
	v_and_b32_sdwa v89, v6, v216 dst_sel:DWORD dst_unused:UNUSED_PAD src0_sel:WORD_1 src1_sel:DWORD
	v_pk_fma_f32 v[2:3], v[0:1], v[2:3], v[4:5]
	v_add3_u32 v90, v7, v88, s82
	v_add3_u32 v88, v6, v89, s82
	v_and_b32_e32 v91, 0xffff0000, v88
	v_and_b32_sdwa v88, v3, v216 dst_sel:DWORD dst_unused:UNUSED_PAD src0_sel:WORD_1 src1_sel:DWORD
	v_and_b32_sdwa v89, v2, v216 dst_sel:DWORD dst_unused:UNUSED_PAD src0_sel:WORD_1 src1_sel:DWORD
	v_add3_u32 v88, v3, v88, s82
	v_add3_u32 v102, v2, v89, s82
	v_and_b32_e32 v103, 0xffff0000, v88
	v_or_b32_sdwa v89, v103, v90 dst_sel:DWORD dst_unused:UNUSED_PAD src0_sel:DWORD src1_sel:WORD_1
	v_or_b32_sdwa v88, v102, v91 dst_sel:DWORD dst_unused:UNUSED_PAD src0_sel:WORD_1 src1_sel:DWORD
	ds_write_b64 v101, v[88:89]
	v_and_b32_e32 v88, 0xffff0000, v102
	v_sub_u32_e32 v2, v2, v88
	v_sub_u32_e32 v6, v6, v91
	v_and_b32_e32 v88, 0xffff0000, v90
	v_add_u32_e32 v6, 0x80, v6
	v_sub_u32_e32 v7, v7, v88
	v_sub_u32_e32 v3, v3, v103
	v_add_u32_e32 v2, 0x80, v2
	v_ashrrev_i32_e32 v6, 8, v6
	v_add_u32_e32 v7, 0x80, v7
	v_add_u32_e32 v3, 0x80, v3
	v_ashrrev_i32_e32 v2, 8, v2
	v_min_i32_e32 v6, 0x7f, v6
	v_ashrrev_i32_e32 v7, 8, v7
	v_ashrrev_i32_e32 v3, 8, v3
	v_min_i32_e32 v2, 0x7f, v2
	v_min_i32_sdwa v7, v7, s83 dst_sel:WORD_1 dst_unused:UNUSED_PAD src0_sel:DWORD src1_sel:DWORD
	v_min_i32_e32 v3, 0x7f, v3
	v_lshlrev_b32_e32 v6, 8, v6
	v_and_b32_e32 v6, 0xff00, v6
	v_and_b32_e32 v7, 0xff0000, v7
	v_perm_b32 v2, v3, v2, s84
	v_or3_b32 v2, v2, v6, v7
	ds_write_b32 v20, v2 offset:128
	ds_read_b64 v[2:3], v21
	s_waitcnt lgkmcnt(0)
;     ...
;           _Pragma("unroll") for (int bj = 0; bj < 2; ++bj) _Pragma("unroll") for (int n = 0; n < 2; ++n) {
;             const int cc = bj * HALF + wc3 * 32 + n * 16 + fq3 * 4;
;             const float4 gm = *reinterpret_cast<const float4*>(g.gam + pn * BM + cc), bt = *reinterpret_cast<const float4*>(g.bet + pn * BM + cc);
;             _Pragma("unroll") for (int m = 0; m < 4; ++m) {
;               const int rr = wr3 * 64 + m * 16 + fr3;
;               const float2 ms = *reinterpret_cast<const float2*>(mr + (ai * HALF + rr) * 2);
;               f32x4 y = acc[ai][bj][m][n];
;               const float o0 = (y[0] - ms.x) * ms.y * gm.x + bt.x, o1 = (y[1] - ms.x) * ms.y * gm.y + bt.y;
;               const float o2 = (y[2] - ms.x) * ms.y * gm.z + bt.z, o3 = (y[3] - ms.x) * ms.y * gm.w + bt.w;
;               const unsigned h0 = f2bf(o0), h1 = f2bf(o1), h2 = f2bf(o2), h3 = f2bf(o3);
;               u32x2 ob; ob[0] = h0 | (h1 << 16); ob[1] = h2 | (h3 << 16);
;               *reinterpret_cast<u32x2*>(smem + (rr >> 1) * PIECE + (rr & 1) * 512 + cc * 2) = ob;
;               const int l0 = min(((int)__float_as_uint(o0) - (int)(h0 << 16) + 128) >> 8, 127);
;               const int l1 = min(((int)__float_as_uint(o1) - (int)(h1 << 16) + 128) >> 8, 127);
;               const int l2 = min(((int)__float_as_uint(o2) - (int)(h2 << 16) + 128) >> 8, 127);
;               const int l3 = min(((int)__float_as_uint(o3) - (int)(h3 << 16) + 128) >> 8, 127);
;               *reinterpret_cast<unsigned*>(smem + LOBASE + (rr >> 2) * PIECE + (rr & 3) * 256 + cc) =
;                   (unsigned)(l0 & 255) | ((unsigned)(l1 & 255) << 8) | ((unsigned)(l2 & 255) << 16) | ((unsigned)l3 << 24);
;             }
	v_pk_add_f32 v[6:7], v[94:95], v[2:3] op_sel_hi:[1,0] neg_lo:[0,1] neg_hi:[0,1]
	s_nop 0
	v_pk_mul_f32 v[6:7], v[2:3], v[6:7] op_sel:[1,0]
	v_pk_add_f32 v[88:89], v[92:93], v[2:3] op_sel_hi:[1,0] neg_lo:[0,1] neg_hi:[0,1]
	v_pk_fma_f32 v[6:7], v[108:109], v[6:7], v[110:111]
	v_pk_mul_f32 v[2:3], v[2:3], v[88:89] op_sel:[1,0]
	v_add_u32_e32 v92, v122, v135
	v_pk_fma_f32 v[0:1], v[0:1], v[2:3], v[4:5]
	v_and_b32_sdwa v2, v7, v216 dst_sel:DWORD dst_unused:UNUSED_PAD src0_sel:WORD_1 src1_sel:DWORD
	v_and_b32_sdwa v3, v6, v216 dst_sel:DWORD dst_unused:UNUSED_PAD src0_sel:WORD_1 src1_sel:DWORD
	v_add3_u32 v4, v7, v2, s82
	v_add3_u32 v2, v6, v3, s82
	v_and_b32_e32 v5, 0xffff0000, v2
	v_and_b32_sdwa v2, v1, v216 dst_sel:DWORD dst_unused:UNUSED_PAD src0_sel:WORD_1 src1_sel:DWORD
	v_and_b32_sdwa v3, v0, v216 dst_sel:DWORD dst_unused:UNUSED_PAD src0_sel:WORD_1 src1_sel:DWORD
	v_add3_u32 v2, v1, v2, s82
	v_add3_u32 v88, v0, v3, s82
	v_and_b32_e32 v89, 0xffff0000, v2
	v_or_b32_sdwa v3, v89, v4 dst_sel:DWORD dst_unused:UNUSED_PAD src0_sel:DWORD src1_sel:WORD_1
	v_or_b32_sdwa v2, v88, v5 dst_sel:DWORD dst_unused:UNUSED_PAD src0_sel:WORD_1 src1_sel:DWORD
	ds_write_b64 v92, v[2:3]
	v_and_b32_e32 v2, 0xffff0000, v88
	v_sub_u32_e32 v0, v0, v2
	v_sub_u32_e32 v2, v6, v5
	v_and_b32_e32 v3, 0xffff0000, v4
	v_add_u32_e32 v2, 0x80, v2
	v_sub_u32_e32 v3, v7, v3
	v_sub_u32_e32 v1, v1, v89
	v_add_u32_e32 v0, 0x80, v0
	v_ashrrev_i32_e32 v2, 8, v2
	v_add_u32_e32 v3, 0x80, v3
	v_add_u32_e32 v1, 0x80, v1
	v_ashrrev_i32_e32 v0, 8, v0
	v_min_i32_e32 v2, 0x7f, v2
	v_ashrrev_i32_e32 v3, 8, v3
	v_ashrrev_i32_e32 v1, 8, v1
	v_min_i32_e32 v0, 0x7f, v0
	v_min_i32_sdwa v3, v3, s83 dst_sel:WORD_1 dst_unused:UNUSED_PAD src0_sel:DWORD src1_sel:DWORD
	v_min_i32_e32 v1, 0x7f, v1
	v_lshlrev_b32_e32 v2, 8, v2
	v_and_b32_e32 v2, 0xff00, v2
	v_and_b32_e32 v3, 0xff0000, v3
	v_perm_b32 v0, v1, v0, s84
	v_or3_b32 v0, v0, v2, v3
	ds_write_b32 v22, v0 offset:128
	v_mov_b32_e32 v0, v232
	v_mov_b32_e32 v1, v233
	v_mov_b32_e32 v2, v234
	v_mov_b32_e32 v3, v235
	v_mov_b32_e32 v4, v248
	v_mov_b32_e32 v5, v249
	v_mov_b32_e32 v6, v250
	v_mov_b32_e32 v7, v251
	ds_read_b64 v[94:95], v149
	s_waitcnt lgkmcnt(0)
	v_pk_add_f32 v[102:103], v[116:117], v[94:95] op_sel_hi:[1,0] neg_lo:[0,1] neg_hi:[0,1]
	s_nop 0
	v_pk_mul_f32 v[102:103], v[94:95], v[102:103] op_sel:[1,0]
	v_pk_add_f32 v[108:109], v[112:113], v[94:95] op_sel_hi:[1,0] neg_lo:[0,1] neg_hi:[0,1]
	v_mov_b32_e32 v88, v1
	v_mov_b32_e32 v89, v2
	v_mov_b32_e32 v90, v5
	v_mov_b32_e32 v91, v6
	v_pk_fma_f32 v[102:103], v[88:89], v[102:103], v[90:91]
	v_pk_mul_f32 v[94:95], v[94:95], v[108:109] op_sel:[1,0]
	v_mov_b32_e32 v1, v3
	v_mov_b32_e32 v5, v7
	v_and_b32_sdwa v93, v102, v216 dst_sel:DWORD dst_unused:UNUSED_PAD src0_sel:WORD_1 src1_sel:DWORD
	v_pk_fma_f32 v[6:7], v[0:1], v[94:95], v[4:5]
	v_add3_u32 v93, v102, v93, s82
	v_and_b32_e32 v108, 0xffff0000, v93
	v_and_b32_sdwa v93, v7, v216 dst_sel:DWORD dst_unused:UNUSED_PAD src0_sel:WORD_1 src1_sel:DWORD
	v_and_b32_sdwa v3, v103, v216 dst_sel:DWORD dst_unused:UNUSED_PAD src0_sel:WORD_1 src1_sel:DWORD
	v_and_b32_sdwa v94, v6, v216 dst_sel:DWORD dst_unused:UNUSED_PAD src0_sel:WORD_1 src1_sel:DWORD
	v_add3_u32 v93, v7, v93, s82
	v_or_b32_e32 v2, 0x120, v155
	v_add3_u32 v3, v103, v3, s82
	v_add3_u32 v109, v6, v94, s82
	v_and_b32_e32 v110, 0xffff0000, v93
	v_or_b32_sdwa v95, v110, v3 dst_sel:DWORD dst_unused:UNUSED_PAD src0_sel:DWORD src1_sel:WORD_1
	v_or_b32_sdwa v94, v109, v108 dst_sel:DWORD dst_unused:UNUSED_PAD src0_sel:WORD_1 src1_sel:DWORD
	v_add_u32_e32 v93, v2, v153
	ds_write_b64 v93, v[94:95]
	v_and_b32_e32 v94, 0xffff0000, v109
	v_sub_u32_e32 v6, v6, v94
	v_sub_u32_e32 v94, v102, v108
	v_and_b32_e32 v3, 0xffff0000, v3
	v_add_u32_e32 v94, 0x80, v94
	v_sub_u32_e32 v3, v103, v3
	v_sub_u32_e32 v7, v7, v110
	v_add_u32_e32 v6, 0x80, v6
	v_ashrrev_i32_e32 v94, 8, v94
	v_add_u32_e32 v3, 0x80, v3
	v_add_u32_e32 v7, 0x80, v7
	v_ashrrev_i32_e32 v6, 8, v6
	v_min_i32_e32 v94, 0x7f, v94
	v_ashrrev_i32_e32 v3, 8, v3
	v_ashrrev_i32_e32 v7, 8, v7
	v_min_i32_e32 v6, 0x7f, v6
	v_min_i32_sdwa v3, v3, s83 dst_sel:WORD_1 dst_unused:UNUSED_PAD src0_sel:DWORD src1_sel:DWORD
	v_min_i32_e32 v7, 0x7f, v7
	v_lshlrev_b32_e32 v94, 8, v94
	v_and_b32_e32 v94, 0xff00, v94
	v_and_b32_e32 v3, 0xff0000, v3
	v_perm_b32 v6, v7, v6, s84
	v_or3_b32 v3, v6, v94, v3
	ds_write_b32 v12, v3 offset:144
	ds_read_b64 v[6:7], v13
	s_waitcnt lgkmcnt(0)
	v_pk_add_f32 v[94:95], v[98:99], v[6:7] op_sel_hi:[1,0] neg_lo:[0,1] neg_hi:[0,1]
	s_nop 0
	v_pk_mul_f32 v[94:95], v[6:7], v[94:95] op_sel:[1,0]
	s_nop 0
	v_pk_fma_f32 v[98:99], v[88:89], v[94:95], v[90:91]
	v_pk_add_f32 v[94:95], v[96:97], v[6:7] op_sel_hi:[1,0] neg_lo:[0,1] neg_hi:[0,1]
	v_and_b32_sdwa v3, v99, v216 dst_sel:DWORD dst_unused:UNUSED_PAD src0_sel:WORD_1 src1_sel:DWORD
	v_pk_mul_f32 v[6:7], v[6:7], v[94:95] op_sel:[1,0]
	v_and_b32_sdwa v94, v98, v216 dst_sel:DWORD dst_unused:UNUSED_PAD src0_sel:WORD_1 src1_sel:DWORD
	v_pk_fma_f32 v[6:7], v[0:1], v[6:7], v[4:5]
	v_add3_u32 v94, v98, v94, s82
	v_and_b32_e32 v95, 0xffff0000, v94
	v_and_b32_sdwa v94, v7, v216 dst_sel:DWORD dst_unused:UNUSED_PAD src0_sel:WORD_1 src1_sel:DWORD
	v_and_b32_sdwa v96, v6, v216 dst_sel:DWORD dst_unused:UNUSED_PAD src0_sel:WORD_1 src1_sel:DWORD
	v_add3_u32 v94, v7, v94, s82
	v_add3_u32 v3, v99, v3, s82
	v_add3_u32 v102, v6, v96, s82
	v_and_b32_e32 v103, 0xffff0000, v94
	v_or_b32_sdwa v97, v103, v3 dst_sel:DWORD dst_unused:UNUSED_PAD src0_sel:DWORD src1_sel:WORD_1
	v_or_b32_sdwa v96, v102, v95 dst_sel:DWORD dst_unused:UNUSED_PAD src0_sel:WORD_1 src1_sel:DWORD
	v_add_u32_e32 v94, v2, v154
	ds_write_b64 v94, v[96:97]
	v_and_b32_e32 v96, 0xffff0000, v102
	v_sub_u32_e32 v95, v98, v95
	v_and_b32_e32 v3, 0xffff0000, v3
	v_sub_u32_e32 v6, v6, v96
	v_add_u32_e32 v95, 0x80, v95
	v_sub_u32_e32 v3, v99, v3
	v_sub_u32_e32 v7, v7, v103
	v_add_u32_e32 v6, 0x80, v6
	v_ashrrev_i32_e32 v95, 8, v95
	v_add_u32_e32 v3, 0x80, v3
	v_add_u32_e32 v7, 0x80, v7
	v_ashrrev_i32_e32 v6, 8, v6
	v_min_i32_e32 v95, 0x7f, v95
	v_ashrrev_i32_e32 v3, 8, v3
	v_ashrrev_i32_e32 v7, 8, v7
	v_min_i32_e32 v6, 0x7f, v6
	v_min_i32_sdwa v3, v3, s83 dst_sel:WORD_1 dst_unused:UNUSED_PAD src0_sel:DWORD src1_sel:DWORD
	v_min_i32_e32 v7, 0x7f, v7
	v_lshlrev_b32_e32 v95, 8, v95
	v_and_b32_e32 v95, 0xff00, v95
	v_and_b32_e32 v3, 0xff0000, v3
	v_perm_b32 v6, v7, v6, s84
	v_or3_b32 v3, v6, v95, v3
	ds_write_b32 v14, v3 offset:144
	ds_read_b64 v[6:7], v15
	s_waitcnt lgkmcnt(0)
; #define WAIT_L(n) asm volatile("s_waitcnt lgkmcnt(" #n ")" ::: "memory")
; #define BAR __builtin_amdgcn_s_barrier()
;     ...
;             _Pragma("unroll") for (int m = 0; m < 4; ++m) {
;               const int rr = wr3 * 64 + m * 16 + fr3;
;               const float2 ms = *reinterpret_cast<const float2*>(mr + (ai * HALF + rr) * 2);
;               f32x4 y = acc[ai][bj][m][n];
;               const float o0 = (y[0] - ms.x) * ms.y * gm.x + bt.x, o1 = (y[1] - ms.x) * ms.y * gm.y + bt.y;
;               const float o2 = (y[2] - ms.x) * ms.y * gm.z + bt.z, o3 = (y[3] - ms.x) * ms.y * gm.w + bt.w;
;               const unsigned h0 = f2bf(o0), h1 = f2bf(o1), h2 = f2bf(o2), h3 = f2bf(o3);
;               u32x2 ob; ob[0] = h0 | (h1 << 16); ob[1] = h2 | (h3 << 16);
;               *reinterpret_cast<u32x2*>(smem + (rr >> 1) * PIECE + (rr & 1) * 512 + cc * 2) = ob;
;               const int l0 = min(((int)__float_as_uint(o0) - (int)(h0 << 16) + 128) >> 8, 127);
;               const int l1 = min(((int)__float_as_uint(o1) - (int)(h1 << 16) + 128) >> 8, 127);
;               const int l2 = min(((int)__float_as_uint(o2) - (int)(h2 << 16) + 128) >> 8, 127);
;               const int l3 = min(((int)__float_as_uint(o3) - (int)(h3 << 16) + 128) >> 8, 127);
;               *reinterpret_cast<unsigned*>(smem + LOBASE + (rr >> 2) * PIECE + (rr & 3) * 256 + cc) =
;                   (unsigned)(l0 & 255) | ((unsigned)(l1 & 255) << 8) | ((unsigned)(l2 & 255) << 16) | ((unsigned)l3 << 24);
;             }
;           }
;           WAIT_L(0); BAR;
;           const int hso = ((brow + ai * HALF + 16 * wave) * DM + pn * BM) * 2;
;           const int lso = (brow + ai * HALF + 16 * wave) * DM + pn * BM;
;           _Pragma("unroll") for (int i = 0; i < 8; ++i) {
;             const u32x4 v = *reinterpret_cast<const u32x4*>(smem + (wave * 8 + i) * PIECE + lane3 * 16);
;             __builtin_amdgcn_raw_buffer_store_b128(v, rsXB, hvo + i * (2 * DM * 2), hso, 0);
;           }
;           _Pragma("unroll") for (int i = 0; i < 4; ++i) {
;             const u32x4 v = *reinterpret_cast<const u32x4*>(smem + LOBASE + (wave * 4 + i) * PIECE + lane3 * 16);
	v_pk_add_f32 v[82:83], v[82:83], v[6:7] op_sel_hi:[1,0] neg_lo:[0,1] neg_hi:[0,1]
	s_nop 0
	v_pk_mul_f32 v[82:83], v[6:7], v[82:83] op_sel:[1,0]
	v_pk_add_f32 v[80:81], v[80:81], v[6:7] op_sel_hi:[1,0] neg_lo:[0,1] neg_hi:[0,1]
	v_pk_fma_f32 v[82:83], v[88:89], v[82:83], v[90:91]
	v_pk_mul_f32 v[6:7], v[6:7], v[80:81] op_sel:[1,0]
	v_and_b32_sdwa v80, v82, v216 dst_sel:DWORD dst_unused:UNUSED_PAD src0_sel:WORD_1 src1_sel:DWORD
	v_pk_fma_f32 v[6:7], v[0:1], v[6:7], v[4:5]
	v_add3_u32 v80, v82, v80, s82
	v_and_b32_e32 v81, 0xffff0000, v80
	v_and_b32_sdwa v80, v7, v216 dst_sel:DWORD dst_unused:UNUSED_PAD src0_sel:WORD_1 src1_sel:DWORD
	v_and_b32_sdwa v3, v83, v216 dst_sel:DWORD dst_unused:UNUSED_PAD src0_sel:WORD_1 src1_sel:DWORD
	v_and_b32_sdwa v95, v6, v216 dst_sel:DWORD dst_unused:UNUSED_PAD src0_sel:WORD_1 src1_sel:DWORD
	v_add3_u32 v80, v7, v80, s82
	v_add3_u32 v3, v83, v3, s82
	v_add3_u32 v95, v6, v95, s82
	v_and_b32_e32 v98, 0xffff0000, v80
	v_or_b32_sdwa v97, v98, v3 dst_sel:DWORD dst_unused:UNUSED_PAD src0_sel:DWORD src1_sel:WORD_1
	v_or_b32_sdwa v96, v95, v81 dst_sel:DWORD dst_unused:UNUSED_PAD src0_sel:WORD_1 src1_sel:DWORD
	v_and_b32_e32 v95, 0xffff0000, v95
	v_sub_u32_e32 v81, v82, v81
	v_and_b32_e32 v3, 0xffff0000, v3
	v_sub_u32_e32 v6, v6, v95
	v_add_u32_e32 v81, 0x80, v81
	v_sub_u32_e32 v3, v83, v3
	v_sub_u32_e32 v7, v7, v98
	v_add_u32_e32 v6, 0x80, v6
	v_ashrrev_i32_e32 v81, 8, v81
	v_add_u32_e32 v3, 0x80, v3
	v_add_u32_e32 v7, 0x80, v7
	v_ashrrev_i32_e32 v6, 8, v6
	v_min_i32_e32 v81, 0x7f, v81
	v_ashrrev_i32_e32 v3, 8, v3
	v_ashrrev_i32_e32 v7, 8, v7
	v_min_i32_e32 v6, 0x7f, v6
	v_min_i32_sdwa v3, v3, s83 dst_sel:WORD_1 dst_unused:UNUSED_PAD src0_sel:DWORD src1_sel:DWORD
	v_min_i32_e32 v7, 0x7f, v7
	v_lshlrev_b32_e32 v81, 8, v81
	v_and_b32_e32 v81, 0xff00, v81
	v_and_b32_e32 v3, 0xff0000, v3
	v_perm_b32 v6, v7, v6, s84
	v_add_u32_e32 v80, v2, v136
	v_or3_b32 v3, v6, v81, v3
	ds_write_b64 v80, v[96:97]
	ds_write_b32 v20, v3 offset:144
	ds_read_b64 v[6:7], v21
	v_or_b32_e32 v81, 0x6000, v148
	v_or_b32_e32 v82, 0x8000, v148
	v_or_b32_e32 v83, 0xa000, v148
	v_or_b32_e32 v95, 0x6000, v146
	s_waitcnt lgkmcnt(0)
	v_pk_add_f32 v[74:75], v[74:75], v[6:7] op_sel_hi:[1,0] neg_lo:[0,1] neg_hi:[0,1]
	v_pk_add_f32 v[72:73], v[72:73], v[6:7] op_sel_hi:[1,0] neg_lo:[0,1] neg_hi:[0,1]
	v_pk_mul_f32 v[74:75], v[6:7], v[74:75] op_sel:[1,0]
	v_pk_mul_f32 v[6:7], v[6:7], v[72:73] op_sel:[1,0]
	v_pk_fma_f32 v[74:75], v[88:89], v[74:75], v[90:91]
	v_pk_fma_f32 v[0:1], v[0:1], v[6:7], v[4:5]
	v_and_b32_sdwa v4, v74, v216 dst_sel:DWORD dst_unused:UNUSED_PAD src0_sel:WORD_1 src1_sel:DWORD
	v_add3_u32 v4, v74, v4, s82
	v_and_b32_e32 v6, 0xffff0000, v4
	v_and_b32_sdwa v4, v1, v216 dst_sel:DWORD dst_unused:UNUSED_PAD src0_sel:WORD_1 src1_sel:DWORD
	v_and_b32_sdwa v5, v0, v216 dst_sel:DWORD dst_unused:UNUSED_PAD src0_sel:WORD_1 src1_sel:DWORD
	v_and_b32_sdwa v3, v75, v216 dst_sel:DWORD dst_unused:UNUSED_PAD src0_sel:WORD_1 src1_sel:DWORD
	v_add3_u32 v4, v1, v4, s82
	v_add3_u32 v7, v0, v5, s82
	v_add3_u32 v3, v75, v3, s82
	v_and_b32_e32 v72, 0xffff0000, v4
	v_add_u32_e32 v73, v2, v135
	v_and_b32_e32 v2, 0xffff0000, v7
	v_or_b32_sdwa v5, v72, v3 dst_sel:DWORD dst_unused:UNUSED_PAD src0_sel:DWORD src1_sel:WORD_1
	v_sub_u32_e32 v0, v0, v2
	v_sub_u32_e32 v2, v74, v6
	v_and_b32_e32 v3, 0xffff0000, v3
	v_add_u32_e32 v2, 0x80, v2
	v_sub_u32_e32 v3, v75, v3
	v_sub_u32_e32 v1, v1, v72
	v_add_u32_e32 v0, 0x80, v0
	v_ashrrev_i32_e32 v2, 8, v2
	v_add_u32_e32 v3, 0x80, v3
	v_add_u32_e32 v1, 0x80, v1
	v_ashrrev_i32_e32 v0, 8, v0
	v_min_i32_e32 v2, 0x7f, v2
	v_ashrrev_i32_e32 v3, 8, v3
	v_ashrrev_i32_e32 v1, 8, v1
	v_min_i32_e32 v0, 0x7f, v0
	v_min_i32_sdwa v3, v3, s83 dst_sel:WORD_1 dst_unused:UNUSED_PAD src0_sel:DWORD src1_sel:DWORD
	v_min_i32_e32 v1, 0x7f, v1
	v_lshlrev_b32_e32 v2, 8, v2
	v_and_b32_e32 v2, 0xff00, v2
	v_and_b32_e32 v3, 0xff0000, v3
	v_perm_b32 v0, v1, v0, s84
	v_or_b32_sdwa v4, v7, v6 dst_sel:DWORD dst_unused:UNUSED_PAD src0_sel:WORD_1 src1_sel:DWORD
	v_or3_b32 v0, v0, v2, v3
	ds_write_b64 v73, v[4:5]
	ds_write_b32 v22, v0 offset:144
	v_add_u32_e32 v72, s47, v152
	s_waitcnt lgkmcnt(0)
	s_barrier
	ds_read_b128 v[128:131], v72
	v_or_b32_e32 v74, 0x2000, v148
	v_or_b32_e32 v75, 0x4000, v148
	v_or_b32_e32 v88, 0xc000, v148
	v_or_b32_e32 v89, 0xe000, v148
	ds_read_b128 v[136:139], v72 offset:1040
	v_or_b32_e32 v90, 0x2000, v146
	v_or_b32_e32 v91, 0x4000, v146
	ds_read_b128 v[140:143], v72 offset:2080
	ds_read_b128 v[152:155], v72 offset:3120
	ds_read_b128 v[156:159], v72 offset:4160
	ds_read_b128 v[160:163], v72 offset:5200
	ds_read_b128 v[164:167], v72 offset:6240
	ds_read_b128 v[168:171], v72 offset:7280
	ds_read_b128 v[172:175], v147
	ds_read_b128 v[176:179], v147 offset:1040
	ds_read_b128 v[180:183], v147 offset:2080
	ds_read_b128 v[184:187], v147 offset:3120
	s_waitcnt lgkmcnt(0)
	s_barrier
;     ...
;           _Pragma("unroll") for (int bj = 0; bj < 2; ++bj) _Pragma("unroll") for (int n = 0; n < 2; ++n) {
;             const int cc = bj * HALF + wc3 * 32 + n * 16 + fq3 * 4;
;             const float4 gm = *reinterpret_cast<const float4*>(g.gam + pn * BM + cc), bt = *reinterpret_cast<const float4*>(g.bet + pn * BM + cc);
;             _Pragma("unroll") for (int m = 0; m < 4; ++m) {
;               const int rr = wr3 * 64 + m * 16 + fr3;
;               const float2 ms = *reinterpret_cast<const float2*>(mr + (ai * HALF + rr) * 2);
;               f32x4 y = acc[ai][bj][m][n];
;               const float o0 = (y[0] - ms.x) * ms.y * gm.x + bt.x, o1 = (y[1] - ms.x) * ms.y * gm.y + bt.y;
;               const float o2 = (y[2] - ms.x) * ms.y * gm.z + bt.z, o3 = (y[3] - ms.x) * ms.y * gm.w + bt.w;
;               const unsigned h0 = f2bf(o0), h1 = f2bf(o1), h2 = f2bf(o2), h3 = f2bf(o3);
;               u32x2 ob; ob[0] = h0 | (h1 << 16); ob[1] = h2 | (h3 << 16);
;               *reinterpret_cast<u32x2*>(smem + (rr >> 1) * PIECE + (rr & 1) * 512 + cc * 2) = ob;
;               const int l0 = min(((int)__float_as_uint(o0) - (int)(h0 << 16) + 128) >> 8, 127);
;               const int l1 = min(((int)__float_as_uint(o1) - (int)(h1 << 16) + 128) >> 8, 127);
;               const int l2 = min(((int)__float_as_uint(o2) - (int)(h2 << 16) + 128) >> 8, 127);
;               const int l3 = min(((int)__float_as_uint(o3) - (int)(h3 << 16) + 128) >> 8, 127);
;               *reinterpret_cast<unsigned*>(smem + LOBASE + (rr >> 2) * PIECE + (rr & 3) * 256 + cc) =
;                   (unsigned)(l0 & 255) | ((unsigned)(l1 & 255) << 8) | ((unsigned)(l2 & 255) << 16) | ((unsigned)l3 << 24);
;             }
;     ...
;           _Pragma("unroll") for (int i = 0; i < 8; ++i) {
;             const u32x4 v = *reinterpret_cast<const u32x4*>(smem + (wave * 8 + i) * PIECE + lane3 * 16);
;             __builtin_amdgcn_raw_buffer_store_b128(v, rsXB, hvo + i * (2 * DM * 2), hso, 0);
;           }
;           _Pragma("unroll") for (int i = 0; i < 4; ++i) {
;             const u32x4 v = *reinterpret_cast<const u32x4*>(smem + LOBASE + (wave * 4 + i) * PIECE + lane3 * 16);
;             __builtin_amdgcn_raw_buffer_store_b128(v, rsLO, lvo + i * (4 * DM), lso, 0);
;           }
	s_nop 1
	v_mov_b32_e32 v0, v220
	v_mov_b32_e32 v1, v221
	v_mov_b32_e32 v2, v222
	v_mov_b32_e32 v3, v223
	v_mov_b32_e32 v4, v236
	v_mov_b32_e32 v5, v237
	v_mov_b32_e32 v6, v238
	v_mov_b32_e32 v7, v239
	ds_read_b64 v[102:103], v149 offset:1024
	s_waitcnt lgkmcnt(0)
	v_pk_add_f32 v[66:67], v[66:67], v[102:103] op_sel_hi:[1,0] neg_lo:[0,1] neg_hi:[0,1]
	s_nop 0
	v_pk_mul_f32 v[66:67], v[102:103], v[66:67] op_sel:[1,0]
	v_pk_add_f32 v[64:65], v[64:65], v[102:103] op_sel_hi:[1,0] neg_lo:[0,1] neg_hi:[0,1]
	v_mov_b32_e32 v96, v1
	v_mov_b32_e32 v97, v2
	v_mov_b32_e32 v98, v5
	v_mov_b32_e32 v99, v6
	v_pk_fma_f32 v[66:67], v[96:97], v[66:67], v[98:99]
	v_pk_mul_f32 v[64:65], v[102:103], v[64:65] op_sel:[1,0]
	v_mov_b32_e32 v1, v3
	v_mov_b32_e32 v5, v7
	v_and_b32_sdwa v6, v67, v216 dst_sel:DWORD dst_unused:UNUSED_PAD src0_sel:WORD_1 src1_sel:DWORD
	v_and_b32_sdwa v7, v66, v216 dst_sel:DWORD dst_unused:UNUSED_PAD src0_sel:WORD_1 src1_sel:DWORD
	v_pk_fma_f32 v[2:3], v[0:1], v[64:65], v[4:5]
	v_add3_u32 v64, v67, v6, s82
	v_add3_u32 v6, v66, v7, s82
	v_and_b32_e32 v65, 0xffff0000, v6
	v_and_b32_sdwa v6, v3, v216 dst_sel:DWORD dst_unused:UNUSED_PAD src0_sel:WORD_1 src1_sel:DWORD
	v_and_b32_sdwa v7, v2, v216 dst_sel:DWORD dst_unused:UNUSED_PAD src0_sel:WORD_1 src1_sel:DWORD
	v_add3_u32 v6, v3, v6, s82
	v_add3_u32 v102, v2, v7, s82
	v_and_b32_e32 v103, 0xffff0000, v6
	v_or_b32_sdwa v7, v103, v64 dst_sel:DWORD dst_unused:UNUSED_PAD src0_sel:DWORD src1_sel:WORD_1
	v_or_b32_sdwa v6, v102, v65 dst_sel:DWORD dst_unused:UNUSED_PAD src0_sel:WORD_1 src1_sel:DWORD
	ds_write_b64 v151, v[6:7]
	v_and_b32_e32 v6, 0xffff0000, v102
	v_sub_u32_e32 v2, v2, v6
	v_sub_u32_e32 v6, v66, v65
	v_and_b32_e32 v7, 0xffff0000, v64
	v_add_u32_e32 v6, 0x80, v6
	v_sub_u32_e32 v7, v67, v7
	v_sub_u32_e32 v3, v3, v103
	v_add_u32_e32 v2, 0x80, v2
	v_ashrrev_i32_e32 v6, 8, v6
	v_add_u32_e32 v7, 0x80, v7
	v_add_u32_e32 v3, 0x80, v3
	v_ashrrev_i32_e32 v2, 8, v2
	v_min_i32_e32 v6, 0x7f, v6
	v_ashrrev_i32_e32 v7, 8, v7
	v_ashrrev_i32_e32 v3, 8, v3
	v_min_i32_e32 v2, 0x7f, v2
	v_min_i32_sdwa v7, v7, s83 dst_sel:WORD_1 dst_unused:UNUSED_PAD src0_sel:DWORD src1_sel:DWORD
	v_min_i32_e32 v3, 0x7f, v3
	v_lshlrev_b32_e32 v6, 8, v6
	v_and_b32_e32 v6, 0xff00, v6
	v_and_b32_e32 v7, 0xff0000, v7
	v_perm_b32 v2, v3, v2, s84
	v_or3_b32 v2, v2, v6, v7
	ds_write_b32 v12, v2
	buffer_store_dwordx4 v[128:131], v148, s[16:19], s33 offen
	ds_read_b64 v[2:3], v13 offset:1024
	s_waitcnt lgkmcnt(0)
	v_pk_add_f32 v[6:7], v[70:71], v[2:3] op_sel_hi:[1,0] neg_lo:[0,1] neg_hi:[0,1]
	s_nop 0
	v_pk_mul_f32 v[6:7], v[2:3], v[6:7] op_sel:[1,0]
	v_pk_add_f32 v[64:65], v[68:69], v[2:3] op_sel_hi:[1,0] neg_lo:[0,1] neg_hi:[0,1]
	v_pk_fma_f32 v[6:7], v[96:97], v[6:7], v[98:99]
	v_pk_mul_f32 v[2:3], v[2:3], v[64:65] op_sel:[1,0]
	v_and_b32_sdwa v64, v7, v216 dst_sel:DWORD dst_unused:UNUSED_PAD src0_sel:WORD_1 src1_sel:DWORD
	v_and_b32_sdwa v65, v6, v216 dst_sel:DWORD dst_unused:UNUSED_PAD src0_sel:WORD_1 src1_sel:DWORD
	v_pk_fma_f32 v[2:3], v[0:1], v[2:3], v[4:5]
	v_add3_u32 v66, v7, v64, s82
	v_add3_u32 v64, v6, v65, s82
	v_and_b32_e32 v67, 0xffff0000, v64
	v_and_b32_sdwa v64, v3, v216 dst_sel:DWORD dst_unused:UNUSED_PAD src0_sel:WORD_1 src1_sel:DWORD
	v_and_b32_sdwa v65, v2, v216 dst_sel:DWORD dst_unused:UNUSED_PAD src0_sel:WORD_1 src1_sel:DWORD
	v_add3_u32 v64, v3, v64, s82
	v_add3_u32 v68, v2, v65, s82
	v_and_b32_e32 v69, 0xffff0000, v64
	v_or_b32_sdwa v65, v69, v66 dst_sel:DWORD dst_unused:UNUSED_PAD src0_sel:DWORD src1_sel:WORD_1
	v_or_b32_sdwa v64, v68, v67 dst_sel:DWORD dst_unused:UNUSED_PAD src0_sel:WORD_1 src1_sel:DWORD
	ds_write_b64 v132, v[64:65]
	v_and_b32_e32 v64, 0xffff0000, v68
	v_sub_u32_e32 v2, v2, v64
	v_sub_u32_e32 v6, v6, v67
	v_and_b32_e32 v64, 0xffff0000, v66
	v_add_u32_e32 v6, 0x80, v6
	v_sub_u32_e32 v7, v7, v64
	v_sub_u32_e32 v3, v3, v69
	v_add_u32_e32 v2, 0x80, v2
	v_ashrrev_i32_e32 v6, 8, v6
	v_add_u32_e32 v7, 0x80, v7
	v_add_u32_e32 v3, 0x80, v3
	v_ashrrev_i32_e32 v2, 8, v2
	v_min_i32_e32 v6, 0x7f, v6
	v_ashrrev_i32_e32 v7, 8, v7
	v_ashrrev_i32_e32 v3, 8, v3
	v_min_i32_e32 v2, 0x7f, v2
	v_min_i32_sdwa v7, v7, s83 dst_sel:WORD_1 dst_unused:UNUSED_PAD src0_sel:DWORD src1_sel:DWORD
	v_min_i32_e32 v3, 0x7f, v3
	v_lshlrev_b32_e32 v6, 8, v6
	v_and_b32_e32 v6, 0xff00, v6
	v_and_b32_e32 v7, 0xff0000, v7
	v_perm_b32 v2, v3, v2, s84
	v_or3_b32 v2, v2, v6, v7
	ds_write_b32 v14, v2
	buffer_store_dwordx4 v[136:139], v74, s[16:19], s33 offen
	ds_read_b64 v[2:3], v15 offset:1024
	s_waitcnt lgkmcnt(0)
	v_pk_add_f32 v[6:7], v[78:79], v[2:3] op_sel_hi:[1,0] neg_lo:[0,1] neg_hi:[0,1]
	s_nop 0
	v_pk_mul_f32 v[6:7], v[2:3], v[6:7] op_sel:[1,0]
	v_pk_add_f32 v[64:65], v[76:77], v[2:3] op_sel_hi:[1,0] neg_lo:[0,1] neg_hi:[0,1]
	v_pk_fma_f32 v[6:7], v[96:97], v[6:7], v[98:99]
	v_pk_mul_f32 v[2:3], v[2:3], v[64:65] op_sel:[1,0]
	v_and_b32_sdwa v64, v7, v216 dst_sel:DWORD dst_unused:UNUSED_PAD src0_sel:WORD_1 src1_sel:DWORD
	v_and_b32_sdwa v65, v6, v216 dst_sel:DWORD dst_unused:UNUSED_PAD src0_sel:WORD_1 src1_sel:DWORD
	v_pk_fma_f32 v[2:3], v[0:1], v[2:3], v[4:5]
	v_add3_u32 v66, v7, v64, s82
	v_add3_u32 v64, v6, v65, s82
	v_and_b32_e32 v67, 0xffff0000, v64
	v_and_b32_sdwa v64, v3, v216 dst_sel:DWORD dst_unused:UNUSED_PAD src0_sel:WORD_1 src1_sel:DWORD
	v_and_b32_sdwa v65, v2, v216 dst_sel:DWORD dst_unused:UNUSED_PAD src0_sel:WORD_1 src1_sel:DWORD
	v_add3_u32 v64, v3, v64, s82
	v_add3_u32 v68, v2, v65, s82
	v_and_b32_e32 v69, 0xffff0000, v64
	v_or_b32_sdwa v65, v69, v66 dst_sel:DWORD dst_unused:UNUSED_PAD src0_sel:DWORD src1_sel:WORD_1
	v_or_b32_sdwa v64, v68, v67 dst_sel:DWORD dst_unused:UNUSED_PAD src0_sel:WORD_1 src1_sel:DWORD
	ds_write_b64 v133, v[64:65]
	v_and_b32_e32 v64, 0xffff0000, v68
	v_sub_u32_e32 v2, v2, v64
	v_sub_u32_e32 v6, v6, v67
	v_and_b32_e32 v64, 0xffff0000, v66
	v_add_u32_e32 v6, 0x80, v6
	v_sub_u32_e32 v7, v7, v64
	v_sub_u32_e32 v3, v3, v69
	v_add_u32_e32 v2, 0x80, v2
	v_ashrrev_i32_e32 v6, 8, v6
	v_add_u32_e32 v7, 0x80, v7
	v_add_u32_e32 v3, 0x80, v3
	v_ashrrev_i32_e32 v2, 8, v2
	v_min_i32_e32 v6, 0x7f, v6
	v_ashrrev_i32_e32 v7, 8, v7
	v_ashrrev_i32_e32 v3, 8, v3
	v_min_i32_e32 v2, 0x7f, v2
	v_min_i32_sdwa v7, v7, s83 dst_sel:WORD_1 dst_unused:UNUSED_PAD src0_sel:DWORD src1_sel:DWORD
	v_min_i32_e32 v3, 0x7f, v3
	v_lshlrev_b32_e32 v6, 8, v6
	v_and_b32_e32 v6, 0xff00, v6
	v_and_b32_e32 v7, 0xff0000, v7
	v_perm_b32 v2, v3, v2, s84
	v_or3_b32 v2, v2, v6, v7
	ds_write_b32 v20, v2
	buffer_store_dwordx4 v[140:143], v75, s[16:19], s33 offen
	ds_read_b64 v[2:3], v21 offset:1024
	s_waitcnt lgkmcnt(0)
;     ...
;           _Pragma("unroll") for (int bj = 0; bj < 2; ++bj) _Pragma("unroll") for (int n = 0; n < 2; ++n) {
;             const int cc = bj * HALF + wc3 * 32 + n * 16 + fq3 * 4;
;             const float4 gm = *reinterpret_cast<const float4*>(g.gam + pn * BM + cc), bt = *reinterpret_cast<const float4*>(g.bet + pn * BM + cc);
;             _Pragma("unroll") for (int m = 0; m < 4; ++m) {
;               const int rr = wr3 * 64 + m * 16 + fr3;
;               const float2 ms = *reinterpret_cast<const float2*>(mr + (ai * HALF + rr) * 2);
;               f32x4 y = acc[ai][bj][m][n];
;               const float o0 = (y[0] - ms.x) * ms.y * gm.x + bt.x, o1 = (y[1] - ms.x) * ms.y * gm.y + bt.y;
;               const float o2 = (y[2] - ms.x) * ms.y * gm.z + bt.z, o3 = (y[3] - ms.x) * ms.y * gm.w + bt.w;
;               const unsigned h0 = f2bf(o0), h1 = f2bf(o1), h2 = f2bf(o2), h3 = f2bf(o3);
;               u32x2 ob; ob[0] = h0 | (h1 << 16); ob[1] = h2 | (h3 << 16);
;               *reinterpret_cast<u32x2*>(smem + (rr >> 1) * PIECE + (rr & 1) * 512 + cc * 2) = ob;
;               const int l0 = min(((int)__float_as_uint(o0) - (int)(h0 << 16) + 128) >> 8, 127);
;               const int l1 = min(((int)__float_as_uint(o1) - (int)(h1 << 16) + 128) >> 8, 127);
;               const int l2 = min(((int)__float_as_uint(o2) - (int)(h2 << 16) + 128) >> 8, 127);
;               const int l3 = min(((int)__float_as_uint(o3) - (int)(h3 << 16) + 128) >> 8, 127);
;               *reinterpret_cast<unsigned*>(smem + LOBASE + (rr >> 2) * PIECE + (rr & 3) * 256 + cc) =
;                   (unsigned)(l0 & 255) | ((unsigned)(l1 & 255) << 8) | ((unsigned)(l2 & 255) << 16) | ((unsigned)l3 << 24);
;             }
;     ...
;           _Pragma("unroll") for (int i = 0; i < 8; ++i) {
;             const u32x4 v = *reinterpret_cast<const u32x4*>(smem + (wave * 8 + i) * PIECE + lane3 * 16);
;             __builtin_amdgcn_raw_buffer_store_b128(v, rsXB, hvo + i * (2 * DM * 2), hso, 0);
;           }
;           _Pragma("unroll") for (int i = 0; i < 4; ++i) {
;             const u32x4 v = *reinterpret_cast<const u32x4*>(smem + LOBASE + (wave * 4 + i) * PIECE + lane3 * 16);
;             __builtin_amdgcn_raw_buffer_store_b128(v, rsLO, lvo + i * (4 * DM), lso, 0);
;           }
	v_pk_add_f32 v[6:7], v[86:87], v[2:3] op_sel_hi:[1,0] neg_lo:[0,1] neg_hi:[0,1]
	s_nop 0
	v_pk_mul_f32 v[6:7], v[2:3], v[6:7] op_sel:[1,0]
	v_pk_add_f32 v[64:65], v[84:85], v[2:3] op_sel_hi:[1,0] neg_lo:[0,1] neg_hi:[0,1]
	v_pk_fma_f32 v[6:7], v[96:97], v[6:7], v[98:99]
	v_pk_mul_f32 v[2:3], v[2:3], v[64:65] op_sel:[1,0]
	s_nop 0
	v_pk_fma_f32 v[0:1], v[0:1], v[2:3], v[4:5]
	v_and_b32_sdwa v2, v7, v216 dst_sel:DWORD dst_unused:UNUSED_PAD src0_sel:WORD_1 src1_sel:DWORD
	v_and_b32_sdwa v3, v6, v216 dst_sel:DWORD dst_unused:UNUSED_PAD src0_sel:WORD_1 src1_sel:DWORD
	v_add3_u32 v4, v7, v2, s82
	v_add3_u32 v2, v6, v3, s82
	v_and_b32_e32 v5, 0xffff0000, v2
	v_and_b32_sdwa v2, v1, v216 dst_sel:DWORD dst_unused:UNUSED_PAD src0_sel:WORD_1 src1_sel:DWORD
	v_and_b32_sdwa v3, v0, v216 dst_sel:DWORD dst_unused:UNUSED_PAD src0_sel:WORD_1 src1_sel:DWORD
	v_add3_u32 v2, v1, v2, s82
	v_add3_u32 v64, v0, v3, s82
	v_and_b32_e32 v65, 0xffff0000, v2
	v_or_b32_sdwa v3, v65, v4 dst_sel:DWORD dst_unused:UNUSED_PAD src0_sel:DWORD src1_sel:WORD_1
	v_or_b32_sdwa v2, v64, v5 dst_sel:DWORD dst_unused:UNUSED_PAD src0_sel:WORD_1 src1_sel:DWORD
	ds_write_b64 v134, v[2:3]
	v_and_b32_e32 v2, 0xffff0000, v64
	v_sub_u32_e32 v0, v0, v2
	v_sub_u32_e32 v2, v6, v5
	v_and_b32_e32 v3, 0xffff0000, v4
	v_add_u32_e32 v2, 0x80, v2
	v_sub_u32_e32 v3, v7, v3
	v_sub_u32_e32 v1, v1, v65
	v_add_u32_e32 v0, 0x80, v0
	v_ashrrev_i32_e32 v2, 8, v2
	v_add_u32_e32 v3, 0x80, v3
	v_add_u32_e32 v1, 0x80, v1
	v_ashrrev_i32_e32 v0, 8, v0
	v_min_i32_e32 v2, 0x7f, v2
	v_ashrrev_i32_e32 v3, 8, v3
	v_ashrrev_i32_e32 v1, 8, v1
	v_min_i32_e32 v0, 0x7f, v0
	v_min_i32_sdwa v3, v3, s83 dst_sel:WORD_1 dst_unused:UNUSED_PAD src0_sel:DWORD src1_sel:DWORD
	v_min_i32_e32 v1, 0x7f, v1
	v_lshlrev_b32_e32 v2, 8, v2
	v_and_b32_e32 v2, 0xff00, v2
	v_and_b32_e32 v3, 0xff0000, v3
	v_perm_b32 v0, v1, v0, s84
	v_or3_b32 v0, v0, v2, v3
	ds_write_b32 v22, v0
	buffer_store_dwordx4 v[152:155], v81, s[16:19], s33 offen
	v_mov_b32_e32 v0, v224
	v_mov_b32_e32 v1, v225
	v_mov_b32_e32 v2, v226
	v_mov_b32_e32 v3, v227
	v_mov_b32_e32 v4, v240
	v_mov_b32_e32 v5, v241
	v_mov_b32_e32 v6, v242
	v_mov_b32_e32 v7, v243
	ds_read_b64 v[68:69], v149 offset:1024
	s_waitcnt lgkmcnt(0)
	v_pk_add_f32 v[58:59], v[58:59], v[68:69] op_sel_hi:[1,0] neg_lo:[0,1] neg_hi:[0,1]
	s_nop 0
	v_pk_mul_f32 v[58:59], v[68:69], v[58:59] op_sel:[1,0]
	v_pk_add_f32 v[56:57], v[56:57], v[68:69] op_sel_hi:[1,0] neg_lo:[0,1] neg_hi:[0,1]
	v_mov_b32_e32 v64, v1
	v_mov_b32_e32 v65, v2
	v_mov_b32_e32 v66, v5
	v_mov_b32_e32 v67, v6
	v_pk_fma_f32 v[58:59], v[64:65], v[58:59], v[66:67]
	v_pk_mul_f32 v[56:57], v[68:69], v[56:57] op_sel:[1,0]
	v_mov_b32_e32 v1, v3
	v_mov_b32_e32 v5, v7
	v_and_b32_sdwa v6, v59, v216 dst_sel:DWORD dst_unused:UNUSED_PAD src0_sel:WORD_1 src1_sel:DWORD
	v_and_b32_sdwa v7, v58, v216 dst_sel:DWORD dst_unused:UNUSED_PAD src0_sel:WORD_1 src1_sel:DWORD
	v_pk_fma_f32 v[2:3], v[0:1], v[56:57], v[4:5]
	v_add3_u32 v56, v59, v6, s82
	v_add3_u32 v6, v58, v7, s82
	v_and_b32_e32 v57, 0xffff0000, v6
	v_and_b32_sdwa v6, v3, v216 dst_sel:DWORD dst_unused:UNUSED_PAD src0_sel:WORD_1 src1_sel:DWORD
	v_and_b32_sdwa v7, v2, v216 dst_sel:DWORD dst_unused:UNUSED_PAD src0_sel:WORD_1 src1_sel:DWORD
	v_add3_u32 v6, v3, v6, s82
	v_add3_u32 v68, v2, v7, s82
	v_and_b32_e32 v69, 0xffff0000, v6
	v_or_b32_sdwa v7, v69, v56 dst_sel:DWORD dst_unused:UNUSED_PAD src0_sel:DWORD src1_sel:WORD_1
	v_or_b32_sdwa v6, v68, v57 dst_sel:DWORD dst_unused:UNUSED_PAD src0_sel:WORD_1 src1_sel:DWORD
	ds_write_b64 v23, v[6:7]
	v_and_b32_e32 v6, 0xffff0000, v68
	v_sub_u32_e32 v2, v2, v6
	v_sub_u32_e32 v6, v58, v57
	v_and_b32_e32 v7, 0xffff0000, v56
	v_add_u32_e32 v6, 0x80, v6
	v_sub_u32_e32 v7, v59, v7
	v_sub_u32_e32 v3, v3, v69
	v_add_u32_e32 v2, 0x80, v2
	v_ashrrev_i32_e32 v6, 8, v6
	v_add_u32_e32 v7, 0x80, v7
	v_add_u32_e32 v3, 0x80, v3
	v_ashrrev_i32_e32 v2, 8, v2
	v_min_i32_e32 v6, 0x7f, v6
	v_ashrrev_i32_e32 v7, 8, v7
	v_ashrrev_i32_e32 v3, 8, v3
	v_min_i32_e32 v2, 0x7f, v2
	v_min_i32_sdwa v7, v7, s83 dst_sel:WORD_1 dst_unused:UNUSED_PAD src0_sel:DWORD src1_sel:DWORD
	v_min_i32_e32 v3, 0x7f, v3
	v_lshlrev_b32_e32 v6, 8, v6
	v_and_b32_e32 v6, 0xff00, v6
	v_and_b32_e32 v7, 0xff0000, v7
	v_perm_b32 v2, v3, v2, s84
	v_or3_b32 v2, v2, v6, v7
	ds_write_b32 v12, v2 offset:16
	buffer_store_dwordx4 v[156:159], v82, s[16:19], s33 offen
	ds_read_b64 v[2:3], v13 offset:1024
	s_waitcnt lgkmcnt(0)
	v_pk_add_f32 v[6:7], v[42:43], v[2:3] op_sel_hi:[1,0] neg_lo:[0,1] neg_hi:[0,1]
	s_nop 0
	v_pk_mul_f32 v[6:7], v[2:3], v[6:7] op_sel:[1,0]
	v_pk_add_f32 v[40:41], v[40:41], v[2:3] op_sel_hi:[1,0] neg_lo:[0,1] neg_hi:[0,1]
	v_pk_fma_f32 v[6:7], v[64:65], v[6:7], v[66:67]
	v_pk_mul_f32 v[2:3], v[2:3], v[40:41] op_sel:[1,0]
	v_and_b32_sdwa v40, v6, v216 dst_sel:DWORD dst_unused:UNUSED_PAD src0_sel:WORD_1 src1_sel:DWORD
	v_pk_fma_f32 v[2:3], v[0:1], v[2:3], v[4:5]
	v_add3_u32 v40, v6, v40, s82
	v_and_b32_e32 v42, 0xffff0000, v40
	v_and_b32_sdwa v40, v3, v216 dst_sel:DWORD dst_unused:UNUSED_PAD src0_sel:WORD_1 src1_sel:DWORD
	v_and_b32_sdwa v23, v7, v216 dst_sel:DWORD dst_unused:UNUSED_PAD src0_sel:WORD_1 src1_sel:DWORD
	v_and_b32_sdwa v41, v2, v216 dst_sel:DWORD dst_unused:UNUSED_PAD src0_sel:WORD_1 src1_sel:DWORD
	v_add3_u32 v40, v3, v40, s82
	v_add3_u32 v23, v7, v23, s82
	v_add3_u32 v43, v2, v41, s82
	v_and_b32_e32 v56, 0xffff0000, v40
	v_or_b32_sdwa v41, v56, v23 dst_sel:DWORD dst_unused:UNUSED_PAD src0_sel:DWORD src1_sel:WORD_1
	v_or_b32_sdwa v40, v43, v42 dst_sel:DWORD dst_unused:UNUSED_PAD src0_sel:WORD_1 src1_sel:DWORD
	ds_write_b64 v104, v[40:41]
	v_and_b32_e32 v40, 0xffff0000, v43
	v_sub_u32_e32 v6, v6, v42
	v_and_b32_e32 v23, 0xffff0000, v23
	v_sub_u32_e32 v2, v2, v40
	v_add_u32_e32 v6, 0x80, v6
	v_sub_u32_e32 v7, v7, v23
	v_sub_u32_e32 v3, v3, v56
	v_add_u32_e32 v2, 0x80, v2
	v_ashrrev_i32_e32 v6, 8, v6
	v_add_u32_e32 v7, 0x80, v7
	v_add_u32_e32 v3, 0x80, v3
	v_ashrrev_i32_e32 v2, 8, v2
	v_min_i32_e32 v6, 0x7f, v6
	v_ashrrev_i32_e32 v7, 8, v7
	v_ashrrev_i32_e32 v3, 8, v3
	v_min_i32_e32 v2, 0x7f, v2
	v_min_i32_sdwa v7, v7, s83 dst_sel:WORD_1 dst_unused:UNUSED_PAD src0_sel:DWORD src1_sel:DWORD
	v_min_i32_e32 v3, 0x7f, v3
	v_lshlrev_b32_e32 v6, 8, v6
	v_and_b32_e32 v6, 0xff00, v6
	v_and_b32_e32 v7, 0xff0000, v7
	v_perm_b32 v2, v3, v2, s84
	v_or3_b32 v2, v2, v6, v7
	ds_write_b32 v14, v2 offset:16
	buffer_store_dwordx4 v[160:163], v83, s[16:19], s33 offen
	ds_read_b64 v[2:3], v15 offset:1024
	s_waitcnt lgkmcnt(0)
;     ...
;           _Pragma("unroll") for (int bj = 0; bj < 2; ++bj) _Pragma("unroll") for (int n = 0; n < 2; ++n) {
;             const int cc = bj * HALF + wc3 * 32 + n * 16 + fq3 * 4;
;             const float4 gm = *reinterpret_cast<const float4*>(g.gam + pn * BM + cc), bt = *reinterpret_cast<const float4*>(g.bet + pn * BM + cc);
;             _Pragma("unroll") for (int m = 0; m < 4; ++m) {
;               const int rr = wr3 * 64 + m * 16 + fr3;
;               const float2 ms = *reinterpret_cast<const float2*>(mr + (ai * HALF + rr) * 2);
;               f32x4 y = acc[ai][bj][m][n];
;               const float o0 = (y[0] - ms.x) * ms.y * gm.x + bt.x, o1 = (y[1] - ms.x) * ms.y * gm.y + bt.y;
;               const float o2 = (y[2] - ms.x) * ms.y * gm.z + bt.z, o3 = (y[3] - ms.x) * ms.y * gm.w + bt.w;
;               const unsigned h0 = f2bf(o0), h1 = f2bf(o1), h2 = f2bf(o2), h3 = f2bf(o3);
;               u32x2 ob; ob[0] = h0 | (h1 << 16); ob[1] = h2 | (h3 << 16);
;               *reinterpret_cast<u32x2*>(smem + (rr >> 1) * PIECE + (rr & 1) * 512 + cc * 2) = ob;
;               const int l0 = min(((int)__float_as_uint(o0) - (int)(h0 << 16) + 128) >> 8, 127);
;               const int l1 = min(((int)__float_as_uint(o1) - (int)(h1 << 16) + 128) >> 8, 127);
;               const int l2 = min(((int)__float_as_uint(o2) - (int)(h2 << 16) + 128) >> 8, 127);
;               const int l3 = min(((int)__float_as_uint(o3) - (int)(h3 << 16) + 128) >> 8, 127);
;               *reinterpret_cast<unsigned*>(smem + LOBASE + (rr >> 2) * PIECE + (rr & 3) * 256 + cc) =
;                   (unsigned)(l0 & 255) | ((unsigned)(l1 & 255) << 8) | ((unsigned)(l2 & 255) << 16) | ((unsigned)l3 << 24);
;             }
;     ...
;           _Pragma("unroll") for (int i = 0; i < 8; ++i) {
;             const u32x4 v = *reinterpret_cast<const u32x4*>(smem + (wave * 8 + i) * PIECE + lane3 * 16);
;             __builtin_amdgcn_raw_buffer_store_b128(v, rsXB, hvo + i * (2 * DM * 2), hso, 0);
;           }
;           _Pragma("unroll") for (int i = 0; i < 4; ++i) {
;             const u32x4 v = *reinterpret_cast<const u32x4*>(smem + LOBASE + (wave * 4 + i) * PIECE + lane3 * 16);
;             __builtin_amdgcn_raw_buffer_store_b128(v, rsLO, lvo + i * (4 * DM), lso, 0);
;           }
	v_pk_add_f32 v[6:7], v[46:47], v[2:3] op_sel_hi:[1,0] neg_lo:[0,1] neg_hi:[0,1]
	s_nop 0
	v_pk_mul_f32 v[6:7], v[2:3], v[6:7] op_sel:[1,0]
	v_pk_add_f32 v[40:41], v[44:45], v[2:3] op_sel_hi:[1,0] neg_lo:[0,1] neg_hi:[0,1]
	v_pk_fma_f32 v[6:7], v[64:65], v[6:7], v[66:67]
	v_pk_mul_f32 v[2:3], v[2:3], v[40:41] op_sel:[1,0]
	v_and_b32_sdwa v40, v6, v216 dst_sel:DWORD dst_unused:UNUSED_PAD src0_sel:WORD_1 src1_sel:DWORD
	v_pk_fma_f32 v[2:3], v[0:1], v[2:3], v[4:5]
	v_add3_u32 v40, v6, v40, s82
	v_and_b32_e32 v42, 0xffff0000, v40
	v_and_b32_sdwa v40, v3, v216 dst_sel:DWORD dst_unused:UNUSED_PAD src0_sel:WORD_1 src1_sel:DWORD
	v_and_b32_sdwa v23, v7, v216 dst_sel:DWORD dst_unused:UNUSED_PAD src0_sel:WORD_1 src1_sel:DWORD
	v_and_b32_sdwa v41, v2, v216 dst_sel:DWORD dst_unused:UNUSED_PAD src0_sel:WORD_1 src1_sel:DWORD
	v_add3_u32 v40, v3, v40, s82
	v_add3_u32 v23, v7, v23, s82
	v_add3_u32 v43, v2, v41, s82
	v_and_b32_e32 v44, 0xffff0000, v40
	v_or_b32_sdwa v41, v44, v23 dst_sel:DWORD dst_unused:UNUSED_PAD src0_sel:DWORD src1_sel:WORD_1
	v_or_b32_sdwa v40, v43, v42 dst_sel:DWORD dst_unused:UNUSED_PAD src0_sel:WORD_1 src1_sel:DWORD
	ds_write_b64 v105, v[40:41]
	v_and_b32_e32 v40, 0xffff0000, v43
	v_sub_u32_e32 v6, v6, v42
	v_and_b32_e32 v23, 0xffff0000, v23
	v_sub_u32_e32 v2, v2, v40
	v_add_u32_e32 v6, 0x80, v6
	v_sub_u32_e32 v7, v7, v23
	v_sub_u32_e32 v3, v3, v44
	v_add_u32_e32 v2, 0x80, v2
	v_ashrrev_i32_e32 v6, 8, v6
	v_add_u32_e32 v7, 0x80, v7
	v_add_u32_e32 v3, 0x80, v3
	v_ashrrev_i32_e32 v2, 8, v2
	v_min_i32_e32 v6, 0x7f, v6
	v_ashrrev_i32_e32 v7, 8, v7
	v_ashrrev_i32_e32 v3, 8, v3
	v_min_i32_e32 v2, 0x7f, v2
	v_min_i32_sdwa v7, v7, s83 dst_sel:WORD_1 dst_unused:UNUSED_PAD src0_sel:DWORD src1_sel:DWORD
	v_min_i32_e32 v3, 0x7f, v3
	v_lshlrev_b32_e32 v6, 8, v6
	v_and_b32_e32 v6, 0xff00, v6
	v_and_b32_e32 v7, 0xff0000, v7
	v_perm_b32 v2, v3, v2, s84
	v_or3_b32 v2, v2, v6, v7
	ds_write_b32 v20, v2 offset:16
	buffer_store_dwordx4 v[164:167], v88, s[16:19], s33 offen
	ds_read_b64 v[2:3], v21 offset:1024
	s_waitcnt lgkmcnt(0)
	v_pk_add_f32 v[6:7], v[62:63], v[2:3] op_sel_hi:[1,0] neg_lo:[0,1] neg_hi:[0,1]
	s_nop 0
	v_pk_mul_f32 v[6:7], v[2:3], v[6:7] op_sel:[1,0]
	v_pk_add_f32 v[40:41], v[60:61], v[2:3] op_sel_hi:[1,0] neg_lo:[0,1] neg_hi:[0,1]
	v_pk_fma_f32 v[6:7], v[64:65], v[6:7], v[66:67]
	v_pk_mul_f32 v[2:3], v[2:3], v[40:41] op_sel:[1,0]
	s_nop 0
	v_pk_fma_f32 v[0:1], v[0:1], v[2:3], v[4:5]
	v_and_b32_sdwa v2, v7, v216 dst_sel:DWORD dst_unused:UNUSED_PAD src0_sel:WORD_1 src1_sel:DWORD
	v_and_b32_sdwa v3, v6, v216 dst_sel:DWORD dst_unused:UNUSED_PAD src0_sel:WORD_1 src1_sel:DWORD
	v_add3_u32 v4, v7, v2, s82
	v_add3_u32 v2, v6, v3, s82
	v_and_b32_e32 v5, 0xffff0000, v2
	v_and_b32_sdwa v2, v1, v216 dst_sel:DWORD dst_unused:UNUSED_PAD src0_sel:WORD_1 src1_sel:DWORD
	v_and_b32_sdwa v3, v0, v216 dst_sel:DWORD dst_unused:UNUSED_PAD src0_sel:WORD_1 src1_sel:DWORD
	v_add3_u32 v2, v1, v2, s82
	v_add3_u32 v23, v0, v3, s82
	v_and_b32_e32 v40, 0xffff0000, v2
	v_or_b32_sdwa v3, v40, v4 dst_sel:DWORD dst_unused:UNUSED_PAD src0_sel:DWORD src1_sel:WORD_1
	v_or_b32_sdwa v2, v23, v5 dst_sel:DWORD dst_unused:UNUSED_PAD src0_sel:WORD_1 src1_sel:DWORD
	ds_write_b64 v106, v[2:3]
	v_and_b32_e32 v2, 0xffff0000, v23
	v_sub_u32_e32 v0, v0, v2
	v_sub_u32_e32 v2, v6, v5
	v_and_b32_e32 v3, 0xffff0000, v4
	v_add_u32_e32 v2, 0x80, v2
	v_sub_u32_e32 v3, v7, v3
	v_sub_u32_e32 v1, v1, v40
	v_add_u32_e32 v0, 0x80, v0
	v_ashrrev_i32_e32 v2, 8, v2
	v_add_u32_e32 v3, 0x80, v3
	v_add_u32_e32 v1, 0x80, v1
	v_ashrrev_i32_e32 v0, 8, v0
	v_min_i32_e32 v2, 0x7f, v2
	v_ashrrev_i32_e32 v3, 8, v3
	v_ashrrev_i32_e32 v1, 8, v1
	v_min_i32_e32 v0, 0x7f, v0
	v_min_i32_sdwa v3, v3, s83 dst_sel:WORD_1 dst_unused:UNUSED_PAD src0_sel:DWORD src1_sel:DWORD
	v_min_i32_e32 v1, 0x7f, v1
	v_lshlrev_b32_e32 v2, 8, v2
	v_and_b32_e32 v2, 0xff00, v2
	v_and_b32_e32 v3, 0xff0000, v3
	v_perm_b32 v0, v1, v0, s84
	v_or3_b32 v0, v0, v2, v3
	ds_write_b32 v22, v0 offset:16
	buffer_store_dwordx4 v[168:171], v89, s[16:19], s33 offen
	v_mov_b32_e32 v0, v228
	v_mov_b32_e32 v1, v229
	v_mov_b32_e32 v2, v230
	v_mov_b32_e32 v3, v231
	v_mov_b32_e32 v4, v244
	v_mov_b32_e32 v5, v245
	v_mov_b32_e32 v6, v246
	v_mov_b32_e32 v7, v247
	ds_read_b64 v[44:45], v149 offset:1024
	s_waitcnt lgkmcnt(0)
	v_pk_add_f32 v[46:47], v[54:55], v[44:45] op_sel_hi:[1,0] neg_lo:[0,1] neg_hi:[0,1]
	s_nop 0
	v_pk_mul_f32 v[46:47], v[44:45], v[46:47] op_sel:[1,0]
	v_pk_add_f32 v[52:53], v[52:53], v[44:45] op_sel_hi:[1,0] neg_lo:[0,1] neg_hi:[0,1]
	v_mov_b32_e32 v40, v1
	v_mov_b32_e32 v41, v2
	v_mov_b32_e32 v42, v5
	v_mov_b32_e32 v43, v6
	v_pk_fma_f32 v[46:47], v[40:41], v[46:47], v[42:43]
	v_pk_mul_f32 v[44:45], v[44:45], v[52:53] op_sel:[1,0]
	v_mov_b32_e32 v1, v3
	v_mov_b32_e32 v5, v7
	v_and_b32_sdwa v6, v47, v216 dst_sel:DWORD dst_unused:UNUSED_PAD src0_sel:WORD_1 src1_sel:DWORD
	v_and_b32_sdwa v7, v46, v216 dst_sel:DWORD dst_unused:UNUSED_PAD src0_sel:WORD_1 src1_sel:DWORD
	v_pk_fma_f32 v[2:3], v[0:1], v[44:45], v[4:5]
	v_add3_u32 v23, v47, v6, s82
	v_add3_u32 v6, v46, v7, s82
	v_and_b32_e32 v44, 0xffff0000, v6
	v_and_b32_sdwa v6, v3, v216 dst_sel:DWORD dst_unused:UNUSED_PAD src0_sel:WORD_1 src1_sel:DWORD
	v_and_b32_sdwa v7, v2, v216 dst_sel:DWORD dst_unused:UNUSED_PAD src0_sel:WORD_1 src1_sel:DWORD
	v_add3_u32 v6, v3, v6, s82
	v_add3_u32 v45, v2, v7, s82
	v_and_b32_e32 v52, 0xffff0000, v6
	v_or_b32_sdwa v7, v52, v23 dst_sel:DWORD dst_unused:UNUSED_PAD src0_sel:DWORD src1_sel:WORD_1
	v_or_b32_sdwa v6, v45, v44 dst_sel:DWORD dst_unused:UNUSED_PAD src0_sel:WORD_1 src1_sel:DWORD
	ds_write_b64 v107, v[6:7]
	v_and_b32_e32 v6, 0xffff0000, v45
	v_sub_u32_e32 v2, v2, v6
	v_sub_u32_e32 v6, v46, v44
	v_and_b32_e32 v7, 0xffff0000, v23
	v_add_u32_e32 v6, 0x80, v6
	v_sub_u32_e32 v7, v47, v7
	v_sub_u32_e32 v3, v3, v52
	v_add_u32_e32 v2, 0x80, v2
	v_ashrrev_i32_e32 v6, 8, v6
	v_add_u32_e32 v7, 0x80, v7
	v_add_u32_e32 v3, 0x80, v3
	v_ashrrev_i32_e32 v2, 8, v2
	v_min_i32_e32 v6, 0x7f, v6
	v_ashrrev_i32_e32 v7, 8, v7
	v_ashrrev_i32_e32 v3, 8, v3
	v_min_i32_e32 v2, 0x7f, v2
	v_min_i32_sdwa v7, v7, s83 dst_sel:WORD_1 dst_unused:UNUSED_PAD src0_sel:DWORD src1_sel:DWORD
	v_min_i32_e32 v3, 0x7f, v3
	v_lshlrev_b32_e32 v6, 8, v6
	v_and_b32_e32 v6, 0xff00, v6
	v_and_b32_e32 v7, 0xff0000, v7
	v_perm_b32 v2, v3, v2, s84
	v_or3_b32 v2, v2, v6, v7
	ds_write_b32 v12, v2 offset:128
	buffer_store_dwordx4 v[172:175], v146, s[20:23], s0 offen
	ds_read_b64 v[2:3], v13 offset:1024
	s_waitcnt lgkmcnt(0)
;     ...
;           _Pragma("unroll") for (int bj = 0; bj < 2; ++bj) _Pragma("unroll") for (int n = 0; n < 2; ++n) {
;             const int cc = bj * HALF + wc3 * 32 + n * 16 + fq3 * 4;
;             const float4 gm = *reinterpret_cast<const float4*>(g.gam + pn * BM + cc), bt = *reinterpret_cast<const float4*>(g.bet + pn * BM + cc);
;             _Pragma("unroll") for (int m = 0; m < 4; ++m) {
;               const int rr = wr3 * 64 + m * 16 + fr3;
;               const float2 ms = *reinterpret_cast<const float2*>(mr + (ai * HALF + rr) * 2);
;               f32x4 y = acc[ai][bj][m][n];
;               const float o0 = (y[0] - ms.x) * ms.y * gm.x + bt.x, o1 = (y[1] - ms.x) * ms.y * gm.y + bt.y;
;               const float o2 = (y[2] - ms.x) * ms.y * gm.z + bt.z, o3 = (y[3] - ms.x) * ms.y * gm.w + bt.w;
;               const unsigned h0 = f2bf(o0), h1 = f2bf(o1), h2 = f2bf(o2), h3 = f2bf(o3);
;               u32x2 ob; ob[0] = h0 | (h1 << 16); ob[1] = h2 | (h3 << 16);
;               *reinterpret_cast<u32x2*>(smem + (rr >> 1) * PIECE + (rr & 1) * 512 + cc * 2) = ob;
;               const int l0 = min(((int)__float_as_uint(o0) - (int)(h0 << 16) + 128) >> 8, 127);
;               const int l1 = min(((int)__float_as_uint(o1) - (int)(h1 << 16) + 128) >> 8, 127);
;               const int l2 = min(((int)__float_as_uint(o2) - (int)(h2 << 16) + 128) >> 8, 127);
;               const int l3 = min(((int)__float_as_uint(o3) - (int)(h3 << 16) + 128) >> 8, 127);
;               *reinterpret_cast<unsigned*>(smem + LOBASE + (rr >> 2) * PIECE + (rr & 3) * 256 + cc) =
;                   (unsigned)(l0 & 255) | ((unsigned)(l1 & 255) << 8) | ((unsigned)(l2 & 255) << 16) | ((unsigned)l3 << 24);
;             }
;     ...
;           _Pragma("unroll") for (int i = 0; i < 8; ++i) {
;             const u32x4 v = *reinterpret_cast<const u32x4*>(smem + (wave * 8 + i) * PIECE + lane3 * 16);
;             __builtin_amdgcn_raw_buffer_store_b128(v, rsXB, hvo + i * (2 * DM * 2), hso, 0);
;           }
;           _Pragma("unroll") for (int i = 0; i < 4; ++i) {
;             const u32x4 v = *reinterpret_cast<const u32x4*>(smem + LOBASE + (wave * 4 + i) * PIECE + lane3 * 16);
;             __builtin_amdgcn_raw_buffer_store_b128(v, rsLO, lvo + i * (4 * DM), lso, 0);
;           }
	v_pk_add_f32 v[6:7], v[38:39], v[2:3] op_sel_hi:[1,0] neg_lo:[0,1] neg_hi:[0,1]
	s_nop 0
	v_pk_mul_f32 v[6:7], v[2:3], v[6:7] op_sel:[1,0]
	v_pk_add_f32 v[36:37], v[36:37], v[2:3] op_sel_hi:[1,0] neg_lo:[0,1] neg_hi:[0,1]
	v_pk_fma_f32 v[6:7], v[40:41], v[6:7], v[42:43]
	v_pk_mul_f32 v[2:3], v[2:3], v[36:37] op_sel:[1,0]
	v_and_b32_sdwa v36, v6, v216 dst_sel:DWORD dst_unused:UNUSED_PAD src0_sel:WORD_1 src1_sel:DWORD
	v_pk_fma_f32 v[2:3], v[0:1], v[2:3], v[4:5]
	v_add3_u32 v36, v6, v36, s82
	v_and_b32_e32 v38, 0xffff0000, v36
	v_and_b32_sdwa v36, v3, v216 dst_sel:DWORD dst_unused:UNUSED_PAD src0_sel:WORD_1 src1_sel:DWORD
	v_and_b32_sdwa v23, v7, v216 dst_sel:DWORD dst_unused:UNUSED_PAD src0_sel:WORD_1 src1_sel:DWORD
	v_and_b32_sdwa v37, v2, v216 dst_sel:DWORD dst_unused:UNUSED_PAD src0_sel:WORD_1 src1_sel:DWORD
	v_add3_u32 v36, v3, v36, s82
	v_add3_u32 v23, v7, v23, s82
	v_add3_u32 v39, v2, v37, s82
	v_and_b32_e32 v44, 0xffff0000, v36
	v_or_b32_sdwa v37, v44, v23 dst_sel:DWORD dst_unused:UNUSED_PAD src0_sel:DWORD src1_sel:WORD_1
	v_or_b32_sdwa v36, v39, v38 dst_sel:DWORD dst_unused:UNUSED_PAD src0_sel:WORD_1 src1_sel:DWORD
	ds_write_b64 v100, v[36:37]
	v_and_b32_e32 v36, 0xffff0000, v39
	v_sub_u32_e32 v6, v6, v38
	v_and_b32_e32 v23, 0xffff0000, v23
	v_sub_u32_e32 v2, v2, v36
	v_add_u32_e32 v6, 0x80, v6
	v_sub_u32_e32 v7, v7, v23
	v_sub_u32_e32 v3, v3, v44
	v_add_u32_e32 v2, 0x80, v2
	v_ashrrev_i32_e32 v6, 8, v6
	v_add_u32_e32 v7, 0x80, v7
	v_add_u32_e32 v3, 0x80, v3
	v_ashrrev_i32_e32 v2, 8, v2
	v_min_i32_e32 v6, 0x7f, v6
	v_ashrrev_i32_e32 v7, 8, v7
	v_ashrrev_i32_e32 v3, 8, v3
	v_min_i32_e32 v2, 0x7f, v2
	v_min_i32_sdwa v7, v7, s83 dst_sel:WORD_1 dst_unused:UNUSED_PAD src0_sel:DWORD src1_sel:DWORD
	v_min_i32_e32 v3, 0x7f, v3
	v_lshlrev_b32_e32 v6, 8, v6
	v_and_b32_e32 v6, 0xff00, v6
	v_and_b32_e32 v7, 0xff0000, v7
	v_perm_b32 v2, v3, v2, s84
	v_or3_b32 v2, v2, v6, v7
	ds_write_b32 v14, v2 offset:128
	buffer_store_dwordx4 v[176:179], v90, s[20:23], s0 offen
	ds_read_b64 v[2:3], v15 offset:1024
	s_waitcnt lgkmcnt(0)
	v_pk_add_f32 v[6:7], v[26:27], v[2:3] op_sel_hi:[1,0] neg_lo:[0,1] neg_hi:[0,1]
	s_nop 0
	v_pk_mul_f32 v[6:7], v[2:3], v[6:7] op_sel:[1,0]
	v_pk_add_f32 v[24:25], v[24:25], v[2:3] op_sel_hi:[1,0] neg_lo:[0,1] neg_hi:[0,1]
	v_pk_fma_f32 v[6:7], v[40:41], v[6:7], v[42:43]
	v_pk_mul_f32 v[2:3], v[2:3], v[24:25] op_sel:[1,0]
	v_and_b32_sdwa v24, v6, v216 dst_sel:DWORD dst_unused:UNUSED_PAD src0_sel:WORD_1 src1_sel:DWORD
	v_pk_fma_f32 v[2:3], v[0:1], v[2:3], v[4:5]
	v_add3_u32 v24, v6, v24, s82
	v_and_b32_e32 v26, 0xffff0000, v24
	v_and_b32_sdwa v24, v3, v216 dst_sel:DWORD dst_unused:UNUSED_PAD src0_sel:WORD_1 src1_sel:DWORD
	v_and_b32_sdwa v23, v7, v216 dst_sel:DWORD dst_unused:UNUSED_PAD src0_sel:WORD_1 src1_sel:DWORD
	v_and_b32_sdwa v25, v2, v216 dst_sel:DWORD dst_unused:UNUSED_PAD src0_sel:WORD_1 src1_sel:DWORD
	v_add3_u32 v24, v3, v24, s82
	v_add3_u32 v23, v7, v23, s82
	v_add3_u32 v27, v2, v25, s82
	v_and_b32_e32 v36, 0xffff0000, v24
	v_or_b32_sdwa v25, v36, v23 dst_sel:DWORD dst_unused:UNUSED_PAD src0_sel:DWORD src1_sel:WORD_1
	v_or_b32_sdwa v24, v27, v26 dst_sel:DWORD dst_unused:UNUSED_PAD src0_sel:WORD_1 src1_sel:DWORD
	ds_write_b64 v101, v[24:25]
	v_and_b32_e32 v24, 0xffff0000, v27
	v_sub_u32_e32 v6, v6, v26
	v_and_b32_e32 v23, 0xffff0000, v23
	v_sub_u32_e32 v2, v2, v24
	v_add_u32_e32 v6, 0x80, v6
	v_sub_u32_e32 v7, v7, v23
	v_sub_u32_e32 v3, v3, v36
	v_add_u32_e32 v2, 0x80, v2
	v_ashrrev_i32_e32 v6, 8, v6
	v_add_u32_e32 v7, 0x80, v7
	v_add_u32_e32 v3, 0x80, v3
	v_ashrrev_i32_e32 v2, 8, v2
	v_min_i32_e32 v6, 0x7f, v6
	v_ashrrev_i32_e32 v7, 8, v7
	v_ashrrev_i32_e32 v3, 8, v3
	v_min_i32_e32 v2, 0x7f, v2
	v_min_i32_sdwa v7, v7, s83 dst_sel:WORD_1 dst_unused:UNUSED_PAD src0_sel:DWORD src1_sel:DWORD
	v_min_i32_e32 v3, 0x7f, v3
	v_lshlrev_b32_e32 v6, 8, v6
	v_and_b32_e32 v6, 0xff00, v6
	v_and_b32_e32 v7, 0xff0000, v7
	v_perm_b32 v2, v3, v2, s84
	v_or3_b32 v2, v2, v6, v7
	ds_write_b32 v20, v2 offset:128
	buffer_store_dwordx4 v[180:183], v91, s[20:23], s0 offen
	ds_read_b64 v[2:3], v21 offset:1024
	s_waitcnt lgkmcnt(0)
	v_pk_add_f32 v[6:7], v[30:31], v[2:3] op_sel_hi:[1,0] neg_lo:[0,1] neg_hi:[0,1]
	s_nop 0
	v_pk_mul_f32 v[6:7], v[2:3], v[6:7] op_sel:[1,0]
	v_pk_add_f32 v[24:25], v[28:29], v[2:3] op_sel_hi:[1,0] neg_lo:[0,1] neg_hi:[0,1]
	v_pk_fma_f32 v[6:7], v[40:41], v[6:7], v[42:43]
	v_pk_mul_f32 v[2:3], v[2:3], v[24:25] op_sel:[1,0]
	s_nop 0
	v_pk_fma_f32 v[0:1], v[0:1], v[2:3], v[4:5]
	v_and_b32_sdwa v2, v7, v216 dst_sel:DWORD dst_unused:UNUSED_PAD src0_sel:WORD_1 src1_sel:DWORD
	v_and_b32_sdwa v3, v6, v216 dst_sel:DWORD dst_unused:UNUSED_PAD src0_sel:WORD_1 src1_sel:DWORD
	v_add3_u32 v4, v7, v2, s82
	v_add3_u32 v2, v6, v3, s82
	v_and_b32_e32 v5, 0xffff0000, v2
	v_and_b32_sdwa v2, v1, v216 dst_sel:DWORD dst_unused:UNUSED_PAD src0_sel:WORD_1 src1_sel:DWORD
	v_and_b32_sdwa v3, v0, v216 dst_sel:DWORD dst_unused:UNUSED_PAD src0_sel:WORD_1 src1_sel:DWORD
	v_add3_u32 v2, v1, v2, s82
	v_add3_u32 v23, v0, v3, s82
	v_and_b32_e32 v24, 0xffff0000, v2
	v_or_b32_sdwa v3, v24, v4 dst_sel:DWORD dst_unused:UNUSED_PAD src0_sel:DWORD src1_sel:WORD_1
	v_or_b32_sdwa v2, v23, v5 dst_sel:DWORD dst_unused:UNUSED_PAD src0_sel:WORD_1 src1_sel:DWORD
	ds_write_b64 v92, v[2:3]
	v_and_b32_e32 v2, 0xffff0000, v23
	v_sub_u32_e32 v0, v0, v2
	v_sub_u32_e32 v2, v6, v5
	v_and_b32_e32 v3, 0xffff0000, v4
	v_add_u32_e32 v2, 0x80, v2
	v_sub_u32_e32 v3, v7, v3
	v_sub_u32_e32 v1, v1, v24
	v_add_u32_e32 v0, 0x80, v0
	v_ashrrev_i32_e32 v2, 8, v2
	v_add_u32_e32 v3, 0x80, v3
	v_add_u32_e32 v1, 0x80, v1
	v_ashrrev_i32_e32 v0, 8, v0
	v_min_i32_e32 v2, 0x7f, v2
	v_ashrrev_i32_e32 v3, 8, v3
	v_ashrrev_i32_e32 v1, 8, v1
	v_min_i32_e32 v0, 0x7f, v0
	v_min_i32_sdwa v3, v3, s83 dst_sel:WORD_1 dst_unused:UNUSED_PAD src0_sel:DWORD src1_sel:DWORD
	v_min_i32_e32 v1, 0x7f, v1
	v_lshlrev_b32_e32 v2, 8, v2
	v_and_b32_e32 v2, 0xff00, v2
	v_and_b32_e32 v3, 0xff0000, v3
	v_perm_b32 v0, v1, v0, s84
	v_or3_b32 v0, v0, v2, v3
	ds_write_b32 v22, v0 offset:128
	buffer_store_dwordx4 v[184:187], v95, s[20:23], s0 offen
	v_mov_b32_e32 v0, v232
	v_mov_b32_e32 v1, v233
	v_mov_b32_e32 v2, v234
	v_mov_b32_e32 v3, v235
	v_mov_b32_e32 v4, v248
	v_mov_b32_e32 v5, v249
	v_mov_b32_e32 v6, v250
	v_mov_b32_e32 v7, v251
	ds_read_b64 v[28:29], v149 offset:1024
	s_mov_b64 s[4:5], -1
	s_waitcnt lgkmcnt(0)
;     ...
;             _Pragma("unroll") for (int m = 0; m < 4; ++m) {
;               const int rr = wr3 * 64 + m * 16 + fr3;
;               const float2 ms = *reinterpret_cast<const float2*>(mr + (ai * HALF + rr) * 2);
;               f32x4 y = acc[ai][bj][m][n];
;               const float o0 = (y[0] - ms.x) * ms.y * gm.x + bt.x, o1 = (y[1] - ms.x) * ms.y * gm.y + bt.y;
;               const float o2 = (y[2] - ms.x) * ms.y * gm.z + bt.z, o3 = (y[3] - ms.x) * ms.y * gm.w + bt.w;
;               const unsigned h0 = f2bf(o0), h1 = f2bf(o1), h2 = f2bf(o2), h3 = f2bf(o3);
;               u32x2 ob; ob[0] = h0 | (h1 << 16); ob[1] = h2 | (h3 << 16);
;               *reinterpret_cast<u32x2*>(smem + (rr >> 1) * PIECE + (rr & 1) * 512 + cc * 2) = ob;
;               const int l0 = min(((int)__float_as_uint(o0) - (int)(h0 << 16) + 128) >> 8, 127);
;               const int l1 = min(((int)__float_as_uint(o1) - (int)(h1 << 16) + 128) >> 8, 127);
;               const int l2 = min(((int)__float_as_uint(o2) - (int)(h2 << 16) + 128) >> 8, 127);
;               const int l3 = min(((int)__float_as_uint(o3) - (int)(h3 << 16) + 128) >> 8, 127);
;               *reinterpret_cast<unsigned*>(smem + LOBASE + (rr >> 2) * PIECE + (rr & 3) * 256 + cc) =
;                   (unsigned)(l0 & 255) | ((unsigned)(l1 & 255) << 8) | ((unsigned)(l2 & 255) << 16) | ((unsigned)l3 << 24);
;             }
	v_pk_add_f32 v[30:31], v[50:51], v[28:29] op_sel_hi:[1,0] neg_lo:[0,1] neg_hi:[0,1]
	s_nop 0
	v_pk_mul_f32 v[30:31], v[28:29], v[30:31] op_sel:[1,0]
	v_pk_add_f32 v[36:37], v[48:49], v[28:29] op_sel_hi:[1,0] neg_lo:[0,1] neg_hi:[0,1]
	v_mov_b32_e32 v24, v1
	v_mov_b32_e32 v25, v2
	v_mov_b32_e32 v26, v5
	v_mov_b32_e32 v27, v6
	v_pk_fma_f32 v[30:31], v[24:25], v[30:31], v[26:27]
	v_pk_mul_f32 v[28:29], v[28:29], v[36:37] op_sel:[1,0]
	v_mov_b32_e32 v1, v3
	v_mov_b32_e32 v5, v7
	v_and_b32_sdwa v6, v31, v216 dst_sel:DWORD dst_unused:UNUSED_PAD src0_sel:WORD_1 src1_sel:DWORD
	v_and_b32_sdwa v7, v30, v216 dst_sel:DWORD dst_unused:UNUSED_PAD src0_sel:WORD_1 src1_sel:DWORD
	v_pk_fma_f32 v[2:3], v[0:1], v[28:29], v[4:5]
	v_add3_u32 v23, v31, v6, s82
	v_add3_u32 v6, v30, v7, s82
	v_and_b32_e32 v28, 0xffff0000, v6
	v_and_b32_sdwa v6, v3, v216 dst_sel:DWORD dst_unused:UNUSED_PAD src0_sel:WORD_1 src1_sel:DWORD
	v_and_b32_sdwa v7, v2, v216 dst_sel:DWORD dst_unused:UNUSED_PAD src0_sel:WORD_1 src1_sel:DWORD
	v_add3_u32 v6, v3, v6, s82
	v_add3_u32 v29, v2, v7, s82
	v_and_b32_e32 v36, 0xffff0000, v6
	v_or_b32_sdwa v7, v36, v23 dst_sel:DWORD dst_unused:UNUSED_PAD src0_sel:DWORD src1_sel:WORD_1
	v_or_b32_sdwa v6, v29, v28 dst_sel:DWORD dst_unused:UNUSED_PAD src0_sel:WORD_1 src1_sel:DWORD
	ds_write_b64 v93, v[6:7]
	v_and_b32_e32 v6, 0xffff0000, v29
	v_sub_u32_e32 v2, v2, v6
	v_sub_u32_e32 v6, v30, v28
	v_and_b32_e32 v7, 0xffff0000, v23
	v_add_u32_e32 v6, 0x80, v6
	v_sub_u32_e32 v7, v31, v7
	v_sub_u32_e32 v3, v3, v36
	v_add_u32_e32 v2, 0x80, v2
	v_ashrrev_i32_e32 v6, 8, v6
	v_add_u32_e32 v7, 0x80, v7
	v_add_u32_e32 v3, 0x80, v3
	v_ashrrev_i32_e32 v2, 8, v2
	v_min_i32_e32 v6, 0x7f, v6
	v_ashrrev_i32_e32 v7, 8, v7
	v_ashrrev_i32_e32 v3, 8, v3
	v_min_i32_e32 v2, 0x7f, v2
	v_min_i32_sdwa v7, v7, s83 dst_sel:WORD_1 dst_unused:UNUSED_PAD src0_sel:DWORD src1_sel:DWORD
	v_min_i32_e32 v3, 0x7f, v3
	v_lshlrev_b32_e32 v6, 8, v6
	v_and_b32_e32 v6, 0xff00, v6
	v_and_b32_e32 v7, 0xff0000, v7
	v_perm_b32 v2, v3, v2, s84
	v_or3_b32 v2, v2, v6, v7
	ds_write_b32 v12, v2 offset:144
	ds_read_b64 v[2:3], v13 offset:1024
	s_waitcnt lgkmcnt(0)
	v_pk_add_f32 v[6:7], v[34:35], v[2:3] op_sel_hi:[1,0] neg_lo:[0,1] neg_hi:[0,1]
	s_nop 0
	v_pk_mul_f32 v[6:7], v[2:3], v[6:7] op_sel:[1,0]
	v_pk_add_f32 v[12:13], v[32:33], v[2:3] op_sel_hi:[1,0] neg_lo:[0,1] neg_hi:[0,1]
	v_pk_fma_f32 v[6:7], v[24:25], v[6:7], v[26:27]
	v_pk_mul_f32 v[2:3], v[2:3], v[12:13] op_sel:[1,0]
	v_and_b32_sdwa v12, v7, v216 dst_sel:DWORD dst_unused:UNUSED_PAD src0_sel:WORD_1 src1_sel:DWORD
	v_and_b32_sdwa v13, v6, v216 dst_sel:DWORD dst_unused:UNUSED_PAD src0_sel:WORD_1 src1_sel:DWORD
	v_pk_fma_f32 v[2:3], v[0:1], v[2:3], v[4:5]
	v_add3_u32 v23, v7, v12, s82
	v_add3_u32 v12, v6, v13, s82
	v_and_b32_e32 v28, 0xffff0000, v12
	v_and_b32_sdwa v12, v3, v216 dst_sel:DWORD dst_unused:UNUSED_PAD src0_sel:WORD_1 src1_sel:DWORD
	v_and_b32_sdwa v13, v2, v216 dst_sel:DWORD dst_unused:UNUSED_PAD src0_sel:WORD_1 src1_sel:DWORD
	v_add3_u32 v12, v3, v12, s82
	v_add3_u32 v29, v2, v13, s82
	v_and_b32_e32 v30, 0xffff0000, v12
	v_or_b32_sdwa v13, v30, v23 dst_sel:DWORD dst_unused:UNUSED_PAD src0_sel:DWORD src1_sel:WORD_1
	v_or_b32_sdwa v12, v29, v28 dst_sel:DWORD dst_unused:UNUSED_PAD src0_sel:WORD_1 src1_sel:DWORD
	ds_write_b64 v94, v[12:13]
	v_and_b32_e32 v12, 0xffff0000, v29
	v_sub_u32_e32 v2, v2, v12
	v_sub_u32_e32 v6, v6, v28
	v_and_b32_e32 v12, 0xffff0000, v23
	v_add_u32_e32 v6, 0x80, v6
	v_sub_u32_e32 v7, v7, v12
	v_sub_u32_e32 v3, v3, v30
	v_add_u32_e32 v2, 0x80, v2
	v_ashrrev_i32_e32 v6, 8, v6
	v_add_u32_e32 v7, 0x80, v7
	v_add_u32_e32 v3, 0x80, v3
	v_ashrrev_i32_e32 v2, 8, v2
	v_min_i32_e32 v6, 0x7f, v6
	v_ashrrev_i32_e32 v7, 8, v7
	v_ashrrev_i32_e32 v3, 8, v3
	v_min_i32_e32 v2, 0x7f, v2
	v_min_i32_sdwa v7, v7, s83 dst_sel:WORD_1 dst_unused:UNUSED_PAD src0_sel:DWORD src1_sel:DWORD
	v_min_i32_e32 v3, 0x7f, v3
	v_lshlrev_b32_e32 v6, 8, v6
	v_and_b32_e32 v6, 0xff00, v6
	v_and_b32_e32 v7, 0xff0000, v7
	v_perm_b32 v2, v3, v2, s84
	v_or3_b32 v2, v2, v6, v7
	ds_write_b32 v14, v2 offset:144
	ds_read_b64 v[2:3], v15 offset:1024
	s_waitcnt lgkmcnt(0)
	v_pk_add_f32 v[6:7], v[18:19], v[2:3] op_sel_hi:[1,0] neg_lo:[0,1] neg_hi:[0,1]
	s_nop 0
	v_pk_mul_f32 v[6:7], v[2:3], v[6:7] op_sel:[1,0]
	v_pk_add_f32 v[12:13], v[16:17], v[2:3] op_sel_hi:[1,0] neg_lo:[0,1] neg_hi:[0,1]
	v_pk_fma_f32 v[6:7], v[24:25], v[6:7], v[26:27]
	v_pk_mul_f32 v[2:3], v[2:3], v[12:13] op_sel:[1,0]
	v_and_b32_sdwa v12, v7, v216 dst_sel:DWORD dst_unused:UNUSED_PAD src0_sel:WORD_1 src1_sel:DWORD
	v_and_b32_sdwa v13, v6, v216 dst_sel:DWORD dst_unused:UNUSED_PAD src0_sel:WORD_1 src1_sel:DWORD
	v_pk_fma_f32 v[2:3], v[0:1], v[2:3], v[4:5]
	v_add3_u32 v14, v7, v12, s82
	v_add3_u32 v12, v6, v13, s82
	v_and_b32_e32 v15, 0xffff0000, v12
	v_and_b32_sdwa v12, v3, v216 dst_sel:DWORD dst_unused:UNUSED_PAD src0_sel:WORD_1 src1_sel:DWORD
	v_and_b32_sdwa v13, v2, v216 dst_sel:DWORD dst_unused:UNUSED_PAD src0_sel:WORD_1 src1_sel:DWORD
	v_add3_u32 v12, v3, v12, s82
	v_add3_u32 v16, v2, v13, s82
	v_and_b32_e32 v17, 0xffff0000, v12
	v_or_b32_sdwa v13, v17, v14 dst_sel:DWORD dst_unused:UNUSED_PAD src0_sel:DWORD src1_sel:WORD_1
	v_or_b32_sdwa v12, v16, v15 dst_sel:DWORD dst_unused:UNUSED_PAD src0_sel:WORD_1 src1_sel:DWORD
	ds_write_b64 v80, v[12:13]
	v_and_b32_e32 v12, 0xffff0000, v16
	v_sub_u32_e32 v2, v2, v12
	v_sub_u32_e32 v6, v6, v15
	v_and_b32_e32 v12, 0xffff0000, v14
	v_add_u32_e32 v6, 0x80, v6
	v_sub_u32_e32 v7, v7, v12
	v_sub_u32_e32 v3, v3, v17
	v_add_u32_e32 v2, 0x80, v2
	v_ashrrev_i32_e32 v6, 8, v6
	v_add_u32_e32 v7, 0x80, v7
	v_add_u32_e32 v3, 0x80, v3
	v_ashrrev_i32_e32 v2, 8, v2
	v_min_i32_e32 v6, 0x7f, v6
	v_ashrrev_i32_e32 v7, 8, v7
	v_ashrrev_i32_e32 v3, 8, v3
	v_min_i32_e32 v2, 0x7f, v2
	v_min_i32_sdwa v7, v7, s83 dst_sel:WORD_1 dst_unused:UNUSED_PAD src0_sel:DWORD src1_sel:DWORD
	v_min_i32_e32 v3, 0x7f, v3
	v_lshlrev_b32_e32 v6, 8, v6
	v_and_b32_e32 v6, 0xff00, v6
	v_and_b32_e32 v7, 0xff0000, v7
	v_perm_b32 v2, v3, v2, s84
	v_or3_b32 v2, v2, v6, v7
	ds_write_b32 v20, v2 offset:144
	ds_read_b64 v[2:3], v21 offset:1024
	s_waitcnt lgkmcnt(0)
;     ...
;   auto issue_prologue = [&](int sA0, int sA1, int sB0, int sB1) {
;     const int tid = opaque_tid(wave);
;     int offA[2], offB[2];
;     _Pragma("unroll") for (int i = 0; i < 2; ++i) {
;       int r, c; stage_rc(tid * 16 + i * 8192, r, c);
;       offA[i] = (r * lda + c) * 2; offB[i] = (r * ldb + c) * 2;
;     }
;     STAGE(SB(0, 0), rsB, sB0, offB, 0); STAGE(SA(0, 0), rsA, sA0, offA, 0);
;     STAGE(SB(0, 1), rsB, sB1, offB, 0); STAGE(SA(0, 1), rsA, sA1, offA, 0);
;     ...
;               const float o0 = (y[0] - ms.x) * ms.y * gm.x + bt.x, o1 = (y[1] - ms.x) * ms.y * gm.y + bt.y;
;               const float o2 = (y[2] - ms.x) * ms.y * gm.z + bt.z, o3 = (y[3] - ms.x) * ms.y * gm.w + bt.w;
;               const unsigned h0 = f2bf(o0), h1 = f2bf(o1), h2 = f2bf(o2), h3 = f2bf(o3);
;               u32x2 ob; ob[0] = h0 | (h1 << 16); ob[1] = h2 | (h3 << 16);
;               *reinterpret_cast<u32x2*>(smem + (rr >> 1) * PIECE + (rr & 1) * 512 + cc * 2) = ob;
;               const int l0 = min(((int)__float_as_uint(o0) - (int)(h0 << 16) + 128) >> 8, 127);
;               const int l1 = min(((int)__float_as_uint(o1) - (int)(h1 << 16) + 128) >> 8, 127);
;               const int l2 = min(((int)__float_as_uint(o2) - (int)(h2 << 16) + 128) >> 8, 127);
;               const int l3 = min(((int)__float_as_uint(o3) - (int)(h3 << 16) + 128) >> 8, 127);
;               *reinterpret_cast<unsigned*>(smem + LOBASE + (rr >> 2) * PIECE + (rr & 3) * 256 + cc) =
;                   (unsigned)(l0 & 255) | ((unsigned)(l1 & 255) << 8) | ((unsigned)(l2 & 255) << 16) | ((unsigned)l3 << 24);
;             }
;           }
;           WAIT_L(0); BAR;
;           const int hso = ((brow + ai * HALF + 16 * wave) * DM + pn * BM) * 2;
;           const int lso = (brow + ai * HALF + 16 * wave) * DM + pn * BM;
;           _Pragma("unroll") for (int i = 0; i < 8; ++i) {
;             const u32x4 v = *reinterpret_cast<const u32x4*>(smem + (wave * 8 + i) * PIECE + lane3 * 16);
;             __builtin_amdgcn_raw_buffer_store_b128(v, rsXB, hvo + i * (2 * DM * 2), hso, 0);
;           }
;           _Pragma("unroll") for (int i = 0; i < 4; ++i) {
;             const u32x4 v = *reinterpret_cast<const u32x4*>(smem + LOBASE + (wave * 4 + i) * PIECE + lane3 * 16);
;             __builtin_amdgcn_raw_buffer_store_b128(v, rsLO, lvo + i * (4 * DM), lso, 0);
;           }
;           WAIT_L(0); BAR;
	v_pk_add_f32 v[6:7], v[10:11], v[2:3] op_sel_hi:[1,0] neg_lo:[0,1] neg_hi:[0,1]
	s_nop 0
	v_pk_mul_f32 v[6:7], v[2:3], v[6:7] op_sel:[1,0]
	v_pk_add_f32 v[8:9], v[8:9], v[2:3] op_sel_hi:[1,0] neg_lo:[0,1] neg_hi:[0,1]
	v_pk_fma_f32 v[6:7], v[24:25], v[6:7], v[26:27]
	v_pk_mul_f32 v[2:3], v[2:3], v[8:9] op_sel:[1,0]
	s_nop 0
	v_pk_fma_f32 v[0:1], v[0:1], v[2:3], v[4:5]
	v_and_b32_sdwa v2, v7, v216 dst_sel:DWORD dst_unused:UNUSED_PAD src0_sel:WORD_1 src1_sel:DWORD
	v_and_b32_sdwa v3, v6, v216 dst_sel:DWORD dst_unused:UNUSED_PAD src0_sel:WORD_1 src1_sel:DWORD
	v_add3_u32 v4, v7, v2, s82
	v_add3_u32 v2, v6, v3, s82
	v_and_b32_e32 v5, 0xffff0000, v2
	v_and_b32_sdwa v2, v1, v216 dst_sel:DWORD dst_unused:UNUSED_PAD src0_sel:WORD_1 src1_sel:DWORD
	v_and_b32_sdwa v3, v0, v216 dst_sel:DWORD dst_unused:UNUSED_PAD src0_sel:WORD_1 src1_sel:DWORD
	v_add3_u32 v2, v1, v2, s82
	v_add3_u32 v8, v0, v3, s82
	v_and_b32_e32 v9, 0xffff0000, v2
	v_or_b32_sdwa v3, v9, v4 dst_sel:DWORD dst_unused:UNUSED_PAD src0_sel:DWORD src1_sel:WORD_1
	v_or_b32_sdwa v2, v8, v5 dst_sel:DWORD dst_unused:UNUSED_PAD src0_sel:WORD_1 src1_sel:DWORD
	ds_write_b64 v73, v[2:3]
	v_and_b32_e32 v2, 0xffff0000, v8
	v_sub_u32_e32 v0, v0, v2
	v_sub_u32_e32 v2, v6, v5
	v_and_b32_e32 v3, 0xffff0000, v4
	v_add_u32_e32 v2, 0x80, v2
	v_sub_u32_e32 v3, v7, v3
	v_sub_u32_e32 v1, v1, v9
	v_add_u32_e32 v0, 0x80, v0
	v_ashrrev_i32_e32 v2, 8, v2
	v_add_u32_e32 v3, 0x80, v3
	v_add_u32_e32 v1, 0x80, v1
	v_ashrrev_i32_e32 v0, 8, v0
	v_min_i32_e32 v2, 0x7f, v2
	v_ashrrev_i32_e32 v3, 8, v3
	v_ashrrev_i32_e32 v1, 8, v1
	v_min_i32_e32 v0, 0x7f, v0
	v_min_i32_sdwa v3, v3, s83 dst_sel:WORD_1 dst_unused:UNUSED_PAD src0_sel:DWORD src1_sel:DWORD
	v_min_i32_e32 v1, 0x7f, v1
	v_lshlrev_b32_e32 v2, 8, v2
	v_and_b32_e32 v2, 0xff00, v2
	v_and_b32_e32 v3, 0xff0000, v3
	v_perm_b32 v0, v1, v0, s84
	v_or3_b32 v0, v0, v2, v3
	ds_write_b32 v22, v0 offset:144
	s_waitcnt lgkmcnt(0)
	s_barrier
	ds_read_b128 v[0:3], v72
	s_waitcnt lgkmcnt(0)
	buffer_store_dwordx4 v[0:3], v148, s[16:19], s3 offen
	ds_read_b128 v[0:3], v72 offset:1040
	s_waitcnt lgkmcnt(0)
	buffer_store_dwordx4 v[0:3], v74, s[16:19], s3 offen
	ds_read_b128 v[0:3], v72 offset:2080
	s_waitcnt lgkmcnt(0)
	buffer_store_dwordx4 v[0:3], v75, s[16:19], s3 offen
	ds_read_b128 v[0:3], v72 offset:3120
	s_waitcnt lgkmcnt(0)
	buffer_store_dwordx4 v[0:3], v81, s[16:19], s3 offen
	ds_read_b128 v[0:3], v72 offset:4160
	s_waitcnt lgkmcnt(0)
	buffer_store_dwordx4 v[0:3], v82, s[16:19], s3 offen
	ds_read_b128 v[0:3], v72 offset:5200
	s_waitcnt lgkmcnt(0)
	buffer_store_dwordx4 v[0:3], v83, s[16:19], s3 offen
	ds_read_b128 v[0:3], v72 offset:6240
	s_waitcnt lgkmcnt(0)
	buffer_store_dwordx4 v[0:3], v88, s[16:19], s3 offen
	ds_read_b128 v[0:3], v72 offset:7280
	s_waitcnt lgkmcnt(0)
	buffer_store_dwordx4 v[0:3], v89, s[16:19], s3 offen
	ds_read_b128 v[0:3], v147
	s_waitcnt lgkmcnt(0)
	buffer_store_dwordx4 v[0:3], v146, s[20:23], s1 offen
	ds_read_b128 v[0:3], v147 offset:1040
	s_waitcnt lgkmcnt(0)
	buffer_store_dwordx4 v[0:3], v90, s[20:23], s1 offen
	ds_read_b128 v[0:3], v147 offset:2080
	s_waitcnt lgkmcnt(0)
	buffer_store_dwordx4 v[0:3], v91, s[20:23], s1 offen
	ds_read_b128 v[0:3], v147 offset:3120
	s_waitcnt lgkmcnt(0)
	buffer_store_dwordx4 v[0:3], v95, s[20:23], s1 offen
	s_waitcnt lgkmcnt(0)
	s_barrier
	s_cbranch_vccnz .LBB0_384
	v_mbcnt_lo_u32_b32 v0, -1, 0
	v_mbcnt_hi_u32_b32 v0, -1, v0
	s_mov_b32 m0, s37
	v_lshl_add_u32 v0, v0, 4, s35
	v_ashrrev_i32_e32 v1, 31, v0
	v_lshrrev_b32_e32 v1, 22, v1
	v_add_u32_e32 v1, v0, v1
	v_ashrrev_i32_e32 v1, 10, v1
	v_mul_i32_i24_e32 v2, 0x400, v1
	v_sub_u32_e32 v2, v0, v2
	v_lshrrev_b32_e32 v3, 4, v2
	v_bitop3_b32 v2, v3, v2, 32 bitop3:0x6c
	v_ashrrev_i32_e32 v4, 31, v2
	v_lshrrev_b32_e32 v4, 26, v4
	v_add_u32_e32 v4, v2, v4
	v_lshrrev_b32_e32 v5, 6, v4
	v_and_b32_e32 v4, 0xc0, v4
	v_lshlrev_b32_e32 v3, 3, v1
	v_lshlrev_b32_e32 v1, 5, v1
	v_sub_u32_e32 v2, v2, v4
	v_and_b32_e32 v3, 0x7fff0, v3
	v_and_b32_e32 v1, 32, v1
	v_ashrrev_i16_sdwa v2, v216, sext(v2) dst_sel:DWORD dst_unused:UNUSED_PAD src0_sel:DWORD src1_sel:BYTE_0
	v_add_u32_sdwa v1, v1, sext(v2) dst_sel:DWORD dst_unused:UNUSED_PAD src0_sel:DWORD src1_sel:WORD_0
	v_add_lshl_u32 v2, v5, v3, 13
	v_add_u32_e32 v0, 0x2000, v0
	v_lshl_add_u32 v1, v1, 1, v2
	v_ashrrev_i32_e32 v2, 31, v0
	v_lshrrev_b32_e32 v2, 22, v2
	v_add_u32_e32 v2, v0, v2
	v_ashrrev_i32_e32 v2, 10, v2
	v_mul_i32_i24_e32 v3, 0x400, v2
	v_sub_u32_e32 v0, v0, v3
	v_lshrrev_b32_e32 v3, 4, v0
	v_bitop3_b32 v0, v3, v0, 32 bitop3:0x6c
	v_ashrrev_i32_e32 v4, 31, v0
	v_lshrrev_b32_e32 v4, 26, v4
	v_add_u32_e32 v4, v0, v4
	v_lshrrev_b32_e32 v5, 6, v4
	v_and_b32_e32 v4, 0xffc0, v4
	v_sub_u32_e32 v0, v0, v4
	v_lshrrev_b16_e32 v4, 7, v0
	v_and_b32_e32 v4, 1, v4
	v_lshlrev_b32_e32 v3, 3, v2
	v_lshlrev_b32_e32 v2, 5, v2
	v_add_u16_e32 v0, v0, v4
	v_and_b32_e32 v3, 0x7fff0, v3
	v_and_b32_e32 v2, 32, v2
	v_ashrrev_i16_sdwa v0, v216, sext(v0) dst_sel:DWORD dst_unused:UNUSED_PAD src0_sel:DWORD src1_sel:BYTE_0
	v_add_u32_sdwa v0, v2, sext(v0) dst_sel:DWORD dst_unused:UNUSED_PAD src0_sel:DWORD src1_sel:WORD_0
	v_add_lshl_u32 v2, v5, v3, 13
	s_mov_b32 s14, s10
	s_mov_b32 s15, s11
	v_lshl_add_u32 v0, v0, 1, v2
	buffer_load_dwordx4 v1, s[12:15], s92 offen lds
	s_mov_b32 m0, s48
	s_or_b32 s0, s92, 0x80
	buffer_load_dwordx4 v0, s[12:15], s92 offen lds
	s_mov_b32 m0, s35
	s_mov_b64 s[4:5], 0
	buffer_load_dwordx4 v1, s[8:11], s87 offen lds
	s_mov_b32 m0, s49
	s_nop 0
	buffer_load_dwordx4 v0, s[8:11], s87 offen lds
	s_mov_b32 m0, s38
	s_nop 0
	buffer_load_dwordx4 v1, s[12:15], s93 offen lds
	s_mov_b32 m0, s54
	s_nop 0
	buffer_load_dwordx4 v0, s[12:15], s93 offen lds
	s_mov_b32 m0, s39
	s_nop 0
	buffer_load_dwordx4 v1, s[8:11], s86 offen lds
	s_mov_b32 m0, s55
	s_nop 0
	buffer_load_dwordx4 v0, s[8:11], s86 offen lds
	s_mov_b32 m0, s42
	s_nop 0
	buffer_load_dwordx4 v1, s[12:15], s0 offen lds
	s_mov_b32 m0, s56
	s_nop 0
	buffer_load_dwordx4 v0, s[12:15], s0 offen lds
	s_or_b32 s0, s87, 0x80
	s_mov_b32 m0, s43
	s_nop 0
	buffer_load_dwordx4 v1, s[8:11], s0 offen lds
	s_mov_b32 m0, s57
	s_nop 0
	buffer_load_dwordx4 v0, s[8:11], s0 offen lds
	s_add_i32 s0, s93, 0x80
	s_mov_b32 m0, s44
	s_nop 0
	buffer_load_dwordx4 v1, s[12:15], s0 offen lds
	s_mov_b32 m0, s58
	s_nop 0
	buffer_load_dwordx4 v0, s[12:15], s0 offen lds
	s_branch .LBB0_384

;     ...
;       const int tid3 = opaque_tid(wave);
;       const int wr3 = tid3 >> 8, wc3 = (tid3 >> 6) & 3, fr3 = tid3 & 15, fq3 = (tid3 & 63) >> 4;
;       const int ebase3 = (brow + wr3 * 64 + fr3) * DM + pn * BM + wc3 * 32 + fq3 * 4;
;       const int vo4b = ebase3 * 4, vo2 = ebase3 * 2, vo1 = ebase3;
;     ...
;         constexpr int PIECE = 1024 + 16, LOBASE = 64 * PIECE;
;         const int lane3 = tid3 & 63;
;         const int hvo = (lane3 >> 5) * (DM * 2) + (lane3 & 31) * 16;
;         const int lvo = (lane3 >> 4) * DM + (lane3 & 15) * 16;
;         _Pragma("unroll") for (int ai = 0; ai < 2; ++ai) {
;           _Pragma("unroll") for (int bj = 0; bj < 2; ++bj) _Pragma("unroll") for (int n = 0; n < 2; ++n) {
;             const int cc = bj * HALF + wc3 * 32 + n * 16 + fq3 * 4;
;             const float4 gm = *reinterpret_cast<const float4*>(g.gam + pn * BM + cc), bt = *reinterpret_cast<const float4*>(g.bet + pn * BM + cc);
;             _Pragma("unroll") for (int m = 0; m < 4; ++m) {
;               const int rr = wr3 * 64 + m * 16 + fr3;
;               const float2 ms = *reinterpret_cast<const float2*>(mr + (ai * HALF + rr) * 2);
;               f32x4 y = acc[ai][bj][m][n];
;               const float o0 = (y[0] - ms.x) * ms.y * gm.x + bt.x, o1 = (y[1] - ms.x) * ms.y * gm.y + bt.y;
;               const float o2 = (y[2] - ms.x) * ms.y * gm.z + bt.z, o3 = (y[3] - ms.x) * ms.y * gm.w + bt.w;
;               const unsigned h0 = f2bf(o0), h1 = f2bf(o1), h2 = f2bf(o2), h3 = f2bf(o3);
;               u32x2 ob; ob[0] = h0 | (h1 << 16); ob[1] = h2 | (h3 << 16);
;               *reinterpret_cast<u32x2*>(smem + (rr >> 1) * PIECE + (rr & 1) * 512 + cc * 2) = ob;
;               const int l0 = min(((int)__float_as_uint(o0) - (int)(h0 << 16) + 128) >> 8, 127);
;               const int l1 = min(((int)__float_as_uint(o1) - (int)(h1 << 16) + 128) >> 8, 127);
;               const int l2 = min(((int)__float_as_uint(o2) - (int)(h2 << 16) + 128) >> 8, 127);
;               const int l3 = min(((int)__float_as_uint(o3) - (int)(h3 << 16) + 128) >> 8, 127);
;               *reinterpret_cast<unsigned*>(smem + LOBASE + (rr >> 2) * PIECE + (rr & 3) * 256 + cc) =
;                   (unsigned)(l0 & 255) | ((unsigned)(l1 & 255) << 8) | ((unsigned)(l2 & 255) << 16) | ((unsigned)l3 << 24);
;             }
.LBB0_523:
	s_or_b64 exec, exec, s[6:7]
	s_waitcnt lgkmcnt(0)
	s_barrier
	v_mbcnt_lo_u32_b32 v0, -1, 0
	v_mbcnt_hi_u32_b32 v0, -1, v0
	v_readlane_b32 s40, v255, 0
	v_add_u32_e32 v1, s34, v0
	v_bfe_u32 v4, v0, 4, 2
	v_ashrrev_i32_e32 v5, 2, v1
	v_lshrrev_b32_e32 v6, 1, v1
	v_lshlrev_b32_e32 v1, 4, v1
	v_lshlrev_b32_e32 v7, 2, v4
	v_lshlrev_b32_e32 v12, 7, v0
	v_and_b32_e32 v13, 0x1f0, v1
	s_movk_i32 s4, 0x60
	s_ashr_i32 s29, s28, 31
	v_readlane_b32 s54, v255, 14
	v_readlane_b32 s55, v255, 15
	v_and_or_b32 v148, v12, s75, v13
	v_and_or_b32 v12, v6, s4, v7
	s_lshl_b64 s[4:5], s[28:29], 2
	s_mov_b64 s[22:23], s[54:55]
	s_add_u32 s6, s22, s4
	v_and_b32_e32 v2, 15, v0
	v_and_b32_e32 v3, 63, v0
	v_and_b32_e32 v1, 0xf0, v1
	v_lshlrev_b32_e32 v13, 9, v0
	v_lshlrev_b32_e32 v0, 8, v0
	s_addc_u32 s7, s23, s5
	v_lshlrev_b32_e32 v150, 2, v12
	v_lshl_or_b32 v146, v4, 11, v1
	v_and_or_b32 v156, v5, s31, v2
	v_and_b32_e32 v14, 0x300, v0
	v_lshlrev_b32_e32 v151, 4, v3
	global_load_dwordx4 v[220:223], v150, s[6:7]
	global_load_dwordx4 v[224:227], v150, s[6:7] offset:64
	global_load_dwordx4 v[228:231], v150, s[6:7] offset:512
	global_load_dwordx4 v[232:235], v150, s[6:7] offset:576
	v_readlane_b32 s41, v255, 1
	v_readlane_b32 s42, v255, 2
	v_readlane_b32 s43, v255, 3
	v_readlane_b32 s44, v255, 4
	v_readlane_b32 s45, v255, 5
	v_readlane_b32 s46, v255, 6
	v_readlane_b32 s47, v255, 7
	v_readlane_b32 s48, v255, 8
	v_readlane_b32 s49, v255, 9
	v_readlane_b32 s50, v255, 10
	v_readlane_b32 s51, v255, 11
	v_readlane_b32 s52, v255, 12
	v_readlane_b32 s53, v255, 13
	v_readlane_b32 s40, v255, 16
	v_readlane_b32 s41, v255, 17
	s_add_u32 s4, s40, s4
	s_addc_u32 s5, s41, s5
	global_load_dwordx4 v[236:239], v150, s[4:5]
	global_load_dwordx4 v[240:243], v150, s[4:5] offset:64
	global_load_dwordx4 v[244:247], v150, s[4:5] offset:512
	global_load_dwordx4 v[248:251], v150, s[4:5] offset:576
	s_movk_i32 s22, 0x200
	v_lshl_add_u32 v149, v156, 3, v219
	v_add_u32_e32 v147, s69, v151
	s_andn2_b64 vcc, exec, s[14:15]
	v_readlane_b32 s42, v255, 18
	v_readlane_b32 s43, v255, 19
	v_readlane_b32 s44, v255, 20
	v_readlane_b32 s45, v255, 21
	v_readlane_b32 s46, v255, 22
	v_readlane_b32 s47, v255, 23
	v_readlane_b32 s48, v255, 24
	v_readlane_b32 s49, v255, 25
	v_readlane_b32 s50, v255, 26
	v_readlane_b32 s51, v255, 27
	v_readlane_b32 s52, v255, 28
	v_readlane_b32 s53, v255, 29
	v_readlane_b32 s54, v255, 30
	v_readlane_b32 s55, v255, 31
	s_waitcnt vmcnt(0)
	v_mov_b32_e32 v0, v220
	v_mov_b32_e32 v1, v221
	v_mov_b32_e32 v2, v222
	v_mov_b32_e32 v3, v223
	v_mov_b32_e32 v4, v236
	v_mov_b32_e32 v5, v237
	v_mov_b32_e32 v6, v238
	v_mov_b32_e32 v7, v239
	v_mov_b32_e32 v22, v1
	v_lshlrev_b32_e32 v1, 1, v12
	v_and_or_b32 v155, v13, s22, v1
	s_mov_b32 s22, 0x10400
	v_mov_b32_e32 v23, v2
	v_or3_b32 v2, v14, v12, s22
	ds_read_b64 v[12:13], v149
	v_mov_b32_e32 v1, v3
	s_waitcnt lgkmcnt(0)
	v_pk_add_f32 v[14:15], v[128:129], v[12:13] op_sel_hi:[1,0] neg_lo:[0,1] neg_hi:[0,1]
	s_nop 0
	v_pk_mul_f32 v[14:15], v[12:13], v[14:15] op_sel:[1,0]
	v_pk_add_f32 v[20:21], v[130:131], v[12:13] op_sel_hi:[1,0] neg_lo:[0,1] neg_hi:[0,1]
	v_lshrrev_b32_e32 v129, 1, v156
	v_pk_mul_f32 v[12:13], v[12:13], v[20:21] op_sel:[1,0]
	v_mul_lo_u32 v153, v129, s61
	v_add_u32_e32 v152, v155, v153
	v_mov_b32_e32 v144, v5
	v_mov_b32_e32 v145, v6
	v_pk_fma_f32 v[14:15], v[22:23], v[14:15], v[144:145]
	v_mov_b32_e32 v5, v7
	v_pk_fma_f32 v[6:7], v[0:1], v[12:13], v[4:5]
	v_and_b32_sdwa v12, v14, v216 dst_sel:DWORD dst_unused:UNUSED_PAD src0_sel:WORD_1 src1_sel:DWORD
	v_add3_u32 v12, v14, v12, s78
	v_and_b32_e32 v20, 0xffff0000, v12
	v_and_b32_sdwa v12, v7, v216 dst_sel:DWORD dst_unused:UNUSED_PAD src0_sel:WORD_1 src1_sel:DWORD
	v_and_b32_sdwa v3, v15, v216 dst_sel:DWORD dst_unused:UNUSED_PAD src0_sel:WORD_1 src1_sel:DWORD
	v_and_b32_sdwa v13, v6, v216 dst_sel:DWORD dst_unused:UNUSED_PAD src0_sel:WORD_1 src1_sel:DWORD
	v_add3_u32 v12, v7, v12, s78
	v_add3_u32 v3, v15, v3, s78
	v_add3_u32 v21, v6, v13, s78
	v_and_b32_e32 v128, 0xffff0000, v12
	v_or_b32_sdwa v13, v128, v3 dst_sel:DWORD dst_unused:UNUSED_PAD src0_sel:DWORD src1_sel:WORD_1
	v_or_b32_sdwa v12, v21, v20 dst_sel:DWORD dst_unused:UNUSED_PAD src0_sel:WORD_1 src1_sel:DWORD
	ds_write_b64 v152, v[12:13]
	v_and_b32_e32 v12, 0xffff0000, v21
	v_sub_u32_e32 v6, v6, v12
	v_sub_u32_e32 v12, v14, v20
	v_and_b32_e32 v3, 0xffff0000, v3
	v_add_u32_e32 v12, 0x80, v12
	v_sub_u32_e32 v3, v15, v3
	v_sub_u32_e32 v7, v7, v128
	v_add_u32_e32 v6, 0x80, v6
	v_ashrrev_i32_e32 v12, 8, v12
	v_add_u32_e32 v3, 0x80, v3
	v_add_u32_e32 v7, 0x80, v7
	v_ashrrev_i32_e32 v6, 8, v6
	v_min_i32_e32 v12, 0x7f, v12
	v_ashrrev_i32_e32 v3, 8, v3
	v_ashrrev_i32_e32 v7, 8, v7
	v_min_i32_e32 v6, 0x7f, v6
	v_min_i32_sdwa v3, v3, s79 dst_sel:WORD_1 dst_unused:UNUSED_PAD src0_sel:DWORD src1_sel:DWORD
	v_min_i32_e32 v7, 0x7f, v7
	v_lshlrev_b32_e32 v12, 8, v12
	v_and_b32_e32 v12, 0xff00, v12
	v_and_b32_e32 v3, 0xff0000, v3
	v_perm_b32 v6, v7, v6, s80
	v_or3_b32 v3, v6, v12, v3
	v_lshrrev_b32_e32 v6, 2, v156
	v_mad_u64_u32 v[12:13], s[22:23], v6, s61, v[2:3]
	ds_write_b32 v12, v3
	v_or_b32_e32 v3, 16, v156
	v_lshl_add_u32 v13, v3, 3, v219
	ds_read_b64 v[6:7], v13
	s_waitcnt lgkmcnt(0)
;     ...
;             _Pragma("unroll") for (int m = 0; m < 4; ++m) {
;               const int rr = wr3 * 64 + m * 16 + fr3;
;               const float2 ms = *reinterpret_cast<const float2*>(mr + (ai * HALF + rr) * 2);
;               f32x4 y = acc[ai][bj][m][n];
;               const float o0 = (y[0] - ms.x) * ms.y * gm.x + bt.x, o1 = (y[1] - ms.x) * ms.y * gm.y + bt.y;
;               const float o2 = (y[2] - ms.x) * ms.y * gm.z + bt.z, o3 = (y[3] - ms.x) * ms.y * gm.w + bt.w;
;               const unsigned h0 = f2bf(o0), h1 = f2bf(o1), h2 = f2bf(o2), h3 = f2bf(o3);
;               u32x2 ob; ob[0] = h0 | (h1 << 16); ob[1] = h2 | (h3 << 16);
;               *reinterpret_cast<u32x2*>(smem + (rr >> 1) * PIECE + (rr & 1) * 512 + cc * 2) = ob;
;               const int l0 = min(((int)__float_as_uint(o0) - (int)(h0 << 16) + 128) >> 8, 127);
;               const int l1 = min(((int)__float_as_uint(o1) - (int)(h1 << 16) + 128) >> 8, 127);
;               const int l2 = min(((int)__float_as_uint(o2) - (int)(h2 << 16) + 128) >> 8, 127);
;               const int l3 = min(((int)__float_as_uint(o3) - (int)(h3 << 16) + 128) >> 8, 127);
;               *reinterpret_cast<unsigned*>(smem + LOBASE + (rr >> 2) * PIECE + (rr & 3) * 256 + cc) =
;                   (unsigned)(l0 & 255) | ((unsigned)(l1 & 255) << 8) | ((unsigned)(l2 & 255) << 16) | ((unsigned)l3 << 24);
;             }
	v_pk_add_f32 v[14:15], v[134:135], v[6:7] op_sel_hi:[1,0] neg_lo:[0,1] neg_hi:[0,1]
	s_nop 0
	v_pk_mul_f32 v[14:15], v[6:7], v[14:15] op_sel:[1,0]
	v_pk_add_f32 v[20:21], v[132:133], v[6:7] op_sel_hi:[1,0] neg_lo:[0,1] neg_hi:[0,1]
	v_pk_fma_f32 v[14:15], v[22:23], v[14:15], v[144:145]
	v_pk_mul_f32 v[6:7], v[6:7], v[20:21] op_sel:[1,0]
	v_and_b32_sdwa v20, v15, v216 dst_sel:DWORD dst_unused:UNUSED_PAD src0_sel:WORD_1 src1_sel:DWORD
	v_and_b32_sdwa v21, v14, v216 dst_sel:DWORD dst_unused:UNUSED_PAD src0_sel:WORD_1 src1_sel:DWORD
	v_pk_fma_f32 v[6:7], v[0:1], v[6:7], v[4:5]
	v_add3_u32 v128, v15, v20, s78
	v_add3_u32 v20, v14, v21, s78
	v_and_b32_e32 v129, 0xffff0000, v20
	v_and_b32_sdwa v20, v7, v216 dst_sel:DWORD dst_unused:UNUSED_PAD src0_sel:WORD_1 src1_sel:DWORD
	v_and_b32_sdwa v21, v6, v216 dst_sel:DWORD dst_unused:UNUSED_PAD src0_sel:WORD_1 src1_sel:DWORD
	v_add3_u32 v20, v7, v20, s78
	v_lshrrev_b32_e32 v132, 1, v3
	v_add3_u32 v130, v6, v21, s78
	v_and_b32_e32 v131, 0xffff0000, v20
	v_mul_lo_u32 v154, v132, s61
	v_or_b32_sdwa v21, v131, v128 dst_sel:DWORD dst_unused:UNUSED_PAD src0_sel:DWORD src1_sel:WORD_1
	v_or_b32_sdwa v20, v130, v129 dst_sel:DWORD dst_unused:UNUSED_PAD src0_sel:WORD_1 src1_sel:DWORD
	v_add_u32_e32 v132, v155, v154
	ds_write_b64 v132, v[20:21]
	v_and_b32_e32 v20, 0xffff0000, v130
	v_sub_u32_e32 v6, v6, v20
	v_sub_u32_e32 v14, v14, v129
	v_and_b32_e32 v20, 0xffff0000, v128
	v_add_u32_e32 v14, 0x80, v14
	v_sub_u32_e32 v15, v15, v20
	v_sub_u32_e32 v7, v7, v131
	v_add_u32_e32 v6, 0x80, v6
	v_ashrrev_i32_e32 v14, 8, v14
	v_add_u32_e32 v15, 0x80, v15
	v_add_u32_e32 v7, 0x80, v7
	v_ashrrev_i32_e32 v6, 8, v6
	v_min_i32_e32 v14, 0x7f, v14
	v_ashrrev_i32_e32 v15, 8, v15
	v_ashrrev_i32_e32 v7, 8, v7
	v_min_i32_e32 v6, 0x7f, v6
	v_min_i32_sdwa v15, v15, s79 dst_sel:WORD_1 dst_unused:UNUSED_PAD src0_sel:DWORD src1_sel:DWORD
	v_min_i32_e32 v7, 0x7f, v7
	v_lshlrev_b32_e32 v14, 8, v14
	v_and_b32_e32 v14, 0xff00, v14
	v_and_b32_e32 v15, 0xff0000, v15
	v_perm_b32 v6, v7, v6, s80
	v_lshrrev_b32_e32 v3, 2, v3
	v_or3_b32 v6, v6, v14, v15
	v_mad_u64_u32 v[14:15], s[22:23], v3, s61, v[2:3]
	v_or_b32_e32 v3, 32, v156
	ds_write_b32 v14, v6
	v_lshl_add_u32 v15, v3, 3, v219
	ds_read_b64 v[6:7], v15
	v_lshrrev_b32_e32 v133, 1, v3
	v_lshrrev_b32_e32 v3, 2, v3
	s_waitcnt lgkmcnt(0)
	v_pk_add_f32 v[20:21], v[138:139], v[6:7] op_sel_hi:[1,0] neg_lo:[0,1] neg_hi:[0,1]
	s_nop 0
	v_pk_mul_f32 v[20:21], v[6:7], v[20:21] op_sel:[1,0]
	v_pk_add_f32 v[128:129], v[136:137], v[6:7] op_sel_hi:[1,0] neg_lo:[0,1] neg_hi:[0,1]
	v_pk_fma_f32 v[20:21], v[22:23], v[20:21], v[144:145]
	v_pk_mul_f32 v[6:7], v[6:7], v[128:129] op_sel:[1,0]
	v_and_b32_sdwa v128, v21, v216 dst_sel:DWORD dst_unused:UNUSED_PAD src0_sel:WORD_1 src1_sel:DWORD
	v_and_b32_sdwa v129, v20, v216 dst_sel:DWORD dst_unused:UNUSED_PAD src0_sel:WORD_1 src1_sel:DWORD
	v_pk_fma_f32 v[6:7], v[0:1], v[6:7], v[4:5]
	v_add3_u32 v130, v21, v128, s78
	v_add3_u32 v128, v20, v129, s78
	v_and_b32_e32 v131, 0xffff0000, v128
	v_and_b32_sdwa v128, v7, v216 dst_sel:DWORD dst_unused:UNUSED_PAD src0_sel:WORD_1 src1_sel:DWORD
	v_and_b32_sdwa v129, v6, v216 dst_sel:DWORD dst_unused:UNUSED_PAD src0_sel:WORD_1 src1_sel:DWORD
	v_add3_u32 v128, v7, v128, s78
	v_add3_u32 v134, v6, v129, s78
	v_and_b32_e32 v135, 0xffff0000, v128
	v_mul_lo_u32 v136, v133, s61
	v_or_b32_sdwa v129, v135, v130 dst_sel:DWORD dst_unused:UNUSED_PAD src0_sel:DWORD src1_sel:WORD_1
	v_or_b32_sdwa v128, v134, v131 dst_sel:DWORD dst_unused:UNUSED_PAD src0_sel:WORD_1 src1_sel:DWORD
	v_add_u32_e32 v133, v155, v136
	ds_write_b64 v133, v[128:129]
	v_and_b32_e32 v128, 0xffff0000, v134
	v_sub_u32_e32 v6, v6, v128
	v_sub_u32_e32 v20, v20, v131
	v_and_b32_e32 v128, 0xffff0000, v130
	v_add_u32_e32 v20, 0x80, v20
	v_sub_u32_e32 v21, v21, v128
	v_sub_u32_e32 v7, v7, v135
	v_add_u32_e32 v6, 0x80, v6
	v_ashrrev_i32_e32 v20, 8, v20
	v_add_u32_e32 v21, 0x80, v21
	v_add_u32_e32 v7, 0x80, v7
	v_ashrrev_i32_e32 v6, 8, v6
	v_min_i32_e32 v20, 0x7f, v20
	v_ashrrev_i32_e32 v21, 8, v21
	v_ashrrev_i32_e32 v7, 8, v7
	v_min_i32_e32 v6, 0x7f, v6
	v_min_i32_sdwa v21, v21, s79 dst_sel:WORD_1 dst_unused:UNUSED_PAD src0_sel:DWORD src1_sel:DWORD
	v_min_i32_e32 v7, 0x7f, v7
	v_lshlrev_b32_e32 v20, 8, v20
	v_and_b32_e32 v20, 0xff00, v20
	v_and_b32_e32 v21, 0xff0000, v21
	v_perm_b32 v6, v7, v6, s80
	v_or3_b32 v6, v6, v20, v21
	v_mad_u64_u32 v[20:21], s[22:23], v3, s61, v[2:3]
	v_or_b32_e32 v3, 48, v156
	ds_write_b32 v20, v6
	v_lshl_add_u32 v21, v3, 3, v219
	ds_read_b64 v[6:7], v21
	v_lshrrev_b32_e32 v130, 1, v3
	v_mul_lo_u32 v135, v130, s61
	v_add_u32_e32 v134, v155, v135
	s_waitcnt lgkmcnt(0)
;     ...
;           _Pragma("unroll") for (int bj = 0; bj < 2; ++bj) _Pragma("unroll") for (int n = 0; n < 2; ++n) {
;             const int cc = bj * HALF + wc3 * 32 + n * 16 + fq3 * 4;
;             const float4 gm = *reinterpret_cast<const float4*>(g.gam + pn * BM + cc), bt = *reinterpret_cast<const float4*>(g.bet + pn * BM + cc);
;             _Pragma("unroll") for (int m = 0; m < 4; ++m) {
;               const int rr = wr3 * 64 + m * 16 + fr3;
;               const float2 ms = *reinterpret_cast<const float2*>(mr + (ai * HALF + rr) * 2);
;               f32x4 y = acc[ai][bj][m][n];
;               const float o0 = (y[0] - ms.x) * ms.y * gm.x + bt.x, o1 = (y[1] - ms.x) * ms.y * gm.y + bt.y;
;               const float o2 = (y[2] - ms.x) * ms.y * gm.z + bt.z, o3 = (y[3] - ms.x) * ms.y * gm.w + bt.w;
;               const unsigned h0 = f2bf(o0), h1 = f2bf(o1), h2 = f2bf(o2), h3 = f2bf(o3);
;               u32x2 ob; ob[0] = h0 | (h1 << 16); ob[1] = h2 | (h3 << 16);
;               *reinterpret_cast<u32x2*>(smem + (rr >> 1) * PIECE + (rr & 1) * 512 + cc * 2) = ob;
;               const int l0 = min(((int)__float_as_uint(o0) - (int)(h0 << 16) + 128) >> 8, 127);
;               const int l1 = min(((int)__float_as_uint(o1) - (int)(h1 << 16) + 128) >> 8, 127);
;               const int l2 = min(((int)__float_as_uint(o2) - (int)(h2 << 16) + 128) >> 8, 127);
;               const int l3 = min(((int)__float_as_uint(o3) - (int)(h3 << 16) + 128) >> 8, 127);
;               *reinterpret_cast<unsigned*>(smem + LOBASE + (rr >> 2) * PIECE + (rr & 3) * 256 + cc) =
;                   (unsigned)(l0 & 255) | ((unsigned)(l1 & 255) << 8) | ((unsigned)(l2 & 255) << 16) | ((unsigned)l3 << 24);
;             }
	v_pk_add_f32 v[128:129], v[142:143], v[6:7] op_sel_hi:[1,0] neg_lo:[0,1] neg_hi:[0,1]
	s_nop 0
	v_pk_mul_f32 v[128:129], v[6:7], v[128:129] op_sel:[1,0]
	s_nop 0
	v_pk_fma_f32 v[22:23], v[22:23], v[128:129], v[144:145]
	v_pk_add_f32 v[128:129], v[140:141], v[6:7] op_sel_hi:[1,0] neg_lo:[0,1] neg_hi:[0,1]
	s_nop 0
	v_pk_mul_f32 v[6:7], v[6:7], v[128:129] op_sel:[1,0]
	s_nop 0
	v_pk_fma_f32 v[0:1], v[0:1], v[6:7], v[4:5]
	v_and_b32_sdwa v4, v23, v216 dst_sel:DWORD dst_unused:UNUSED_PAD src0_sel:WORD_1 src1_sel:DWORD
	v_and_b32_sdwa v5, v22, v216 dst_sel:DWORD dst_unused:UNUSED_PAD src0_sel:WORD_1 src1_sel:DWORD
	v_add3_u32 v6, v23, v4, s78
	v_add3_u32 v4, v22, v5, s78
	v_and_b32_e32 v7, 0xffff0000, v4
	v_and_b32_sdwa v4, v1, v216 dst_sel:DWORD dst_unused:UNUSED_PAD src0_sel:WORD_1 src1_sel:DWORD
	v_and_b32_sdwa v5, v0, v216 dst_sel:DWORD dst_unused:UNUSED_PAD src0_sel:WORD_1 src1_sel:DWORD
	v_add3_u32 v4, v1, v4, s78
	v_add3_u32 v128, v0, v5, s78
	v_and_b32_e32 v129, 0xffff0000, v4
	v_or_b32_sdwa v5, v129, v6 dst_sel:DWORD dst_unused:UNUSED_PAD src0_sel:DWORD src1_sel:WORD_1
	v_or_b32_sdwa v4, v128, v7 dst_sel:DWORD dst_unused:UNUSED_PAD src0_sel:WORD_1 src1_sel:DWORD
	ds_write_b64 v134, v[4:5]
	v_and_b32_e32 v4, 0xffff0000, v128
	v_sub_u32_e32 v0, v0, v4
	v_sub_u32_e32 v4, v22, v7
	v_and_b32_e32 v5, 0xffff0000, v6
	v_add_u32_e32 v4, 0x80, v4
	v_sub_u32_e32 v5, v23, v5
	v_sub_u32_e32 v1, v1, v129
	v_add_u32_e32 v0, 0x80, v0
	v_ashrrev_i32_e32 v4, 8, v4
	v_add_u32_e32 v5, 0x80, v5
	v_add_u32_e32 v1, 0x80, v1
	v_ashrrev_i32_e32 v0, 8, v0
	v_min_i32_e32 v4, 0x7f, v4
	v_ashrrev_i32_e32 v5, 8, v5
	v_ashrrev_i32_e32 v1, 8, v1
	v_min_i32_e32 v0, 0x7f, v0
	v_min_i32_sdwa v5, v5, s79 dst_sel:WORD_1 dst_unused:UNUSED_PAD src0_sel:DWORD src1_sel:DWORD
	v_min_i32_e32 v1, 0x7f, v1
	v_lshlrev_b32_e32 v4, 8, v4
	v_and_b32_e32 v4, 0xff00, v4
	v_and_b32_e32 v5, 0xff0000, v5
	v_perm_b32 v0, v1, v0, s80
	v_lshrrev_b32_e32 v1, 2, v3
	v_or3_b32 v0, v0, v4, v5
	v_mad_u64_u32 v[22:23], s[22:23], v1, s61, v[2:3]
	ds_write_b32 v22, v0
	v_mov_b32_e32 v0, v224
	v_mov_b32_e32 v1, v225
	v_mov_b32_e32 v2, v226
	v_mov_b32_e32 v3, v227
	v_mov_b32_e32 v4, v240
	v_mov_b32_e32 v5, v241
	v_mov_b32_e32 v6, v242
	v_mov_b32_e32 v7, v243
	ds_read_b64 v[138:139], v149
	s_mov_b32 s22, s18
	s_mov_b32 s23, s19
	s_waitcnt lgkmcnt(0)
	v_pk_add_f32 v[124:125], v[124:125], v[138:139] op_sel_hi:[1,0] neg_lo:[0,1] neg_hi:[0,1]
	s_nop 0
	v_pk_mul_f32 v[124:125], v[138:139], v[124:125] op_sel:[1,0]
	v_pk_add_f32 v[126:127], v[126:127], v[138:139] op_sel_hi:[1,0] neg_lo:[0,1] neg_hi:[0,1]
	v_mov_b32_e32 v128, v1
	v_mov_b32_e32 v129, v2
	v_mov_b32_e32 v130, v5
	v_mov_b32_e32 v131, v6
	v_pk_fma_f32 v[124:125], v[128:129], v[124:125], v[130:131]
	v_pk_mul_f32 v[126:127], v[138:139], v[126:127] op_sel:[1,0]
	v_mov_b32_e32 v1, v3
	v_mov_b32_e32 v5, v7
	v_and_b32_sdwa v23, v124, v216 dst_sel:DWORD dst_unused:UNUSED_PAD src0_sel:WORD_1 src1_sel:DWORD
	v_pk_fma_f32 v[6:7], v[0:1], v[126:127], v[4:5]
	v_add3_u32 v23, v124, v23, s78
	v_and_b32_e32 v137, 0xffff0000, v23
	v_and_b32_sdwa v23, v7, v216 dst_sel:DWORD dst_unused:UNUSED_PAD src0_sel:WORD_1 src1_sel:DWORD
	v_and_b32_sdwa v3, v125, v216 dst_sel:DWORD dst_unused:UNUSED_PAD src0_sel:WORD_1 src1_sel:DWORD
	v_and_b32_sdwa v126, v6, v216 dst_sel:DWORD dst_unused:UNUSED_PAD src0_sel:WORD_1 src1_sel:DWORD
	v_add3_u32 v23, v7, v23, s78
	v_or_b32_e32 v2, 32, v155
	v_add3_u32 v3, v125, v3, s78
	v_add3_u32 v138, v6, v126, s78
	v_and_b32_e32 v139, 0xffff0000, v23
	v_or_b32_sdwa v127, v139, v3 dst_sel:DWORD dst_unused:UNUSED_PAD src0_sel:DWORD src1_sel:WORD_1
	v_or_b32_sdwa v126, v138, v137 dst_sel:DWORD dst_unused:UNUSED_PAD src0_sel:WORD_1 src1_sel:DWORD
	v_add_u32_e32 v23, v2, v153
	ds_write_b64 v23, v[126:127]
	v_and_b32_e32 v126, 0xffff0000, v138
	v_sub_u32_e32 v124, v124, v137
	v_and_b32_e32 v3, 0xffff0000, v3
	v_sub_u32_e32 v6, v6, v126
	v_add_u32_e32 v124, 0x80, v124
	v_sub_u32_e32 v3, v125, v3
	v_sub_u32_e32 v7, v7, v139
	v_add_u32_e32 v6, 0x80, v6
	v_ashrrev_i32_e32 v124, 8, v124
	v_add_u32_e32 v3, 0x80, v3
	v_add_u32_e32 v7, 0x80, v7
	v_ashrrev_i32_e32 v6, 8, v6
	v_min_i32_e32 v124, 0x7f, v124
	v_ashrrev_i32_e32 v3, 8, v3
	v_ashrrev_i32_e32 v7, 8, v7
	v_min_i32_e32 v6, 0x7f, v6
	v_min_i32_sdwa v3, v3, s79 dst_sel:WORD_1 dst_unused:UNUSED_PAD src0_sel:DWORD src1_sel:DWORD
	v_min_i32_e32 v7, 0x7f, v7
	v_lshlrev_b32_e32 v124, 8, v124
	v_and_b32_e32 v124, 0xff00, v124
	v_and_b32_e32 v3, 0xff0000, v3
	v_perm_b32 v6, v7, v6, s80
	v_or3_b32 v3, v6, v124, v3
	ds_write_b32 v12, v3 offset:16
	ds_read_b64 v[6:7], v13
	s_waitcnt lgkmcnt(0)
;     ...
;           _Pragma("unroll") for (int bj = 0; bj < 2; ++bj) _Pragma("unroll") for (int n = 0; n < 2; ++n) {
;             const int cc = bj * HALF + wc3 * 32 + n * 16 + fq3 * 4;
;             const float4 gm = *reinterpret_cast<const float4*>(g.gam + pn * BM + cc), bt = *reinterpret_cast<const float4*>(g.bet + pn * BM + cc);
;             _Pragma("unroll") for (int m = 0; m < 4; ++m) {
;               const int rr = wr3 * 64 + m * 16 + fr3;
;               const float2 ms = *reinterpret_cast<const float2*>(mr + (ai * HALF + rr) * 2);
;               f32x4 y = acc[ai][bj][m][n];
;               const float o0 = (y[0] - ms.x) * ms.y * gm.x + bt.x, o1 = (y[1] - ms.x) * ms.y * gm.y + bt.y;
;               const float o2 = (y[2] - ms.x) * ms.y * gm.z + bt.z, o3 = (y[3] - ms.x) * ms.y * gm.w + bt.w;
;               const unsigned h0 = f2bf(o0), h1 = f2bf(o1), h2 = f2bf(o2), h3 = f2bf(o3);
;               u32x2 ob; ob[0] = h0 | (h1 << 16); ob[1] = h2 | (h3 << 16);
;               *reinterpret_cast<u32x2*>(smem + (rr >> 1) * PIECE + (rr & 1) * 512 + cc * 2) = ob;
;               const int l0 = min(((int)__float_as_uint(o0) - (int)(h0 << 16) + 128) >> 8, 127);
;               const int l1 = min(((int)__float_as_uint(o1) - (int)(h1 << 16) + 128) >> 8, 127);
;               const int l2 = min(((int)__float_as_uint(o2) - (int)(h2 << 16) + 128) >> 8, 127);
;               const int l3 = min(((int)__float_as_uint(o3) - (int)(h3 << 16) + 128) >> 8, 127);
;               *reinterpret_cast<unsigned*>(smem + LOBASE + (rr >> 2) * PIECE + (rr & 3) * 256 + cc) =
;                   (unsigned)(l0 & 255) | ((unsigned)(l1 & 255) << 8) | ((unsigned)(l2 & 255) << 16) | ((unsigned)l3 << 24);
;             }
	v_pk_add_f32 v[106:107], v[106:107], v[6:7] op_sel_hi:[1,0] neg_lo:[0,1] neg_hi:[0,1]
	s_nop 0
	v_pk_mul_f32 v[106:107], v[6:7], v[106:107] op_sel:[1,0]
	v_pk_add_f32 v[104:105], v[104:105], v[6:7] op_sel_hi:[1,0] neg_lo:[0,1] neg_hi:[0,1]
	v_pk_fma_f32 v[106:107], v[128:129], v[106:107], v[130:131]
	v_pk_mul_f32 v[6:7], v[6:7], v[104:105] op_sel:[1,0]
	v_and_b32_sdwa v104, v106, v216 dst_sel:DWORD dst_unused:UNUSED_PAD src0_sel:WORD_1 src1_sel:DWORD
	v_pk_fma_f32 v[6:7], v[0:1], v[6:7], v[4:5]
	v_add3_u32 v104, v106, v104, s78
	v_and_b32_e32 v105, 0xffff0000, v104
	v_and_b32_sdwa v104, v7, v216 dst_sel:DWORD dst_unused:UNUSED_PAD src0_sel:WORD_1 src1_sel:DWORD
	v_and_b32_sdwa v3, v107, v216 dst_sel:DWORD dst_unused:UNUSED_PAD src0_sel:WORD_1 src1_sel:DWORD
	v_and_b32_sdwa v124, v6, v216 dst_sel:DWORD dst_unused:UNUSED_PAD src0_sel:WORD_1 src1_sel:DWORD
	v_add3_u32 v104, v7, v104, s78
	v_add3_u32 v3, v107, v3, s78
	v_add3_u32 v126, v6, v124, s78
	v_and_b32_e32 v127, 0xffff0000, v104
	v_or_b32_sdwa v125, v127, v3 dst_sel:DWORD dst_unused:UNUSED_PAD src0_sel:DWORD src1_sel:WORD_1
	v_or_b32_sdwa v124, v126, v105 dst_sel:DWORD dst_unused:UNUSED_PAD src0_sel:WORD_1 src1_sel:DWORD
	v_add_u32_e32 v104, v2, v154
	ds_write_b64 v104, v[124:125]
	v_and_b32_e32 v124, 0xffff0000, v126
	v_sub_u32_e32 v105, v106, v105
	v_and_b32_e32 v3, 0xffff0000, v3
	v_sub_u32_e32 v6, v6, v124
	v_add_u32_e32 v105, 0x80, v105
	v_sub_u32_e32 v3, v107, v3
	v_sub_u32_e32 v7, v7, v127
	v_add_u32_e32 v6, 0x80, v6
	v_ashrrev_i32_e32 v105, 8, v105
	v_add_u32_e32 v3, 0x80, v3
	v_add_u32_e32 v7, 0x80, v7
	v_ashrrev_i32_e32 v6, 8, v6
	v_min_i32_e32 v105, 0x7f, v105
	v_ashrrev_i32_e32 v3, 8, v3
	v_ashrrev_i32_e32 v7, 8, v7
	v_min_i32_e32 v6, 0x7f, v6
	v_min_i32_sdwa v3, v3, s79 dst_sel:WORD_1 dst_unused:UNUSED_PAD src0_sel:DWORD src1_sel:DWORD
	v_min_i32_e32 v7, 0x7f, v7
	v_lshlrev_b32_e32 v105, 8, v105
	v_and_b32_e32 v105, 0xff00, v105
	v_and_b32_e32 v3, 0xff0000, v3
	v_perm_b32 v6, v7, v6, s80
	v_or3_b32 v3, v6, v105, v3
	ds_write_b32 v14, v3 offset:16
	ds_read_b64 v[6:7], v15
	s_waitcnt lgkmcnt(0)
	v_pk_add_f32 v[106:107], v[110:111], v[6:7] op_sel_hi:[1,0] neg_lo:[0,1] neg_hi:[0,1]
	s_nop 0
	v_pk_mul_f32 v[106:107], v[6:7], v[106:107] op_sel:[1,0]
	v_pk_add_f32 v[108:109], v[108:109], v[6:7] op_sel_hi:[1,0] neg_lo:[0,1] neg_hi:[0,1]
	v_pk_fma_f32 v[106:107], v[128:129], v[106:107], v[130:131]
	v_pk_mul_f32 v[6:7], v[6:7], v[108:109] op_sel:[1,0]
	v_and_b32_sdwa v105, v106, v216 dst_sel:DWORD dst_unused:UNUSED_PAD src0_sel:WORD_1 src1_sel:DWORD
	v_pk_fma_f32 v[6:7], v[0:1], v[6:7], v[4:5]
	v_add3_u32 v105, v106, v105, s78
	v_and_b32_e32 v110, 0xffff0000, v105
	v_and_b32_sdwa v105, v7, v216 dst_sel:DWORD dst_unused:UNUSED_PAD src0_sel:WORD_1 src1_sel:DWORD
	v_and_b32_sdwa v3, v107, v216 dst_sel:DWORD dst_unused:UNUSED_PAD src0_sel:WORD_1 src1_sel:DWORD
	v_and_b32_sdwa v108, v6, v216 dst_sel:DWORD dst_unused:UNUSED_PAD src0_sel:WORD_1 src1_sel:DWORD
	v_add3_u32 v105, v7, v105, s78
	v_add3_u32 v3, v107, v3, s78
	v_add3_u32 v111, v6, v108, s78
	v_and_b32_e32 v124, 0xffff0000, v105
	v_or_b32_sdwa v109, v124, v3 dst_sel:DWORD dst_unused:UNUSED_PAD src0_sel:DWORD src1_sel:WORD_1
	v_or_b32_sdwa v108, v111, v110 dst_sel:DWORD dst_unused:UNUSED_PAD src0_sel:WORD_1 src1_sel:DWORD
	v_add_u32_e32 v105, v2, v136
	ds_write_b64 v105, v[108:109]
	v_and_b32_e32 v108, 0xffff0000, v111
	v_sub_u32_e32 v106, v106, v110
	v_and_b32_e32 v3, 0xffff0000, v3
	v_sub_u32_e32 v6, v6, v108
	v_add_u32_e32 v106, 0x80, v106
	v_sub_u32_e32 v3, v107, v3
	v_sub_u32_e32 v7, v7, v124
	v_add_u32_e32 v6, 0x80, v6
	v_ashrrev_i32_e32 v106, 8, v106
	v_add_u32_e32 v3, 0x80, v3
	v_add_u32_e32 v7, 0x80, v7
	v_ashrrev_i32_e32 v6, 8, v6
	v_min_i32_e32 v106, 0x7f, v106
	v_ashrrev_i32_e32 v3, 8, v3
	v_ashrrev_i32_e32 v7, 8, v7
	v_min_i32_e32 v6, 0x7f, v6
	v_min_i32_sdwa v3, v3, s79 dst_sel:WORD_1 dst_unused:UNUSED_PAD src0_sel:DWORD src1_sel:DWORD
	v_min_i32_e32 v7, 0x7f, v7
	v_lshlrev_b32_e32 v106, 8, v106
	v_and_b32_e32 v106, 0xff00, v106
	v_and_b32_e32 v3, 0xff0000, v3
	v_perm_b32 v6, v7, v6, s80
	v_or3_b32 v3, v6, v106, v3
	ds_write_b32 v20, v3 offset:16
	ds_read_b64 v[6:7], v21
	s_waitcnt lgkmcnt(0)
	v_pk_add_f32 v[106:107], v[122:123], v[6:7] op_sel_hi:[1,0] neg_lo:[0,1] neg_hi:[0,1]
	s_nop 0
	v_pk_mul_f32 v[106:107], v[6:7], v[106:107] op_sel:[1,0]
	v_or_b32_e32 v122, 0x100, v155
	v_pk_fma_f32 v[108:109], v[128:129], v[106:107], v[130:131]
	v_pk_add_f32 v[106:107], v[114:115], v[6:7] op_sel_hi:[1,0] neg_lo:[0,1] neg_hi:[0,1]
	v_and_b32_sdwa v3, v109, v216 dst_sel:DWORD dst_unused:UNUSED_PAD src0_sel:WORD_1 src1_sel:DWORD
	v_pk_mul_f32 v[6:7], v[6:7], v[106:107] op_sel:[1,0]
	v_add3_u32 v3, v109, v3, s78
	v_pk_fma_f32 v[0:1], v[0:1], v[6:7], v[4:5]
	v_and_b32_sdwa v4, v108, v216 dst_sel:DWORD dst_unused:UNUSED_PAD src0_sel:WORD_1 src1_sel:DWORD
	v_add3_u32 v4, v108, v4, s78
	v_and_b32_e32 v6, 0xffff0000, v4
	v_and_b32_sdwa v4, v1, v216 dst_sel:DWORD dst_unused:UNUSED_PAD src0_sel:WORD_1 src1_sel:DWORD
	v_and_b32_sdwa v5, v0, v216 dst_sel:DWORD dst_unused:UNUSED_PAD src0_sel:WORD_1 src1_sel:DWORD
	v_add3_u32 v4, v1, v4, s78
	v_add3_u32 v7, v0, v5, s78
	v_and_b32_e32 v107, 0xffff0000, v4
	v_add_u32_e32 v106, v2, v135
	v_and_b32_e32 v2, 0xffff0000, v7
	v_or_b32_sdwa v5, v107, v3 dst_sel:DWORD dst_unused:UNUSED_PAD src0_sel:DWORD src1_sel:WORD_1
	v_sub_u32_e32 v0, v0, v2
	v_sub_u32_e32 v2, v108, v6
	v_and_b32_e32 v3, 0xffff0000, v3
	v_add_u32_e32 v2, 0x80, v2
	v_sub_u32_e32 v3, v109, v3
	v_sub_u32_e32 v1, v1, v107
	v_add_u32_e32 v0, 0x80, v0
	v_ashrrev_i32_e32 v2, 8, v2
	v_add_u32_e32 v3, 0x80, v3
	v_add_u32_e32 v1, 0x80, v1
	v_ashrrev_i32_e32 v0, 8, v0
	v_min_i32_e32 v2, 0x7f, v2
	v_ashrrev_i32_e32 v3, 8, v3
	v_ashrrev_i32_e32 v1, 8, v1
	v_min_i32_e32 v0, 0x7f, v0
	v_min_i32_sdwa v3, v3, s79 dst_sel:WORD_1 dst_unused:UNUSED_PAD src0_sel:DWORD src1_sel:DWORD
	v_min_i32_e32 v1, 0x7f, v1
	v_lshlrev_b32_e32 v2, 8, v2
	v_and_b32_e32 v2, 0xff00, v2
	v_and_b32_e32 v3, 0xff0000, v3
	v_perm_b32 v0, v1, v0, s80
	v_or_b32_sdwa v4, v7, v6 dst_sel:DWORD dst_unused:UNUSED_PAD src0_sel:WORD_1 src1_sel:DWORD
	v_or3_b32 v0, v0, v2, v3
	ds_write_b64 v106, v[4:5]
	ds_write_b32 v22, v0 offset:16
	v_mov_b32_e32 v0, v228
	v_mov_b32_e32 v1, v229
	v_mov_b32_e32 v2, v230
	v_mov_b32_e32 v3, v231
	v_mov_b32_e32 v4, v244
	v_mov_b32_e32 v5, v245
	v_mov_b32_e32 v6, v246
	v_mov_b32_e32 v7, v247
	ds_read_b64 v[114:115], v149
	v_add_u32_e32 v107, v122, v153
	s_waitcnt lgkmcnt(0)
;     ...
;           _Pragma("unroll") for (int bj = 0; bj < 2; ++bj) _Pragma("unroll") for (int n = 0; n < 2; ++n) {
;             const int cc = bj * HALF + wc3 * 32 + n * 16 + fq3 * 4;
;             const float4 gm = *reinterpret_cast<const float4*>(g.gam + pn * BM + cc), bt = *reinterpret_cast<const float4*>(g.bet + pn * BM + cc);
;             _Pragma("unroll") for (int m = 0; m < 4; ++m) {
;               const int rr = wr3 * 64 + m * 16 + fr3;
;               const float2 ms = *reinterpret_cast<const float2*>(mr + (ai * HALF + rr) * 2);
;               f32x4 y = acc[ai][bj][m][n];
;               const float o0 = (y[0] - ms.x) * ms.y * gm.x + bt.x, o1 = (y[1] - ms.x) * ms.y * gm.y + bt.y;
;               const float o2 = (y[2] - ms.x) * ms.y * gm.z + bt.z, o3 = (y[3] - ms.x) * ms.y * gm.w + bt.w;
;               const unsigned h0 = f2bf(o0), h1 = f2bf(o1), h2 = f2bf(o2), h3 = f2bf(o3);
;               u32x2 ob; ob[0] = h0 | (h1 << 16); ob[1] = h2 | (h3 << 16);
;               *reinterpret_cast<u32x2*>(smem + (rr >> 1) * PIECE + (rr & 1) * 512 + cc * 2) = ob;
;               const int l0 = min(((int)__float_as_uint(o0) - (int)(h0 << 16) + 128) >> 8, 127);
;               const int l1 = min(((int)__float_as_uint(o1) - (int)(h1 << 16) + 128) >> 8, 127);
;               const int l2 = min(((int)__float_as_uint(o2) - (int)(h2 << 16) + 128) >> 8, 127);
;               const int l3 = min(((int)__float_as_uint(o3) - (int)(h3 << 16) + 128) >> 8, 127);
;               *reinterpret_cast<unsigned*>(smem + LOBASE + (rr >> 2) * PIECE + (rr & 3) * 256 + cc) =
;                   (unsigned)(l0 & 255) | ((unsigned)(l1 & 255) << 8) | ((unsigned)(l2 & 255) << 16) | ((unsigned)l3 << 24);
;             }
	v_pk_add_f32 v[118:119], v[118:119], v[114:115] op_sel_hi:[1,0] neg_lo:[0,1] neg_hi:[0,1]
	s_nop 0
	v_pk_mul_f32 v[118:119], v[114:115], v[118:119] op_sel:[1,0]
	v_pk_add_f32 v[120:121], v[120:121], v[114:115] op_sel_hi:[1,0] neg_lo:[0,1] neg_hi:[0,1]
	v_mov_b32_e32 v108, v1
	v_mov_b32_e32 v109, v2
	v_mov_b32_e32 v110, v5
	v_mov_b32_e32 v111, v6
	v_pk_fma_f32 v[118:119], v[108:109], v[118:119], v[110:111]
	v_pk_mul_f32 v[114:115], v[114:115], v[120:121] op_sel:[1,0]
	v_mov_b32_e32 v1, v3
	v_mov_b32_e32 v5, v7
	v_and_b32_sdwa v6, v119, v216 dst_sel:DWORD dst_unused:UNUSED_PAD src0_sel:WORD_1 src1_sel:DWORD
	v_and_b32_sdwa v7, v118, v216 dst_sel:DWORD dst_unused:UNUSED_PAD src0_sel:WORD_1 src1_sel:DWORD
	v_pk_fma_f32 v[2:3], v[0:1], v[114:115], v[4:5]
	v_add3_u32 v114, v119, v6, s78
	v_add3_u32 v6, v118, v7, s78
	v_and_b32_e32 v115, 0xffff0000, v6
	v_and_b32_sdwa v6, v3, v216 dst_sel:DWORD dst_unused:UNUSED_PAD src0_sel:WORD_1 src1_sel:DWORD
	v_and_b32_sdwa v7, v2, v216 dst_sel:DWORD dst_unused:UNUSED_PAD src0_sel:WORD_1 src1_sel:DWORD
	v_add3_u32 v6, v3, v6, s78
	v_add3_u32 v120, v2, v7, s78
	v_and_b32_e32 v121, 0xffff0000, v6
	v_or_b32_sdwa v7, v121, v114 dst_sel:DWORD dst_unused:UNUSED_PAD src0_sel:DWORD src1_sel:WORD_1
	v_or_b32_sdwa v6, v120, v115 dst_sel:DWORD dst_unused:UNUSED_PAD src0_sel:WORD_1 src1_sel:DWORD
	ds_write_b64 v107, v[6:7]
	v_and_b32_e32 v6, 0xffff0000, v120
	v_sub_u32_e32 v2, v2, v6
	v_sub_u32_e32 v6, v118, v115
	v_and_b32_e32 v7, 0xffff0000, v114
	v_add_u32_e32 v6, 0x80, v6
	v_sub_u32_e32 v7, v119, v7
	v_sub_u32_e32 v3, v3, v121
	v_add_u32_e32 v2, 0x80, v2
	v_ashrrev_i32_e32 v6, 8, v6
	v_add_u32_e32 v7, 0x80, v7
	v_add_u32_e32 v3, 0x80, v3
	v_ashrrev_i32_e32 v2, 8, v2
	v_min_i32_e32 v6, 0x7f, v6
	v_ashrrev_i32_e32 v7, 8, v7
	v_ashrrev_i32_e32 v3, 8, v3
	v_min_i32_e32 v2, 0x7f, v2
	v_min_i32_sdwa v7, v7, s79 dst_sel:WORD_1 dst_unused:UNUSED_PAD src0_sel:DWORD src1_sel:DWORD
	v_min_i32_e32 v3, 0x7f, v3
	v_lshlrev_b32_e32 v6, 8, v6
	v_and_b32_e32 v6, 0xff00, v6
	v_and_b32_e32 v7, 0xff0000, v7
	v_perm_b32 v2, v3, v2, s80
	v_or3_b32 v2, v2, v6, v7
	ds_write_b32 v12, v2 offset:128
	ds_read_b64 v[2:3], v13
	s_waitcnt lgkmcnt(0)
	v_pk_add_f32 v[6:7], v[102:103], v[2:3] op_sel_hi:[1,0] neg_lo:[0,1] neg_hi:[0,1]
	s_nop 0
	v_pk_mul_f32 v[6:7], v[2:3], v[6:7] op_sel:[1,0]
	v_pk_add_f32 v[100:101], v[100:101], v[2:3] op_sel_hi:[1,0] neg_lo:[0,1] neg_hi:[0,1]
	v_pk_fma_f32 v[6:7], v[108:109], v[6:7], v[110:111]
	v_pk_mul_f32 v[2:3], v[2:3], v[100:101] op_sel:[1,0]
	v_and_b32_sdwa v100, v7, v216 dst_sel:DWORD dst_unused:UNUSED_PAD src0_sel:WORD_1 src1_sel:DWORD
	v_and_b32_sdwa v101, v6, v216 dst_sel:DWORD dst_unused:UNUSED_PAD src0_sel:WORD_1 src1_sel:DWORD
	v_pk_fma_f32 v[2:3], v[0:1], v[2:3], v[4:5]
	v_add3_u32 v114, v7, v100, s78
	v_add3_u32 v100, v6, v101, s78
	v_and_b32_e32 v101, 0xffff0000, v100
	v_and_b32_sdwa v100, v3, v216 dst_sel:DWORD dst_unused:UNUSED_PAD src0_sel:WORD_1 src1_sel:DWORD
	v_and_b32_sdwa v102, v2, v216 dst_sel:DWORD dst_unused:UNUSED_PAD src0_sel:WORD_1 src1_sel:DWORD
	v_add3_u32 v100, v3, v100, s78
	v_add3_u32 v115, v2, v102, s78
	v_and_b32_e32 v118, 0xffff0000, v100
	v_or_b32_sdwa v103, v118, v114 dst_sel:DWORD dst_unused:UNUSED_PAD src0_sel:DWORD src1_sel:WORD_1
	v_or_b32_sdwa v102, v115, v101 dst_sel:DWORD dst_unused:UNUSED_PAD src0_sel:WORD_1 src1_sel:DWORD
	v_add_u32_e32 v100, v122, v154
	ds_write_b64 v100, v[102:103]
	v_and_b32_e32 v102, 0xffff0000, v115
	v_sub_u32_e32 v6, v6, v101
	v_and_b32_e32 v101, 0xffff0000, v114
	v_sub_u32_e32 v2, v2, v102
	v_add_u32_e32 v6, 0x80, v6
	v_sub_u32_e32 v7, v7, v101
	v_sub_u32_e32 v3, v3, v118
	v_add_u32_e32 v2, 0x80, v2
	v_ashrrev_i32_e32 v6, 8, v6
	v_add_u32_e32 v7, 0x80, v7
	v_add_u32_e32 v3, 0x80, v3
	v_ashrrev_i32_e32 v2, 8, v2
	v_min_i32_e32 v6, 0x7f, v6
	v_ashrrev_i32_e32 v7, 8, v7
	v_ashrrev_i32_e32 v3, 8, v3
	v_min_i32_e32 v2, 0x7f, v2
	v_min_i32_sdwa v7, v7, s79 dst_sel:WORD_1 dst_unused:UNUSED_PAD src0_sel:DWORD src1_sel:DWORD
	v_min_i32_e32 v3, 0x7f, v3
	v_lshlrev_b32_e32 v6, 8, v6
	v_and_b32_e32 v6, 0xff00, v6
	v_and_b32_e32 v7, 0xff0000, v7
	v_perm_b32 v2, v3, v2, s80
	v_or3_b32 v2, v2, v6, v7
	ds_write_b32 v14, v2 offset:128
	ds_read_b64 v[2:3], v15
	v_add_u32_e32 v101, v122, v136
	s_waitcnt lgkmcnt(0)
	v_pk_add_f32 v[6:7], v[90:91], v[2:3] op_sel_hi:[1,0] neg_lo:[0,1] neg_hi:[0,1]
	s_nop 0
	v_pk_mul_f32 v[6:7], v[2:3], v[6:7] op_sel:[1,0]
	v_pk_add_f32 v[88:89], v[88:89], v[2:3] op_sel_hi:[1,0] neg_lo:[0,1] neg_hi:[0,1]
	v_pk_fma_f32 v[6:7], v[108:109], v[6:7], v[110:111]
	v_pk_mul_f32 v[2:3], v[2:3], v[88:89] op_sel:[1,0]
	v_and_b32_sdwa v88, v7, v216 dst_sel:DWORD dst_unused:UNUSED_PAD src0_sel:WORD_1 src1_sel:DWORD
	v_and_b32_sdwa v89, v6, v216 dst_sel:DWORD dst_unused:UNUSED_PAD src0_sel:WORD_1 src1_sel:DWORD
	v_pk_fma_f32 v[2:3], v[0:1], v[2:3], v[4:5]
	v_add3_u32 v90, v7, v88, s78
	v_add3_u32 v88, v6, v89, s78
	v_and_b32_e32 v91, 0xffff0000, v88
	v_and_b32_sdwa v88, v3, v216 dst_sel:DWORD dst_unused:UNUSED_PAD src0_sel:WORD_1 src1_sel:DWORD
	v_and_b32_sdwa v89, v2, v216 dst_sel:DWORD dst_unused:UNUSED_PAD src0_sel:WORD_1 src1_sel:DWORD
	v_add3_u32 v88, v3, v88, s78
	v_add3_u32 v102, v2, v89, s78
	v_and_b32_e32 v103, 0xffff0000, v88
	v_or_b32_sdwa v89, v103, v90 dst_sel:DWORD dst_unused:UNUSED_PAD src0_sel:DWORD src1_sel:WORD_1
	v_or_b32_sdwa v88, v102, v91 dst_sel:DWORD dst_unused:UNUSED_PAD src0_sel:WORD_1 src1_sel:DWORD
	ds_write_b64 v101, v[88:89]
	v_and_b32_e32 v88, 0xffff0000, v102
	v_sub_u32_e32 v2, v2, v88
	v_sub_u32_e32 v6, v6, v91
	v_and_b32_e32 v88, 0xffff0000, v90
	v_add_u32_e32 v6, 0x80, v6
	v_sub_u32_e32 v7, v7, v88
	v_sub_u32_e32 v3, v3, v103
	v_add_u32_e32 v2, 0x80, v2
	v_ashrrev_i32_e32 v6, 8, v6
	v_add_u32_e32 v7, 0x80, v7
	v_add_u32_e32 v3, 0x80, v3
	v_ashrrev_i32_e32 v2, 8, v2
	v_min_i32_e32 v6, 0x7f, v6
	v_ashrrev_i32_e32 v7, 8, v7
	v_ashrrev_i32_e32 v3, 8, v3
	v_min_i32_e32 v2, 0x7f, v2
	v_min_i32_sdwa v7, v7, s79 dst_sel:WORD_1 dst_unused:UNUSED_PAD src0_sel:DWORD src1_sel:DWORD
	v_min_i32_e32 v3, 0x7f, v3
	v_lshlrev_b32_e32 v6, 8, v6
	v_and_b32_e32 v6, 0xff00, v6
	v_and_b32_e32 v7, 0xff0000, v7
	v_perm_b32 v2, v3, v2, s80
	v_or3_b32 v2, v2, v6, v7
	ds_write_b32 v20, v2 offset:128
	ds_read_b64 v[2:3], v21
	s_waitcnt lgkmcnt(0)
;     ...
;           _Pragma("unroll") for (int bj = 0; bj < 2; ++bj) _Pragma("unroll") for (int n = 0; n < 2; ++n) {
;             const int cc = bj * HALF + wc3 * 32 + n * 16 + fq3 * 4;
;             const float4 gm = *reinterpret_cast<const float4*>(g.gam + pn * BM + cc), bt = *reinterpret_cast<const float4*>(g.bet + pn * BM + cc);
;             _Pragma("unroll") for (int m = 0; m < 4; ++m) {
;               const int rr = wr3 * 64 + m * 16 + fr3;
;               const float2 ms = *reinterpret_cast<const float2*>(mr + (ai * HALF + rr) * 2);
;               f32x4 y = acc[ai][bj][m][n];
;               const float o0 = (y[0] - ms.x) * ms.y * gm.x + bt.x, o1 = (y[1] - ms.x) * ms.y * gm.y + bt.y;
;               const float o2 = (y[2] - ms.x) * ms.y * gm.z + bt.z, o3 = (y[3] - ms.x) * ms.y * gm.w + bt.w;
;               const unsigned h0 = f2bf(o0), h1 = f2bf(o1), h2 = f2bf(o2), h3 = f2bf(o3);
;               u32x2 ob; ob[0] = h0 | (h1 << 16); ob[1] = h2 | (h3 << 16);
;               *reinterpret_cast<u32x2*>(smem + (rr >> 1) * PIECE + (rr & 1) * 512 + cc * 2) = ob;
;               const int l0 = min(((int)__float_as_uint(o0) - (int)(h0 << 16) + 128) >> 8, 127);
;               const int l1 = min(((int)__float_as_uint(o1) - (int)(h1 << 16) + 128) >> 8, 127);
;               const int l2 = min(((int)__float_as_uint(o2) - (int)(h2 << 16) + 128) >> 8, 127);
;               const int l3 = min(((int)__float_as_uint(o3) - (int)(h3 << 16) + 128) >> 8, 127);
;               *reinterpret_cast<unsigned*>(smem + LOBASE + (rr >> 2) * PIECE + (rr & 3) * 256 + cc) =
;                   (unsigned)(l0 & 255) | ((unsigned)(l1 & 255) << 8) | ((unsigned)(l2 & 255) << 16) | ((unsigned)l3 << 24);
;             }
	v_pk_add_f32 v[6:7], v[94:95], v[2:3] op_sel_hi:[1,0] neg_lo:[0,1] neg_hi:[0,1]
	s_nop 0
	v_pk_mul_f32 v[6:7], v[2:3], v[6:7] op_sel:[1,0]
	v_pk_add_f32 v[88:89], v[92:93], v[2:3] op_sel_hi:[1,0] neg_lo:[0,1] neg_hi:[0,1]
	v_pk_fma_f32 v[6:7], v[108:109], v[6:7], v[110:111]
	v_pk_mul_f32 v[2:3], v[2:3], v[88:89] op_sel:[1,0]
	v_add_u32_e32 v92, v122, v135
	v_pk_fma_f32 v[0:1], v[0:1], v[2:3], v[4:5]
	v_and_b32_sdwa v2, v7, v216 dst_sel:DWORD dst_unused:UNUSED_PAD src0_sel:WORD_1 src1_sel:DWORD
	v_and_b32_sdwa v3, v6, v216 dst_sel:DWORD dst_unused:UNUSED_PAD src0_sel:WORD_1 src1_sel:DWORD
	v_add3_u32 v4, v7, v2, s78
	v_add3_u32 v2, v6, v3, s78
	v_and_b32_e32 v5, 0xffff0000, v2
	v_and_b32_sdwa v2, v1, v216 dst_sel:DWORD dst_unused:UNUSED_PAD src0_sel:WORD_1 src1_sel:DWORD
	v_and_b32_sdwa v3, v0, v216 dst_sel:DWORD dst_unused:UNUSED_PAD src0_sel:WORD_1 src1_sel:DWORD
	v_add3_u32 v2, v1, v2, s78
	v_add3_u32 v88, v0, v3, s78
	v_and_b32_e32 v89, 0xffff0000, v2
	v_or_b32_sdwa v3, v89, v4 dst_sel:DWORD dst_unused:UNUSED_PAD src0_sel:DWORD src1_sel:WORD_1
	v_or_b32_sdwa v2, v88, v5 dst_sel:DWORD dst_unused:UNUSED_PAD src0_sel:WORD_1 src1_sel:DWORD
	ds_write_b64 v92, v[2:3]
	v_and_b32_e32 v2, 0xffff0000, v88
	v_sub_u32_e32 v0, v0, v2
	v_sub_u32_e32 v2, v6, v5
	v_and_b32_e32 v3, 0xffff0000, v4
	v_add_u32_e32 v2, 0x80, v2
	v_sub_u32_e32 v3, v7, v3
	v_sub_u32_e32 v1, v1, v89
	v_add_u32_e32 v0, 0x80, v0
	v_ashrrev_i32_e32 v2, 8, v2
	v_add_u32_e32 v3, 0x80, v3
	v_add_u32_e32 v1, 0x80, v1
	v_ashrrev_i32_e32 v0, 8, v0
	v_min_i32_e32 v2, 0x7f, v2
	v_ashrrev_i32_e32 v3, 8, v3
	v_ashrrev_i32_e32 v1, 8, v1
	v_min_i32_e32 v0, 0x7f, v0
	v_min_i32_sdwa v3, v3, s79 dst_sel:WORD_1 dst_unused:UNUSED_PAD src0_sel:DWORD src1_sel:DWORD
	v_min_i32_e32 v1, 0x7f, v1
	v_lshlrev_b32_e32 v2, 8, v2
	v_and_b32_e32 v2, 0xff00, v2
	v_and_b32_e32 v3, 0xff0000, v3
	v_perm_b32 v0, v1, v0, s80
	v_or3_b32 v0, v0, v2, v3
	ds_write_b32 v22, v0 offset:128
	v_mov_b32_e32 v0, v232
	v_mov_b32_e32 v1, v233
	v_mov_b32_e32 v2, v234
	v_mov_b32_e32 v3, v235
	v_mov_b32_e32 v4, v248
	v_mov_b32_e32 v5, v249
	v_mov_b32_e32 v6, v250
	v_mov_b32_e32 v7, v251
	ds_read_b64 v[94:95], v149
	s_waitcnt lgkmcnt(0)
	v_pk_add_f32 v[102:103], v[116:117], v[94:95] op_sel_hi:[1,0] neg_lo:[0,1] neg_hi:[0,1]
	s_nop 0
	v_pk_mul_f32 v[102:103], v[94:95], v[102:103] op_sel:[1,0]
	v_pk_add_f32 v[108:109], v[112:113], v[94:95] op_sel_hi:[1,0] neg_lo:[0,1] neg_hi:[0,1]
	v_mov_b32_e32 v88, v1
	v_mov_b32_e32 v89, v2
	v_mov_b32_e32 v90, v5
	v_mov_b32_e32 v91, v6
	v_pk_fma_f32 v[102:103], v[88:89], v[102:103], v[90:91]
	v_pk_mul_f32 v[94:95], v[94:95], v[108:109] op_sel:[1,0]
	v_mov_b32_e32 v1, v3
	v_mov_b32_e32 v5, v7
	v_and_b32_sdwa v93, v102, v216 dst_sel:DWORD dst_unused:UNUSED_PAD src0_sel:WORD_1 src1_sel:DWORD
	v_pk_fma_f32 v[6:7], v[0:1], v[94:95], v[4:5]
	v_add3_u32 v93, v102, v93, s78
	v_and_b32_e32 v108, 0xffff0000, v93
	v_and_b32_sdwa v93, v7, v216 dst_sel:DWORD dst_unused:UNUSED_PAD src0_sel:WORD_1 src1_sel:DWORD
	v_and_b32_sdwa v3, v103, v216 dst_sel:DWORD dst_unused:UNUSED_PAD src0_sel:WORD_1 src1_sel:DWORD
	v_and_b32_sdwa v94, v6, v216 dst_sel:DWORD dst_unused:UNUSED_PAD src0_sel:WORD_1 src1_sel:DWORD
	v_add3_u32 v93, v7, v93, s78
	v_or_b32_e32 v2, 0x120, v155
	v_add3_u32 v3, v103, v3, s78
	v_add3_u32 v109, v6, v94, s78
	v_and_b32_e32 v110, 0xffff0000, v93
	v_or_b32_sdwa v95, v110, v3 dst_sel:DWORD dst_unused:UNUSED_PAD src0_sel:DWORD src1_sel:WORD_1
	v_or_b32_sdwa v94, v109, v108 dst_sel:DWORD dst_unused:UNUSED_PAD src0_sel:WORD_1 src1_sel:DWORD
	v_add_u32_e32 v93, v2, v153
	ds_write_b64 v93, v[94:95]
	v_and_b32_e32 v94, 0xffff0000, v109
	v_sub_u32_e32 v6, v6, v94
	v_sub_u32_e32 v94, v102, v108
	v_and_b32_e32 v3, 0xffff0000, v3
	v_add_u32_e32 v94, 0x80, v94
	v_sub_u32_e32 v3, v103, v3
	v_sub_u32_e32 v7, v7, v110
	v_add_u32_e32 v6, 0x80, v6
	v_ashrrev_i32_e32 v94, 8, v94
	v_add_u32_e32 v3, 0x80, v3
	v_add_u32_e32 v7, 0x80, v7
	v_ashrrev_i32_e32 v6, 8, v6
	v_min_i32_e32 v94, 0x7f, v94
	v_ashrrev_i32_e32 v3, 8, v3
	v_ashrrev_i32_e32 v7, 8, v7
	v_min_i32_e32 v6, 0x7f, v6
	v_min_i32_sdwa v3, v3, s79 dst_sel:WORD_1 dst_unused:UNUSED_PAD src0_sel:DWORD src1_sel:DWORD
	v_min_i32_e32 v7, 0x7f, v7
	v_lshlrev_b32_e32 v94, 8, v94
	v_and_b32_e32 v94, 0xff00, v94
	v_and_b32_e32 v3, 0xff0000, v3
	v_perm_b32 v6, v7, v6, s80
	v_or3_b32 v3, v6, v94, v3
	ds_write_b32 v12, v3 offset:144
	ds_read_b64 v[6:7], v13
	s_waitcnt lgkmcnt(0)
	v_pk_add_f32 v[94:95], v[98:99], v[6:7] op_sel_hi:[1,0] neg_lo:[0,1] neg_hi:[0,1]
	s_nop 0
	v_pk_mul_f32 v[94:95], v[6:7], v[94:95] op_sel:[1,0]
	s_nop 0
	v_pk_fma_f32 v[98:99], v[88:89], v[94:95], v[90:91]
	v_pk_add_f32 v[94:95], v[96:97], v[6:7] op_sel_hi:[1,0] neg_lo:[0,1] neg_hi:[0,1]
	v_and_b32_sdwa v3, v99, v216 dst_sel:DWORD dst_unused:UNUSED_PAD src0_sel:WORD_1 src1_sel:DWORD
	v_pk_mul_f32 v[6:7], v[6:7], v[94:95] op_sel:[1,0]
	v_and_b32_sdwa v94, v98, v216 dst_sel:DWORD dst_unused:UNUSED_PAD src0_sel:WORD_1 src1_sel:DWORD
	v_pk_fma_f32 v[6:7], v[0:1], v[6:7], v[4:5]
	v_add3_u32 v94, v98, v94, s78
	v_and_b32_e32 v95, 0xffff0000, v94
	v_and_b32_sdwa v94, v7, v216 dst_sel:DWORD dst_unused:UNUSED_PAD src0_sel:WORD_1 src1_sel:DWORD
	v_and_b32_sdwa v96, v6, v216 dst_sel:DWORD dst_unused:UNUSED_PAD src0_sel:WORD_1 src1_sel:DWORD
	v_add3_u32 v94, v7, v94, s78
	v_add3_u32 v3, v99, v3, s78
	v_add3_u32 v102, v6, v96, s78
	v_and_b32_e32 v103, 0xffff0000, v94
	v_or_b32_sdwa v97, v103, v3 dst_sel:DWORD dst_unused:UNUSED_PAD src0_sel:DWORD src1_sel:WORD_1
	v_or_b32_sdwa v96, v102, v95 dst_sel:DWORD dst_unused:UNUSED_PAD src0_sel:WORD_1 src1_sel:DWORD
	v_add_u32_e32 v94, v2, v154
	ds_write_b64 v94, v[96:97]
	v_and_b32_e32 v96, 0xffff0000, v102
	v_sub_u32_e32 v95, v98, v95
	v_and_b32_e32 v3, 0xffff0000, v3
	v_sub_u32_e32 v6, v6, v96
	v_add_u32_e32 v95, 0x80, v95
	v_sub_u32_e32 v3, v99, v3
	v_sub_u32_e32 v7, v7, v103
	v_add_u32_e32 v6, 0x80, v6
	v_ashrrev_i32_e32 v95, 8, v95
	v_add_u32_e32 v3, 0x80, v3
	v_add_u32_e32 v7, 0x80, v7
	v_ashrrev_i32_e32 v6, 8, v6
	v_min_i32_e32 v95, 0x7f, v95
	v_ashrrev_i32_e32 v3, 8, v3
	v_ashrrev_i32_e32 v7, 8, v7
	v_min_i32_e32 v6, 0x7f, v6
	v_min_i32_sdwa v3, v3, s79 dst_sel:WORD_1 dst_unused:UNUSED_PAD src0_sel:DWORD src1_sel:DWORD
	v_min_i32_e32 v7, 0x7f, v7
	v_lshlrev_b32_e32 v95, 8, v95
	v_and_b32_e32 v95, 0xff00, v95
	v_and_b32_e32 v3, 0xff0000, v3
	v_perm_b32 v6, v7, v6, s80
	v_or3_b32 v3, v6, v95, v3
	ds_write_b32 v14, v3 offset:144
	ds_read_b64 v[6:7], v15
	s_waitcnt lgkmcnt(0)
;     ...
;           _Pragma("unroll") for (int bj = 0; bj < 2; ++bj) _Pragma("unroll") for (int n = 0; n < 2; ++n) {
;             const int cc = bj * HALF + wc3 * 32 + n * 16 + fq3 * 4;
;             const float4 gm = *reinterpret_cast<const float4*>(g.gam + pn * BM + cc), bt = *reinterpret_cast<const float4*>(g.bet + pn * BM + cc);
;             _Pragma("unroll") for (int m = 0; m < 4; ++m) {
;               const int rr = wr3 * 64 + m * 16 + fr3;
;               const float2 ms = *reinterpret_cast<const float2*>(mr + (ai * HALF + rr) * 2);
;               f32x4 y = acc[ai][bj][m][n];
;               const float o0 = (y[0] - ms.x) * ms.y * gm.x + bt.x, o1 = (y[1] - ms.x) * ms.y * gm.y + bt.y;
;               const float o2 = (y[2] - ms.x) * ms.y * gm.z + bt.z, o3 = (y[3] - ms.x) * ms.y * gm.w + bt.w;
;               const unsigned h0 = f2bf(o0), h1 = f2bf(o1), h2 = f2bf(o2), h3 = f2bf(o3);
;               u32x2 ob; ob[0] = h0 | (h1 << 16); ob[1] = h2 | (h3 << 16);
;               *reinterpret_cast<u32x2*>(smem + (rr >> 1) * PIECE + (rr & 1) * 512 + cc * 2) = ob;
;               const int l0 = min(((int)__float_as_uint(o0) - (int)(h0 << 16) + 128) >> 8, 127);
;               const int l1 = min(((int)__float_as_uint(o1) - (int)(h1 << 16) + 128) >> 8, 127);
;               const int l2 = min(((int)__float_as_uint(o2) - (int)(h2 << 16) + 128) >> 8, 127);
;               const int l3 = min(((int)__float_as_uint(o3) - (int)(h3 << 16) + 128) >> 8, 127);
;               *reinterpret_cast<unsigned*>(smem + LOBASE + (rr >> 2) * PIECE + (rr & 3) * 256 + cc) =
;                   (unsigned)(l0 & 255) | ((unsigned)(l1 & 255) << 8) | ((unsigned)(l2 & 255) << 16) | ((unsigned)l3 << 24);
;             }
;           }
;           WAIT_L(0); BAR;
;           const int hso = ((brow + ai * HALF + 16 * wave) * DM + pn * BM) * 2;
;           const int lso = (brow + ai * HALF + 16 * wave) * DM + pn * BM;
;           _Pragma("unroll") for (int i = 0; i < 8; ++i) {
;             const u32x4 v = *reinterpret_cast<const u32x4*>(smem + (wave * 8 + i) * PIECE + lane3 * 16);
;             __builtin_amdgcn_raw_buffer_store_b128(v, rsXB, hvo + i * (2 * DM * 2), hso, 0);
;           }
;           _Pragma("unroll") for (int i = 0; i < 4; ++i) {
;             const u32x4 v = *reinterpret_cast<const u32x4*>(smem + LOBASE + (wave * 4 + i) * PIECE + lane3 * 16);
	v_pk_add_f32 v[82:83], v[82:83], v[6:7] op_sel_hi:[1,0] neg_lo:[0,1] neg_hi:[0,1]
	s_nop 0
	v_pk_mul_f32 v[82:83], v[6:7], v[82:83] op_sel:[1,0]
	v_pk_add_f32 v[80:81], v[80:81], v[6:7] op_sel_hi:[1,0] neg_lo:[0,1] neg_hi:[0,1]
	v_pk_fma_f32 v[82:83], v[88:89], v[82:83], v[90:91]
	v_pk_mul_f32 v[6:7], v[6:7], v[80:81] op_sel:[1,0]
	v_and_b32_sdwa v80, v82, v216 dst_sel:DWORD dst_unused:UNUSED_PAD src0_sel:WORD_1 src1_sel:DWORD
	v_pk_fma_f32 v[6:7], v[0:1], v[6:7], v[4:5]
	v_add3_u32 v80, v82, v80, s78
	v_and_b32_e32 v81, 0xffff0000, v80
	v_and_b32_sdwa v80, v7, v216 dst_sel:DWORD dst_unused:UNUSED_PAD src0_sel:WORD_1 src1_sel:DWORD
	v_and_b32_sdwa v3, v83, v216 dst_sel:DWORD dst_unused:UNUSED_PAD src0_sel:WORD_1 src1_sel:DWORD
	v_and_b32_sdwa v95, v6, v216 dst_sel:DWORD dst_unused:UNUSED_PAD src0_sel:WORD_1 src1_sel:DWORD
	v_add3_u32 v80, v7, v80, s78
	v_add3_u32 v3, v83, v3, s78
	v_add3_u32 v95, v6, v95, s78
	v_and_b32_e32 v98, 0xffff0000, v80
	v_or_b32_sdwa v97, v98, v3 dst_sel:DWORD dst_unused:UNUSED_PAD src0_sel:DWORD src1_sel:WORD_1
	v_or_b32_sdwa v96, v95, v81 dst_sel:DWORD dst_unused:UNUSED_PAD src0_sel:WORD_1 src1_sel:DWORD
	v_and_b32_e32 v95, 0xffff0000, v95
	v_sub_u32_e32 v81, v82, v81
	v_and_b32_e32 v3, 0xffff0000, v3
	v_sub_u32_e32 v6, v6, v95
	v_add_u32_e32 v81, 0x80, v81
	v_sub_u32_e32 v3, v83, v3
	v_sub_u32_e32 v7, v7, v98
	v_add_u32_e32 v6, 0x80, v6
	v_ashrrev_i32_e32 v81, 8, v81
	v_add_u32_e32 v3, 0x80, v3
	v_add_u32_e32 v7, 0x80, v7
	v_ashrrev_i32_e32 v6, 8, v6
	v_min_i32_e32 v81, 0x7f, v81
	v_ashrrev_i32_e32 v3, 8, v3
	v_ashrrev_i32_e32 v7, 8, v7
	v_min_i32_e32 v6, 0x7f, v6
	v_min_i32_sdwa v3, v3, s79 dst_sel:WORD_1 dst_unused:UNUSED_PAD src0_sel:DWORD src1_sel:DWORD
	v_min_i32_e32 v7, 0x7f, v7
	v_lshlrev_b32_e32 v81, 8, v81
	v_and_b32_e32 v81, 0xff00, v81
	v_and_b32_e32 v3, 0xff0000, v3
	v_perm_b32 v6, v7, v6, s80
	v_add_u32_e32 v80, v2, v136
	v_or3_b32 v3, v6, v81, v3
	ds_write_b64 v80, v[96:97]
	ds_write_b32 v20, v3 offset:144
	ds_read_b64 v[6:7], v21
	v_or_b32_e32 v81, 0x6000, v148
	v_or_b32_e32 v82, 0x8000, v148
	v_or_b32_e32 v83, 0xa000, v148
	v_or_b32_e32 v95, 0x6000, v146
	s_waitcnt lgkmcnt(0)
	v_pk_add_f32 v[74:75], v[74:75], v[6:7] op_sel_hi:[1,0] neg_lo:[0,1] neg_hi:[0,1]
	v_pk_add_f32 v[72:73], v[72:73], v[6:7] op_sel_hi:[1,0] neg_lo:[0,1] neg_hi:[0,1]
	v_pk_mul_f32 v[74:75], v[6:7], v[74:75] op_sel:[1,0]
	v_pk_mul_f32 v[6:7], v[6:7], v[72:73] op_sel:[1,0]
	v_pk_fma_f32 v[74:75], v[88:89], v[74:75], v[90:91]
	v_pk_fma_f32 v[0:1], v[0:1], v[6:7], v[4:5]
	v_and_b32_sdwa v4, v74, v216 dst_sel:DWORD dst_unused:UNUSED_PAD src0_sel:WORD_1 src1_sel:DWORD
	v_add3_u32 v4, v74, v4, s78
	v_and_b32_e32 v6, 0xffff0000, v4
	v_and_b32_sdwa v4, v1, v216 dst_sel:DWORD dst_unused:UNUSED_PAD src0_sel:WORD_1 src1_sel:DWORD
	v_and_b32_sdwa v5, v0, v216 dst_sel:DWORD dst_unused:UNUSED_PAD src0_sel:WORD_1 src1_sel:DWORD
	v_and_b32_sdwa v3, v75, v216 dst_sel:DWORD dst_unused:UNUSED_PAD src0_sel:WORD_1 src1_sel:DWORD
	v_add3_u32 v4, v1, v4, s78
	v_add3_u32 v7, v0, v5, s78
	v_add3_u32 v3, v75, v3, s78
	v_and_b32_e32 v72, 0xffff0000, v4
	v_add_u32_e32 v73, v2, v135
	v_and_b32_e32 v2, 0xffff0000, v7
	v_or_b32_sdwa v5, v72, v3 dst_sel:DWORD dst_unused:UNUSED_PAD src0_sel:DWORD src1_sel:WORD_1
	v_sub_u32_e32 v0, v0, v2
	v_sub_u32_e32 v2, v74, v6
	v_and_b32_e32 v3, 0xffff0000, v3
	v_add_u32_e32 v2, 0x80, v2
	v_sub_u32_e32 v3, v75, v3
	v_sub_u32_e32 v1, v1, v72
	v_add_u32_e32 v0, 0x80, v0
	v_ashrrev_i32_e32 v2, 8, v2
	v_add_u32_e32 v3, 0x80, v3
	v_add_u32_e32 v1, 0x80, v1
	v_ashrrev_i32_e32 v0, 8, v0
	v_min_i32_e32 v2, 0x7f, v2
	v_ashrrev_i32_e32 v3, 8, v3
	v_ashrrev_i32_e32 v1, 8, v1
	v_min_i32_e32 v0, 0x7f, v0
	v_min_i32_sdwa v3, v3, s79 dst_sel:WORD_1 dst_unused:UNUSED_PAD src0_sel:DWORD src1_sel:DWORD
	v_min_i32_e32 v1, 0x7f, v1
	v_lshlrev_b32_e32 v2, 8, v2
	v_and_b32_e32 v2, 0xff00, v2
	v_and_b32_e32 v3, 0xff0000, v3
	v_perm_b32 v0, v1, v0, s80
	v_or_b32_sdwa v4, v7, v6 dst_sel:DWORD dst_unused:UNUSED_PAD src0_sel:WORD_1 src1_sel:DWORD
	v_or3_b32 v0, v0, v2, v3
	ds_write_b64 v73, v[4:5]
	ds_write_b32 v22, v0 offset:144
	v_add_u32_e32 v72, s60, v151
	s_waitcnt lgkmcnt(0)
	s_barrier
	ds_read_b128 v[128:131], v72
	v_or_b32_e32 v74, 0x2000, v148
	v_or_b32_e32 v75, 0x4000, v148
	v_or_b32_e32 v88, 0xc000, v148
	v_or_b32_e32 v89, 0xe000, v148
	ds_read_b128 v[136:139], v72 offset:1040
	v_or_b32_e32 v90, 0x2000, v146
	v_or_b32_e32 v91, 0x4000, v146
	ds_read_b128 v[140:143], v72 offset:2080
	ds_read_b128 v[156:159], v72 offset:3120
	ds_read_b128 v[160:163], v72 offset:4160
	ds_read_b128 v[164:167], v72 offset:5200
	ds_read_b128 v[168:171], v72 offset:6240
	ds_read_b128 v[172:175], v72 offset:7280
	ds_read_b128 v[176:179], v147
	ds_read_b128 v[180:183], v147 offset:1040
	ds_read_b128 v[184:187], v147 offset:2080
	ds_read_b128 v[188:191], v147 offset:3120
	s_waitcnt lgkmcnt(0)
	s_barrier
;     ...
;           _Pragma("unroll") for (int bj = 0; bj < 2; ++bj) _Pragma("unroll") for (int n = 0; n < 2; ++n) {
;             const int cc = bj * HALF + wc3 * 32 + n * 16 + fq3 * 4;
;             const float4 gm = *reinterpret_cast<const float4*>(g.gam + pn * BM + cc), bt = *reinterpret_cast<const float4*>(g.bet + pn * BM + cc);
;             _Pragma("unroll") for (int m = 0; m < 4; ++m) {
;               const int rr = wr3 * 64 + m * 16 + fr3;
;               const float2 ms = *reinterpret_cast<const float2*>(mr + (ai * HALF + rr) * 2);
;               f32x4 y = acc[ai][bj][m][n];
;               const float o0 = (y[0] - ms.x) * ms.y * gm.x + bt.x, o1 = (y[1] - ms.x) * ms.y * gm.y + bt.y;
;               const float o2 = (y[2] - ms.x) * ms.y * gm.z + bt.z, o3 = (y[3] - ms.x) * ms.y * gm.w + bt.w;
;               const unsigned h0 = f2bf(o0), h1 = f2bf(o1), h2 = f2bf(o2), h3 = f2bf(o3);
;               u32x2 ob; ob[0] = h0 | (h1 << 16); ob[1] = h2 | (h3 << 16);
;               *reinterpret_cast<u32x2*>(smem + (rr >> 1) * PIECE + (rr & 1) * 512 + cc * 2) = ob;
;               const int l0 = min(((int)__float_as_uint(o0) - (int)(h0 << 16) + 128) >> 8, 127);
;               const int l1 = min(((int)__float_as_uint(o1) - (int)(h1 << 16) + 128) >> 8, 127);
;               const int l2 = min(((int)__float_as_uint(o2) - (int)(h2 << 16) + 128) >> 8, 127);
;               const int l3 = min(((int)__float_as_uint(o3) - (int)(h3 << 16) + 128) >> 8, 127);
;               *reinterpret_cast<unsigned*>(smem + LOBASE + (rr >> 2) * PIECE + (rr & 3) * 256 + cc) =
;                   (unsigned)(l0 & 255) | ((unsigned)(l1 & 255) << 8) | ((unsigned)(l2 & 255) << 16) | ((unsigned)l3 << 24);
;             }
;     ...
;           _Pragma("unroll") for (int i = 0; i < 8; ++i) {
;             const u32x4 v = *reinterpret_cast<const u32x4*>(smem + (wave * 8 + i) * PIECE + lane3 * 16);
;             __builtin_amdgcn_raw_buffer_store_b128(v, rsXB, hvo + i * (2 * DM * 2), hso, 0);
;           }
;           _Pragma("unroll") for (int i = 0; i < 4; ++i) {
;             const u32x4 v = *reinterpret_cast<const u32x4*>(smem + LOBASE + (wave * 4 + i) * PIECE + lane3 * 16);
;             __builtin_amdgcn_raw_buffer_store_b128(v, rsLO, lvo + i * (4 * DM), lso, 0);
	s_nop 1
	v_mov_b32_e32 v0, v220
	v_mov_b32_e32 v1, v221
	v_mov_b32_e32 v2, v222
	v_mov_b32_e32 v3, v223
	v_mov_b32_e32 v4, v236
	v_mov_b32_e32 v5, v237
	v_mov_b32_e32 v6, v238
	v_mov_b32_e32 v7, v239
	ds_read_b64 v[102:103], v149 offset:1024
	s_waitcnt lgkmcnt(0)
	v_pk_add_f32 v[66:67], v[66:67], v[102:103] op_sel_hi:[1,0] neg_lo:[0,1] neg_hi:[0,1]
	s_nop 0
	v_pk_mul_f32 v[66:67], v[102:103], v[66:67] op_sel:[1,0]
	v_pk_add_f32 v[64:65], v[64:65], v[102:103] op_sel_hi:[1,0] neg_lo:[0,1] neg_hi:[0,1]
	v_mov_b32_e32 v96, v1
	v_mov_b32_e32 v97, v2
	v_mov_b32_e32 v98, v5
	v_mov_b32_e32 v99, v6
	v_pk_fma_f32 v[66:67], v[96:97], v[66:67], v[98:99]
	v_pk_mul_f32 v[64:65], v[102:103], v[64:65] op_sel:[1,0]
	v_mov_b32_e32 v1, v3
	v_mov_b32_e32 v5, v7
	v_and_b32_sdwa v6, v67, v216 dst_sel:DWORD dst_unused:UNUSED_PAD src0_sel:WORD_1 src1_sel:DWORD
	v_and_b32_sdwa v7, v66, v216 dst_sel:DWORD dst_unused:UNUSED_PAD src0_sel:WORD_1 src1_sel:DWORD
	v_pk_fma_f32 v[2:3], v[0:1], v[64:65], v[4:5]
	v_add3_u32 v64, v67, v6, s78
	v_add3_u32 v6, v66, v7, s78
	v_and_b32_e32 v65, 0xffff0000, v6
	v_and_b32_sdwa v6, v3, v216 dst_sel:DWORD dst_unused:UNUSED_PAD src0_sel:WORD_1 src1_sel:DWORD
	v_and_b32_sdwa v7, v2, v216 dst_sel:DWORD dst_unused:UNUSED_PAD src0_sel:WORD_1 src1_sel:DWORD
	v_add3_u32 v6, v3, v6, s78
	v_add3_u32 v102, v2, v7, s78
	v_and_b32_e32 v103, 0xffff0000, v6
	v_or_b32_sdwa v7, v103, v64 dst_sel:DWORD dst_unused:UNUSED_PAD src0_sel:DWORD src1_sel:WORD_1
	v_or_b32_sdwa v6, v102, v65 dst_sel:DWORD dst_unused:UNUSED_PAD src0_sel:WORD_1 src1_sel:DWORD
	ds_write_b64 v152, v[6:7]
	v_and_b32_e32 v6, 0xffff0000, v102
	v_sub_u32_e32 v2, v2, v6
	v_sub_u32_e32 v6, v66, v65
	v_and_b32_e32 v7, 0xffff0000, v64
	v_add_u32_e32 v6, 0x80, v6
	v_sub_u32_e32 v7, v67, v7
	v_sub_u32_e32 v3, v3, v103
	v_add_u32_e32 v2, 0x80, v2
	v_ashrrev_i32_e32 v6, 8, v6
	v_add_u32_e32 v7, 0x80, v7
	v_add_u32_e32 v3, 0x80, v3
	v_ashrrev_i32_e32 v2, 8, v2
	v_min_i32_e32 v6, 0x7f, v6
	v_ashrrev_i32_e32 v7, 8, v7
	v_ashrrev_i32_e32 v3, 8, v3
	v_min_i32_e32 v2, 0x7f, v2
	v_min_i32_sdwa v7, v7, s79 dst_sel:WORD_1 dst_unused:UNUSED_PAD src0_sel:DWORD src1_sel:DWORD
	v_min_i32_e32 v3, 0x7f, v3
	v_lshlrev_b32_e32 v6, 8, v6
	v_and_b32_e32 v6, 0xff00, v6
	v_and_b32_e32 v7, 0xff0000, v7
	v_perm_b32 v2, v3, v2, s80
	v_or3_b32 v2, v2, v6, v7
	ds_write_b32 v12, v2
	buffer_store_dwordx4 v[128:131], v148, s[16:19], s33 offen
	ds_read_b64 v[2:3], v13 offset:1024
	s_waitcnt lgkmcnt(0)
	v_pk_add_f32 v[6:7], v[70:71], v[2:3] op_sel_hi:[1,0] neg_lo:[0,1] neg_hi:[0,1]
	s_nop 0
	v_pk_mul_f32 v[6:7], v[2:3], v[6:7] op_sel:[1,0]
	v_pk_add_f32 v[64:65], v[68:69], v[2:3] op_sel_hi:[1,0] neg_lo:[0,1] neg_hi:[0,1]
	v_pk_fma_f32 v[6:7], v[96:97], v[6:7], v[98:99]
	v_pk_mul_f32 v[2:3], v[2:3], v[64:65] op_sel:[1,0]
	v_and_b32_sdwa v64, v7, v216 dst_sel:DWORD dst_unused:UNUSED_PAD src0_sel:WORD_1 src1_sel:DWORD
	v_and_b32_sdwa v65, v6, v216 dst_sel:DWORD dst_unused:UNUSED_PAD src0_sel:WORD_1 src1_sel:DWORD
	v_pk_fma_f32 v[2:3], v[0:1], v[2:3], v[4:5]
	v_add3_u32 v66, v7, v64, s78
	v_add3_u32 v64, v6, v65, s78
	v_and_b32_e32 v67, 0xffff0000, v64
	v_and_b32_sdwa v64, v3, v216 dst_sel:DWORD dst_unused:UNUSED_PAD src0_sel:WORD_1 src1_sel:DWORD
	v_and_b32_sdwa v65, v2, v216 dst_sel:DWORD dst_unused:UNUSED_PAD src0_sel:WORD_1 src1_sel:DWORD
	v_add3_u32 v64, v3, v64, s78
	v_add3_u32 v68, v2, v65, s78
	v_and_b32_e32 v69, 0xffff0000, v64
	v_or_b32_sdwa v65, v69, v66 dst_sel:DWORD dst_unused:UNUSED_PAD src0_sel:DWORD src1_sel:WORD_1
	v_or_b32_sdwa v64, v68, v67 dst_sel:DWORD dst_unused:UNUSED_PAD src0_sel:WORD_1 src1_sel:DWORD
	ds_write_b64 v132, v[64:65]
	v_and_b32_e32 v64, 0xffff0000, v68
	v_sub_u32_e32 v2, v2, v64
	v_sub_u32_e32 v6, v6, v67
	v_and_b32_e32 v64, 0xffff0000, v66
	v_add_u32_e32 v6, 0x80, v6
	v_sub_u32_e32 v7, v7, v64
	v_sub_u32_e32 v3, v3, v69
	v_add_u32_e32 v2, 0x80, v2
	v_ashrrev_i32_e32 v6, 8, v6
	v_add_u32_e32 v7, 0x80, v7
	v_add_u32_e32 v3, 0x80, v3
	v_ashrrev_i32_e32 v2, 8, v2
	v_min_i32_e32 v6, 0x7f, v6
	v_ashrrev_i32_e32 v7, 8, v7
	v_ashrrev_i32_e32 v3, 8, v3
	v_min_i32_e32 v2, 0x7f, v2
	v_min_i32_sdwa v7, v7, s79 dst_sel:WORD_1 dst_unused:UNUSED_PAD src0_sel:DWORD src1_sel:DWORD
	v_min_i32_e32 v3, 0x7f, v3
	v_lshlrev_b32_e32 v6, 8, v6
	v_and_b32_e32 v6, 0xff00, v6
	v_and_b32_e32 v7, 0xff0000, v7
	v_perm_b32 v2, v3, v2, s80
	v_or3_b32 v2, v2, v6, v7
	ds_write_b32 v14, v2
	buffer_store_dwordx4 v[136:139], v74, s[16:19], s33 offen
	ds_read_b64 v[2:3], v15 offset:1024
	s_waitcnt lgkmcnt(0)
	v_pk_add_f32 v[6:7], v[78:79], v[2:3] op_sel_hi:[1,0] neg_lo:[0,1] neg_hi:[0,1]
	s_nop 0
	v_pk_mul_f32 v[6:7], v[2:3], v[6:7] op_sel:[1,0]
	v_pk_add_f32 v[64:65], v[76:77], v[2:3] op_sel_hi:[1,0] neg_lo:[0,1] neg_hi:[0,1]
	v_pk_fma_f32 v[6:7], v[96:97], v[6:7], v[98:99]
	v_pk_mul_f32 v[2:3], v[2:3], v[64:65] op_sel:[1,0]
	v_and_b32_sdwa v64, v7, v216 dst_sel:DWORD dst_unused:UNUSED_PAD src0_sel:WORD_1 src1_sel:DWORD
	v_and_b32_sdwa v65, v6, v216 dst_sel:DWORD dst_unused:UNUSED_PAD src0_sel:WORD_1 src1_sel:DWORD
	v_pk_fma_f32 v[2:3], v[0:1], v[2:3], v[4:5]
	v_add3_u32 v66, v7, v64, s78
	v_add3_u32 v64, v6, v65, s78
	v_and_b32_e32 v67, 0xffff0000, v64
	v_and_b32_sdwa v64, v3, v216 dst_sel:DWORD dst_unused:UNUSED_PAD src0_sel:WORD_1 src1_sel:DWORD
	v_and_b32_sdwa v65, v2, v216 dst_sel:DWORD dst_unused:UNUSED_PAD src0_sel:WORD_1 src1_sel:DWORD
	v_add3_u32 v64, v3, v64, s78
	v_add3_u32 v68, v2, v65, s78
	v_and_b32_e32 v69, 0xffff0000, v64
	v_or_b32_sdwa v65, v69, v66 dst_sel:DWORD dst_unused:UNUSED_PAD src0_sel:DWORD src1_sel:WORD_1
	v_or_b32_sdwa v64, v68, v67 dst_sel:DWORD dst_unused:UNUSED_PAD src0_sel:WORD_1 src1_sel:DWORD
	ds_write_b64 v133, v[64:65]
	v_and_b32_e32 v64, 0xffff0000, v68
	v_sub_u32_e32 v2, v2, v64
	v_sub_u32_e32 v6, v6, v67
	v_and_b32_e32 v64, 0xffff0000, v66
	v_add_u32_e32 v6, 0x80, v6
	v_sub_u32_e32 v7, v7, v64
	v_sub_u32_e32 v3, v3, v69
	v_add_u32_e32 v2, 0x80, v2
	v_ashrrev_i32_e32 v6, 8, v6
	v_add_u32_e32 v7, 0x80, v7
	v_add_u32_e32 v3, 0x80, v3
	v_ashrrev_i32_e32 v2, 8, v2
	v_min_i32_e32 v6, 0x7f, v6
	v_ashrrev_i32_e32 v7, 8, v7
	v_ashrrev_i32_e32 v3, 8, v3
	v_min_i32_e32 v2, 0x7f, v2
	v_min_i32_sdwa v7, v7, s79 dst_sel:WORD_1 dst_unused:UNUSED_PAD src0_sel:DWORD src1_sel:DWORD
	v_min_i32_e32 v3, 0x7f, v3
	v_lshlrev_b32_e32 v6, 8, v6
	v_and_b32_e32 v6, 0xff00, v6
	v_and_b32_e32 v7, 0xff0000, v7
	v_perm_b32 v2, v3, v2, s80
	v_or3_b32 v2, v2, v6, v7
	ds_write_b32 v20, v2
	buffer_store_dwordx4 v[140:143], v75, s[16:19], s33 offen
	ds_read_b64 v[2:3], v21 offset:1024
	s_waitcnt lgkmcnt(0)
;     ...
;           _Pragma("unroll") for (int bj = 0; bj < 2; ++bj) _Pragma("unroll") for (int n = 0; n < 2; ++n) {
;             const int cc = bj * HALF + wc3 * 32 + n * 16 + fq3 * 4;
;             const float4 gm = *reinterpret_cast<const float4*>(g.gam + pn * BM + cc), bt = *reinterpret_cast<const float4*>(g.bet + pn * BM + cc);
;             _Pragma("unroll") for (int m = 0; m < 4; ++m) {
;               const int rr = wr3 * 64 + m * 16 + fr3;
;               const float2 ms = *reinterpret_cast<const float2*>(mr + (ai * HALF + rr) * 2);
;               f32x4 y = acc[ai][bj][m][n];
;               const float o0 = (y[0] - ms.x) * ms.y * gm.x + bt.x, o1 = (y[1] - ms.x) * ms.y * gm.y + bt.y;
;               const float o2 = (y[2] - ms.x) * ms.y * gm.z + bt.z, o3 = (y[3] - ms.x) * ms.y * gm.w + bt.w;
;               const unsigned h0 = f2bf(o0), h1 = f2bf(o1), h2 = f2bf(o2), h3 = f2bf(o3);
;               u32x2 ob; ob[0] = h0 | (h1 << 16); ob[1] = h2 | (h3 << 16);
;               *reinterpret_cast<u32x2*>(smem + (rr >> 1) * PIECE + (rr & 1) * 512 + cc * 2) = ob;
;               const int l0 = min(((int)__float_as_uint(o0) - (int)(h0 << 16) + 128) >> 8, 127);
;               const int l1 = min(((int)__float_as_uint(o1) - (int)(h1 << 16) + 128) >> 8, 127);
;               const int l2 = min(((int)__float_as_uint(o2) - (int)(h2 << 16) + 128) >> 8, 127);
;               const int l3 = min(((int)__float_as_uint(o3) - (int)(h3 << 16) + 128) >> 8, 127);
;               *reinterpret_cast<unsigned*>(smem + LOBASE + (rr >> 2) * PIECE + (rr & 3) * 256 + cc) =
;                   (unsigned)(l0 & 255) | ((unsigned)(l1 & 255) << 8) | ((unsigned)(l2 & 255) << 16) | ((unsigned)l3 << 24);
;             }
;     ...
;           _Pragma("unroll") for (int i = 0; i < 8; ++i) {
;             const u32x4 v = *reinterpret_cast<const u32x4*>(smem + (wave * 8 + i) * PIECE + lane3 * 16);
;             __builtin_amdgcn_raw_buffer_store_b128(v, rsXB, hvo + i * (2 * DM * 2), hso, 0);
;           }
;           _Pragma("unroll") for (int i = 0; i < 4; ++i) {
;             const u32x4 v = *reinterpret_cast<const u32x4*>(smem + LOBASE + (wave * 4 + i) * PIECE + lane3 * 16);
;             __builtin_amdgcn_raw_buffer_store_b128(v, rsLO, lvo + i * (4 * DM), lso, 0);
	v_pk_add_f32 v[6:7], v[86:87], v[2:3] op_sel_hi:[1,0] neg_lo:[0,1] neg_hi:[0,1]
	s_nop 0
	v_pk_mul_f32 v[6:7], v[2:3], v[6:7] op_sel:[1,0]
	v_pk_add_f32 v[64:65], v[84:85], v[2:3] op_sel_hi:[1,0] neg_lo:[0,1] neg_hi:[0,1]
	v_pk_fma_f32 v[6:7], v[96:97], v[6:7], v[98:99]
	v_pk_mul_f32 v[2:3], v[2:3], v[64:65] op_sel:[1,0]
	s_nop 0
	v_pk_fma_f32 v[0:1], v[0:1], v[2:3], v[4:5]
	v_and_b32_sdwa v2, v7, v216 dst_sel:DWORD dst_unused:UNUSED_PAD src0_sel:WORD_1 src1_sel:DWORD
	v_and_b32_sdwa v3, v6, v216 dst_sel:DWORD dst_unused:UNUSED_PAD src0_sel:WORD_1 src1_sel:DWORD
	v_add3_u32 v4, v7, v2, s78
	v_add3_u32 v2, v6, v3, s78
	v_and_b32_e32 v5, 0xffff0000, v2
	v_and_b32_sdwa v2, v1, v216 dst_sel:DWORD dst_unused:UNUSED_PAD src0_sel:WORD_1 src1_sel:DWORD
	v_and_b32_sdwa v3, v0, v216 dst_sel:DWORD dst_unused:UNUSED_PAD src0_sel:WORD_1 src1_sel:DWORD
	v_add3_u32 v2, v1, v2, s78
	v_add3_u32 v64, v0, v3, s78
	v_and_b32_e32 v65, 0xffff0000, v2
	v_or_b32_sdwa v3, v65, v4 dst_sel:DWORD dst_unused:UNUSED_PAD src0_sel:DWORD src1_sel:WORD_1
	v_or_b32_sdwa v2, v64, v5 dst_sel:DWORD dst_unused:UNUSED_PAD src0_sel:WORD_1 src1_sel:DWORD
	ds_write_b64 v134, v[2:3]
	v_and_b32_e32 v2, 0xffff0000, v64
	v_sub_u32_e32 v0, v0, v2
	v_sub_u32_e32 v2, v6, v5
	v_and_b32_e32 v3, 0xffff0000, v4
	v_add_u32_e32 v2, 0x80, v2
	v_sub_u32_e32 v3, v7, v3
	v_sub_u32_e32 v1, v1, v65
	v_add_u32_e32 v0, 0x80, v0
	v_ashrrev_i32_e32 v2, 8, v2
	v_add_u32_e32 v3, 0x80, v3
	v_add_u32_e32 v1, 0x80, v1
	v_ashrrev_i32_e32 v0, 8, v0
	v_min_i32_e32 v2, 0x7f, v2
	v_ashrrev_i32_e32 v3, 8, v3
	v_ashrrev_i32_e32 v1, 8, v1
	v_min_i32_e32 v0, 0x7f, v0
	v_min_i32_sdwa v3, v3, s79 dst_sel:WORD_1 dst_unused:UNUSED_PAD src0_sel:DWORD src1_sel:DWORD
	v_min_i32_e32 v1, 0x7f, v1
	v_lshlrev_b32_e32 v2, 8, v2
	v_and_b32_e32 v2, 0xff00, v2
	v_and_b32_e32 v3, 0xff0000, v3
	v_perm_b32 v0, v1, v0, s80
	v_or3_b32 v0, v0, v2, v3
	ds_write_b32 v22, v0
	buffer_store_dwordx4 v[156:159], v81, s[16:19], s33 offen
	v_mov_b32_e32 v0, v224
	v_mov_b32_e32 v1, v225
	v_mov_b32_e32 v2, v226
	v_mov_b32_e32 v3, v227
	v_mov_b32_e32 v4, v240
	v_mov_b32_e32 v5, v241
	v_mov_b32_e32 v6, v242
	v_mov_b32_e32 v7, v243
	ds_read_b64 v[68:69], v149 offset:1024
	s_waitcnt lgkmcnt(0)
	v_pk_add_f32 v[58:59], v[58:59], v[68:69] op_sel_hi:[1,0] neg_lo:[0,1] neg_hi:[0,1]
	s_nop 0
	v_pk_mul_f32 v[58:59], v[68:69], v[58:59] op_sel:[1,0]
	v_pk_add_f32 v[56:57], v[56:57], v[68:69] op_sel_hi:[1,0] neg_lo:[0,1] neg_hi:[0,1]
	v_mov_b32_e32 v64, v1
	v_mov_b32_e32 v65, v2
	v_mov_b32_e32 v66, v5
	v_mov_b32_e32 v67, v6
	v_pk_fma_f32 v[58:59], v[64:65], v[58:59], v[66:67]
	v_pk_mul_f32 v[56:57], v[68:69], v[56:57] op_sel:[1,0]
	v_mov_b32_e32 v1, v3
	v_mov_b32_e32 v5, v7
	v_and_b32_sdwa v6, v59, v216 dst_sel:DWORD dst_unused:UNUSED_PAD src0_sel:WORD_1 src1_sel:DWORD
	v_and_b32_sdwa v7, v58, v216 dst_sel:DWORD dst_unused:UNUSED_PAD src0_sel:WORD_1 src1_sel:DWORD
	v_pk_fma_f32 v[2:3], v[0:1], v[56:57], v[4:5]
	v_add3_u32 v56, v59, v6, s78
	v_add3_u32 v6, v58, v7, s78
	v_and_b32_e32 v57, 0xffff0000, v6
	v_and_b32_sdwa v6, v3, v216 dst_sel:DWORD dst_unused:UNUSED_PAD src0_sel:WORD_1 src1_sel:DWORD
	v_and_b32_sdwa v7, v2, v216 dst_sel:DWORD dst_unused:UNUSED_PAD src0_sel:WORD_1 src1_sel:DWORD
	v_add3_u32 v6, v3, v6, s78
	v_add3_u32 v68, v2, v7, s78
	v_and_b32_e32 v69, 0xffff0000, v6
	v_or_b32_sdwa v7, v69, v56 dst_sel:DWORD dst_unused:UNUSED_PAD src0_sel:DWORD src1_sel:WORD_1
	v_or_b32_sdwa v6, v68, v57 dst_sel:DWORD dst_unused:UNUSED_PAD src0_sel:WORD_1 src1_sel:DWORD
	ds_write_b64 v23, v[6:7]
	v_and_b32_e32 v6, 0xffff0000, v68
	v_sub_u32_e32 v2, v2, v6
	v_sub_u32_e32 v6, v58, v57
	v_and_b32_e32 v7, 0xffff0000, v56
	v_add_u32_e32 v6, 0x80, v6
	v_sub_u32_e32 v7, v59, v7
	v_sub_u32_e32 v3, v3, v69
	v_add_u32_e32 v2, 0x80, v2
	v_ashrrev_i32_e32 v6, 8, v6
	v_add_u32_e32 v7, 0x80, v7
	v_add_u32_e32 v3, 0x80, v3
	v_ashrrev_i32_e32 v2, 8, v2
	v_min_i32_e32 v6, 0x7f, v6
	v_ashrrev_i32_e32 v7, 8, v7
	v_ashrrev_i32_e32 v3, 8, v3
	v_min_i32_e32 v2, 0x7f, v2
	v_min_i32_sdwa v7, v7, s79 dst_sel:WORD_1 dst_unused:UNUSED_PAD src0_sel:DWORD src1_sel:DWORD
	v_min_i32_e32 v3, 0x7f, v3
	v_lshlrev_b32_e32 v6, 8, v6
	v_and_b32_e32 v6, 0xff00, v6
	v_and_b32_e32 v7, 0xff0000, v7
	v_perm_b32 v2, v3, v2, s80
	v_or3_b32 v2, v2, v6, v7
	ds_write_b32 v12, v2 offset:16
	buffer_store_dwordx4 v[160:163], v82, s[16:19], s33 offen
	ds_read_b64 v[2:3], v13 offset:1024
	s_waitcnt lgkmcnt(0)
	v_pk_add_f32 v[6:7], v[42:43], v[2:3] op_sel_hi:[1,0] neg_lo:[0,1] neg_hi:[0,1]
	s_nop 0
	v_pk_mul_f32 v[6:7], v[2:3], v[6:7] op_sel:[1,0]
	v_pk_add_f32 v[40:41], v[40:41], v[2:3] op_sel_hi:[1,0] neg_lo:[0,1] neg_hi:[0,1]
	v_pk_fma_f32 v[6:7], v[64:65], v[6:7], v[66:67]
	v_pk_mul_f32 v[2:3], v[2:3], v[40:41] op_sel:[1,0]
	v_and_b32_sdwa v40, v6, v216 dst_sel:DWORD dst_unused:UNUSED_PAD src0_sel:WORD_1 src1_sel:DWORD
	v_pk_fma_f32 v[2:3], v[0:1], v[2:3], v[4:5]
	v_add3_u32 v40, v6, v40, s78
	v_and_b32_e32 v42, 0xffff0000, v40
	v_and_b32_sdwa v40, v3, v216 dst_sel:DWORD dst_unused:UNUSED_PAD src0_sel:WORD_1 src1_sel:DWORD
	v_and_b32_sdwa v23, v7, v216 dst_sel:DWORD dst_unused:UNUSED_PAD src0_sel:WORD_1 src1_sel:DWORD
	v_and_b32_sdwa v41, v2, v216 dst_sel:DWORD dst_unused:UNUSED_PAD src0_sel:WORD_1 src1_sel:DWORD
	v_add3_u32 v40, v3, v40, s78
	v_add3_u32 v23, v7, v23, s78
	v_add3_u32 v43, v2, v41, s78
	v_and_b32_e32 v56, 0xffff0000, v40
	v_or_b32_sdwa v41, v56, v23 dst_sel:DWORD dst_unused:UNUSED_PAD src0_sel:DWORD src1_sel:WORD_1
	v_or_b32_sdwa v40, v43, v42 dst_sel:DWORD dst_unused:UNUSED_PAD src0_sel:WORD_1 src1_sel:DWORD
	ds_write_b64 v104, v[40:41]
	v_and_b32_e32 v40, 0xffff0000, v43
	v_sub_u32_e32 v6, v6, v42
	v_and_b32_e32 v23, 0xffff0000, v23
	v_sub_u32_e32 v2, v2, v40
	v_add_u32_e32 v6, 0x80, v6
	v_sub_u32_e32 v7, v7, v23
	v_sub_u32_e32 v3, v3, v56
	v_add_u32_e32 v2, 0x80, v2
	v_ashrrev_i32_e32 v6, 8, v6
	v_add_u32_e32 v7, 0x80, v7
	v_add_u32_e32 v3, 0x80, v3
	v_ashrrev_i32_e32 v2, 8, v2
	v_min_i32_e32 v6, 0x7f, v6
	v_ashrrev_i32_e32 v7, 8, v7
	v_ashrrev_i32_e32 v3, 8, v3
	v_min_i32_e32 v2, 0x7f, v2
	v_min_i32_sdwa v7, v7, s79 dst_sel:WORD_1 dst_unused:UNUSED_PAD src0_sel:DWORD src1_sel:DWORD
	v_min_i32_e32 v3, 0x7f, v3
	v_lshlrev_b32_e32 v6, 8, v6
	v_and_b32_e32 v6, 0xff00, v6
	v_and_b32_e32 v7, 0xff0000, v7
	v_perm_b32 v2, v3, v2, s80
	v_or3_b32 v2, v2, v6, v7
	ds_write_b32 v14, v2 offset:16
	buffer_store_dwordx4 v[164:167], v83, s[16:19], s33 offen
	ds_read_b64 v[2:3], v15 offset:1024
	s_waitcnt lgkmcnt(0)
;     ...
;           _Pragma("unroll") for (int bj = 0; bj < 2; ++bj) _Pragma("unroll") for (int n = 0; n < 2; ++n) {
;             const int cc = bj * HALF + wc3 * 32 + n * 16 + fq3 * 4;
;             const float4 gm = *reinterpret_cast<const float4*>(g.gam + pn * BM + cc), bt = *reinterpret_cast<const float4*>(g.bet + pn * BM + cc);
;             _Pragma("unroll") for (int m = 0; m < 4; ++m) {
;               const int rr = wr3 * 64 + m * 16 + fr3;
;               const float2 ms = *reinterpret_cast<const float2*>(mr + (ai * HALF + rr) * 2);
;               f32x4 y = acc[ai][bj][m][n];
;               const float o0 = (y[0] - ms.x) * ms.y * gm.x + bt.x, o1 = (y[1] - ms.x) * ms.y * gm.y + bt.y;
;               const float o2 = (y[2] - ms.x) * ms.y * gm.z + bt.z, o3 = (y[3] - ms.x) * ms.y * gm.w + bt.w;
;               const unsigned h0 = f2bf(o0), h1 = f2bf(o1), h2 = f2bf(o2), h3 = f2bf(o3);
;               u32x2 ob; ob[0] = h0 | (h1 << 16); ob[1] = h2 | (h3 << 16);
;               *reinterpret_cast<u32x2*>(smem + (rr >> 1) * PIECE + (rr & 1) * 512 + cc * 2) = ob;
;               const int l0 = min(((int)__float_as_uint(o0) - (int)(h0 << 16) + 128) >> 8, 127);
;               const int l1 = min(((int)__float_as_uint(o1) - (int)(h1 << 16) + 128) >> 8, 127);
;               const int l2 = min(((int)__float_as_uint(o2) - (int)(h2 << 16) + 128) >> 8, 127);
;               const int l3 = min(((int)__float_as_uint(o3) - (int)(h3 << 16) + 128) >> 8, 127);
;               *reinterpret_cast<unsigned*>(smem + LOBASE + (rr >> 2) * PIECE + (rr & 3) * 256 + cc) =
;                   (unsigned)(l0 & 255) | ((unsigned)(l1 & 255) << 8) | ((unsigned)(l2 & 255) << 16) | ((unsigned)l3 << 24);
;             }
;     ...
;           _Pragma("unroll") for (int i = 0; i < 8; ++i) {
;             const u32x4 v = *reinterpret_cast<const u32x4*>(smem + (wave * 8 + i) * PIECE + lane3 * 16);
;             __builtin_amdgcn_raw_buffer_store_b128(v, rsXB, hvo + i * (2 * DM * 2), hso, 0);
;           }
;           _Pragma("unroll") for (int i = 0; i < 4; ++i) {
;             const u32x4 v = *reinterpret_cast<const u32x4*>(smem + LOBASE + (wave * 4 + i) * PIECE + lane3 * 16);
;             __builtin_amdgcn_raw_buffer_store_b128(v, rsLO, lvo + i * (4 * DM), lso, 0);
	v_pk_add_f32 v[6:7], v[46:47], v[2:3] op_sel_hi:[1,0] neg_lo:[0,1] neg_hi:[0,1]
	s_nop 0
	v_pk_mul_f32 v[6:7], v[2:3], v[6:7] op_sel:[1,0]
	v_pk_add_f32 v[40:41], v[44:45], v[2:3] op_sel_hi:[1,0] neg_lo:[0,1] neg_hi:[0,1]
	v_pk_fma_f32 v[6:7], v[64:65], v[6:7], v[66:67]
	v_pk_mul_f32 v[2:3], v[2:3], v[40:41] op_sel:[1,0]
	v_and_b32_sdwa v40, v6, v216 dst_sel:DWORD dst_unused:UNUSED_PAD src0_sel:WORD_1 src1_sel:DWORD
	v_pk_fma_f32 v[2:3], v[0:1], v[2:3], v[4:5]
	v_add3_u32 v40, v6, v40, s78
	v_and_b32_e32 v42, 0xffff0000, v40
	v_and_b32_sdwa v40, v3, v216 dst_sel:DWORD dst_unused:UNUSED_PAD src0_sel:WORD_1 src1_sel:DWORD
	v_and_b32_sdwa v23, v7, v216 dst_sel:DWORD dst_unused:UNUSED_PAD src0_sel:WORD_1 src1_sel:DWORD
	v_and_b32_sdwa v41, v2, v216 dst_sel:DWORD dst_unused:UNUSED_PAD src0_sel:WORD_1 src1_sel:DWORD
	v_add3_u32 v40, v3, v40, s78
	v_add3_u32 v23, v7, v23, s78
	v_add3_u32 v43, v2, v41, s78
	v_and_b32_e32 v44, 0xffff0000, v40
	v_or_b32_sdwa v41, v44, v23 dst_sel:DWORD dst_unused:UNUSED_PAD src0_sel:DWORD src1_sel:WORD_1
	v_or_b32_sdwa v40, v43, v42 dst_sel:DWORD dst_unused:UNUSED_PAD src0_sel:WORD_1 src1_sel:DWORD
	ds_write_b64 v105, v[40:41]
	v_and_b32_e32 v40, 0xffff0000, v43
	v_sub_u32_e32 v6, v6, v42
	v_and_b32_e32 v23, 0xffff0000, v23
	v_sub_u32_e32 v2, v2, v40
	v_add_u32_e32 v6, 0x80, v6
	v_sub_u32_e32 v7, v7, v23
	v_sub_u32_e32 v3, v3, v44
	v_add_u32_e32 v2, 0x80, v2
	v_ashrrev_i32_e32 v6, 8, v6
	v_add_u32_e32 v7, 0x80, v7
	v_add_u32_e32 v3, 0x80, v3
	v_ashrrev_i32_e32 v2, 8, v2
	v_min_i32_e32 v6, 0x7f, v6
	v_ashrrev_i32_e32 v7, 8, v7
	v_ashrrev_i32_e32 v3, 8, v3
	v_min_i32_e32 v2, 0x7f, v2
	v_min_i32_sdwa v7, v7, s79 dst_sel:WORD_1 dst_unused:UNUSED_PAD src0_sel:DWORD src1_sel:DWORD
	v_min_i32_e32 v3, 0x7f, v3
	v_lshlrev_b32_e32 v6, 8, v6
	v_and_b32_e32 v6, 0xff00, v6
	v_and_b32_e32 v7, 0xff0000, v7
	v_perm_b32 v2, v3, v2, s80
	v_or3_b32 v2, v2, v6, v7
	ds_write_b32 v20, v2 offset:16
	buffer_store_dwordx4 v[168:171], v88, s[16:19], s33 offen
	ds_read_b64 v[2:3], v21 offset:1024
	s_waitcnt lgkmcnt(0)
	v_pk_add_f32 v[6:7], v[62:63], v[2:3] op_sel_hi:[1,0] neg_lo:[0,1] neg_hi:[0,1]
	s_nop 0
	v_pk_mul_f32 v[6:7], v[2:3], v[6:7] op_sel:[1,0]
	v_pk_add_f32 v[40:41], v[60:61], v[2:3] op_sel_hi:[1,0] neg_lo:[0,1] neg_hi:[0,1]
	v_pk_fma_f32 v[6:7], v[64:65], v[6:7], v[66:67]
	v_pk_mul_f32 v[2:3], v[2:3], v[40:41] op_sel:[1,0]
	s_nop 0
	v_pk_fma_f32 v[0:1], v[0:1], v[2:3], v[4:5]
	v_and_b32_sdwa v2, v7, v216 dst_sel:DWORD dst_unused:UNUSED_PAD src0_sel:WORD_1 src1_sel:DWORD
	v_and_b32_sdwa v3, v6, v216 dst_sel:DWORD dst_unused:UNUSED_PAD src0_sel:WORD_1 src1_sel:DWORD
	v_add3_u32 v4, v7, v2, s78
	v_add3_u32 v2, v6, v3, s78
	v_and_b32_e32 v5, 0xffff0000, v2
	v_and_b32_sdwa v2, v1, v216 dst_sel:DWORD dst_unused:UNUSED_PAD src0_sel:WORD_1 src1_sel:DWORD
	v_and_b32_sdwa v3, v0, v216 dst_sel:DWORD dst_unused:UNUSED_PAD src0_sel:WORD_1 src1_sel:DWORD
	v_add3_u32 v2, v1, v2, s78
	v_add3_u32 v23, v0, v3, s78
	v_and_b32_e32 v40, 0xffff0000, v2
	v_or_b32_sdwa v3, v40, v4 dst_sel:DWORD dst_unused:UNUSED_PAD src0_sel:DWORD src1_sel:WORD_1
	v_or_b32_sdwa v2, v23, v5 dst_sel:DWORD dst_unused:UNUSED_PAD src0_sel:WORD_1 src1_sel:DWORD
	ds_write_b64 v106, v[2:3]
	v_and_b32_e32 v2, 0xffff0000, v23
	v_sub_u32_e32 v0, v0, v2
	v_sub_u32_e32 v2, v6, v5
	v_and_b32_e32 v3, 0xffff0000, v4
	v_add_u32_e32 v2, 0x80, v2
	v_sub_u32_e32 v3, v7, v3
	v_sub_u32_e32 v1, v1, v40
	v_add_u32_e32 v0, 0x80, v0
	v_ashrrev_i32_e32 v2, 8, v2
	v_add_u32_e32 v3, 0x80, v3
	v_add_u32_e32 v1, 0x80, v1
	v_ashrrev_i32_e32 v0, 8, v0
	v_min_i32_e32 v2, 0x7f, v2
	v_ashrrev_i32_e32 v3, 8, v3
	v_ashrrev_i32_e32 v1, 8, v1
	v_min_i32_e32 v0, 0x7f, v0
	v_min_i32_sdwa v3, v3, s79 dst_sel:WORD_1 dst_unused:UNUSED_PAD src0_sel:DWORD src1_sel:DWORD
	v_min_i32_e32 v1, 0x7f, v1
	v_lshlrev_b32_e32 v2, 8, v2
	v_and_b32_e32 v2, 0xff00, v2
	v_and_b32_e32 v3, 0xff0000, v3
	v_perm_b32 v0, v1, v0, s80
	v_or3_b32 v0, v0, v2, v3
	ds_write_b32 v22, v0 offset:16
	buffer_store_dwordx4 v[172:175], v89, s[16:19], s33 offen
	v_mov_b32_e32 v0, v228
	v_mov_b32_e32 v1, v229
	v_mov_b32_e32 v2, v230
	v_mov_b32_e32 v3, v231
	v_mov_b32_e32 v4, v244
	v_mov_b32_e32 v5, v245
	v_mov_b32_e32 v6, v246
	v_mov_b32_e32 v7, v247
	ds_read_b64 v[44:45], v149 offset:1024
	s_waitcnt lgkmcnt(0)
	v_pk_add_f32 v[46:47], v[54:55], v[44:45] op_sel_hi:[1,0] neg_lo:[0,1] neg_hi:[0,1]
	s_nop 0
	v_pk_mul_f32 v[46:47], v[44:45], v[46:47] op_sel:[1,0]
	v_pk_add_f32 v[52:53], v[52:53], v[44:45] op_sel_hi:[1,0] neg_lo:[0,1] neg_hi:[0,1]
	v_mov_b32_e32 v40, v1
	v_mov_b32_e32 v41, v2
	v_mov_b32_e32 v42, v5
	v_mov_b32_e32 v43, v6
	v_pk_fma_f32 v[46:47], v[40:41], v[46:47], v[42:43]
	v_pk_mul_f32 v[44:45], v[44:45], v[52:53] op_sel:[1,0]
	v_mov_b32_e32 v1, v3
	v_mov_b32_e32 v5, v7
	v_and_b32_sdwa v6, v47, v216 dst_sel:DWORD dst_unused:UNUSED_PAD src0_sel:WORD_1 src1_sel:DWORD
	v_and_b32_sdwa v7, v46, v216 dst_sel:DWORD dst_unused:UNUSED_PAD src0_sel:WORD_1 src1_sel:DWORD
	v_pk_fma_f32 v[2:3], v[0:1], v[44:45], v[4:5]
	v_add3_u32 v23, v47, v6, s78
	v_add3_u32 v6, v46, v7, s78
	v_and_b32_e32 v44, 0xffff0000, v6
	v_and_b32_sdwa v6, v3, v216 dst_sel:DWORD dst_unused:UNUSED_PAD src0_sel:WORD_1 src1_sel:DWORD
	v_and_b32_sdwa v7, v2, v216 dst_sel:DWORD dst_unused:UNUSED_PAD src0_sel:WORD_1 src1_sel:DWORD
	v_add3_u32 v6, v3, v6, s78
	v_add3_u32 v45, v2, v7, s78
	v_and_b32_e32 v52, 0xffff0000, v6
	v_or_b32_sdwa v7, v52, v23 dst_sel:DWORD dst_unused:UNUSED_PAD src0_sel:DWORD src1_sel:WORD_1
	v_or_b32_sdwa v6, v45, v44 dst_sel:DWORD dst_unused:UNUSED_PAD src0_sel:WORD_1 src1_sel:DWORD
	ds_write_b64 v107, v[6:7]
	v_and_b32_e32 v6, 0xffff0000, v45
	v_sub_u32_e32 v2, v2, v6
	v_sub_u32_e32 v6, v46, v44
	v_and_b32_e32 v7, 0xffff0000, v23
	v_add_u32_e32 v6, 0x80, v6
	v_sub_u32_e32 v7, v47, v7
	v_sub_u32_e32 v3, v3, v52
	v_add_u32_e32 v2, 0x80, v2
	v_ashrrev_i32_e32 v6, 8, v6
	v_add_u32_e32 v7, 0x80, v7
	v_add_u32_e32 v3, 0x80, v3
	v_ashrrev_i32_e32 v2, 8, v2
	v_min_i32_e32 v6, 0x7f, v6
	v_ashrrev_i32_e32 v7, 8, v7
	v_ashrrev_i32_e32 v3, 8, v3
	v_min_i32_e32 v2, 0x7f, v2
	v_min_i32_sdwa v7, v7, s79 dst_sel:WORD_1 dst_unused:UNUSED_PAD src0_sel:DWORD src1_sel:DWORD
	v_min_i32_e32 v3, 0x7f, v3
	v_lshlrev_b32_e32 v6, 8, v6
	v_and_b32_e32 v6, 0xff00, v6
	v_and_b32_e32 v7, 0xff0000, v7
	v_perm_b32 v2, v3, v2, s80
	v_or3_b32 v2, v2, v6, v7
	ds_write_b32 v12, v2 offset:128
	buffer_store_dwordx4 v[176:179], v146, s[20:23], s0 offen
	ds_read_b64 v[2:3], v13 offset:1024
	s_waitcnt lgkmcnt(0)
;     ...
;           _Pragma("unroll") for (int bj = 0; bj < 2; ++bj) _Pragma("unroll") for (int n = 0; n < 2; ++n) {
;             const int cc = bj * HALF + wc3 * 32 + n * 16 + fq3 * 4;
;             const float4 gm = *reinterpret_cast<const float4*>(g.gam + pn * BM + cc), bt = *reinterpret_cast<const float4*>(g.bet + pn * BM + cc);
;             _Pragma("unroll") for (int m = 0; m < 4; ++m) {
;               const int rr = wr3 * 64 + m * 16 + fr3;
;               const float2 ms = *reinterpret_cast<const float2*>(mr + (ai * HALF + rr) * 2);
;               f32x4 y = acc[ai][bj][m][n];
;               const float o0 = (y[0] - ms.x) * ms.y * gm.x + bt.x, o1 = (y[1] - ms.x) * ms.y * gm.y + bt.y;
;               const float o2 = (y[2] - ms.x) * ms.y * gm.z + bt.z, o3 = (y[3] - ms.x) * ms.y * gm.w + bt.w;
;               const unsigned h0 = f2bf(o0), h1 = f2bf(o1), h2 = f2bf(o2), h3 = f2bf(o3);
;               u32x2 ob; ob[0] = h0 | (h1 << 16); ob[1] = h2 | (h3 << 16);
;               *reinterpret_cast<u32x2*>(smem + (rr >> 1) * PIECE + (rr & 1) * 512 + cc * 2) = ob;
;               const int l0 = min(((int)__float_as_uint(o0) - (int)(h0 << 16) + 128) >> 8, 127);
;               const int l1 = min(((int)__float_as_uint(o1) - (int)(h1 << 16) + 128) >> 8, 127);
;               const int l2 = min(((int)__float_as_uint(o2) - (int)(h2 << 16) + 128) >> 8, 127);
;               const int l3 = min(((int)__float_as_uint(o3) - (int)(h3 << 16) + 128) >> 8, 127);
;               *reinterpret_cast<unsigned*>(smem + LOBASE + (rr >> 2) * PIECE + (rr & 3) * 256 + cc) =
;                   (unsigned)(l0 & 255) | ((unsigned)(l1 & 255) << 8) | ((unsigned)(l2 & 255) << 16) | ((unsigned)l3 << 24);
;             }
;     ...
;           _Pragma("unroll") for (int i = 0; i < 8; ++i) {
;             const u32x4 v = *reinterpret_cast<const u32x4*>(smem + (wave * 8 + i) * PIECE + lane3 * 16);
;             __builtin_amdgcn_raw_buffer_store_b128(v, rsXB, hvo + i * (2 * DM * 2), hso, 0);
;           }
;           _Pragma("unroll") for (int i = 0; i < 4; ++i) {
;             const u32x4 v = *reinterpret_cast<const u32x4*>(smem + LOBASE + (wave * 4 + i) * PIECE + lane3 * 16);
;             __builtin_amdgcn_raw_buffer_store_b128(v, rsLO, lvo + i * (4 * DM), lso, 0);
	v_pk_add_f32 v[6:7], v[38:39], v[2:3] op_sel_hi:[1,0] neg_lo:[0,1] neg_hi:[0,1]
	s_nop 0
	v_pk_mul_f32 v[6:7], v[2:3], v[6:7] op_sel:[1,0]
	v_pk_add_f32 v[36:37], v[36:37], v[2:3] op_sel_hi:[1,0] neg_lo:[0,1] neg_hi:[0,1]
	v_pk_fma_f32 v[6:7], v[40:41], v[6:7], v[42:43]
	v_pk_mul_f32 v[2:3], v[2:3], v[36:37] op_sel:[1,0]
	v_and_b32_sdwa v36, v6, v216 dst_sel:DWORD dst_unused:UNUSED_PAD src0_sel:WORD_1 src1_sel:DWORD
	v_pk_fma_f32 v[2:3], v[0:1], v[2:3], v[4:5]
	v_add3_u32 v36, v6, v36, s78
	v_and_b32_e32 v38, 0xffff0000, v36
	v_and_b32_sdwa v36, v3, v216 dst_sel:DWORD dst_unused:UNUSED_PAD src0_sel:WORD_1 src1_sel:DWORD
	v_and_b32_sdwa v23, v7, v216 dst_sel:DWORD dst_unused:UNUSED_PAD src0_sel:WORD_1 src1_sel:DWORD
	v_and_b32_sdwa v37, v2, v216 dst_sel:DWORD dst_unused:UNUSED_PAD src0_sel:WORD_1 src1_sel:DWORD
	v_add3_u32 v36, v3, v36, s78
	v_add3_u32 v23, v7, v23, s78
	v_add3_u32 v39, v2, v37, s78
	v_and_b32_e32 v44, 0xffff0000, v36
	v_or_b32_sdwa v37, v44, v23 dst_sel:DWORD dst_unused:UNUSED_PAD src0_sel:DWORD src1_sel:WORD_1
	v_or_b32_sdwa v36, v39, v38 dst_sel:DWORD dst_unused:UNUSED_PAD src0_sel:WORD_1 src1_sel:DWORD
	ds_write_b64 v100, v[36:37]
	v_and_b32_e32 v36, 0xffff0000, v39
	v_sub_u32_e32 v6, v6, v38
	v_and_b32_e32 v23, 0xffff0000, v23
	v_sub_u32_e32 v2, v2, v36
	v_add_u32_e32 v6, 0x80, v6
	v_sub_u32_e32 v7, v7, v23
	v_sub_u32_e32 v3, v3, v44
	v_add_u32_e32 v2, 0x80, v2
	v_ashrrev_i32_e32 v6, 8, v6
	v_add_u32_e32 v7, 0x80, v7
	v_add_u32_e32 v3, 0x80, v3
	v_ashrrev_i32_e32 v2, 8, v2
	v_min_i32_e32 v6, 0x7f, v6
	v_ashrrev_i32_e32 v7, 8, v7
	v_ashrrev_i32_e32 v3, 8, v3
	v_min_i32_e32 v2, 0x7f, v2
	v_min_i32_sdwa v7, v7, s79 dst_sel:WORD_1 dst_unused:UNUSED_PAD src0_sel:DWORD src1_sel:DWORD
	v_min_i32_e32 v3, 0x7f, v3
	v_lshlrev_b32_e32 v6, 8, v6
	v_and_b32_e32 v6, 0xff00, v6
	v_and_b32_e32 v7, 0xff0000, v7
	v_perm_b32 v2, v3, v2, s80
	v_or3_b32 v2, v2, v6, v7
	ds_write_b32 v14, v2 offset:128
	buffer_store_dwordx4 v[180:183], v90, s[20:23], s0 offen
	ds_read_b64 v[2:3], v15 offset:1024
	s_waitcnt lgkmcnt(0)
	v_pk_add_f32 v[6:7], v[26:27], v[2:3] op_sel_hi:[1,0] neg_lo:[0,1] neg_hi:[0,1]
	s_nop 0
	v_pk_mul_f32 v[6:7], v[2:3], v[6:7] op_sel:[1,0]
	v_pk_add_f32 v[24:25], v[24:25], v[2:3] op_sel_hi:[1,0] neg_lo:[0,1] neg_hi:[0,1]
	v_pk_fma_f32 v[6:7], v[40:41], v[6:7], v[42:43]
	v_pk_mul_f32 v[2:3], v[2:3], v[24:25] op_sel:[1,0]
	v_and_b32_sdwa v24, v6, v216 dst_sel:DWORD dst_unused:UNUSED_PAD src0_sel:WORD_1 src1_sel:DWORD
	v_pk_fma_f32 v[2:3], v[0:1], v[2:3], v[4:5]
	v_add3_u32 v24, v6, v24, s78
	v_and_b32_e32 v26, 0xffff0000, v24
	v_and_b32_sdwa v24, v3, v216 dst_sel:DWORD dst_unused:UNUSED_PAD src0_sel:WORD_1 src1_sel:DWORD
	v_and_b32_sdwa v23, v7, v216 dst_sel:DWORD dst_unused:UNUSED_PAD src0_sel:WORD_1 src1_sel:DWORD
	v_and_b32_sdwa v25, v2, v216 dst_sel:DWORD dst_unused:UNUSED_PAD src0_sel:WORD_1 src1_sel:DWORD
	v_add3_u32 v24, v3, v24, s78
	v_add3_u32 v23, v7, v23, s78
	v_add3_u32 v27, v2, v25, s78
	v_and_b32_e32 v36, 0xffff0000, v24
	v_or_b32_sdwa v25, v36, v23 dst_sel:DWORD dst_unused:UNUSED_PAD src0_sel:DWORD src1_sel:WORD_1
	v_or_b32_sdwa v24, v27, v26 dst_sel:DWORD dst_unused:UNUSED_PAD src0_sel:WORD_1 src1_sel:DWORD
	ds_write_b64 v101, v[24:25]
	v_and_b32_e32 v24, 0xffff0000, v27
	v_sub_u32_e32 v6, v6, v26
	v_and_b32_e32 v23, 0xffff0000, v23
	v_sub_u32_e32 v2, v2, v24
	v_add_u32_e32 v6, 0x80, v6
	v_sub_u32_e32 v7, v7, v23
	v_sub_u32_e32 v3, v3, v36
	v_add_u32_e32 v2, 0x80, v2
	v_ashrrev_i32_e32 v6, 8, v6
	v_add_u32_e32 v7, 0x80, v7
	v_add_u32_e32 v3, 0x80, v3
	v_ashrrev_i32_e32 v2, 8, v2
	v_min_i32_e32 v6, 0x7f, v6
	v_ashrrev_i32_e32 v7, 8, v7
	v_ashrrev_i32_e32 v3, 8, v3
	v_min_i32_e32 v2, 0x7f, v2
	v_min_i32_sdwa v7, v7, s79 dst_sel:WORD_1 dst_unused:UNUSED_PAD src0_sel:DWORD src1_sel:DWORD
	v_min_i32_e32 v3, 0x7f, v3
	v_lshlrev_b32_e32 v6, 8, v6
	v_and_b32_e32 v6, 0xff00, v6
	v_and_b32_e32 v7, 0xff0000, v7
	v_perm_b32 v2, v3, v2, s80
	v_or3_b32 v2, v2, v6, v7
	ds_write_b32 v20, v2 offset:128
	buffer_store_dwordx4 v[184:187], v91, s[20:23], s0 offen
	ds_read_b64 v[2:3], v21 offset:1024
	s_waitcnt lgkmcnt(0)
	v_pk_add_f32 v[6:7], v[30:31], v[2:3] op_sel_hi:[1,0] neg_lo:[0,1] neg_hi:[0,1]
	s_nop 0
	v_pk_mul_f32 v[6:7], v[2:3], v[6:7] op_sel:[1,0]
	v_pk_add_f32 v[24:25], v[28:29], v[2:3] op_sel_hi:[1,0] neg_lo:[0,1] neg_hi:[0,1]
	v_pk_fma_f32 v[6:7], v[40:41], v[6:7], v[42:43]
	v_pk_mul_f32 v[2:3], v[2:3], v[24:25] op_sel:[1,0]
	s_nop 0
	v_pk_fma_f32 v[0:1], v[0:1], v[2:3], v[4:5]
	v_and_b32_sdwa v2, v7, v216 dst_sel:DWORD dst_unused:UNUSED_PAD src0_sel:WORD_1 src1_sel:DWORD
	v_and_b32_sdwa v3, v6, v216 dst_sel:DWORD dst_unused:UNUSED_PAD src0_sel:WORD_1 src1_sel:DWORD
	v_add3_u32 v4, v7, v2, s78
	v_add3_u32 v2, v6, v3, s78
	v_and_b32_e32 v5, 0xffff0000, v2
	v_and_b32_sdwa v2, v1, v216 dst_sel:DWORD dst_unused:UNUSED_PAD src0_sel:WORD_1 src1_sel:DWORD
	v_and_b32_sdwa v3, v0, v216 dst_sel:DWORD dst_unused:UNUSED_PAD src0_sel:WORD_1 src1_sel:DWORD
	v_add3_u32 v2, v1, v2, s78
	v_add3_u32 v23, v0, v3, s78
	v_and_b32_e32 v24, 0xffff0000, v2
	v_or_b32_sdwa v3, v24, v4 dst_sel:DWORD dst_unused:UNUSED_PAD src0_sel:DWORD src1_sel:WORD_1
	v_or_b32_sdwa v2, v23, v5 dst_sel:DWORD dst_unused:UNUSED_PAD src0_sel:WORD_1 src1_sel:DWORD
	ds_write_b64 v92, v[2:3]
	v_and_b32_e32 v2, 0xffff0000, v23
	v_sub_u32_e32 v0, v0, v2
	v_sub_u32_e32 v2, v6, v5
	v_and_b32_e32 v3, 0xffff0000, v4
	v_add_u32_e32 v2, 0x80, v2
	v_sub_u32_e32 v3, v7, v3
	v_sub_u32_e32 v1, v1, v24
	v_add_u32_e32 v0, 0x80, v0
	v_ashrrev_i32_e32 v2, 8, v2
	v_add_u32_e32 v3, 0x80, v3
	v_add_u32_e32 v1, 0x80, v1
	v_ashrrev_i32_e32 v0, 8, v0
	v_min_i32_e32 v2, 0x7f, v2
	v_ashrrev_i32_e32 v3, 8, v3
	v_ashrrev_i32_e32 v1, 8, v1
	v_min_i32_e32 v0, 0x7f, v0
	v_min_i32_sdwa v3, v3, s79 dst_sel:WORD_1 dst_unused:UNUSED_PAD src0_sel:DWORD src1_sel:DWORD
	v_min_i32_e32 v1, 0x7f, v1
	v_lshlrev_b32_e32 v2, 8, v2
	v_and_b32_e32 v2, 0xff00, v2
	v_and_b32_e32 v3, 0xff0000, v3
	v_perm_b32 v0, v1, v0, s80
	v_or3_b32 v0, v0, v2, v3
	ds_write_b32 v22, v0 offset:128
	buffer_store_dwordx4 v[188:191], v95, s[20:23], s0 offen
	v_mov_b32_e32 v0, v232
	v_mov_b32_e32 v1, v233
	v_mov_b32_e32 v2, v234
	v_mov_b32_e32 v3, v235
	v_mov_b32_e32 v4, v248
	v_mov_b32_e32 v5, v249
	v_mov_b32_e32 v6, v250
	v_mov_b32_e32 v7, v251
	ds_read_b64 v[28:29], v149 offset:1024
	s_mov_b64 s[4:5], -1
	s_waitcnt lgkmcnt(0)
;     ...
;           _Pragma("unroll") for (int bj = 0; bj < 2; ++bj) _Pragma("unroll") for (int n = 0; n < 2; ++n) {
;             const int cc = bj * HALF + wc3 * 32 + n * 16 + fq3 * 4;
;             const float4 gm = *reinterpret_cast<const float4*>(g.gam + pn * BM + cc), bt = *reinterpret_cast<const float4*>(g.bet + pn * BM + cc);
;             _Pragma("unroll") for (int m = 0; m < 4; ++m) {
;               const int rr = wr3 * 64 + m * 16 + fr3;
;               const float2 ms = *reinterpret_cast<const float2*>(mr + (ai * HALF + rr) * 2);
;               f32x4 y = acc[ai][bj][m][n];
;               const float o0 = (y[0] - ms.x) * ms.y * gm.x + bt.x, o1 = (y[1] - ms.x) * ms.y * gm.y + bt.y;
;               const float o2 = (y[2] - ms.x) * ms.y * gm.z + bt.z, o3 = (y[3] - ms.x) * ms.y * gm.w + bt.w;
;               const unsigned h0 = f2bf(o0), h1 = f2bf(o1), h2 = f2bf(o2), h3 = f2bf(o3);
;               u32x2 ob; ob[0] = h0 | (h1 << 16); ob[1] = h2 | (h3 << 16);
;               *reinterpret_cast<u32x2*>(smem + (rr >> 1) * PIECE + (rr & 1) * 512 + cc * 2) = ob;
;               const int l0 = min(((int)__float_as_uint(o0) - (int)(h0 << 16) + 128) >> 8, 127);
;               const int l1 = min(((int)__float_as_uint(o1) - (int)(h1 << 16) + 128) >> 8, 127);
;               const int l2 = min(((int)__float_as_uint(o2) - (int)(h2 << 16) + 128) >> 8, 127);
;               const int l3 = min(((int)__float_as_uint(o3) - (int)(h3 << 16) + 128) >> 8, 127);
;               *reinterpret_cast<unsigned*>(smem + LOBASE + (rr >> 2) * PIECE + (rr & 3) * 256 + cc) =
;                   (unsigned)(l0 & 255) | ((unsigned)(l1 & 255) << 8) | ((unsigned)(l2 & 255) << 16) | ((unsigned)l3 << 24);
;             }
	v_pk_add_f32 v[30:31], v[50:51], v[28:29] op_sel_hi:[1,0] neg_lo:[0,1] neg_hi:[0,1]
	s_nop 0
	v_pk_mul_f32 v[30:31], v[28:29], v[30:31] op_sel:[1,0]
	v_pk_add_f32 v[36:37], v[48:49], v[28:29] op_sel_hi:[1,0] neg_lo:[0,1] neg_hi:[0,1]
	v_mov_b32_e32 v24, v1
	v_mov_b32_e32 v25, v2
	v_mov_b32_e32 v26, v5
	v_mov_b32_e32 v27, v6
	v_pk_fma_f32 v[30:31], v[24:25], v[30:31], v[26:27]
	v_pk_mul_f32 v[28:29], v[28:29], v[36:37] op_sel:[1,0]
	v_mov_b32_e32 v1, v3
	v_mov_b32_e32 v5, v7
	v_and_b32_sdwa v6, v31, v216 dst_sel:DWORD dst_unused:UNUSED_PAD src0_sel:WORD_1 src1_sel:DWORD
	v_and_b32_sdwa v7, v30, v216 dst_sel:DWORD dst_unused:UNUSED_PAD src0_sel:WORD_1 src1_sel:DWORD
	v_pk_fma_f32 v[2:3], v[0:1], v[28:29], v[4:5]
	v_add3_u32 v23, v31, v6, s78
	v_add3_u32 v6, v30, v7, s78
	v_and_b32_e32 v28, 0xffff0000, v6
	v_and_b32_sdwa v6, v3, v216 dst_sel:DWORD dst_unused:UNUSED_PAD src0_sel:WORD_1 src1_sel:DWORD
	v_and_b32_sdwa v7, v2, v216 dst_sel:DWORD dst_unused:UNUSED_PAD src0_sel:WORD_1 src1_sel:DWORD
	v_add3_u32 v6, v3, v6, s78
	v_add3_u32 v29, v2, v7, s78
	v_and_b32_e32 v36, 0xffff0000, v6
	v_or_b32_sdwa v7, v36, v23 dst_sel:DWORD dst_unused:UNUSED_PAD src0_sel:DWORD src1_sel:WORD_1
	v_or_b32_sdwa v6, v29, v28 dst_sel:DWORD dst_unused:UNUSED_PAD src0_sel:WORD_1 src1_sel:DWORD
	ds_write_b64 v93, v[6:7]
	v_and_b32_e32 v6, 0xffff0000, v29
	v_sub_u32_e32 v2, v2, v6
	v_sub_u32_e32 v6, v30, v28
	v_and_b32_e32 v7, 0xffff0000, v23
	v_add_u32_e32 v6, 0x80, v6
	v_sub_u32_e32 v7, v31, v7
	v_sub_u32_e32 v3, v3, v36
	v_add_u32_e32 v2, 0x80, v2
	v_ashrrev_i32_e32 v6, 8, v6
	v_add_u32_e32 v7, 0x80, v7
	v_add_u32_e32 v3, 0x80, v3
	v_ashrrev_i32_e32 v2, 8, v2
	v_min_i32_e32 v6, 0x7f, v6
	v_ashrrev_i32_e32 v7, 8, v7
	v_ashrrev_i32_e32 v3, 8, v3
	v_min_i32_e32 v2, 0x7f, v2
	v_min_i32_sdwa v7, v7, s79 dst_sel:WORD_1 dst_unused:UNUSED_PAD src0_sel:DWORD src1_sel:DWORD
	v_min_i32_e32 v3, 0x7f, v3
	v_lshlrev_b32_e32 v6, 8, v6
	v_and_b32_e32 v6, 0xff00, v6
	v_and_b32_e32 v7, 0xff0000, v7
	v_perm_b32 v2, v3, v2, s80
	v_or3_b32 v2, v2, v6, v7
	ds_write_b32 v12, v2 offset:144
	ds_read_b64 v[2:3], v13 offset:1024
	s_waitcnt lgkmcnt(0)
	v_pk_add_f32 v[6:7], v[34:35], v[2:3] op_sel_hi:[1,0] neg_lo:[0,1] neg_hi:[0,1]
	s_nop 0
	v_pk_mul_f32 v[6:7], v[2:3], v[6:7] op_sel:[1,0]
	v_pk_add_f32 v[12:13], v[32:33], v[2:3] op_sel_hi:[1,0] neg_lo:[0,1] neg_hi:[0,1]
	v_pk_fma_f32 v[6:7], v[24:25], v[6:7], v[26:27]
	v_pk_mul_f32 v[2:3], v[2:3], v[12:13] op_sel:[1,0]
	v_and_b32_sdwa v12, v7, v216 dst_sel:DWORD dst_unused:UNUSED_PAD src0_sel:WORD_1 src1_sel:DWORD
	v_and_b32_sdwa v13, v6, v216 dst_sel:DWORD dst_unused:UNUSED_PAD src0_sel:WORD_1 src1_sel:DWORD
	v_pk_fma_f32 v[2:3], v[0:1], v[2:3], v[4:5]
	v_add3_u32 v23, v7, v12, s78
	v_add3_u32 v12, v6, v13, s78
	v_and_b32_e32 v28, 0xffff0000, v12
	v_and_b32_sdwa v12, v3, v216 dst_sel:DWORD dst_unused:UNUSED_PAD src0_sel:WORD_1 src1_sel:DWORD
	v_and_b32_sdwa v13, v2, v216 dst_sel:DWORD dst_unused:UNUSED_PAD src0_sel:WORD_1 src1_sel:DWORD
	v_add3_u32 v12, v3, v12, s78
	v_add3_u32 v29, v2, v13, s78
	v_and_b32_e32 v30, 0xffff0000, v12
	v_or_b32_sdwa v13, v30, v23 dst_sel:DWORD dst_unused:UNUSED_PAD src0_sel:DWORD src1_sel:WORD_1
	v_or_b32_sdwa v12, v29, v28 dst_sel:DWORD dst_unused:UNUSED_PAD src0_sel:WORD_1 src1_sel:DWORD
	ds_write_b64 v94, v[12:13]
	v_and_b32_e32 v12, 0xffff0000, v29
	v_sub_u32_e32 v2, v2, v12
	v_sub_u32_e32 v6, v6, v28
	v_and_b32_e32 v12, 0xffff0000, v23
	v_add_u32_e32 v6, 0x80, v6
	v_sub_u32_e32 v7, v7, v12
	v_sub_u32_e32 v3, v3, v30
	v_add_u32_e32 v2, 0x80, v2
	v_ashrrev_i32_e32 v6, 8, v6
	v_add_u32_e32 v7, 0x80, v7
	v_add_u32_e32 v3, 0x80, v3
	v_ashrrev_i32_e32 v2, 8, v2
	v_min_i32_e32 v6, 0x7f, v6
	v_ashrrev_i32_e32 v7, 8, v7
	v_ashrrev_i32_e32 v3, 8, v3
	v_min_i32_e32 v2, 0x7f, v2
	v_min_i32_sdwa v7, v7, s79 dst_sel:WORD_1 dst_unused:UNUSED_PAD src0_sel:DWORD src1_sel:DWORD
	v_min_i32_e32 v3, 0x7f, v3
	v_lshlrev_b32_e32 v6, 8, v6
	v_and_b32_e32 v6, 0xff00, v6
	v_and_b32_e32 v7, 0xff0000, v7
	v_perm_b32 v2, v3, v2, s80
	v_or3_b32 v2, v2, v6, v7
	ds_write_b32 v14, v2 offset:144
	ds_read_b64 v[2:3], v15 offset:1024
	s_waitcnt lgkmcnt(0)
	v_pk_add_f32 v[6:7], v[18:19], v[2:3] op_sel_hi:[1,0] neg_lo:[0,1] neg_hi:[0,1]
	s_nop 0
	v_pk_mul_f32 v[6:7], v[2:3], v[6:7] op_sel:[1,0]
	v_pk_add_f32 v[12:13], v[16:17], v[2:3] op_sel_hi:[1,0] neg_lo:[0,1] neg_hi:[0,1]
	v_pk_fma_f32 v[6:7], v[24:25], v[6:7], v[26:27]
	v_pk_mul_f32 v[2:3], v[2:3], v[12:13] op_sel:[1,0]
	v_and_b32_sdwa v12, v7, v216 dst_sel:DWORD dst_unused:UNUSED_PAD src0_sel:WORD_1 src1_sel:DWORD
	v_and_b32_sdwa v13, v6, v216 dst_sel:DWORD dst_unused:UNUSED_PAD src0_sel:WORD_1 src1_sel:DWORD
	v_pk_fma_f32 v[2:3], v[0:1], v[2:3], v[4:5]
	v_add3_u32 v14, v7, v12, s78
	v_add3_u32 v12, v6, v13, s78
	v_and_b32_e32 v15, 0xffff0000, v12
	v_and_b32_sdwa v12, v3, v216 dst_sel:DWORD dst_unused:UNUSED_PAD src0_sel:WORD_1 src1_sel:DWORD
	v_and_b32_sdwa v13, v2, v216 dst_sel:DWORD dst_unused:UNUSED_PAD src0_sel:WORD_1 src1_sel:DWORD
	v_add3_u32 v12, v3, v12, s78
	v_add3_u32 v16, v2, v13, s78
	v_and_b32_e32 v17, 0xffff0000, v12
	v_or_b32_sdwa v13, v17, v14 dst_sel:DWORD dst_unused:UNUSED_PAD src0_sel:DWORD src1_sel:WORD_1
	v_or_b32_sdwa v12, v16, v15 dst_sel:DWORD dst_unused:UNUSED_PAD src0_sel:WORD_1 src1_sel:DWORD
	ds_write_b64 v80, v[12:13]
	v_and_b32_e32 v12, 0xffff0000, v16
	v_sub_u32_e32 v2, v2, v12
	v_sub_u32_e32 v6, v6, v15
	v_and_b32_e32 v12, 0xffff0000, v14
	v_add_u32_e32 v6, 0x80, v6
	v_sub_u32_e32 v7, v7, v12
	v_sub_u32_e32 v3, v3, v17
	v_add_u32_e32 v2, 0x80, v2
	v_ashrrev_i32_e32 v6, 8, v6
	v_add_u32_e32 v7, 0x80, v7
	v_add_u32_e32 v3, 0x80, v3
	v_ashrrev_i32_e32 v2, 8, v2
	v_min_i32_e32 v6, 0x7f, v6
	v_ashrrev_i32_e32 v7, 8, v7
	v_ashrrev_i32_e32 v3, 8, v3
	v_min_i32_e32 v2, 0x7f, v2
	v_min_i32_sdwa v7, v7, s79 dst_sel:WORD_1 dst_unused:UNUSED_PAD src0_sel:DWORD src1_sel:DWORD
	v_min_i32_e32 v3, 0x7f, v3
	v_lshlrev_b32_e32 v6, 8, v6
	v_and_b32_e32 v6, 0xff00, v6
	v_and_b32_e32 v7, 0xff0000, v7
	v_perm_b32 v2, v3, v2, s80
	v_or3_b32 v2, v2, v6, v7
	ds_write_b32 v20, v2 offset:144
	ds_read_b64 v[2:3], v21 offset:1024
	s_waitcnt lgkmcnt(0)
; #define STAGE(P, RS, SOFF, OFF, kt) do { const int _so = (SOFF) + (kt) * (BK * 2); \
;     _Pragma("unroll") for (int _i = 0; _i < 2; ++_i) { \
;       __builtin_amdgcn_raw_ptr_buffer_load_lds(RS, (__attribute__((address_space(3))) void*)((P) + wave * 1024 + _i * 8192), 16, OFF[_i], _so, 0, 0); } } while (0)
; #define WAIT_L(n) asm volatile("s_waitcnt lgkmcnt(" #n ")" ::: "memory")
; #define BAR __builtin_amdgcn_s_barrier()
;     ...
;   auto issue_prologue = [&](int sA0, int sA1, int sB0, int sB1) {
;     const int tid = opaque_tid(wave);
;     int offA[2], offB[2];
;     _Pragma("unroll") for (int i = 0; i < 2; ++i) {
;       int r, c; stage_rc(tid * 16 + i * 8192, r, c);
;       offA[i] = (r * lda + c) * 2; offB[i] = (r * ldb + c) * 2;
;     }
;     STAGE(SB(0, 0), rsB, sB0, offB, 0); STAGE(SA(0, 0), rsA, sA0, offA, 0);
;     STAGE(SB(0, 1), rsB, sB1, offB, 0); STAGE(SA(0, 1), rsA, sA1, offA, 0);
;     STAGE(SB(1, 0), rsB, sB0, offB, 1); STAGE(SA(1, 0), rsA, sA0, offA, 1); STAGE(SB(1, 1), rsB, sB1, offB, 1);
;   };
;     ...
;           WAIT_L(0); BAR;
;           const int hso = ((brow + ai * HALF + 16 * wave) * DM + pn * BM) * 2;
;           const int lso = (brow + ai * HALF + 16 * wave) * DM + pn * BM;
;           _Pragma("unroll") for (int i = 0; i < 8; ++i) {
;             const u32x4 v = *reinterpret_cast<const u32x4*>(smem + (wave * 8 + i) * PIECE + lane3 * 16);
;             __builtin_amdgcn_raw_buffer_store_b128(v, rsXB, hvo + i * (2 * DM * 2), hso, 0);
;           }
;           _Pragma("unroll") for (int i = 0; i < 4; ++i) {
;             const u32x4 v = *reinterpret_cast<const u32x4*>(smem + LOBASE + (wave * 4 + i) * PIECE + lane3 * 16);
;             __builtin_amdgcn_raw_buffer_store_b128(v, rsLO, lvo + i * (4 * DM), lso, 0);
;           }
;           WAIT_L(0); BAR;
;         }
;       }
;       if (has_next) issue_prologue(nA0, nA1, nB0, nB1);
	v_pk_add_f32 v[6:7], v[10:11], v[2:3] op_sel_hi:[1,0] neg_lo:[0,1] neg_hi:[0,1]
	s_nop 0
	v_pk_mul_f32 v[6:7], v[2:3], v[6:7] op_sel:[1,0]
	v_pk_add_f32 v[8:9], v[8:9], v[2:3] op_sel_hi:[1,0] neg_lo:[0,1] neg_hi:[0,1]
	v_pk_fma_f32 v[6:7], v[24:25], v[6:7], v[26:27]
	v_pk_mul_f32 v[2:3], v[2:3], v[8:9] op_sel:[1,0]
	s_nop 0
	v_pk_fma_f32 v[0:1], v[0:1], v[2:3], v[4:5]
	v_and_b32_sdwa v2, v7, v216 dst_sel:DWORD dst_unused:UNUSED_PAD src0_sel:WORD_1 src1_sel:DWORD
	v_and_b32_sdwa v3, v6, v216 dst_sel:DWORD dst_unused:UNUSED_PAD src0_sel:WORD_1 src1_sel:DWORD
	v_add3_u32 v4, v7, v2, s78
	v_add3_u32 v2, v6, v3, s78
	v_and_b32_e32 v5, 0xffff0000, v2
	v_and_b32_sdwa v2, v1, v216 dst_sel:DWORD dst_unused:UNUSED_PAD src0_sel:WORD_1 src1_sel:DWORD
	v_and_b32_sdwa v3, v0, v216 dst_sel:DWORD dst_unused:UNUSED_PAD src0_sel:WORD_1 src1_sel:DWORD
	v_add3_u32 v2, v1, v2, s78
	v_add3_u32 v8, v0, v3, s78
	v_and_b32_e32 v9, 0xffff0000, v2
	v_or_b32_sdwa v3, v9, v4 dst_sel:DWORD dst_unused:UNUSED_PAD src0_sel:DWORD src1_sel:WORD_1
	v_or_b32_sdwa v2, v8, v5 dst_sel:DWORD dst_unused:UNUSED_PAD src0_sel:WORD_1 src1_sel:DWORD
	ds_write_b64 v73, v[2:3]
	v_and_b32_e32 v2, 0xffff0000, v8
	v_sub_u32_e32 v0, v0, v2
	v_sub_u32_e32 v2, v6, v5
	v_and_b32_e32 v3, 0xffff0000, v4
	v_add_u32_e32 v2, 0x80, v2
	v_sub_u32_e32 v3, v7, v3
	v_sub_u32_e32 v1, v1, v9
	v_add_u32_e32 v0, 0x80, v0
	v_ashrrev_i32_e32 v2, 8, v2
	v_add_u32_e32 v3, 0x80, v3
	v_add_u32_e32 v1, 0x80, v1
	v_ashrrev_i32_e32 v0, 8, v0
	v_min_i32_e32 v2, 0x7f, v2
	v_ashrrev_i32_e32 v3, 8, v3
	v_ashrrev_i32_e32 v1, 8, v1
	v_min_i32_e32 v0, 0x7f, v0
	v_min_i32_sdwa v3, v3, s79 dst_sel:WORD_1 dst_unused:UNUSED_PAD src0_sel:DWORD src1_sel:DWORD
	v_min_i32_e32 v1, 0x7f, v1
	v_lshlrev_b32_e32 v2, 8, v2
	v_and_b32_e32 v2, 0xff00, v2
	v_and_b32_e32 v3, 0xff0000, v3
	v_perm_b32 v0, v1, v0, s80
	v_or3_b32 v0, v0, v2, v3
	ds_write_b32 v22, v0 offset:144
	s_waitcnt lgkmcnt(0)
	s_barrier
	ds_read_b128 v[0:3], v72
	s_waitcnt lgkmcnt(0)
	buffer_store_dwordx4 v[0:3], v148, s[16:19], s3 offen
	ds_read_b128 v[0:3], v72 offset:1040
	s_waitcnt lgkmcnt(0)
	buffer_store_dwordx4 v[0:3], v74, s[16:19], s3 offen
	ds_read_b128 v[0:3], v72 offset:2080
	s_waitcnt lgkmcnt(0)
	buffer_store_dwordx4 v[0:3], v75, s[16:19], s3 offen
	ds_read_b128 v[0:3], v72 offset:3120
	s_waitcnt lgkmcnt(0)
	buffer_store_dwordx4 v[0:3], v81, s[16:19], s3 offen
	ds_read_b128 v[0:3], v72 offset:4160
	s_waitcnt lgkmcnt(0)
	buffer_store_dwordx4 v[0:3], v82, s[16:19], s3 offen
	ds_read_b128 v[0:3], v72 offset:5200
	s_waitcnt lgkmcnt(0)
	buffer_store_dwordx4 v[0:3], v83, s[16:19], s3 offen
	ds_read_b128 v[0:3], v72 offset:6240
	s_waitcnt lgkmcnt(0)
	buffer_store_dwordx4 v[0:3], v88, s[16:19], s3 offen
	ds_read_b128 v[0:3], v72 offset:7280
	s_waitcnt lgkmcnt(0)
	buffer_store_dwordx4 v[0:3], v89, s[16:19], s3 offen
	ds_read_b128 v[0:3], v147
	s_waitcnt lgkmcnt(0)
	buffer_store_dwordx4 v[0:3], v146, s[20:23], s1 offen
	ds_read_b128 v[0:3], v147 offset:1040
	s_waitcnt lgkmcnt(0)
	buffer_store_dwordx4 v[0:3], v90, s[20:23], s1 offen
	ds_read_b128 v[0:3], v147 offset:2080
	s_waitcnt lgkmcnt(0)
	buffer_store_dwordx4 v[0:3], v91, s[20:23], s1 offen
	ds_read_b128 v[0:3], v147 offset:3120
	s_waitcnt lgkmcnt(0)
	buffer_store_dwordx4 v[0:3], v95, s[20:23], s1 offen
	s_waitcnt lgkmcnt(0)
	s_barrier
	s_cbranch_vccnz .LBB0_486
	v_mbcnt_lo_u32_b32 v0, -1, 0
	v_mbcnt_hi_u32_b32 v0, -1, v0
	s_mov_b32 m0, s37
	v_lshl_add_u32 v0, v0, 4, s35
	v_ashrrev_i32_e32 v1, 31, v0
	v_lshrrev_b32_e32 v1, 22, v1
	v_add_u32_e32 v1, v0, v1
	v_ashrrev_i32_e32 v1, 10, v1
	v_mul_i32_i24_e32 v2, 0x400, v1
	v_sub_u32_e32 v2, v0, v2
	v_lshrrev_b32_e32 v3, 4, v2
	v_bitop3_b32 v2, v3, v2, 32 bitop3:0x6c
	v_ashrrev_i32_e32 v4, 31, v2
	v_lshrrev_b32_e32 v4, 26, v4
	v_add_u32_e32 v4, v2, v4
	v_lshrrev_b32_e32 v5, 6, v4
	v_and_b32_e32 v4, 0xc0, v4
	v_lshlrev_b32_e32 v3, 3, v1
	v_lshlrev_b32_e32 v1, 5, v1
	v_sub_u32_e32 v2, v2, v4
	v_and_b32_e32 v3, 0x7fff0, v3
	v_and_b32_e32 v1, 32, v1
	v_ashrrev_i16_sdwa v2, v216, sext(v2) dst_sel:DWORD dst_unused:UNUSED_PAD src0_sel:DWORD src1_sel:BYTE_0
	v_add_u32_sdwa v1, v1, sext(v2) dst_sel:DWORD dst_unused:UNUSED_PAD src0_sel:DWORD src1_sel:WORD_0
	v_add_lshl_u32 v2, v5, v3, 13
	v_add_u32_e32 v0, 0x2000, v0
	v_lshl_add_u32 v1, v1, 1, v2
	v_ashrrev_i32_e32 v2, 31, v0
	v_lshrrev_b32_e32 v2, 22, v2
	v_add_u32_e32 v2, v0, v2
	v_ashrrev_i32_e32 v2, 10, v2
	v_mul_i32_i24_e32 v3, 0x400, v2
	v_sub_u32_e32 v0, v0, v3
	v_lshrrev_b32_e32 v3, 4, v0
	v_bitop3_b32 v0, v3, v0, 32 bitop3:0x6c
	v_ashrrev_i32_e32 v4, 31, v0
	v_lshrrev_b32_e32 v4, 26, v4
	v_add_u32_e32 v4, v0, v4
	v_lshrrev_b32_e32 v5, 6, v4
	v_and_b32_e32 v4, 0xffc0, v4
	v_sub_u32_e32 v0, v0, v4
	v_lshrrev_b16_e32 v4, 7, v0
	v_and_b32_e32 v4, 1, v4
	v_lshlrev_b32_e32 v3, 3, v2
	v_lshlrev_b32_e32 v2, 5, v2
	v_add_u16_e32 v0, v0, v4
	v_and_b32_e32 v3, 0x7fff0, v3
	v_and_b32_e32 v2, 32, v2
	v_ashrrev_i16_sdwa v0, v216, sext(v0) dst_sel:DWORD dst_unused:UNUSED_PAD src0_sel:DWORD src1_sel:BYTE_0
	v_add_u32_sdwa v0, v2, sext(v0) dst_sel:DWORD dst_unused:UNUSED_PAD src0_sel:DWORD src1_sel:WORD_0
	v_add_lshl_u32 v2, v5, v3, 13
	s_mov_b32 s14, s10
	s_mov_b32 s15, s11
	v_lshl_add_u32 v0, v0, 1, v2
	buffer_load_dwordx4 v1, s[12:15], s84 offen lds
	s_mov_b32 m0, s70
	s_or_b32 s0, s84, 0x80
	buffer_load_dwordx4 v0, s[12:15], s84 offen lds
	s_mov_b32 m0, s35
	s_mov_b64 s[4:5], 0
	buffer_load_dwordx4 v1, s[8:11], s83 offen lds
	s_mov_b32 m0, s95
	s_nop 0
	buffer_load_dwordx4 v0, s[8:11], s83 offen lds
	s_mov_b32 m0, s38
	s_nop 0
	buffer_load_dwordx4 v1, s[12:15], s85 offen lds
	s_mov_b32 m0, s71
	s_nop 0
	buffer_load_dwordx4 v0, s[12:15], s85 offen lds
	s_mov_b32 m0, s39
	s_nop 0
	buffer_load_dwordx4 v1, s[8:11], s82 offen lds
	s_mov_b32 m0, s97
	s_nop 0
	buffer_load_dwordx4 v0, s[8:11], s82 offen lds
	s_mov_b32 m0, s92
	s_nop 0
	buffer_load_dwordx4 v1, s[12:15], s0 offen lds
	s_mov_b32 m0, s56
	s_nop 0
	buffer_load_dwordx4 v0, s[12:15], s0 offen lds
	s_or_b32 s0, s83, 0x80
	s_mov_b32 m0, s93
	s_nop 0
	buffer_load_dwordx4 v1, s[8:11], s0 offen lds
	s_mov_b32 m0, s57
	s_nop 0
	buffer_load_dwordx4 v0, s[8:11], s0 offen lds
	s_add_i32 s0, s85, 0x80
	s_mov_b32 m0, s94
	s_nop 0
	buffer_load_dwordx4 v1, s[12:15], s0 offen lds
	s_mov_b32 m0, s58
	s_nop 0
	buffer_load_dwordx4 v0, s[12:15], s0 offen lds
	s_branch .LBB0_486

; __device__ __forceinline__ void pool_phase(const u16* __restrict__ UG, u16* __restrict__ PL, const float* __restrict__ scale, const int wave) {
;   const int nitems = (MT / 64) * 256;
;   for (int item = blockIdx.x * NTHREADS + opaque_tid(wave); item < nitems; item += gridDim.x * NTHREADS) {
;     const int cg8 = item & 255, chunk = item >> 8;
;     const int c0 = cg8 * 8;
;     const int w = 2 << (c0 >> 9);
;     const int r0 = chunk * 64;
;     const int s0 = r0 % SEQ;
;     float sum[8], sc[8];
;     for (int e = 0; e < 8; ++e) { sum[e] = 0.f; sc[e] = scale[c0 + e]; }
;     for (int i = 1; i <= w; ++i) {
;       if (s0 - i >= 0) {
;         uint4 u = *reinterpret_cast<const uint4*>(UG + (long)(r0 - i) * 4096 + c0);
;         sum[0] += __uint_as_float(u.x << 16); sum[1] += __uint_as_float(u.x & 0xffff0000u);
;         sum[2] += __uint_as_float(u.y << 16); sum[3] += __uint_as_float(u.y & 0xffff0000u);
;         sum[4] += __uint_as_float(u.z << 16); sum[5] += __uint_as_float(u.z & 0xffff0000u);
;         sum[6] += __uint_as_float(u.w << 16); sum[7] += __uint_as_float(u.w & 0xffff0000u);
;       }
;     }
.LBB0_581:
	s_cmp_gt_i32 s90, 11
	s_cselect_b64 s[0:1], -1, 0
	s_cmp_lt_i32 s91, 12
	s_cselect_b64 s[4:5], -1, 0
	s_or_b64 s[0:1], s[0:1], s[4:5]
	s_and_b64 vcc, exec, s[0:1]
	s_cbranch_vccnz .LBB0_643
	s_and_b32 s0, s62, 0xffffffc0
	v_mbcnt_lo_u32_b32 v0, -1, 0
	v_mbcnt_hi_u32_b32 v0, -1, v0
	v_readlane_b32 s4, v255, 22
	v_readlane_b32 s5, v255, 23
	s_and_b32 s1, s0, 0xff
	v_add_u32_e32 v1, s1, v0
	v_lshlrev_b32_e32 v2, 4, v1
	v_lshlrev_b32_e32 v3, 5, v1
	s_lshr_b32 s3, s0, 8
	s_lshl_b32 s6, s2, 1
	s_add_i32 s6, s6, s3
	s_lshr_b32 s7, s0, 6
	s_and_b32 s7, s7, 3
	s_lshl_b32 s7, 2, s7
	s_lshl_b32 s8, s6, 6
	s_and_b32 s9, s8, 0x3fff
	global_load_dwordx4 v[4:7], v3, s[4:5]
	global_load_dwordx4 v[8:11], v3, s[4:5] offset:16
	s_lshl_b32 s10, s8, 13
	s_add_u32 s12, s88, 0x16a00000
	s_addc_u32 s13, s89, 0
	s_add_u32 s12, s12, s10
	s_addc_u32 s13, s13, 0
	s_add_u32 s14, s12, 0x1000
	s_addc_u32 s15, s13, 0
	s_lshl_b32 s11, s7, 13
	s_sub_u32 s16, s12, s11
	s_subb_u32 s17, s13, 0
	s_lshl_b32 s10, s8, 12
	s_add_u32 s18, s88, 0x26a00000
	s_addc_u32 s19, s89, 0
	s_add_u32 s18, s18, s10
	s_addc_u32 s19, s19, 0
	v_add_u32_e32 v20, 0x0, v2
	v_add_u32_e32 v28, 0x0, v2
	v_add_u32_e32 v21, 0x2000, v2
	v_add_u32_e32 v29, 0x1000, v2
	v_add_u32_e32 v22, 0x4000, v2
	v_add_u32_e32 v30, 0x2000, v2
	v_add_u32_e32 v23, 0x6000, v2
	v_add_u32_e32 v31, 0x3000, v2
	v_add_u32_e32 v24, 0x8000, v2
	v_add_u32_e32 v32, 0x4000, v2
	v_add_u32_e32 v25, 0xa000, v2
	v_add_u32_e32 v33, 0x5000, v2
	v_add_u32_e32 v26, 0xc000, v2
	v_add_u32_e32 v34, 0x6000, v2
	v_add_u32_e32 v27, 0xe000, v2
	v_add_u32_e32 v35, 0x7000, v2
	v_mov_b32_e32 v12, 0
	v_mov_b32_e32 v13, 0
	v_mov_b32_e32 v14, 0
	v_mov_b32_e32 v15, 0
	v_mov_b32_e32 v16, 0
	v_mov_b32_e32 v17, 0
	v_mov_b32_e32 v18, 0
	v_mov_b32_e32 v19, 0
	s_cmp_eq_u32 s9, 0
	s_cbranch_scc1 .Lmy_pool_main
	s_sub_u32 s20, s12, 0x10000
	s_subb_u32 s21, s13, 0
	global_load_dwordx4 v[40:43], v27, s[20:21]
	global_load_dwordx4 v[44:47], v26, s[20:21]
	s_cmp_eq_u32 s7, 2
	s_cbranch_scc1 .Lmy_pool_pw
	global_load_dwordx4 v[48:51], v25, s[20:21]
	global_load_dwordx4 v[52:55], v24, s[20:21]
	s_cmp_eq_u32 s7, 4
	s_cbranch_scc1 .Lmy_pool_pw
	global_load_dwordx4 v[56:59], v23, s[20:21]
	global_load_dwordx4 v[60:63], v22, s[20:21]
	global_load_dwordx4 v[64:67], v21, s[20:21]
	global_load_dwordx4 v[68:71], v20, s[20:21]
	s_cmp_eq_u32 s7, 8
	s_cbranch_scc1 .Lmy_pool_pw
	s_sub_u32 s20, s20, 0x10000
	s_subb_u32 s21, s21, 0
	global_load_dwordx4 v[72:75], v27, s[20:21]
	global_load_dwordx4 v[76:79], v26, s[20:21]
	global_load_dwordx4 v[80:83], v25, s[20:21]
	global_load_dwordx4 v[84:87], v24, s[20:21]
	global_load_dwordx4 v[88:91], v23, s[20:21]
	global_load_dwordx4 v[92:95], v22, s[20:21]
	global_load_dwordx4 v[96:99], v21, s[20:21]
	global_load_dwordx4 v[100:103], v20, s[20:21]
.Lmy_pool_pw:
	s_waitcnt vmcnt(0)
	v_lshlrev_b32_e32 v136, 16, v40
	v_and_b32_e32 v137, 0xffff0000, v40
	v_lshlrev_b32_e32 v138, 16, v41
	v_and_b32_e32 v139, 0xffff0000, v41
	v_lshlrev_b32_e32 v140, 16, v42
	v_and_b32_e32 v141, 0xffff0000, v42
	v_lshlrev_b32_e32 v142, 16, v43
	v_and_b32_e32 v143, 0xffff0000, v43
	v_pk_add_f32 v[12:13], v[12:13], v[136:137]
	v_pk_add_f32 v[14:15], v[14:15], v[138:139]
	v_pk_add_f32 v[16:17], v[16:17], v[140:141]
	v_pk_add_f32 v[18:19], v[18:19], v[142:143]
	v_lshlrev_b32_e32 v136, 16, v44
	v_and_b32_e32 v137, 0xffff0000, v44
	v_lshlrev_b32_e32 v138, 16, v45
	v_and_b32_e32 v139, 0xffff0000, v45
	v_lshlrev_b32_e32 v140, 16, v46
	v_and_b32_e32 v141, 0xffff0000, v46
	v_lshlrev_b32_e32 v142, 16, v47
	v_and_b32_e32 v143, 0xffff0000, v47
	v_pk_add_f32 v[12:13], v[12:13], v[136:137]
	v_pk_add_f32 v[14:15], v[14:15], v[138:139]
	v_pk_add_f32 v[16:17], v[16:17], v[140:141]
	v_pk_add_f32 v[18:19], v[18:19], v[142:143]
	s_cmp_eq_u32 s7, 2
	s_cbranch_scc1 .Lmy_pool_main
	v_lshlrev_b32_e32 v136, 16, v48
	v_and_b32_e32 v137, 0xffff0000, v48
	v_lshlrev_b32_e32 v138, 16, v49
	v_and_b32_e32 v139, 0xffff0000, v49
	v_lshlrev_b32_e32 v140, 16, v50
	v_and_b32_e32 v141, 0xffff0000, v50
	v_lshlrev_b32_e32 v142, 16, v51
	v_and_b32_e32 v143, 0xffff0000, v51
	v_pk_add_f32 v[12:13], v[12:13], v[136:137]
	v_pk_add_f32 v[14:15], v[14:15], v[138:139]
	v_pk_add_f32 v[16:17], v[16:17], v[140:141]
	v_pk_add_f32 v[18:19], v[18:19], v[142:143]
	v_lshlrev_b32_e32 v136, 16, v52
	v_and_b32_e32 v137, 0xffff0000, v52
	v_lshlrev_b32_e32 v138, 16, v53
	v_and_b32_e32 v139, 0xffff0000, v53
	v_lshlrev_b32_e32 v140, 16, v54
	v_and_b32_e32 v141, 0xffff0000, v54
	v_lshlrev_b32_e32 v142, 16, v55
	v_and_b32_e32 v143, 0xffff0000, v55
	v_pk_add_f32 v[12:13], v[12:13], v[136:137]
	v_pk_add_f32 v[14:15], v[14:15], v[138:139]
	v_pk_add_f32 v[16:17], v[16:17], v[140:141]
	v_pk_add_f32 v[18:19], v[18:19], v[142:143]
	s_cmp_eq_u32 s7, 4
	s_cbranch_scc1 .Lmy_pool_main
; __device__ __forceinline__ void pool_phase(const u16* __restrict__ UG, u16* __restrict__ PL, const float* __restrict__ scale, const int wave) {
;     ...
;     for (int i = 1; i <= w; ++i) {
;       if (s0 - i >= 0) {
;         uint4 u = *reinterpret_cast<const uint4*>(UG + (long)(r0 - i) * 4096 + c0);
;         sum[0] += __uint_as_float(u.x << 16); sum[1] += __uint_as_float(u.x & 0xffff0000u);
;         sum[2] += __uint_as_float(u.y << 16); sum[3] += __uint_as_float(u.y & 0xffff0000u);
;         sum[4] += __uint_as_float(u.z << 16); sum[5] += __uint_as_float(u.z & 0xffff0000u);
;         sum[6] += __uint_as_float(u.w << 16); sum[7] += __uint_as_float(u.w & 0xffff0000u);
;       }
;     }
	v_lshlrev_b32_e32 v136, 16, v56
	v_and_b32_e32 v137, 0xffff0000, v56
	v_lshlrev_b32_e32 v138, 16, v57
	v_and_b32_e32 v139, 0xffff0000, v57
	v_lshlrev_b32_e32 v140, 16, v58
	v_and_b32_e32 v141, 0xffff0000, v58
	v_lshlrev_b32_e32 v142, 16, v59
	v_and_b32_e32 v143, 0xffff0000, v59
	v_pk_add_f32 v[12:13], v[12:13], v[136:137]
	v_pk_add_f32 v[14:15], v[14:15], v[138:139]
	v_pk_add_f32 v[16:17], v[16:17], v[140:141]
	v_pk_add_f32 v[18:19], v[18:19], v[142:143]
	v_lshlrev_b32_e32 v136, 16, v60
	v_and_b32_e32 v137, 0xffff0000, v60
	v_lshlrev_b32_e32 v138, 16, v61
	v_and_b32_e32 v139, 0xffff0000, v61
	v_lshlrev_b32_e32 v140, 16, v62
	v_and_b32_e32 v141, 0xffff0000, v62
	v_lshlrev_b32_e32 v142, 16, v63
	v_and_b32_e32 v143, 0xffff0000, v63
	v_pk_add_f32 v[12:13], v[12:13], v[136:137]
	v_pk_add_f32 v[14:15], v[14:15], v[138:139]
	v_pk_add_f32 v[16:17], v[16:17], v[140:141]
	v_pk_add_f32 v[18:19], v[18:19], v[142:143]
	v_lshlrev_b32_e32 v136, 16, v64
	v_and_b32_e32 v137, 0xffff0000, v64
	v_lshlrev_b32_e32 v138, 16, v65
	v_and_b32_e32 v139, 0xffff0000, v65
	v_lshlrev_b32_e32 v140, 16, v66
	v_and_b32_e32 v141, 0xffff0000, v66
	v_lshlrev_b32_e32 v142, 16, v67
	v_and_b32_e32 v143, 0xffff0000, v67
	v_pk_add_f32 v[12:13], v[12:13], v[136:137]
	v_pk_add_f32 v[14:15], v[14:15], v[138:139]
	v_pk_add_f32 v[16:17], v[16:17], v[140:141]
	v_pk_add_f32 v[18:19], v[18:19], v[142:143]
	v_lshlrev_b32_e32 v136, 16, v68
	v_and_b32_e32 v137, 0xffff0000, v68
	v_lshlrev_b32_e32 v138, 16, v69
	v_and_b32_e32 v139, 0xffff0000, v69
	v_lshlrev_b32_e32 v140, 16, v70
	v_and_b32_e32 v141, 0xffff0000, v70
	v_lshlrev_b32_e32 v142, 16, v71
	v_and_b32_e32 v143, 0xffff0000, v71
	v_pk_add_f32 v[12:13], v[12:13], v[136:137]
	v_pk_add_f32 v[14:15], v[14:15], v[138:139]
	v_pk_add_f32 v[16:17], v[16:17], v[140:141]
	v_pk_add_f32 v[18:19], v[18:19], v[142:143]
	s_cmp_eq_u32 s7, 8
	s_cbranch_scc1 .Lmy_pool_main
	v_lshlrev_b32_e32 v136, 16, v72
	v_and_b32_e32 v137, 0xffff0000, v72
	v_lshlrev_b32_e32 v138, 16, v73
	v_and_b32_e32 v139, 0xffff0000, v73
	v_lshlrev_b32_e32 v140, 16, v74
	v_and_b32_e32 v141, 0xffff0000, v74
	v_lshlrev_b32_e32 v142, 16, v75
	v_and_b32_e32 v143, 0xffff0000, v75
	v_pk_add_f32 v[12:13], v[12:13], v[136:137]
	v_pk_add_f32 v[14:15], v[14:15], v[138:139]
	v_pk_add_f32 v[16:17], v[16:17], v[140:141]
	v_pk_add_f32 v[18:19], v[18:19], v[142:143]
	v_lshlrev_b32_e32 v136, 16, v76
	v_and_b32_e32 v137, 0xffff0000, v76
	v_lshlrev_b32_e32 v138, 16, v77
	v_and_b32_e32 v139, 0xffff0000, v77
	v_lshlrev_b32_e32 v140, 16, v78
	v_and_b32_e32 v141, 0xffff0000, v78
	v_lshlrev_b32_e32 v142, 16, v79
	v_and_b32_e32 v143, 0xffff0000, v79
	v_pk_add_f32 v[12:13], v[12:13], v[136:137]
	v_pk_add_f32 v[14:15], v[14:15], v[138:139]
	v_pk_add_f32 v[16:17], v[16:17], v[140:141]
	v_pk_add_f32 v[18:19], v[18:19], v[142:143]
	v_lshlrev_b32_e32 v136, 16, v80
	v_and_b32_e32 v137, 0xffff0000, v80
	v_lshlrev_b32_e32 v138, 16, v81
	v_and_b32_e32 v139, 0xffff0000, v81
	v_lshlrev_b32_e32 v140, 16, v82
	v_and_b32_e32 v141, 0xffff0000, v82
	v_lshlrev_b32_e32 v142, 16, v83
	v_and_b32_e32 v143, 0xffff0000, v83
	v_pk_add_f32 v[12:13], v[12:13], v[136:137]
	v_pk_add_f32 v[14:15], v[14:15], v[138:139]
	v_pk_add_f32 v[16:17], v[16:17], v[140:141]
	v_pk_add_f32 v[18:19], v[18:19], v[142:143]
	v_lshlrev_b32_e32 v136, 16, v84
	v_and_b32_e32 v137, 0xffff0000, v84
	v_lshlrev_b32_e32 v138, 16, v85
	v_and_b32_e32 v139, 0xffff0000, v85
	v_lshlrev_b32_e32 v140, 16, v86
	v_and_b32_e32 v141, 0xffff0000, v86
	v_lshlrev_b32_e32 v142, 16, v87
	v_and_b32_e32 v143, 0xffff0000, v87
	v_pk_add_f32 v[12:13], v[12:13], v[136:137]
	v_pk_add_f32 v[14:15], v[14:15], v[138:139]
	v_pk_add_f32 v[16:17], v[16:17], v[140:141]
	v_pk_add_f32 v[18:19], v[18:19], v[142:143]
	v_lshlrev_b32_e32 v136, 16, v88
	v_and_b32_e32 v137, 0xffff0000, v88
	v_lshlrev_b32_e32 v138, 16, v89
	v_and_b32_e32 v139, 0xffff0000, v89
	v_lshlrev_b32_e32 v140, 16, v90
	v_and_b32_e32 v141, 0xffff0000, v90
	v_lshlrev_b32_e32 v142, 16, v91
	v_and_b32_e32 v143, 0xffff0000, v91
	v_pk_add_f32 v[12:13], v[12:13], v[136:137]
	v_pk_add_f32 v[14:15], v[14:15], v[138:139]
	v_pk_add_f32 v[16:17], v[16:17], v[140:141]
	v_pk_add_f32 v[18:19], v[18:19], v[142:143]
	v_lshlrev_b32_e32 v136, 16, v92
	v_and_b32_e32 v137, 0xffff0000, v92
	v_lshlrev_b32_e32 v138, 16, v93
	v_and_b32_e32 v139, 0xffff0000, v93
	v_lshlrev_b32_e32 v140, 16, v94
	v_and_b32_e32 v141, 0xffff0000, v94
	v_lshlrev_b32_e32 v142, 16, v95
	v_and_b32_e32 v143, 0xffff0000, v95
	v_pk_add_f32 v[12:13], v[12:13], v[136:137]
	v_pk_add_f32 v[14:15], v[14:15], v[138:139]
	v_pk_add_f32 v[16:17], v[16:17], v[140:141]
	v_pk_add_f32 v[18:19], v[18:19], v[142:143]
	v_lshlrev_b32_e32 v136, 16, v96
	v_and_b32_e32 v137, 0xffff0000, v96
	v_lshlrev_b32_e32 v138, 16, v97
	v_and_b32_e32 v139, 0xffff0000, v97
	v_lshlrev_b32_e32 v140, 16, v98
	v_and_b32_e32 v141, 0xffff0000, v98
	v_lshlrev_b32_e32 v142, 16, v99
	v_and_b32_e32 v143, 0xffff0000, v99
	v_pk_add_f32 v[12:13], v[12:13], v[136:137]
	v_pk_add_f32 v[14:15], v[14:15], v[138:139]
	v_pk_add_f32 v[16:17], v[16:17], v[140:141]
	v_pk_add_f32 v[18:19], v[18:19], v[142:143]
	v_lshlrev_b32_e32 v136, 16, v100
	v_and_b32_e32 v137, 0xffff0000, v100
	v_lshlrev_b32_e32 v138, 16, v101
	v_and_b32_e32 v139, 0xffff0000, v101
	v_lshlrev_b32_e32 v140, 16, v102
	v_and_b32_e32 v141, 0xffff0000, v102
	v_lshlrev_b32_e32 v142, 16, v103
	v_and_b32_e32 v143, 0xffff0000, v103
	v_pk_add_f32 v[12:13], v[12:13], v[136:137]
	v_pk_add_f32 v[14:15], v[14:15], v[138:139]
	v_pk_add_f32 v[16:17], v[16:17], v[140:141]
	v_pk_add_f32 v[18:19], v[18:19], v[142:143]
.Lmy_pool_main:
	s_mov_b32 s3, 0
; __device__ __forceinline__ float silu_f(float x) { return x * __builtin_amdgcn_rcpf(1.0f + __expf(-x)); }
; __device__ __forceinline__ void pool_phase(const u16* __restrict__ UG, u16* __restrict__ PL, const float* __restrict__ scale, const int wave) {
;     ...
;     _Pragma("unroll 16") for (int t = 0; t < 64; ++t) {
;       const int s = s0 + t;
;       uint4 u = *reinterpret_cast<const uint4*>(UG + (long)(r0 + t) * 4096 + c0);
;       float cur[8];
;       cur[0] = __uint_as_float(u.x << 16); cur[1] = __uint_as_float(u.x & 0xffff0000u);
;       cur[2] = __uint_as_float(u.y << 16); cur[3] = __uint_as_float(u.y & 0xffff0000u);
;       cur[4] = __uint_as_float(u.z << 16); cur[5] = __uint_as_float(u.z & 0xffff0000u);
;       cur[6] = __uint_as_float(u.w << 16); cur[7] = __uint_as_float(u.w & 0xffff0000u);
;       for (int e = 0; e < 8; ++e) sum[e] += cur[e];
;       if (s - w >= 0) {
;         uint4 o = *reinterpret_cast<const uint4*>(UG + (long)(r0 + t - w) * 4096 + c0);
;         sum[0] -= __uint_as_float(o.x << 16); sum[1] -= __uint_as_float(o.x & 0xffff0000u);
;         sum[2] -= __uint_as_float(o.y << 16); sum[3] -= __uint_as_float(o.y & 0xffff0000u);
;         sum[4] -= __uint_as_float(o.z << 16); sum[5] -= __uint_as_float(o.z & 0xffff0000u);
;         sum[6] -= __uint_as_float(o.w << 16); sum[7] -= __uint_as_float(o.w & 0xffff0000u);
;       }
;       const float inv = __builtin_amdgcn_rcpf((float)min(s + 1, w));
;       const uint4 gq = *reinterpret_cast<const uint4*>(UG + (long)(r0 + t) * 4096 + 2048 + c0);
;       float gt[8];
;       gt[0] = __uint_as_float(gq.x << 16); gt[1] = __uint_as_float(gq.x & 0xffff0000u);
;       gt[2] = __uint_as_float(gq.y << 16); gt[3] = __uint_as_float(gq.y & 0xffff0000u);
;       gt[4] = __uint_as_float(gq.z << 16); gt[5] = __uint_as_float(gq.z & 0xffff0000u);
;       gt[6] = __uint_as_float(gq.w << 16); gt[7] = __uint_as_float(gq.w & 0xffff0000u);
;       float hv[8];
;       _Pragma("unroll") for (int e = 0; e < 8; ++e) hv[e] = sc[e] * (sum[e] * inv - cur[e]) * silu_f(gt[e]);
;       uint4 pk;
;       pk.x = pack2(hv[0], hv[1]); pk.y = pack2(hv[2], hv[3]); pk.z = pack2(hv[4], hv[5]); pk.w = pack2(hv[6], hv[7]);
;       *reinterpret_cast<uint4*>(PL + (long)(r0 + t) * DM + c0) = pk;
;     }
.Lmy_pool_batch:
	global_load_dwordx4 v[40:43], v20, s[12:13]
	global_load_dwordx4 v[72:75], v20, s[14:15]
	global_load_dwordx4 v[104:107], v20, s[16:17]
	global_load_dwordx4 v[44:47], v21, s[12:13]
	global_load_dwordx4 v[76:79], v21, s[14:15]
	global_load_dwordx4 v[108:111], v21, s[16:17]
	global_load_dwordx4 v[48:51], v22, s[12:13]
	global_load_dwordx4 v[80:83], v22, s[14:15]
	global_load_dwordx4 v[112:115], v22, s[16:17]
	global_load_dwordx4 v[52:55], v23, s[12:13]
	global_load_dwordx4 v[84:87], v23, s[14:15]
	global_load_dwordx4 v[116:119], v23, s[16:17]
	global_load_dwordx4 v[56:59], v24, s[12:13]
	global_load_dwordx4 v[88:91], v24, s[14:15]
	global_load_dwordx4 v[120:123], v24, s[16:17]
	global_load_dwordx4 v[60:63], v25, s[12:13]
	global_load_dwordx4 v[92:95], v25, s[14:15]
	global_load_dwordx4 v[124:127], v25, s[16:17]
	global_load_dwordx4 v[64:67], v26, s[12:13]
	global_load_dwordx4 v[96:99], v26, s[14:15]
	global_load_dwordx4 v[128:131], v26, s[16:17]
	global_load_dwordx4 v[68:71], v27, s[12:13]
	global_load_dwordx4 v[100:103], v27, s[14:15]
	global_load_dwordx4 v[132:135], v27, s[16:17]
	s_add_i32 s10, s9, s3
	s_add_i32 s1, s10, 1
	s_min_i32 s11, s1, s7
	v_cvt_f32_i32_e32 v168, s11
	s_waitcnt vmcnt(21)
	v_lshlrev_b32_e32 v136, 16, v40
	v_and_b32_e32 v137, 0xffff0000, v40
	v_lshlrev_b32_e32 v138, 16, v41
	v_and_b32_e32 v139, 0xffff0000, v41
	v_lshlrev_b32_e32 v140, 16, v42
	v_and_b32_e32 v141, 0xffff0000, v42
	v_lshlrev_b32_e32 v142, 16, v43
	v_and_b32_e32 v143, 0xffff0000, v43
	v_rcp_iflag_f32_e32 v168, v168
	v_pk_add_f32 v[12:13], v[12:13], v[136:137]
	v_pk_add_f32 v[14:15], v[14:15], v[138:139]
	v_pk_add_f32 v[16:17], v[16:17], v[140:141]
	v_pk_add_f32 v[18:19], v[18:19], v[142:143]
	s_cmp_gt_i32 s1, s7
	s_cbranch_scc0 .Lmy_pool_nosub_0
	v_lshlrev_b32_e32 v144, 16, v104
	v_and_b32_e32 v145, 0xffff0000, v104
	v_lshlrev_b32_e32 v146, 16, v105
	v_and_b32_e32 v147, 0xffff0000, v105
	v_lshlrev_b32_e32 v148, 16, v106
	v_and_b32_e32 v149, 0xffff0000, v106
	v_lshlrev_b32_e32 v150, 16, v107
	v_and_b32_e32 v151, 0xffff0000, v107
	v_sub_f32_e32 v12, v12, v144
	v_sub_f32_e32 v13, v13, v145
	v_sub_f32_e32 v14, v14, v146
	v_sub_f32_e32 v15, v15, v147
	v_sub_f32_e32 v16, v16, v148
	v_sub_f32_e32 v17, v17, v149
	v_sub_f32_e32 v18, v18, v150
	v_sub_f32_e32 v19, v19, v151
.Lmy_pool_nosub_0:
	v_lshlrev_b32_e32 v144, 16, v72
	v_and_b32_e32 v145, 0xffff0000, v72
	v_lshlrev_b32_e32 v146, 16, v73
	v_and_b32_e32 v147, 0xffff0000, v73
	v_lshlrev_b32_e32 v148, 16, v74
	v_and_b32_e32 v149, 0xffff0000, v74
	v_lshlrev_b32_e32 v150, 16, v75
	v_and_b32_e32 v151, 0xffff0000, v75
	v_fma_f32 v152, v168, v12, -v136
	v_fma_f32 v153, v168, v13, -v137
	v_fma_f32 v154, v168, v14, -v138
	v_fma_f32 v155, v168, v15, -v139
	v_fma_f32 v156, v168, v16, -v140
	v_fma_f32 v157, v168, v17, -v141
	v_fma_f32 v158, v168, v18, -v142
	v_fma_f32 v159, v168, v19, -v143
	v_mul_f32_e32 v160, 0xbfb8aa3b, v144
	v_mul_f32_e32 v161, 0xbfb8aa3b, v145
	v_mul_f32_e32 v162, 0xbfb8aa3b, v146
	v_mul_f32_e32 v163, 0xbfb8aa3b, v147
	v_mul_f32_e32 v164, 0xbfb8aa3b, v148
	v_mul_f32_e32 v165, 0xbfb8aa3b, v149
	v_mul_f32_e32 v166, 0xbfb8aa3b, v150
	v_mul_f32_e32 v167, 0xbfb8aa3b, v151
	v_exp_f32_e32 v160, v160
	v_exp_f32_e32 v161, v161
	v_exp_f32_e32 v162, v162
	v_exp_f32_e32 v163, v163
	v_exp_f32_e32 v164, v164
	v_exp_f32_e32 v165, v165
	v_exp_f32_e32 v166, v166
	v_exp_f32_e32 v167, v167
	v_mul_f32_e32 v152, v4, v152
	v_mul_f32_e32 v153, v5, v153
	v_mul_f32_e32 v154, v6, v154
	v_mul_f32_e32 v155, v7, v155
	v_mul_f32_e32 v156, v8, v156
	v_mul_f32_e32 v157, v9, v157
	v_mul_f32_e32 v158, v10, v158
	v_mul_f32_e32 v159, v11, v159
	v_add_f32_e32 v160, 1.0, v160
	v_add_f32_e32 v161, 1.0, v161
	v_add_f32_e32 v162, 1.0, v162
	v_add_f32_e32 v163, 1.0, v163
	v_add_f32_e32 v164, 1.0, v164
	v_add_f32_e32 v165, 1.0, v165
	v_add_f32_e32 v166, 1.0, v166
	v_add_f32_e32 v167, 1.0, v167
	v_rcp_f32_e32 v160, v160
	v_rcp_f32_e32 v161, v161
	v_rcp_f32_e32 v162, v162
	v_rcp_f32_e32 v163, v163
	v_rcp_f32_e32 v164, v164
	v_rcp_f32_e32 v165, v165
	v_rcp_f32_e32 v166, v166
	v_rcp_f32_e32 v167, v167
	s_nop 0
	v_mul_f32_e32 v160, v160, v144
	v_mul_f32_e32 v161, v161, v145
	v_mul_f32_e32 v162, v162, v146
	v_mul_f32_e32 v163, v163, v147
	v_mul_f32_e32 v164, v164, v148
	v_mul_f32_e32 v165, v165, v149
	v_mul_f32_e32 v166, v166, v150
	v_mul_f32_e32 v167, v167, v151
	v_mul_f32_e32 v152, v152, v160
	v_mul_f32_e32 v153, v153, v161
	v_mul_f32_e32 v154, v154, v162
	v_mul_f32_e32 v155, v155, v163
	v_mul_f32_e32 v156, v156, v164
	v_mul_f32_e32 v157, v157, v165
	v_mul_f32_e32 v158, v158, v166
	v_mul_f32_e32 v159, v159, v167
	v_cvt_pk_bf16_f32 v172, v152, v153
	v_cvt_pk_bf16_f32 v173, v154, v155
	v_cvt_pk_bf16_f32 v174, v156, v157
	v_cvt_pk_bf16_f32 v175, v158, v159
	s_nop 0
	global_store_dwordx4 v28, v[172:175], s[18:19]
	s_add_i32 s1, s10, 2
	s_min_i32 s11, s1, s7
	v_cvt_f32_i32_e32 v168, s11
	s_waitcnt vmcnt(19)
	v_lshlrev_b32_e32 v136, 16, v44
	v_and_b32_e32 v137, 0xffff0000, v44
	v_lshlrev_b32_e32 v138, 16, v45
	v_and_b32_e32 v139, 0xffff0000, v45
	v_lshlrev_b32_e32 v140, 16, v46
	v_and_b32_e32 v141, 0xffff0000, v46
	v_lshlrev_b32_e32 v142, 16, v47
	v_and_b32_e32 v143, 0xffff0000, v47
	v_rcp_iflag_f32_e32 v168, v168
	v_pk_add_f32 v[12:13], v[12:13], v[136:137]
	v_pk_add_f32 v[14:15], v[14:15], v[138:139]
	v_pk_add_f32 v[16:17], v[16:17], v[140:141]
	v_pk_add_f32 v[18:19], v[18:19], v[142:143]
	s_cmp_gt_i32 s1, s7
	s_cbranch_scc0 .Lmy_pool_nosub_1
	v_lshlrev_b32_e32 v144, 16, v108
	v_and_b32_e32 v145, 0xffff0000, v108
	v_lshlrev_b32_e32 v146, 16, v109
	v_and_b32_e32 v147, 0xffff0000, v109
	v_lshlrev_b32_e32 v148, 16, v110
	v_and_b32_e32 v149, 0xffff0000, v110
	v_lshlrev_b32_e32 v150, 16, v111
	v_and_b32_e32 v151, 0xffff0000, v111
	v_sub_f32_e32 v12, v12, v144
	v_sub_f32_e32 v13, v13, v145
	v_sub_f32_e32 v14, v14, v146
	v_sub_f32_e32 v15, v15, v147
	v_sub_f32_e32 v16, v16, v148
	v_sub_f32_e32 v17, v17, v149
	v_sub_f32_e32 v18, v18, v150
	v_sub_f32_e32 v19, v19, v151
; __device__ __forceinline__ float silu_f(float x) { return x * __builtin_amdgcn_rcpf(1.0f + __expf(-x)); }
; __device__ __forceinline__ void pool_phase(const u16* __restrict__ UG, u16* __restrict__ PL, const float* __restrict__ scale, const int wave) {
;     ...
;     _Pragma("unroll 16") for (int t = 0; t < 64; ++t) {
;       const int s = s0 + t;
;       uint4 u = *reinterpret_cast<const uint4*>(UG + (long)(r0 + t) * 4096 + c0);
;       float cur[8];
;       cur[0] = __uint_as_float(u.x << 16); cur[1] = __uint_as_float(u.x & 0xffff0000u);
;       cur[2] = __uint_as_float(u.y << 16); cur[3] = __uint_as_float(u.y & 0xffff0000u);
;       cur[4] = __uint_as_float(u.z << 16); cur[5] = __uint_as_float(u.z & 0xffff0000u);
;       cur[6] = __uint_as_float(u.w << 16); cur[7] = __uint_as_float(u.w & 0xffff0000u);
;       for (int e = 0; e < 8; ++e) sum[e] += cur[e];
;       if (s - w >= 0) {
;         uint4 o = *reinterpret_cast<const uint4*>(UG + (long)(r0 + t - w) * 4096 + c0);
;         sum[0] -= __uint_as_float(o.x << 16); sum[1] -= __uint_as_float(o.x & 0xffff0000u);
;         sum[2] -= __uint_as_float(o.y << 16); sum[3] -= __uint_as_float(o.y & 0xffff0000u);
;         sum[4] -= __uint_as_float(o.z << 16); sum[5] -= __uint_as_float(o.z & 0xffff0000u);
;         sum[6] -= __uint_as_float(o.w << 16); sum[7] -= __uint_as_float(o.w & 0xffff0000u);
;       }
;       const float inv = __builtin_amdgcn_rcpf((float)min(s + 1, w));
;       const uint4 gq = *reinterpret_cast<const uint4*>(UG + (long)(r0 + t) * 4096 + 2048 + c0);
;       float gt[8];
;       gt[0] = __uint_as_float(gq.x << 16); gt[1] = __uint_as_float(gq.x & 0xffff0000u);
;       gt[2] = __uint_as_float(gq.y << 16); gt[3] = __uint_as_float(gq.y & 0xffff0000u);
;       gt[4] = __uint_as_float(gq.z << 16); gt[5] = __uint_as_float(gq.z & 0xffff0000u);
;       gt[6] = __uint_as_float(gq.w << 16); gt[7] = __uint_as_float(gq.w & 0xffff0000u);
;       float hv[8];
;       _Pragma("unroll") for (int e = 0; e < 8; ++e) hv[e] = sc[e] * (sum[e] * inv - cur[e]) * silu_f(gt[e]);
;       uint4 pk;
;       pk.x = pack2(hv[0], hv[1]); pk.y = pack2(hv[2], hv[3]); pk.z = pack2(hv[4], hv[5]); pk.w = pack2(hv[6], hv[7]);
;       *reinterpret_cast<uint4*>(PL + (long)(r0 + t) * DM + c0) = pk;
;     }
.Lmy_pool_nosub_1:
	v_lshlrev_b32_e32 v144, 16, v76
	v_and_b32_e32 v145, 0xffff0000, v76
	v_lshlrev_b32_e32 v146, 16, v77
	v_and_b32_e32 v147, 0xffff0000, v77
	v_lshlrev_b32_e32 v148, 16, v78
	v_and_b32_e32 v149, 0xffff0000, v78
	v_lshlrev_b32_e32 v150, 16, v79
	v_and_b32_e32 v151, 0xffff0000, v79
	v_fma_f32 v152, v168, v12, -v136
	v_fma_f32 v153, v168, v13, -v137
	v_fma_f32 v154, v168, v14, -v138
	v_fma_f32 v155, v168, v15, -v139
	v_fma_f32 v156, v168, v16, -v140
	v_fma_f32 v157, v168, v17, -v141
	v_fma_f32 v158, v168, v18, -v142
	v_fma_f32 v159, v168, v19, -v143
	v_mul_f32_e32 v160, 0xbfb8aa3b, v144
	v_mul_f32_e32 v161, 0xbfb8aa3b, v145
	v_mul_f32_e32 v162, 0xbfb8aa3b, v146
	v_mul_f32_e32 v163, 0xbfb8aa3b, v147
	v_mul_f32_e32 v164, 0xbfb8aa3b, v148
	v_mul_f32_e32 v165, 0xbfb8aa3b, v149
	v_mul_f32_e32 v166, 0xbfb8aa3b, v150
	v_mul_f32_e32 v167, 0xbfb8aa3b, v151
	v_exp_f32_e32 v160, v160
	v_exp_f32_e32 v161, v161
	v_exp_f32_e32 v162, v162
	v_exp_f32_e32 v163, v163
	v_exp_f32_e32 v164, v164
	v_exp_f32_e32 v165, v165
	v_exp_f32_e32 v166, v166
	v_exp_f32_e32 v167, v167
	v_mul_f32_e32 v152, v4, v152
	v_mul_f32_e32 v153, v5, v153
	v_mul_f32_e32 v154, v6, v154
	v_mul_f32_e32 v155, v7, v155
	v_mul_f32_e32 v156, v8, v156
	v_mul_f32_e32 v157, v9, v157
	v_mul_f32_e32 v158, v10, v158
	v_mul_f32_e32 v159, v11, v159
	v_add_f32_e32 v160, 1.0, v160
	v_add_f32_e32 v161, 1.0, v161
	v_add_f32_e32 v162, 1.0, v162
	v_add_f32_e32 v163, 1.0, v163
	v_add_f32_e32 v164, 1.0, v164
	v_add_f32_e32 v165, 1.0, v165
	v_add_f32_e32 v166, 1.0, v166
	v_add_f32_e32 v167, 1.0, v167
	v_rcp_f32_e32 v160, v160
	v_rcp_f32_e32 v161, v161
	v_rcp_f32_e32 v162, v162
	v_rcp_f32_e32 v163, v163
	v_rcp_f32_e32 v164, v164
	v_rcp_f32_e32 v165, v165
	v_rcp_f32_e32 v166, v166
	v_rcp_f32_e32 v167, v167
	s_nop 0
	v_mul_f32_e32 v160, v160, v144
	v_mul_f32_e32 v161, v161, v145
	v_mul_f32_e32 v162, v162, v146
	v_mul_f32_e32 v163, v163, v147
	v_mul_f32_e32 v164, v164, v148
	v_mul_f32_e32 v165, v165, v149
	v_mul_f32_e32 v166, v166, v150
	v_mul_f32_e32 v167, v167, v151
	v_mul_f32_e32 v152, v152, v160
	v_mul_f32_e32 v153, v153, v161
	v_mul_f32_e32 v154, v154, v162
	v_mul_f32_e32 v155, v155, v163
	v_mul_f32_e32 v156, v156, v164
	v_mul_f32_e32 v157, v157, v165
	v_mul_f32_e32 v158, v158, v166
	v_mul_f32_e32 v159, v159, v167
	v_cvt_pk_bf16_f32 v172, v152, v153
	v_cvt_pk_bf16_f32 v173, v154, v155
	v_cvt_pk_bf16_f32 v174, v156, v157
	v_cvt_pk_bf16_f32 v175, v158, v159
	s_nop 0
	global_store_dwordx4 v29, v[172:175], s[18:19]
	s_add_i32 s1, s10, 3
	s_min_i32 s11, s1, s7
	v_cvt_f32_i32_e32 v168, s11
	s_waitcnt vmcnt(17)
	v_lshlrev_b32_e32 v136, 16, v48
	v_and_b32_e32 v137, 0xffff0000, v48
	v_lshlrev_b32_e32 v138, 16, v49
	v_and_b32_e32 v139, 0xffff0000, v49
	v_lshlrev_b32_e32 v140, 16, v50
	v_and_b32_e32 v141, 0xffff0000, v50
	v_lshlrev_b32_e32 v142, 16, v51
	v_and_b32_e32 v143, 0xffff0000, v51
	v_rcp_iflag_f32_e32 v168, v168
	v_pk_add_f32 v[12:13], v[12:13], v[136:137]
	v_pk_add_f32 v[14:15], v[14:15], v[138:139]
	v_pk_add_f32 v[16:17], v[16:17], v[140:141]
	v_pk_add_f32 v[18:19], v[18:19], v[142:143]
	s_cmp_gt_i32 s1, s7
	s_cbranch_scc0 .Lmy_pool_nosub_2
	v_lshlrev_b32_e32 v144, 16, v112
	v_and_b32_e32 v145, 0xffff0000, v112
	v_lshlrev_b32_e32 v146, 16, v113
	v_and_b32_e32 v147, 0xffff0000, v113
	v_lshlrev_b32_e32 v148, 16, v114
	v_and_b32_e32 v149, 0xffff0000, v114
	v_lshlrev_b32_e32 v150, 16, v115
	v_and_b32_e32 v151, 0xffff0000, v115
	v_sub_f32_e32 v12, v12, v144
	v_sub_f32_e32 v13, v13, v145
	v_sub_f32_e32 v14, v14, v146
	v_sub_f32_e32 v15, v15, v147
	v_sub_f32_e32 v16, v16, v148
	v_sub_f32_e32 v17, v17, v149
	v_sub_f32_e32 v18, v18, v150
	v_sub_f32_e32 v19, v19, v151
.Lmy_pool_nosub_2:
	v_lshlrev_b32_e32 v144, 16, v80
	v_and_b32_e32 v145, 0xffff0000, v80
	v_lshlrev_b32_e32 v146, 16, v81
	v_and_b32_e32 v147, 0xffff0000, v81
	v_lshlrev_b32_e32 v148, 16, v82
	v_and_b32_e32 v149, 0xffff0000, v82
	v_lshlrev_b32_e32 v150, 16, v83
	v_and_b32_e32 v151, 0xffff0000, v83
	v_fma_f32 v152, v168, v12, -v136
	v_fma_f32 v153, v168, v13, -v137
	v_fma_f32 v154, v168, v14, -v138
	v_fma_f32 v155, v168, v15, -v139
	v_fma_f32 v156, v168, v16, -v140
	v_fma_f32 v157, v168, v17, -v141
	v_fma_f32 v158, v168, v18, -v142
	v_fma_f32 v159, v168, v19, -v143
	v_mul_f32_e32 v160, 0xbfb8aa3b, v144
	v_mul_f32_e32 v161, 0xbfb8aa3b, v145
	v_mul_f32_e32 v162, 0xbfb8aa3b, v146
	v_mul_f32_e32 v163, 0xbfb8aa3b, v147
	v_mul_f32_e32 v164, 0xbfb8aa3b, v148
	v_mul_f32_e32 v165, 0xbfb8aa3b, v149
	v_mul_f32_e32 v166, 0xbfb8aa3b, v150
	v_mul_f32_e32 v167, 0xbfb8aa3b, v151
	v_exp_f32_e32 v160, v160
	v_exp_f32_e32 v161, v161
	v_exp_f32_e32 v162, v162
	v_exp_f32_e32 v163, v163
	v_exp_f32_e32 v164, v164
	v_exp_f32_e32 v165, v165
	v_exp_f32_e32 v166, v166
	v_exp_f32_e32 v167, v167
	v_mul_f32_e32 v152, v4, v152
	v_mul_f32_e32 v153, v5, v153
	v_mul_f32_e32 v154, v6, v154
	v_mul_f32_e32 v155, v7, v155
	v_mul_f32_e32 v156, v8, v156
	v_mul_f32_e32 v157, v9, v157
	v_mul_f32_e32 v158, v10, v158
	v_mul_f32_e32 v159, v11, v159
	v_add_f32_e32 v160, 1.0, v160
	v_add_f32_e32 v161, 1.0, v161
	v_add_f32_e32 v162, 1.0, v162
	v_add_f32_e32 v163, 1.0, v163
	v_add_f32_e32 v164, 1.0, v164
	v_add_f32_e32 v165, 1.0, v165
	v_add_f32_e32 v166, 1.0, v166
	v_add_f32_e32 v167, 1.0, v167
	v_rcp_f32_e32 v160, v160
	v_rcp_f32_e32 v161, v161
	v_rcp_f32_e32 v162, v162
	v_rcp_f32_e32 v163, v163
	v_rcp_f32_e32 v164, v164
	v_rcp_f32_e32 v165, v165
	v_rcp_f32_e32 v166, v166
	v_rcp_f32_e32 v167, v167
	s_nop 0
	v_mul_f32_e32 v160, v160, v144
	v_mul_f32_e32 v161, v161, v145
	v_mul_f32_e32 v162, v162, v146
	v_mul_f32_e32 v163, v163, v147
	v_mul_f32_e32 v164, v164, v148
	v_mul_f32_e32 v165, v165, v149
	v_mul_f32_e32 v166, v166, v150
	v_mul_f32_e32 v167, v167, v151
	v_mul_f32_e32 v152, v152, v160
	v_mul_f32_e32 v153, v153, v161
	v_mul_f32_e32 v154, v154, v162
	v_mul_f32_e32 v155, v155, v163
	v_mul_f32_e32 v156, v156, v164
	v_mul_f32_e32 v157, v157, v165
	v_mul_f32_e32 v158, v158, v166
	v_mul_f32_e32 v159, v159, v167
	v_cvt_pk_bf16_f32 v172, v152, v153
	v_cvt_pk_bf16_f32 v173, v154, v155
	v_cvt_pk_bf16_f32 v174, v156, v157
	v_cvt_pk_bf16_f32 v175, v158, v159
	s_nop 0
	global_store_dwordx4 v30, v[172:175], s[18:19]
	s_add_i32 s1, s10, 4
	s_min_i32 s11, s1, s7
	v_cvt_f32_i32_e32 v168, s11
	s_waitcnt vmcnt(15)
	v_lshlrev_b32_e32 v136, 16, v52
	v_and_b32_e32 v137, 0xffff0000, v52
	v_lshlrev_b32_e32 v138, 16, v53
	v_and_b32_e32 v139, 0xffff0000, v53
	v_lshlrev_b32_e32 v140, 16, v54
	v_and_b32_e32 v141, 0xffff0000, v54
	v_lshlrev_b32_e32 v142, 16, v55
	v_and_b32_e32 v143, 0xffff0000, v55
	v_rcp_iflag_f32_e32 v168, v168
	v_pk_add_f32 v[12:13], v[12:13], v[136:137]
	v_pk_add_f32 v[14:15], v[14:15], v[138:139]
	v_pk_add_f32 v[16:17], v[16:17], v[140:141]
	v_pk_add_f32 v[18:19], v[18:19], v[142:143]
	s_cmp_gt_i32 s1, s7
	s_cbranch_scc0 .Lmy_pool_nosub_3
; __device__ __forceinline__ float silu_f(float x) { return x * __builtin_amdgcn_rcpf(1.0f + __expf(-x)); }
; __device__ __forceinline__ void pool_phase(const u16* __restrict__ UG, u16* __restrict__ PL, const float* __restrict__ scale, const int wave) {
;     ...
;     _Pragma("unroll 16") for (int t = 0; t < 64; ++t) {
;       const int s = s0 + t;
;       uint4 u = *reinterpret_cast<const uint4*>(UG + (long)(r0 + t) * 4096 + c0);
;       float cur[8];
;       cur[0] = __uint_as_float(u.x << 16); cur[1] = __uint_as_float(u.x & 0xffff0000u);
;       cur[2] = __uint_as_float(u.y << 16); cur[3] = __uint_as_float(u.y & 0xffff0000u);
;       cur[4] = __uint_as_float(u.z << 16); cur[5] = __uint_as_float(u.z & 0xffff0000u);
;       cur[6] = __uint_as_float(u.w << 16); cur[7] = __uint_as_float(u.w & 0xffff0000u);
;       for (int e = 0; e < 8; ++e) sum[e] += cur[e];
;       if (s - w >= 0) {
;         uint4 o = *reinterpret_cast<const uint4*>(UG + (long)(r0 + t - w) * 4096 + c0);
;         sum[0] -= __uint_as_float(o.x << 16); sum[1] -= __uint_as_float(o.x & 0xffff0000u);
;         sum[2] -= __uint_as_float(o.y << 16); sum[3] -= __uint_as_float(o.y & 0xffff0000u);
;         sum[4] -= __uint_as_float(o.z << 16); sum[5] -= __uint_as_float(o.z & 0xffff0000u);
;         sum[6] -= __uint_as_float(o.w << 16); sum[7] -= __uint_as_float(o.w & 0xffff0000u);
;       }
;       const float inv = __builtin_amdgcn_rcpf((float)min(s + 1, w));
;       const uint4 gq = *reinterpret_cast<const uint4*>(UG + (long)(r0 + t) * 4096 + 2048 + c0);
;       float gt[8];
;       gt[0] = __uint_as_float(gq.x << 16); gt[1] = __uint_as_float(gq.x & 0xffff0000u);
;       gt[2] = __uint_as_float(gq.y << 16); gt[3] = __uint_as_float(gq.y & 0xffff0000u);
;       gt[4] = __uint_as_float(gq.z << 16); gt[5] = __uint_as_float(gq.z & 0xffff0000u);
;       gt[6] = __uint_as_float(gq.w << 16); gt[7] = __uint_as_float(gq.w & 0xffff0000u);
;       float hv[8];
;       _Pragma("unroll") for (int e = 0; e < 8; ++e) hv[e] = sc[e] * (sum[e] * inv - cur[e]) * silu_f(gt[e]);
;       uint4 pk;
;       pk.x = pack2(hv[0], hv[1]); pk.y = pack2(hv[2], hv[3]); pk.z = pack2(hv[4], hv[5]); pk.w = pack2(hv[6], hv[7]);
;       *reinterpret_cast<uint4*>(PL + (long)(r0 + t) * DM + c0) = pk;
;     }
	v_lshlrev_b32_e32 v144, 16, v116
	v_and_b32_e32 v145, 0xffff0000, v116
	v_lshlrev_b32_e32 v146, 16, v117
	v_and_b32_e32 v147, 0xffff0000, v117
	v_lshlrev_b32_e32 v148, 16, v118
	v_and_b32_e32 v149, 0xffff0000, v118
	v_lshlrev_b32_e32 v150, 16, v119
	v_and_b32_e32 v151, 0xffff0000, v119
	v_sub_f32_e32 v12, v12, v144
	v_sub_f32_e32 v13, v13, v145
	v_sub_f32_e32 v14, v14, v146
	v_sub_f32_e32 v15, v15, v147
	v_sub_f32_e32 v16, v16, v148
	v_sub_f32_e32 v17, v17, v149
	v_sub_f32_e32 v18, v18, v150
	v_sub_f32_e32 v19, v19, v151
.Lmy_pool_nosub_3:
	v_lshlrev_b32_e32 v144, 16, v84
	v_and_b32_e32 v145, 0xffff0000, v84
	v_lshlrev_b32_e32 v146, 16, v85
	v_and_b32_e32 v147, 0xffff0000, v85
	v_lshlrev_b32_e32 v148, 16, v86
	v_and_b32_e32 v149, 0xffff0000, v86
	v_lshlrev_b32_e32 v150, 16, v87
	v_and_b32_e32 v151, 0xffff0000, v87
	v_fma_f32 v152, v168, v12, -v136
	v_fma_f32 v153, v168, v13, -v137
	v_fma_f32 v154, v168, v14, -v138
	v_fma_f32 v155, v168, v15, -v139
	v_fma_f32 v156, v168, v16, -v140
	v_fma_f32 v157, v168, v17, -v141
	v_fma_f32 v158, v168, v18, -v142
	v_fma_f32 v159, v168, v19, -v143
	v_mul_f32_e32 v160, 0xbfb8aa3b, v144
	v_mul_f32_e32 v161, 0xbfb8aa3b, v145
	v_mul_f32_e32 v162, 0xbfb8aa3b, v146
	v_mul_f32_e32 v163, 0xbfb8aa3b, v147
	v_mul_f32_e32 v164, 0xbfb8aa3b, v148
	v_mul_f32_e32 v165, 0xbfb8aa3b, v149
	v_mul_f32_e32 v166, 0xbfb8aa3b, v150
	v_mul_f32_e32 v167, 0xbfb8aa3b, v151
	v_exp_f32_e32 v160, v160
	v_exp_f32_e32 v161, v161
	v_exp_f32_e32 v162, v162
	v_exp_f32_e32 v163, v163
	v_exp_f32_e32 v164, v164
	v_exp_f32_e32 v165, v165
	v_exp_f32_e32 v166, v166
	v_exp_f32_e32 v167, v167
	v_mul_f32_e32 v152, v4, v152
	v_mul_f32_e32 v153, v5, v153
	v_mul_f32_e32 v154, v6, v154
	v_mul_f32_e32 v155, v7, v155
	v_mul_f32_e32 v156, v8, v156
	v_mul_f32_e32 v157, v9, v157
	v_mul_f32_e32 v158, v10, v158
	v_mul_f32_e32 v159, v11, v159
	v_add_f32_e32 v160, 1.0, v160
	v_add_f32_e32 v161, 1.0, v161
	v_add_f32_e32 v162, 1.0, v162
	v_add_f32_e32 v163, 1.0, v163
	v_add_f32_e32 v164, 1.0, v164
	v_add_f32_e32 v165, 1.0, v165
	v_add_f32_e32 v166, 1.0, v166
	v_add_f32_e32 v167, 1.0, v167
	v_rcp_f32_e32 v160, v160
	v_rcp_f32_e32 v161, v161
	v_rcp_f32_e32 v162, v162
	v_rcp_f32_e32 v163, v163
	v_rcp_f32_e32 v164, v164
	v_rcp_f32_e32 v165, v165
	v_rcp_f32_e32 v166, v166
	v_rcp_f32_e32 v167, v167
	s_nop 0
	v_mul_f32_e32 v160, v160, v144
	v_mul_f32_e32 v161, v161, v145
	v_mul_f32_e32 v162, v162, v146
	v_mul_f32_e32 v163, v163, v147
	v_mul_f32_e32 v164, v164, v148
	v_mul_f32_e32 v165, v165, v149
	v_mul_f32_e32 v166, v166, v150
	v_mul_f32_e32 v167, v167, v151
	v_mul_f32_e32 v152, v152, v160
	v_mul_f32_e32 v153, v153, v161
	v_mul_f32_e32 v154, v154, v162
	v_mul_f32_e32 v155, v155, v163
	v_mul_f32_e32 v156, v156, v164
	v_mul_f32_e32 v157, v157, v165
	v_mul_f32_e32 v158, v158, v166
	v_mul_f32_e32 v159, v159, v167
	v_cvt_pk_bf16_f32 v172, v152, v153
	v_cvt_pk_bf16_f32 v173, v154, v155
	v_cvt_pk_bf16_f32 v174, v156, v157
	v_cvt_pk_bf16_f32 v175, v158, v159
	s_nop 0
	global_store_dwordx4 v31, v[172:175], s[18:19]
	s_add_i32 s1, s10, 5
	s_min_i32 s11, s1, s7
	v_cvt_f32_i32_e32 v168, s11
	s_waitcnt vmcnt(13)
	v_lshlrev_b32_e32 v136, 16, v56
	v_and_b32_e32 v137, 0xffff0000, v56
	v_lshlrev_b32_e32 v138, 16, v57
	v_and_b32_e32 v139, 0xffff0000, v57
	v_lshlrev_b32_e32 v140, 16, v58
	v_and_b32_e32 v141, 0xffff0000, v58
	v_lshlrev_b32_e32 v142, 16, v59
	v_and_b32_e32 v143, 0xffff0000, v59
	v_rcp_iflag_f32_e32 v168, v168
	v_pk_add_f32 v[12:13], v[12:13], v[136:137]
	v_pk_add_f32 v[14:15], v[14:15], v[138:139]
	v_pk_add_f32 v[16:17], v[16:17], v[140:141]
	v_pk_add_f32 v[18:19], v[18:19], v[142:143]
	s_cmp_gt_i32 s1, s7
	s_cbranch_scc0 .Lmy_pool_nosub_4
	v_lshlrev_b32_e32 v144, 16, v120
	v_and_b32_e32 v145, 0xffff0000, v120
	v_lshlrev_b32_e32 v146, 16, v121
	v_and_b32_e32 v147, 0xffff0000, v121
	v_lshlrev_b32_e32 v148, 16, v122
	v_and_b32_e32 v149, 0xffff0000, v122
	v_lshlrev_b32_e32 v150, 16, v123
	v_and_b32_e32 v151, 0xffff0000, v123
	v_sub_f32_e32 v12, v12, v144
	v_sub_f32_e32 v13, v13, v145
	v_sub_f32_e32 v14, v14, v146
	v_sub_f32_e32 v15, v15, v147
	v_sub_f32_e32 v16, v16, v148
	v_sub_f32_e32 v17, v17, v149
	v_sub_f32_e32 v18, v18, v150
	v_sub_f32_e32 v19, v19, v151
.Lmy_pool_nosub_4:
	v_lshlrev_b32_e32 v144, 16, v88
	v_and_b32_e32 v145, 0xffff0000, v88
	v_lshlrev_b32_e32 v146, 16, v89
	v_and_b32_e32 v147, 0xffff0000, v89
	v_lshlrev_b32_e32 v148, 16, v90
	v_and_b32_e32 v149, 0xffff0000, v90
	v_lshlrev_b32_e32 v150, 16, v91
	v_and_b32_e32 v151, 0xffff0000, v91
	v_fma_f32 v152, v168, v12, -v136
	v_fma_f32 v153, v168, v13, -v137
	v_fma_f32 v154, v168, v14, -v138
	v_fma_f32 v155, v168, v15, -v139
	v_fma_f32 v156, v168, v16, -v140
	v_fma_f32 v157, v168, v17, -v141
	v_fma_f32 v158, v168, v18, -v142
	v_fma_f32 v159, v168, v19, -v143
	v_mul_f32_e32 v160, 0xbfb8aa3b, v144
	v_mul_f32_e32 v161, 0xbfb8aa3b, v145
	v_mul_f32_e32 v162, 0xbfb8aa3b, v146
	v_mul_f32_e32 v163, 0xbfb8aa3b, v147
	v_mul_f32_e32 v164, 0xbfb8aa3b, v148
	v_mul_f32_e32 v165, 0xbfb8aa3b, v149
	v_mul_f32_e32 v166, 0xbfb8aa3b, v150
	v_mul_f32_e32 v167, 0xbfb8aa3b, v151
	v_exp_f32_e32 v160, v160
	v_exp_f32_e32 v161, v161
	v_exp_f32_e32 v162, v162
	v_exp_f32_e32 v163, v163
	v_exp_f32_e32 v164, v164
	v_exp_f32_e32 v165, v165
	v_exp_f32_e32 v166, v166
	v_exp_f32_e32 v167, v167
	v_mul_f32_e32 v152, v4, v152
	v_mul_f32_e32 v153, v5, v153
	v_mul_f32_e32 v154, v6, v154
	v_mul_f32_e32 v155, v7, v155
	v_mul_f32_e32 v156, v8, v156
	v_mul_f32_e32 v157, v9, v157
	v_mul_f32_e32 v158, v10, v158
	v_mul_f32_e32 v159, v11, v159
	v_add_f32_e32 v160, 1.0, v160
	v_add_f32_e32 v161, 1.0, v161
	v_add_f32_e32 v162, 1.0, v162
	v_add_f32_e32 v163, 1.0, v163
	v_add_f32_e32 v164, 1.0, v164
	v_add_f32_e32 v165, 1.0, v165
	v_add_f32_e32 v166, 1.0, v166
	v_add_f32_e32 v167, 1.0, v167
	v_rcp_f32_e32 v160, v160
	v_rcp_f32_e32 v161, v161
	v_rcp_f32_e32 v162, v162
	v_rcp_f32_e32 v163, v163
	v_rcp_f32_e32 v164, v164
	v_rcp_f32_e32 v165, v165
	v_rcp_f32_e32 v166, v166
	v_rcp_f32_e32 v167, v167
	s_nop 0
	v_mul_f32_e32 v160, v160, v144
	v_mul_f32_e32 v161, v161, v145
	v_mul_f32_e32 v162, v162, v146
	v_mul_f32_e32 v163, v163, v147
	v_mul_f32_e32 v164, v164, v148
	v_mul_f32_e32 v165, v165, v149
	v_mul_f32_e32 v166, v166, v150
	v_mul_f32_e32 v167, v167, v151
	v_mul_f32_e32 v152, v152, v160
	v_mul_f32_e32 v153, v153, v161
	v_mul_f32_e32 v154, v154, v162
	v_mul_f32_e32 v155, v155, v163
	v_mul_f32_e32 v156, v156, v164
	v_mul_f32_e32 v157, v157, v165
	v_mul_f32_e32 v158, v158, v166
	v_mul_f32_e32 v159, v159, v167
	v_cvt_pk_bf16_f32 v172, v152, v153
	v_cvt_pk_bf16_f32 v173, v154, v155
	v_cvt_pk_bf16_f32 v174, v156, v157
	v_cvt_pk_bf16_f32 v175, v158, v159
	s_nop 0
	global_store_dwordx4 v32, v[172:175], s[18:19]
	s_add_i32 s1, s10, 6
	s_min_i32 s11, s1, s7
	v_cvt_f32_i32_e32 v168, s11
	s_waitcnt vmcnt(11)
; __device__ __forceinline__ float silu_f(float x) { return x * __builtin_amdgcn_rcpf(1.0f + __expf(-x)); }
; __device__ __forceinline__ void pool_phase(const u16* __restrict__ UG, u16* __restrict__ PL, const float* __restrict__ scale, const int wave) {
;     ...
;     _Pragma("unroll 16") for (int t = 0; t < 64; ++t) {
;       const int s = s0 + t;
;       uint4 u = *reinterpret_cast<const uint4*>(UG + (long)(r0 + t) * 4096 + c0);
;       float cur[8];
;       cur[0] = __uint_as_float(u.x << 16); cur[1] = __uint_as_float(u.x & 0xffff0000u);
;       cur[2] = __uint_as_float(u.y << 16); cur[3] = __uint_as_float(u.y & 0xffff0000u);
;       cur[4] = __uint_as_float(u.z << 16); cur[5] = __uint_as_float(u.z & 0xffff0000u);
;       cur[6] = __uint_as_float(u.w << 16); cur[7] = __uint_as_float(u.w & 0xffff0000u);
;       for (int e = 0; e < 8; ++e) sum[e] += cur[e];
;       if (s - w >= 0) {
;         uint4 o = *reinterpret_cast<const uint4*>(UG + (long)(r0 + t - w) * 4096 + c0);
;         sum[0] -= __uint_as_float(o.x << 16); sum[1] -= __uint_as_float(o.x & 0xffff0000u);
;         sum[2] -= __uint_as_float(o.y << 16); sum[3] -= __uint_as_float(o.y & 0xffff0000u);
;         sum[4] -= __uint_as_float(o.z << 16); sum[5] -= __uint_as_float(o.z & 0xffff0000u);
;         sum[6] -= __uint_as_float(o.w << 16); sum[7] -= __uint_as_float(o.w & 0xffff0000u);
;       }
;       const float inv = __builtin_amdgcn_rcpf((float)min(s + 1, w));
;       const uint4 gq = *reinterpret_cast<const uint4*>(UG + (long)(r0 + t) * 4096 + 2048 + c0);
;       float gt[8];
;       gt[0] = __uint_as_float(gq.x << 16); gt[1] = __uint_as_float(gq.x & 0xffff0000u);
;       gt[2] = __uint_as_float(gq.y << 16); gt[3] = __uint_as_float(gq.y & 0xffff0000u);
;       gt[4] = __uint_as_float(gq.z << 16); gt[5] = __uint_as_float(gq.z & 0xffff0000u);
;       gt[6] = __uint_as_float(gq.w << 16); gt[7] = __uint_as_float(gq.w & 0xffff0000u);
;       float hv[8];
;       _Pragma("unroll") for (int e = 0; e < 8; ++e) hv[e] = sc[e] * (sum[e] * inv - cur[e]) * silu_f(gt[e]);
;       uint4 pk;
;       pk.x = pack2(hv[0], hv[1]); pk.y = pack2(hv[2], hv[3]); pk.z = pack2(hv[4], hv[5]); pk.w = pack2(hv[6], hv[7]);
;       *reinterpret_cast<uint4*>(PL + (long)(r0 + t) * DM + c0) = pk;
;     }
	v_lshlrev_b32_e32 v136, 16, v60
	v_and_b32_e32 v137, 0xffff0000, v60
	v_lshlrev_b32_e32 v138, 16, v61
	v_and_b32_e32 v139, 0xffff0000, v61
	v_lshlrev_b32_e32 v140, 16, v62
	v_and_b32_e32 v141, 0xffff0000, v62
	v_lshlrev_b32_e32 v142, 16, v63
	v_and_b32_e32 v143, 0xffff0000, v63
	v_rcp_iflag_f32_e32 v168, v168
	v_pk_add_f32 v[12:13], v[12:13], v[136:137]
	v_pk_add_f32 v[14:15], v[14:15], v[138:139]
	v_pk_add_f32 v[16:17], v[16:17], v[140:141]
	v_pk_add_f32 v[18:19], v[18:19], v[142:143]
	s_cmp_gt_i32 s1, s7
	s_cbranch_scc0 .Lmy_pool_nosub_5
	v_lshlrev_b32_e32 v144, 16, v124
	v_and_b32_e32 v145, 0xffff0000, v124
	v_lshlrev_b32_e32 v146, 16, v125
	v_and_b32_e32 v147, 0xffff0000, v125
	v_lshlrev_b32_e32 v148, 16, v126
	v_and_b32_e32 v149, 0xffff0000, v126
	v_lshlrev_b32_e32 v150, 16, v127
	v_and_b32_e32 v151, 0xffff0000, v127
	v_sub_f32_e32 v12, v12, v144
	v_sub_f32_e32 v13, v13, v145
	v_sub_f32_e32 v14, v14, v146
	v_sub_f32_e32 v15, v15, v147
	v_sub_f32_e32 v16, v16, v148
	v_sub_f32_e32 v17, v17, v149
	v_sub_f32_e32 v18, v18, v150
	v_sub_f32_e32 v19, v19, v151
.Lmy_pool_nosub_5:
	v_lshlrev_b32_e32 v144, 16, v92
	v_and_b32_e32 v145, 0xffff0000, v92
	v_lshlrev_b32_e32 v146, 16, v93
	v_and_b32_e32 v147, 0xffff0000, v93
	v_lshlrev_b32_e32 v148, 16, v94
	v_and_b32_e32 v149, 0xffff0000, v94
	v_lshlrev_b32_e32 v150, 16, v95
	v_and_b32_e32 v151, 0xffff0000, v95
	v_fma_f32 v152, v168, v12, -v136
	v_fma_f32 v153, v168, v13, -v137
	v_fma_f32 v154, v168, v14, -v138
	v_fma_f32 v155, v168, v15, -v139
	v_fma_f32 v156, v168, v16, -v140
	v_fma_f32 v157, v168, v17, -v141
	v_fma_f32 v158, v168, v18, -v142
	v_fma_f32 v159, v168, v19, -v143
	v_mul_f32_e32 v160, 0xbfb8aa3b, v144
	v_mul_f32_e32 v161, 0xbfb8aa3b, v145
	v_mul_f32_e32 v162, 0xbfb8aa3b, v146
	v_mul_f32_e32 v163, 0xbfb8aa3b, v147
	v_mul_f32_e32 v164, 0xbfb8aa3b, v148
	v_mul_f32_e32 v165, 0xbfb8aa3b, v149
	v_mul_f32_e32 v166, 0xbfb8aa3b, v150
	v_mul_f32_e32 v167, 0xbfb8aa3b, v151
	v_exp_f32_e32 v160, v160
	v_exp_f32_e32 v161, v161
	v_exp_f32_e32 v162, v162
	v_exp_f32_e32 v163, v163
	v_exp_f32_e32 v164, v164
	v_exp_f32_e32 v165, v165
	v_exp_f32_e32 v166, v166
	v_exp_f32_e32 v167, v167
	v_mul_f32_e32 v152, v4, v152
	v_mul_f32_e32 v153, v5, v153
	v_mul_f32_e32 v154, v6, v154
	v_mul_f32_e32 v155, v7, v155
	v_mul_f32_e32 v156, v8, v156
	v_mul_f32_e32 v157, v9, v157
	v_mul_f32_e32 v158, v10, v158
	v_mul_f32_e32 v159, v11, v159
	v_add_f32_e32 v160, 1.0, v160
	v_add_f32_e32 v161, 1.0, v161
	v_add_f32_e32 v162, 1.0, v162
	v_add_f32_e32 v163, 1.0, v163
	v_add_f32_e32 v164, 1.0, v164
	v_add_f32_e32 v165, 1.0, v165
	v_add_f32_e32 v166, 1.0, v166
	v_add_f32_e32 v167, 1.0, v167
	v_rcp_f32_e32 v160, v160
	v_rcp_f32_e32 v161, v161
	v_rcp_f32_e32 v162, v162
	v_rcp_f32_e32 v163, v163
	v_rcp_f32_e32 v164, v164
	v_rcp_f32_e32 v165, v165
	v_rcp_f32_e32 v166, v166
	v_rcp_f32_e32 v167, v167
	s_nop 0
	v_mul_f32_e32 v160, v160, v144
	v_mul_f32_e32 v161, v161, v145
	v_mul_f32_e32 v162, v162, v146
	v_mul_f32_e32 v163, v163, v147
	v_mul_f32_e32 v164, v164, v148
	v_mul_f32_e32 v165, v165, v149
	v_mul_f32_e32 v166, v166, v150
	v_mul_f32_e32 v167, v167, v151
	v_mul_f32_e32 v152, v152, v160
	v_mul_f32_e32 v153, v153, v161
	v_mul_f32_e32 v154, v154, v162
	v_mul_f32_e32 v155, v155, v163
	v_mul_f32_e32 v156, v156, v164
	v_mul_f32_e32 v157, v157, v165
	v_mul_f32_e32 v158, v158, v166
	v_mul_f32_e32 v159, v159, v167
	v_cvt_pk_bf16_f32 v172, v152, v153
	v_cvt_pk_bf16_f32 v173, v154, v155
	v_cvt_pk_bf16_f32 v174, v156, v157
	v_cvt_pk_bf16_f32 v175, v158, v159
	s_nop 0
	global_store_dwordx4 v33, v[172:175], s[18:19]
	s_add_i32 s1, s10, 7
	s_min_i32 s11, s1, s7
	v_cvt_f32_i32_e32 v168, s11
	s_waitcnt vmcnt(9)
	v_lshlrev_b32_e32 v136, 16, v64
	v_and_b32_e32 v137, 0xffff0000, v64
	v_lshlrev_b32_e32 v138, 16, v65
	v_and_b32_e32 v139, 0xffff0000, v65
	v_lshlrev_b32_e32 v140, 16, v66
	v_and_b32_e32 v141, 0xffff0000, v66
	v_lshlrev_b32_e32 v142, 16, v67
	v_and_b32_e32 v143, 0xffff0000, v67
	v_rcp_iflag_f32_e32 v168, v168
	v_pk_add_f32 v[12:13], v[12:13], v[136:137]
	v_pk_add_f32 v[14:15], v[14:15], v[138:139]
	v_pk_add_f32 v[16:17], v[16:17], v[140:141]
	v_pk_add_f32 v[18:19], v[18:19], v[142:143]
	s_cmp_gt_i32 s1, s7
	s_cbranch_scc0 .Lmy_pool_nosub_6
	v_lshlrev_b32_e32 v144, 16, v128
	v_and_b32_e32 v145, 0xffff0000, v128
	v_lshlrev_b32_e32 v146, 16, v129
	v_and_b32_e32 v147, 0xffff0000, v129
	v_lshlrev_b32_e32 v148, 16, v130
	v_and_b32_e32 v149, 0xffff0000, v130
	v_lshlrev_b32_e32 v150, 16, v131
	v_and_b32_e32 v151, 0xffff0000, v131
	v_sub_f32_e32 v12, v12, v144
	v_sub_f32_e32 v13, v13, v145
	v_sub_f32_e32 v14, v14, v146
	v_sub_f32_e32 v15, v15, v147
	v_sub_f32_e32 v16, v16, v148
	v_sub_f32_e32 v17, v17, v149
	v_sub_f32_e32 v18, v18, v150
	v_sub_f32_e32 v19, v19, v151
; __device__ __forceinline__ float silu_f(float x) { return x * __builtin_amdgcn_rcpf(1.0f + __expf(-x)); }
; __device__ __forceinline__ void pool_phase(const u16* __restrict__ UG, u16* __restrict__ PL, const float* __restrict__ scale, const int wave) {
;     ...
;     _Pragma("unroll 16") for (int t = 0; t < 64; ++t) {
;       const int s = s0 + t;
;       uint4 u = *reinterpret_cast<const uint4*>(UG + (long)(r0 + t) * 4096 + c0);
;       float cur[8];
;       cur[0] = __uint_as_float(u.x << 16); cur[1] = __uint_as_float(u.x & 0xffff0000u);
;       cur[2] = __uint_as_float(u.y << 16); cur[3] = __uint_as_float(u.y & 0xffff0000u);
;       cur[4] = __uint_as_float(u.z << 16); cur[5] = __uint_as_float(u.z & 0xffff0000u);
;       cur[6] = __uint_as_float(u.w << 16); cur[7] = __uint_as_float(u.w & 0xffff0000u);
;       for (int e = 0; e < 8; ++e) sum[e] += cur[e];
;       if (s - w >= 0) {
;         uint4 o = *reinterpret_cast<const uint4*>(UG + (long)(r0 + t - w) * 4096 + c0);
;         sum[0] -= __uint_as_float(o.x << 16); sum[1] -= __uint_as_float(o.x & 0xffff0000u);
;         sum[2] -= __uint_as_float(o.y << 16); sum[3] -= __uint_as_float(o.y & 0xffff0000u);
;         sum[4] -= __uint_as_float(o.z << 16); sum[5] -= __uint_as_float(o.z & 0xffff0000u);
;         sum[6] -= __uint_as_float(o.w << 16); sum[7] -= __uint_as_float(o.w & 0xffff0000u);
;       }
;       const float inv = __builtin_amdgcn_rcpf((float)min(s + 1, w));
;       const uint4 gq = *reinterpret_cast<const uint4*>(UG + (long)(r0 + t) * 4096 + 2048 + c0);
;       float gt[8];
;       gt[0] = __uint_as_float(gq.x << 16); gt[1] = __uint_as_float(gq.x & 0xffff0000u);
;       gt[2] = __uint_as_float(gq.y << 16); gt[3] = __uint_as_float(gq.y & 0xffff0000u);
;       gt[4] = __uint_as_float(gq.z << 16); gt[5] = __uint_as_float(gq.z & 0xffff0000u);
;       gt[6] = __uint_as_float(gq.w << 16); gt[7] = __uint_as_float(gq.w & 0xffff0000u);
;       float hv[8];
;       _Pragma("unroll") for (int e = 0; e < 8; ++e) hv[e] = sc[e] * (sum[e] * inv - cur[e]) * silu_f(gt[e]);
;       uint4 pk;
;       pk.x = pack2(hv[0], hv[1]); pk.y = pack2(hv[2], hv[3]); pk.z = pack2(hv[4], hv[5]); pk.w = pack2(hv[6], hv[7]);
;       *reinterpret_cast<uint4*>(PL + (long)(r0 + t) * DM + c0) = pk;
;     }
.Lmy_pool_nosub_6:
	v_lshlrev_b32_e32 v144, 16, v96
	v_and_b32_e32 v145, 0xffff0000, v96
	v_lshlrev_b32_e32 v146, 16, v97
	v_and_b32_e32 v147, 0xffff0000, v97
	v_lshlrev_b32_e32 v148, 16, v98
	v_and_b32_e32 v149, 0xffff0000, v98
	v_lshlrev_b32_e32 v150, 16, v99
	v_and_b32_e32 v151, 0xffff0000, v99
	v_fma_f32 v152, v168, v12, -v136
	v_fma_f32 v153, v168, v13, -v137
	v_fma_f32 v154, v168, v14, -v138
	v_fma_f32 v155, v168, v15, -v139
	v_fma_f32 v156, v168, v16, -v140
	v_fma_f32 v157, v168, v17, -v141
	v_fma_f32 v158, v168, v18, -v142
	v_fma_f32 v159, v168, v19, -v143
	v_mul_f32_e32 v160, 0xbfb8aa3b, v144
	v_mul_f32_e32 v161, 0xbfb8aa3b, v145
	v_mul_f32_e32 v162, 0xbfb8aa3b, v146
	v_mul_f32_e32 v163, 0xbfb8aa3b, v147
	v_mul_f32_e32 v164, 0xbfb8aa3b, v148
	v_mul_f32_e32 v165, 0xbfb8aa3b, v149
	v_mul_f32_e32 v166, 0xbfb8aa3b, v150
	v_mul_f32_e32 v167, 0xbfb8aa3b, v151
	v_exp_f32_e32 v160, v160
	v_exp_f32_e32 v161, v161
	v_exp_f32_e32 v162, v162
	v_exp_f32_e32 v163, v163
	v_exp_f32_e32 v164, v164
	v_exp_f32_e32 v165, v165
	v_exp_f32_e32 v166, v166
	v_exp_f32_e32 v167, v167
	v_mul_f32_e32 v152, v4, v152
	v_mul_f32_e32 v153, v5, v153
	v_mul_f32_e32 v154, v6, v154
	v_mul_f32_e32 v155, v7, v155
	v_mul_f32_e32 v156, v8, v156
	v_mul_f32_e32 v157, v9, v157
	v_mul_f32_e32 v158, v10, v158
	v_mul_f32_e32 v159, v11, v159
	v_add_f32_e32 v160, 1.0, v160
	v_add_f32_e32 v161, 1.0, v161
	v_add_f32_e32 v162, 1.0, v162
	v_add_f32_e32 v163, 1.0, v163
	v_add_f32_e32 v164, 1.0, v164
	v_add_f32_e32 v165, 1.0, v165
	v_add_f32_e32 v166, 1.0, v166
	v_add_f32_e32 v167, 1.0, v167
	v_rcp_f32_e32 v160, v160
	v_rcp_f32_e32 v161, v161
	v_rcp_f32_e32 v162, v162
	v_rcp_f32_e32 v163, v163
	v_rcp_f32_e32 v164, v164
	v_rcp_f32_e32 v165, v165
	v_rcp_f32_e32 v166, v166
	v_rcp_f32_e32 v167, v167
	s_nop 0
	v_mul_f32_e32 v160, v160, v144
	v_mul_f32_e32 v161, v161, v145
	v_mul_f32_e32 v162, v162, v146
	v_mul_f32_e32 v163, v163, v147
	v_mul_f32_e32 v164, v164, v148
	v_mul_f32_e32 v165, v165, v149
	v_mul_f32_e32 v166, v166, v150
	v_mul_f32_e32 v167, v167, v151
	v_mul_f32_e32 v152, v152, v160
	v_mul_f32_e32 v153, v153, v161
	v_mul_f32_e32 v154, v154, v162
	v_mul_f32_e32 v155, v155, v163
	v_mul_f32_e32 v156, v156, v164
	v_mul_f32_e32 v157, v157, v165
	v_mul_f32_e32 v158, v158, v166
	v_mul_f32_e32 v159, v159, v167
	v_cvt_pk_bf16_f32 v172, v152, v153
	v_cvt_pk_bf16_f32 v173, v154, v155
	v_cvt_pk_bf16_f32 v174, v156, v157
	v_cvt_pk_bf16_f32 v175, v158, v159
	s_nop 0
	global_store_dwordx4 v34, v[172:175], s[18:19]
	s_add_i32 s1, s10, 8
	s_min_i32 s11, s1, s7
	v_cvt_f32_i32_e32 v168, s11
	s_waitcnt vmcnt(7)
	v_lshlrev_b32_e32 v136, 16, v68
	v_and_b32_e32 v137, 0xffff0000, v68
	v_lshlrev_b32_e32 v138, 16, v69
	v_and_b32_e32 v139, 0xffff0000, v69
	v_lshlrev_b32_e32 v140, 16, v70
	v_and_b32_e32 v141, 0xffff0000, v70
	v_lshlrev_b32_e32 v142, 16, v71
	v_and_b32_e32 v143, 0xffff0000, v71
	v_rcp_iflag_f32_e32 v168, v168
	v_pk_add_f32 v[12:13], v[12:13], v[136:137]
	v_pk_add_f32 v[14:15], v[14:15], v[138:139]
	v_pk_add_f32 v[16:17], v[16:17], v[140:141]
	v_pk_add_f32 v[18:19], v[18:19], v[142:143]
	s_cmp_gt_i32 s1, s7
	s_cbranch_scc0 .Lmy_pool_nosub_7
	v_lshlrev_b32_e32 v144, 16, v132
	v_and_b32_e32 v145, 0xffff0000, v132
	v_lshlrev_b32_e32 v146, 16, v133
	v_and_b32_e32 v147, 0xffff0000, v133
	v_lshlrev_b32_e32 v148, 16, v134
	v_and_b32_e32 v149, 0xffff0000, v134
	v_lshlrev_b32_e32 v150, 16, v135
	v_and_b32_e32 v151, 0xffff0000, v135
	v_sub_f32_e32 v12, v12, v144
	v_sub_f32_e32 v13, v13, v145
	v_sub_f32_e32 v14, v14, v146
	v_sub_f32_e32 v15, v15, v147
	v_sub_f32_e32 v16, v16, v148
	v_sub_f32_e32 v17, v17, v149
	v_sub_f32_e32 v18, v18, v150
	v_sub_f32_e32 v19, v19, v151
.Lmy_pool_nosub_7:
	v_lshlrev_b32_e32 v144, 16, v100
	v_and_b32_e32 v145, 0xffff0000, v100
	v_lshlrev_b32_e32 v146, 16, v101
	v_and_b32_e32 v147, 0xffff0000, v101
	v_lshlrev_b32_e32 v148, 16, v102
	v_and_b32_e32 v149, 0xffff0000, v102
	v_lshlrev_b32_e32 v150, 16, v103
	v_and_b32_e32 v151, 0xffff0000, v103
	v_fma_f32 v152, v168, v12, -v136
	v_fma_f32 v153, v168, v13, -v137
	v_fma_f32 v154, v168, v14, -v138
	v_fma_f32 v155, v168, v15, -v139
	v_fma_f32 v156, v168, v16, -v140
	v_fma_f32 v157, v168, v17, -v141
	v_fma_f32 v158, v168, v18, -v142
	v_fma_f32 v159, v168, v19, -v143
	v_mul_f32_e32 v160, 0xbfb8aa3b, v144
	v_mul_f32_e32 v161, 0xbfb8aa3b, v145
	v_mul_f32_e32 v162, 0xbfb8aa3b, v146
	v_mul_f32_e32 v163, 0xbfb8aa3b, v147
	v_mul_f32_e32 v164, 0xbfb8aa3b, v148
	v_mul_f32_e32 v165, 0xbfb8aa3b, v149
	v_mul_f32_e32 v166, 0xbfb8aa3b, v150
	v_mul_f32_e32 v167, 0xbfb8aa3b, v151
	v_exp_f32_e32 v160, v160
	v_exp_f32_e32 v161, v161
	v_exp_f32_e32 v162, v162
	v_exp_f32_e32 v163, v163
	v_exp_f32_e32 v164, v164
	v_exp_f32_e32 v165, v165
	v_exp_f32_e32 v166, v166
	v_exp_f32_e32 v167, v167
	v_mul_f32_e32 v152, v4, v152
	v_mul_f32_e32 v153, v5, v153
	v_mul_f32_e32 v154, v6, v154
	v_mul_f32_e32 v155, v7, v155
	v_mul_f32_e32 v156, v8, v156
	v_mul_f32_e32 v157, v9, v157
	v_mul_f32_e32 v158, v10, v158
	v_mul_f32_e32 v159, v11, v159
	v_add_f32_e32 v160, 1.0, v160
	v_add_f32_e32 v161, 1.0, v161
	v_add_f32_e32 v162, 1.0, v162
	v_add_f32_e32 v163, 1.0, v163
	v_add_f32_e32 v164, 1.0, v164
	v_add_f32_e32 v165, 1.0, v165
	v_add_f32_e32 v166, 1.0, v166
	v_add_f32_e32 v167, 1.0, v167
	v_rcp_f32_e32 v160, v160
	v_rcp_f32_e32 v161, v161
	v_rcp_f32_e32 v162, v162
	v_rcp_f32_e32 v163, v163
	v_rcp_f32_e32 v164, v164
	v_rcp_f32_e32 v165, v165
	v_rcp_f32_e32 v166, v166
	v_rcp_f32_e32 v167, v167
	s_nop 0
	v_mul_f32_e32 v160, v160, v144
	v_mul_f32_e32 v161, v161, v145
	v_mul_f32_e32 v162, v162, v146
	v_mul_f32_e32 v163, v163, v147
	v_mul_f32_e32 v164, v164, v148
	v_mul_f32_e32 v165, v165, v149
	v_mul_f32_e32 v166, v166, v150
	v_mul_f32_e32 v167, v167, v151
	v_mul_f32_e32 v152, v152, v160
	v_mul_f32_e32 v153, v153, v161
	v_mul_f32_e32 v154, v154, v162
	v_mul_f32_e32 v155, v155, v163
	v_mul_f32_e32 v156, v156, v164
	v_mul_f32_e32 v157, v157, v165
	v_mul_f32_e32 v158, v158, v166
	v_mul_f32_e32 v159, v159, v167
	v_cvt_pk_bf16_f32 v172, v152, v153
	v_cvt_pk_bf16_f32 v173, v154, v155
	v_cvt_pk_bf16_f32 v174, v156, v157
	v_cvt_pk_bf16_f32 v175, v158, v159
	s_nop 0
	global_store_dwordx4 v35, v[172:175], s[18:19]
	s_add_u32 s12, s12, 0x10000
	s_addc_u32 s13, s13, 0
	s_add_u32 s14, s14, 0x10000
	s_addc_u32 s15, s15, 0
	s_add_u32 s16, s16, 0x10000
	s_addc_u32 s17, s17, 0
	s_add_u32 s18, s18, 0x8000
	s_addc_u32 s19, s19, 0
	s_add_i32 s3, s3, 8
	s_cmp_lt_u32 s3, 64
	s_cbranch_scc1 .Lmy_pool_batch
	s_mov_b64 s[4:5], exec

;     ...
;       const int tid3 = opaque_tid(wave);
;       const int wr3 = tid3 >> 8, wc3 = (tid3 >> 6) & 3, fr3 = tid3 & 15, fq3 = (tid3 & 63) >> 4;
;       const int ebase3 = (brow + wr3 * 64 + fr3) * DM + pn * BM + wc3 * 32 + fq3 * 4;
;       const int vo4b = ebase3 * 4, vo2 = ebase3 * 2, vo1 = ebase3;
;       (void)vo4b; (void)vo2; (void)vo1;
;       if constexpr (OUTF) {
;         _Pragma("unroll") for (int bj = 0; bj < 2; ++bj) _Pragma("unroll") for (int n = 0; n < 2; ++n) {
;           const int col = pn * BM + bj * HALF + wc3 * 32 + n * 16 + fq3 * 4;
;           const float4 gm = *reinterpret_cast<const float4*>(g.gam + col), bt = *reinterpret_cast<const float4*>(g.bet + col);
;           _Pragma("unroll") for (int ai = 0; ai < 2; ++ai) _Pragma("unroll") for (int m = 0; m < 4; ++m) {
;             const int rl = ai * HALF + wr3 * 64 + m * 16 + fr3;
;             const float2 ms = *reinterpret_cast<const float2*>(mr + rl * 2);
;             f32x4 y = acc[ai][bj][m][n];
;             u32x4 o;
;             o[0] = __float_as_uint((y[0] - ms.x) * ms.y * gm.x + bt.x); o[1] = __float_as_uint((y[1] - ms.x) * ms.y * gm.y + bt.y);
;             o[2] = __float_as_uint((y[2] - ms.x) * ms.y * gm.z + bt.z); o[3] = __float_as_uint((y[3] - ms.x) * ms.y * gm.w + bt.w);
;             __builtin_amdgcn_raw_buffer_store_b128(o, rsO, vo4b + ((ai * HALF + m * 16) * DM + bj * HALF + n * 16) * 4, 0, 0);
;           }
;         }
;       } else {
;         constexpr int PIECE = 1024 + 16, LOBASE = 64 * PIECE;
;         const int lane3 = tid3 & 63;
;         const int hvo = (lane3 >> 5) * (DM * 2) + (lane3 & 31) * 16;
;         const int lvo = (lane3 >> 4) * DM + (lane3 & 15) * 16;
;         _Pragma("unroll") for (int ai = 0; ai < 2; ++ai) {
;           _Pragma("unroll") for (int bj = 0; bj < 2; ++bj) _Pragma("unroll") for (int n = 0; n < 2; ++n) {
;             const int cc = bj * HALF + wc3 * 32 + n * 16 + fq3 * 4;
;             const float4 gm = *reinterpret_cast<const float4*>(g.gam + pn * BM + cc), bt = *reinterpret_cast<const float4*>(g.bet + pn * BM + cc);
;             _Pragma("unroll") for (int m = 0; m < 4; ++m) {
;               const int rr = wr3 * 64 + m * 16 + fr3;
;               const float2 ms = *reinterpret_cast<const float2*>(mr + (ai * HALF + rr) * 2);
;               f32x4 y = acc[ai][bj][m][n];
.LBB0_686:
	s_or_b64 exec, exec, s[6:7]
	s_waitcnt lgkmcnt(0)
	s_barrier
	v_mbcnt_lo_u32_b32 v0, -1, 0
	v_mbcnt_hi_u32_b32 v0, -1, v0
	s_ashr_i32 s35, s34, 31
	v_add_u32_e32 v1, s37, v0
	v_bfe_u32 v4, v0, 4, 2
	v_ashrrev_i32_e32 v5, 2, v1
	v_lshrrev_b32_e32 v6, 1, v1
	v_lshlrev_b32_e32 v1, 4, v1
	v_readlane_b32 s40, v255, 16
	v_lshlrev_b32_e32 v7, 2, v4
	v_lshlrev_b32_e32 v12, 7, v0
	v_and_b32_e32 v13, 0x1f0, v1
	s_movk_i32 s2, 0x60
	s_lshl_b64 s[4:5], s[34:35], 2
	v_readlane_b32 s50, v255, 26
	v_and_or_b32 v148, v12, s72, v13
	v_and_or_b32 v12, v6, s2, v7
	v_readlane_b32 s51, v255, 27
	s_add_u32 s6, s50, s4
	v_and_b32_e32 v2, 15, v0
	v_and_b32_e32 v3, 63, v0
	v_and_b32_e32 v1, 0xf0, v1
	v_lshlrev_b32_e32 v13, 9, v0
	v_lshlrev_b32_e32 v0, 8, v0
	s_addc_u32 s7, s51, s5
	v_lshlrev_b32_e32 v150, 2, v12
	v_lshl_or_b32 v146, v4, 11, v1
	v_and_or_b32 v155, v5, s36, v2
	v_and_b32_e32 v14, 0x300, v0
	v_lshlrev_b32_e32 v151, 4, v3
	global_load_dwordx4 v[220:223], v150, s[6:7]
	global_load_dwordx4 v[224:227], v150, s[6:7] offset:64
	global_load_dwordx4 v[228:231], v150, s[6:7] offset:512
	global_load_dwordx4 v[232:235], v150, s[6:7] offset:576
	v_readlane_b32 s52, v255, 28
	v_readlane_b32 s53, v255, 29
	s_add_u32 s4, s52, s4
	s_addc_u32 s5, s53, s5
	global_load_dwordx4 v[236:239], v150, s[4:5]
	global_load_dwordx4 v[240:243], v150, s[4:5] offset:64
	global_load_dwordx4 v[244:247], v150, s[4:5] offset:512
	global_load_dwordx4 v[248:251], v150, s[4:5] offset:576
	s_movk_i32 s22, 0x200
	v_lshl_add_u32 v149, v155, 3, v219
	v_add_u32_e32 v147, s68, v151
	s_andn2_b64 vcc, exec, s[14:15]
	v_readlane_b32 s41, v255, 17
	v_readlane_b32 s42, v255, 18
	v_readlane_b32 s43, v255, 19
	v_readlane_b32 s44, v255, 20
	v_readlane_b32 s45, v255, 21
	v_readlane_b32 s46, v255, 22
	v_readlane_b32 s47, v255, 23
	v_readlane_b32 s48, v255, 24
	v_readlane_b32 s49, v255, 25
	v_readlane_b32 s54, v255, 30
	v_readlane_b32 s55, v255, 31
	s_waitcnt vmcnt(0)
	v_mov_b32_e32 v0, v220
	v_mov_b32_e32 v1, v221
	v_mov_b32_e32 v2, v222
	v_mov_b32_e32 v3, v223
	v_mov_b32_e32 v4, v236
	v_mov_b32_e32 v5, v237
	v_mov_b32_e32 v6, v238
	v_mov_b32_e32 v7, v239
	v_mov_b32_e32 v22, v1
	v_lshlrev_b32_e32 v1, 1, v12
	v_and_or_b32 v154, v13, s22, v1
	s_mov_b32 s22, 0x10400
	v_mov_b32_e32 v23, v2
	v_or3_b32 v2, v14, v12, s22
	ds_read_b64 v[12:13], v149
	v_mov_b32_e32 v144, v5
	v_mov_b32_e32 v145, v6
	v_mov_b32_e32 v1, v3
	v_mov_b32_e32 v5, v7
	s_waitcnt lgkmcnt(0)
	v_pk_add_f32 v[14:15], v[132:133], v[12:13] op_sel_hi:[1,0] neg_lo:[0,1] neg_hi:[0,1]
	v_pk_add_f32 v[18:19], v[130:131], v[12:13] op_sel_hi:[1,0] neg_lo:[0,1] neg_hi:[0,1]
	v_pk_mul_f32 v[14:15], v[12:13], v[14:15] op_sel:[1,0]
	v_pk_mul_f32 v[12:13], v[12:13], v[18:19] op_sel:[1,0]
	v_pk_fma_f32 v[14:15], v[22:23], v[14:15], v[144:145]
	v_pk_fma_f32 v[6:7], v[0:1], v[12:13], v[4:5]
	v_and_b32_sdwa v12, v14, v216 dst_sel:DWORD dst_unused:UNUSED_PAD src0_sel:WORD_1 src1_sel:DWORD
	v_add3_u32 v12, v14, v12, s77
	v_and_b32_e32 v18, 0xffff0000, v12
	v_and_b32_sdwa v12, v7, v216 dst_sel:DWORD dst_unused:UNUSED_PAD src0_sel:WORD_1 src1_sel:DWORD
	v_and_b32_sdwa v3, v15, v216 dst_sel:DWORD dst_unused:UNUSED_PAD src0_sel:WORD_1 src1_sel:DWORD
	v_and_b32_sdwa v13, v6, v216 dst_sel:DWORD dst_unused:UNUSED_PAD src0_sel:WORD_1 src1_sel:DWORD
	v_add3_u32 v12, v7, v12, s77
	v_lshrrev_b32_e32 v131, 1, v155
	v_add3_u32 v3, v15, v3, s77
	v_add3_u32 v19, v6, v13, s77
	v_and_b32_e32 v130, 0xffff0000, v12
	v_mul_lo_u32 v152, v131, s60
	v_or_b32_sdwa v13, v130, v3 dst_sel:DWORD dst_unused:UNUSED_PAD src0_sel:DWORD src1_sel:WORD_1
	v_or_b32_sdwa v12, v19, v18 dst_sel:DWORD dst_unused:UNUSED_PAD src0_sel:WORD_1 src1_sel:DWORD
	v_add_u32_e32 v132, v154, v152
	ds_write_b64 v132, v[12:13]
	v_and_b32_e32 v12, 0xffff0000, v19
	v_sub_u32_e32 v6, v6, v12
	v_sub_u32_e32 v12, v14, v18
	v_and_b32_e32 v3, 0xffff0000, v3
	v_add_u32_e32 v12, 0x80, v12
	v_sub_u32_e32 v3, v15, v3
	v_sub_u32_e32 v7, v7, v130
	v_add_u32_e32 v6, 0x80, v6
	v_ashrrev_i32_e32 v12, 8, v12
	v_add_u32_e32 v3, 0x80, v3
	v_add_u32_e32 v7, 0x80, v7
	v_ashrrev_i32_e32 v6, 8, v6
	v_min_i32_e32 v12, 0x7f, v12
	v_ashrrev_i32_e32 v3, 8, v3
	v_ashrrev_i32_e32 v7, 8, v7
	v_min_i32_e32 v6, 0x7f, v6
	v_min_i32_sdwa v3, v3, s78 dst_sel:WORD_1 dst_unused:UNUSED_PAD src0_sel:DWORD src1_sel:DWORD
	v_min_i32_e32 v7, 0x7f, v7
	v_lshlrev_b32_e32 v12, 8, v12
	v_and_b32_e32 v12, 0xff00, v12
	v_and_b32_e32 v3, 0xff0000, v3
	v_perm_b32 v6, v7, v6, s79
	v_or3_b32 v3, v6, v12, v3
	v_lshrrev_b32_e32 v6, 2, v155
	v_mad_u64_u32 v[12:13], s[22:23], v6, s60, v[2:3]
	ds_write_b32 v12, v3
	v_or_b32_e32 v3, 16, v155
	v_lshl_add_u32 v13, v3, 3, v219
	ds_read_b64 v[6:7], v13
	v_lshrrev_b32_e32 v133, 1, v3
	v_mul_lo_u32 v153, v133, s60
	v_add_u32_e32 v133, v154, v153
	v_lshrrev_b32_e32 v3, 2, v3
	s_waitcnt lgkmcnt(0)
;     ...
;             _Pragma("unroll") for (int m = 0; m < 4; ++m) {
;               const int rr = wr3 * 64 + m * 16 + fr3;
;               const float2 ms = *reinterpret_cast<const float2*>(mr + (ai * HALF + rr) * 2);
;               f32x4 y = acc[ai][bj][m][n];
;               const float o0 = (y[0] - ms.x) * ms.y * gm.x + bt.x, o1 = (y[1] - ms.x) * ms.y * gm.y + bt.y;
;               const float o2 = (y[2] - ms.x) * ms.y * gm.z + bt.z, o3 = (y[3] - ms.x) * ms.y * gm.w + bt.w;
;               const unsigned h0 = f2bf(o0), h1 = f2bf(o1), h2 = f2bf(o2), h3 = f2bf(o3);
;               u32x2 ob; ob[0] = h0 | (h1 << 16); ob[1] = h2 | (h3 << 16);
;               *reinterpret_cast<u32x2*>(smem + (rr >> 1) * PIECE + (rr & 1) * 512 + cc * 2) = ob;
;               const int l0 = min(((int)__float_as_uint(o0) - (int)(h0 << 16) + 128) >> 8, 127);
;               const int l1 = min(((int)__float_as_uint(o1) - (int)(h1 << 16) + 128) >> 8, 127);
;               const int l2 = min(((int)__float_as_uint(o2) - (int)(h2 << 16) + 128) >> 8, 127);
;               const int l3 = min(((int)__float_as_uint(o3) - (int)(h3 << 16) + 128) >> 8, 127);
;               *reinterpret_cast<unsigned*>(smem + LOBASE + (rr >> 2) * PIECE + (rr & 3) * 256 + cc) =
;                   (unsigned)(l0 & 255) | ((unsigned)(l1 & 255) << 8) | ((unsigned)(l2 & 255) << 16) | ((unsigned)l3 << 24);
;             }
	v_pk_add_f32 v[14:15], v[122:123], v[6:7] op_sel_hi:[1,0] neg_lo:[0,1] neg_hi:[0,1]
	v_pk_add_f32 v[18:19], v[134:135], v[6:7] op_sel_hi:[1,0] neg_lo:[0,1] neg_hi:[0,1]
	v_pk_mul_f32 v[14:15], v[6:7], v[14:15] op_sel:[1,0]
	v_pk_mul_f32 v[6:7], v[6:7], v[18:19] op_sel:[1,0]
	v_pk_fma_f32 v[14:15], v[22:23], v[14:15], v[144:145]
	v_pk_fma_f32 v[6:7], v[0:1], v[6:7], v[4:5]
	v_and_b32_sdwa v18, v15, v216 dst_sel:DWORD dst_unused:UNUSED_PAD src0_sel:WORD_1 src1_sel:DWORD
	v_and_b32_sdwa v19, v14, v216 dst_sel:DWORD dst_unused:UNUSED_PAD src0_sel:WORD_1 src1_sel:DWORD
	v_add3_u32 v122, v15, v18, s77
	v_add3_u32 v18, v14, v19, s77
	v_and_b32_e32 v123, 0xffff0000, v18
	v_and_b32_sdwa v18, v7, v216 dst_sel:DWORD dst_unused:UNUSED_PAD src0_sel:WORD_1 src1_sel:DWORD
	v_and_b32_sdwa v19, v6, v216 dst_sel:DWORD dst_unused:UNUSED_PAD src0_sel:WORD_1 src1_sel:DWORD
	v_add3_u32 v18, v7, v18, s77
	v_add3_u32 v130, v6, v19, s77
	v_and_b32_e32 v131, 0xffff0000, v18
	v_or_b32_sdwa v19, v131, v122 dst_sel:DWORD dst_unused:UNUSED_PAD src0_sel:DWORD src1_sel:WORD_1
	v_or_b32_sdwa v18, v130, v123 dst_sel:DWORD dst_unused:UNUSED_PAD src0_sel:WORD_1 src1_sel:DWORD
	ds_write_b64 v133, v[18:19]
	v_and_b32_e32 v18, 0xffff0000, v130
	v_sub_u32_e32 v6, v6, v18
	v_sub_u32_e32 v14, v14, v123
	v_and_b32_e32 v18, 0xffff0000, v122
	v_add_u32_e32 v14, 0x80, v14
	v_sub_u32_e32 v15, v15, v18
	v_sub_u32_e32 v7, v7, v131
	v_add_u32_e32 v6, 0x80, v6
	v_ashrrev_i32_e32 v14, 8, v14
	v_add_u32_e32 v15, 0x80, v15
	v_add_u32_e32 v7, 0x80, v7
	v_ashrrev_i32_e32 v6, 8, v6
	v_min_i32_e32 v14, 0x7f, v14
	v_ashrrev_i32_e32 v15, 8, v15
	v_ashrrev_i32_e32 v7, 8, v7
	v_min_i32_e32 v6, 0x7f, v6
	v_min_i32_sdwa v15, v15, s78 dst_sel:WORD_1 dst_unused:UNUSED_PAD src0_sel:DWORD src1_sel:DWORD
	v_min_i32_e32 v7, 0x7f, v7
	v_lshlrev_b32_e32 v14, 8, v14
	v_and_b32_e32 v14, 0xff00, v14
	v_and_b32_e32 v15, 0xff0000, v15
	v_perm_b32 v6, v7, v6, s79
	v_or3_b32 v6, v6, v14, v15
	v_mad_u64_u32 v[14:15], s[22:23], v3, s60, v[2:3]
	v_or_b32_e32 v3, 32, v155
	ds_write_b32 v14, v6
	v_lshl_add_u32 v15, v3, 3, v219
	ds_read_b64 v[6:7], v15
	v_lshrrev_b32_e32 v134, 1, v3
	v_lshrrev_b32_e32 v3, 2, v3
	s_waitcnt lgkmcnt(0)
	v_pk_add_f32 v[18:19], v[136:137], v[6:7] op_sel_hi:[1,0] neg_lo:[0,1] neg_hi:[0,1]
	s_nop 0
	v_pk_mul_f32 v[18:19], v[6:7], v[18:19] op_sel:[1,0]
	v_pk_add_f32 v[122:123], v[138:139], v[6:7] op_sel_hi:[1,0] neg_lo:[0,1] neg_hi:[0,1]
	v_pk_fma_f32 v[18:19], v[22:23], v[18:19], v[144:145]
	v_pk_mul_f32 v[6:7], v[6:7], v[122:123] op_sel:[1,0]
	v_and_b32_sdwa v122, v19, v216 dst_sel:DWORD dst_unused:UNUSED_PAD src0_sel:WORD_1 src1_sel:DWORD
	v_and_b32_sdwa v123, v18, v216 dst_sel:DWORD dst_unused:UNUSED_PAD src0_sel:WORD_1 src1_sel:DWORD
	v_pk_fma_f32 v[6:7], v[0:1], v[6:7], v[4:5]
	v_add3_u32 v130, v19, v122, s77
	v_add3_u32 v122, v18, v123, s77
	v_and_b32_e32 v131, 0xffff0000, v122
	v_and_b32_sdwa v122, v7, v216 dst_sel:DWORD dst_unused:UNUSED_PAD src0_sel:WORD_1 src1_sel:DWORD
	v_and_b32_sdwa v123, v6, v216 dst_sel:DWORD dst_unused:UNUSED_PAD src0_sel:WORD_1 src1_sel:DWORD
	v_add3_u32 v122, v7, v122, s77
	v_add3_u32 v135, v6, v123, s77
	v_and_b32_e32 v136, 0xffff0000, v122
	v_mul_lo_u32 v137, v134, s60
	v_or_b32_sdwa v123, v136, v130 dst_sel:DWORD dst_unused:UNUSED_PAD src0_sel:DWORD src1_sel:WORD_1
	v_or_b32_sdwa v122, v135, v131 dst_sel:DWORD dst_unused:UNUSED_PAD src0_sel:WORD_1 src1_sel:DWORD
	v_add_u32_e32 v134, v154, v137
	ds_write_b64 v134, v[122:123]
	v_and_b32_e32 v122, 0xffff0000, v135
	v_sub_u32_e32 v6, v6, v122
	v_sub_u32_e32 v18, v18, v131
	v_and_b32_e32 v122, 0xffff0000, v130
	v_add_u32_e32 v18, 0x80, v18
	v_sub_u32_e32 v19, v19, v122
	v_sub_u32_e32 v7, v7, v136
	v_add_u32_e32 v6, 0x80, v6
	v_ashrrev_i32_e32 v18, 8, v18
	v_add_u32_e32 v19, 0x80, v19
	v_add_u32_e32 v7, 0x80, v7
	v_ashrrev_i32_e32 v6, 8, v6
	v_min_i32_e32 v18, 0x7f, v18
	v_ashrrev_i32_e32 v19, 8, v19
	v_ashrrev_i32_e32 v7, 8, v7
	v_min_i32_e32 v6, 0x7f, v6
	v_min_i32_sdwa v19, v19, s78 dst_sel:WORD_1 dst_unused:UNUSED_PAD src0_sel:DWORD src1_sel:DWORD
	v_min_i32_e32 v7, 0x7f, v7
	v_lshlrev_b32_e32 v18, 8, v18
	v_and_b32_e32 v18, 0xff00, v18
	v_and_b32_e32 v19, 0xff0000, v19
	v_perm_b32 v6, v7, v6, s79
	v_or3_b32 v6, v6, v18, v19
	v_mad_u64_u32 v[18:19], s[22:23], v3, s60, v[2:3]
	v_or_b32_e32 v3, 48, v155
	ds_write_b32 v18, v6
	v_lshl_add_u32 v19, v3, 3, v219
	ds_read_b64 v[6:7], v19
	v_lshrrev_b32_e32 v130, 1, v3
	v_mul_lo_u32 v136, v130, s60
	v_add_u32_e32 v135, v154, v136
	s_waitcnt lgkmcnt(0)
;     ...
;           _Pragma("unroll") for (int bj = 0; bj < 2; ++bj) _Pragma("unroll") for (int n = 0; n < 2; ++n) {
;             const int cc = bj * HALF + wc3 * 32 + n * 16 + fq3 * 4;
;             const float4 gm = *reinterpret_cast<const float4*>(g.gam + pn * BM + cc), bt = *reinterpret_cast<const float4*>(g.bet + pn * BM + cc);
;             _Pragma("unroll") for (int m = 0; m < 4; ++m) {
;               const int rr = wr3 * 64 + m * 16 + fr3;
;               const float2 ms = *reinterpret_cast<const float2*>(mr + (ai * HALF + rr) * 2);
;               f32x4 y = acc[ai][bj][m][n];
;               const float o0 = (y[0] - ms.x) * ms.y * gm.x + bt.x, o1 = (y[1] - ms.x) * ms.y * gm.y + bt.y;
;               const float o2 = (y[2] - ms.x) * ms.y * gm.z + bt.z, o3 = (y[3] - ms.x) * ms.y * gm.w + bt.w;
;               const unsigned h0 = f2bf(o0), h1 = f2bf(o1), h2 = f2bf(o2), h3 = f2bf(o3);
;               u32x2 ob; ob[0] = h0 | (h1 << 16); ob[1] = h2 | (h3 << 16);
;               *reinterpret_cast<u32x2*>(smem + (rr >> 1) * PIECE + (rr & 1) * 512 + cc * 2) = ob;
;               const int l0 = min(((int)__float_as_uint(o0) - (int)(h0 << 16) + 128) >> 8, 127);
;               const int l1 = min(((int)__float_as_uint(o1) - (int)(h1 << 16) + 128) >> 8, 127);
;               const int l2 = min(((int)__float_as_uint(o2) - (int)(h2 << 16) + 128) >> 8, 127);
;               const int l3 = min(((int)__float_as_uint(o3) - (int)(h3 << 16) + 128) >> 8, 127);
;               *reinterpret_cast<unsigned*>(smem + LOBASE + (rr >> 2) * PIECE + (rr & 3) * 256 + cc) =
;                   (unsigned)(l0 & 255) | ((unsigned)(l1 & 255) << 8) | ((unsigned)(l2 & 255) << 16) | ((unsigned)l3 << 24);
;             }
	v_pk_add_f32 v[122:123], v[140:141], v[6:7] op_sel_hi:[1,0] neg_lo:[0,1] neg_hi:[0,1]
	s_nop 0
	v_pk_mul_f32 v[122:123], v[6:7], v[122:123] op_sel:[1,0]
	s_nop 0
	v_pk_fma_f32 v[22:23], v[22:23], v[122:123], v[144:145]
	v_pk_add_f32 v[122:123], v[142:143], v[6:7] op_sel_hi:[1,0] neg_lo:[0,1] neg_hi:[0,1]
	s_nop 0
	v_pk_mul_f32 v[6:7], v[6:7], v[122:123] op_sel:[1,0]
	s_nop 0
	v_pk_fma_f32 v[0:1], v[0:1], v[6:7], v[4:5]
	v_and_b32_sdwa v4, v23, v216 dst_sel:DWORD dst_unused:UNUSED_PAD src0_sel:WORD_1 src1_sel:DWORD
	v_and_b32_sdwa v5, v22, v216 dst_sel:DWORD dst_unused:UNUSED_PAD src0_sel:WORD_1 src1_sel:DWORD
	v_add3_u32 v6, v23, v4, s77
	v_add3_u32 v4, v22, v5, s77
	v_and_b32_e32 v7, 0xffff0000, v4
	v_and_b32_sdwa v4, v1, v216 dst_sel:DWORD dst_unused:UNUSED_PAD src0_sel:WORD_1 src1_sel:DWORD
	v_and_b32_sdwa v5, v0, v216 dst_sel:DWORD dst_unused:UNUSED_PAD src0_sel:WORD_1 src1_sel:DWORD
	v_add3_u32 v4, v1, v4, s77
	v_add3_u32 v122, v0, v5, s77
	v_and_b32_e32 v123, 0xffff0000, v4
	v_or_b32_sdwa v5, v123, v6 dst_sel:DWORD dst_unused:UNUSED_PAD src0_sel:DWORD src1_sel:WORD_1
	v_or_b32_sdwa v4, v122, v7 dst_sel:DWORD dst_unused:UNUSED_PAD src0_sel:WORD_1 src1_sel:DWORD
	ds_write_b64 v135, v[4:5]
	v_and_b32_e32 v4, 0xffff0000, v122
	v_sub_u32_e32 v0, v0, v4
	v_sub_u32_e32 v4, v22, v7
	v_and_b32_e32 v5, 0xffff0000, v6
	v_add_u32_e32 v4, 0x80, v4
	v_sub_u32_e32 v5, v23, v5
	v_sub_u32_e32 v1, v1, v123
	v_add_u32_e32 v0, 0x80, v0
	v_ashrrev_i32_e32 v4, 8, v4
	v_add_u32_e32 v5, 0x80, v5
	v_add_u32_e32 v1, 0x80, v1
	v_ashrrev_i32_e32 v0, 8, v0
	v_min_i32_e32 v4, 0x7f, v4
	v_ashrrev_i32_e32 v5, 8, v5
	v_ashrrev_i32_e32 v1, 8, v1
	v_min_i32_e32 v0, 0x7f, v0
	v_min_i32_sdwa v5, v5, s78 dst_sel:WORD_1 dst_unused:UNUSED_PAD src0_sel:DWORD src1_sel:DWORD
	v_min_i32_e32 v1, 0x7f, v1
	v_lshlrev_b32_e32 v4, 8, v4
	v_and_b32_e32 v4, 0xff00, v4
	v_and_b32_e32 v5, 0xff0000, v5
	v_perm_b32 v0, v1, v0, s79
	v_lshrrev_b32_e32 v1, 2, v3
	v_or3_b32 v0, v0, v4, v5
	v_mad_u64_u32 v[22:23], s[22:23], v1, s60, v[2:3]
	ds_write_b32 v22, v0
	v_mov_b32_e32 v0, v224
	v_mov_b32_e32 v1, v225
	v_mov_b32_e32 v2, v226
	v_mov_b32_e32 v3, v227
	v_mov_b32_e32 v4, v240
	v_mov_b32_e32 v5, v241
	v_mov_b32_e32 v6, v242
	v_mov_b32_e32 v7, v243
	ds_read_b64 v[138:139], v149
	s_mov_b32 s22, s18
	s_mov_b32 s23, s19
	s_waitcnt lgkmcnt(0)
	v_pk_add_f32 v[128:129], v[128:129], v[138:139] op_sel_hi:[1,0] neg_lo:[0,1] neg_hi:[0,1]
	s_nop 0
	v_pk_mul_f32 v[128:129], v[138:139], v[128:129] op_sel:[1,0]
	v_pk_add_f32 v[126:127], v[126:127], v[138:139] op_sel_hi:[1,0] neg_lo:[0,1] neg_hi:[0,1]
	v_mov_b32_e32 v122, v1
	v_mov_b32_e32 v123, v2
	v_mov_b32_e32 v130, v5
	v_mov_b32_e32 v131, v6
	v_pk_fma_f32 v[128:129], v[122:123], v[128:129], v[130:131]
	v_pk_mul_f32 v[126:127], v[138:139], v[126:127] op_sel:[1,0]
	v_mov_b32_e32 v1, v3
	v_mov_b32_e32 v5, v7
	v_and_b32_sdwa v23, v128, v216 dst_sel:DWORD dst_unused:UNUSED_PAD src0_sel:WORD_1 src1_sel:DWORD
	v_pk_fma_f32 v[6:7], v[0:1], v[126:127], v[4:5]
	v_add3_u32 v23, v128, v23, s77
	v_and_b32_e32 v138, 0xffff0000, v23
	v_and_b32_sdwa v23, v7, v216 dst_sel:DWORD dst_unused:UNUSED_PAD src0_sel:WORD_1 src1_sel:DWORD
	v_and_b32_sdwa v3, v129, v216 dst_sel:DWORD dst_unused:UNUSED_PAD src0_sel:WORD_1 src1_sel:DWORD
	v_and_b32_sdwa v126, v6, v216 dst_sel:DWORD dst_unused:UNUSED_PAD src0_sel:WORD_1 src1_sel:DWORD
	v_add3_u32 v23, v7, v23, s77
	v_or_b32_e32 v2, 32, v154
	v_add3_u32 v3, v129, v3, s77
	v_add3_u32 v139, v6, v126, s77
	v_and_b32_e32 v140, 0xffff0000, v23
	v_or_b32_sdwa v127, v140, v3 dst_sel:DWORD dst_unused:UNUSED_PAD src0_sel:DWORD src1_sel:WORD_1
	v_or_b32_sdwa v126, v139, v138 dst_sel:DWORD dst_unused:UNUSED_PAD src0_sel:WORD_1 src1_sel:DWORD
	v_add_u32_e32 v23, v2, v152
	ds_write_b64 v23, v[126:127]
	v_and_b32_e32 v126, 0xffff0000, v139
	v_sub_u32_e32 v6, v6, v126
	v_sub_u32_e32 v126, v128, v138
	v_and_b32_e32 v3, 0xffff0000, v3
	v_add_u32_e32 v126, 0x80, v126
	v_sub_u32_e32 v3, v129, v3
	v_sub_u32_e32 v7, v7, v140
	v_add_u32_e32 v6, 0x80, v6
	v_ashrrev_i32_e32 v126, 8, v126
	v_add_u32_e32 v3, 0x80, v3
	v_add_u32_e32 v7, 0x80, v7
	v_ashrrev_i32_e32 v6, 8, v6
	v_min_i32_e32 v126, 0x7f, v126
	v_ashrrev_i32_e32 v3, 8, v3
	v_ashrrev_i32_e32 v7, 8, v7
	v_min_i32_e32 v6, 0x7f, v6
	v_min_i32_sdwa v3, v3, s78 dst_sel:WORD_1 dst_unused:UNUSED_PAD src0_sel:DWORD src1_sel:DWORD
	v_min_i32_e32 v7, 0x7f, v7
	v_lshlrev_b32_e32 v126, 8, v126
	v_and_b32_e32 v126, 0xff00, v126
	v_and_b32_e32 v3, 0xff0000, v3
	v_perm_b32 v6, v7, v6, s79
	v_or3_b32 v3, v6, v126, v3
	ds_write_b32 v12, v3 offset:16
	ds_read_b64 v[6:7], v13
	s_waitcnt lgkmcnt(0)
;     ...
;           _Pragma("unroll") for (int bj = 0; bj < 2; ++bj) _Pragma("unroll") for (int n = 0; n < 2; ++n) {
;             const int cc = bj * HALF + wc3 * 32 + n * 16 + fq3 * 4;
;             const float4 gm = *reinterpret_cast<const float4*>(g.gam + pn * BM + cc), bt = *reinterpret_cast<const float4*>(g.bet + pn * BM + cc);
;             _Pragma("unroll") for (int m = 0; m < 4; ++m) {
;               const int rr = wr3 * 64 + m * 16 + fr3;
;               const float2 ms = *reinterpret_cast<const float2*>(mr + (ai * HALF + rr) * 2);
;               f32x4 y = acc[ai][bj][m][n];
;               const float o0 = (y[0] - ms.x) * ms.y * gm.x + bt.x, o1 = (y[1] - ms.x) * ms.y * gm.y + bt.y;
;               const float o2 = (y[2] - ms.x) * ms.y * gm.z + bt.z, o3 = (y[3] - ms.x) * ms.y * gm.w + bt.w;
;               const unsigned h0 = f2bf(o0), h1 = f2bf(o1), h2 = f2bf(o2), h3 = f2bf(o3);
;               u32x2 ob; ob[0] = h0 | (h1 << 16); ob[1] = h2 | (h3 << 16);
;               *reinterpret_cast<u32x2*>(smem + (rr >> 1) * PIECE + (rr & 1) * 512 + cc * 2) = ob;
;               const int l0 = min(((int)__float_as_uint(o0) - (int)(h0 << 16) + 128) >> 8, 127);
;               const int l1 = min(((int)__float_as_uint(o1) - (int)(h1 << 16) + 128) >> 8, 127);
;               const int l2 = min(((int)__float_as_uint(o2) - (int)(h2 << 16) + 128) >> 8, 127);
;               const int l3 = min(((int)__float_as_uint(o3) - (int)(h3 << 16) + 128) >> 8, 127);
;               *reinterpret_cast<unsigned*>(smem + LOBASE + (rr >> 2) * PIECE + (rr & 3) * 256 + cc) =
;                   (unsigned)(l0 & 255) | ((unsigned)(l1 & 255) << 8) | ((unsigned)(l2 & 255) << 16) | ((unsigned)l3 << 24);
;             }
	v_pk_add_f32 v[108:109], v[108:109], v[6:7] op_sel_hi:[1,0] neg_lo:[0,1] neg_hi:[0,1]
	s_nop 0
	v_pk_mul_f32 v[108:109], v[6:7], v[108:109] op_sel:[1,0]
	s_nop 0
	v_pk_fma_f32 v[126:127], v[122:123], v[108:109], v[130:131]
	v_pk_add_f32 v[108:109], v[110:111], v[6:7] op_sel_hi:[1,0] neg_lo:[0,1] neg_hi:[0,1]
	v_and_b32_sdwa v3, v127, v216 dst_sel:DWORD dst_unused:UNUSED_PAD src0_sel:WORD_1 src1_sel:DWORD
	v_pk_mul_f32 v[6:7], v[6:7], v[108:109] op_sel:[1,0]
	v_and_b32_sdwa v108, v126, v216 dst_sel:DWORD dst_unused:UNUSED_PAD src0_sel:WORD_1 src1_sel:DWORD
	v_pk_fma_f32 v[6:7], v[0:1], v[6:7], v[4:5]
	v_add3_u32 v108, v126, v108, s77
	v_and_b32_e32 v109, 0xffff0000, v108
	v_and_b32_sdwa v108, v7, v216 dst_sel:DWORD dst_unused:UNUSED_PAD src0_sel:WORD_1 src1_sel:DWORD
	v_and_b32_sdwa v110, v6, v216 dst_sel:DWORD dst_unused:UNUSED_PAD src0_sel:WORD_1 src1_sel:DWORD
	v_add3_u32 v108, v7, v108, s77
	v_add3_u32 v3, v127, v3, s77
	v_add3_u32 v128, v6, v110, s77
	v_and_b32_e32 v129, 0xffff0000, v108
	v_or_b32_sdwa v111, v129, v3 dst_sel:DWORD dst_unused:UNUSED_PAD src0_sel:DWORD src1_sel:WORD_1
	v_or_b32_sdwa v110, v128, v109 dst_sel:DWORD dst_unused:UNUSED_PAD src0_sel:WORD_1 src1_sel:DWORD
	v_add_u32_e32 v108, v2, v153
	ds_write_b64 v108, v[110:111]
	v_and_b32_e32 v110, 0xffff0000, v128
	v_sub_u32_e32 v109, v126, v109
	v_and_b32_e32 v3, 0xffff0000, v3
	v_sub_u32_e32 v6, v6, v110
	v_add_u32_e32 v109, 0x80, v109
	v_sub_u32_e32 v3, v127, v3
	v_sub_u32_e32 v7, v7, v129
	v_add_u32_e32 v6, 0x80, v6
	v_ashrrev_i32_e32 v109, 8, v109
	v_add_u32_e32 v3, 0x80, v3
	v_add_u32_e32 v7, 0x80, v7
	v_ashrrev_i32_e32 v6, 8, v6
	v_min_i32_e32 v109, 0x7f, v109
	v_ashrrev_i32_e32 v3, 8, v3
	v_ashrrev_i32_e32 v7, 8, v7
	v_min_i32_e32 v6, 0x7f, v6
	v_min_i32_sdwa v3, v3, s78 dst_sel:WORD_1 dst_unused:UNUSED_PAD src0_sel:DWORD src1_sel:DWORD
	v_min_i32_e32 v7, 0x7f, v7
	v_lshlrev_b32_e32 v109, 8, v109
	v_and_b32_e32 v109, 0xff00, v109
	v_and_b32_e32 v3, 0xff0000, v3
	v_perm_b32 v6, v7, v6, s79
	v_or3_b32 v3, v6, v109, v3
	ds_write_b32 v14, v3 offset:16
	ds_read_b64 v[6:7], v15
	s_waitcnt lgkmcnt(0)
	v_pk_add_f32 v[98:99], v[98:99], v[6:7] op_sel_hi:[1,0] neg_lo:[0,1] neg_hi:[0,1]
	s_nop 0
	v_pk_mul_f32 v[98:99], v[6:7], v[98:99] op_sel:[1,0]
	s_nop 0
	v_pk_fma_f32 v[110:111], v[122:123], v[98:99], v[130:131]
	v_pk_add_f32 v[98:99], v[106:107], v[6:7] op_sel_hi:[1,0] neg_lo:[0,1] neg_hi:[0,1]
	v_and_b32_sdwa v3, v111, v216 dst_sel:DWORD dst_unused:UNUSED_PAD src0_sel:WORD_1 src1_sel:DWORD
	v_pk_mul_f32 v[6:7], v[6:7], v[98:99] op_sel:[1,0]
	v_and_b32_sdwa v98, v110, v216 dst_sel:DWORD dst_unused:UNUSED_PAD src0_sel:WORD_1 src1_sel:DWORD
	v_pk_fma_f32 v[6:7], v[0:1], v[6:7], v[4:5]
	v_add3_u32 v98, v110, v98, s77
	v_and_b32_e32 v99, 0xffff0000, v98
	v_and_b32_sdwa v98, v7, v216 dst_sel:DWORD dst_unused:UNUSED_PAD src0_sel:WORD_1 src1_sel:DWORD
	v_and_b32_sdwa v106, v6, v216 dst_sel:DWORD dst_unused:UNUSED_PAD src0_sel:WORD_1 src1_sel:DWORD
	v_add3_u32 v98, v7, v98, s77
	v_add3_u32 v3, v111, v3, s77
	v_add3_u32 v109, v6, v106, s77
	v_and_b32_e32 v126, 0xffff0000, v98
	v_or_b32_sdwa v107, v126, v3 dst_sel:DWORD dst_unused:UNUSED_PAD src0_sel:DWORD src1_sel:WORD_1
	v_or_b32_sdwa v106, v109, v99 dst_sel:DWORD dst_unused:UNUSED_PAD src0_sel:WORD_1 src1_sel:DWORD
	v_add_u32_e32 v98, v2, v137
	ds_write_b64 v98, v[106:107]
	v_and_b32_e32 v106, 0xffff0000, v109
	v_sub_u32_e32 v99, v110, v99
	v_and_b32_e32 v3, 0xffff0000, v3
	v_sub_u32_e32 v6, v6, v106
	v_add_u32_e32 v99, 0x80, v99
	v_sub_u32_e32 v3, v111, v3
	v_sub_u32_e32 v7, v7, v126
	v_add_u32_e32 v6, 0x80, v6
	v_ashrrev_i32_e32 v99, 8, v99
	v_add_u32_e32 v3, 0x80, v3
	v_add_u32_e32 v7, 0x80, v7
	v_ashrrev_i32_e32 v6, 8, v6
	v_min_i32_e32 v99, 0x7f, v99
	v_ashrrev_i32_e32 v3, 8, v3
	v_ashrrev_i32_e32 v7, 8, v7
	v_min_i32_e32 v6, 0x7f, v6
	v_min_i32_sdwa v3, v3, s78 dst_sel:WORD_1 dst_unused:UNUSED_PAD src0_sel:DWORD src1_sel:DWORD
	v_min_i32_e32 v7, 0x7f, v7
	v_lshlrev_b32_e32 v99, 8, v99
	v_and_b32_e32 v99, 0xff00, v99
	v_and_b32_e32 v3, 0xff0000, v3
	v_perm_b32 v6, v7, v6, s79
	v_or3_b32 v3, v6, v99, v3
	ds_write_b32 v18, v3 offset:16
	ds_read_b64 v[6:7], v19
	v_add_u32_e32 v99, v2, v136
	s_waitcnt lgkmcnt(0)
	v_pk_add_f32 v[106:107], v[114:115], v[6:7] op_sel_hi:[1,0] neg_lo:[0,1] neg_hi:[0,1]
	s_nop 0
	v_pk_mul_f32 v[106:107], v[6:7], v[106:107] op_sel:[1,0]
	v_pk_add_f32 v[110:111], v[120:121], v[6:7] op_sel_hi:[1,0] neg_lo:[0,1] neg_hi:[0,1]
	v_pk_fma_f32 v[106:107], v[122:123], v[106:107], v[130:131]
	v_pk_mul_f32 v[6:7], v[6:7], v[110:111] op_sel:[1,0]
	v_and_b32_sdwa v3, v107, v216 dst_sel:DWORD dst_unused:UNUSED_PAD src0_sel:WORD_1 src1_sel:DWORD
	v_pk_fma_f32 v[0:1], v[0:1], v[6:7], v[4:5]
	v_and_b32_sdwa v4, v106, v216 dst_sel:DWORD dst_unused:UNUSED_PAD src0_sel:WORD_1 src1_sel:DWORD
	v_add3_u32 v4, v106, v4, s77
	v_and_b32_e32 v6, 0xffff0000, v4
	v_and_b32_sdwa v4, v1, v216 dst_sel:DWORD dst_unused:UNUSED_PAD src0_sel:WORD_1 src1_sel:DWORD
	v_and_b32_sdwa v5, v0, v216 dst_sel:DWORD dst_unused:UNUSED_PAD src0_sel:WORD_1 src1_sel:DWORD
	v_add3_u32 v4, v1, v4, s77
	v_add3_u32 v7, v0, v5, s77
	v_add3_u32 v3, v107, v3, s77
	v_and_b32_e32 v109, 0xffff0000, v4
	v_and_b32_e32 v2, 0xffff0000, v7
	v_or_b32_sdwa v5, v109, v3 dst_sel:DWORD dst_unused:UNUSED_PAD src0_sel:DWORD src1_sel:WORD_1
	v_sub_u32_e32 v0, v0, v2
	v_sub_u32_e32 v2, v106, v6
	v_and_b32_e32 v3, 0xffff0000, v3
	v_add_u32_e32 v2, 0x80, v2
	v_sub_u32_e32 v3, v107, v3
	v_sub_u32_e32 v1, v1, v109
	v_add_u32_e32 v0, 0x80, v0
	v_ashrrev_i32_e32 v2, 8, v2
	v_add_u32_e32 v3, 0x80, v3
	v_add_u32_e32 v1, 0x80, v1
	v_ashrrev_i32_e32 v0, 8, v0
	v_min_i32_e32 v2, 0x7f, v2
	v_ashrrev_i32_e32 v3, 8, v3
	v_ashrrev_i32_e32 v1, 8, v1
	v_min_i32_e32 v0, 0x7f, v0
	v_min_i32_sdwa v3, v3, s78 dst_sel:WORD_1 dst_unused:UNUSED_PAD src0_sel:DWORD src1_sel:DWORD
	v_min_i32_e32 v1, 0x7f, v1
	v_lshlrev_b32_e32 v2, 8, v2
	v_and_b32_e32 v2, 0xff00, v2
	v_and_b32_e32 v3, 0xff0000, v3
	v_perm_b32 v0, v1, v0, s79
	v_or_b32_sdwa v4, v7, v6 dst_sel:DWORD dst_unused:UNUSED_PAD src0_sel:WORD_1 src1_sel:DWORD
	v_or3_b32 v0, v0, v2, v3
	ds_write_b64 v99, v[4:5]
	ds_write_b32 v22, v0 offset:16
	v_mov_b32_e32 v0, v228
	v_mov_b32_e32 v1, v229
	v_mov_b32_e32 v2, v230
	v_mov_b32_e32 v3, v231
	v_mov_b32_e32 v4, v244
	v_mov_b32_e32 v5, v245
	v_mov_b32_e32 v6, v246
	v_mov_b32_e32 v7, v247
	ds_read_b64 v[106:107], v149
	v_or_b32_e32 v109, 0x100, v154
	s_waitcnt lgkmcnt(0)
;     ...
;             _Pragma("unroll") for (int m = 0; m < 4; ++m) {
;               const int rr = wr3 * 64 + m * 16 + fr3;
;               const float2 ms = *reinterpret_cast<const float2*>(mr + (ai * HALF + rr) * 2);
;               f32x4 y = acc[ai][bj][m][n];
;               const float o0 = (y[0] - ms.x) * ms.y * gm.x + bt.x, o1 = (y[1] - ms.x) * ms.y * gm.y + bt.y;
;               const float o2 = (y[2] - ms.x) * ms.y * gm.z + bt.z, o3 = (y[3] - ms.x) * ms.y * gm.w + bt.w;
;               const unsigned h0 = f2bf(o0), h1 = f2bf(o1), h2 = f2bf(o2), h3 = f2bf(o3);
;               u32x2 ob; ob[0] = h0 | (h1 << 16); ob[1] = h2 | (h3 << 16);
;               *reinterpret_cast<u32x2*>(smem + (rr >> 1) * PIECE + (rr & 1) * 512 + cc * 2) = ob;
;               const int l0 = min(((int)__float_as_uint(o0) - (int)(h0 << 16) + 128) >> 8, 127);
;               const int l1 = min(((int)__float_as_uint(o1) - (int)(h1 << 16) + 128) >> 8, 127);
;               const int l2 = min(((int)__float_as_uint(o2) - (int)(h2 << 16) + 128) >> 8, 127);
;               const int l3 = min(((int)__float_as_uint(o3) - (int)(h3 << 16) + 128) >> 8, 127);
;               *reinterpret_cast<unsigned*>(smem + LOBASE + (rr >> 2) * PIECE + (rr & 3) * 256 + cc) =
;                   (unsigned)(l0 & 255) | ((unsigned)(l1 & 255) << 8) | ((unsigned)(l2 & 255) << 16) | ((unsigned)l3 << 24);
;             }
	v_pk_add_f32 v[120:121], v[124:125], v[106:107] op_sel_hi:[1,0] neg_lo:[0,1] neg_hi:[0,1]
	s_nop 0
	v_pk_mul_f32 v[120:121], v[106:107], v[120:121] op_sel:[1,0]
	v_pk_add_f32 v[118:119], v[118:119], v[106:107] op_sel_hi:[1,0] neg_lo:[0,1] neg_hi:[0,1]
	v_mov_b32_e32 v110, v1
	v_mov_b32_e32 v111, v2
	v_mov_b32_e32 v114, v5
	v_mov_b32_e32 v115, v6
	v_pk_fma_f32 v[120:121], v[110:111], v[120:121], v[114:115]
	v_pk_mul_f32 v[106:107], v[106:107], v[118:119] op_sel:[1,0]
	v_mov_b32_e32 v1, v3
	v_mov_b32_e32 v5, v7
	v_and_b32_sdwa v6, v121, v216 dst_sel:DWORD dst_unused:UNUSED_PAD src0_sel:WORD_1 src1_sel:DWORD
	v_and_b32_sdwa v7, v120, v216 dst_sel:DWORD dst_unused:UNUSED_PAD src0_sel:WORD_1 src1_sel:DWORD
	v_pk_fma_f32 v[2:3], v[0:1], v[106:107], v[4:5]
	v_add3_u32 v107, v121, v6, s77
	v_add3_u32 v6, v120, v7, s77
	v_and_b32_e32 v118, 0xffff0000, v6
	v_and_b32_sdwa v6, v3, v216 dst_sel:DWORD dst_unused:UNUSED_PAD src0_sel:WORD_1 src1_sel:DWORD
	v_and_b32_sdwa v7, v2, v216 dst_sel:DWORD dst_unused:UNUSED_PAD src0_sel:WORD_1 src1_sel:DWORD
	v_add3_u32 v6, v3, v6, s77
	v_add3_u32 v119, v2, v7, s77
	v_and_b32_e32 v122, 0xffff0000, v6
	v_or_b32_sdwa v7, v122, v107 dst_sel:DWORD dst_unused:UNUSED_PAD src0_sel:DWORD src1_sel:WORD_1
	v_or_b32_sdwa v6, v119, v118 dst_sel:DWORD dst_unused:UNUSED_PAD src0_sel:WORD_1 src1_sel:DWORD
	v_add_u32_e32 v106, v109, v152
	ds_write_b64 v106, v[6:7]
	v_and_b32_e32 v6, 0xffff0000, v119
	v_sub_u32_e32 v2, v2, v6
	v_sub_u32_e32 v6, v120, v118
	v_and_b32_e32 v7, 0xffff0000, v107
	v_add_u32_e32 v6, 0x80, v6
	v_sub_u32_e32 v7, v121, v7
	v_sub_u32_e32 v3, v3, v122
	v_add_u32_e32 v2, 0x80, v2
	v_ashrrev_i32_e32 v6, 8, v6
	v_add_u32_e32 v7, 0x80, v7
	v_add_u32_e32 v3, 0x80, v3
	v_ashrrev_i32_e32 v2, 8, v2
	v_min_i32_e32 v6, 0x7f, v6
	v_ashrrev_i32_e32 v7, 8, v7
	v_ashrrev_i32_e32 v3, 8, v3
	v_min_i32_e32 v2, 0x7f, v2
	v_min_i32_sdwa v7, v7, s78 dst_sel:WORD_1 dst_unused:UNUSED_PAD src0_sel:DWORD src1_sel:DWORD
	v_min_i32_e32 v3, 0x7f, v3
	v_lshlrev_b32_e32 v6, 8, v6
	v_and_b32_e32 v6, 0xff00, v6
	v_and_b32_e32 v7, 0xff0000, v7
	v_perm_b32 v2, v3, v2, s79
	v_or3_b32 v2, v2, v6, v7
	ds_write_b32 v12, v2 offset:128
	ds_read_b64 v[2:3], v13
	s_waitcnt lgkmcnt(0)
	v_pk_add_f32 v[6:7], v[102:103], v[2:3] op_sel_hi:[1,0] neg_lo:[0,1] neg_hi:[0,1]
	s_nop 0
	v_pk_mul_f32 v[6:7], v[2:3], v[6:7] op_sel:[1,0]
	v_pk_add_f32 v[102:103], v[104:105], v[2:3] op_sel_hi:[1,0] neg_lo:[0,1] neg_hi:[0,1]
	v_pk_fma_f32 v[6:7], v[110:111], v[6:7], v[114:115]
	v_pk_mul_f32 v[2:3], v[2:3], v[102:103] op_sel:[1,0]
	v_and_b32_sdwa v102, v7, v216 dst_sel:DWORD dst_unused:UNUSED_PAD src0_sel:WORD_1 src1_sel:DWORD
	v_and_b32_sdwa v103, v6, v216 dst_sel:DWORD dst_unused:UNUSED_PAD src0_sel:WORD_1 src1_sel:DWORD
	v_pk_fma_f32 v[2:3], v[0:1], v[2:3], v[4:5]
	v_add3_u32 v107, v7, v102, s77
	v_add3_u32 v102, v6, v103, s77
	v_and_b32_e32 v103, 0xffff0000, v102
	v_and_b32_sdwa v102, v3, v216 dst_sel:DWORD dst_unused:UNUSED_PAD src0_sel:WORD_1 src1_sel:DWORD
	v_and_b32_sdwa v104, v2, v216 dst_sel:DWORD dst_unused:UNUSED_PAD src0_sel:WORD_1 src1_sel:DWORD
	v_add3_u32 v102, v3, v102, s77
	v_add3_u32 v118, v2, v104, s77
	v_and_b32_e32 v119, 0xffff0000, v102
	v_or_b32_sdwa v105, v119, v107 dst_sel:DWORD dst_unused:UNUSED_PAD src0_sel:DWORD src1_sel:WORD_1
	v_or_b32_sdwa v104, v118, v103 dst_sel:DWORD dst_unused:UNUSED_PAD src0_sel:WORD_1 src1_sel:DWORD
	v_add_u32_e32 v102, v109, v153
	ds_write_b64 v102, v[104:105]
	v_and_b32_e32 v104, 0xffff0000, v118
	v_sub_u32_e32 v6, v6, v103
	v_and_b32_e32 v103, 0xffff0000, v107
	v_sub_u32_e32 v2, v2, v104
	v_add_u32_e32 v6, 0x80, v6
	v_sub_u32_e32 v7, v7, v103
	v_sub_u32_e32 v3, v3, v119
	v_add_u32_e32 v2, 0x80, v2
	v_ashrrev_i32_e32 v6, 8, v6
	v_add_u32_e32 v7, 0x80, v7
	v_add_u32_e32 v3, 0x80, v3
	v_ashrrev_i32_e32 v2, 8, v2
	v_min_i32_e32 v6, 0x7f, v6
	v_ashrrev_i32_e32 v7, 8, v7
	v_ashrrev_i32_e32 v3, 8, v3
	v_min_i32_e32 v2, 0x7f, v2
	v_min_i32_sdwa v7, v7, s78 dst_sel:WORD_1 dst_unused:UNUSED_PAD src0_sel:DWORD src1_sel:DWORD
	v_min_i32_e32 v3, 0x7f, v3
	v_lshlrev_b32_e32 v6, 8, v6
	v_and_b32_e32 v6, 0xff00, v6
	v_and_b32_e32 v7, 0xff0000, v7
	v_perm_b32 v2, v3, v2, s79
	v_or3_b32 v2, v2, v6, v7
	ds_write_b32 v14, v2 offset:128
	ds_read_b64 v[2:3], v15
	s_waitcnt lgkmcnt(0)
	v_pk_add_f32 v[6:7], v[92:93], v[2:3] op_sel_hi:[1,0] neg_lo:[0,1] neg_hi:[0,1]
	s_nop 0
	v_pk_mul_f32 v[6:7], v[2:3], v[6:7] op_sel:[1,0]
	v_pk_add_f32 v[88:89], v[88:89], v[2:3] op_sel_hi:[1,0] neg_lo:[0,1] neg_hi:[0,1]
	v_pk_fma_f32 v[6:7], v[110:111], v[6:7], v[114:115]
	v_pk_mul_f32 v[2:3], v[2:3], v[88:89] op_sel:[1,0]
	v_and_b32_sdwa v88, v7, v216 dst_sel:DWORD dst_unused:UNUSED_PAD src0_sel:WORD_1 src1_sel:DWORD
	v_and_b32_sdwa v89, v6, v216 dst_sel:DWORD dst_unused:UNUSED_PAD src0_sel:WORD_1 src1_sel:DWORD
	v_pk_fma_f32 v[2:3], v[0:1], v[2:3], v[4:5]
	v_add3_u32 v93, v7, v88, s77
	v_add3_u32 v88, v6, v89, s77
	v_and_b32_e32 v103, 0xffff0000, v88
	v_and_b32_sdwa v88, v3, v216 dst_sel:DWORD dst_unused:UNUSED_PAD src0_sel:WORD_1 src1_sel:DWORD
	v_and_b32_sdwa v89, v2, v216 dst_sel:DWORD dst_unused:UNUSED_PAD src0_sel:WORD_1 src1_sel:DWORD
	v_add3_u32 v88, v3, v88, s77
	v_add3_u32 v104, v2, v89, s77
	v_and_b32_e32 v105, 0xffff0000, v88
	v_or_b32_sdwa v89, v105, v93 dst_sel:DWORD dst_unused:UNUSED_PAD src0_sel:DWORD src1_sel:WORD_1
	v_or_b32_sdwa v88, v104, v103 dst_sel:DWORD dst_unused:UNUSED_PAD src0_sel:WORD_1 src1_sel:DWORD
	v_add_u32_e32 v92, v109, v137
	ds_write_b64 v92, v[88:89]
	v_and_b32_e32 v88, 0xffff0000, v104
	v_sub_u32_e32 v2, v2, v88
	v_sub_u32_e32 v6, v6, v103
	v_and_b32_e32 v88, 0xffff0000, v93
	v_add_u32_e32 v6, 0x80, v6
	v_sub_u32_e32 v7, v7, v88
	v_sub_u32_e32 v3, v3, v105
	v_add_u32_e32 v2, 0x80, v2
	v_ashrrev_i32_e32 v6, 8, v6
	v_add_u32_e32 v7, 0x80, v7
	v_add_u32_e32 v3, 0x80, v3
	v_ashrrev_i32_e32 v2, 8, v2
	v_min_i32_e32 v6, 0x7f, v6
	v_ashrrev_i32_e32 v7, 8, v7
	v_ashrrev_i32_e32 v3, 8, v3
	v_min_i32_e32 v2, 0x7f, v2
	v_min_i32_sdwa v7, v7, s78 dst_sel:WORD_1 dst_unused:UNUSED_PAD src0_sel:DWORD src1_sel:DWORD
	v_min_i32_e32 v3, 0x7f, v3
	v_lshlrev_b32_e32 v6, 8, v6
	v_and_b32_e32 v6, 0xff00, v6
	v_and_b32_e32 v7, 0xff0000, v7
	v_perm_b32 v2, v3, v2, s79
	v_or3_b32 v2, v2, v6, v7
	ds_write_b32 v18, v2 offset:128
	ds_read_b64 v[2:3], v19
	v_add_u32_e32 v93, v109, v136
	s_waitcnt lgkmcnt(0)
;     ...
;           _Pragma("unroll") for (int bj = 0; bj < 2; ++bj) _Pragma("unroll") for (int n = 0; n < 2; ++n) {
;             const int cc = bj * HALF + wc3 * 32 + n * 16 + fq3 * 4;
;             const float4 gm = *reinterpret_cast<const float4*>(g.gam + pn * BM + cc), bt = *reinterpret_cast<const float4*>(g.bet + pn * BM + cc);
;             _Pragma("unroll") for (int m = 0; m < 4; ++m) {
;               const int rr = wr3 * 64 + m * 16 + fr3;
;               const float2 ms = *reinterpret_cast<const float2*>(mr + (ai * HALF + rr) * 2);
;               f32x4 y = acc[ai][bj][m][n];
;               const float o0 = (y[0] - ms.x) * ms.y * gm.x + bt.x, o1 = (y[1] - ms.x) * ms.y * gm.y + bt.y;
;               const float o2 = (y[2] - ms.x) * ms.y * gm.z + bt.z, o3 = (y[3] - ms.x) * ms.y * gm.w + bt.w;
;               const unsigned h0 = f2bf(o0), h1 = f2bf(o1), h2 = f2bf(o2), h3 = f2bf(o3);
;               u32x2 ob; ob[0] = h0 | (h1 << 16); ob[1] = h2 | (h3 << 16);
;               *reinterpret_cast<u32x2*>(smem + (rr >> 1) * PIECE + (rr & 1) * 512 + cc * 2) = ob;
;               const int l0 = min(((int)__float_as_uint(o0) - (int)(h0 << 16) + 128) >> 8, 127);
;               const int l1 = min(((int)__float_as_uint(o1) - (int)(h1 << 16) + 128) >> 8, 127);
;               const int l2 = min(((int)__float_as_uint(o2) - (int)(h2 << 16) + 128) >> 8, 127);
;               const int l3 = min(((int)__float_as_uint(o3) - (int)(h3 << 16) + 128) >> 8, 127);
;               *reinterpret_cast<unsigned*>(smem + LOBASE + (rr >> 2) * PIECE + (rr & 3) * 256 + cc) =
;                   (unsigned)(l0 & 255) | ((unsigned)(l1 & 255) << 8) | ((unsigned)(l2 & 255) << 16) | ((unsigned)l3 << 24);
;             }
	v_pk_add_f32 v[6:7], v[90:91], v[2:3] op_sel_hi:[1,0] neg_lo:[0,1] neg_hi:[0,1]
	s_nop 0
	v_pk_mul_f32 v[6:7], v[2:3], v[6:7] op_sel:[1,0]
	v_pk_add_f32 v[88:89], v[94:95], v[2:3] op_sel_hi:[1,0] neg_lo:[0,1] neg_hi:[0,1]
	v_pk_fma_f32 v[6:7], v[110:111], v[6:7], v[114:115]
	v_pk_mul_f32 v[2:3], v[2:3], v[88:89] op_sel:[1,0]
	s_nop 0
	v_pk_fma_f32 v[0:1], v[0:1], v[2:3], v[4:5]
	v_and_b32_sdwa v2, v7, v216 dst_sel:DWORD dst_unused:UNUSED_PAD src0_sel:WORD_1 src1_sel:DWORD
	v_and_b32_sdwa v3, v6, v216 dst_sel:DWORD dst_unused:UNUSED_PAD src0_sel:WORD_1 src1_sel:DWORD
	v_add3_u32 v4, v7, v2, s77
	v_add3_u32 v2, v6, v3, s77
	v_and_b32_e32 v5, 0xffff0000, v2
	v_and_b32_sdwa v2, v1, v216 dst_sel:DWORD dst_unused:UNUSED_PAD src0_sel:WORD_1 src1_sel:DWORD
	v_and_b32_sdwa v3, v0, v216 dst_sel:DWORD dst_unused:UNUSED_PAD src0_sel:WORD_1 src1_sel:DWORD
	v_add3_u32 v2, v1, v2, s77
	v_add3_u32 v88, v0, v3, s77
	v_and_b32_e32 v89, 0xffff0000, v2
	v_or_b32_sdwa v3, v89, v4 dst_sel:DWORD dst_unused:UNUSED_PAD src0_sel:DWORD src1_sel:WORD_1
	v_or_b32_sdwa v2, v88, v5 dst_sel:DWORD dst_unused:UNUSED_PAD src0_sel:WORD_1 src1_sel:DWORD
	ds_write_b64 v93, v[2:3]
	v_and_b32_e32 v2, 0xffff0000, v88
	v_sub_u32_e32 v0, v0, v2
	v_sub_u32_e32 v2, v6, v5
	v_and_b32_e32 v3, 0xffff0000, v4
	v_add_u32_e32 v2, 0x80, v2
	v_sub_u32_e32 v3, v7, v3
	v_sub_u32_e32 v1, v1, v89
	v_add_u32_e32 v0, 0x80, v0
	v_ashrrev_i32_e32 v2, 8, v2
	v_add_u32_e32 v3, 0x80, v3
	v_add_u32_e32 v1, 0x80, v1
	v_ashrrev_i32_e32 v0, 8, v0
	v_min_i32_e32 v2, 0x7f, v2
	v_ashrrev_i32_e32 v3, 8, v3
	v_ashrrev_i32_e32 v1, 8, v1
	v_min_i32_e32 v0, 0x7f, v0
	v_min_i32_sdwa v3, v3, s78 dst_sel:WORD_1 dst_unused:UNUSED_PAD src0_sel:DWORD src1_sel:DWORD
	v_min_i32_e32 v1, 0x7f, v1
	v_lshlrev_b32_e32 v2, 8, v2
	v_and_b32_e32 v2, 0xff00, v2
	v_and_b32_e32 v3, 0xff0000, v3
	v_perm_b32 v0, v1, v0, s79
	v_or3_b32 v0, v0, v2, v3
	ds_write_b32 v22, v0 offset:128
	v_mov_b32_e32 v0, v232
	v_mov_b32_e32 v1, v233
	v_mov_b32_e32 v2, v234
	v_mov_b32_e32 v3, v235
	v_mov_b32_e32 v4, v248
	v_mov_b32_e32 v5, v249
	v_mov_b32_e32 v6, v250
	v_mov_b32_e32 v7, v251
	ds_read_b64 v[94:95], v149
	s_waitcnt lgkmcnt(0)
	v_pk_add_f32 v[104:105], v[116:117], v[94:95] op_sel_hi:[1,0] neg_lo:[0,1] neg_hi:[0,1]
	s_nop 0
	v_pk_mul_f32 v[104:105], v[94:95], v[104:105] op_sel:[1,0]
	v_pk_add_f32 v[110:111], v[112:113], v[94:95] op_sel_hi:[1,0] neg_lo:[0,1] neg_hi:[0,1]
	v_mov_b32_e32 v88, v1
	v_mov_b32_e32 v89, v2
	v_mov_b32_e32 v90, v5
	v_mov_b32_e32 v91, v6
	v_pk_fma_f32 v[104:105], v[88:89], v[104:105], v[90:91]
	v_pk_mul_f32 v[94:95], v[94:95], v[110:111] op_sel:[1,0]
	v_mov_b32_e32 v1, v3
	v_mov_b32_e32 v5, v7
	v_pk_fma_f32 v[6:7], v[0:1], v[94:95], v[4:5]
	v_and_b32_sdwa v94, v104, v216 dst_sel:DWORD dst_unused:UNUSED_PAD src0_sel:WORD_1 src1_sel:DWORD
	v_add3_u32 v94, v104, v94, s77
	v_and_b32_e32 v95, 0xffff0000, v94
	v_and_b32_sdwa v94, v7, v216 dst_sel:DWORD dst_unused:UNUSED_PAD src0_sel:WORD_1 src1_sel:DWORD
	v_and_b32_sdwa v3, v105, v216 dst_sel:DWORD dst_unused:UNUSED_PAD src0_sel:WORD_1 src1_sel:DWORD
	v_and_b32_sdwa v103, v6, v216 dst_sel:DWORD dst_unused:UNUSED_PAD src0_sel:WORD_1 src1_sel:DWORD
	v_add3_u32 v94, v7, v94, s77
	v_add3_u32 v3, v105, v3, s77
	v_add3_u32 v103, v6, v103, s77
	v_and_b32_e32 v107, 0xffff0000, v94
	v_or_b32_sdwa v111, v107, v3 dst_sel:DWORD dst_unused:UNUSED_PAD src0_sel:DWORD src1_sel:WORD_1
	v_or_b32_sdwa v110, v103, v95 dst_sel:DWORD dst_unused:UNUSED_PAD src0_sel:WORD_1 src1_sel:DWORD
	v_and_b32_e32 v103, 0xffff0000, v103
	v_sub_u32_e32 v95, v104, v95
	v_and_b32_e32 v3, 0xffff0000, v3
	v_sub_u32_e32 v6, v6, v103
	v_add_u32_e32 v95, 0x80, v95
	v_sub_u32_e32 v3, v105, v3
	v_sub_u32_e32 v7, v7, v107
	v_add_u32_e32 v6, 0x80, v6
	v_ashrrev_i32_e32 v95, 8, v95
	v_add_u32_e32 v3, 0x80, v3
	v_add_u32_e32 v7, 0x80, v7
	v_ashrrev_i32_e32 v6, 8, v6
	v_min_i32_e32 v95, 0x7f, v95
	v_ashrrev_i32_e32 v3, 8, v3
	v_ashrrev_i32_e32 v7, 8, v7
	v_min_i32_e32 v6, 0x7f, v6
	v_min_i32_sdwa v3, v3, s78 dst_sel:WORD_1 dst_unused:UNUSED_PAD src0_sel:DWORD src1_sel:DWORD
	v_min_i32_e32 v7, 0x7f, v7
	v_lshlrev_b32_e32 v95, 8, v95
	v_or_b32_e32 v2, 0x120, v154
	v_and_b32_e32 v95, 0xff00, v95
	v_and_b32_e32 v3, 0xff0000, v3
	v_perm_b32 v6, v7, v6, s79
	v_add_u32_e32 v94, v2, v152
	v_or3_b32 v3, v6, v95, v3
	ds_write_b64 v94, v[110:111]
	ds_write_b32 v12, v3 offset:144
	ds_read_b64 v[6:7], v13
	s_waitcnt lgkmcnt(0)
	v_pk_add_f32 v[100:101], v[100:101], v[6:7] op_sel_hi:[1,0] neg_lo:[0,1] neg_hi:[0,1]
	s_nop 0
	v_pk_mul_f32 v[100:101], v[6:7], v[100:101] op_sel:[1,0]
	v_pk_add_f32 v[96:97], v[96:97], v[6:7] op_sel_hi:[1,0] neg_lo:[0,1] neg_hi:[0,1]
	v_pk_fma_f32 v[100:101], v[88:89], v[100:101], v[90:91]
	v_pk_mul_f32 v[6:7], v[6:7], v[96:97] op_sel:[1,0]
	v_and_b32_sdwa v95, v100, v216 dst_sel:DWORD dst_unused:UNUSED_PAD src0_sel:WORD_1 src1_sel:DWORD
	v_pk_fma_f32 v[6:7], v[0:1], v[6:7], v[4:5]
	v_add3_u32 v95, v100, v95, s77
	v_and_b32_e32 v103, 0xffff0000, v95
	v_and_b32_sdwa v95, v7, v216 dst_sel:DWORD dst_unused:UNUSED_PAD src0_sel:WORD_1 src1_sel:DWORD
	v_and_b32_sdwa v3, v101, v216 dst_sel:DWORD dst_unused:UNUSED_PAD src0_sel:WORD_1 src1_sel:DWORD
	v_and_b32_sdwa v96, v6, v216 dst_sel:DWORD dst_unused:UNUSED_PAD src0_sel:WORD_1 src1_sel:DWORD
	v_add3_u32 v95, v7, v95, s77
	v_add3_u32 v3, v101, v3, s77
	v_add3_u32 v104, v6, v96, s77
	v_and_b32_e32 v105, 0xffff0000, v95
	v_or_b32_sdwa v97, v105, v3 dst_sel:DWORD dst_unused:UNUSED_PAD src0_sel:DWORD src1_sel:WORD_1
	v_or_b32_sdwa v96, v104, v103 dst_sel:DWORD dst_unused:UNUSED_PAD src0_sel:WORD_1 src1_sel:DWORD
	v_add_u32_e32 v95, v2, v153
	ds_write_b64 v95, v[96:97]
	v_and_b32_e32 v96, 0xffff0000, v104
	v_sub_u32_e32 v6, v6, v96
	v_sub_u32_e32 v96, v100, v103
	v_and_b32_e32 v3, 0xffff0000, v3
	v_add_u32_e32 v96, 0x80, v96
	v_sub_u32_e32 v3, v101, v3
	v_sub_u32_e32 v7, v7, v105
	v_add_u32_e32 v6, 0x80, v6
	v_ashrrev_i32_e32 v96, 8, v96
	v_add_u32_e32 v3, 0x80, v3
	v_add_u32_e32 v7, 0x80, v7
	v_ashrrev_i32_e32 v6, 8, v6
	v_min_i32_e32 v96, 0x7f, v96
	v_ashrrev_i32_e32 v3, 8, v3
	v_ashrrev_i32_e32 v7, 8, v7
	v_min_i32_e32 v6, 0x7f, v6
	v_min_i32_sdwa v3, v3, s78 dst_sel:WORD_1 dst_unused:UNUSED_PAD src0_sel:DWORD src1_sel:DWORD
	v_min_i32_e32 v7, 0x7f, v7
	v_lshlrev_b32_e32 v96, 8, v96
	v_and_b32_e32 v96, 0xff00, v96
	v_and_b32_e32 v3, 0xff0000, v3
	v_perm_b32 v6, v7, v6, s79
	v_or3_b32 v3, v6, v96, v3
	ds_write_b32 v14, v3 offset:144
	ds_read_b64 v[6:7], v15
	s_waitcnt lgkmcnt(0)
; #define WAIT_L(n) asm volatile("s_waitcnt lgkmcnt(" #n ")" ::: "memory")
; #define BAR __builtin_amdgcn_s_barrier()
;     ...
;             _Pragma("unroll") for (int m = 0; m < 4; ++m) {
;               const int rr = wr3 * 64 + m * 16 + fr3;
;               const float2 ms = *reinterpret_cast<const float2*>(mr + (ai * HALF + rr) * 2);
;               f32x4 y = acc[ai][bj][m][n];
;               const float o0 = (y[0] - ms.x) * ms.y * gm.x + bt.x, o1 = (y[1] - ms.x) * ms.y * gm.y + bt.y;
;               const float o2 = (y[2] - ms.x) * ms.y * gm.z + bt.z, o3 = (y[3] - ms.x) * ms.y * gm.w + bt.w;
;               const unsigned h0 = f2bf(o0), h1 = f2bf(o1), h2 = f2bf(o2), h3 = f2bf(o3);
;               u32x2 ob; ob[0] = h0 | (h1 << 16); ob[1] = h2 | (h3 << 16);
;               *reinterpret_cast<u32x2*>(smem + (rr >> 1) * PIECE + (rr & 1) * 512 + cc * 2) = ob;
;               const int l0 = min(((int)__float_as_uint(o0) - (int)(h0 << 16) + 128) >> 8, 127);
;               const int l1 = min(((int)__float_as_uint(o1) - (int)(h1 << 16) + 128) >> 8, 127);
;               const int l2 = min(((int)__float_as_uint(o2) - (int)(h2 << 16) + 128) >> 8, 127);
;               const int l3 = min(((int)__float_as_uint(o3) - (int)(h3 << 16) + 128) >> 8, 127);
;               *reinterpret_cast<unsigned*>(smem + LOBASE + (rr >> 2) * PIECE + (rr & 3) * 256 + cc) =
;                   (unsigned)(l0 & 255) | ((unsigned)(l1 & 255) << 8) | ((unsigned)(l2 & 255) << 16) | ((unsigned)l3 << 24);
;             }
;           }
;           WAIT_L(0); BAR;
;           const int hso = ((brow + ai * HALF + 16 * wave) * DM + pn * BM) * 2;
;           const int lso = (brow + ai * HALF + 16 * wave) * DM + pn * BM;
;           _Pragma("unroll") for (int i = 0; i < 8; ++i) {
;             const u32x4 v = *reinterpret_cast<const u32x4*>(smem + (wave * 8 + i) * PIECE + lane3 * 16);
;             __builtin_amdgcn_raw_buffer_store_b128(v, rsXB, hvo + i * (2 * DM * 2), hso, 0);
;           }
;           _Pragma("unroll") for (int i = 0; i < 4; ++i) {
;             const u32x4 v = *reinterpret_cast<const u32x4*>(smem + LOBASE + (wave * 4 + i) * PIECE + lane3 * 16);
;             __builtin_amdgcn_raw_buffer_store_b128(v, rsLO, lvo + i * (4 * DM), lso, 0);
;           }
	v_pk_add_f32 v[84:85], v[84:85], v[6:7] op_sel_hi:[1,0] neg_lo:[0,1] neg_hi:[0,1]
	s_nop 0
	v_pk_mul_f32 v[84:85], v[6:7], v[84:85] op_sel:[1,0]
	v_pk_add_f32 v[80:81], v[80:81], v[6:7] op_sel_hi:[1,0] neg_lo:[0,1] neg_hi:[0,1]
	v_pk_fma_f32 v[84:85], v[88:89], v[84:85], v[90:91]
	v_pk_mul_f32 v[6:7], v[6:7], v[80:81] op_sel:[1,0]
	v_and_b32_sdwa v80, v84, v216 dst_sel:DWORD dst_unused:UNUSED_PAD src0_sel:WORD_1 src1_sel:DWORD
	v_pk_fma_f32 v[6:7], v[0:1], v[6:7], v[4:5]
	v_add3_u32 v80, v84, v80, s77
	v_and_b32_e32 v81, 0xffff0000, v80
	v_and_b32_sdwa v80, v7, v216 dst_sel:DWORD dst_unused:UNUSED_PAD src0_sel:WORD_1 src1_sel:DWORD
	v_and_b32_sdwa v3, v85, v216 dst_sel:DWORD dst_unused:UNUSED_PAD src0_sel:WORD_1 src1_sel:DWORD
	v_and_b32_sdwa v96, v6, v216 dst_sel:DWORD dst_unused:UNUSED_PAD src0_sel:WORD_1 src1_sel:DWORD
	v_add3_u32 v80, v7, v80, s77
	v_add3_u32 v3, v85, v3, s77
	v_add3_u32 v100, v6, v96, s77
	v_and_b32_e32 v101, 0xffff0000, v80
	v_or_b32_sdwa v97, v101, v3 dst_sel:DWORD dst_unused:UNUSED_PAD src0_sel:DWORD src1_sel:WORD_1
	v_or_b32_sdwa v96, v100, v81 dst_sel:DWORD dst_unused:UNUSED_PAD src0_sel:WORD_1 src1_sel:DWORD
	v_add_u32_e32 v80, v2, v137
	ds_write_b64 v80, v[96:97]
	v_and_b32_e32 v96, 0xffff0000, v100
	v_sub_u32_e32 v81, v84, v81
	v_and_b32_e32 v3, 0xffff0000, v3
	v_sub_u32_e32 v6, v6, v96
	v_add_u32_e32 v81, 0x80, v81
	v_sub_u32_e32 v3, v85, v3
	v_sub_u32_e32 v7, v7, v101
	v_add_u32_e32 v6, 0x80, v6
	v_ashrrev_i32_e32 v81, 8, v81
	v_add_u32_e32 v3, 0x80, v3
	v_add_u32_e32 v7, 0x80, v7
	v_ashrrev_i32_e32 v6, 8, v6
	v_min_i32_e32 v81, 0x7f, v81
	v_ashrrev_i32_e32 v3, 8, v3
	v_ashrrev_i32_e32 v7, 8, v7
	v_min_i32_e32 v6, 0x7f, v6
	v_min_i32_sdwa v3, v3, s78 dst_sel:WORD_1 dst_unused:UNUSED_PAD src0_sel:DWORD src1_sel:DWORD
	v_min_i32_e32 v7, 0x7f, v7
	v_lshlrev_b32_e32 v81, 8, v81
	v_and_b32_e32 v81, 0xff00, v81
	v_and_b32_e32 v3, 0xff0000, v3
	v_perm_b32 v6, v7, v6, s79
	v_or3_b32 v3, v6, v81, v3
	ds_write_b32 v18, v3 offset:144
	ds_read_b64 v[6:7], v19
	v_or_b32_e32 v81, 0x6000, v148
	v_or_b32_e32 v96, 0x6000, v146
	s_waitcnt lgkmcnt(0)
	v_pk_add_f32 v[72:73], v[72:73], v[6:7] op_sel_hi:[1,0] neg_lo:[0,1] neg_hi:[0,1]
	s_nop 0
	v_pk_mul_f32 v[72:73], v[6:7], v[72:73] op_sel:[1,0]
	s_nop 0
	v_pk_fma_f32 v[84:85], v[88:89], v[72:73], v[90:91]
	v_pk_add_f32 v[72:73], v[74:75], v[6:7] op_sel_hi:[1,0] neg_lo:[0,1] neg_hi:[0,1]
	v_and_b32_sdwa v3, v85, v216 dst_sel:DWORD dst_unused:UNUSED_PAD src0_sel:WORD_1 src1_sel:DWORD
	v_pk_mul_f32 v[6:7], v[6:7], v[72:73] op_sel:[1,0]
	v_add3_u32 v3, v85, v3, s77
	v_pk_fma_f32 v[0:1], v[0:1], v[6:7], v[4:5]
	v_and_b32_sdwa v4, v84, v216 dst_sel:DWORD dst_unused:UNUSED_PAD src0_sel:WORD_1 src1_sel:DWORD
	v_add3_u32 v4, v84, v4, s77
	v_and_b32_e32 v6, 0xffff0000, v4
	v_and_b32_sdwa v4, v1, v216 dst_sel:DWORD dst_unused:UNUSED_PAD src0_sel:WORD_1 src1_sel:DWORD
	v_and_b32_sdwa v5, v0, v216 dst_sel:DWORD dst_unused:UNUSED_PAD src0_sel:WORD_1 src1_sel:DWORD
	v_add3_u32 v4, v1, v4, s77
	v_add3_u32 v7, v0, v5, s77
	v_and_b32_e32 v72, 0xffff0000, v4
	v_add_u32_e32 v73, v2, v136
	v_and_b32_e32 v2, 0xffff0000, v7
	v_or_b32_sdwa v5, v72, v3 dst_sel:DWORD dst_unused:UNUSED_PAD src0_sel:DWORD src1_sel:WORD_1
	v_sub_u32_e32 v0, v0, v2
	v_sub_u32_e32 v2, v84, v6
	v_and_b32_e32 v3, 0xffff0000, v3
	v_add_u32_e32 v2, 0x80, v2
	v_sub_u32_e32 v3, v85, v3
	v_sub_u32_e32 v1, v1, v72
	v_add_u32_e32 v0, 0x80, v0
	v_ashrrev_i32_e32 v2, 8, v2
	v_add_u32_e32 v3, 0x80, v3
	v_add_u32_e32 v1, 0x80, v1
	v_ashrrev_i32_e32 v0, 8, v0
	v_min_i32_e32 v2, 0x7f, v2
	v_ashrrev_i32_e32 v3, 8, v3
	v_ashrrev_i32_e32 v1, 8, v1
	v_min_i32_e32 v0, 0x7f, v0
	v_min_i32_sdwa v3, v3, s78 dst_sel:WORD_1 dst_unused:UNUSED_PAD src0_sel:DWORD src1_sel:DWORD
	v_min_i32_e32 v1, 0x7f, v1
	v_lshlrev_b32_e32 v2, 8, v2
	v_and_b32_e32 v2, 0xff00, v2
	v_and_b32_e32 v3, 0xff0000, v3
	v_perm_b32 v0, v1, v0, s79
	v_or_b32_sdwa v4, v7, v6 dst_sel:DWORD dst_unused:UNUSED_PAD src0_sel:WORD_1 src1_sel:DWORD
	v_or3_b32 v0, v0, v2, v3
	ds_write_b64 v73, v[4:5]
	ds_write_b32 v22, v0 offset:144
	v_add_u32_e32 v72, s59, v151
	s_waitcnt lgkmcnt(0)
	s_barrier
	ds_read_b128 v[128:131], v72
	v_or_b32_e32 v74, 0x2000, v148
	v_or_b32_e32 v75, 0x4000, v148
	v_or_b32_e32 v84, 0x8000, v148
	v_or_b32_e32 v85, 0xa000, v148
	ds_read_b128 v[136:139], v72 offset:1040
	v_or_b32_e32 v88, 0xc000, v148
	v_or_b32_e32 v89, 0xe000, v148
	v_or_b32_e32 v90, 0x2000, v146
	v_or_b32_e32 v91, 0x4000, v146
	ds_read_b128 v[140:143], v72 offset:2080
	ds_read_b128 v[152:155], v72 offset:3120
	ds_read_b128 v[156:159], v72 offset:4160
	ds_read_b128 v[160:163], v72 offset:5200
	ds_read_b128 v[164:167], v72 offset:6240
	ds_read_b128 v[168:171], v72 offset:7280
	ds_read_b128 v[172:175], v147
	ds_read_b128 v[176:179], v147 offset:1040
	ds_read_b128 v[180:183], v147 offset:2080
	ds_read_b128 v[184:187], v147 offset:3120
	s_waitcnt lgkmcnt(0)
	s_barrier
;     ...
;           _Pragma("unroll") for (int bj = 0; bj < 2; ++bj) _Pragma("unroll") for (int n = 0; n < 2; ++n) {
;             const int cc = bj * HALF + wc3 * 32 + n * 16 + fq3 * 4;
;             const float4 gm = *reinterpret_cast<const float4*>(g.gam + pn * BM + cc), bt = *reinterpret_cast<const float4*>(g.bet + pn * BM + cc);
;             _Pragma("unroll") for (int m = 0; m < 4; ++m) {
;               const int rr = wr3 * 64 + m * 16 + fr3;
;               const float2 ms = *reinterpret_cast<const float2*>(mr + (ai * HALF + rr) * 2);
;               f32x4 y = acc[ai][bj][m][n];
;               const float o0 = (y[0] - ms.x) * ms.y * gm.x + bt.x, o1 = (y[1] - ms.x) * ms.y * gm.y + bt.y;
;               const float o2 = (y[2] - ms.x) * ms.y * gm.z + bt.z, o3 = (y[3] - ms.x) * ms.y * gm.w + bt.w;
;               const unsigned h0 = f2bf(o0), h1 = f2bf(o1), h2 = f2bf(o2), h3 = f2bf(o3);
;               u32x2 ob; ob[0] = h0 | (h1 << 16); ob[1] = h2 | (h3 << 16);
;               *reinterpret_cast<u32x2*>(smem + (rr >> 1) * PIECE + (rr & 1) * 512 + cc * 2) = ob;
;               const int l0 = min(((int)__float_as_uint(o0) - (int)(h0 << 16) + 128) >> 8, 127);
;               const int l1 = min(((int)__float_as_uint(o1) - (int)(h1 << 16) + 128) >> 8, 127);
;               const int l2 = min(((int)__float_as_uint(o2) - (int)(h2 << 16) + 128) >> 8, 127);
;               const int l3 = min(((int)__float_as_uint(o3) - (int)(h3 << 16) + 128) >> 8, 127);
;               *reinterpret_cast<unsigned*>(smem + LOBASE + (rr >> 2) * PIECE + (rr & 3) * 256 + cc) =
;                   (unsigned)(l0 & 255) | ((unsigned)(l1 & 255) << 8) | ((unsigned)(l2 & 255) << 16) | ((unsigned)l3 << 24);
;             }
;     ...
;           _Pragma("unroll") for (int i = 0; i < 8; ++i) {
;             const u32x4 v = *reinterpret_cast<const u32x4*>(smem + (wave * 8 + i) * PIECE + lane3 * 16);
;             __builtin_amdgcn_raw_buffer_store_b128(v, rsXB, hvo + i * (2 * DM * 2), hso, 0);
;           }
;           _Pragma("unroll") for (int i = 0; i < 4; ++i) {
;             const u32x4 v = *reinterpret_cast<const u32x4*>(smem + LOBASE + (wave * 4 + i) * PIECE + lane3 * 16);
;             __builtin_amdgcn_raw_buffer_store_b128(v, rsLO, lvo + i * (4 * DM), lso, 0);
;           }
	s_nop 1
	v_mov_b32_e32 v0, v220
	v_mov_b32_e32 v1, v221
	v_mov_b32_e32 v2, v222
	v_mov_b32_e32 v3, v223
	v_mov_b32_e32 v4, v236
	v_mov_b32_e32 v5, v237
	v_mov_b32_e32 v6, v238
	v_mov_b32_e32 v7, v239
	ds_read_b64 v[110:111], v149 offset:1024
	s_waitcnt lgkmcnt(0)
	v_pk_add_f32 v[64:65], v[64:65], v[110:111] op_sel_hi:[1,0] neg_lo:[0,1] neg_hi:[0,1]
	s_nop 0
	v_pk_mul_f32 v[64:65], v[110:111], v[64:65] op_sel:[1,0]
	v_pk_add_f32 v[66:67], v[66:67], v[110:111] op_sel_hi:[1,0] neg_lo:[0,1] neg_hi:[0,1]
	v_mov_b32_e32 v100, v1
	v_mov_b32_e32 v101, v2
	v_mov_b32_e32 v104, v5
	v_mov_b32_e32 v105, v6
	v_pk_fma_f32 v[64:65], v[100:101], v[64:65], v[104:105]
	v_pk_mul_f32 v[66:67], v[110:111], v[66:67] op_sel:[1,0]
	v_mov_b32_e32 v1, v3
	v_mov_b32_e32 v5, v7
	v_and_b32_sdwa v6, v65, v216 dst_sel:DWORD dst_unused:UNUSED_PAD src0_sel:WORD_1 src1_sel:DWORD
	v_and_b32_sdwa v7, v64, v216 dst_sel:DWORD dst_unused:UNUSED_PAD src0_sel:WORD_1 src1_sel:DWORD
	v_pk_fma_f32 v[2:3], v[0:1], v[66:67], v[4:5]
	v_add3_u32 v66, v65, v6, s77
	v_add3_u32 v6, v64, v7, s77
	v_and_b32_e32 v67, 0xffff0000, v6
	v_and_b32_sdwa v6, v3, v216 dst_sel:DWORD dst_unused:UNUSED_PAD src0_sel:WORD_1 src1_sel:DWORD
	v_and_b32_sdwa v7, v2, v216 dst_sel:DWORD dst_unused:UNUSED_PAD src0_sel:WORD_1 src1_sel:DWORD
	v_add3_u32 v6, v3, v6, s77
	v_add3_u32 v97, v2, v7, s77
	v_and_b32_e32 v103, 0xffff0000, v6
	v_or_b32_sdwa v7, v103, v66 dst_sel:DWORD dst_unused:UNUSED_PAD src0_sel:DWORD src1_sel:WORD_1
	v_or_b32_sdwa v6, v97, v67 dst_sel:DWORD dst_unused:UNUSED_PAD src0_sel:WORD_1 src1_sel:DWORD
	ds_write_b64 v132, v[6:7]
	v_and_b32_e32 v6, 0xffff0000, v97
	v_sub_u32_e32 v2, v2, v6
	v_sub_u32_e32 v6, v64, v67
	v_and_b32_e32 v7, 0xffff0000, v66
	v_add_u32_e32 v6, 0x80, v6
	v_sub_u32_e32 v7, v65, v7
	v_sub_u32_e32 v3, v3, v103
	v_add_u32_e32 v2, 0x80, v2
	v_ashrrev_i32_e32 v6, 8, v6
	v_add_u32_e32 v7, 0x80, v7
	v_add_u32_e32 v3, 0x80, v3
	v_ashrrev_i32_e32 v2, 8, v2
	v_min_i32_e32 v6, 0x7f, v6
	v_ashrrev_i32_e32 v7, 8, v7
	v_ashrrev_i32_e32 v3, 8, v3
	v_min_i32_e32 v2, 0x7f, v2
	v_min_i32_sdwa v7, v7, s78 dst_sel:WORD_1 dst_unused:UNUSED_PAD src0_sel:DWORD src1_sel:DWORD
	v_min_i32_e32 v3, 0x7f, v3
	v_lshlrev_b32_e32 v6, 8, v6
	v_and_b32_e32 v6, 0xff00, v6
	v_and_b32_e32 v7, 0xff0000, v7
	v_perm_b32 v2, v3, v2, s79
	v_or3_b32 v2, v2, v6, v7
	ds_write_b32 v12, v2
	buffer_store_dwordx4 v[128:131], v148, s[16:19], s76 offen
	ds_read_b64 v[2:3], v13 offset:1024
	s_waitcnt lgkmcnt(0)
	v_pk_add_f32 v[6:7], v[68:69], v[2:3] op_sel_hi:[1,0] neg_lo:[0,1] neg_hi:[0,1]
	s_nop 0
	v_pk_mul_f32 v[6:7], v[2:3], v[6:7] op_sel:[1,0]
	v_pk_add_f32 v[64:65], v[70:71], v[2:3] op_sel_hi:[1,0] neg_lo:[0,1] neg_hi:[0,1]
	v_pk_fma_f32 v[6:7], v[100:101], v[6:7], v[104:105]
	v_pk_mul_f32 v[2:3], v[2:3], v[64:65] op_sel:[1,0]
	v_and_b32_sdwa v64, v7, v216 dst_sel:DWORD dst_unused:UNUSED_PAD src0_sel:WORD_1 src1_sel:DWORD
	v_and_b32_sdwa v65, v6, v216 dst_sel:DWORD dst_unused:UNUSED_PAD src0_sel:WORD_1 src1_sel:DWORD
	v_pk_fma_f32 v[2:3], v[0:1], v[2:3], v[4:5]
	v_add3_u32 v66, v7, v64, s77
	v_add3_u32 v64, v6, v65, s77
	v_and_b32_e32 v67, 0xffff0000, v64
	v_and_b32_sdwa v64, v3, v216 dst_sel:DWORD dst_unused:UNUSED_PAD src0_sel:WORD_1 src1_sel:DWORD
	v_and_b32_sdwa v65, v2, v216 dst_sel:DWORD dst_unused:UNUSED_PAD src0_sel:WORD_1 src1_sel:DWORD
	v_add3_u32 v64, v3, v64, s77
	v_add3_u32 v68, v2, v65, s77
	v_and_b32_e32 v69, 0xffff0000, v64
	v_or_b32_sdwa v65, v69, v66 dst_sel:DWORD dst_unused:UNUSED_PAD src0_sel:DWORD src1_sel:WORD_1
	v_or_b32_sdwa v64, v68, v67 dst_sel:DWORD dst_unused:UNUSED_PAD src0_sel:WORD_1 src1_sel:DWORD
	ds_write_b64 v133, v[64:65]
	v_and_b32_e32 v64, 0xffff0000, v68
	v_sub_u32_e32 v2, v2, v64
	v_sub_u32_e32 v6, v6, v67
	v_and_b32_e32 v64, 0xffff0000, v66
	v_add_u32_e32 v6, 0x80, v6
	v_sub_u32_e32 v7, v7, v64
	v_sub_u32_e32 v3, v3, v69
	v_add_u32_e32 v2, 0x80, v2
	v_ashrrev_i32_e32 v6, 8, v6
	v_add_u32_e32 v7, 0x80, v7
	v_add_u32_e32 v3, 0x80, v3
	v_ashrrev_i32_e32 v2, 8, v2
	v_min_i32_e32 v6, 0x7f, v6
	v_ashrrev_i32_e32 v7, 8, v7
	v_ashrrev_i32_e32 v3, 8, v3
	v_min_i32_e32 v2, 0x7f, v2
	v_min_i32_sdwa v7, v7, s78 dst_sel:WORD_1 dst_unused:UNUSED_PAD src0_sel:DWORD src1_sel:DWORD
	v_min_i32_e32 v3, 0x7f, v3
	v_lshlrev_b32_e32 v6, 8, v6
	v_and_b32_e32 v6, 0xff00, v6
	v_and_b32_e32 v7, 0xff0000, v7
	v_perm_b32 v2, v3, v2, s79
	v_or3_b32 v2, v2, v6, v7
	ds_write_b32 v14, v2
	buffer_store_dwordx4 v[136:139], v74, s[16:19], s76 offen
	ds_read_b64 v[2:3], v15 offset:1024
	s_waitcnt lgkmcnt(0)
	v_pk_add_f32 v[6:7], v[76:77], v[2:3] op_sel_hi:[1,0] neg_lo:[0,1] neg_hi:[0,1]
	s_nop 0
	v_pk_mul_f32 v[6:7], v[2:3], v[6:7] op_sel:[1,0]
	v_pk_add_f32 v[64:65], v[78:79], v[2:3] op_sel_hi:[1,0] neg_lo:[0,1] neg_hi:[0,1]
	v_pk_fma_f32 v[6:7], v[100:101], v[6:7], v[104:105]
	v_pk_mul_f32 v[2:3], v[2:3], v[64:65] op_sel:[1,0]
	v_and_b32_sdwa v64, v7, v216 dst_sel:DWORD dst_unused:UNUSED_PAD src0_sel:WORD_1 src1_sel:DWORD
	v_and_b32_sdwa v65, v6, v216 dst_sel:DWORD dst_unused:UNUSED_PAD src0_sel:WORD_1 src1_sel:DWORD
	v_pk_fma_f32 v[2:3], v[0:1], v[2:3], v[4:5]
	v_add3_u32 v66, v7, v64, s77
	v_add3_u32 v64, v6, v65, s77
	v_and_b32_e32 v67, 0xffff0000, v64
	v_and_b32_sdwa v64, v3, v216 dst_sel:DWORD dst_unused:UNUSED_PAD src0_sel:WORD_1 src1_sel:DWORD
	v_and_b32_sdwa v65, v2, v216 dst_sel:DWORD dst_unused:UNUSED_PAD src0_sel:WORD_1 src1_sel:DWORD
	v_add3_u32 v64, v3, v64, s77
	v_add3_u32 v68, v2, v65, s77
	v_and_b32_e32 v69, 0xffff0000, v64
	v_or_b32_sdwa v65, v69, v66 dst_sel:DWORD dst_unused:UNUSED_PAD src0_sel:DWORD src1_sel:WORD_1
	v_or_b32_sdwa v64, v68, v67 dst_sel:DWORD dst_unused:UNUSED_PAD src0_sel:WORD_1 src1_sel:DWORD
	ds_write_b64 v134, v[64:65]
	v_and_b32_e32 v64, 0xffff0000, v68
	v_sub_u32_e32 v2, v2, v64
	v_sub_u32_e32 v6, v6, v67
	v_and_b32_e32 v64, 0xffff0000, v66
	v_add_u32_e32 v6, 0x80, v6
	v_sub_u32_e32 v7, v7, v64
	v_sub_u32_e32 v3, v3, v69
	v_add_u32_e32 v2, 0x80, v2
	v_ashrrev_i32_e32 v6, 8, v6
	v_add_u32_e32 v7, 0x80, v7
	v_add_u32_e32 v3, 0x80, v3
	v_ashrrev_i32_e32 v2, 8, v2
	v_min_i32_e32 v6, 0x7f, v6
	v_ashrrev_i32_e32 v7, 8, v7
	v_ashrrev_i32_e32 v3, 8, v3
	v_min_i32_e32 v2, 0x7f, v2
	v_min_i32_sdwa v7, v7, s78 dst_sel:WORD_1 dst_unused:UNUSED_PAD src0_sel:DWORD src1_sel:DWORD
	v_min_i32_e32 v3, 0x7f, v3
	v_lshlrev_b32_e32 v6, 8, v6
	v_and_b32_e32 v6, 0xff00, v6
	v_and_b32_e32 v7, 0xff0000, v7
	v_perm_b32 v2, v3, v2, s79
	v_or3_b32 v2, v2, v6, v7
	ds_write_b32 v18, v2
	buffer_store_dwordx4 v[140:143], v75, s[16:19], s76 offen
	ds_read_b64 v[2:3], v19 offset:1024
	s_waitcnt lgkmcnt(0)
;     ...
;           _Pragma("unroll") for (int bj = 0; bj < 2; ++bj) _Pragma("unroll") for (int n = 0; n < 2; ++n) {
;             const int cc = bj * HALF + wc3 * 32 + n * 16 + fq3 * 4;
;             const float4 gm = *reinterpret_cast<const float4*>(g.gam + pn * BM + cc), bt = *reinterpret_cast<const float4*>(g.bet + pn * BM + cc);
;             _Pragma("unroll") for (int m = 0; m < 4; ++m) {
;               const int rr = wr3 * 64 + m * 16 + fr3;
;               const float2 ms = *reinterpret_cast<const float2*>(mr + (ai * HALF + rr) * 2);
;               f32x4 y = acc[ai][bj][m][n];
;               const float o0 = (y[0] - ms.x) * ms.y * gm.x + bt.x, o1 = (y[1] - ms.x) * ms.y * gm.y + bt.y;
;               const float o2 = (y[2] - ms.x) * ms.y * gm.z + bt.z, o3 = (y[3] - ms.x) * ms.y * gm.w + bt.w;
;               const unsigned h0 = f2bf(o0), h1 = f2bf(o1), h2 = f2bf(o2), h3 = f2bf(o3);
;               u32x2 ob; ob[0] = h0 | (h1 << 16); ob[1] = h2 | (h3 << 16);
;               *reinterpret_cast<u32x2*>(smem + (rr >> 1) * PIECE + (rr & 1) * 512 + cc * 2) = ob;
;               const int l0 = min(((int)__float_as_uint(o0) - (int)(h0 << 16) + 128) >> 8, 127);
;               const int l1 = min(((int)__float_as_uint(o1) - (int)(h1 << 16) + 128) >> 8, 127);
;               const int l2 = min(((int)__float_as_uint(o2) - (int)(h2 << 16) + 128) >> 8, 127);
;               const int l3 = min(((int)__float_as_uint(o3) - (int)(h3 << 16) + 128) >> 8, 127);
;               *reinterpret_cast<unsigned*>(smem + LOBASE + (rr >> 2) * PIECE + (rr & 3) * 256 + cc) =
;                   (unsigned)(l0 & 255) | ((unsigned)(l1 & 255) << 8) | ((unsigned)(l2 & 255) << 16) | ((unsigned)l3 << 24);
;             }
;     ...
;           _Pragma("unroll") for (int i = 0; i < 8; ++i) {
;             const u32x4 v = *reinterpret_cast<const u32x4*>(smem + (wave * 8 + i) * PIECE + lane3 * 16);
;             __builtin_amdgcn_raw_buffer_store_b128(v, rsXB, hvo + i * (2 * DM * 2), hso, 0);
;           }
;           _Pragma("unroll") for (int i = 0; i < 4; ++i) {
;             const u32x4 v = *reinterpret_cast<const u32x4*>(smem + LOBASE + (wave * 4 + i) * PIECE + lane3 * 16);
;             __builtin_amdgcn_raw_buffer_store_b128(v, rsLO, lvo + i * (4 * DM), lso, 0);
;           }
	v_pk_add_f32 v[6:7], v[82:83], v[2:3] op_sel_hi:[1,0] neg_lo:[0,1] neg_hi:[0,1]
	s_nop 0
	v_pk_mul_f32 v[6:7], v[2:3], v[6:7] op_sel:[1,0]
	v_pk_add_f32 v[64:65], v[86:87], v[2:3] op_sel_hi:[1,0] neg_lo:[0,1] neg_hi:[0,1]
	v_pk_fma_f32 v[6:7], v[100:101], v[6:7], v[104:105]
	v_pk_mul_f32 v[2:3], v[2:3], v[64:65] op_sel:[1,0]
	s_nop 0
	v_pk_fma_f32 v[0:1], v[0:1], v[2:3], v[4:5]
	v_and_b32_sdwa v2, v7, v216 dst_sel:DWORD dst_unused:UNUSED_PAD src0_sel:WORD_1 src1_sel:DWORD
	v_and_b32_sdwa v3, v6, v216 dst_sel:DWORD dst_unused:UNUSED_PAD src0_sel:WORD_1 src1_sel:DWORD
	v_add3_u32 v4, v7, v2, s77
	v_add3_u32 v2, v6, v3, s77
	v_and_b32_e32 v5, 0xffff0000, v2
	v_and_b32_sdwa v2, v1, v216 dst_sel:DWORD dst_unused:UNUSED_PAD src0_sel:WORD_1 src1_sel:DWORD
	v_and_b32_sdwa v3, v0, v216 dst_sel:DWORD dst_unused:UNUSED_PAD src0_sel:WORD_1 src1_sel:DWORD
	v_add3_u32 v2, v1, v2, s77
	v_add3_u32 v64, v0, v3, s77
	v_and_b32_e32 v65, 0xffff0000, v2
	v_or_b32_sdwa v3, v65, v4 dst_sel:DWORD dst_unused:UNUSED_PAD src0_sel:DWORD src1_sel:WORD_1
	v_or_b32_sdwa v2, v64, v5 dst_sel:DWORD dst_unused:UNUSED_PAD src0_sel:WORD_1 src1_sel:DWORD
	ds_write_b64 v135, v[2:3]
	v_and_b32_e32 v2, 0xffff0000, v64
	v_sub_u32_e32 v0, v0, v2
	v_sub_u32_e32 v2, v6, v5
	v_and_b32_e32 v3, 0xffff0000, v4
	v_add_u32_e32 v2, 0x80, v2
	v_sub_u32_e32 v3, v7, v3
	v_sub_u32_e32 v1, v1, v65
	v_add_u32_e32 v0, 0x80, v0
	v_ashrrev_i32_e32 v2, 8, v2
	v_add_u32_e32 v3, 0x80, v3
	v_add_u32_e32 v1, 0x80, v1
	v_ashrrev_i32_e32 v0, 8, v0
	v_min_i32_e32 v2, 0x7f, v2
	v_ashrrev_i32_e32 v3, 8, v3
	v_ashrrev_i32_e32 v1, 8, v1
	v_min_i32_e32 v0, 0x7f, v0
	v_min_i32_sdwa v3, v3, s78 dst_sel:WORD_1 dst_unused:UNUSED_PAD src0_sel:DWORD src1_sel:DWORD
	v_min_i32_e32 v1, 0x7f, v1
	v_lshlrev_b32_e32 v2, 8, v2
	v_and_b32_e32 v2, 0xff00, v2
	v_and_b32_e32 v3, 0xff0000, v3
	v_perm_b32 v0, v1, v0, s79
	v_or3_b32 v0, v0, v2, v3
	ds_write_b32 v22, v0
	buffer_store_dwordx4 v[152:155], v81, s[16:19], s76 offen
	v_mov_b32_e32 v0, v224
	v_mov_b32_e32 v1, v225
	v_mov_b32_e32 v2, v226
	v_mov_b32_e32 v3, v227
	v_mov_b32_e32 v4, v240
	v_mov_b32_e32 v5, v241
	v_mov_b32_e32 v6, v242
	v_mov_b32_e32 v7, v243
	ds_read_b64 v[68:69], v149 offset:1024
	s_waitcnt lgkmcnt(0)
	v_pk_add_f32 v[60:61], v[60:61], v[68:69] op_sel_hi:[1,0] neg_lo:[0,1] neg_hi:[0,1]
	s_nop 0
	v_pk_mul_f32 v[60:61], v[68:69], v[60:61] op_sel:[1,0]
	v_pk_add_f32 v[58:59], v[58:59], v[68:69] op_sel_hi:[1,0] neg_lo:[0,1] neg_hi:[0,1]
	v_mov_b32_e32 v64, v1
	v_mov_b32_e32 v65, v2
	v_mov_b32_e32 v66, v5
	v_mov_b32_e32 v67, v6
	v_pk_fma_f32 v[60:61], v[64:65], v[60:61], v[66:67]
	v_pk_mul_f32 v[58:59], v[68:69], v[58:59] op_sel:[1,0]
	v_mov_b32_e32 v1, v3
	v_mov_b32_e32 v5, v7
	v_and_b32_sdwa v6, v61, v216 dst_sel:DWORD dst_unused:UNUSED_PAD src0_sel:WORD_1 src1_sel:DWORD
	v_and_b32_sdwa v7, v60, v216 dst_sel:DWORD dst_unused:UNUSED_PAD src0_sel:WORD_1 src1_sel:DWORD
	v_pk_fma_f32 v[2:3], v[0:1], v[58:59], v[4:5]
	v_add3_u32 v58, v61, v6, s77
	v_add3_u32 v6, v60, v7, s77
	v_and_b32_e32 v59, 0xffff0000, v6
	v_and_b32_sdwa v6, v3, v216 dst_sel:DWORD dst_unused:UNUSED_PAD src0_sel:WORD_1 src1_sel:DWORD
	v_and_b32_sdwa v7, v2, v216 dst_sel:DWORD dst_unused:UNUSED_PAD src0_sel:WORD_1 src1_sel:DWORD
	v_add3_u32 v6, v3, v6, s77
	v_add3_u32 v68, v2, v7, s77
	v_and_b32_e32 v69, 0xffff0000, v6
	v_or_b32_sdwa v7, v69, v58 dst_sel:DWORD dst_unused:UNUSED_PAD src0_sel:DWORD src1_sel:WORD_1
	v_or_b32_sdwa v6, v68, v59 dst_sel:DWORD dst_unused:UNUSED_PAD src0_sel:WORD_1 src1_sel:DWORD
	ds_write_b64 v23, v[6:7]
	v_and_b32_e32 v6, 0xffff0000, v68
	v_sub_u32_e32 v2, v2, v6
	v_sub_u32_e32 v6, v60, v59
	v_and_b32_e32 v7, 0xffff0000, v58
	v_add_u32_e32 v6, 0x80, v6
	v_sub_u32_e32 v7, v61, v7
	v_sub_u32_e32 v3, v3, v69
	v_add_u32_e32 v2, 0x80, v2
	v_ashrrev_i32_e32 v6, 8, v6
	v_add_u32_e32 v7, 0x80, v7
	v_add_u32_e32 v3, 0x80, v3
	v_ashrrev_i32_e32 v2, 8, v2
	v_min_i32_e32 v6, 0x7f, v6
	v_ashrrev_i32_e32 v7, 8, v7
	v_ashrrev_i32_e32 v3, 8, v3
	v_min_i32_e32 v2, 0x7f, v2
	v_min_i32_sdwa v7, v7, s78 dst_sel:WORD_1 dst_unused:UNUSED_PAD src0_sel:DWORD src1_sel:DWORD
	v_min_i32_e32 v3, 0x7f, v3
	v_lshlrev_b32_e32 v6, 8, v6
	v_and_b32_e32 v6, 0xff00, v6
	v_and_b32_e32 v7, 0xff0000, v7
	v_perm_b32 v2, v3, v2, s79
	v_or3_b32 v2, v2, v6, v7
	ds_write_b32 v12, v2 offset:16
	buffer_store_dwordx4 v[156:159], v84, s[16:19], s76 offen
	ds_read_b64 v[2:3], v13 offset:1024
	s_waitcnt lgkmcnt(0)
	v_pk_add_f32 v[6:7], v[44:45], v[2:3] op_sel_hi:[1,0] neg_lo:[0,1] neg_hi:[0,1]
	s_nop 0
	v_pk_mul_f32 v[6:7], v[2:3], v[6:7] op_sel:[1,0]
	v_pk_add_f32 v[42:43], v[42:43], v[2:3] op_sel_hi:[1,0] neg_lo:[0,1] neg_hi:[0,1]
	v_pk_fma_f32 v[6:7], v[64:65], v[6:7], v[66:67]
	v_pk_mul_f32 v[2:3], v[2:3], v[42:43] op_sel:[1,0]
	v_and_b32_sdwa v42, v6, v216 dst_sel:DWORD dst_unused:UNUSED_PAD src0_sel:WORD_1 src1_sel:DWORD
	v_pk_fma_f32 v[2:3], v[0:1], v[2:3], v[4:5]
	v_add3_u32 v42, v6, v42, s77
	v_and_b32_e32 v44, 0xffff0000, v42
	v_and_b32_sdwa v42, v3, v216 dst_sel:DWORD dst_unused:UNUSED_PAD src0_sel:WORD_1 src1_sel:DWORD
	v_and_b32_sdwa v23, v7, v216 dst_sel:DWORD dst_unused:UNUSED_PAD src0_sel:WORD_1 src1_sel:DWORD
	v_and_b32_sdwa v43, v2, v216 dst_sel:DWORD dst_unused:UNUSED_PAD src0_sel:WORD_1 src1_sel:DWORD
	v_add3_u32 v42, v3, v42, s77
	v_add3_u32 v23, v7, v23, s77
	v_add3_u32 v45, v2, v43, s77
	v_and_b32_e32 v58, 0xffff0000, v42
	v_or_b32_sdwa v43, v58, v23 dst_sel:DWORD dst_unused:UNUSED_PAD src0_sel:DWORD src1_sel:WORD_1
	v_or_b32_sdwa v42, v45, v44 dst_sel:DWORD dst_unused:UNUSED_PAD src0_sel:WORD_1 src1_sel:DWORD
	ds_write_b64 v108, v[42:43]
	v_and_b32_e32 v42, 0xffff0000, v45
	v_sub_u32_e32 v6, v6, v44
	v_and_b32_e32 v23, 0xffff0000, v23
	v_sub_u32_e32 v2, v2, v42
	v_add_u32_e32 v6, 0x80, v6
	v_sub_u32_e32 v7, v7, v23
	v_sub_u32_e32 v3, v3, v58
	v_add_u32_e32 v2, 0x80, v2
	v_ashrrev_i32_e32 v6, 8, v6
	v_add_u32_e32 v7, 0x80, v7
	v_add_u32_e32 v3, 0x80, v3
	v_ashrrev_i32_e32 v2, 8, v2
	v_min_i32_e32 v6, 0x7f, v6
	v_ashrrev_i32_e32 v7, 8, v7
	v_ashrrev_i32_e32 v3, 8, v3
	v_min_i32_e32 v2, 0x7f, v2
	v_min_i32_sdwa v7, v7, s78 dst_sel:WORD_1 dst_unused:UNUSED_PAD src0_sel:DWORD src1_sel:DWORD
	v_min_i32_e32 v3, 0x7f, v3
	v_lshlrev_b32_e32 v6, 8, v6
	v_and_b32_e32 v6, 0xff00, v6
	v_and_b32_e32 v7, 0xff0000, v7
	v_perm_b32 v2, v3, v2, s79
	v_or3_b32 v2, v2, v6, v7
	ds_write_b32 v14, v2 offset:16
	buffer_store_dwordx4 v[160:163], v85, s[16:19], s76 offen
	ds_read_b64 v[2:3], v15 offset:1024
	s_waitcnt lgkmcnt(0)
;     ...
;           _Pragma("unroll") for (int bj = 0; bj < 2; ++bj) _Pragma("unroll") for (int n = 0; n < 2; ++n) {
;             const int cc = bj * HALF + wc3 * 32 + n * 16 + fq3 * 4;
;             const float4 gm = *reinterpret_cast<const float4*>(g.gam + pn * BM + cc), bt = *reinterpret_cast<const float4*>(g.bet + pn * BM + cc);
;             _Pragma("unroll") for (int m = 0; m < 4; ++m) {
;               const int rr = wr3 * 64 + m * 16 + fr3;
;               const float2 ms = *reinterpret_cast<const float2*>(mr + (ai * HALF + rr) * 2);
;               f32x4 y = acc[ai][bj][m][n];
;               const float o0 = (y[0] - ms.x) * ms.y * gm.x + bt.x, o1 = (y[1] - ms.x) * ms.y * gm.y + bt.y;
;               const float o2 = (y[2] - ms.x) * ms.y * gm.z + bt.z, o3 = (y[3] - ms.x) * ms.y * gm.w + bt.w;
;               const unsigned h0 = f2bf(o0), h1 = f2bf(o1), h2 = f2bf(o2), h3 = f2bf(o3);
;               u32x2 ob; ob[0] = h0 | (h1 << 16); ob[1] = h2 | (h3 << 16);
;               *reinterpret_cast<u32x2*>(smem + (rr >> 1) * PIECE + (rr & 1) * 512 + cc * 2) = ob;
;               const int l0 = min(((int)__float_as_uint(o0) - (int)(h0 << 16) + 128) >> 8, 127);
;               const int l1 = min(((int)__float_as_uint(o1) - (int)(h1 << 16) + 128) >> 8, 127);
;               const int l2 = min(((int)__float_as_uint(o2) - (int)(h2 << 16) + 128) >> 8, 127);
;               const int l3 = min(((int)__float_as_uint(o3) - (int)(h3 << 16) + 128) >> 8, 127);
;               *reinterpret_cast<unsigned*>(smem + LOBASE + (rr >> 2) * PIECE + (rr & 3) * 256 + cc) =
;                   (unsigned)(l0 & 255) | ((unsigned)(l1 & 255) << 8) | ((unsigned)(l2 & 255) << 16) | ((unsigned)l3 << 24);
;             }
;     ...
;           _Pragma("unroll") for (int i = 0; i < 8; ++i) {
;             const u32x4 v = *reinterpret_cast<const u32x4*>(smem + (wave * 8 + i) * PIECE + lane3 * 16);
;             __builtin_amdgcn_raw_buffer_store_b128(v, rsXB, hvo + i * (2 * DM * 2), hso, 0);
;           }
;           _Pragma("unroll") for (int i = 0; i < 4; ++i) {
;             const u32x4 v = *reinterpret_cast<const u32x4*>(smem + LOBASE + (wave * 4 + i) * PIECE + lane3 * 16);
;             __builtin_amdgcn_raw_buffer_store_b128(v, rsLO, lvo + i * (4 * DM), lso, 0);
;           }
	v_pk_add_f32 v[6:7], v[34:35], v[2:3] op_sel_hi:[1,0] neg_lo:[0,1] neg_hi:[0,1]
	s_nop 0
	v_pk_mul_f32 v[6:7], v[2:3], v[6:7] op_sel:[1,0]
	v_pk_add_f32 v[34:35], v[46:47], v[2:3] op_sel_hi:[1,0] neg_lo:[0,1] neg_hi:[0,1]
	v_pk_fma_f32 v[6:7], v[64:65], v[6:7], v[66:67]
	v_pk_mul_f32 v[2:3], v[2:3], v[34:35] op_sel:[1,0]
	v_and_b32_sdwa v34, v6, v216 dst_sel:DWORD dst_unused:UNUSED_PAD src0_sel:WORD_1 src1_sel:DWORD
	v_pk_fma_f32 v[2:3], v[0:1], v[2:3], v[4:5]
	v_add3_u32 v34, v6, v34, s77
	v_and_b32_e32 v42, 0xffff0000, v34
	v_and_b32_sdwa v34, v3, v216 dst_sel:DWORD dst_unused:UNUSED_PAD src0_sel:WORD_1 src1_sel:DWORD
	v_and_b32_sdwa v23, v7, v216 dst_sel:DWORD dst_unused:UNUSED_PAD src0_sel:WORD_1 src1_sel:DWORD
	v_and_b32_sdwa v35, v2, v216 dst_sel:DWORD dst_unused:UNUSED_PAD src0_sel:WORD_1 src1_sel:DWORD
	v_add3_u32 v34, v3, v34, s77
	v_add3_u32 v23, v7, v23, s77
	v_add3_u32 v43, v2, v35, s77
	v_and_b32_e32 v44, 0xffff0000, v34
	v_or_b32_sdwa v35, v44, v23 dst_sel:DWORD dst_unused:UNUSED_PAD src0_sel:DWORD src1_sel:WORD_1
	v_or_b32_sdwa v34, v43, v42 dst_sel:DWORD dst_unused:UNUSED_PAD src0_sel:WORD_1 src1_sel:DWORD
	ds_write_b64 v98, v[34:35]
	v_and_b32_e32 v34, 0xffff0000, v43
	v_sub_u32_e32 v6, v6, v42
	v_and_b32_e32 v23, 0xffff0000, v23
	v_sub_u32_e32 v2, v2, v34
	v_add_u32_e32 v6, 0x80, v6
	v_sub_u32_e32 v7, v7, v23
	v_sub_u32_e32 v3, v3, v44
	v_add_u32_e32 v2, 0x80, v2
	v_ashrrev_i32_e32 v6, 8, v6
	v_add_u32_e32 v7, 0x80, v7
	v_add_u32_e32 v3, 0x80, v3
	v_ashrrev_i32_e32 v2, 8, v2
	v_min_i32_e32 v6, 0x7f, v6
	v_ashrrev_i32_e32 v7, 8, v7
	v_ashrrev_i32_e32 v3, 8, v3
	v_min_i32_e32 v2, 0x7f, v2
	v_min_i32_sdwa v7, v7, s78 dst_sel:WORD_1 dst_unused:UNUSED_PAD src0_sel:DWORD src1_sel:DWORD
	v_min_i32_e32 v3, 0x7f, v3
	v_lshlrev_b32_e32 v6, 8, v6
	v_and_b32_e32 v6, 0xff00, v6
	v_and_b32_e32 v7, 0xff0000, v7
	v_perm_b32 v2, v3, v2, s79
	v_or3_b32 v2, v2, v6, v7
	ds_write_b32 v18, v2 offset:16
	buffer_store_dwordx4 v[164:167], v88, s[16:19], s76 offen
	ds_read_b64 v[2:3], v19 offset:1024
	s_waitcnt lgkmcnt(0)
	v_pk_add_f32 v[6:7], v[50:51], v[2:3] op_sel_hi:[1,0] neg_lo:[0,1] neg_hi:[0,1]
	s_nop 0
	v_pk_mul_f32 v[6:7], v[2:3], v[6:7] op_sel:[1,0]
	v_pk_add_f32 v[34:35], v[62:63], v[2:3] op_sel_hi:[1,0] neg_lo:[0,1] neg_hi:[0,1]
	v_pk_fma_f32 v[6:7], v[64:65], v[6:7], v[66:67]
	v_pk_mul_f32 v[2:3], v[2:3], v[34:35] op_sel:[1,0]
	s_nop 0
	v_pk_fma_f32 v[0:1], v[0:1], v[2:3], v[4:5]
	v_and_b32_sdwa v2, v7, v216 dst_sel:DWORD dst_unused:UNUSED_PAD src0_sel:WORD_1 src1_sel:DWORD
	v_and_b32_sdwa v3, v6, v216 dst_sel:DWORD dst_unused:UNUSED_PAD src0_sel:WORD_1 src1_sel:DWORD
	v_add3_u32 v4, v7, v2, s77
	v_add3_u32 v2, v6, v3, s77
	v_and_b32_e32 v5, 0xffff0000, v2
	v_and_b32_sdwa v2, v1, v216 dst_sel:DWORD dst_unused:UNUSED_PAD src0_sel:WORD_1 src1_sel:DWORD
	v_and_b32_sdwa v3, v0, v216 dst_sel:DWORD dst_unused:UNUSED_PAD src0_sel:WORD_1 src1_sel:DWORD
	v_add3_u32 v2, v1, v2, s77
	v_add3_u32 v23, v0, v3, s77
	v_and_b32_e32 v34, 0xffff0000, v2
	v_or_b32_sdwa v3, v34, v4 dst_sel:DWORD dst_unused:UNUSED_PAD src0_sel:DWORD src1_sel:WORD_1
	v_or_b32_sdwa v2, v23, v5 dst_sel:DWORD dst_unused:UNUSED_PAD src0_sel:WORD_1 src1_sel:DWORD
	ds_write_b64 v99, v[2:3]
	v_and_b32_e32 v2, 0xffff0000, v23
	v_sub_u32_e32 v0, v0, v2
	v_sub_u32_e32 v2, v6, v5
	v_and_b32_e32 v3, 0xffff0000, v4
	v_add_u32_e32 v2, 0x80, v2
	v_sub_u32_e32 v3, v7, v3
	v_sub_u32_e32 v1, v1, v34
	v_add_u32_e32 v0, 0x80, v0
	v_ashrrev_i32_e32 v2, 8, v2
	v_add_u32_e32 v3, 0x80, v3
	v_add_u32_e32 v1, 0x80, v1
	v_ashrrev_i32_e32 v0, 8, v0
	v_min_i32_e32 v2, 0x7f, v2
	v_ashrrev_i32_e32 v3, 8, v3
	v_ashrrev_i32_e32 v1, 8, v1
	v_min_i32_e32 v0, 0x7f, v0
	v_min_i32_sdwa v3, v3, s78 dst_sel:WORD_1 dst_unused:UNUSED_PAD src0_sel:DWORD src1_sel:DWORD
	v_min_i32_e32 v1, 0x7f, v1
	v_lshlrev_b32_e32 v2, 8, v2
	v_and_b32_e32 v2, 0xff00, v2
	v_and_b32_e32 v3, 0xff0000, v3
	v_perm_b32 v0, v1, v0, s79
	v_or3_b32 v0, v0, v2, v3
	ds_write_b32 v22, v0 offset:16
	buffer_store_dwordx4 v[168:171], v89, s[16:19], s76 offen
	v_mov_b32_e32 v0, v228
	v_mov_b32_e32 v1, v229
	v_mov_b32_e32 v2, v230
	v_mov_b32_e32 v3, v231
	v_mov_b32_e32 v4, v244
	v_mov_b32_e32 v5, v245
	v_mov_b32_e32 v6, v246
	v_mov_b32_e32 v7, v247
	ds_read_b64 v[44:45], v149 offset:1024
	s_waitcnt lgkmcnt(0)
	v_pk_add_f32 v[46:47], v[56:57], v[44:45] op_sel_hi:[1,0] neg_lo:[0,1] neg_hi:[0,1]
	s_nop 0
	v_pk_mul_f32 v[46:47], v[44:45], v[46:47] op_sel:[1,0]
	v_pk_add_f32 v[50:51], v[54:55], v[44:45] op_sel_hi:[1,0] neg_lo:[0,1] neg_hi:[0,1]
	v_mov_b32_e32 v34, v1
	v_mov_b32_e32 v35, v2
	v_mov_b32_e32 v42, v5
	v_mov_b32_e32 v43, v6
	v_pk_fma_f32 v[46:47], v[34:35], v[46:47], v[42:43]
	v_pk_mul_f32 v[44:45], v[44:45], v[50:51] op_sel:[1,0]
	v_mov_b32_e32 v1, v3
	v_mov_b32_e32 v5, v7
	v_and_b32_sdwa v6, v47, v216 dst_sel:DWORD dst_unused:UNUSED_PAD src0_sel:WORD_1 src1_sel:DWORD
	v_and_b32_sdwa v7, v46, v216 dst_sel:DWORD dst_unused:UNUSED_PAD src0_sel:WORD_1 src1_sel:DWORD
	v_pk_fma_f32 v[2:3], v[0:1], v[44:45], v[4:5]
	v_add3_u32 v23, v47, v6, s77
	v_add3_u32 v6, v46, v7, s77
	v_and_b32_e32 v44, 0xffff0000, v6
	v_and_b32_sdwa v6, v3, v216 dst_sel:DWORD dst_unused:UNUSED_PAD src0_sel:WORD_1 src1_sel:DWORD
	v_and_b32_sdwa v7, v2, v216 dst_sel:DWORD dst_unused:UNUSED_PAD src0_sel:WORD_1 src1_sel:DWORD
	v_add3_u32 v6, v3, v6, s77
	v_add3_u32 v45, v2, v7, s77
	v_and_b32_e32 v50, 0xffff0000, v6
	v_or_b32_sdwa v7, v50, v23 dst_sel:DWORD dst_unused:UNUSED_PAD src0_sel:DWORD src1_sel:WORD_1
	v_or_b32_sdwa v6, v45, v44 dst_sel:DWORD dst_unused:UNUSED_PAD src0_sel:WORD_1 src1_sel:DWORD
	ds_write_b64 v106, v[6:7]
	v_and_b32_e32 v6, 0xffff0000, v45
	v_sub_u32_e32 v2, v2, v6
	v_sub_u32_e32 v6, v46, v44
	v_and_b32_e32 v7, 0xffff0000, v23
	v_add_u32_e32 v6, 0x80, v6
	v_sub_u32_e32 v7, v47, v7
	v_sub_u32_e32 v3, v3, v50
	v_add_u32_e32 v2, 0x80, v2
	v_ashrrev_i32_e32 v6, 8, v6
	v_add_u32_e32 v7, 0x80, v7
	v_add_u32_e32 v3, 0x80, v3
	v_ashrrev_i32_e32 v2, 8, v2
	v_min_i32_e32 v6, 0x7f, v6
	v_ashrrev_i32_e32 v7, 8, v7
	v_ashrrev_i32_e32 v3, 8, v3
	v_min_i32_e32 v2, 0x7f, v2
	v_min_i32_sdwa v7, v7, s78 dst_sel:WORD_1 dst_unused:UNUSED_PAD src0_sel:DWORD src1_sel:DWORD
	v_min_i32_e32 v3, 0x7f, v3
	v_lshlrev_b32_e32 v6, 8, v6
	v_and_b32_e32 v6, 0xff00, v6
	v_and_b32_e32 v7, 0xff0000, v7
	v_perm_b32 v2, v3, v2, s79
	v_or3_b32 v2, v2, v6, v7
	ds_write_b32 v12, v2 offset:128
	buffer_store_dwordx4 v[172:175], v146, s[20:23], s33 offen
	ds_read_b64 v[2:3], v13 offset:1024
	s_waitcnt lgkmcnt(0)
;     ...
;           _Pragma("unroll") for (int bj = 0; bj < 2; ++bj) _Pragma("unroll") for (int n = 0; n < 2; ++n) {
;             const int cc = bj * HALF + wc3 * 32 + n * 16 + fq3 * 4;
;             const float4 gm = *reinterpret_cast<const float4*>(g.gam + pn * BM + cc), bt = *reinterpret_cast<const float4*>(g.bet + pn * BM + cc);
;             _Pragma("unroll") for (int m = 0; m < 4; ++m) {
;               const int rr = wr3 * 64 + m * 16 + fr3;
;               const float2 ms = *reinterpret_cast<const float2*>(mr + (ai * HALF + rr) * 2);
;               f32x4 y = acc[ai][bj][m][n];
;               const float o0 = (y[0] - ms.x) * ms.y * gm.x + bt.x, o1 = (y[1] - ms.x) * ms.y * gm.y + bt.y;
;               const float o2 = (y[2] - ms.x) * ms.y * gm.z + bt.z, o3 = (y[3] - ms.x) * ms.y * gm.w + bt.w;
;               const unsigned h0 = f2bf(o0), h1 = f2bf(o1), h2 = f2bf(o2), h3 = f2bf(o3);
;               u32x2 ob; ob[0] = h0 | (h1 << 16); ob[1] = h2 | (h3 << 16);
;               *reinterpret_cast<u32x2*>(smem + (rr >> 1) * PIECE + (rr & 1) * 512 + cc * 2) = ob;
;               const int l0 = min(((int)__float_as_uint(o0) - (int)(h0 << 16) + 128) >> 8, 127);
;               const int l1 = min(((int)__float_as_uint(o1) - (int)(h1 << 16) + 128) >> 8, 127);
;               const int l2 = min(((int)__float_as_uint(o2) - (int)(h2 << 16) + 128) >> 8, 127);
;               const int l3 = min(((int)__float_as_uint(o3) - (int)(h3 << 16) + 128) >> 8, 127);
;               *reinterpret_cast<unsigned*>(smem + LOBASE + (rr >> 2) * PIECE + (rr & 3) * 256 + cc) =
;                   (unsigned)(l0 & 255) | ((unsigned)(l1 & 255) << 8) | ((unsigned)(l2 & 255) << 16) | ((unsigned)l3 << 24);
;             }
;     ...
;           _Pragma("unroll") for (int i = 0; i < 8; ++i) {
;             const u32x4 v = *reinterpret_cast<const u32x4*>(smem + (wave * 8 + i) * PIECE + lane3 * 16);
;             __builtin_amdgcn_raw_buffer_store_b128(v, rsXB, hvo + i * (2 * DM * 2), hso, 0);
;           }
;           _Pragma("unroll") for (int i = 0; i < 4; ++i) {
;             const u32x4 v = *reinterpret_cast<const u32x4*>(smem + LOBASE + (wave * 4 + i) * PIECE + lane3 * 16);
;             __builtin_amdgcn_raw_buffer_store_b128(v, rsLO, lvo + i * (4 * DM), lso, 0);
;           }
	v_pk_add_f32 v[6:7], v[40:41], v[2:3] op_sel_hi:[1,0] neg_lo:[0,1] neg_hi:[0,1]
	s_nop 0
	v_pk_mul_f32 v[6:7], v[2:3], v[6:7] op_sel:[1,0]
	v_pk_add_f32 v[38:39], v[38:39], v[2:3] op_sel_hi:[1,0] neg_lo:[0,1] neg_hi:[0,1]
	v_pk_fma_f32 v[6:7], v[34:35], v[6:7], v[42:43]
	v_pk_mul_f32 v[2:3], v[2:3], v[38:39] op_sel:[1,0]
	v_and_b32_sdwa v38, v6, v216 dst_sel:DWORD dst_unused:UNUSED_PAD src0_sel:WORD_1 src1_sel:DWORD
	v_pk_fma_f32 v[2:3], v[0:1], v[2:3], v[4:5]
	v_add3_u32 v38, v6, v38, s77
	v_and_b32_e32 v40, 0xffff0000, v38
	v_and_b32_sdwa v38, v3, v216 dst_sel:DWORD dst_unused:UNUSED_PAD src0_sel:WORD_1 src1_sel:DWORD
	v_and_b32_sdwa v23, v7, v216 dst_sel:DWORD dst_unused:UNUSED_PAD src0_sel:WORD_1 src1_sel:DWORD
	v_and_b32_sdwa v39, v2, v216 dst_sel:DWORD dst_unused:UNUSED_PAD src0_sel:WORD_1 src1_sel:DWORD
	v_add3_u32 v38, v3, v38, s77
	v_add3_u32 v23, v7, v23, s77
	v_add3_u32 v41, v2, v39, s77
	v_and_b32_e32 v44, 0xffff0000, v38
	v_or_b32_sdwa v39, v44, v23 dst_sel:DWORD dst_unused:UNUSED_PAD src0_sel:DWORD src1_sel:WORD_1
	v_or_b32_sdwa v38, v41, v40 dst_sel:DWORD dst_unused:UNUSED_PAD src0_sel:WORD_1 src1_sel:DWORD
	ds_write_b64 v102, v[38:39]
	v_and_b32_e32 v38, 0xffff0000, v41
	v_sub_u32_e32 v6, v6, v40
	v_and_b32_e32 v23, 0xffff0000, v23
	v_sub_u32_e32 v2, v2, v38
	v_add_u32_e32 v6, 0x80, v6
	v_sub_u32_e32 v7, v7, v23
	v_sub_u32_e32 v3, v3, v44
	v_add_u32_e32 v2, 0x80, v2
	v_ashrrev_i32_e32 v6, 8, v6
	v_add_u32_e32 v7, 0x80, v7
	v_add_u32_e32 v3, 0x80, v3
	v_ashrrev_i32_e32 v2, 8, v2
	v_min_i32_e32 v6, 0x7f, v6
	v_ashrrev_i32_e32 v7, 8, v7
	v_ashrrev_i32_e32 v3, 8, v3
	v_min_i32_e32 v2, 0x7f, v2
	v_min_i32_sdwa v7, v7, s78 dst_sel:WORD_1 dst_unused:UNUSED_PAD src0_sel:DWORD src1_sel:DWORD
	v_min_i32_e32 v3, 0x7f, v3
	v_lshlrev_b32_e32 v6, 8, v6
	v_and_b32_e32 v6, 0xff00, v6
	v_and_b32_e32 v7, 0xff0000, v7
	v_perm_b32 v2, v3, v2, s79
	v_or3_b32 v2, v2, v6, v7
	ds_write_b32 v14, v2 offset:128
	buffer_store_dwordx4 v[176:179], v90, s[20:23], s33 offen
	ds_read_b64 v[2:3], v15 offset:1024
	s_waitcnt lgkmcnt(0)
	v_pk_add_f32 v[6:7], v[24:25], v[2:3] op_sel_hi:[1,0] neg_lo:[0,1] neg_hi:[0,1]
	s_nop 0
	v_pk_mul_f32 v[6:7], v[2:3], v[6:7] op_sel:[1,0]
	v_pk_add_f32 v[24:25], v[26:27], v[2:3] op_sel_hi:[1,0] neg_lo:[0,1] neg_hi:[0,1]
	v_pk_fma_f32 v[6:7], v[34:35], v[6:7], v[42:43]
	v_pk_mul_f32 v[2:3], v[2:3], v[24:25] op_sel:[1,0]
	v_and_b32_sdwa v24, v6, v216 dst_sel:DWORD dst_unused:UNUSED_PAD src0_sel:WORD_1 src1_sel:DWORD
	v_pk_fma_f32 v[2:3], v[0:1], v[2:3], v[4:5]
	v_add3_u32 v24, v6, v24, s77
	v_and_b32_e32 v26, 0xffff0000, v24
	v_and_b32_sdwa v24, v3, v216 dst_sel:DWORD dst_unused:UNUSED_PAD src0_sel:WORD_1 src1_sel:DWORD
	v_and_b32_sdwa v23, v7, v216 dst_sel:DWORD dst_unused:UNUSED_PAD src0_sel:WORD_1 src1_sel:DWORD
	v_and_b32_sdwa v25, v2, v216 dst_sel:DWORD dst_unused:UNUSED_PAD src0_sel:WORD_1 src1_sel:DWORD
	v_add3_u32 v24, v3, v24, s77
	v_add3_u32 v23, v7, v23, s77
	v_add3_u32 v27, v2, v25, s77
	v_and_b32_e32 v38, 0xffff0000, v24
	v_or_b32_sdwa v25, v38, v23 dst_sel:DWORD dst_unused:UNUSED_PAD src0_sel:DWORD src1_sel:WORD_1
	v_or_b32_sdwa v24, v27, v26 dst_sel:DWORD dst_unused:UNUSED_PAD src0_sel:WORD_1 src1_sel:DWORD
	ds_write_b64 v92, v[24:25]
	v_and_b32_e32 v24, 0xffff0000, v27
	v_sub_u32_e32 v6, v6, v26
	v_and_b32_e32 v23, 0xffff0000, v23
	v_sub_u32_e32 v2, v2, v24
	v_add_u32_e32 v6, 0x80, v6
	v_sub_u32_e32 v7, v7, v23
	v_sub_u32_e32 v3, v3, v38
	v_add_u32_e32 v2, 0x80, v2
	v_ashrrev_i32_e32 v6, 8, v6
	v_add_u32_e32 v7, 0x80, v7
	v_add_u32_e32 v3, 0x80, v3
	v_ashrrev_i32_e32 v2, 8, v2
	v_min_i32_e32 v6, 0x7f, v6
	v_ashrrev_i32_e32 v7, 8, v7
	v_ashrrev_i32_e32 v3, 8, v3
	v_min_i32_e32 v2, 0x7f, v2
	v_min_i32_sdwa v7, v7, s78 dst_sel:WORD_1 dst_unused:UNUSED_PAD src0_sel:DWORD src1_sel:DWORD
	v_min_i32_e32 v3, 0x7f, v3
	v_lshlrev_b32_e32 v6, 8, v6
	v_and_b32_e32 v6, 0xff00, v6
	v_and_b32_e32 v7, 0xff0000, v7
	v_perm_b32 v2, v3, v2, s79
	v_or3_b32 v2, v2, v6, v7
	ds_write_b32 v18, v2 offset:128
	buffer_store_dwordx4 v[180:183], v91, s[20:23], s33 offen
	ds_read_b64 v[2:3], v19 offset:1024
	s_waitcnt lgkmcnt(0)
	v_pk_add_f32 v[6:7], v[28:29], v[2:3] op_sel_hi:[1,0] neg_lo:[0,1] neg_hi:[0,1]
	s_nop 0
	v_pk_mul_f32 v[6:7], v[2:3], v[6:7] op_sel:[1,0]
	v_pk_add_f32 v[24:25], v[30:31], v[2:3] op_sel_hi:[1,0] neg_lo:[0,1] neg_hi:[0,1]
	v_pk_fma_f32 v[6:7], v[34:35], v[6:7], v[42:43]
	v_pk_mul_f32 v[2:3], v[2:3], v[24:25] op_sel:[1,0]
	s_nop 0
	v_pk_fma_f32 v[0:1], v[0:1], v[2:3], v[4:5]
	v_and_b32_sdwa v2, v7, v216 dst_sel:DWORD dst_unused:UNUSED_PAD src0_sel:WORD_1 src1_sel:DWORD
	v_and_b32_sdwa v3, v6, v216 dst_sel:DWORD dst_unused:UNUSED_PAD src0_sel:WORD_1 src1_sel:DWORD
	v_add3_u32 v4, v7, v2, s77
	v_add3_u32 v2, v6, v3, s77
	v_and_b32_e32 v5, 0xffff0000, v2
	v_and_b32_sdwa v2, v1, v216 dst_sel:DWORD dst_unused:UNUSED_PAD src0_sel:WORD_1 src1_sel:DWORD
	v_and_b32_sdwa v3, v0, v216 dst_sel:DWORD dst_unused:UNUSED_PAD src0_sel:WORD_1 src1_sel:DWORD
	v_add3_u32 v2, v1, v2, s77
	v_add3_u32 v23, v0, v3, s77
	v_and_b32_e32 v24, 0xffff0000, v2
	v_or_b32_sdwa v3, v24, v4 dst_sel:DWORD dst_unused:UNUSED_PAD src0_sel:DWORD src1_sel:WORD_1
	v_or_b32_sdwa v2, v23, v5 dst_sel:DWORD dst_unused:UNUSED_PAD src0_sel:WORD_1 src1_sel:DWORD
	ds_write_b64 v93, v[2:3]
	v_and_b32_e32 v2, 0xffff0000, v23
	v_sub_u32_e32 v0, v0, v2
	v_sub_u32_e32 v2, v6, v5
	v_and_b32_e32 v3, 0xffff0000, v4
	v_add_u32_e32 v2, 0x80, v2
	v_sub_u32_e32 v3, v7, v3
	v_sub_u32_e32 v1, v1, v24
	v_add_u32_e32 v0, 0x80, v0
	v_ashrrev_i32_e32 v2, 8, v2
	v_add_u32_e32 v3, 0x80, v3
	v_add_u32_e32 v1, 0x80, v1
	v_ashrrev_i32_e32 v0, 8, v0
	v_min_i32_e32 v2, 0x7f, v2
	v_ashrrev_i32_e32 v3, 8, v3
	v_ashrrev_i32_e32 v1, 8, v1
	v_min_i32_e32 v0, 0x7f, v0
	v_min_i32_sdwa v3, v3, s78 dst_sel:WORD_1 dst_unused:UNUSED_PAD src0_sel:DWORD src1_sel:DWORD
	v_min_i32_e32 v1, 0x7f, v1
	v_lshlrev_b32_e32 v2, 8, v2
	v_and_b32_e32 v2, 0xff00, v2
	v_and_b32_e32 v3, 0xff0000, v3
	v_perm_b32 v0, v1, v0, s79
	v_or3_b32 v0, v0, v2, v3
	ds_write_b32 v22, v0 offset:128
	buffer_store_dwordx4 v[184:187], v96, s[20:23], s33 offen
	v_mov_b32_e32 v0, v232
	v_mov_b32_e32 v1, v233
	v_mov_b32_e32 v2, v234
	v_mov_b32_e32 v3, v235
	v_mov_b32_e32 v4, v248
	v_mov_b32_e32 v5, v249
	v_mov_b32_e32 v6, v250
	v_mov_b32_e32 v7, v251
	ds_read_b64 v[28:29], v149 offset:1024
	s_mov_b64 s[4:5], -1
	s_waitcnt lgkmcnt(0)
;     ...
;             _Pragma("unroll") for (int m = 0; m < 4; ++m) {
;               const int rr = wr3 * 64 + m * 16 + fr3;
;               const float2 ms = *reinterpret_cast<const float2*>(mr + (ai * HALF + rr) * 2);
;               f32x4 y = acc[ai][bj][m][n];
;               const float o0 = (y[0] - ms.x) * ms.y * gm.x + bt.x, o1 = (y[1] - ms.x) * ms.y * gm.y + bt.y;
;               const float o2 = (y[2] - ms.x) * ms.y * gm.z + bt.z, o3 = (y[3] - ms.x) * ms.y * gm.w + bt.w;
;               const unsigned h0 = f2bf(o0), h1 = f2bf(o1), h2 = f2bf(o2), h3 = f2bf(o3);
;               u32x2 ob; ob[0] = h0 | (h1 << 16); ob[1] = h2 | (h3 << 16);
;               *reinterpret_cast<u32x2*>(smem + (rr >> 1) * PIECE + (rr & 1) * 512 + cc * 2) = ob;
;               const int l0 = min(((int)__float_as_uint(o0) - (int)(h0 << 16) + 128) >> 8, 127);
;               const int l1 = min(((int)__float_as_uint(o1) - (int)(h1 << 16) + 128) >> 8, 127);
;               const int l2 = min(((int)__float_as_uint(o2) - (int)(h2 << 16) + 128) >> 8, 127);
;               const int l3 = min(((int)__float_as_uint(o3) - (int)(h3 << 16) + 128) >> 8, 127);
;               *reinterpret_cast<unsigned*>(smem + LOBASE + (rr >> 2) * PIECE + (rr & 3) * 256 + cc) =
;                   (unsigned)(l0 & 255) | ((unsigned)(l1 & 255) << 8) | ((unsigned)(l2 & 255) << 16) | ((unsigned)l3 << 24);
;             }
	v_pk_add_f32 v[30:31], v[52:53], v[28:29] op_sel_hi:[1,0] neg_lo:[0,1] neg_hi:[0,1]
	s_nop 0
	v_pk_mul_f32 v[30:31], v[28:29], v[30:31] op_sel:[1,0]
	v_pk_add_f32 v[34:35], v[48:49], v[28:29] op_sel_hi:[1,0] neg_lo:[0,1] neg_hi:[0,1]
	v_mov_b32_e32 v24, v1
	v_mov_b32_e32 v25, v2
	v_mov_b32_e32 v26, v5
	v_mov_b32_e32 v27, v6
	v_pk_fma_f32 v[30:31], v[24:25], v[30:31], v[26:27]
	v_pk_mul_f32 v[28:29], v[28:29], v[34:35] op_sel:[1,0]
	v_mov_b32_e32 v1, v3
	v_mov_b32_e32 v5, v7
	v_and_b32_sdwa v6, v31, v216 dst_sel:DWORD dst_unused:UNUSED_PAD src0_sel:WORD_1 src1_sel:DWORD
	v_and_b32_sdwa v7, v30, v216 dst_sel:DWORD dst_unused:UNUSED_PAD src0_sel:WORD_1 src1_sel:DWORD
	v_pk_fma_f32 v[2:3], v[0:1], v[28:29], v[4:5]
	v_add3_u32 v23, v31, v6, s77
	v_add3_u32 v6, v30, v7, s77
	v_and_b32_e32 v28, 0xffff0000, v6
	v_and_b32_sdwa v6, v3, v216 dst_sel:DWORD dst_unused:UNUSED_PAD src0_sel:WORD_1 src1_sel:DWORD
	v_and_b32_sdwa v7, v2, v216 dst_sel:DWORD dst_unused:UNUSED_PAD src0_sel:WORD_1 src1_sel:DWORD
	v_add3_u32 v6, v3, v6, s77
	v_add3_u32 v29, v2, v7, s77
	v_and_b32_e32 v34, 0xffff0000, v6
	v_or_b32_sdwa v7, v34, v23 dst_sel:DWORD dst_unused:UNUSED_PAD src0_sel:DWORD src1_sel:WORD_1
	v_or_b32_sdwa v6, v29, v28 dst_sel:DWORD dst_unused:UNUSED_PAD src0_sel:WORD_1 src1_sel:DWORD
	ds_write_b64 v94, v[6:7]
	v_and_b32_e32 v6, 0xffff0000, v29
	v_sub_u32_e32 v2, v2, v6
	v_sub_u32_e32 v6, v30, v28
	v_and_b32_e32 v7, 0xffff0000, v23
	v_add_u32_e32 v6, 0x80, v6
	v_sub_u32_e32 v7, v31, v7
	v_sub_u32_e32 v3, v3, v34
	v_add_u32_e32 v2, 0x80, v2
	v_ashrrev_i32_e32 v6, 8, v6
	v_add_u32_e32 v7, 0x80, v7
	v_add_u32_e32 v3, 0x80, v3
	v_ashrrev_i32_e32 v2, 8, v2
	v_min_i32_e32 v6, 0x7f, v6
	v_ashrrev_i32_e32 v7, 8, v7
	v_ashrrev_i32_e32 v3, 8, v3
	v_min_i32_e32 v2, 0x7f, v2
	v_min_i32_sdwa v7, v7, s78 dst_sel:WORD_1 dst_unused:UNUSED_PAD src0_sel:DWORD src1_sel:DWORD
	v_min_i32_e32 v3, 0x7f, v3
	v_lshlrev_b32_e32 v6, 8, v6
	v_and_b32_e32 v6, 0xff00, v6
	v_and_b32_e32 v7, 0xff0000, v7
	v_perm_b32 v2, v3, v2, s79
	v_or3_b32 v2, v2, v6, v7
	ds_write_b32 v12, v2 offset:144
	ds_read_b64 v[2:3], v13 offset:1024
	s_waitcnt lgkmcnt(0)
	v_pk_add_f32 v[6:7], v[36:37], v[2:3] op_sel_hi:[1,0] neg_lo:[0,1] neg_hi:[0,1]
	s_nop 0
	v_pk_mul_f32 v[6:7], v[2:3], v[6:7] op_sel:[1,0]
	v_pk_add_f32 v[12:13], v[32:33], v[2:3] op_sel_hi:[1,0] neg_lo:[0,1] neg_hi:[0,1]
	v_pk_fma_f32 v[6:7], v[24:25], v[6:7], v[26:27]
	v_pk_mul_f32 v[2:3], v[2:3], v[12:13] op_sel:[1,0]
	v_and_b32_sdwa v12, v7, v216 dst_sel:DWORD dst_unused:UNUSED_PAD src0_sel:WORD_1 src1_sel:DWORD
	v_and_b32_sdwa v13, v6, v216 dst_sel:DWORD dst_unused:UNUSED_PAD src0_sel:WORD_1 src1_sel:DWORD
	v_pk_fma_f32 v[2:3], v[0:1], v[2:3], v[4:5]
	v_add3_u32 v23, v7, v12, s77
	v_add3_u32 v12, v6, v13, s77
	v_and_b32_e32 v28, 0xffff0000, v12
	v_and_b32_sdwa v12, v3, v216 dst_sel:DWORD dst_unused:UNUSED_PAD src0_sel:WORD_1 src1_sel:DWORD
	v_and_b32_sdwa v13, v2, v216 dst_sel:DWORD dst_unused:UNUSED_PAD src0_sel:WORD_1 src1_sel:DWORD
	v_add3_u32 v12, v3, v12, s77
	v_add3_u32 v29, v2, v13, s77
	v_and_b32_e32 v30, 0xffff0000, v12
	v_or_b32_sdwa v13, v30, v23 dst_sel:DWORD dst_unused:UNUSED_PAD src0_sel:DWORD src1_sel:WORD_1
	v_or_b32_sdwa v12, v29, v28 dst_sel:DWORD dst_unused:UNUSED_PAD src0_sel:WORD_1 src1_sel:DWORD
	ds_write_b64 v95, v[12:13]
	v_and_b32_e32 v12, 0xffff0000, v29
	v_sub_u32_e32 v2, v2, v12
	v_sub_u32_e32 v6, v6, v28
	v_and_b32_e32 v12, 0xffff0000, v23
	v_add_u32_e32 v6, 0x80, v6
	v_sub_u32_e32 v7, v7, v12
	v_sub_u32_e32 v3, v3, v30
	v_add_u32_e32 v2, 0x80, v2
	v_ashrrev_i32_e32 v6, 8, v6
	v_add_u32_e32 v7, 0x80, v7
	v_add_u32_e32 v3, 0x80, v3
	v_ashrrev_i32_e32 v2, 8, v2
	v_min_i32_e32 v6, 0x7f, v6
	v_ashrrev_i32_e32 v7, 8, v7
	v_ashrrev_i32_e32 v3, 8, v3
	v_min_i32_e32 v2, 0x7f, v2
	v_min_i32_sdwa v7, v7, s78 dst_sel:WORD_1 dst_unused:UNUSED_PAD src0_sel:DWORD src1_sel:DWORD
	v_min_i32_e32 v3, 0x7f, v3
	v_lshlrev_b32_e32 v6, 8, v6
	v_and_b32_e32 v6, 0xff00, v6
	v_and_b32_e32 v7, 0xff0000, v7
	v_perm_b32 v2, v3, v2, s79
	v_or3_b32 v2, v2, v6, v7
	ds_write_b32 v14, v2 offset:144
	ds_read_b64 v[2:3], v15 offset:1024
	s_waitcnt lgkmcnt(0)
	v_pk_add_f32 v[6:7], v[20:21], v[2:3] op_sel_hi:[1,0] neg_lo:[0,1] neg_hi:[0,1]
	s_nop 0
	v_pk_mul_f32 v[6:7], v[2:3], v[6:7] op_sel:[1,0]
	v_pk_add_f32 v[12:13], v[16:17], v[2:3] op_sel_hi:[1,0] neg_lo:[0,1] neg_hi:[0,1]
	v_pk_fma_f32 v[6:7], v[24:25], v[6:7], v[26:27]
	v_pk_mul_f32 v[2:3], v[2:3], v[12:13] op_sel:[1,0]
	v_and_b32_sdwa v12, v7, v216 dst_sel:DWORD dst_unused:UNUSED_PAD src0_sel:WORD_1 src1_sel:DWORD
	v_and_b32_sdwa v13, v6, v216 dst_sel:DWORD dst_unused:UNUSED_PAD src0_sel:WORD_1 src1_sel:DWORD
	v_pk_fma_f32 v[2:3], v[0:1], v[2:3], v[4:5]
	v_add3_u32 v14, v7, v12, s77
	v_add3_u32 v12, v6, v13, s77
	v_and_b32_e32 v15, 0xffff0000, v12
	v_and_b32_sdwa v12, v3, v216 dst_sel:DWORD dst_unused:UNUSED_PAD src0_sel:WORD_1 src1_sel:DWORD
	v_and_b32_sdwa v13, v2, v216 dst_sel:DWORD dst_unused:UNUSED_PAD src0_sel:WORD_1 src1_sel:DWORD
	v_add3_u32 v12, v3, v12, s77
	v_add3_u32 v16, v2, v13, s77
	v_and_b32_e32 v17, 0xffff0000, v12
	v_or_b32_sdwa v13, v17, v14 dst_sel:DWORD dst_unused:UNUSED_PAD src0_sel:DWORD src1_sel:WORD_1
	v_or_b32_sdwa v12, v16, v15 dst_sel:DWORD dst_unused:UNUSED_PAD src0_sel:WORD_1 src1_sel:DWORD
	ds_write_b64 v80, v[12:13]
	v_and_b32_e32 v12, 0xffff0000, v16
	v_sub_u32_e32 v2, v2, v12
	v_sub_u32_e32 v6, v6, v15
	v_and_b32_e32 v12, 0xffff0000, v14
	v_add_u32_e32 v6, 0x80, v6
	v_sub_u32_e32 v7, v7, v12
	v_sub_u32_e32 v3, v3, v17
	v_add_u32_e32 v2, 0x80, v2
	v_ashrrev_i32_e32 v6, 8, v6
	v_add_u32_e32 v7, 0x80, v7
	v_add_u32_e32 v3, 0x80, v3
	v_ashrrev_i32_e32 v2, 8, v2
	v_min_i32_e32 v6, 0x7f, v6
	v_ashrrev_i32_e32 v7, 8, v7
	v_ashrrev_i32_e32 v3, 8, v3
	v_min_i32_e32 v2, 0x7f, v2
	v_min_i32_sdwa v7, v7, s78 dst_sel:WORD_1 dst_unused:UNUSED_PAD src0_sel:DWORD src1_sel:DWORD
	v_min_i32_e32 v3, 0x7f, v3
	v_lshlrev_b32_e32 v6, 8, v6
	v_and_b32_e32 v6, 0xff00, v6
	v_and_b32_e32 v7, 0xff0000, v7
	v_perm_b32 v2, v3, v2, s79
	v_or3_b32 v2, v2, v6, v7
	ds_write_b32 v18, v2 offset:144
	ds_read_b64 v[2:3], v19 offset:1024
	s_waitcnt lgkmcnt(0)
;     ...
;   auto issue_prologue = [&](int sA0, int sA1, int sB0, int sB1) {
;     const int tid = opaque_tid(wave);
;     int offA[2], offB[2];
;     _Pragma("unroll") for (int i = 0; i < 2; ++i) {
;       int r, c; stage_rc(tid * 16 + i * 8192, r, c);
;       offA[i] = (r * lda + c) * 2; offB[i] = (r * ldb + c) * 2;
;     }
;     STAGE(SB(0, 0), rsB, sB0, offB, 0); STAGE(SA(0, 0), rsA, sA0, offA, 0);
;     ...
;               const float o0 = (y[0] - ms.x) * ms.y * gm.x + bt.x, o1 = (y[1] - ms.x) * ms.y * gm.y + bt.y;
;               const float o2 = (y[2] - ms.x) * ms.y * gm.z + bt.z, o3 = (y[3] - ms.x) * ms.y * gm.w + bt.w;
;               const unsigned h0 = f2bf(o0), h1 = f2bf(o1), h2 = f2bf(o2), h3 = f2bf(o3);
;               u32x2 ob; ob[0] = h0 | (h1 << 16); ob[1] = h2 | (h3 << 16);
;               *reinterpret_cast<u32x2*>(smem + (rr >> 1) * PIECE + (rr & 1) * 512 + cc * 2) = ob;
;               const int l0 = min(((int)__float_as_uint(o0) - (int)(h0 << 16) + 128) >> 8, 127);
;               const int l1 = min(((int)__float_as_uint(o1) - (int)(h1 << 16) + 128) >> 8, 127);
;               const int l2 = min(((int)__float_as_uint(o2) - (int)(h2 << 16) + 128) >> 8, 127);
;               const int l3 = min(((int)__float_as_uint(o3) - (int)(h3 << 16) + 128) >> 8, 127);
;               *reinterpret_cast<unsigned*>(smem + LOBASE + (rr >> 2) * PIECE + (rr & 3) * 256 + cc) =
;                   (unsigned)(l0 & 255) | ((unsigned)(l1 & 255) << 8) | ((unsigned)(l2 & 255) << 16) | ((unsigned)l3 << 24);
;             }
;           }
;           WAIT_L(0); BAR;
;           const int hso = ((brow + ai * HALF + 16 * wave) * DM + pn * BM) * 2;
;           const int lso = (brow + ai * HALF + 16 * wave) * DM + pn * BM;
;           _Pragma("unroll") for (int i = 0; i < 8; ++i) {
;             const u32x4 v = *reinterpret_cast<const u32x4*>(smem + (wave * 8 + i) * PIECE + lane3 * 16);
;             __builtin_amdgcn_raw_buffer_store_b128(v, rsXB, hvo + i * (2 * DM * 2), hso, 0);
;           }
;           _Pragma("unroll") for (int i = 0; i < 4; ++i) {
;             const u32x4 v = *reinterpret_cast<const u32x4*>(smem + LOBASE + (wave * 4 + i) * PIECE + lane3 * 16);
;             __builtin_amdgcn_raw_buffer_store_b128(v, rsLO, lvo + i * (4 * DM), lso, 0);
;           }
;           WAIT_L(0); BAR;
;         }
;       }
;       if (has_next) issue_prologue(nA0, nA1, nB0, nB1);
	v_pk_add_f32 v[6:7], v[8:9], v[2:3] op_sel_hi:[1,0] neg_lo:[0,1] neg_hi:[0,1]
	s_nop 0
	v_pk_mul_f32 v[6:7], v[2:3], v[6:7] op_sel:[1,0]
	v_pk_add_f32 v[8:9], v[10:11], v[2:3] op_sel_hi:[1,0] neg_lo:[0,1] neg_hi:[0,1]
	v_pk_fma_f32 v[6:7], v[24:25], v[6:7], v[26:27]
	v_pk_mul_f32 v[2:3], v[2:3], v[8:9] op_sel:[1,0]
	s_nop 0
	v_pk_fma_f32 v[0:1], v[0:1], v[2:3], v[4:5]
	v_and_b32_sdwa v2, v7, v216 dst_sel:DWORD dst_unused:UNUSED_PAD src0_sel:WORD_1 src1_sel:DWORD
	v_and_b32_sdwa v3, v6, v216 dst_sel:DWORD dst_unused:UNUSED_PAD src0_sel:WORD_1 src1_sel:DWORD
	v_add3_u32 v4, v7, v2, s77
	v_add3_u32 v2, v6, v3, s77
	v_and_b32_e32 v5, 0xffff0000, v2
	v_and_b32_sdwa v2, v1, v216 dst_sel:DWORD dst_unused:UNUSED_PAD src0_sel:WORD_1 src1_sel:DWORD
	v_and_b32_sdwa v3, v0, v216 dst_sel:DWORD dst_unused:UNUSED_PAD src0_sel:WORD_1 src1_sel:DWORD
	v_add3_u32 v2, v1, v2, s77
	v_add3_u32 v8, v0, v3, s77
	v_and_b32_e32 v9, 0xffff0000, v2
	v_or_b32_sdwa v3, v9, v4 dst_sel:DWORD dst_unused:UNUSED_PAD src0_sel:DWORD src1_sel:WORD_1
	v_or_b32_sdwa v2, v8, v5 dst_sel:DWORD dst_unused:UNUSED_PAD src0_sel:WORD_1 src1_sel:DWORD
	ds_write_b64 v73, v[2:3]
	v_and_b32_e32 v2, 0xffff0000, v8
	v_sub_u32_e32 v0, v0, v2
	v_sub_u32_e32 v2, v6, v5
	v_and_b32_e32 v3, 0xffff0000, v4
	v_add_u32_e32 v2, 0x80, v2
	v_sub_u32_e32 v3, v7, v3
	v_sub_u32_e32 v1, v1, v9
	v_add_u32_e32 v0, 0x80, v0
	v_ashrrev_i32_e32 v2, 8, v2
	v_add_u32_e32 v3, 0x80, v3
	v_add_u32_e32 v1, 0x80, v1
	v_ashrrev_i32_e32 v0, 8, v0
	v_min_i32_e32 v2, 0x7f, v2
	v_ashrrev_i32_e32 v3, 8, v3
	v_ashrrev_i32_e32 v1, 8, v1
	v_min_i32_e32 v0, 0x7f, v0
	v_min_i32_sdwa v3, v3, s78 dst_sel:WORD_1 dst_unused:UNUSED_PAD src0_sel:DWORD src1_sel:DWORD
	v_min_i32_e32 v1, 0x7f, v1
	v_lshlrev_b32_e32 v2, 8, v2
	v_and_b32_e32 v2, 0xff00, v2
	v_and_b32_e32 v3, 0xff0000, v3
	v_perm_b32 v0, v1, v0, s79
	v_or3_b32 v0, v0, v2, v3
	ds_write_b32 v22, v0 offset:144
	s_waitcnt lgkmcnt(0)
	s_barrier
	ds_read_b128 v[0:3], v72
	s_waitcnt lgkmcnt(0)
	buffer_store_dwordx4 v[0:3], v148, s[16:19], s0 offen
	ds_read_b128 v[0:3], v72 offset:1040
	s_waitcnt lgkmcnt(0)
	buffer_store_dwordx4 v[0:3], v74, s[16:19], s0 offen
	ds_read_b128 v[0:3], v72 offset:2080
	s_waitcnt lgkmcnt(0)
	buffer_store_dwordx4 v[0:3], v75, s[16:19], s0 offen
	ds_read_b128 v[0:3], v72 offset:3120
	s_waitcnt lgkmcnt(0)
	buffer_store_dwordx4 v[0:3], v81, s[16:19], s0 offen
	ds_read_b128 v[0:3], v72 offset:4160
	s_waitcnt lgkmcnt(0)
	buffer_store_dwordx4 v[0:3], v84, s[16:19], s0 offen
	ds_read_b128 v[0:3], v72 offset:5200
	s_waitcnt lgkmcnt(0)
	buffer_store_dwordx4 v[0:3], v85, s[16:19], s0 offen
	ds_read_b128 v[0:3], v72 offset:6240
	s_waitcnt lgkmcnt(0)
	buffer_store_dwordx4 v[0:3], v88, s[16:19], s0 offen
	ds_read_b128 v[0:3], v72 offset:7280
	s_waitcnt lgkmcnt(0)
	buffer_store_dwordx4 v[0:3], v89, s[16:19], s0 offen
	ds_read_b128 v[0:3], v147
	s_waitcnt lgkmcnt(0)
	buffer_store_dwordx4 v[0:3], v146, s[20:23], s30 offen
	ds_read_b128 v[0:3], v147 offset:1040
	s_waitcnt lgkmcnt(0)
	buffer_store_dwordx4 v[0:3], v90, s[20:23], s30 offen
	ds_read_b128 v[0:3], v147 offset:2080
	s_waitcnt lgkmcnt(0)
	buffer_store_dwordx4 v[0:3], v91, s[20:23], s30 offen
	ds_read_b128 v[0:3], v147 offset:3120
	s_waitcnt lgkmcnt(0)
	buffer_store_dwordx4 v[0:3], v96, s[20:23], s30 offen
	s_waitcnt lgkmcnt(0)
	s_barrier
	s_cbranch_vccnz .LBB0_649
	v_mbcnt_lo_u32_b32 v0, -1, 0
	v_mbcnt_hi_u32_b32 v0, -1, v0
	s_mov_b32 m0, s85
	v_lshl_add_u32 v0, v0, 4, s38
	v_ashrrev_i32_e32 v1, 31, v0
	v_lshrrev_b32_e32 v1, 22, v1
	v_add_u32_e32 v1, v0, v1
	v_ashrrev_i32_e32 v1, 10, v1
	v_mul_i32_i24_e32 v2, 0x400, v1
	v_sub_u32_e32 v2, v0, v2
	v_lshrrev_b32_e32 v3, 4, v2
	v_bitop3_b32 v2, v3, v2, 32 bitop3:0x6c
	v_ashrrev_i32_e32 v4, 31, v2
	v_lshrrev_b32_e32 v4, 26, v4
	v_add_u32_e32 v4, v2, v4
	v_lshrrev_b32_e32 v5, 6, v4
	v_and_b32_e32 v4, 0xc0, v4
	v_lshlrev_b32_e32 v3, 3, v1
	v_lshlrev_b32_e32 v1, 5, v1
	v_sub_u32_e32 v2, v2, v4
	v_and_b32_e32 v3, 0xffff0, v3
	v_and_b32_e32 v1, 32, v1
	v_ashrrev_i16_sdwa v2, v216, sext(v2) dst_sel:DWORD dst_unused:UNUSED_PAD src0_sel:DWORD src1_sel:BYTE_0
	v_add_u32_sdwa v1, v1, sext(v2) dst_sel:DWORD dst_unused:UNUSED_PAD src0_sel:DWORD src1_sel:WORD_0
	v_add_lshl_u32 v2, v5, v3, 12
	v_add_u32_e32 v0, 0x2000, v0
	v_lshl_add_u32 v1, v1, 1, v2
	v_ashrrev_i32_e32 v2, 31, v0
	v_lshrrev_b32_e32 v2, 22, v2
	v_add_u32_e32 v2, v0, v2
	v_ashrrev_i32_e32 v2, 10, v2
	v_mul_i32_i24_e32 v3, 0x400, v2
	v_sub_u32_e32 v0, v0, v3
	v_lshrrev_b32_e32 v3, 4, v0
	v_bitop3_b32 v0, v3, v0, 32 bitop3:0x6c
	v_ashrrev_i32_e32 v4, 31, v0
	v_lshrrev_b32_e32 v4, 26, v4
	v_add_u32_e32 v4, v0, v4
	v_lshrrev_b32_e32 v5, 6, v4
	v_and_b32_e32 v4, 0xffc0, v4
	v_sub_u32_e32 v0, v0, v4
	v_lshrrev_b16_e32 v4, 7, v0
	v_and_b32_e32 v4, 1, v4
	v_lshlrev_b32_e32 v3, 3, v2
	v_lshlrev_b32_e32 v2, 5, v2
	v_add_u16_e32 v0, v0, v4
	v_and_b32_e32 v3, 0xffff0, v3
	v_and_b32_e32 v2, 32, v2
	v_ashrrev_i16_sdwa v0, v216, sext(v0) dst_sel:DWORD dst_unused:UNUSED_PAD src0_sel:DWORD src1_sel:BYTE_0
	v_add_u32_sdwa v0, v2, sext(v0) dst_sel:DWORD dst_unused:UNUSED_PAD src0_sel:DWORD src1_sel:WORD_0
	v_add_lshl_u32 v2, v5, v3, 12
	s_mov_b32 s14, s10
	s_mov_b32 s15, s11
	v_lshl_add_u32 v0, v0, 1, v2
	buffer_load_dwordx4 v1, s[12:15], s83 offen lds
	s_mov_b32 m0, s75
	s_or_b32 s0, s83, 0x80
	buffer_load_dwordx4 v0, s[12:15], s83 offen lds
	s_mov_b32 m0, s38
	s_mov_b64 s[4:5], 0
	buffer_load_dwordx4 v1, s[8:11], s82 offen lds
	s_mov_b32 m0, s95
	s_nop 0
	buffer_load_dwordx4 v0, s[8:11], s82 offen lds
	s_mov_b32 m0, s86
	s_nop 0
	buffer_load_dwordx4 v1, s[12:15], s84 offen lds
	s_mov_b32 m0, s28
	s_nop 0
	buffer_load_dwordx4 v0, s[12:15], s84 offen lds
	s_mov_b32 m0, s87
	s_nop 0
	buffer_load_dwordx4 v1, s[8:11], s81 offen lds
	s_mov_b32 m0, s97
	s_nop 0
	buffer_load_dwordx4 v0, s[8:11], s81 offen lds
	s_mov_b32 m0, s92
	s_nop 0
	buffer_load_dwordx4 v1, s[12:15], s0 offen lds
	s_mov_b32 m0, s29
	s_nop 0
	buffer_load_dwordx4 v0, s[12:15], s0 offen lds
	s_or_b32 s0, s82, 0x80
	s_mov_b32 m0, s93
	s_nop 0
	buffer_load_dwordx4 v1, s[8:11], s0 offen lds
	s_mov_b32 m0, s56
	s_nop 0
	buffer_load_dwordx4 v0, s[8:11], s0 offen lds
	s_add_i32 s0, s84, 0x80
	s_mov_b32 m0, s94
	s_nop 0
	buffer_load_dwordx4 v1, s[12:15], s0 offen lds
	s_mov_b32 m0, s57
	s_nop 0
	buffer_load_dwordx4 v0, s[12:15], s0 offen lds
	s_branch .LBB0_649
